# all flat_load/store/atomic converted to global_ (addresses are always global); waits unchanged
# speedup vs baseline: 1.0058x; 1.0058x over previous
;     const int nblk = N / 32, kb = item / nblk, nb = item % nblk, k0 = 64 * kb, n0 = 32 * nb;
; #pragma unroll
;     for (int i = 0; i < 8; ++i) { const int idx = lane + 64 * i, kk = idx >> 3, n4 = idx & 7; const f32x4 v = *(const f32x4*)(W + (size_t)(k0 + kk) * N + n0 + 4 * n4) * wsc;
;         LAS float* d = scr + kk * 33 + 4 * n4; d[0] = v.x; d[1] = v.y; d[2] = v.z; d[3] = v.w; }
;     asm volatile("s_waitcnt lgkmcnt(0)" ::: "memory");
;     const int c = lane & 7;
; #pragma unroll
;     for (int j = 0; j < 4; ++j) { const int n = (lane >> 3) + 8 * j; const LAS float* s = scr + (8 * c) * 33 + n;
;         u32x4 o; o.x = pk2(s[0 * 33], s[1 * 33]); o.y = pk2(s[2 * 33], s[3 * 33]); o.z = pk2(s[4 * 33], s[5 * 33]); o.w = pk2(s[6 * 33], s[7 * 33]);
;         *(u32x4*)(WT + (size_t)wt_row(mode, row_off, n0 + n) * K + k0 + 8 * c) = o; }
;     asm volatile("s_waitcnt lgkmcnt(0)" ::: "memory");
; }
; __global__ void __launch_bounds__(512, 2) mega_fwd(Params p) {
;     ...
;         for (int it = gw; it < NITEMS; it += NGW) {
;             int r = it;
;             if (r < I_IN) { p0_transpose_item(INP(10), 1024, ZC_END, WSB(WS_WIN), 1.f, 0, scr, r, lane); continue; } r -= I_IN;
;             if (r < I_UQ) { p0_transpose_item(INP(13), 256, 768, WSB(WS_WUQ), 0.10206207261596577f * LOG2E, 0, scr, r, lane); continue; } r -= I_UQ;
;             if (r < I_UK) { p0_transpose_item(INP(14), 128, 512, WSB(WS_WUK), 1.f, 0, scr, r, lane); continue; } r -= I_UK;
;             if (r < I_UV) { p0_transpose_item(INP(15), 128, 512, WSB(WS_WUV), 1.f, 0, scr, r, lane); continue; } r -= I_UV;
;             if (r < I_SQ) { p0_transpose_item(INP(17), 1024, 1024, WSB(WS_WO), 1.f, 0, scr, r, lane); continue; } r -= I_SQ;
;             if (r < I_SQ) { p0_transpose_item(INP(20), 1024, 1024, WSB(WS_WCQ), 0.0625f * LOG2E, 0, scr, r, lane); continue; } r -= I_SQ;
;             if (r < I_SQ) { p0_transpose_item(INP(21), 1024, 1024, WSB(WS_WCKV), 1.f, 0, scr, r, lane); continue; } r -= I_SQ;
;             if (r < I_SQ) { p0_transpose_item(INP(22), 1024, 1024, WSB(WS_WCKV), 1.f, 1024, scr, r, lane); continue; } r -= I_SQ;
;             if (r < I_SQ) { p0_transpose_item(INP(23), 1024, 1024, WSB(WS_WCO), 1.f, 0, scr, r, lane); continue; } r -= I_SQ;
;             if (r < I_UP) { p0_transpose_item(INP(25), 1024, NUP, WSB(WS_WUP), 1.f, 0, scr, r, lane, 1); continue; } r -= I_UP;
.LBB0_11:
	s_cmpk_gt_i32 s47, 0x4cf
	s_mov_b64 s[26:27], -1
	s_cbranch_scc0 .LBB0_49
	s_cmpk_gt_u32 s47, 0x52f
	s_cbranch_scc0 .LBB0_46
	s_cmpk_gt_u32 s47, 0x54f
	s_cbranch_scc0 .LBB0_43
	s_cmpk_gt_u32 s47, 0x56f
	s_cbranch_scc0 .LBB0_40
	s_cmpk_gt_u32 s47, 0x76f
	s_cbranch_scc0 .LBB0_37
	s_cmpk_gt_u32 s47, 0x96f
	s_cbranch_scc0 .LBB0_34
	s_cmpk_gt_u32 s47, 0xb6f
	s_cbranch_scc0 .LBB0_31
	s_cmpk_gt_u32 s47, 0xd6f
	s_cbranch_scc0 .LBB0_28
	s_cmpk_gt_u32 s47, 0xf6f
	s_cbranch_scc0 .LBB0_25
	s_cmpk_gt_u32 s47, 0x1a6f
	s_cbranch_scc0 .LBB0_22
	v_mov_b32_e32 v5, s30
	ds_read_b64 v[6:7], v5
	s_add_i32 s27, s9, 0xfffcb200
	s_and_b32 s27, s27, 0x3e0
	s_and_b32 s26, s28, 0x1ffc0
	s_lshl_b32 s50, s27, 2
	s_waitcnt lgkmcnt(0)
	v_readfirstlane_b32 s48, v6
	v_mov_b32_e32 v5, s31
	v_readfirstlane_b32 s49, v7
	s_add_u32 s48, s48, s50
	ds_read_b64 v[40:41], v5
	s_addc_u32 s49, s49, 0
	v_or_b32_e32 v5, s26, v8
	v_lshl_add_u64 v[6:7], s[48:49], 0, v[2:3]
	v_lshlrev_b32_e32 v36, 12, v5
	v_mov_b32_e32 v37, v3
	v_lshl_add_u64 v[36:37], v[6:7], 0, v[36:37]
	global_load_dwordx4 v[36:39], v[36:37], off
	v_or_b32_e32 v5, s26, v9
	v_mov_b32_e32 v43, v3
	v_lshlrev_b32_e32 v42, 12, v5
	v_lshl_add_u64 v[42:43], v[6:7], 0, v[42:43]
	v_or_b32_e32 v5, s26, v11
	s_waitcnt lgkmcnt(0)
	v_readfirstlane_b32 s48, v40
	v_or_b32_e32 v33, s27, v9
	v_or_b32_e32 v35, s27, v11
	v_mul_u32_u24_e32 v33, 0xb00, v33
	v_mul_u32_u24_e32 v35, 0xb00, v35
	v_lshlrev_b32_e32 v44, 1, v35
	v_mov_b32_e32 v45, v3
	v_mov_b32_e32 v47, v3
	s_waitcnt vmcnt(0)
	ds_write2_b32 v18, v36, v37 offset1:1
	ds_write2_b32 v18, v38, v39 offset0:2 offset1:3
	global_load_dwordx4 v[36:39], v[42:43], off
	v_mov_b32_e32 v43, v3
	v_lshlrev_b32_e32 v42, 12, v5
	v_lshl_add_u64 v[42:43], v[6:7], 0, v[42:43]
	v_or_b32_e32 v5, s26, v12
	s_waitcnt vmcnt(0) lgkmcnt(0)
	ds_write2_b32 v19, v36, v37 offset1:1
	ds_write2_b32 v20, v38, v39 offset1:1
	global_load_dwordx4 v[36:39], v[42:43], off
	v_mov_b32_e32 v43, v3
	v_lshlrev_b32_e32 v42, 12, v5
	v_lshl_add_u64 v[42:43], v[6:7], 0, v[42:43]
	v_or_b32_e32 v5, s26, v13
	s_waitcnt vmcnt(0) lgkmcnt(0)
	ds_write2_b32 v21, v36, v37 offset1:1
	ds_write2_b32 v22, v38, v39 offset1:1
	global_load_dwordx4 v[36:39], v[42:43], off
	v_mov_b32_e32 v43, v3
	v_lshlrev_b32_e32 v42, 12, v5
	v_lshl_add_u64 v[42:43], v[6:7], 0, v[42:43]
	v_or_b32_e32 v5, s26, v14
	s_waitcnt vmcnt(0) lgkmcnt(0)
	ds_write2_b32 v23, v36, v37 offset1:1
	ds_write2_b32 v24, v38, v39 offset1:1
	global_load_dwordx4 v[36:39], v[42:43], off
	v_mov_b32_e32 v43, v3
	v_lshlrev_b32_e32 v42, 12, v5
	v_lshl_add_u64 v[42:43], v[6:7], 0, v[42:43]
	v_or_b32_e32 v5, s26, v15
	s_waitcnt vmcnt(0) lgkmcnt(0)
	ds_write2_b32 v25, v36, v37 offset1:1
	ds_write2_b32 v26, v38, v39 offset1:1
	global_load_dwordx4 v[36:39], v[42:43], off
	v_mov_b32_e32 v43, v3
	v_lshlrev_b32_e32 v42, 12, v5
	v_lshl_add_u64 v[42:43], v[6:7], 0, v[42:43]
	v_or_b32_e32 v5, s26, v16
	s_lshl_b32 s26, s26, 1
	s_add_u32 s26, s48, s26
	s_waitcnt vmcnt(0) lgkmcnt(0)
	ds_write2_b32 v27, v36, v37 offset1:1
	ds_write2_b32 v28, v38, v39 offset1:1
	global_load_dwordx4 v[36:39], v[42:43], off
	v_mov_b32_e32 v43, v3
	v_lshlrev_b32_e32 v42, 12, v5
	v_lshl_add_u64 v[6:7], v[6:7], 0, v[42:43]
	v_or_b32_e32 v42, s27, v12
	v_mov_b32_e32 v5, v3
	v_mul_u32_u24_e32 v46, 0xb00, v42
	v_lshlrev_b32_e32 v42, 1, v33
	v_lshlrev_b32_e32 v46, 1, v46
	s_waitcnt vmcnt(0) lgkmcnt(0)
	ds_write2_b32 v29, v36, v37 offset1:1
	ds_write2_b32 v30, v38, v39 offset1:1
	global_load_dwordx4 v[36:39], v[6:7], off
	v_or_b32_e32 v6, s27, v8
	v_readfirstlane_b32 s27, v41
	s_addc_u32 s27, s27, 0
	v_mul_u32_u24_e32 v6, 0xb00, v6
	v_lshl_add_u64 v[40:41], s[26:27], 0, v[4:5]
	v_mov_b32_e32 v7, v3
	v_lshlrev_b32_e32 v6, 1, v6
	v_lshl_add_u64 v[40:41], v[40:41], 0, s[0:1]
	v_lshl_add_u64 v[6:7], v[40:41], 0, v[6:7]
	s_mov_b64 s[26:27], 0
	s_waitcnt vmcnt(0) lgkmcnt(0)
	ds_write2_b32 v31, v36, v37 offset1:1
	ds_write2_b32 v32, v38, v39 offset1:1
	s_waitcnt lgkmcnt(0)
	ds_read_b32 v5, v17
	ds_read_b32 v33, v17 offset:132
	ds_read_b32 v35, v17 offset:264
	ds_read_b32 v37, v17 offset:396
	ds_read_b32 v38, v17 offset:528
	ds_read_b32 v39, v17 offset:660
	ds_read_b32 v48, v17 offset:792
	ds_read_b32 v49, v17 offset:924
	s_waitcnt lgkmcnt(6)
	v_cvt_pk_bf16_f32 v36, v5, v33
	s_waitcnt lgkmcnt(4)
	v_cvt_pk_bf16_f32 v37, v35, v37
	s_waitcnt lgkmcnt(2)
	v_cvt_pk_bf16_f32 v38, v38, v39
	s_waitcnt lgkmcnt(0)
	v_cvt_pk_bf16_f32 v39, v48, v49
	global_store_dwordx4 v[6:7], v[36:39], off
	ds_read_b32 v5, v17 offset:32
	ds_read_b32 v33, v17 offset:164
	ds_read_b32 v35, v17 offset:296
	ds_read_b32 v37, v17 offset:428
	ds_read_b32 v38, v17 offset:560
	ds_read_b32 v39, v17 offset:692
	ds_read_b32 v48, v17 offset:824
	ds_read_b32 v49, v17 offset:956
	v_lshl_add_u64 v[6:7], v[40:41], 0, v[42:43]
	s_waitcnt lgkmcnt(0)
	v_cvt_pk_bf16_f32 v36, v5, v33
	v_cvt_pk_bf16_f32 v37, v35, v37
	v_cvt_pk_bf16_f32 v38, v38, v39
	v_cvt_pk_bf16_f32 v39, v48, v49
	global_store_dwordx4 v[6:7], v[36:39], off
	ds_read_b32 v5, v17 offset:64
	ds_read_b32 v33, v17 offset:196
	ds_read_b32 v35, v17 offset:328
	ds_read_b32 v37, v17 offset:460
	ds_read_b32 v38, v17 offset:592
	ds_read_b32 v39, v17 offset:724
	ds_read_b32 v42, v17 offset:856
	ds_read_b32 v43, v17 offset:988
	v_lshl_add_u64 v[6:7], v[40:41], 0, v[44:45]
	s_waitcnt lgkmcnt(0)
	v_cvt_pk_bf16_f32 v36, v5, v33
	v_cvt_pk_bf16_f32 v37, v35, v37
	v_cvt_pk_bf16_f32 v38, v38, v39
	v_cvt_pk_bf16_f32 v39, v42, v43
	global_store_dwordx4 v[6:7], v[36:39], off
	ds_read_b32 v5, v17 offset:96
	ds_read_b32 v6, v17 offset:228
	ds_read_b32 v7, v17 offset:360
	ds_read_b32 v33, v17 offset:492
	ds_read_b32 v35, v17 offset:624
	ds_read_b32 v38, v17 offset:756
	ds_read_b32 v39, v17 offset:888
	ds_read_b32 v42, v17 offset:1020
	s_waitcnt lgkmcnt(0)
	v_cvt_pk_bf16_f32 v36, v5, v6
	v_cvt_pk_bf16_f32 v37, v7, v33
	v_cvt_pk_bf16_f32 v38, v35, v38
	v_lshl_add_u64 v[6:7], v[40:41], 0, v[46:47]
	v_cvt_pk_bf16_f32 v39, v39, v42
	global_store_dwordx4 v[6:7], v[36:39], off
	s_waitcnt lgkmcnt(0)
; #define LAS __attribute__((address_space(3)))
; __device__ __forceinline__ unsigned pk2(float lo, float hi) { const f32x2 v = {lo, hi}; return __builtin_bit_cast(unsigned, __builtin_convertvector(v, bf16x2_t)); }
; #define INP(i) ((const float*)tab_get(lds, (i)))
; #define WSB(off) ((bf16*)((unsigned char*)tab_get(lds, 31) + (off)))
; __device__ __forceinline__ int wt_row(int mode, int row_off, int n) { if (mode == 1) { const int g = n >= NFF, f = g ? n - NFF : n; return 256 * (f >> 7) + 128 * g + (f & 127); } return row_off + n; }
;     const int nblk = N / 32, kb = item / nblk, nb = item % nblk, k0 = 64 * kb, n0 = 32 * nb;
; #pragma unroll
;     for (int i = 0; i < 8; ++i) { const int idx = lane + 64 * i, kk = idx >> 3, n4 = idx & 7; const f32x4 v = *(const f32x4*)(W + (size_t)(k0 + kk) * N + n0 + 4 * n4) * wsc;
;         LAS float* d = scr + kk * 33 + 4 * n4; d[0] = v.x; d[1] = v.y; d[2] = v.z; d[3] = v.w; }
;     asm volatile("s_waitcnt lgkmcnt(0)" ::: "memory");
;     const int c = lane & 7;
; #pragma unroll
;     for (int j = 0; j < 4; ++j) { const int n = (lane >> 3) + 8 * j; const LAS float* s = scr + (8 * c) * 33 + n;
;         u32x4 o; o.x = pk2(s[0 * 33], s[1 * 33]); o.y = pk2(s[2 * 33], s[3 * 33]); o.z = pk2(s[4 * 33], s[5 * 33]); o.w = pk2(s[6 * 33], s[7 * 33]);
;         *(u32x4*)(WT + (size_t)wt_row(mode, row_off, n0 + n) * K + k0 + 8 * c) = o; }
; __global__ void __launch_bounds__(512, 2) mega_fwd(Params p) {
;     ...
;             if (r < I_UP) { p0_transpose_item(INP(25), 1024, NUP, WSB(WS_WUP), 1.f, 0, scr, r, lane, 1); continue; } r -= I_UP;
.LBB0_22:
	s_andn2_b64 vcc, exec, s[26:27]
	s_cbranch_vccnz .LBB0_24
	s_add_i32 s26, s47, 0xf090
	s_and_b32 s27, s26, 0xffff
	v_mov_b32_e32 v5, s34
	s_mul_i32 s27, s27, 0xba2f
	ds_read_b64 v[6:7], v5
	s_lshr_b32 s27, s27, 23
	s_mul_i32 s48, s27, 0xb0
	s_sub_i32 s26, s26, s48
	s_lshl_b32 s48, s26, 5
	s_and_b32 s48, s48, 0xffe0
	v_mov_b32_e32 v5, s31
	s_waitcnt lgkmcnt(0)
	v_readfirstlane_b32 s50, v6
	s_lshl_b32 s52, s27, 6
	s_lshl_b32 s51, s48, 2
	ds_read_b64 v[40:41], v5
	v_readfirstlane_b32 s49, v7
	s_add_u32 s50, s50, s51
	v_or_b32_e32 v5, s52, v8
	s_addc_u32 s51, s49, 0
	v_mul_u32_u24_e32 v5, 0x1600, v5
	v_lshl_add_u64 v[6:7], s[50:51], 0, v[2:3]
	v_lshlrev_b32_e32 v36, 2, v5
	v_mov_b32_e32 v37, v3
	v_lshl_add_u64 v[36:37], v[6:7], 0, v[36:37]
	global_load_dwordx4 v[36:39], v[36:37], off
	v_or_b32_e32 v5, s52, v9
	v_mul_u32_u24_e32 v5, 0x1600, v5
	v_mov_b32_e32 v43, v3
	v_lshlrev_b32_e32 v42, 2, v5
	v_lshl_add_u64 v[42:43], v[6:7], 0, v[42:43]
	v_or_b32_e32 v5, s52, v11
	v_mul_u32_u24_e32 v5, 0x1600, v5
	s_waitcnt lgkmcnt(0)
	v_readfirstlane_b32 s50, v40
	s_lshl_b32 s27, s27, 7
	v_readfirstlane_b32 s49, v41
	v_or_b32_e32 v33, s48, v8
	v_or_b32_e32 v35, s48, v9
	v_or_b32_e32 v40, s48, v11
	v_or_b32_e32 v41, s48, v12
	s_add_u32 s48, s50, s27
	s_addc_u32 s49, s49, 0
	s_and_b32 s26, s26, 0xffff
	s_cmpk_gt_u32 s26, 0x57
	s_cselect_b64 vcc, -1, 0
	v_add_u32_e32 v44, 0xfffff500, v40
	s_and_b64 s[26:27], vcc, exec
	v_cndmask_b32_e32 v40, v40, v44, vcc
	s_cselect_b32 s26, 0x80, 0
	v_and_b32_e32 v44, 0x77, v40
	v_add_u32_e32 v45, 0xfffff500, v41
	v_cndmask_b32_e32 v41, v41, v45, vcc
	v_lshlrev_b32_e32 v45, 1, v41
	v_and_b32_e32 v46, 0x7f, v41
	s_waitcnt vmcnt(0)
	ds_write2_b32 v18, v36, v37 offset1:1
	ds_write2_b32 v18, v38, v39 offset0:2 offset1:3
	global_load_dwordx4 v[36:39], v[42:43], off
	v_mov_b32_e32 v43, v3
	v_lshlrev_b32_e32 v42, 2, v5
	v_lshl_add_u64 v[42:43], v[6:7], 0, v[42:43]
	v_or_b32_e32 v5, s52, v12
	v_mul_u32_u24_e32 v5, 0x1600, v5
	s_waitcnt vmcnt(0) lgkmcnt(0)
	ds_write2_b32 v19, v36, v37 offset1:1
	ds_write2_b32 v20, v38, v39 offset1:1
	global_load_dwordx4 v[36:39], v[42:43], off
	v_mov_b32_e32 v43, v3
	v_lshlrev_b32_e32 v42, 2, v5
	v_lshl_add_u64 v[42:43], v[6:7], 0, v[42:43]
	v_or_b32_e32 v5, s52, v13
	v_mul_u32_u24_e32 v5, 0x1600, v5
	s_waitcnt vmcnt(0) lgkmcnt(0)
	ds_write2_b32 v21, v36, v37 offset1:1
	ds_write2_b32 v22, v38, v39 offset1:1
	global_load_dwordx4 v[36:39], v[42:43], off
	v_mov_b32_e32 v43, v3
	v_lshlrev_b32_e32 v42, 2, v5
	v_lshl_add_u64 v[42:43], v[6:7], 0, v[42:43]
	v_or_b32_e32 v5, s52, v14
	v_mul_u32_u24_e32 v5, 0x1600, v5
	s_waitcnt vmcnt(0) lgkmcnt(0)
	ds_write2_b32 v23, v36, v37 offset1:1
	ds_write2_b32 v24, v38, v39 offset1:1
	global_load_dwordx4 v[36:39], v[42:43], off
	v_mov_b32_e32 v43, v3
	v_lshlrev_b32_e32 v42, 2, v5
	v_lshl_add_u64 v[42:43], v[6:7], 0, v[42:43]
	v_or_b32_e32 v5, s52, v15
	v_mul_u32_u24_e32 v5, 0x1600, v5
	s_waitcnt vmcnt(0) lgkmcnt(0)
	ds_write2_b32 v25, v36, v37 offset1:1
	ds_write2_b32 v26, v38, v39 offset1:1
	global_load_dwordx4 v[36:39], v[42:43], off
	v_mov_b32_e32 v43, v3
	v_lshlrev_b32_e32 v42, 2, v5
	v_lshl_add_u64 v[42:43], v[6:7], 0, v[42:43]
	v_or_b32_e32 v5, s52, v16
	v_mul_u32_u24_e32 v5, 0x1600, v5
	s_waitcnt vmcnt(0) lgkmcnt(0)
	ds_write2_b32 v27, v36, v37 offset1:1
	ds_write2_b32 v28, v38, v39 offset1:1
	global_load_dwordx4 v[36:39], v[42:43], off
	v_mov_b32_e32 v43, v3
	v_lshlrev_b32_e32 v42, 2, v5
	v_lshl_add_u64 v[6:7], v[6:7], 0, v[42:43]
	v_mov_b32_e32 v5, v3
	v_add_u32_e32 v42, 0xfffff500, v33
	v_add_u32_e32 v43, 0xfffff500, v35
	v_cndmask_b32_e32 v35, v35, v43, vcc
	v_lshlrev_b32_e32 v43, 1, v40
	s_waitcnt vmcnt(0) lgkmcnt(0)
	ds_write2_b32 v29, v36, v37 offset1:1
	ds_write2_b32 v30, v38, v39 offset1:1
	global_load_dwordx4 v[36:39], v[6:7], off
	v_lshl_add_u64 v[6:7], s[48:49], 0, v[4:5]
	v_cndmask_b32_e32 v5, v33, v42, vcc
	v_lshlrev_b32_e32 v33, 1, v5
	v_and_b32_e32 v5, 0x67, v5
	v_and_b32_e32 v33, 0xffffff00, v33
	v_lshlrev_b32_e32 v42, 1, v35
	v_and_b32_e32 v35, 0x6f, v35
	v_or3_b32 v40, v5, v33, s26
	v_and_b32_e32 v5, 0xffffff00, v42
	v_and_b32_e32 v33, 0xffffff00, v43
	v_or3_b32 v42, v35, v5, s26
	v_or3_b32 v44, v44, v33, s26
	v_ashrrev_i32_e32 v41, 31, v40
	v_lshl_add_u64 v[6:7], v[6:7], 0, s[2:3]
	v_lshlrev_b64 v[40:41], 11, v[40:41]
	v_lshl_add_u64 v[40:41], v[6:7], 0, v[40:41]
	v_and_b32_e32 v43, 0xffffff00, v45
	v_or3_b32 v46, v46, v43, s26
	v_ashrrev_i32_e32 v43, 31, v42
	v_lshlrev_b64 v[42:43], 11, v[42:43]
	v_ashrrev_i32_e32 v45, 31, v44
	v_lshlrev_b64 v[44:45], 11, v[44:45]
	v_ashrrev_i32_e32 v47, 31, v46
	s_waitcnt vmcnt(0) lgkmcnt(0)
	ds_write2_b32 v31, v36, v37 offset1:1
	ds_write2_b32 v32, v38, v39 offset1:1
	s_waitcnt lgkmcnt(0)
	ds_read_b32 v5, v17
	ds_read_b32 v33, v17 offset:132
	ds_read_b32 v35, v17 offset:264
	ds_read_b32 v37, v17 offset:396
	ds_read_b32 v38, v17 offset:528
	ds_read_b32 v39, v17 offset:660
	ds_read_b32 v48, v17 offset:792
	ds_read_b32 v49, v17 offset:924
	s_waitcnt lgkmcnt(6)
	v_cvt_pk_bf16_f32 v36, v5, v33
	s_waitcnt lgkmcnt(4)
	v_cvt_pk_bf16_f32 v37, v35, v37
	s_waitcnt lgkmcnt(2)
	v_cvt_pk_bf16_f32 v38, v38, v39
	s_waitcnt lgkmcnt(0)
	v_cvt_pk_bf16_f32 v39, v48, v49
	global_store_dwordx4 v[40:41], v[36:39], off
	ds_read_b32 v5, v17 offset:32
	ds_read_b32 v33, v17 offset:164
	ds_read_b32 v35, v17 offset:296
	ds_read_b32 v37, v17 offset:428
	ds_read_b32 v38, v17 offset:560
	ds_read_b32 v39, v17 offset:692
	ds_read_b32 v48, v17 offset:824
	ds_read_b32 v49, v17 offset:956
	v_lshl_add_u64 v[40:41], v[6:7], 0, v[42:43]
	s_waitcnt lgkmcnt(0)
	v_cvt_pk_bf16_f32 v36, v5, v33
	v_cvt_pk_bf16_f32 v37, v35, v37
	v_cvt_pk_bf16_f32 v38, v38, v39
	v_cvt_pk_bf16_f32 v39, v48, v49
	global_store_dwordx4 v[40:41], v[36:39], off
	ds_read_b32 v5, v17 offset:64
	ds_read_b32 v33, v17 offset:196
	ds_read_b32 v35, v17 offset:328
	ds_read_b32 v37, v17 offset:460
	ds_read_b32 v38, v17 offset:592
	ds_read_b32 v39, v17 offset:724
	ds_read_b32 v42, v17 offset:856
	ds_read_b32 v43, v17 offset:988
	v_lshl_add_u64 v[40:41], v[6:7], 0, v[44:45]
	s_waitcnt lgkmcnt(0)
	v_cvt_pk_bf16_f32 v36, v5, v33
	v_cvt_pk_bf16_f32 v37, v35, v37
	v_cvt_pk_bf16_f32 v38, v38, v39
	v_cvt_pk_bf16_f32 v39, v42, v43
	global_store_dwordx4 v[40:41], v[36:39], off
	ds_read_b32 v5, v17 offset:96
	ds_read_b32 v33, v17 offset:228
	ds_read_b32 v35, v17 offset:360
	ds_read_b32 v37, v17 offset:492
	ds_read_b32 v38, v17 offset:624
	ds_read_b32 v39, v17 offset:756
	ds_read_b32 v42, v17 offset:888
	ds_read_b32 v43, v17 offset:1020
	v_lshlrev_b64 v[40:41], 11, v[46:47]
	s_waitcnt lgkmcnt(0)
	v_cvt_pk_bf16_f32 v36, v5, v33
	v_cvt_pk_bf16_f32 v37, v35, v37
	v_cvt_pk_bf16_f32 v38, v38, v39
	v_cvt_pk_bf16_f32 v39, v42, v43
	v_lshl_add_u64 v[6:7], v[6:7], 0, v[40:41]
	global_store_dwordx4 v[6:7], v[36:39], off
	s_waitcnt lgkmcnt(0)

; #define LAS __attribute__((address_space(3)))
; __device__ __forceinline__ unsigned pk2(float lo, float hi) { const f32x2 v = {lo, hi}; return __builtin_bit_cast(unsigned, __builtin_convertvector(v, bf16x2_t)); }
; #define INP(i) ((const float*)tab_get(lds, (i)))
; #define WSB(off) ((bf16*)((unsigned char*)tab_get(lds, 31) + (off)))
; __device__ __forceinline__ int wt_row(int mode, int row_off, int n) { if (mode == 1) { const int g = n >= NFF, f = g ? n - NFF : n; return 256 * (f >> 7) + 128 * g + (f & 127); } return row_off + n; }
;     const int nblk = N / 32, kb = item / nblk, nb = item % nblk, k0 = 64 * kb, n0 = 32 * nb;
; #pragma unroll
;     for (int i = 0; i < 8; ++i) { const int idx = lane + 64 * i, kk = idx >> 3, n4 = idx & 7; const f32x4 v = *(const f32x4*)(W + (size_t)(k0 + kk) * N + n0 + 4 * n4) * wsc;
;         LAS float* d = scr + kk * 33 + 4 * n4; d[0] = v.x; d[1] = v.y; d[2] = v.z; d[3] = v.w; }
;     asm volatile("s_waitcnt lgkmcnt(0)" ::: "memory");
;     const int c = lane & 7;
; #pragma unroll
;     for (int j = 0; j < 4; ++j) { const int n = (lane >> 3) + 8 * j; const LAS float* s = scr + (8 * c) * 33 + n;
;         u32x4 o; o.x = pk2(s[0 * 33], s[1 * 33]); o.y = pk2(s[2 * 33], s[3 * 33]); o.z = pk2(s[4 * 33], s[5 * 33]); o.w = pk2(s[6 * 33], s[7 * 33]);
;         *(u32x4*)(WT + (size_t)wt_row(mode, row_off, n0 + n) * K + k0 + 8 * c) = o; }
;     asm volatile("s_waitcnt lgkmcnt(0)" ::: "memory");
; }
; __global__ void __launch_bounds__(512, 2) mega_fwd(Params p) {
;     ...
;             if (r < I_SQ) { p0_transpose_item(INP(23), 1024, 1024, WSB(WS_WCO), 1.f, 0, scr, r, lane); continue; } r -= I_SQ;
.LBB0_25:
	s_andn2_b64 vcc, exec, s[26:27]
	s_cbranch_vccnz .LBB0_27
	v_mov_b32_e32 v5, s35
	ds_read_b64 v[6:7], v5
	s_add_i32 s27, s9, 0xfffe5200
	s_add_i32 s26, s28, 0x1a00
	s_and_b32 s27, s27, 0x3e0
	s_and_b32 s26, s26, 0x1ffc0
	s_waitcnt lgkmcnt(0)
	v_readfirstlane_b32 s48, v6
	s_lshl_b32 s50, s27, 2
	v_mov_b32_e32 v5, s31
	v_readfirstlane_b32 s49, v7
	s_add_u32 s48, s48, s50
	ds_read_b64 v[40:41], v5
	s_addc_u32 s49, s49, 0
	v_or_b32_e32 v5, s26, v8
	v_lshl_add_u64 v[6:7], s[48:49], 0, v[2:3]
	v_lshlrev_b32_e32 v36, 12, v5
	v_mov_b32_e32 v37, v3
	v_lshl_add_u64 v[36:37], v[6:7], 0, v[36:37]
	global_load_dwordx4 v[36:39], v[36:37], off
	v_or_b32_e32 v5, s26, v9
	v_mov_b32_e32 v43, v3
	v_lshlrev_b32_e32 v42, 12, v5
	v_lshl_add_u64 v[42:43], v[6:7], 0, v[42:43]
	v_or_b32_e32 v5, s26, v11
	s_waitcnt lgkmcnt(0)
	v_readfirstlane_b32 s48, v40
	v_or_b32_e32 v33, s27, v9
	v_or_b32_e32 v35, s27, v11
	v_or_b32_e32 v46, s27, v12
	v_lshlrev_b32_e32 v44, 11, v35
	v_mov_b32_e32 v45, v3
	v_mov_b32_e32 v47, v3
	v_lshlrev_b32_e32 v46, 11, v46
	s_waitcnt vmcnt(0)
	ds_write2_b32 v18, v36, v37 offset1:1
	ds_write2_b32 v18, v38, v39 offset0:2 offset1:3
	global_load_dwordx4 v[36:39], v[42:43], off
	v_mov_b32_e32 v43, v3
	v_lshlrev_b32_e32 v42, 12, v5
	v_lshl_add_u64 v[42:43], v[6:7], 0, v[42:43]
	v_or_b32_e32 v5, s26, v12
	s_waitcnt vmcnt(0) lgkmcnt(0)
	ds_write2_b32 v19, v36, v37 offset1:1
	ds_write2_b32 v20, v38, v39 offset1:1
	global_load_dwordx4 v[36:39], v[42:43], off
	v_mov_b32_e32 v43, v3
	v_lshlrev_b32_e32 v42, 12, v5
	v_lshl_add_u64 v[42:43], v[6:7], 0, v[42:43]
	v_or_b32_e32 v5, s26, v13
	s_waitcnt vmcnt(0) lgkmcnt(0)
	ds_write2_b32 v21, v36, v37 offset1:1
	ds_write2_b32 v22, v38, v39 offset1:1
	global_load_dwordx4 v[36:39], v[42:43], off
	v_mov_b32_e32 v43, v3
	v_lshlrev_b32_e32 v42, 12, v5
	v_lshl_add_u64 v[42:43], v[6:7], 0, v[42:43]
	v_or_b32_e32 v5, s26, v14
	s_waitcnt vmcnt(0) lgkmcnt(0)
	ds_write2_b32 v23, v36, v37 offset1:1
	ds_write2_b32 v24, v38, v39 offset1:1
	global_load_dwordx4 v[36:39], v[42:43], off
	v_mov_b32_e32 v43, v3
	v_lshlrev_b32_e32 v42, 12, v5
	v_lshl_add_u64 v[42:43], v[6:7], 0, v[42:43]
	v_or_b32_e32 v5, s26, v15
	s_waitcnt vmcnt(0) lgkmcnt(0)
	ds_write2_b32 v25, v36, v37 offset1:1
	ds_write2_b32 v26, v38, v39 offset1:1
	global_load_dwordx4 v[36:39], v[42:43], off
	v_mov_b32_e32 v43, v3
	v_lshlrev_b32_e32 v42, 12, v5
	v_lshl_add_u64 v[42:43], v[6:7], 0, v[42:43]
	v_or_b32_e32 v5, s26, v16
	s_lshl_b32 s26, s26, 1
	s_add_u32 s26, s48, s26
	s_waitcnt vmcnt(0) lgkmcnt(0)
	ds_write2_b32 v27, v36, v37 offset1:1
	ds_write2_b32 v28, v38, v39 offset1:1
	global_load_dwordx4 v[36:39], v[42:43], off
	v_mov_b32_e32 v43, v3
	v_lshlrev_b32_e32 v42, 12, v5
	v_lshl_add_u64 v[6:7], v[6:7], 0, v[42:43]
	v_mov_b32_e32 v5, v3
	v_lshlrev_b32_e32 v42, 11, v33
	s_waitcnt vmcnt(0) lgkmcnt(0)
	ds_write2_b32 v29, v36, v37 offset1:1
	ds_write2_b32 v30, v38, v39 offset1:1
	global_load_dwordx4 v[36:39], v[6:7], off
	v_or_b32_e32 v6, s27, v8
	v_readfirstlane_b32 s27, v41
	s_addc_u32 s27, s27, 0
	v_mov_b32_e32 v7, v3
	v_lshl_add_u64 v[40:41], s[26:27], 0, v[4:5]
	v_lshlrev_b32_e32 v6, 11, v6
	v_lshl_add_u64 v[40:41], v[40:41], 0, s[4:5]
	v_lshl_add_u64 v[6:7], v[40:41], 0, v[6:7]
	s_waitcnt vmcnt(0) lgkmcnt(0)
	ds_write2_b32 v31, v36, v37 offset1:1
	ds_write2_b32 v32, v38, v39 offset1:1
	s_waitcnt lgkmcnt(0)
	ds_read_b32 v5, v17
	ds_read_b32 v33, v17 offset:132
	ds_read_b32 v35, v17 offset:264
	ds_read_b32 v37, v17 offset:396
	ds_read_b32 v38, v17 offset:528
	ds_read_b32 v39, v17 offset:660
	ds_read_b32 v48, v17 offset:792
	ds_read_b32 v49, v17 offset:924
	s_waitcnt lgkmcnt(6)
	v_cvt_pk_bf16_f32 v36, v5, v33
	s_waitcnt lgkmcnt(4)
	v_cvt_pk_bf16_f32 v37, v35, v37
	s_waitcnt lgkmcnt(2)
	v_cvt_pk_bf16_f32 v38, v38, v39
	s_waitcnt lgkmcnt(0)
	v_cvt_pk_bf16_f32 v39, v48, v49
	global_store_dwordx4 v[6:7], v[36:39], off
	ds_read_b32 v5, v17 offset:32
	ds_read_b32 v33, v17 offset:164
	ds_read_b32 v35, v17 offset:296
	ds_read_b32 v37, v17 offset:428
	ds_read_b32 v38, v17 offset:560
	ds_read_b32 v39, v17 offset:692
	ds_read_b32 v48, v17 offset:824
	ds_read_b32 v49, v17 offset:956
	v_lshl_add_u64 v[6:7], v[40:41], 0, v[42:43]
	s_waitcnt lgkmcnt(0)
	v_cvt_pk_bf16_f32 v36, v5, v33
	v_cvt_pk_bf16_f32 v37, v35, v37
	v_cvt_pk_bf16_f32 v38, v38, v39
	v_cvt_pk_bf16_f32 v39, v48, v49
	global_store_dwordx4 v[6:7], v[36:39], off
	ds_read_b32 v5, v17 offset:64
	ds_read_b32 v33, v17 offset:196
	ds_read_b32 v35, v17 offset:328
	ds_read_b32 v37, v17 offset:460
	ds_read_b32 v38, v17 offset:592
	ds_read_b32 v39, v17 offset:724
	ds_read_b32 v42, v17 offset:856
	ds_read_b32 v43, v17 offset:988
	v_lshl_add_u64 v[6:7], v[40:41], 0, v[44:45]
	s_waitcnt lgkmcnt(0)
	v_cvt_pk_bf16_f32 v36, v5, v33
	v_cvt_pk_bf16_f32 v37, v35, v37
	v_cvt_pk_bf16_f32 v38, v38, v39
	v_cvt_pk_bf16_f32 v39, v42, v43
	global_store_dwordx4 v[6:7], v[36:39], off
	ds_read_b32 v5, v17 offset:96
	ds_read_b32 v6, v17 offset:228
	ds_read_b32 v7, v17 offset:360
	ds_read_b32 v33, v17 offset:492
	ds_read_b32 v35, v17 offset:624
	ds_read_b32 v38, v17 offset:756
	ds_read_b32 v39, v17 offset:888
	ds_read_b32 v42, v17 offset:1020
	s_waitcnt lgkmcnt(0)
	v_cvt_pk_bf16_f32 v36, v5, v6
	v_cvt_pk_bf16_f32 v37, v7, v33
	v_cvt_pk_bf16_f32 v38, v35, v38
	v_lshl_add_u64 v[6:7], v[40:41], 0, v[46:47]
	v_cvt_pk_bf16_f32 v39, v39, v42
	global_store_dwordx4 v[6:7], v[36:39], off
	s_waitcnt lgkmcnt(0)

; #define LAS __attribute__((address_space(3)))
; __device__ __forceinline__ unsigned pk2(float lo, float hi) { const f32x2 v = {lo, hi}; return __builtin_bit_cast(unsigned, __builtin_convertvector(v, bf16x2_t)); }
; #define INP(i) ((const float*)tab_get(lds, (i)))
; #define WSB(off) ((bf16*)((unsigned char*)tab_get(lds, 31) + (off)))
; __device__ __forceinline__ int wt_row(int mode, int row_off, int n) { if (mode == 1) { const int g = n >= NFF, f = g ? n - NFF : n; return 256 * (f >> 7) + 128 * g + (f & 127); } return row_off + n; }
;     const int nblk = N / 32, kb = item / nblk, nb = item % nblk, k0 = 64 * kb, n0 = 32 * nb;
; #pragma unroll
;     for (int i = 0; i < 8; ++i) { const int idx = lane + 64 * i, kk = idx >> 3, n4 = idx & 7; const f32x4 v = *(const f32x4*)(W + (size_t)(k0 + kk) * N + n0 + 4 * n4) * wsc;
;         LAS float* d = scr + kk * 33 + 4 * n4; d[0] = v.x; d[1] = v.y; d[2] = v.z; d[3] = v.w; }
;     asm volatile("s_waitcnt lgkmcnt(0)" ::: "memory");
;     const int c = lane & 7;
; #pragma unroll
;     for (int j = 0; j < 4; ++j) { const int n = (lane >> 3) + 8 * j; const LAS float* s = scr + (8 * c) * 33 + n;
;         u32x4 o; o.x = pk2(s[0 * 33], s[1 * 33]); o.y = pk2(s[2 * 33], s[3 * 33]); o.z = pk2(s[4 * 33], s[5 * 33]); o.w = pk2(s[6 * 33], s[7 * 33]);
;         *(u32x4*)(WT + (size_t)wt_row(mode, row_off, n0 + n) * K + k0 + 8 * c) = o; }
;     asm volatile("s_waitcnt lgkmcnt(0)" ::: "memory");
; }
; __global__ void __launch_bounds__(512, 2) mega_fwd(Params p) {
;     ...
;             if (r < I_SQ) { p0_transpose_item(INP(22), 1024, 1024, WSB(WS_WCKV), 1.f, 1024, scr, r, lane); continue; } r -= I_SQ;
.LBB0_28:
	s_andn2_b64 vcc, exec, s[26:27]
	s_cbranch_vccnz .LBB0_30
	v_mov_b32_e32 v5, s36
	ds_read_b64 v[6:7], v5
	s_add_i32 s27, s9, 0xfffe9200
	s_add_i32 s26, s28, 0x1e00
	s_and_b32 s27, s27, 0x3e0
	s_and_b32 s26, s26, 0x1ffc0
	s_waitcnt lgkmcnt(0)
	v_readfirstlane_b32 s48, v6
	s_lshl_b32 s50, s27, 2
	v_mov_b32_e32 v5, s31
	v_readfirstlane_b32 s49, v7
	s_add_u32 s48, s48, s50
	ds_read_b64 v[40:41], v5
	s_addc_u32 s49, s49, 0
	v_or_b32_e32 v5, s26, v8
	v_lshl_add_u64 v[6:7], s[48:49], 0, v[2:3]
	v_lshlrev_b32_e32 v36, 12, v5
	v_mov_b32_e32 v37, v3
	v_lshl_add_u64 v[36:37], v[6:7], 0, v[36:37]
	global_load_dwordx4 v[36:39], v[36:37], off
	v_or_b32_e32 v5, s26, v9
	v_mov_b32_e32 v43, v3
	v_lshlrev_b32_e32 v42, 12, v5
	v_lshl_add_u64 v[42:43], v[6:7], 0, v[42:43]
	v_or_b32_e32 v5, s26, v11
	s_waitcnt lgkmcnt(0)
	v_readfirstlane_b32 s48, v40
	v_or_b32_e32 v33, s27, v9
	v_or_b32_e32 v35, s27, v11
	v_or_b32_e32 v46, s27, v12
	v_mov_b32_e32 v45, v3
	v_mov_b32_e32 v47, v3
	v_lshlrev_b32_e32 v44, 11, v35
	v_lshlrev_b32_e32 v46, 11, v46
	s_waitcnt vmcnt(0)
	ds_write2_b32 v18, v36, v37 offset1:1
	ds_write2_b32 v18, v38, v39 offset0:2 offset1:3
	global_load_dwordx4 v[36:39], v[42:43], off
	v_mov_b32_e32 v43, v3
	v_lshlrev_b32_e32 v42, 12, v5
	v_lshl_add_u64 v[42:43], v[6:7], 0, v[42:43]
	v_or_b32_e32 v5, s26, v12
	s_waitcnt vmcnt(0) lgkmcnt(0)
	ds_write2_b32 v19, v36, v37 offset1:1
	ds_write2_b32 v20, v38, v39 offset1:1
	global_load_dwordx4 v[36:39], v[42:43], off
	v_mov_b32_e32 v43, v3
	v_lshlrev_b32_e32 v42, 12, v5
	v_lshl_add_u64 v[42:43], v[6:7], 0, v[42:43]
	v_or_b32_e32 v5, s26, v13
	s_waitcnt vmcnt(0) lgkmcnt(0)
	ds_write2_b32 v21, v36, v37 offset1:1
	ds_write2_b32 v22, v38, v39 offset1:1
	global_load_dwordx4 v[36:39], v[42:43], off
	v_mov_b32_e32 v43, v3
	v_lshlrev_b32_e32 v42, 12, v5
	v_lshl_add_u64 v[42:43], v[6:7], 0, v[42:43]
	v_or_b32_e32 v5, s26, v14
	s_waitcnt vmcnt(0) lgkmcnt(0)
	ds_write2_b32 v23, v36, v37 offset1:1
	ds_write2_b32 v24, v38, v39 offset1:1
	global_load_dwordx4 v[36:39], v[42:43], off
	v_mov_b32_e32 v43, v3
	v_lshlrev_b32_e32 v42, 12, v5
	v_lshl_add_u64 v[42:43], v[6:7], 0, v[42:43]
	v_or_b32_e32 v5, s26, v15
	s_waitcnt vmcnt(0) lgkmcnt(0)
	ds_write2_b32 v25, v36, v37 offset1:1
	ds_write2_b32 v26, v38, v39 offset1:1
	global_load_dwordx4 v[36:39], v[42:43], off
	v_mov_b32_e32 v43, v3
	v_lshlrev_b32_e32 v42, 12, v5
	v_lshl_add_u64 v[42:43], v[6:7], 0, v[42:43]
	v_or_b32_e32 v5, s26, v16
	s_lshl_b32 s26, s26, 1
	s_add_u32 s26, s48, s26
	s_waitcnt vmcnt(0) lgkmcnt(0)
	ds_write2_b32 v27, v36, v37 offset1:1
	ds_write2_b32 v28, v38, v39 offset1:1
	global_load_dwordx4 v[36:39], v[42:43], off
	v_mov_b32_e32 v43, v3
	v_lshlrev_b32_e32 v42, 12, v5
	v_lshl_add_u64 v[6:7], v[6:7], 0, v[42:43]
	v_mov_b32_e32 v5, v3
	v_lshlrev_b32_e32 v42, 11, v33
	s_waitcnt vmcnt(0) lgkmcnt(0)
	ds_write2_b32 v29, v36, v37 offset1:1
	ds_write2_b32 v30, v38, v39 offset1:1
	global_load_dwordx4 v[36:39], v[6:7], off
	v_or_b32_e32 v6, s27, v8
	v_readfirstlane_b32 s27, v41
	s_addc_u32 s27, s27, 0
	v_mov_b32_e32 v7, v3
	v_lshl_add_u64 v[40:41], s[26:27], 0, v[4:5]
	v_lshlrev_b32_e32 v6, 11, v6
	v_lshl_add_u64 v[40:41], v[40:41], 0, s[6:7]
	v_lshl_add_u64 v[6:7], v[40:41], 0, v[6:7]
	v_lshl_add_u64 v[42:43], v[40:41], 0, v[42:43]
	v_lshl_add_u64 v[44:45], v[40:41], 0, v[44:45]
	v_lshl_add_u64 v[40:41], v[40:41], 0, v[46:47]
	v_add_co_u32_e32 v6, vcc, s37, v6
	s_waitcnt vmcnt(0) lgkmcnt(0)
	ds_write2_b32 v31, v36, v37 offset1:1
	ds_write2_b32 v32, v38, v39 offset1:1
	s_waitcnt lgkmcnt(0)
	ds_read_b32 v5, v17
	ds_read_b32 v33, v17 offset:132
	ds_read_b32 v35, v17 offset:264
	ds_read_b32 v37, v17 offset:396
	ds_read_b32 v38, v17 offset:528
	ds_read_b32 v39, v17 offset:660
	ds_read_b32 v46, v17 offset:792
	ds_read_b32 v47, v17 offset:924
	v_addc_co_u32_e32 v7, vcc, 0, v7, vcc
	s_waitcnt lgkmcnt(6)
	v_cvt_pk_bf16_f32 v36, v5, v33
	s_waitcnt lgkmcnt(4)
	v_cvt_pk_bf16_f32 v37, v35, v37
	s_waitcnt lgkmcnt(2)
	v_cvt_pk_bf16_f32 v38, v38, v39
	s_waitcnt lgkmcnt(0)
	v_cvt_pk_bf16_f32 v39, v46, v47
	global_store_dwordx4 v[6:7], v[36:39], off
	ds_read_b32 v5, v17 offset:32
	ds_read_b32 v33, v17 offset:164
	ds_read_b32 v35, v17 offset:296
	ds_read_b32 v37, v17 offset:428
	ds_read_b32 v38, v17 offset:560
	ds_read_b32 v39, v17 offset:692
	ds_read_b32 v46, v17 offset:824
	ds_read_b32 v47, v17 offset:956
	v_add_co_u32_e32 v6, vcc, s37, v42
	s_waitcnt lgkmcnt(0)
	v_cvt_pk_bf16_f32 v36, v5, v33
	v_addc_co_u32_e32 v7, vcc, 0, v43, vcc
	v_cvt_pk_bf16_f32 v37, v35, v37
	v_cvt_pk_bf16_f32 v38, v38, v39
	v_cvt_pk_bf16_f32 v39, v46, v47
	global_store_dwordx4 v[6:7], v[36:39], off
	ds_read_b32 v5, v17 offset:64
	ds_read_b32 v33, v17 offset:196
	ds_read_b32 v35, v17 offset:328
	ds_read_b32 v37, v17 offset:460
	ds_read_b32 v38, v17 offset:592
	ds_read_b32 v39, v17 offset:724
	ds_read_b32 v42, v17 offset:856
	ds_read_b32 v43, v17 offset:988
	v_add_co_u32_e32 v6, vcc, s37, v44
	s_waitcnt lgkmcnt(0)
	v_cvt_pk_bf16_f32 v36, v5, v33
	v_addc_co_u32_e32 v7, vcc, 0, v45, vcc
	v_cvt_pk_bf16_f32 v37, v35, v37
	v_cvt_pk_bf16_f32 v38, v38, v39
	v_cvt_pk_bf16_f32 v39, v42, v43
	global_store_dwordx4 v[6:7], v[36:39], off
	ds_read_b32 v5, v17 offset:96
	ds_read_b32 v7, v17 offset:228
	ds_read_b32 v33, v17 offset:360
	ds_read_b32 v35, v17 offset:492
	ds_read_b32 v38, v17 offset:624
	ds_read_b32 v39, v17 offset:756
	ds_read_b32 v42, v17 offset:888
	ds_read_b32 v43, v17 offset:1020
	v_add_co_u32_e32 v6, vcc, 0x200000, v40
	s_waitcnt lgkmcnt(0)
	v_cvt_pk_bf16_f32 v36, v5, v7
	v_cvt_pk_bf16_f32 v37, v33, v35
	v_cvt_pk_bf16_f32 v38, v38, v39
	v_cvt_pk_bf16_f32 v39, v42, v43
	v_addc_co_u32_e32 v7, vcc, 0, v41, vcc
	global_store_dwordx4 v[6:7], v[36:39], off
	s_waitcnt lgkmcnt(0)

; #define LAS __attribute__((address_space(3)))
; __device__ __forceinline__ unsigned pk2(float lo, float hi) { const f32x2 v = {lo, hi}; return __builtin_bit_cast(unsigned, __builtin_convertvector(v, bf16x2_t)); }
; #define INP(i) ((const float*)tab_get(lds, (i)))
; #define WSB(off) ((bf16*)((unsigned char*)tab_get(lds, 31) + (off)))
; __device__ __forceinline__ int wt_row(int mode, int row_off, int n) { if (mode == 1) { const int g = n >= NFF, f = g ? n - NFF : n; return 256 * (f >> 7) + 128 * g + (f & 127); } return row_off + n; }
;     const int nblk = N / 32, kb = item / nblk, nb = item % nblk, k0 = 64 * kb, n0 = 32 * nb;
; #pragma unroll
;     for (int i = 0; i < 8; ++i) { const int idx = lane + 64 * i, kk = idx >> 3, n4 = idx & 7; const f32x4 v = *(const f32x4*)(W + (size_t)(k0 + kk) * N + n0 + 4 * n4) * wsc;
;         LAS float* d = scr + kk * 33 + 4 * n4; d[0] = v.x; d[1] = v.y; d[2] = v.z; d[3] = v.w; }
;     asm volatile("s_waitcnt lgkmcnt(0)" ::: "memory");
;     const int c = lane & 7;
; #pragma unroll
;     for (int j = 0; j < 4; ++j) { const int n = (lane >> 3) + 8 * j; const LAS float* s = scr + (8 * c) * 33 + n;
;         u32x4 o; o.x = pk2(s[0 * 33], s[1 * 33]); o.y = pk2(s[2 * 33], s[3 * 33]); o.z = pk2(s[4 * 33], s[5 * 33]); o.w = pk2(s[6 * 33], s[7 * 33]);
;         *(u32x4*)(WT + (size_t)wt_row(mode, row_off, n0 + n) * K + k0 + 8 * c) = o; }
;     asm volatile("s_waitcnt lgkmcnt(0)" ::: "memory");
; }
; __global__ void __launch_bounds__(512, 2) mega_fwd(Params p) {
;     ...
;             if (r < I_SQ) { p0_transpose_item(INP(21), 1024, 1024, WSB(WS_WCKV), 1.f, 0, scr, r, lane); continue; } r -= I_SQ;
.LBB0_31:
	s_andn2_b64 vcc, exec, s[26:27]
	s_cbranch_vccnz .LBB0_33
	v_mov_b32_e32 v5, s38
	ds_read_b64 v[6:7], v5
	s_add_i32 s27, s9, 0xfffed200
	s_add_i32 s26, s28, 0x2200
	s_and_b32 s27, s27, 0x3e0
	s_and_b32 s26, s26, 0x1ffc0
	s_waitcnt lgkmcnt(0)
	v_readfirstlane_b32 s48, v6
	s_lshl_b32 s50, s27, 2
	v_mov_b32_e32 v5, s31
	v_readfirstlane_b32 s49, v7
	s_add_u32 s48, s48, s50
	ds_read_b64 v[40:41], v5
	s_addc_u32 s49, s49, 0
	v_or_b32_e32 v5, s26, v8
	v_lshl_add_u64 v[6:7], s[48:49], 0, v[2:3]
	v_lshlrev_b32_e32 v36, 12, v5
	v_mov_b32_e32 v37, v3
	v_lshl_add_u64 v[36:37], v[6:7], 0, v[36:37]
	global_load_dwordx4 v[36:39], v[36:37], off
	v_or_b32_e32 v5, s26, v9
	v_mov_b32_e32 v43, v3
	v_lshlrev_b32_e32 v42, 12, v5
	v_lshl_add_u64 v[42:43], v[6:7], 0, v[42:43]
	v_or_b32_e32 v5, s26, v11
	s_waitcnt lgkmcnt(0)
	v_readfirstlane_b32 s48, v40
	v_or_b32_e32 v33, s27, v9
	v_or_b32_e32 v35, s27, v11
	v_or_b32_e32 v46, s27, v12
	v_lshlrev_b32_e32 v44, 11, v35
	v_mov_b32_e32 v45, v3
	v_mov_b32_e32 v47, v3
	v_lshlrev_b32_e32 v46, 11, v46
	s_waitcnt vmcnt(0)
	ds_write2_b32 v18, v36, v37 offset1:1
	ds_write2_b32 v18, v38, v39 offset0:2 offset1:3
	global_load_dwordx4 v[36:39], v[42:43], off
	v_mov_b32_e32 v43, v3
	v_lshlrev_b32_e32 v42, 12, v5
	v_lshl_add_u64 v[42:43], v[6:7], 0, v[42:43]
	v_or_b32_e32 v5, s26, v12
	s_waitcnt vmcnt(0) lgkmcnt(0)
	ds_write2_b32 v19, v36, v37 offset1:1
	ds_write2_b32 v20, v38, v39 offset1:1
	global_load_dwordx4 v[36:39], v[42:43], off
	v_mov_b32_e32 v43, v3
	v_lshlrev_b32_e32 v42, 12, v5
	v_lshl_add_u64 v[42:43], v[6:7], 0, v[42:43]
	v_or_b32_e32 v5, s26, v13
	s_waitcnt vmcnt(0) lgkmcnt(0)
	ds_write2_b32 v21, v36, v37 offset1:1
	ds_write2_b32 v22, v38, v39 offset1:1
	global_load_dwordx4 v[36:39], v[42:43], off
	v_mov_b32_e32 v43, v3
	v_lshlrev_b32_e32 v42, 12, v5
	v_lshl_add_u64 v[42:43], v[6:7], 0, v[42:43]
	v_or_b32_e32 v5, s26, v14
	s_waitcnt vmcnt(0) lgkmcnt(0)
	ds_write2_b32 v23, v36, v37 offset1:1
	ds_write2_b32 v24, v38, v39 offset1:1
	global_load_dwordx4 v[36:39], v[42:43], off
	v_mov_b32_e32 v43, v3
	v_lshlrev_b32_e32 v42, 12, v5
	v_lshl_add_u64 v[42:43], v[6:7], 0, v[42:43]
	v_or_b32_e32 v5, s26, v15
	s_waitcnt vmcnt(0) lgkmcnt(0)
	ds_write2_b32 v25, v36, v37 offset1:1
	ds_write2_b32 v26, v38, v39 offset1:1
	global_load_dwordx4 v[36:39], v[42:43], off
	v_mov_b32_e32 v43, v3
	v_lshlrev_b32_e32 v42, 12, v5
	v_lshl_add_u64 v[42:43], v[6:7], 0, v[42:43]
	v_or_b32_e32 v5, s26, v16
	s_lshl_b32 s26, s26, 1
	s_add_u32 s26, s48, s26
	s_waitcnt vmcnt(0) lgkmcnt(0)
	ds_write2_b32 v27, v36, v37 offset1:1
	ds_write2_b32 v28, v38, v39 offset1:1
	global_load_dwordx4 v[36:39], v[42:43], off
	v_mov_b32_e32 v43, v3
	v_lshlrev_b32_e32 v42, 12, v5
	v_lshl_add_u64 v[6:7], v[6:7], 0, v[42:43]
	v_mov_b32_e32 v5, v3
	v_lshlrev_b32_e32 v42, 11, v33
	s_waitcnt vmcnt(0) lgkmcnt(0)
	ds_write2_b32 v29, v36, v37 offset1:1
	ds_write2_b32 v30, v38, v39 offset1:1
	global_load_dwordx4 v[36:39], v[6:7], off
	v_or_b32_e32 v6, s27, v8
	v_readfirstlane_b32 s27, v41
	s_addc_u32 s27, s27, 0
	v_mov_b32_e32 v7, v3
	v_lshl_add_u64 v[40:41], s[26:27], 0, v[4:5]
	v_lshlrev_b32_e32 v6, 11, v6
	v_lshl_add_u64 v[40:41], v[40:41], 0, s[6:7]
	v_lshl_add_u64 v[6:7], v[40:41], 0, v[6:7]
	s_waitcnt vmcnt(0) lgkmcnt(0)
	ds_write2_b32 v31, v36, v37 offset1:1
	ds_write2_b32 v32, v38, v39 offset1:1
	s_waitcnt lgkmcnt(0)
	ds_read_b32 v5, v17
	ds_read_b32 v33, v17 offset:132
	ds_read_b32 v35, v17 offset:264
	ds_read_b32 v37, v17 offset:396
	ds_read_b32 v38, v17 offset:528
	ds_read_b32 v39, v17 offset:660
	ds_read_b32 v48, v17 offset:792
	ds_read_b32 v49, v17 offset:924
	s_waitcnt lgkmcnt(6)
	v_cvt_pk_bf16_f32 v36, v5, v33
	s_waitcnt lgkmcnt(4)
	v_cvt_pk_bf16_f32 v37, v35, v37
	s_waitcnt lgkmcnt(2)
	v_cvt_pk_bf16_f32 v38, v38, v39
	s_waitcnt lgkmcnt(0)
	v_cvt_pk_bf16_f32 v39, v48, v49
	global_store_dwordx4 v[6:7], v[36:39], off
	ds_read_b32 v5, v17 offset:32
	ds_read_b32 v33, v17 offset:164
	ds_read_b32 v35, v17 offset:296
	ds_read_b32 v37, v17 offset:428
	ds_read_b32 v38, v17 offset:560
	ds_read_b32 v39, v17 offset:692
	ds_read_b32 v48, v17 offset:824
	ds_read_b32 v49, v17 offset:956
	v_lshl_add_u64 v[6:7], v[40:41], 0, v[42:43]
	s_waitcnt lgkmcnt(0)
	v_cvt_pk_bf16_f32 v36, v5, v33
	v_cvt_pk_bf16_f32 v37, v35, v37
	v_cvt_pk_bf16_f32 v38, v38, v39
	v_cvt_pk_bf16_f32 v39, v48, v49
	global_store_dwordx4 v[6:7], v[36:39], off
	ds_read_b32 v5, v17 offset:64
	ds_read_b32 v33, v17 offset:196
	ds_read_b32 v35, v17 offset:328
	ds_read_b32 v37, v17 offset:460
	ds_read_b32 v38, v17 offset:592
	ds_read_b32 v39, v17 offset:724
	ds_read_b32 v42, v17 offset:856
	ds_read_b32 v43, v17 offset:988
	v_lshl_add_u64 v[6:7], v[40:41], 0, v[44:45]
	s_waitcnt lgkmcnt(0)
	v_cvt_pk_bf16_f32 v36, v5, v33
	v_cvt_pk_bf16_f32 v37, v35, v37
	v_cvt_pk_bf16_f32 v38, v38, v39
	v_cvt_pk_bf16_f32 v39, v42, v43
	global_store_dwordx4 v[6:7], v[36:39], off
	ds_read_b32 v5, v17 offset:96
	ds_read_b32 v6, v17 offset:228
	ds_read_b32 v7, v17 offset:360
	ds_read_b32 v33, v17 offset:492
	ds_read_b32 v35, v17 offset:624
	ds_read_b32 v38, v17 offset:756
	ds_read_b32 v39, v17 offset:888
	ds_read_b32 v42, v17 offset:1020
	s_waitcnt lgkmcnt(0)
	v_cvt_pk_bf16_f32 v36, v5, v6
	v_cvt_pk_bf16_f32 v37, v7, v33
	v_cvt_pk_bf16_f32 v38, v35, v38
	v_lshl_add_u64 v[6:7], v[40:41], 0, v[46:47]
	v_cvt_pk_bf16_f32 v39, v39, v42
	global_store_dwordx4 v[6:7], v[36:39], off
	s_waitcnt lgkmcnt(0)

; #define LAS __attribute__((address_space(3)))
; __device__ __forceinline__ unsigned pk2(float lo, float hi) { const f32x2 v = {lo, hi}; return __builtin_bit_cast(unsigned, __builtin_convertvector(v, bf16x2_t)); }
; #define INP(i) ((const float*)tab_get(lds, (i)))
; #define WSB(off) ((bf16*)((unsigned char*)tab_get(lds, 31) + (off)))
; __device__ __forceinline__ int wt_row(int mode, int row_off, int n) { if (mode == 1) { const int g = n >= NFF, f = g ? n - NFF : n; return 256 * (f >> 7) + 128 * g + (f & 127); } return row_off + n; }
;     const int nblk = N / 32, kb = item / nblk, nb = item % nblk, k0 = 64 * kb, n0 = 32 * nb;
; #pragma unroll
;     for (int i = 0; i < 8; ++i) { const int idx = lane + 64 * i, kk = idx >> 3, n4 = idx & 7; const f32x4 v = *(const f32x4*)(W + (size_t)(k0 + kk) * N + n0 + 4 * n4) * wsc;
;         LAS float* d = scr + kk * 33 + 4 * n4; d[0] = v.x; d[1] = v.y; d[2] = v.z; d[3] = v.w; }
;     asm volatile("s_waitcnt lgkmcnt(0)" ::: "memory");
;     const int c = lane & 7;
; #pragma unroll
;     for (int j = 0; j < 4; ++j) { const int n = (lane >> 3) + 8 * j; const LAS float* s = scr + (8 * c) * 33 + n;
;         u32x4 o; o.x = pk2(s[0 * 33], s[1 * 33]); o.y = pk2(s[2 * 33], s[3 * 33]); o.z = pk2(s[4 * 33], s[5 * 33]); o.w = pk2(s[6 * 33], s[7 * 33]);
;         *(u32x4*)(WT + (size_t)wt_row(mode, row_off, n0 + n) * K + k0 + 8 * c) = o; }
;     asm volatile("s_waitcnt lgkmcnt(0)" ::: "memory");
; }
; __global__ void __launch_bounds__(512, 2) mega_fwd(Params p) {
;     ...
;             if (r < I_SQ) { p0_transpose_item(INP(20), 1024, 1024, WSB(WS_WCQ), 0.0625f * LOG2E, 0, scr, r, lane); continue; } r -= I_SQ;
.LBB0_34:
	s_andn2_b64 vcc, exec, s[26:27]
	s_cbranch_vccnz .LBB0_36
	v_mov_b32_e32 v5, s39
	ds_read_b64 v[36:37], v5
	s_add_i32 s27, s9, 0xffff1200
	s_add_i32 s26, s28, 0x2600
	s_and_b32 s27, s27, 0x3e0
	s_and_b32 s26, s26, 0x1ffc0
	s_waitcnt lgkmcnt(0)
	v_readfirstlane_b32 s48, v36
	s_lshl_b32 s50, s27, 2
	v_mov_b32_e32 v5, s31
	v_readfirstlane_b32 s49, v37
	s_add_u32 s48, s48, s50
	ds_read_b64 v[6:7], v5
	s_addc_u32 s49, s49, 0
	v_or_b32_e32 v5, s26, v8
	v_lshl_add_u64 v[40:41], s[48:49], 0, v[2:3]
	v_lshlrev_b32_e32 v36, 12, v5
	v_mov_b32_e32 v37, v3
	v_lshl_add_u64 v[36:37], v[40:41], 0, v[36:37]
	global_load_dwordx4 v[36:39], v[36:37], off
	v_or_b32_e32 v5, s26, v9
	v_mov_b32_e32 v43, v3
	v_lshlrev_b32_e32 v42, 12, v5
	v_lshl_add_u64 v[42:43], v[40:41], 0, v[42:43]
	v_or_b32_e32 v5, s26, v11
	s_waitcnt lgkmcnt(0)
	v_readfirstlane_b32 s48, v6
	v_or_b32_e32 v33, s27, v8
	v_or_b32_e32 v35, s27, v9
	v_or_b32_e32 v44, s27, v11
	v_or_b32_e32 v46, s27, v12
	v_readfirstlane_b32 s27, v7
	v_mov_b32_e32 v45, v3
	v_lshlrev_b32_e32 v44, 11, v44
	v_mov_b32_e32 v47, v3
	v_lshlrev_b32_e32 v46, 11, v46
	s_waitcnt vmcnt(0)
	v_pk_mul_f32 v[36:37], v[36:37], s[8:9] op_sel_hi:[1,0]
	v_pk_mul_f32 v[38:39], v[38:39], s[8:9] op_sel_hi:[1,0]
	ds_write2_b32 v18, v36, v37 offset1:1
	ds_write2_b32 v18, v38, v39 offset0:2 offset1:3
	global_load_dwordx4 v[36:39], v[42:43], off
	v_mov_b32_e32 v43, v3
	v_lshlrev_b32_e32 v42, 12, v5
	v_lshl_add_u64 v[42:43], v[40:41], 0, v[42:43]
	v_or_b32_e32 v5, s26, v12
	s_waitcnt vmcnt(0) lgkmcnt(0)
	v_pk_mul_f32 v[36:37], v[36:37], s[8:9] op_sel_hi:[1,0]
	v_pk_mul_f32 v[38:39], v[38:39], s[8:9] op_sel_hi:[1,0]
	ds_write2_b32 v19, v36, v37 offset1:1
	ds_write2_b32 v20, v38, v39 offset1:1
	global_load_dwordx4 v[36:39], v[42:43], off
	v_mov_b32_e32 v43, v3
	v_lshlrev_b32_e32 v42, 12, v5
	v_lshl_add_u64 v[42:43], v[40:41], 0, v[42:43]
	v_or_b32_e32 v5, s26, v13
	s_waitcnt vmcnt(0) lgkmcnt(0)
	v_pk_mul_f32 v[36:37], v[36:37], s[8:9] op_sel_hi:[1,0]
	v_pk_mul_f32 v[38:39], v[38:39], s[8:9] op_sel_hi:[1,0]
	ds_write2_b32 v21, v36, v37 offset1:1
	ds_write2_b32 v22, v38, v39 offset1:1
	global_load_dwordx4 v[36:39], v[42:43], off
	v_mov_b32_e32 v43, v3
	v_lshlrev_b32_e32 v42, 12, v5
	v_lshl_add_u64 v[42:43], v[40:41], 0, v[42:43]
	v_or_b32_e32 v5, s26, v14
	s_waitcnt vmcnt(0) lgkmcnt(0)
	v_pk_mul_f32 v[36:37], v[36:37], s[8:9] op_sel_hi:[1,0]
	v_pk_mul_f32 v[38:39], v[38:39], s[8:9] op_sel_hi:[1,0]
	ds_write2_b32 v23, v36, v37 offset1:1
	ds_write2_b32 v24, v38, v39 offset1:1
	global_load_dwordx4 v[36:39], v[42:43], off
	v_mov_b32_e32 v43, v3
	v_lshlrev_b32_e32 v42, 12, v5
	v_lshl_add_u64 v[42:43], v[40:41], 0, v[42:43]
	v_or_b32_e32 v5, s26, v15
	s_waitcnt vmcnt(0) lgkmcnt(0)
	v_pk_mul_f32 v[36:37], v[36:37], s[8:9] op_sel_hi:[1,0]
	v_pk_mul_f32 v[38:39], v[38:39], s[8:9] op_sel_hi:[1,0]
	ds_write2_b32 v25, v36, v37 offset1:1
	ds_write2_b32 v26, v38, v39 offset1:1
	global_load_dwordx4 v[36:39], v[42:43], off
	v_mov_b32_e32 v43, v3
	v_lshlrev_b32_e32 v42, 12, v5
	v_lshl_add_u64 v[42:43], v[40:41], 0, v[42:43]
	v_or_b32_e32 v5, s26, v16
	s_lshl_b32 s26, s26, 1
	s_add_u32 s26, s48, s26
	s_addc_u32 s27, s27, 0
	s_waitcnt vmcnt(0) lgkmcnt(0)
	v_pk_mul_f32 v[36:37], v[36:37], s[8:9] op_sel_hi:[1,0]
	v_pk_mul_f32 v[38:39], v[38:39], s[8:9] op_sel_hi:[1,0]
	ds_write2_b32 v27, v36, v37 offset1:1
	ds_write2_b32 v28, v38, v39 offset1:1
	global_load_dwordx4 v[36:39], v[42:43], off
	v_mov_b32_e32 v43, v3
	v_lshlrev_b32_e32 v42, 12, v5
	v_lshl_add_u64 v[40:41], v[40:41], 0, v[42:43]
	v_mov_b32_e32 v5, v3
	v_lshlrev_b32_e32 v42, 11, v35
	v_lshl_add_u64 v[6:7], s[26:27], 0, v[4:5]
	v_lshl_add_u64 v[6:7], v[6:7], 0, s[10:11]
	s_waitcnt vmcnt(0) lgkmcnt(0)
	v_pk_mul_f32 v[36:37], v[36:37], s[8:9] op_sel_hi:[1,0]
	v_pk_mul_f32 v[38:39], v[38:39], s[8:9] op_sel_hi:[1,0]
	ds_write2_b32 v29, v36, v37 offset1:1
	ds_write2_b32 v30, v38, v39 offset1:1
	global_load_dwordx4 v[36:39], v[40:41], off
	v_lshlrev_b32_e32 v40, 11, v33
	v_mov_b32_e32 v41, v3
	v_lshl_add_u64 v[40:41], v[6:7], 0, v[40:41]
	s_waitcnt vmcnt(0) lgkmcnt(0)
	v_pk_mul_f32 v[36:37], v[36:37], s[8:9] op_sel_hi:[1,0]
	v_pk_mul_f32 v[38:39], v[38:39], s[8:9] op_sel_hi:[1,0]
	ds_write2_b32 v31, v36, v37 offset1:1
	ds_write2_b32 v32, v38, v39 offset1:1
	s_waitcnt lgkmcnt(0)
	ds_read_b32 v5, v17
	ds_read_b32 v33, v17 offset:132
	ds_read_b32 v35, v17 offset:264
	ds_read_b32 v37, v17 offset:396
	ds_read_b32 v38, v17 offset:528
	ds_read_b32 v39, v17 offset:660
	ds_read_b32 v48, v17 offset:792
	ds_read_b32 v49, v17 offset:924
	s_waitcnt lgkmcnt(6)
	v_cvt_pk_bf16_f32 v36, v5, v33
	s_waitcnt lgkmcnt(4)
	v_cvt_pk_bf16_f32 v37, v35, v37
	s_waitcnt lgkmcnt(2)
	v_cvt_pk_bf16_f32 v38, v38, v39
	s_waitcnt lgkmcnt(0)
	v_cvt_pk_bf16_f32 v39, v48, v49
	global_store_dwordx4 v[40:41], v[36:39], off
	ds_read_b32 v5, v17 offset:32
	ds_read_b32 v33, v17 offset:164
	ds_read_b32 v35, v17 offset:296
	ds_read_b32 v37, v17 offset:428
	ds_read_b32 v38, v17 offset:560
	ds_read_b32 v39, v17 offset:692
	ds_read_b32 v48, v17 offset:824
	ds_read_b32 v49, v17 offset:956
	v_lshl_add_u64 v[40:41], v[6:7], 0, v[42:43]
	s_waitcnt lgkmcnt(0)
	v_cvt_pk_bf16_f32 v36, v5, v33
	v_cvt_pk_bf16_f32 v37, v35, v37
	v_cvt_pk_bf16_f32 v38, v38, v39
	v_cvt_pk_bf16_f32 v39, v48, v49
	global_store_dwordx4 v[40:41], v[36:39], off
	ds_read_b32 v5, v17 offset:64
	ds_read_b32 v33, v17 offset:196
	ds_read_b32 v35, v17 offset:328
	ds_read_b32 v37, v17 offset:460
	ds_read_b32 v38, v17 offset:592
	ds_read_b32 v39, v17 offset:724
	ds_read_b32 v42, v17 offset:856
	ds_read_b32 v43, v17 offset:988
	v_lshl_add_u64 v[40:41], v[6:7], 0, v[44:45]
	s_waitcnt lgkmcnt(0)
	v_cvt_pk_bf16_f32 v36, v5, v33
	v_cvt_pk_bf16_f32 v37, v35, v37
	v_cvt_pk_bf16_f32 v38, v38, v39
	v_cvt_pk_bf16_f32 v39, v42, v43
	global_store_dwordx4 v[40:41], v[36:39], off
	ds_read_b32 v5, v17 offset:96
	ds_read_b32 v33, v17 offset:228
	ds_read_b32 v35, v17 offset:360
	ds_read_b32 v37, v17 offset:492
	ds_read_b32 v38, v17 offset:624
	ds_read_b32 v39, v17 offset:756
	ds_read_b32 v40, v17 offset:888
	ds_read_b32 v41, v17 offset:1020
	s_waitcnt lgkmcnt(0)
	v_cvt_pk_bf16_f32 v36, v5, v33
	v_cvt_pk_bf16_f32 v37, v35, v37
	v_cvt_pk_bf16_f32 v38, v38, v39
	v_lshl_add_u64 v[6:7], v[6:7], 0, v[46:47]
	v_cvt_pk_bf16_f32 v39, v40, v41
	global_store_dwordx4 v[6:7], v[36:39], off
	s_waitcnt lgkmcnt(0)

; #define LAS __attribute__((address_space(3)))
; __device__ __forceinline__ unsigned pk2(float lo, float hi) { const f32x2 v = {lo, hi}; return __builtin_bit_cast(unsigned, __builtin_convertvector(v, bf16x2_t)); }
; #define INP(i) ((const float*)tab_get(lds, (i)))
; #define WSB(off) ((bf16*)((unsigned char*)tab_get(lds, 31) + (off)))
; __device__ __forceinline__ int wt_row(int mode, int row_off, int n) { if (mode == 1) { const int g = n >= NFF, f = g ? n - NFF : n; return 256 * (f >> 7) + 128 * g + (f & 127); } return row_off + n; }
;     const int nblk = N / 32, kb = item / nblk, nb = item % nblk, k0 = 64 * kb, n0 = 32 * nb;
; #pragma unroll
;     for (int i = 0; i < 8; ++i) { const int idx = lane + 64 * i, kk = idx >> 3, n4 = idx & 7; const f32x4 v = *(const f32x4*)(W + (size_t)(k0 + kk) * N + n0 + 4 * n4) * wsc;
;         LAS float* d = scr + kk * 33 + 4 * n4; d[0] = v.x; d[1] = v.y; d[2] = v.z; d[3] = v.w; }
;     asm volatile("s_waitcnt lgkmcnt(0)" ::: "memory");
;     const int c = lane & 7;
; #pragma unroll
;     for (int j = 0; j < 4; ++j) { const int n = (lane >> 3) + 8 * j; const LAS float* s = scr + (8 * c) * 33 + n;
;         u32x4 o; o.x = pk2(s[0 * 33], s[1 * 33]); o.y = pk2(s[2 * 33], s[3 * 33]); o.z = pk2(s[4 * 33], s[5 * 33]); o.w = pk2(s[6 * 33], s[7 * 33]);
;         *(u32x4*)(WT + (size_t)wt_row(mode, row_off, n0 + n) * K + k0 + 8 * c) = o; }
;     asm volatile("s_waitcnt lgkmcnt(0)" ::: "memory");
; }
; __global__ void __launch_bounds__(512, 2) mega_fwd(Params p) {
;     ...
;             if (r < I_SQ) { p0_transpose_item(INP(17), 1024, 1024, WSB(WS_WO), 1.f, 0, scr, r, lane); continue; } r -= I_SQ;
.LBB0_37:
	s_andn2_b64 vcc, exec, s[26:27]
	s_cbranch_vccnz .LBB0_39
	v_mov_b32_e32 v5, s40
	ds_read_b64 v[6:7], v5
	s_add_i32 s27, s9, 0xffff5200
	s_add_i32 s26, s28, 0x2a00
	s_and_b32 s27, s27, 0x3e0
	s_and_b32 s26, s26, 0x1ffc0
	s_waitcnt lgkmcnt(0)
	v_readfirstlane_b32 s48, v6
	s_lshl_b32 s50, s27, 2
	v_mov_b32_e32 v5, s31
	v_readfirstlane_b32 s49, v7
	s_add_u32 s48, s48, s50
	ds_read_b64 v[40:41], v5
	s_addc_u32 s49, s49, 0
	v_or_b32_e32 v5, s26, v8
	v_lshl_add_u64 v[6:7], s[48:49], 0, v[2:3]
	v_lshlrev_b32_e32 v36, 12, v5
	v_mov_b32_e32 v37, v3
	v_lshl_add_u64 v[36:37], v[6:7], 0, v[36:37]
	global_load_dwordx4 v[36:39], v[36:37], off
	v_or_b32_e32 v5, s26, v9
	v_mov_b32_e32 v43, v3
	v_lshlrev_b32_e32 v42, 12, v5
	v_lshl_add_u64 v[42:43], v[6:7], 0, v[42:43]
	v_or_b32_e32 v5, s26, v11
	s_waitcnt lgkmcnt(0)
	v_readfirstlane_b32 s48, v40
	v_or_b32_e32 v33, s27, v9
	v_or_b32_e32 v35, s27, v11
	v_or_b32_e32 v46, s27, v12
	v_lshlrev_b32_e32 v44, 11, v35
	v_mov_b32_e32 v45, v3
	v_mov_b32_e32 v47, v3
	v_lshlrev_b32_e32 v46, 11, v46
	s_waitcnt vmcnt(0)
	ds_write2_b32 v18, v36, v37 offset1:1
	ds_write2_b32 v18, v38, v39 offset0:2 offset1:3
	global_load_dwordx4 v[36:39], v[42:43], off
	v_mov_b32_e32 v43, v3
	v_lshlrev_b32_e32 v42, 12, v5
	v_lshl_add_u64 v[42:43], v[6:7], 0, v[42:43]
	v_or_b32_e32 v5, s26, v12
	s_waitcnt vmcnt(0) lgkmcnt(0)
	ds_write2_b32 v19, v36, v37 offset1:1
	ds_write2_b32 v20, v38, v39 offset1:1
	global_load_dwordx4 v[36:39], v[42:43], off
	v_mov_b32_e32 v43, v3
	v_lshlrev_b32_e32 v42, 12, v5
	v_lshl_add_u64 v[42:43], v[6:7], 0, v[42:43]
	v_or_b32_e32 v5, s26, v13
	s_waitcnt vmcnt(0) lgkmcnt(0)
	ds_write2_b32 v21, v36, v37 offset1:1
	ds_write2_b32 v22, v38, v39 offset1:1
	global_load_dwordx4 v[36:39], v[42:43], off
	v_mov_b32_e32 v43, v3
	v_lshlrev_b32_e32 v42, 12, v5
	v_lshl_add_u64 v[42:43], v[6:7], 0, v[42:43]
	v_or_b32_e32 v5, s26, v14
	s_waitcnt vmcnt(0) lgkmcnt(0)
	ds_write2_b32 v23, v36, v37 offset1:1
	ds_write2_b32 v24, v38, v39 offset1:1
	global_load_dwordx4 v[36:39], v[42:43], off
	v_mov_b32_e32 v43, v3
	v_lshlrev_b32_e32 v42, 12, v5
	v_lshl_add_u64 v[42:43], v[6:7], 0, v[42:43]
	v_or_b32_e32 v5, s26, v15
	s_waitcnt vmcnt(0) lgkmcnt(0)
	ds_write2_b32 v25, v36, v37 offset1:1
	ds_write2_b32 v26, v38, v39 offset1:1
	global_load_dwordx4 v[36:39], v[42:43], off
	v_mov_b32_e32 v43, v3
	v_lshlrev_b32_e32 v42, 12, v5
	v_lshl_add_u64 v[42:43], v[6:7], 0, v[42:43]
	v_or_b32_e32 v5, s26, v16
	s_lshl_b32 s26, s26, 1
	s_add_u32 s26, s48, s26
	s_waitcnt vmcnt(0) lgkmcnt(0)
	ds_write2_b32 v27, v36, v37 offset1:1
	ds_write2_b32 v28, v38, v39 offset1:1
	global_load_dwordx4 v[36:39], v[42:43], off
	v_mov_b32_e32 v43, v3
	v_lshlrev_b32_e32 v42, 12, v5
	v_lshl_add_u64 v[6:7], v[6:7], 0, v[42:43]
	v_mov_b32_e32 v5, v3
	v_lshlrev_b32_e32 v42, 11, v33
	s_waitcnt vmcnt(0) lgkmcnt(0)
	ds_write2_b32 v29, v36, v37 offset1:1
	ds_write2_b32 v30, v38, v39 offset1:1
	global_load_dwordx4 v[36:39], v[6:7], off
	v_or_b32_e32 v6, s27, v8
	v_readfirstlane_b32 s27, v41
	s_addc_u32 s27, s27, 0
	v_mov_b32_e32 v7, v3
	v_lshl_add_u64 v[40:41], s[26:27], 0, v[4:5]
	v_lshlrev_b32_e32 v6, 11, v6
	v_lshl_add_u64 v[40:41], v[40:41], 0, s[12:13]
	v_lshl_add_u64 v[6:7], v[40:41], 0, v[6:7]
	s_waitcnt vmcnt(0) lgkmcnt(0)
	ds_write2_b32 v31, v36, v37 offset1:1
	ds_write2_b32 v32, v38, v39 offset1:1
	s_waitcnt lgkmcnt(0)
	ds_read_b32 v5, v17
	ds_read_b32 v33, v17 offset:132
	ds_read_b32 v35, v17 offset:264
	ds_read_b32 v37, v17 offset:396
	ds_read_b32 v38, v17 offset:528
	ds_read_b32 v39, v17 offset:660
	ds_read_b32 v48, v17 offset:792
	ds_read_b32 v49, v17 offset:924
	s_waitcnt lgkmcnt(6)
	v_cvt_pk_bf16_f32 v36, v5, v33
	s_waitcnt lgkmcnt(4)
	v_cvt_pk_bf16_f32 v37, v35, v37
	s_waitcnt lgkmcnt(2)
	v_cvt_pk_bf16_f32 v38, v38, v39
	s_waitcnt lgkmcnt(0)
	v_cvt_pk_bf16_f32 v39, v48, v49
	global_store_dwordx4 v[6:7], v[36:39], off
	ds_read_b32 v5, v17 offset:32
	ds_read_b32 v33, v17 offset:164
	ds_read_b32 v35, v17 offset:296
	ds_read_b32 v37, v17 offset:428
	ds_read_b32 v38, v17 offset:560
	ds_read_b32 v39, v17 offset:692
	ds_read_b32 v48, v17 offset:824
	ds_read_b32 v49, v17 offset:956
	v_lshl_add_u64 v[6:7], v[40:41], 0, v[42:43]
	s_waitcnt lgkmcnt(0)
	v_cvt_pk_bf16_f32 v36, v5, v33
	v_cvt_pk_bf16_f32 v37, v35, v37
	v_cvt_pk_bf16_f32 v38, v38, v39
	v_cvt_pk_bf16_f32 v39, v48, v49
	global_store_dwordx4 v[6:7], v[36:39], off
	ds_read_b32 v5, v17 offset:64
	ds_read_b32 v33, v17 offset:196
	ds_read_b32 v35, v17 offset:328
	ds_read_b32 v37, v17 offset:460
	ds_read_b32 v38, v17 offset:592
	ds_read_b32 v39, v17 offset:724
	ds_read_b32 v42, v17 offset:856
	ds_read_b32 v43, v17 offset:988
	v_lshl_add_u64 v[6:7], v[40:41], 0, v[44:45]
	s_waitcnt lgkmcnt(0)
	v_cvt_pk_bf16_f32 v36, v5, v33
	v_cvt_pk_bf16_f32 v37, v35, v37
	v_cvt_pk_bf16_f32 v38, v38, v39
	v_cvt_pk_bf16_f32 v39, v42, v43
	global_store_dwordx4 v[6:7], v[36:39], off
	ds_read_b32 v5, v17 offset:96
	ds_read_b32 v6, v17 offset:228
	ds_read_b32 v7, v17 offset:360
	ds_read_b32 v33, v17 offset:492
	ds_read_b32 v35, v17 offset:624
	ds_read_b32 v38, v17 offset:756
	ds_read_b32 v39, v17 offset:888
	ds_read_b32 v42, v17 offset:1020
	s_waitcnt lgkmcnt(0)
	v_cvt_pk_bf16_f32 v36, v5, v6
	v_cvt_pk_bf16_f32 v37, v7, v33
	v_cvt_pk_bf16_f32 v38, v35, v38
	v_lshl_add_u64 v[6:7], v[40:41], 0, v[46:47]
	v_cvt_pk_bf16_f32 v39, v39, v42
	global_store_dwordx4 v[6:7], v[36:39], off
	s_waitcnt lgkmcnt(0)

; #define LAS __attribute__((address_space(3)))
; __device__ __forceinline__ unsigned pk2(float lo, float hi) { const f32x2 v = {lo, hi}; return __builtin_bit_cast(unsigned, __builtin_convertvector(v, bf16x2_t)); }
; #define INP(i) ((const float*)tab_get(lds, (i)))
; #define WSB(off) ((bf16*)((unsigned char*)tab_get(lds, 31) + (off)))
; __device__ __forceinline__ int wt_row(int mode, int row_off, int n) { if (mode == 1) { const int g = n >= NFF, f = g ? n - NFF : n; return 256 * (f >> 7) + 128 * g + (f & 127); } return row_off + n; }
;     const int nblk = N / 32, kb = item / nblk, nb = item % nblk, k0 = 64 * kb, n0 = 32 * nb;
; #pragma unroll
;     for (int i = 0; i < 8; ++i) { const int idx = lane + 64 * i, kk = idx >> 3, n4 = idx & 7; const f32x4 v = *(const f32x4*)(W + (size_t)(k0 + kk) * N + n0 + 4 * n4) * wsc;
;         LAS float* d = scr + kk * 33 + 4 * n4; d[0] = v.x; d[1] = v.y; d[2] = v.z; d[3] = v.w; }
;     asm volatile("s_waitcnt lgkmcnt(0)" ::: "memory");
;     const int c = lane & 7;
; #pragma unroll
;     for (int j = 0; j < 4; ++j) { const int n = (lane >> 3) + 8 * j; const LAS float* s = scr + (8 * c) * 33 + n;
;         u32x4 o; o.x = pk2(s[0 * 33], s[1 * 33]); o.y = pk2(s[2 * 33], s[3 * 33]); o.z = pk2(s[4 * 33], s[5 * 33]); o.w = pk2(s[6 * 33], s[7 * 33]);
;         *(u32x4*)(WT + (size_t)wt_row(mode, row_off, n0 + n) * K + k0 + 8 * c) = o; }
;     asm volatile("s_waitcnt lgkmcnt(0)" ::: "memory");
; }
; __global__ void __launch_bounds__(512, 2) mega_fwd(Params p) {
;     ...
;             if (r < I_UK) { p0_transpose_item(INP(14), 128, 512, WSB(WS_WUK), 1.f, 0, scr, r, lane); continue; } r -= I_UK;
;             if (r < I_UV) { p0_transpose_item(INP(15), 128, 512, WSB(WS_WUV), 1.f, 0, scr, r, lane); continue; } r -= I_UV;
.LBB0_40:
	s_andn2_b64 vcc, exec, s[26:27]
	s_cbranch_vccnz .LBB0_42
	v_mov_b32_e32 v5, s41
	ds_read_b64 v[6:7], v5
	s_add_i32 s26, s47, 0xfffffab0
	s_add_i32 s27, s47, 0xfffffaa0
	s_cmp_lt_u32 s26, 16
	s_cselect_b32 s27, s26, s27
	s_cmp_gt_u32 s26, 15
	s_cselect_b32 s48, 64, 0
	s_lshl_b32 s26, s27, 5
	s_ashr_i32 s27, s26, 31
	s_waitcnt lgkmcnt(0)
	v_readfirstlane_b32 s52, v6
	s_lshl_b64 s[50:51], s[26:27], 2
	v_mov_b32_e32 v5, s31
	v_readfirstlane_b32 s49, v7
	s_add_u32 s50, s52, s50
	ds_read_b64 v[40:41], v5
	s_addc_u32 s51, s49, s51
	v_or_b32_e32 v5, s48, v8
	v_lshl_add_u64 v[6:7], s[50:51], 0, v[2:3]
	v_lshlrev_b32_e32 v36, 11, v5
	v_mov_b32_e32 v37, v3
	v_lshl_add_u64 v[36:37], v[6:7], 0, v[36:37]
	global_load_dwordx4 v[36:39], v[36:37], off
	v_or_b32_e32 v5, s48, v9
	v_mov_b32_e32 v43, v3
	v_lshlrev_b32_e32 v42, 11, v5
	v_lshl_add_u64 v[42:43], v[6:7], 0, v[42:43]
	v_or_b32_e32 v5, s48, v11
	v_or_b32_e32 v44, s26, v11
	v_or_b32_e32 v46, s26, v12
	s_waitcnt lgkmcnt(0)
	v_readfirstlane_b32 s27, v41
	v_ashrrev_i32_e32 v45, 31, v44
	v_ashrrev_i32_e32 v47, 31, v46
	s_waitcnt vmcnt(0)
	ds_write2_b32 v18, v36, v37 offset1:1
	ds_write2_b32 v18, v38, v39 offset0:2 offset1:3
	global_load_dwordx4 v[36:39], v[42:43], off
	v_mov_b32_e32 v43, v3
	v_lshlrev_b32_e32 v42, 11, v5
	v_lshl_add_u64 v[42:43], v[6:7], 0, v[42:43]
	v_or_b32_e32 v5, s48, v12
	s_waitcnt vmcnt(0) lgkmcnt(0)
	ds_write2_b32 v19, v36, v37 offset1:1
	ds_write2_b32 v20, v38, v39 offset1:1
	global_load_dwordx4 v[36:39], v[42:43], off
	v_mov_b32_e32 v43, v3
	v_lshlrev_b32_e32 v42, 11, v5
	v_lshl_add_u64 v[42:43], v[6:7], 0, v[42:43]
	v_or_b32_e32 v5, s48, v13
	s_waitcnt vmcnt(0) lgkmcnt(0)
	ds_write2_b32 v21, v36, v37 offset1:1
	ds_write2_b32 v22, v38, v39 offset1:1
	global_load_dwordx4 v[36:39], v[42:43], off
	v_mov_b32_e32 v43, v3
	v_lshlrev_b32_e32 v42, 11, v5
	v_lshl_add_u64 v[42:43], v[6:7], 0, v[42:43]
	v_or_b32_e32 v5, s48, v14
	s_waitcnt vmcnt(0) lgkmcnt(0)
	ds_write2_b32 v23, v36, v37 offset1:1
	ds_write2_b32 v24, v38, v39 offset1:1
	global_load_dwordx4 v[36:39], v[42:43], off
	v_mov_b32_e32 v43, v3
	v_lshlrev_b32_e32 v42, 11, v5
	v_lshl_add_u64 v[42:43], v[6:7], 0, v[42:43]
	v_or_b32_e32 v5, s48, v15
	s_waitcnt vmcnt(0) lgkmcnt(0)
	ds_write2_b32 v25, v36, v37 offset1:1
	ds_write2_b32 v26, v38, v39 offset1:1
	global_load_dwordx4 v[36:39], v[42:43], off
	v_mov_b32_e32 v43, v3
	v_lshlrev_b32_e32 v42, 11, v5
	v_lshl_add_u64 v[42:43], v[6:7], 0, v[42:43]
	v_or_b32_e32 v5, s48, v16
	s_lshl_b32 s48, s48, 1
	s_waitcnt vmcnt(0) lgkmcnt(0)
	ds_write2_b32 v27, v36, v37 offset1:1
	ds_write2_b32 v28, v38, v39 offset1:1
	global_load_dwordx4 v[36:39], v[42:43], off
	v_mov_b32_e32 v43, v3
	v_lshlrev_b32_e32 v42, 11, v5
	v_lshl_add_u64 v[6:7], v[6:7], 0, v[42:43]
	v_or_b32_e32 v42, s26, v9
	v_mov_b32_e32 v5, v3
	v_ashrrev_i32_e32 v43, 31, v42
	s_waitcnt vmcnt(0) lgkmcnt(0)
	ds_write2_b32 v29, v36, v37 offset1:1
	ds_write2_b32 v30, v38, v39 offset1:1
	global_load_dwordx4 v[36:39], v[6:7], off
	v_or_b32_e32 v6, s26, v8
	v_readfirstlane_b32 s26, v40
	s_add_u32 s26, s26, s48
	s_addc_u32 s27, s27, 0
	v_lshlrev_b64 v[40:41], 8, v[42:43]
	v_lshlrev_b64 v[42:43], 8, v[44:45]
	v_lshl_add_u64 v[44:45], s[26:27], 0, v[4:5]
	v_ashrrev_i32_e32 v7, 31, v6
	v_lshlrev_b64 v[6:7], 8, v[6:7]
	v_lshl_add_u64 v[44:45], v[44:45], 0, s[14:15]
	v_lshl_add_u64 v[6:7], v[44:45], 0, v[6:7]
	s_waitcnt vmcnt(0) lgkmcnt(0)
	ds_write2_b32 v31, v36, v37 offset1:1
	ds_write2_b32 v32, v38, v39 offset1:1
	s_waitcnt lgkmcnt(0)
	ds_read_b32 v5, v17
	ds_read_b32 v33, v17 offset:132
	ds_read_b32 v35, v17 offset:264
	ds_read_b32 v37, v17 offset:396
	ds_read_b32 v38, v17 offset:528
	ds_read_b32 v39, v17 offset:660
	ds_read_b32 v48, v17 offset:792
	ds_read_b32 v49, v17 offset:924
	s_waitcnt lgkmcnt(6)
	v_cvt_pk_bf16_f32 v36, v5, v33
	s_waitcnt lgkmcnt(4)
	v_cvt_pk_bf16_f32 v37, v35, v37
	s_waitcnt lgkmcnt(2)
	v_cvt_pk_bf16_f32 v38, v38, v39
	s_waitcnt lgkmcnt(0)
	v_cvt_pk_bf16_f32 v39, v48, v49
	global_store_dwordx4 v[6:7], v[36:39], off
	ds_read_b32 v5, v17 offset:32
	ds_read_b32 v33, v17 offset:164
	ds_read_b32 v35, v17 offset:296
	ds_read_b32 v37, v17 offset:428
	ds_read_b32 v38, v17 offset:560
	ds_read_b32 v39, v17 offset:692
	ds_read_b32 v48, v17 offset:824
	ds_read_b32 v49, v17 offset:956
	v_lshl_add_u64 v[6:7], v[44:45], 0, v[40:41]
	s_waitcnt lgkmcnt(0)
	v_cvt_pk_bf16_f32 v36, v5, v33
	v_cvt_pk_bf16_f32 v37, v35, v37
	v_cvt_pk_bf16_f32 v38, v38, v39
	v_cvt_pk_bf16_f32 v39, v48, v49
	global_store_dwordx4 v[6:7], v[36:39], off
	ds_read_b32 v5, v17 offset:64
	ds_read_b32 v33, v17 offset:196
	ds_read_b32 v35, v17 offset:328
	ds_read_b32 v37, v17 offset:460
	ds_read_b32 v38, v17 offset:592
	ds_read_b32 v39, v17 offset:724
	ds_read_b32 v40, v17 offset:856
	ds_read_b32 v41, v17 offset:988
	v_lshl_add_u64 v[6:7], v[44:45], 0, v[42:43]
	s_waitcnt lgkmcnt(0)
	v_cvt_pk_bf16_f32 v36, v5, v33
	v_cvt_pk_bf16_f32 v37, v35, v37
	v_cvt_pk_bf16_f32 v38, v38, v39
	v_cvt_pk_bf16_f32 v39, v40, v41
	global_store_dwordx4 v[6:7], v[36:39], off
	ds_read_b32 v5, v17 offset:96
	ds_read_b32 v33, v17 offset:228
	ds_read_b32 v35, v17 offset:360
	ds_read_b32 v37, v17 offset:492
	ds_read_b32 v38, v17 offset:624
	ds_read_b32 v39, v17 offset:756
	ds_read_b32 v40, v17 offset:888
	ds_read_b32 v41, v17 offset:1020
	v_lshlrev_b64 v[6:7], 8, v[46:47]
	s_waitcnt lgkmcnt(0)
	v_cvt_pk_bf16_f32 v36, v5, v33
	v_cvt_pk_bf16_f32 v37, v35, v37
	v_cvt_pk_bf16_f32 v38, v38, v39
	v_cvt_pk_bf16_f32 v39, v40, v41
	v_lshl_add_u64 v[6:7], v[44:45], 0, v[6:7]
	global_store_dwordx4 v[6:7], v[36:39], off
	s_waitcnt lgkmcnt(0)

; #define LAS __attribute__((address_space(3)))
; __device__ __forceinline__ unsigned pk2(float lo, float hi) { const f32x2 v = {lo, hi}; return __builtin_bit_cast(unsigned, __builtin_convertvector(v, bf16x2_t)); }
; #define INP(i) ((const float*)tab_get(lds, (i)))
; #define WSB(off) ((bf16*)((unsigned char*)tab_get(lds, 31) + (off)))
; __device__ __forceinline__ int wt_row(int mode, int row_off, int n) { if (mode == 1) { const int g = n >= NFF, f = g ? n - NFF : n; return 256 * (f >> 7) + 128 * g + (f & 127); } return row_off + n; }
;     const int nblk = N / 32, kb = item / nblk, nb = item % nblk, k0 = 64 * kb, n0 = 32 * nb;
; #pragma unroll
;     for (int i = 0; i < 8; ++i) { const int idx = lane + 64 * i, kk = idx >> 3, n4 = idx & 7; const f32x4 v = *(const f32x4*)(W + (size_t)(k0 + kk) * N + n0 + 4 * n4) * wsc;
;         LAS float* d = scr + kk * 33 + 4 * n4; d[0] = v.x; d[1] = v.y; d[2] = v.z; d[3] = v.w; }
;     asm volatile("s_waitcnt lgkmcnt(0)" ::: "memory");
;     const int c = lane & 7;
; #pragma unroll
;     for (int j = 0; j < 4; ++j) { const int n = (lane >> 3) + 8 * j; const LAS float* s = scr + (8 * c) * 33 + n;
;         u32x4 o; o.x = pk2(s[0 * 33], s[1 * 33]); o.y = pk2(s[2 * 33], s[3 * 33]); o.z = pk2(s[4 * 33], s[5 * 33]); o.w = pk2(s[6 * 33], s[7 * 33]);
;         *(u32x4*)(WT + (size_t)wt_row(mode, row_off, n0 + n) * K + k0 + 8 * c) = o; }
;     asm volatile("s_waitcnt lgkmcnt(0)" ::: "memory");
; }
; __global__ void __launch_bounds__(512, 2) mega_fwd(Params p) {
;     ...
;             if (r < I_UK) { p0_transpose_item(INP(14), 128, 512, WSB(WS_WUK), 1.f, 0, scr, r, lane); continue; } r -= I_UK;
.LBB0_43:
	s_andn2_b64 vcc, exec, s[26:27]
	s_cbranch_vccnz .LBB0_45
	v_mov_b32_e32 v5, s42
	ds_read_b64 v[6:7], v5
	s_add_i32 s26, s47, 0xfffffad0
	s_add_i32 s27, s47, 0xfffffac0
	s_cmp_lt_u32 s26, 16
	s_cselect_b32 s27, s26, s27
	s_cmp_gt_u32 s26, 15
	s_cselect_b32 s48, 64, 0
	s_lshl_b32 s26, s27, 5
	s_ashr_i32 s27, s26, 31
	s_waitcnt lgkmcnt(0)
	v_readfirstlane_b32 s52, v6
	s_lshl_b64 s[50:51], s[26:27], 2
	v_mov_b32_e32 v5, s31
	v_readfirstlane_b32 s49, v7
	s_add_u32 s50, s52, s50
	ds_read_b64 v[40:41], v5
	s_addc_u32 s51, s49, s51
	v_or_b32_e32 v5, s48, v8
	v_lshl_add_u64 v[6:7], s[50:51], 0, v[2:3]
	v_lshlrev_b32_e32 v36, 11, v5
	v_mov_b32_e32 v37, v3
	v_lshl_add_u64 v[36:37], v[6:7], 0, v[36:37]
	global_load_dwordx4 v[36:39], v[36:37], off
	v_or_b32_e32 v5, s48, v9
	v_mov_b32_e32 v43, v3
	v_lshlrev_b32_e32 v42, 11, v5
	v_lshl_add_u64 v[42:43], v[6:7], 0, v[42:43]
	v_or_b32_e32 v5, s48, v11
	v_or_b32_e32 v44, s26, v11
	v_or_b32_e32 v46, s26, v12
	s_waitcnt lgkmcnt(0)
	v_readfirstlane_b32 s27, v41
	v_ashrrev_i32_e32 v45, 31, v44
	v_ashrrev_i32_e32 v47, 31, v46
	s_waitcnt vmcnt(0)
	ds_write2_b32 v18, v36, v37 offset1:1
	ds_write2_b32 v18, v38, v39 offset0:2 offset1:3
	global_load_dwordx4 v[36:39], v[42:43], off
	v_mov_b32_e32 v43, v3
	v_lshlrev_b32_e32 v42, 11, v5
	v_lshl_add_u64 v[42:43], v[6:7], 0, v[42:43]
	v_or_b32_e32 v5, s48, v12
	s_waitcnt vmcnt(0) lgkmcnt(0)
	ds_write2_b32 v19, v36, v37 offset1:1
	ds_write2_b32 v20, v38, v39 offset1:1
	global_load_dwordx4 v[36:39], v[42:43], off
	v_mov_b32_e32 v43, v3
	v_lshlrev_b32_e32 v42, 11, v5
	v_lshl_add_u64 v[42:43], v[6:7], 0, v[42:43]
	v_or_b32_e32 v5, s48, v13
	s_waitcnt vmcnt(0) lgkmcnt(0)
	ds_write2_b32 v21, v36, v37 offset1:1
	ds_write2_b32 v22, v38, v39 offset1:1
	global_load_dwordx4 v[36:39], v[42:43], off
	v_mov_b32_e32 v43, v3
	v_lshlrev_b32_e32 v42, 11, v5
	v_lshl_add_u64 v[42:43], v[6:7], 0, v[42:43]
	v_or_b32_e32 v5, s48, v14
	s_waitcnt vmcnt(0) lgkmcnt(0)
	ds_write2_b32 v23, v36, v37 offset1:1
	ds_write2_b32 v24, v38, v39 offset1:1
	global_load_dwordx4 v[36:39], v[42:43], off
	v_mov_b32_e32 v43, v3
	v_lshlrev_b32_e32 v42, 11, v5
	v_lshl_add_u64 v[42:43], v[6:7], 0, v[42:43]
	v_or_b32_e32 v5, s48, v15
	s_waitcnt vmcnt(0) lgkmcnt(0)
	ds_write2_b32 v25, v36, v37 offset1:1
	ds_write2_b32 v26, v38, v39 offset1:1
	global_load_dwordx4 v[36:39], v[42:43], off
	v_mov_b32_e32 v43, v3
	v_lshlrev_b32_e32 v42, 11, v5
	v_lshl_add_u64 v[42:43], v[6:7], 0, v[42:43]
	v_or_b32_e32 v5, s48, v16
	s_lshl_b32 s48, s48, 1
	s_waitcnt vmcnt(0) lgkmcnt(0)
	ds_write2_b32 v27, v36, v37 offset1:1
	ds_write2_b32 v28, v38, v39 offset1:1
	global_load_dwordx4 v[36:39], v[42:43], off
	v_mov_b32_e32 v43, v3
	v_lshlrev_b32_e32 v42, 11, v5
	v_lshl_add_u64 v[6:7], v[6:7], 0, v[42:43]
	v_or_b32_e32 v42, s26, v9
	v_mov_b32_e32 v5, v3
	v_ashrrev_i32_e32 v43, 31, v42
	s_waitcnt vmcnt(0) lgkmcnt(0)
	ds_write2_b32 v29, v36, v37 offset1:1
	ds_write2_b32 v30, v38, v39 offset1:1
	global_load_dwordx4 v[36:39], v[6:7], off
	v_or_b32_e32 v6, s26, v8
	v_readfirstlane_b32 s26, v40
	s_add_u32 s26, s26, s48
	s_addc_u32 s27, s27, 0
	v_lshlrev_b64 v[40:41], 8, v[42:43]
	v_lshlrev_b64 v[42:43], 8, v[44:45]
	v_lshl_add_u64 v[44:45], s[26:27], 0, v[4:5]
	v_ashrrev_i32_e32 v7, 31, v6
	v_lshlrev_b64 v[6:7], 8, v[6:7]
	v_lshl_add_u64 v[44:45], v[44:45], 0, s[16:17]
	v_lshl_add_u64 v[6:7], v[44:45], 0, v[6:7]
	s_waitcnt vmcnt(0) lgkmcnt(0)
	ds_write2_b32 v31, v36, v37 offset1:1
	ds_write2_b32 v32, v38, v39 offset1:1
	s_waitcnt lgkmcnt(0)
	ds_read_b32 v5, v17
	ds_read_b32 v33, v17 offset:132
	ds_read_b32 v35, v17 offset:264
	ds_read_b32 v37, v17 offset:396
	ds_read_b32 v38, v17 offset:528
	ds_read_b32 v39, v17 offset:660
	ds_read_b32 v48, v17 offset:792
	ds_read_b32 v49, v17 offset:924
	s_waitcnt lgkmcnt(6)
	v_cvt_pk_bf16_f32 v36, v5, v33
	s_waitcnt lgkmcnt(4)
	v_cvt_pk_bf16_f32 v37, v35, v37
	s_waitcnt lgkmcnt(2)
	v_cvt_pk_bf16_f32 v38, v38, v39
	s_waitcnt lgkmcnt(0)
	v_cvt_pk_bf16_f32 v39, v48, v49
	global_store_dwordx4 v[6:7], v[36:39], off
	ds_read_b32 v5, v17 offset:32
	ds_read_b32 v33, v17 offset:164
	ds_read_b32 v35, v17 offset:296
	ds_read_b32 v37, v17 offset:428
	ds_read_b32 v38, v17 offset:560
	ds_read_b32 v39, v17 offset:692
	ds_read_b32 v48, v17 offset:824
	ds_read_b32 v49, v17 offset:956
	v_lshl_add_u64 v[6:7], v[44:45], 0, v[40:41]
	s_waitcnt lgkmcnt(0)
	v_cvt_pk_bf16_f32 v36, v5, v33
	v_cvt_pk_bf16_f32 v37, v35, v37
	v_cvt_pk_bf16_f32 v38, v38, v39
	v_cvt_pk_bf16_f32 v39, v48, v49
	global_store_dwordx4 v[6:7], v[36:39], off
	ds_read_b32 v5, v17 offset:64
	ds_read_b32 v33, v17 offset:196
	ds_read_b32 v35, v17 offset:328
	ds_read_b32 v37, v17 offset:460
	ds_read_b32 v38, v17 offset:592
	ds_read_b32 v39, v17 offset:724
	ds_read_b32 v40, v17 offset:856
	ds_read_b32 v41, v17 offset:988
	v_lshl_add_u64 v[6:7], v[44:45], 0, v[42:43]
	s_waitcnt lgkmcnt(0)
	v_cvt_pk_bf16_f32 v36, v5, v33
	v_cvt_pk_bf16_f32 v37, v35, v37
	v_cvt_pk_bf16_f32 v38, v38, v39
	v_cvt_pk_bf16_f32 v39, v40, v41
	global_store_dwordx4 v[6:7], v[36:39], off
	ds_read_b32 v5, v17 offset:96
	ds_read_b32 v33, v17 offset:228
	ds_read_b32 v35, v17 offset:360
	ds_read_b32 v37, v17 offset:492
	ds_read_b32 v38, v17 offset:624
	ds_read_b32 v39, v17 offset:756
	ds_read_b32 v40, v17 offset:888
	ds_read_b32 v41, v17 offset:1020
	v_lshlrev_b64 v[6:7], 8, v[46:47]
	s_waitcnt lgkmcnt(0)
	v_cvt_pk_bf16_f32 v36, v5, v33
	v_cvt_pk_bf16_f32 v37, v35, v37
	v_cvt_pk_bf16_f32 v38, v38, v39
	v_cvt_pk_bf16_f32 v39, v40, v41
	v_lshl_add_u64 v[6:7], v[44:45], 0, v[6:7]
	global_store_dwordx4 v[6:7], v[36:39], off
	s_waitcnt lgkmcnt(0)

; #define LAS __attribute__((address_space(3)))
; __device__ __forceinline__ unsigned pk2(float lo, float hi) { const f32x2 v = {lo, hi}; return __builtin_bit_cast(unsigned, __builtin_convertvector(v, bf16x2_t)); }
; #define INP(i) ((const float*)tab_get(lds, (i)))
; #define WSB(off) ((bf16*)((unsigned char*)tab_get(lds, 31) + (off)))
; __device__ __forceinline__ int wt_row(int mode, int row_off, int n) { if (mode == 1) { const int g = n >= NFF, f = g ? n - NFF : n; return 256 * (f >> 7) + 128 * g + (f & 127); } return row_off + n; }
;     const int nblk = N / 32, kb = item / nblk, nb = item % nblk, k0 = 64 * kb, n0 = 32 * nb;
; #pragma unroll
;     for (int i = 0; i < 8; ++i) { const int idx = lane + 64 * i, kk = idx >> 3, n4 = idx & 7; const f32x4 v = *(const f32x4*)(W + (size_t)(k0 + kk) * N + n0 + 4 * n4) * wsc;
;         LAS float* d = scr + kk * 33 + 4 * n4; d[0] = v.x; d[1] = v.y; d[2] = v.z; d[3] = v.w; }
;     asm volatile("s_waitcnt lgkmcnt(0)" ::: "memory");
;     const int c = lane & 7;
; #pragma unroll
;     for (int j = 0; j < 4; ++j) { const int n = (lane >> 3) + 8 * j; const LAS float* s = scr + (8 * c) * 33 + n;
;         u32x4 o; o.x = pk2(s[0 * 33], s[1 * 33]); o.y = pk2(s[2 * 33], s[3 * 33]); o.z = pk2(s[4 * 33], s[5 * 33]); o.w = pk2(s[6 * 33], s[7 * 33]);
;         *(u32x4*)(WT + (size_t)wt_row(mode, row_off, n0 + n) * K + k0 + 8 * c) = o; }
;     asm volatile("s_waitcnt lgkmcnt(0)" ::: "memory");
; }
; __global__ void __launch_bounds__(512, 2) mega_fwd(Params p) {
;     ...
;             if (r < I_UQ) { p0_transpose_item(INP(13), 256, 768, WSB(WS_WUQ), 0.10206207261596577f * LOG2E, 0, scr, r, lane); continue; } r -= I_UQ;
.LBB0_46:
	s_andn2_b64 vcc, exec, s[26:27]
	s_cbranch_vccnz .LBB0_48
	s_add_i32 s27, s47, 48
	v_mov_b32_e32 v5, s43
	s_and_b32 s26, s27, 0xff
	ds_read_b64 v[36:37], v5
	s_mulk_i32 s26, 0xab
	s_lshr_b32 s26, s26, 12
	s_mul_i32 s50, s26, 24
	s_sub_i32 s27, s27, s50
	s_and_b32 s50, s27, 0xff
	v_mov_b32_e32 v5, s31
	s_waitcnt lgkmcnt(0)
	v_readfirstlane_b32 s48, v36
	s_lshl_b32 s51, s26, 6
	s_lshl_b32 s27, s50, 5
	s_lshl_b32 s50, s50, 7
	ds_read_b64 v[6:7], v5
	v_readfirstlane_b32 s49, v37
	s_add_u32 s48, s48, s50
	v_or_b32_e32 v5, s51, v8
	s_addc_u32 s49, s49, 0
	v_mul_u32_u24_e32 v5, 0x300, v5
	v_lshl_add_u64 v[40:41], s[48:49], 0, v[2:3]
	v_lshlrev_b32_e32 v36, 2, v5
	v_mov_b32_e32 v37, v3
	v_lshl_add_u64 v[36:37], v[40:41], 0, v[36:37]
	global_load_dwordx4 v[36:39], v[36:37], off
	v_or_b32_e32 v5, s51, v9
	v_mul_u32_u24_e32 v5, 0x300, v5
	v_mov_b32_e32 v43, v3
	v_lshlrev_b32_e32 v42, 2, v5
	v_lshl_add_u64 v[42:43], v[40:41], 0, v[42:43]
	v_or_b32_e32 v5, s51, v11
	v_mul_u32_u24_e32 v5, 0x300, v5
	s_waitcnt lgkmcnt(0)
	v_readfirstlane_b32 s49, v6
	s_lshl_b32 s26, s26, 7
	v_readfirstlane_b32 s48, v7
	s_add_u32 s26, s49, s26
	v_or_b32_e32 v6, s27, v8
	v_or_b32_e32 v7, s27, v9
	v_or_b32_e32 v33, s27, v11
	v_or_b32_e32 v35, s27, v12
	s_addc_u32 s27, s48, 0
	v_lshlrev_b32_e32 v44, 9, v33
	v_mov_b32_e32 v45, v3
	v_mov_b32_e32 v47, v3
	s_waitcnt vmcnt(0)
	v_pk_mul_f32 v[36:37], v[36:37], s[18:19] op_sel_hi:[1,0]
	v_pk_mul_f32 v[38:39], v[38:39], s[18:19] op_sel_hi:[1,0]
	ds_write2_b32 v18, v36, v37 offset1:1
	ds_write2_b32 v18, v38, v39 offset0:2 offset1:3
	global_load_dwordx4 v[36:39], v[42:43], off
	v_mov_b32_e32 v43, v3
	v_lshlrev_b32_e32 v42, 2, v5
	v_lshl_add_u64 v[42:43], v[40:41], 0, v[42:43]
	v_or_b32_e32 v5, s51, v12
	v_mul_u32_u24_e32 v5, 0x300, v5
	s_waitcnt vmcnt(0) lgkmcnt(0)
	v_pk_mul_f32 v[36:37], v[36:37], s[18:19] op_sel_hi:[1,0]
	v_pk_mul_f32 v[38:39], v[38:39], s[18:19] op_sel_hi:[1,0]
	ds_write2_b32 v19, v36, v37 offset1:1
	ds_write2_b32 v20, v38, v39 offset1:1
	global_load_dwordx4 v[36:39], v[42:43], off
	v_mov_b32_e32 v43, v3
	v_lshlrev_b32_e32 v42, 2, v5
	v_lshl_add_u64 v[42:43], v[40:41], 0, v[42:43]
	v_or_b32_e32 v5, s51, v13
	v_mul_u32_u24_e32 v5, 0x300, v5
	s_waitcnt vmcnt(0) lgkmcnt(0)
	v_pk_mul_f32 v[36:37], v[36:37], s[18:19] op_sel_hi:[1,0]
	v_pk_mul_f32 v[38:39], v[38:39], s[18:19] op_sel_hi:[1,0]
	ds_write2_b32 v21, v36, v37 offset1:1
	ds_write2_b32 v22, v38, v39 offset1:1
	global_load_dwordx4 v[36:39], v[42:43], off
	v_mov_b32_e32 v43, v3
	v_lshlrev_b32_e32 v42, 2, v5
	v_lshl_add_u64 v[42:43], v[40:41], 0, v[42:43]
	v_or_b32_e32 v5, s51, v14
	v_mul_u32_u24_e32 v5, 0x300, v5
	s_waitcnt vmcnt(0) lgkmcnt(0)
	v_pk_mul_f32 v[36:37], v[36:37], s[18:19] op_sel_hi:[1,0]
	v_pk_mul_f32 v[38:39], v[38:39], s[18:19] op_sel_hi:[1,0]
	ds_write2_b32 v23, v36, v37 offset1:1
	ds_write2_b32 v24, v38, v39 offset1:1
	global_load_dwordx4 v[36:39], v[42:43], off
	v_mov_b32_e32 v43, v3
	v_lshlrev_b32_e32 v42, 2, v5
	v_lshl_add_u64 v[42:43], v[40:41], 0, v[42:43]
	v_or_b32_e32 v5, s51, v15
	v_mul_u32_u24_e32 v5, 0x300, v5
	s_waitcnt vmcnt(0) lgkmcnt(0)
	v_pk_mul_f32 v[36:37], v[36:37], s[18:19] op_sel_hi:[1,0]
	v_pk_mul_f32 v[38:39], v[38:39], s[18:19] op_sel_hi:[1,0]
	ds_write2_b32 v25, v36, v37 offset1:1
	ds_write2_b32 v26, v38, v39 offset1:1
	global_load_dwordx4 v[36:39], v[42:43], off
	v_mov_b32_e32 v43, v3
	v_lshlrev_b32_e32 v42, 2, v5
	v_lshl_add_u64 v[42:43], v[40:41], 0, v[42:43]
	v_or_b32_e32 v5, s51, v16
	v_mul_u32_u24_e32 v5, 0x300, v5
	s_waitcnt vmcnt(0) lgkmcnt(0)
	v_pk_mul_f32 v[36:37], v[36:37], s[18:19] op_sel_hi:[1,0]
	v_pk_mul_f32 v[38:39], v[38:39], s[18:19] op_sel_hi:[1,0]
	ds_write2_b32 v27, v36, v37 offset1:1
	ds_write2_b32 v28, v38, v39 offset1:1
	global_load_dwordx4 v[36:39], v[42:43], off
	v_mov_b32_e32 v43, v3
	v_lshlrev_b32_e32 v42, 2, v5
	v_lshl_add_u64 v[40:41], v[40:41], 0, v[42:43]
	v_mov_b32_e32 v5, v3
	v_lshlrev_b32_e32 v42, 9, v7
	s_waitcnt vmcnt(0) lgkmcnt(0)
	v_pk_mul_f32 v[36:37], v[36:37], s[18:19] op_sel_hi:[1,0]
	v_pk_mul_f32 v[38:39], v[38:39], s[18:19] op_sel_hi:[1,0]
	ds_write2_b32 v29, v36, v37 offset1:1
	ds_write2_b32 v30, v38, v39 offset1:1
	global_load_dwordx4 v[36:39], v[40:41], off
	v_lshlrev_b32_e32 v40, 9, v6
	v_lshl_add_u64 v[6:7], s[26:27], 0, v[4:5]
	v_mov_b32_e32 v41, v3
	v_lshl_add_u64 v[6:7], v[6:7], 0, s[20:21]
	v_lshl_add_u64 v[40:41], v[6:7], 0, v[40:41]
	s_waitcnt vmcnt(0) lgkmcnt(0)
	v_pk_mul_f32 v[36:37], v[36:37], s[18:19] op_sel_hi:[1,0]
	v_pk_mul_f32 v[38:39], v[38:39], s[18:19] op_sel_hi:[1,0]
	ds_write2_b32 v31, v36, v37 offset1:1
	ds_write2_b32 v32, v38, v39 offset1:1
	s_waitcnt lgkmcnt(0)
	ds_read_b32 v5, v17
	ds_read_b32 v33, v17 offset:132
	ds_read_b32 v37, v17 offset:264
	ds_read_b32 v38, v17 offset:396
	ds_read_b32 v39, v17 offset:528
	ds_read_b32 v46, v17 offset:660
	ds_read_b32 v48, v17 offset:792
	ds_read_b32 v49, v17 offset:924
	s_waitcnt lgkmcnt(6)
	v_cvt_pk_bf16_f32 v36, v5, v33
	s_waitcnt lgkmcnt(4)
	v_cvt_pk_bf16_f32 v37, v37, v38
	s_waitcnt lgkmcnt(2)
	v_cvt_pk_bf16_f32 v38, v39, v46
	s_waitcnt lgkmcnt(0)
	v_cvt_pk_bf16_f32 v39, v48, v49
	global_store_dwordx4 v[40:41], v[36:39], off
	ds_read_b32 v5, v17 offset:32
	ds_read_b32 v33, v17 offset:164
	ds_read_b32 v37, v17 offset:296
	ds_read_b32 v38, v17 offset:428
	ds_read_b32 v39, v17 offset:560
	ds_read_b32 v46, v17 offset:692
	ds_read_b32 v48, v17 offset:824
	ds_read_b32 v49, v17 offset:956
	v_lshl_add_u64 v[40:41], v[6:7], 0, v[42:43]
	s_waitcnt lgkmcnt(0)
	v_cvt_pk_bf16_f32 v36, v5, v33
	v_cvt_pk_bf16_f32 v37, v37, v38
	v_cvt_pk_bf16_f32 v38, v39, v46
	v_cvt_pk_bf16_f32 v39, v48, v49
	global_store_dwordx4 v[40:41], v[36:39], off
	ds_read_b32 v5, v17 offset:64
	ds_read_b32 v33, v17 offset:196
	ds_read_b32 v37, v17 offset:328
	ds_read_b32 v38, v17 offset:460
	ds_read_b32 v39, v17 offset:592
	ds_read_b32 v42, v17 offset:724
	ds_read_b32 v43, v17 offset:856
	ds_read_b32 v46, v17 offset:988
	v_lshl_add_u64 v[40:41], v[6:7], 0, v[44:45]
	s_waitcnt lgkmcnt(0)
	v_cvt_pk_bf16_f32 v36, v5, v33
	v_cvt_pk_bf16_f32 v37, v37, v38
	v_cvt_pk_bf16_f32 v38, v39, v42
	v_cvt_pk_bf16_f32 v39, v43, v46
	global_store_dwordx4 v[40:41], v[36:39], off
	ds_read_b32 v5, v17 offset:96
	ds_read_b32 v33, v17 offset:228
	ds_read_b32 v37, v17 offset:360
	ds_read_b32 v38, v17 offset:492
	ds_read_b32 v39, v17 offset:624
	ds_read_b32 v40, v17 offset:756
	ds_read_b32 v41, v17 offset:888
	ds_read_b32 v42, v17 offset:1020
	v_lshlrev_b32_e32 v46, 9, v35
	s_waitcnt lgkmcnt(0)
	v_cvt_pk_bf16_f32 v36, v5, v33
	v_cvt_pk_bf16_f32 v37, v37, v38
	v_cvt_pk_bf16_f32 v38, v39, v40
	v_cvt_pk_bf16_f32 v39, v41, v42
	v_lshl_add_u64 v[6:7], v[6:7], 0, v[46:47]
	global_store_dwordx4 v[6:7], v[36:39], off
	s_waitcnt lgkmcnt(0)

; #define LAS __attribute__((address_space(3)))
; __device__ __forceinline__ unsigned pk2(float lo, float hi) { const f32x2 v = {lo, hi}; return __builtin_bit_cast(unsigned, __builtin_convertvector(v, bf16x2_t)); }
; #define INP(i) ((const float*)tab_get(lds, (i)))
; #define WSB(off) ((bf16*)((unsigned char*)tab_get(lds, 31) + (off)))
; __device__ __forceinline__ int wt_row(int mode, int row_off, int n) { if (mode == 1) { const int g = n >= NFF, f = g ? n - NFF : n; return 256 * (f >> 7) + 128 * g + (f & 127); } return row_off + n; }
;     const int nblk = N / 32, kb = item / nblk, nb = item % nblk, k0 = 64 * kb, n0 = 32 * nb;
; #pragma unroll
;     for (int i = 0; i < 8; ++i) { const int idx = lane + 64 * i, kk = idx >> 3, n4 = idx & 7; const f32x4 v = *(const f32x4*)(W + (size_t)(k0 + kk) * N + n0 + 4 * n4) * wsc;
;         LAS float* d = scr + kk * 33 + 4 * n4; d[0] = v.x; d[1] = v.y; d[2] = v.z; d[3] = v.w; }
;     asm volatile("s_waitcnt lgkmcnt(0)" ::: "memory");
;     const int c = lane & 7;
; #pragma unroll
;     for (int j = 0; j < 4; ++j) { const int n = (lane >> 3) + 8 * j; const LAS float* s = scr + (8 * c) * 33 + n;
;         u32x4 o; o.x = pk2(s[0 * 33], s[1 * 33]); o.y = pk2(s[2 * 33], s[3 * 33]); o.z = pk2(s[4 * 33], s[5 * 33]); o.w = pk2(s[6 * 33], s[7 * 33]);
;         *(u32x4*)(WT + (size_t)wt_row(mode, row_off, n0 + n) * K + k0 + 8 * c) = o; }
;     asm volatile("s_waitcnt lgkmcnt(0)" ::: "memory");
; }
; __global__ void __launch_bounds__(512, 2) mega_fwd(Params p) {
;     ...
;             if (r < I_IN) { p0_transpose_item(INP(10), 1024, ZC_END, WSB(WS_WIN), 1.f, 0, scr, r, lane); continue; } r -= I_IN;
.LBB0_49:
	s_andn2_b64 vcc, exec, s[26:27]
	s_cbranch_vccnz .LBB0_10
	v_mov_b32_e32 v5, s45
	s_mul_hi_i32 s26, s47, 0x3531dec1
	ds_read_b64 v[6:7], v5
	s_lshr_b32 s48, s26, 31
	s_ashr_i32 s26, s26, 4
	s_add_i32 s48, s26, s48
	s_lshl_b32 s26, s48, 6
	s_mulk_i32 s48, 0xf660
	s_add_i32 s48, s9, s48
	s_ashr_i32 s49, s48, 31
	s_waitcnt lgkmcnt(0)
	v_readfirstlane_b32 s52, v6
	s_lshl_b64 s[50:51], s[48:49], 2
	v_readfirstlane_b32 s27, v7
	s_add_u32 s50, s52, s50
	v_mov_b32_e32 v5, s31
	s_addc_u32 s51, s27, s51
	ds_read_b64 v[40:41], v5
	v_lshl_add_u64 v[6:7], s[50:51], 0, v[2:3]
	v_or_b32_e32 v5, s26, v8
	v_mad_i64_i32 v[36:37], s[50:51], v5, s46, v[6:7]
	global_load_dwordx4 v[36:39], v[36:37], off
	v_or_b32_e32 v5, s26, v9
	v_mad_i64_i32 v[42:43], s[50:51], v5, s46, v[6:7]
	v_or_b32_e32 v5, s26, v11
	s_ashr_i32 s27, s26, 31
	s_waitcnt lgkmcnt(0)
	v_readfirstlane_b32 s49, v40
	s_waitcnt vmcnt(0)
	ds_write2_b32 v18, v36, v37 offset1:1
	ds_write2_b32 v18, v38, v39 offset0:2 offset1:3
	global_load_dwordx4 v[36:39], v[42:43], off
	v_mad_i64_i32 v[42:43], s[50:51], v5, s46, v[6:7]
	v_or_b32_e32 v5, s26, v12
	s_waitcnt vmcnt(0) lgkmcnt(0)
	ds_write2_b32 v19, v36, v37 offset1:1
	ds_write2_b32 v20, v38, v39 offset1:1
	global_load_dwordx4 v[36:39], v[42:43], off
	v_mad_i64_i32 v[42:43], s[50:51], v5, s46, v[6:7]
	v_or_b32_e32 v5, s26, v13
	s_waitcnt vmcnt(0) lgkmcnt(0)
	ds_write2_b32 v21, v36, v37 offset1:1
	ds_write2_b32 v22, v38, v39 offset1:1
	global_load_dwordx4 v[36:39], v[42:43], off
	v_mad_i64_i32 v[42:43], s[50:51], v5, s46, v[6:7]
	v_or_b32_e32 v5, s26, v14
	s_waitcnt vmcnt(0) lgkmcnt(0)
	ds_write2_b32 v23, v36, v37 offset1:1
	ds_write2_b32 v24, v38, v39 offset1:1
	global_load_dwordx4 v[36:39], v[42:43], off
	v_mad_i64_i32 v[42:43], s[50:51], v5, s46, v[6:7]
	v_or_b32_e32 v5, s26, v15
	s_waitcnt vmcnt(0) lgkmcnt(0)
	ds_write2_b32 v25, v36, v37 offset1:1
	ds_write2_b32 v26, v38, v39 offset1:1
	global_load_dwordx4 v[36:39], v[42:43], off
	v_mad_i64_i32 v[42:43], s[50:51], v5, s46, v[6:7]
	v_or_b32_e32 v5, s26, v16
	v_mad_i64_i32 v[6:7], s[50:51], v5, s46, v[6:7]
	s_lshl_b64 s[26:27], s[26:27], 1
	s_add_u32 s26, s49, s26
	v_mov_b32_e32 v5, v3
	s_waitcnt vmcnt(0) lgkmcnt(0)
	ds_write2_b32 v27, v36, v37 offset1:1
	ds_write2_b32 v28, v38, v39 offset1:1
	global_load_dwordx4 v[36:39], v[42:43], off
	s_waitcnt vmcnt(0) lgkmcnt(0)
	ds_write2_b32 v29, v36, v37 offset1:1
	ds_write2_b32 v30, v38, v39 offset1:1
	global_load_dwordx4 v[36:39], v[6:7], off
	v_add_u32_e32 v6, s48, v8
	v_readfirstlane_b32 s48, v41
	s_addc_u32 s27, s48, s27
	v_lshl_add_u64 v[46:47], s[26:27], 0, v[4:5]
	v_ashrrev_i32_e32 v7, 31, v6
	v_add_u32_e32 v40, 8, v6
	v_add_u32_e32 v42, 16, v6
	v_add_u32_e32 v44, 24, v6
	v_lshlrev_b64 v[6:7], 11, v[6:7]
	v_lshl_add_u64 v[46:47], v[46:47], 0, s[22:23]
	v_lshl_add_u64 v[6:7], v[46:47], 0, v[6:7]
	v_ashrrev_i32_e32 v41, 31, v40
	v_lshlrev_b64 v[40:41], 11, v[40:41]
	v_ashrrev_i32_e32 v43, 31, v42
	v_lshlrev_b64 v[42:43], 11, v[42:43]
	v_ashrrev_i32_e32 v45, 31, v44
	s_waitcnt vmcnt(0) lgkmcnt(0)
	ds_write2_b32 v31, v36, v37 offset1:1
	ds_write2_b32 v32, v38, v39 offset1:1
	s_waitcnt lgkmcnt(0)
	ds_read_b32 v5, v17
	ds_read_b32 v33, v17 offset:132
	ds_read_b32 v35, v17 offset:264
	ds_read_b32 v37, v17 offset:396
	ds_read_b32 v38, v17 offset:528
	ds_read_b32 v39, v17 offset:660
	ds_read_b32 v48, v17 offset:792
	ds_read_b32 v49, v17 offset:924
	s_waitcnt lgkmcnt(6)
	v_cvt_pk_bf16_f32 v36, v5, v33
	s_waitcnt lgkmcnt(4)
	v_cvt_pk_bf16_f32 v37, v35, v37
	s_waitcnt lgkmcnt(2)
	v_cvt_pk_bf16_f32 v38, v38, v39
	s_waitcnt lgkmcnt(0)
	v_cvt_pk_bf16_f32 v39, v48, v49
	global_store_dwordx4 v[6:7], v[36:39], off
	ds_read_b32 v5, v17 offset:32
	ds_read_b32 v33, v17 offset:164
	ds_read_b32 v35, v17 offset:296
	ds_read_b32 v37, v17 offset:428
	ds_read_b32 v38, v17 offset:560
	ds_read_b32 v39, v17 offset:692
	ds_read_b32 v48, v17 offset:824
	ds_read_b32 v49, v17 offset:956
	v_lshl_add_u64 v[6:7], v[46:47], 0, v[40:41]
	s_waitcnt lgkmcnt(0)
	v_cvt_pk_bf16_f32 v36, v5, v33
	v_cvt_pk_bf16_f32 v37, v35, v37
	v_cvt_pk_bf16_f32 v38, v38, v39
	v_cvt_pk_bf16_f32 v39, v48, v49
	global_store_dwordx4 v[6:7], v[36:39], off
	ds_read_b32 v5, v17 offset:64
	ds_read_b32 v33, v17 offset:196
	ds_read_b32 v35, v17 offset:328
	ds_read_b32 v37, v17 offset:460
	ds_read_b32 v38, v17 offset:592
	ds_read_b32 v39, v17 offset:724
	ds_read_b32 v40, v17 offset:856
	ds_read_b32 v41, v17 offset:988
	v_lshl_add_u64 v[6:7], v[46:47], 0, v[42:43]
	s_waitcnt lgkmcnt(0)
	v_cvt_pk_bf16_f32 v36, v5, v33
	v_cvt_pk_bf16_f32 v37, v35, v37
	v_cvt_pk_bf16_f32 v38, v38, v39
	v_cvt_pk_bf16_f32 v39, v40, v41
	global_store_dwordx4 v[6:7], v[36:39], off
	ds_read_b32 v5, v17 offset:96
	ds_read_b32 v33, v17 offset:228
	ds_read_b32 v35, v17 offset:360
	ds_read_b32 v37, v17 offset:492
	ds_read_b32 v38, v17 offset:624
	ds_read_b32 v39, v17 offset:756
	ds_read_b32 v40, v17 offset:888
	ds_read_b32 v41, v17 offset:1020
	v_lshlrev_b64 v[6:7], 11, v[44:45]
	s_waitcnt lgkmcnt(0)
	v_cvt_pk_bf16_f32 v36, v5, v33
	v_cvt_pk_bf16_f32 v37, v35, v37
	v_cvt_pk_bf16_f32 v38, v38, v39
	v_cvt_pk_bf16_f32 v39, v40, v41
	v_lshl_add_u64 v[6:7], v[46:47], 0, v[6:7]
	global_store_dwordx4 v[6:7], v[36:39], off
	s_waitcnt lgkmcnt(0)
	s_branch .LBB0_10

; #define WSB(off) ((bf16*)((unsigned char*)tab_get(lds, 31) + (off)))
; __global__ void __launch_bounds__(512, 2) mega_fwd(Params p) {
;     ...
;         { const int t_ = my_tid(lds); bf16* WIN = WSB(WS_WIN); for (int i = bx * 512 + t_; i < 96 * 128; i += G * 512) ((u32x4*)(WIN + (size_t)ZC_END * 1024))[i] = (u32x4){0u, 0u, 0u, 0u}; }
.LBB0_53:
	v_add_u32_e32 v6, s2, v6
	v_cmp_lt_i32_e32 vcc, s3, v6
	global_store_dwordx4 v[8:9], v[2:5], off
	s_or_b64 s[6:7], vcc, s[6:7]
	v_lshl_add_u64 v[8:9], v[8:9], 0, s[4:5]
	s_andn2_b64 exec, exec, s[6:7]
	s_cbranch_execnz .LBB0_53

; __device__ __forceinline__ unsigned pk2(float lo, float hi) { const f32x2 v = {lo, hi}; return __builtin_bit_cast(unsigned, __builtin_convertvector(v, bf16x2_t)); }
; __device__ __forceinline__ void rms_row_to_bf16(const float* xrow, const float* g, bf16* orow, int lane) {
;     const f32x4* xr = (const f32x4*)xrow + lane; f32x4 v[4]; float s = 0.f;
; #pragma unroll
;     for (int j = 0; j < 4; ++j) { v[j] = xr[64 * j]; s += (v[j].x * v[j].x + v[j].y * v[j].y) + (v[j].z * v[j].z + v[j].w * v[j].w); }
;     const float rstd = rsqrtf(wave_sum(s) * (1.f / DM) + EPS);
;     u32x2* o8 = (u32x2*)orow + lane;
; #pragma unroll
;     for (int j = 0; j < 4; ++j) { const f32x4 gg = ((const f32x4*)g)[lane + 64 * j]; u32x2 w; w.x = pk2(v[j].x * rstd * gg.x, v[j].y * rstd * gg.y); w.y = pk2(v[j].z * rstd * gg.z, v[j].w * rstd * gg.w); o8[64 * j] = w; }
; }
; __device__ __forceinline__ void rms_row2_to_bf16(const float* x0, const float* x1, const float* g, bf16* o0, bf16* o1, int lane) {
;     const f32x4* xr0 = (const f32x4*)x0 + lane; const f32x4* xr1 = (const f32x4*)x1 + lane; f32x4 v[4], w[4]; float s = 0.f, t = 0.f;
; #pragma unroll
;     for (int j = 0; j < 4; ++j) { v[j] = xr0[64 * j]; w[j] = xr1[64 * j]; }
; #pragma unroll
;     for (int j = 0; j < 4; ++j) { s += (v[j].x * v[j].x + v[j].y * v[j].y) + (v[j].z * v[j].z + v[j].w * v[j].w); t += (w[j].x * w[j].x + w[j].y * w[j].y) + (w[j].z * w[j].z + w[j].w * w[j].w); }
;     const float r0 = rsqrtf(wave_sum(s) * (1.f / DM) + EPS), r1 = rsqrtf(wave_sum(t) * (1.f / DM) + EPS);
;     u32x2* p0 = (u32x2*)o0 + lane; u32x2* p1 = (u32x2*)o1 + lane;
; #pragma unroll
;     for (int j = 0; j < 4; ++j) { const f32x4 gg = ((const f32x4*)g)[lane + 64 * j]; u32x2 a, b;
;         a.x = pk2(v[j].x * r0 * gg.x, v[j].y * r0 * gg.y); a.y = pk2(v[j].z * r0 * gg.z, v[j].w * r0 * gg.w); b.x = pk2(w[j].x * r1 * gg.x, w[j].y * r1 * gg.y); b.y = pk2(w[j].z * r1 * gg.z, w[j].w * r1 * gg.w);
;         p0[64 * j] = a; p1[64 * j] = b; }
; }
; __global__ void __launch_bounds__(512, 2) mega_fwd(Params p) {
;     ...
;           for (int m = gw; m < MP; m += 2 * NGW) { const int m1 = m + NGW;
;               if (m1 < MP) rms_row2_to_bf16(x_p + (size_t)m * DM, x_p + (size_t)m1 * DM, g, H + (size_t)m * DM, H + (size_t)m1 * DM, lane); else rms_row_to_bf16(x_p + (size_t)m * DM, g, H + (size_t)m * DM, lane); }
.LBB0_56:
	v_lshl_add_u64 v[2:3], s[0:1], 1, v[40:41]
	s_add_i32 s0, s8, s44
	s_cmpk_gt_i32 s0, 0x7fff
	global_store_dwordx2 v[2:3], v[4:5], off offset:1536
	s_cbranch_scc1 .LBB0_61
.LBB0_57:
	s_ashr_i32 s1, s0, 31
	s_add_i32 s8, s0, s44
	s_lshl_b64 s[0:1], s[0:1], 10
	s_cmpk_gt_i32 s8, 0x7fff
	s_mov_b64 s[10:11], -1
	v_lshl_add_u64 v[2:3], s[0:1], 2, v[38:39]
	v_lshl_add_u64 v[46:47], s[0:1], 1, v[40:41]
	s_cbranch_scc0 .LBB0_59
	global_load_dwordx4 v[4:7], v[2:3], off
	global_load_dwordx4 v[8:11], v[2:3], off offset:1024
	global_load_dwordx4 v[12:15], v[2:3], off offset:2048
	global_load_dwordx4 v[16:19], v[2:3], off offset:3072
	global_load_dwordx4 v[20:23], v[42:43], off
	s_mov_b64 s[10:11], 0
	s_waitcnt vmcnt(0) lgkmcnt(0)
	v_mul_f32_e32 v24, v5, v5
	v_mul_f32_e32 v25, v7, v7
	v_mul_f32_e32 v26, v9, v9
	v_mul_f32_e32 v27, v11, v11
	v_mul_f32_e32 v28, v13, v13
	v_mul_f32_e32 v29, v15, v15
	v_fmac_f32_e32 v24, v4, v4
	v_fmac_f32_e32 v25, v6, v6
	v_fmac_f32_e32 v26, v8, v8
	v_fmac_f32_e32 v27, v10, v10
	v_mul_f32_e32 v30, v17, v17
	v_mul_f32_e32 v31, v19, v19
	v_fmac_f32_e32 v28, v12, v12
	v_fmac_f32_e32 v29, v14, v14
	v_add_f32_e32 v24, v24, v25
	v_add_f32_e32 v25, v26, v27
	v_fmac_f32_e32 v30, v16, v16
	v_fmac_f32_e32 v31, v18, v18
	v_add_f32_e32 v26, v28, v29
	v_add_f32_e32 v24, v24, v25
	v_add_f32_e32 v27, v30, v31
	v_add_f32_e32 v24, v24, v26
	v_add_f32_e32 v24, v24, v27
	ds_swizzle_b32 v25, v24 offset:swizzle(SWAP,1)
	s_waitcnt lgkmcnt(0)
	v_add_f32_e32 v24, v24, v25
	ds_swizzle_b32 v25, v24 offset:swizzle(SWAP,2)
	s_waitcnt lgkmcnt(0)
	v_add_f32_e32 v24, v24, v25
	ds_swizzle_b32 v25, v24 offset:swizzle(SWAP,4)
	s_waitcnt lgkmcnt(0)
	v_add_f32_e32 v24, v24, v25
	ds_swizzle_b32 v25, v24 offset:swizzle(SWAP,8)
	s_waitcnt lgkmcnt(0)
	v_add_f32_e32 v24, v24, v25
	ds_swizzle_b32 v25, v24 offset:swizzle(SWAP,16)
	s_waitcnt lgkmcnt(0)
	v_add_f32_e32 v24, v24, v25
	v_mov_b32_e32 v25, v24
	s_nop 1
	v_permlane32_swap_b32_e32 v24, v25
	v_add_f32_e32 v24, v24, v25
	v_fmamk_f32 v24, v24, 0x3a800000, v44
	v_mul_f32_e32 v25, 0x4b800000, v24
	v_cmp_gt_f32_e32 vcc, s7, v24
	s_nop 1
	v_cndmask_b32_e32 v24, v24, v25, vcc
	v_rsq_f32_e32 v24, v24
	s_nop 0
	v_mul_f32_e32 v25, 0x45800000, v24
	v_cndmask_b32_e32 v24, v24, v25, vcc
	v_pk_mul_f32 v[4:5], v[4:5], v[24:25] op_sel_hi:[1,0]
	v_pk_mul_f32 v[6:7], v[6:7], v[24:25] op_sel_hi:[1,0]
	v_pk_mul_f32 v[4:5], v[20:21], v[4:5]
	v_pk_mul_f32 v[6:7], v[22:23], v[6:7]
	v_cvt_pk_bf16_f32 v4, v4, v5
	v_cvt_pk_bf16_f32 v5, v6, v7
	global_store_dwordx2 v[46:47], v[4:5], off
	global_load_dwordx4 v[4:7], v[42:43], off offset:1024
	v_pk_mul_f32 v[8:9], v[8:9], v[24:25] op_sel_hi:[1,0]
	v_pk_mul_f32 v[10:11], v[10:11], v[24:25] op_sel_hi:[1,0]
	s_waitcnt vmcnt(0) lgkmcnt(0)
	v_pk_mul_f32 v[4:5], v[4:5], v[8:9]
	v_pk_mul_f32 v[6:7], v[6:7], v[10:11]
	v_cvt_pk_bf16_f32 v4, v4, v5
	v_cvt_pk_bf16_f32 v5, v6, v7
	global_store_dwordx2 v[46:47], v[4:5], off offset:512
	global_load_dwordx4 v[4:7], v[42:43], off offset:2048
	v_pk_mul_f32 v[8:9], v[12:13], v[24:25] op_sel_hi:[1,0]
	v_pk_mul_f32 v[10:11], v[14:15], v[24:25] op_sel_hi:[1,0]
	s_waitcnt vmcnt(0) lgkmcnt(0)
	v_pk_mul_f32 v[4:5], v[4:5], v[8:9]
	v_pk_mul_f32 v[6:7], v[6:7], v[10:11]
	v_cvt_pk_bf16_f32 v4, v4, v5
	v_cvt_pk_bf16_f32 v5, v6, v7
	global_store_dwordx2 v[46:47], v[4:5], off offset:1024
	global_load_dwordx4 v[4:7], v[42:43], off offset:3072
	v_pk_mul_f32 v[8:9], v[16:17], v[24:25] op_sel_hi:[1,0]
	v_pk_mul_f32 v[10:11], v[18:19], v[24:25] op_sel_hi:[1,0]
	s_waitcnt vmcnt(0) lgkmcnt(0)
	v_pk_mul_f32 v[4:5], v[4:5], v[8:9]
	v_pk_mul_f32 v[6:7], v[6:7], v[10:11]
	v_cvt_pk_bf16_f32 v4, v4, v5
	v_cvt_pk_bf16_f32 v5, v6, v7
.LBB0_59:
	s_andn2_b64 vcc, exec, s[10:11]
	s_cbranch_vccnz .LBB0_56
	global_load_dwordx4 v[26:29], v[2:3], off
	global_load_dwordx4 v[18:21], v[2:3], off offset:1024
	global_load_dwordx4 v[6:9], v[2:3], off offset:3072
	global_load_dwordx4 v[14:17], v[2:3], off offset:2048
	s_ashr_i32 s9, s8, 31
	s_lshl_b64 s[0:1], s[8:9], 12
	v_lshl_add_u64 v[52:53], v[38:39], 0, s[0:1]
	global_load_dwordx4 v[30:33], v[52:53], off
	global_load_dwordx4 v[22:25], v[52:53], off offset:1024
	global_load_dwordx4 v[2:5], v[52:53], off offset:3072
	global_load_dwordx4 v[10:13], v[52:53], off offset:2048
	global_load_dwordx4 v[48:51], v[42:43], off
	s_lshl_b64 s[10:11], s[8:9], 11
	s_waitcnt vmcnt(0) lgkmcnt(0)
	v_pk_mul_f32 v[52:53], v[28:29], v[28:29]
	v_pk_mul_f32 v[54:55], v[26:27], v[26:27]
	v_pk_mul_f32 v[56:57], v[20:21], v[20:21]
	v_pk_mul_f32 v[58:59], v[18:19], v[18:19]
	v_pk_mov_b32 v[64:65], v[54:55], v[52:53] op_sel:[1,0]
	v_mov_b32_e32 v55, v53
	v_pk_mov_b32 v[52:53], v[58:59], v[56:57] op_sel:[1,0]
	v_mov_b32_e32 v59, v57
	v_mul_f32_e32 v60, v15, v15
	v_mul_f32_e32 v62, v17, v17
	v_pk_add_f32 v[54:55], v[64:65], v[54:55]
	v_pk_add_f32 v[52:53], v[52:53], v[58:59]
	v_mul_f32_e32 v35, v8, v8
	v_mul_f32_e32 v37, v9, v9
	v_mul_f32_e32 v45, v6, v6
	v_mul_f32_e32 v69, v7, v7
	v_pk_fma_f32 v[56:57], v[14:15], v[14:15], v[60:61] op_sel_hi:[1,1,0]
	v_pk_fma_f32 v[60:61], v[16:17], v[16:17], v[62:63] op_sel_hi:[1,1,0]
	v_pk_mul_f32 v[58:59], v[32:33], v[32:33]
	v_pk_mul_f32 v[62:63], v[30:31], v[30:31]
	v_pk_mul_f32 v[64:65], v[24:25], v[24:25]
	v_pk_mul_f32 v[66:67], v[22:23], v[22:23]
	v_pk_add_f32 v[54:55], v[54:55], v[54:55] op_sel:[0,1] op_sel_hi:[1,0]
	v_pk_add_f32 v[52:53], v[52:53], v[52:53] op_sel:[0,1] op_sel_hi:[1,0]
	v_mov_b32_e32 v57, v35
	v_mov_b32_e32 v61, v37
	v_pk_mov_b32 v[70:71], v[62:63], v[58:59] op_sel:[1,0]
	v_mov_b32_e32 v63, v59
	v_pk_mov_b32 v[58:59], v[66:67], v[64:65] op_sel:[1,0]
	v_mov_b32_e32 v67, v65
	v_mov_b32_e32 v55, v45
	v_mov_b32_e32 v53, v69
	v_pk_add_f32 v[56:57], v[56:57], v[60:61]
	v_mul_f32_e32 v60, v11, v11
	v_mul_f32_e32 v68, v13, v13
	v_pk_add_f32 v[62:63], v[70:71], v[62:63]
	v_pk_add_f32 v[58:59], v[58:59], v[66:67]
	v_pk_add_f32 v[52:53], v[54:55], v[52:53]
	v_mul_f32_e32 v35, v2, v2
	v_mul_f32_e32 v37, v4, v4
	v_mul_f32_e32 v72, v5, v5
	v_mul_f32_e32 v73, v3, v3
	v_pk_fma_f32 v[60:61], v[10:11], v[10:11], v[60:61] op_sel_hi:[1,1,0]
	v_pk_fma_f32 v[64:65], v[12:13], v[12:13], v[68:69] op_sel_hi:[1,1,0]
	v_pk_add_f32 v[52:53], v[52:53], v[56:57]
	v_pk_add_f32 v[54:55], v[62:63], v[62:63] op_sel:[0,1] op_sel_hi:[1,0]
	v_pk_add_f32 v[56:57], v[58:59], v[58:59] op_sel:[0,1] op_sel_hi:[1,0]
	v_mov_b32_e32 v61, v37
	v_mov_b32_e32 v65, v72
	v_mov_b32_e32 v55, v35
	v_mov_b32_e32 v57, v73
	v_pk_add_f32 v[58:59], v[60:61], v[64:65]
	v_add_f32_e32 v37, v52, v53
	v_pk_add_f32 v[52:53], v[54:55], v[56:57]
	ds_swizzle_b32 v35, v37 offset:swizzle(SWAP,1)
	v_pk_add_f32 v[52:53], v[52:53], v[58:59]
	s_waitcnt lgkmcnt(0)
; __device__ __forceinline__ unsigned pk2(float lo, float hi) { const f32x2 v = {lo, hi}; return __builtin_bit_cast(unsigned, __builtin_convertvector(v, bf16x2_t)); }
; __device__ __forceinline__ float wave_sum(float v) { v += swz_xor<1>(v); v += swz_xor<2>(v); v += swz_xor<4>(v); v += swz_xor<8>(v); v += swz_xor<16>(v); return half_sum(v); }
; __device__ __forceinline__ void rms_row2_to_bf16(const float* x0, const float* x1, const float* g, bf16* o0, bf16* o1, int lane) {
;     ...
;     const float r0 = rsqrtf(wave_sum(s) * (1.f / DM) + EPS), r1 = rsqrtf(wave_sum(t) * (1.f / DM) + EPS);
;     u32x2* p0 = (u32x2*)o0 + lane; u32x2* p1 = (u32x2*)o1 + lane;
; #pragma unroll
;     for (int j = 0; j < 4; ++j) { const f32x4 gg = ((const f32x4*)g)[lane + 64 * j]; u32x2 a, b;
;         a.x = pk2(v[j].x * r0 * gg.x, v[j].y * r0 * gg.y); a.y = pk2(v[j].z * r0 * gg.z, v[j].w * r0 * gg.w); b.x = pk2(w[j].x * r1 * gg.x, w[j].y * r1 * gg.y); b.y = pk2(w[j].z * r1 * gg.z, w[j].w * r1 * gg.w);
;         p0[64 * j] = a; p1[64 * j] = b; }
	v_add_f32_e32 v35, v37, v35
	v_add_f32_e32 v45, v52, v53
	ds_swizzle_b32 v52, v45 offset:swizzle(SWAP,1)
	ds_swizzle_b32 v37, v35 offset:swizzle(SWAP,2)
	s_waitcnt lgkmcnt(1)
	v_add_f32_e32 v45, v45, v52
	ds_swizzle_b32 v52, v45 offset:swizzle(SWAP,2)
	s_waitcnt lgkmcnt(1)
	v_add_f32_e32 v35, v35, v37
	ds_swizzle_b32 v37, v35 offset:swizzle(SWAP,4)
	s_waitcnt lgkmcnt(1)
	v_add_f32_e32 v45, v45, v52
	ds_swizzle_b32 v52, v45 offset:swizzle(SWAP,4)
	s_waitcnt lgkmcnt(1)
	v_add_f32_e32 v35, v35, v37
	ds_swizzle_b32 v37, v35 offset:swizzle(SWAP,8)
	s_waitcnt lgkmcnt(1)
	v_add_f32_e32 v45, v45, v52
	ds_swizzle_b32 v52, v45 offset:swizzle(SWAP,8)
	s_waitcnt lgkmcnt(1)
	v_add_f32_e32 v35, v35, v37
	ds_swizzle_b32 v37, v35 offset:swizzle(SWAP,16)
	s_waitcnt lgkmcnt(1)
	v_add_f32_e32 v45, v45, v52
	ds_swizzle_b32 v52, v45 offset:swizzle(SWAP,16)
	s_waitcnt lgkmcnt(1)
	v_add_f32_e32 v53, v35, v37
	v_mov_b32_e32 v55, v53
	s_nop 1
	v_permlane32_swap_b32_e32 v53, v55
	s_waitcnt lgkmcnt(0)
	v_add_f32_e32 v52, v45, v52
	v_mov_b32_e32 v54, v52
	s_nop 1
	v_permlane32_swap_b32_e32 v52, v54
	v_pk_add_f32 v[52:53], v[52:53], v[54:55]
	s_nop 0
	v_pk_fma_f32 v[52:53], v[52:53], s[6:7], v[44:45] op_sel_hi:[1,0,0]
	s_nop 0
	v_mul_f32_e32 v35, 0x4b800000, v53
	v_cmp_gt_f32_e32 vcc, s7, v53
	v_mul_f32_e32 v37, 0x4b800000, v52
	v_cmp_gt_f32_e64 s[0:1], s7, v52
	v_cndmask_b32_e32 v35, v53, v35, vcc
	v_rsq_f32_e32 v35, v35
	v_cndmask_b32_e64 v37, v52, v37, s[0:1]
	v_rsq_f32_e32 v37, v37
	v_lshl_add_u64 v[52:53], v[40:41], 0, s[10:11]
	v_mul_f32_e32 v45, 0x45800000, v35
	v_cndmask_b32_e32 v54, v35, v45, vcc
	v_mul_f32_e32 v55, 0x45800000, v37
	v_cndmask_b32_e64 v56, v37, v55, s[0:1]
	v_pk_mul_f32 v[26:27], v[26:27], v[54:55] op_sel_hi:[1,0]
	v_pk_mul_f32 v[28:29], v[28:29], v[54:55] op_sel_hi:[1,0]
	v_pk_mul_f32 v[30:31], v[30:31], v[56:57] op_sel_hi:[1,0]
	v_pk_mul_f32 v[32:33], v[32:33], v[56:57] op_sel_hi:[1,0]
	v_pk_mul_f32 v[26:27], v[48:49], v[26:27]
	v_pk_mul_f32 v[28:29], v[50:51], v[28:29]
	v_pk_mul_f32 v[30:31], v[48:49], v[30:31]
	v_pk_mul_f32 v[32:33], v[50:51], v[32:33]
	v_cvt_pk_bf16_f32 v26, v26, v27
	v_cvt_pk_bf16_f32 v27, v28, v29
	v_cvt_pk_bf16_f32 v28, v30, v31
	v_cvt_pk_bf16_f32 v29, v32, v33
	global_store_dwordx2 v[46:47], v[26:27], off
	global_store_dwordx2 v[52:53], v[28:29], off
	global_load_dwordx4 v[26:29], v[42:43], off offset:1024
	v_pk_mul_f32 v[18:19], v[18:19], v[54:55] op_sel_hi:[1,0]
	v_pk_mul_f32 v[20:21], v[20:21], v[54:55] op_sel_hi:[1,0]
	v_pk_mul_f32 v[22:23], v[22:23], v[56:57] op_sel_hi:[1,0]
	v_pk_mul_f32 v[24:25], v[24:25], v[56:57] op_sel_hi:[1,0]
	v_pk_mul_f32 v[14:15], v[14:15], v[54:55] op_sel_hi:[1,0]
	v_pk_mul_f32 v[16:17], v[16:17], v[54:55] op_sel_hi:[1,0]
	v_pk_mul_f32 v[10:11], v[10:11], v[56:57] op_sel_hi:[1,0]
	v_pk_mul_f32 v[12:13], v[12:13], v[56:57] op_sel_hi:[1,0]
	v_pk_mul_f32 v[6:7], v[6:7], v[54:55] op_sel_hi:[1,0]
	v_pk_mul_f32 v[8:9], v[8:9], v[54:55] op_sel_hi:[1,0]
	v_pk_mul_f32 v[2:3], v[2:3], v[56:57] op_sel_hi:[1,0]
	v_pk_mul_f32 v[4:5], v[4:5], v[56:57] op_sel_hi:[1,0]
	s_lshl_b64 s[0:1], s[8:9], 10
	s_waitcnt vmcnt(0) lgkmcnt(0)
	v_pk_mul_f32 v[18:19], v[18:19], v[26:27]
	v_pk_mul_f32 v[20:21], v[20:21], v[28:29]
	v_pk_mul_f32 v[22:23], v[26:27], v[22:23]
	v_pk_mul_f32 v[24:25], v[28:29], v[24:25]
	v_cvt_pk_bf16_f32 v18, v18, v19
	v_cvt_pk_bf16_f32 v19, v20, v21
	v_cvt_pk_bf16_f32 v20, v22, v23
	v_cvt_pk_bf16_f32 v21, v24, v25
	global_store_dwordx2 v[46:47], v[18:19], off offset:512
	global_store_dwordx2 v[52:53], v[20:21], off offset:512
	global_load_dwordx4 v[18:21], v[42:43], off offset:2048
	s_waitcnt vmcnt(0) lgkmcnt(0)
	v_pk_mul_f32 v[14:15], v[14:15], v[18:19]
	v_pk_mul_f32 v[16:17], v[16:17], v[20:21]
	v_pk_mul_f32 v[10:11], v[18:19], v[10:11]
	v_pk_mul_f32 v[12:13], v[20:21], v[12:13]
	v_cvt_pk_bf16_f32 v14, v14, v15
	v_cvt_pk_bf16_f32 v15, v16, v17
	v_cvt_pk_bf16_f32 v10, v10, v11
	v_cvt_pk_bf16_f32 v11, v12, v13
	global_store_dwordx2 v[46:47], v[14:15], off offset:1024
	global_store_dwordx2 v[52:53], v[10:11], off offset:1024
	global_load_dwordx4 v[10:13], v[42:43], off offset:3072
	s_waitcnt vmcnt(0) lgkmcnt(0)
	v_pk_mul_f32 v[6:7], v[6:7], v[10:11]
	v_pk_mul_f32 v[8:9], v[8:9], v[12:13]
	v_pk_mul_f32 v[2:3], v[2:3], v[10:11]
	v_pk_mul_f32 v[10:11], v[4:5], v[12:13]
	v_cvt_pk_bf16_f32 v6, v6, v7
	v_cvt_pk_bf16_f32 v7, v8, v9
	v_cvt_pk_bf16_f32 v4, v2, v3
	v_cvt_pk_bf16_f32 v5, v10, v11
	global_store_dwordx2 v[46:47], v[6:7], off offset:1536
	s_branch .LBB0_56

; __device__ __forceinline__ unsigned pk2(float lo, float hi) { const f32x2 v = {lo, hi}; return __builtin_bit_cast(unsigned, __builtin_convertvector(v, bf16x2_t)); }
; __device__ __forceinline__ float wave_sum(float v) { v += swz_xor<1>(v); v += swz_xor<2>(v); v += swz_xor<4>(v); v += swz_xor<8>(v); v += swz_xor<16>(v); return half_sum(v); }
; __device__ __forceinline__ void rms_row_to_bf16(const float* xrow, const float* g, bf16* orow, int lane) {
;     const f32x4* xr = (const f32x4*)xrow + lane; f32x4 v[4]; float s = 0.f;
; #pragma unroll
;     for (int j = 0; j < 4; ++j) { v[j] = xr[64 * j]; s += (v[j].x * v[j].x + v[j].y * v[j].y) + (v[j].z * v[j].z + v[j].w * v[j].w); }
;     const float rstd = rsqrtf(wave_sum(s) * (1.f / DM) + EPS);
;     u32x2* o8 = (u32x2*)orow + lane;
; #pragma unroll
;     for (int j = 0; j < 4; ++j) { const f32x4 gg = ((const f32x4*)g)[lane + 64 * j]; u32x2 w; w.x = pk2(v[j].x * rstd * gg.x, v[j].y * rstd * gg.y); w.y = pk2(v[j].z * rstd * gg.z, v[j].w * rstd * gg.w); o8[64 * j] = w; }
; }
; __global__ void __launch_bounds__(512, 2) mega_fwd(Params p) {
;     ...
;           for (int m = gw; m < MS; m += NGW) rms_row_to_bf16(x_s + (size_t)m * DM, g, H + (size_t)(MP + m) * DM, lane); }
.LBB0_63:
	global_load_dwordx4 v[10:13], v[6:7], off
	global_load_dwordx4 v[14:17], v[6:7], off offset:1024
	global_load_dwordx4 v[18:21], v[6:7], off offset:2048
	global_load_dwordx4 v[22:25], v[6:7], off offset:3072
	global_load_dwordx4 v[26:29], v[4:5], off
	s_add_i32 s4, s3, 0x8000
	s_ashr_i32 s5, s4, 31
	s_lshl_b64 s[4:5], s[4:5], 11
	v_lshl_add_u64 v[30:31], v[2:3], 0, s[4:5]
	s_add_i32 s3, s3, s44
	v_lshl_add_u64 v[6:7], v[6:7], 0, s[0:1]
	s_cmpk_gt_i32 s3, 0x1ff
	s_waitcnt vmcnt(0) lgkmcnt(0)
	v_mul_f32_e32 v9, v11, v11
	v_mul_f32_e32 v32, v13, v13
	v_mul_f32_e32 v33, v15, v15
	v_mul_f32_e32 v35, v17, v17
	v_mul_f32_e32 v37, v19, v19
	v_mul_f32_e32 v38, v21, v21
	v_fmac_f32_e32 v9, v10, v10
	v_fmac_f32_e32 v32, v12, v12
	v_fmac_f32_e32 v33, v14, v14
	v_fmac_f32_e32 v35, v16, v16
	v_mul_f32_e32 v39, v23, v23
	v_mul_f32_e32 v40, v25, v25
	v_fmac_f32_e32 v37, v18, v18
	v_fmac_f32_e32 v38, v20, v20
	v_add_f32_e32 v9, v9, v32
	v_add_f32_e32 v32, v33, v35
	v_fmac_f32_e32 v39, v22, v22
	v_fmac_f32_e32 v40, v24, v24
	v_add_f32_e32 v33, v37, v38
	v_add_f32_e32 v9, v9, v32
	v_add_f32_e32 v35, v39, v40
	v_add_f32_e32 v9, v9, v33
	v_add_f32_e32 v9, v9, v35
	ds_swizzle_b32 v32, v9 offset:swizzle(SWAP,1)
	s_waitcnt lgkmcnt(0)
	v_add_f32_e32 v9, v9, v32
	ds_swizzle_b32 v32, v9 offset:swizzle(SWAP,2)
	s_waitcnt lgkmcnt(0)
	v_add_f32_e32 v9, v9, v32
	ds_swizzle_b32 v32, v9 offset:swizzle(SWAP,4)
	s_waitcnt lgkmcnt(0)
	v_add_f32_e32 v9, v9, v32
	ds_swizzle_b32 v32, v9 offset:swizzle(SWAP,8)
	s_waitcnt lgkmcnt(0)
	v_add_f32_e32 v9, v9, v32
	ds_swizzle_b32 v32, v9 offset:swizzle(SWAP,16)
	s_waitcnt lgkmcnt(0)
	v_add_f32_e32 v9, v9, v32
	v_mov_b32_e32 v32, v9
	s_nop 1
	v_permlane32_swap_b32_e32 v9, v32
	v_add_f32_e32 v9, v9, v32
	v_fmamk_f32 v9, v9, 0x3a800000, v8
	v_mul_f32_e32 v32, 0x4b800000, v9
	v_cmp_gt_f32_e32 vcc, s2, v9
	s_nop 1
	v_cndmask_b32_e32 v9, v9, v32, vcc
	v_rsq_f32_e32 v9, v9
	s_nop 0
	v_mul_f32_e32 v32, 0x45800000, v9
	v_cndmask_b32_e32 v32, v9, v32, vcc
	v_pk_mul_f32 v[10:11], v[10:11], v[32:33] op_sel_hi:[1,0]
	v_pk_mul_f32 v[12:13], v[12:13], v[32:33] op_sel_hi:[1,0]
	v_pk_mul_f32 v[10:11], v[26:27], v[10:11]
	v_pk_mul_f32 v[12:13], v[28:29], v[12:13]
	v_cvt_pk_bf16_f32 v10, v10, v11
	v_cvt_pk_bf16_f32 v11, v12, v13
	global_store_dwordx2 v[30:31], v[10:11], off
	global_load_dwordx4 v[10:13], v[4:5], off offset:1024
	v_pk_mul_f32 v[14:15], v[14:15], v[32:33] op_sel_hi:[1,0]
	v_pk_mul_f32 v[16:17], v[16:17], v[32:33] op_sel_hi:[1,0]
	s_waitcnt vmcnt(0) lgkmcnt(0)
	v_pk_mul_f32 v[10:11], v[10:11], v[14:15]
	v_pk_mul_f32 v[12:13], v[12:13], v[16:17]
	v_cvt_pk_bf16_f32 v10, v10, v11
	v_cvt_pk_bf16_f32 v11, v12, v13
	global_store_dwordx2 v[30:31], v[10:11], off offset:512
	global_load_dwordx4 v[10:13], v[4:5], off offset:2048
	v_pk_mul_f32 v[14:15], v[18:19], v[32:33] op_sel_hi:[1,0]
	v_pk_mul_f32 v[16:17], v[20:21], v[32:33] op_sel_hi:[1,0]
	s_waitcnt vmcnt(0) lgkmcnt(0)
	v_pk_mul_f32 v[10:11], v[10:11], v[14:15]
	v_pk_mul_f32 v[12:13], v[12:13], v[16:17]
	v_cvt_pk_bf16_f32 v10, v10, v11
	v_cvt_pk_bf16_f32 v11, v12, v13
	global_store_dwordx2 v[30:31], v[10:11], off offset:1024
	global_load_dwordx4 v[10:13], v[4:5], off offset:3072
	v_pk_mul_f32 v[14:15], v[22:23], v[32:33] op_sel_hi:[1,0]
	v_pk_mul_f32 v[16:17], v[24:25], v[32:33] op_sel_hi:[1,0]
	s_waitcnt vmcnt(0) lgkmcnt(0)
	v_pk_mul_f32 v[10:11], v[10:11], v[14:15]
	v_pk_mul_f32 v[12:13], v[12:13], v[16:17]
	v_cvt_pk_bf16_f32 v10, v10, v11
	v_cvt_pk_bf16_f32 v11, v12, v13
	global_store_dwordx2 v[30:31], v[10:11], off offset:1536
	s_cbranch_scc0 .LBB0_63

; __device__ __forceinline__ unsigned pk2(float lo, float hi) { const f32x2 v = {lo, hi}; return __builtin_bit_cast(unsigned, __builtin_convertvector(v, bf16x2_t)); }
; __device__ __forceinline__ float wave_sum(float v) { v += swz_xor<1>(v); v += swz_xor<2>(v); v += swz_xor<4>(v); v += swz_xor<8>(v); v += swz_xor<16>(v); return half_sum(v); }
; #define INP(i) ((const float*)tab_get(lds, (i)))
; #define WSB(off) ((bf16*)((unsigned char*)tab_get(lds, 31) + (off)))
; __device__ __forceinline__ void rms_row_to_bf16(const float* xrow, const float* g, bf16* orow, int lane) {
;     const f32x4* xr = (const f32x4*)xrow + lane; f32x4 v[4]; float s = 0.f;
; #pragma unroll
;     for (int j = 0; j < 4; ++j) { v[j] = xr[64 * j]; s += (v[j].x * v[j].x + v[j].y * v[j].y) + (v[j].z * v[j].z + v[j].w * v[j].w); }
;     const float rstd = rsqrtf(wave_sum(s) * (1.f / DM) + EPS);
;     u32x2* o8 = (u32x2*)orow + lane;
; #pragma unroll
;     for (int j = 0; j < 4; ++j) { const f32x4 gg = ((const f32x4*)g)[lane + 64 * j]; u32x2 w; w.x = pk2(v[j].x * rstd * gg.x, v[j].y * rstd * gg.y); w.y = pk2(v[j].z * rstd * gg.z, v[j].w * rstd * gg.w); o8[64 * j] = w; }
; }
; __global__ void __launch_bounds__(512, 2) mega_fwd(Params p) {
;     ...
;         { const float* mem_p = INP(8); const float* g = INP(19); bf16* MN = WSB(WS_MN);
;           for (int m = gw; m < 512; m += NGW) rms_row_to_bf16(mem_p + (size_t)m * DM, g, MN + (size_t)m * DM, lane); }
.LBB0_66:
	global_load_dwordx4 v[10:13], v[6:7], off
	global_load_dwordx4 v[14:17], v[6:7], off offset:1024
	global_load_dwordx4 v[18:21], v[6:7], off offset:2048
	global_load_dwordx4 v[22:25], v[6:7], off offset:3072
	global_load_dwordx4 v[26:29], v[2:3], off
	s_add_i32 s1, s1, s44
	v_lshl_add_u64 v[6:7], v[6:7], 0, s[4:5]
	s_cmpk_gt_i32 s1, 0x1ff
	s_waitcnt vmcnt(0) lgkmcnt(0)
	v_mul_f32_e32 v9, v11, v11
	v_mul_f32_e32 v30, v13, v13
	v_mul_f32_e32 v31, v15, v15
	v_mul_f32_e32 v32, v17, v17
	v_mul_f32_e32 v33, v19, v19
	v_mul_f32_e32 v34, v21, v21
	v_fmac_f32_e32 v9, v10, v10
	v_fmac_f32_e32 v30, v12, v12
	v_fmac_f32_e32 v31, v14, v14
	v_fmac_f32_e32 v32, v16, v16
	v_mul_f32_e32 v35, v23, v23
	v_mul_f32_e32 v36, v25, v25
	v_fmac_f32_e32 v33, v18, v18
	v_fmac_f32_e32 v34, v20, v20
	v_add_f32_e32 v9, v9, v30
	v_add_f32_e32 v30, v31, v32
	v_fmac_f32_e32 v35, v22, v22
	v_fmac_f32_e32 v36, v24, v24
	v_add_f32_e32 v31, v33, v34
	v_add_f32_e32 v9, v9, v30
	v_add_f32_e32 v32, v35, v36
	v_add_f32_e32 v9, v9, v31
	v_add_f32_e32 v9, v9, v32
	ds_swizzle_b32 v30, v9 offset:swizzle(SWAP,1)
	s_waitcnt lgkmcnt(0)
	v_add_f32_e32 v9, v9, v30
	ds_swizzle_b32 v30, v9 offset:swizzle(SWAP,2)
	s_waitcnt lgkmcnt(0)
	v_add_f32_e32 v9, v9, v30
	ds_swizzle_b32 v30, v9 offset:swizzle(SWAP,4)
	s_waitcnt lgkmcnt(0)
	v_add_f32_e32 v9, v9, v30
	ds_swizzle_b32 v30, v9 offset:swizzle(SWAP,8)
	s_waitcnt lgkmcnt(0)
	v_add_f32_e32 v9, v9, v30
	ds_swizzle_b32 v30, v9 offset:swizzle(SWAP,16)
	s_waitcnt lgkmcnt(0)
	v_add_f32_e32 v9, v9, v30
	v_mov_b32_e32 v30, v9
	s_nop 1
	v_permlane32_swap_b32_e32 v9, v30
	v_add_f32_e32 v9, v9, v30
	v_fmamk_f32 v9, v9, 0x3a800000, v8
	v_mul_f32_e32 v30, 0x4b800000, v9
	v_cmp_gt_f32_e32 vcc, s0, v9
	s_nop 1
	v_cndmask_b32_e32 v9, v9, v30, vcc
	v_rsq_f32_e32 v9, v9
	s_nop 0
	v_mul_f32_e32 v30, 0x45800000, v9
	v_cndmask_b32_e32 v30, v9, v30, vcc
	v_pk_mul_f32 v[10:11], v[10:11], v[30:31] op_sel_hi:[1,0]
	v_pk_mul_f32 v[12:13], v[12:13], v[30:31] op_sel_hi:[1,0]
	v_pk_mul_f32 v[10:11], v[26:27], v[10:11]
	v_pk_mul_f32 v[12:13], v[28:29], v[12:13]
	v_cvt_pk_bf16_f32 v10, v10, v11
	v_cvt_pk_bf16_f32 v11, v12, v13
	global_store_dwordx2 v[4:5], v[10:11], off
	global_load_dwordx4 v[10:13], v[2:3], off offset:1024
	v_pk_mul_f32 v[14:15], v[14:15], v[30:31] op_sel_hi:[1,0]
	v_pk_mul_f32 v[16:17], v[16:17], v[30:31] op_sel_hi:[1,0]
	s_waitcnt vmcnt(0) lgkmcnt(0)
	v_pk_mul_f32 v[10:11], v[10:11], v[14:15]
	v_pk_mul_f32 v[12:13], v[12:13], v[16:17]
	v_cvt_pk_bf16_f32 v10, v10, v11
	v_cvt_pk_bf16_f32 v11, v12, v13
	global_store_dwordx2 v[4:5], v[10:11], off offset:512
	global_load_dwordx4 v[10:13], v[2:3], off offset:2048
	v_pk_mul_f32 v[14:15], v[18:19], v[30:31] op_sel_hi:[1,0]
	v_pk_mul_f32 v[16:17], v[20:21], v[30:31] op_sel_hi:[1,0]
	s_waitcnt vmcnt(0) lgkmcnt(0)
	v_pk_mul_f32 v[10:11], v[10:11], v[14:15]
	v_pk_mul_f32 v[12:13], v[12:13], v[16:17]
	v_cvt_pk_bf16_f32 v10, v10, v11
	v_cvt_pk_bf16_f32 v11, v12, v13
	global_store_dwordx2 v[4:5], v[10:11], off offset:1024
	global_load_dwordx4 v[10:13], v[2:3], off offset:3072
	v_pk_mul_f32 v[14:15], v[22:23], v[30:31] op_sel_hi:[1,0]
	v_pk_mul_f32 v[16:17], v[24:25], v[30:31] op_sel_hi:[1,0]
	s_waitcnt vmcnt(0) lgkmcnt(0)
	v_pk_mul_f32 v[10:11], v[10:11], v[14:15]
	v_pk_mul_f32 v[12:13], v[12:13], v[16:17]
	v_cvt_pk_bf16_f32 v10, v10, v11
	v_cvt_pk_bf16_f32 v11, v12, v13
	global_store_dwordx2 v[4:5], v[10:11], off offset:1536
	v_lshl_add_u64 v[4:5], v[4:5], 0, s[2:3]
	s_cbranch_scc0 .LBB0_66

; __device__ __forceinline__ unsigned xb_ld(unsigned* p)              { return __hip_atomic_load(p, __ATOMIC_RELAXED, __HIP_MEMORY_SCOPE_AGENT); }
; __device__ __forceinline__ void xcd_barrier_complete(unsigned* bar, unsigned x, unsigned& nloc, unsigned& nx) {
;     const unsigned G = gridDim.x * gridDim.y * gridDim.z;
;     unsigned sum, cnt, mine, sp = 0u;
;     for (;;) {
;         sum = 0u; cnt = 0u; mine = 0u;
; #pragma unroll
;         for (unsigned j = 0; j < 16; ++j) { const unsigned c = xb_ld(&bar[XB_XCNT(j)]); sum += c; cnt += (c > 0u) ? 1u : 0u; mine = (j == x) ? c : mine; }
;         if (sum == G) break;
;         __builtin_amdgcn_s_sleep(1);
;         if ((++sp & 255u) == 0u) { if (xb_ld(&bar[XB_TMO])) break; if (sp > XB_SPIN_CAP) { atomicAdd(&bar[XB_TMO], 1u); break; } }
;     }
;     nloc = mine > 0u ? mine : 1u; nx = cnt > 0u ? cnt : 1u;
; }
.LBB0_84:
	global_load_dword v47, v[0:1], off sc1
	global_load_dword v32, v[2:3], off sc1
	global_load_dword v33, v[4:5], off sc1
	global_load_dword v34, v[6:7], off sc1
	global_load_dword v35, v[8:9], off sc1
	global_load_dword v36, v[10:11], off sc1
	global_load_dword v37, v[12:13], off sc1
	global_load_dword v38, v[14:15], off sc1
	global_load_dword v39, v[16:17], off sc1
	global_load_dword v40, v[18:19], off sc1
	global_load_dword v41, v[20:21], off sc1
	global_load_dword v42, v[22:23], off sc1
	global_load_dword v43, v[24:25], off sc1
	global_load_dword v44, v[26:27], off sc1
	global_load_dword v45, v[28:29], off sc1
	global_load_dword v46, v[30:31], off sc1
	s_or_b64 s[10:11], s[10:11], exec
	s_or_b64 s[8:9], s[8:9], exec
	s_waitcnt vmcnt(0) lgkmcnt(0)
	v_add_u32_e32 v48, v32, v47
	v_add_u32_e32 v48, v48, v33
	v_add_u32_e32 v48, v48, v34
	v_add_u32_e32 v48, v48, v35
	v_add_u32_e32 v48, v48, v36
	v_add_u32_e32 v48, v48, v37
	v_add_u32_e32 v48, v48, v38
	v_add_u32_e32 v48, v48, v39
	v_add_u32_e32 v48, v48, v40
	v_add_u32_e32 v48, v48, v41
	v_add_u32_e32 v48, v48, v42
	v_add_u32_e32 v48, v48, v43
	v_add_u32_e32 v48, v48, v44
	v_add_u32_e32 v48, v48, v45
	v_add_u32_e32 v48, v48, v46
	v_cmp_ne_u32_e32 vcc, s22, v48
	s_and_saveexec_b64 s[12:13], vcc
	s_cbranch_execz .LBB0_83
	s_and_b32 s16, s23, 0xff
	s_mov_b64 s[14:15], -1
	s_cmp_eq_u32 s16, 0
	s_mov_b64 s[18:19], -1
	s_mov_b64 s[16:17], -1
	s_sleep 1
	s_cbranch_scc1 .LBB0_87
	s_and_saveexec_b64 s[20:21], s[18:19]
	s_cbranch_execz .LBB0_82
	s_branch .LBB0_90
.LBB0_87:
	v_mov_b64_e32 v[48:49], s[2:3]
	global_load_dword v48, v[48:49], off sc1
	s_mov_b64 s[18:19], 0
	s_waitcnt vmcnt(0) lgkmcnt(0)
	v_cmp_eq_u32_e32 vcc, 0, v48
	s_and_saveexec_b64 s[20:21], vcc
	s_cmp_lt_u32 s23, 0x400001
	s_cselect_b64 s[18:19], -1, 0
	s_xor_b64 s[16:17], exec, -1
	s_and_b64 s[18:19], s[18:19], exec
	s_or_b64 exec, exec, s[20:21]
	s_and_saveexec_b64 s[20:21], s[18:19]
	s_cbranch_execz .LBB0_82

; __device__ __forceinline__ unsigned xb_ld(unsigned* p)              { return __hip_atomic_load(p, __ATOMIC_RELAXED, __HIP_MEMORY_SCOPE_AGENT); }
; __device__ __forceinline__ void xcd_barrier_complete(unsigned* bar, unsigned x, unsigned& nloc, unsigned& nx) {
;     ...
;         __builtin_amdgcn_s_sleep(1);
;         if ((++sp & 255u) == 0u) { if (xb_ld(&bar[XB_TMO])) break; if (sp > XB_SPIN_CAP) { atomicAdd(&bar[XB_TMO], 1u); break; } }
;     }
;     nloc = mine > 0u ? mine : 1u; nx = cnt > 0u ? cnt : 1u;
.LBB0_91:
	s_or_b64 exec, exec, s[4:5]
	s_xor_b64 s[4:5], s[6:7], -1
	s_and_saveexec_b64 s[6:7], s[4:5]
	s_xor_b64 s[4:5], exec, s[6:7]
	s_cbranch_execz .LBB0_93
	v_mov_b32_e32 v2, 1
	v_mov_b64_e32 v[0:1], s[2:3]
	global_atomic_add v[0:1], v2, off

; __device__ __forceinline__ unsigned xb_ld(unsigned* p)              { return __hip_atomic_load(p, __ATOMIC_RELAXED, __HIP_MEMORY_SCOPE_AGENT); }
; __device__ __forceinline__ unsigned xb_add(unsigned* p, unsigned v) { return __hip_atomic_fetch_add(p, v, __ATOMIC_RELAXED, __HIP_MEMORY_SCOPE_AGENT); }
; #define XB_SPIN(cond, bar) do { unsigned _sp = 0; while (cond) { __builtin_amdgcn_s_sleep(1); \
;     if ((++_sp & 255u) == 0u) { if (xb_ld(&(bar)[XB_TMO])) break; if (_sp > XB_SPIN_CAP) { atomicAdd(&(bar)[XB_TMO], 1u); break; } } } } while (0)
; __device__ __forceinline__ void xcd_barrier(const XcdBarrier& b, bool leader) {
;     asm volatile("s_waitcnt vmcnt(0)" ::: "memory");
;     __syncthreads();
;     if (leader) {
;         unsigned* bar = b.bar;
;         __builtin_amdgcn_s_waitcnt(0);
;         unsigned nloc = b.st[0], nx = b.st[1];
;         if (nloc == 0u) { xcd_barrier_complete(bar, b.x, nloc, nx); b.st[0] = nloc; b.st[1] = nx; }
;         const unsigned old = xb_add(&bar[XB_XSUB(b.x)], 1u);
;         const unsigned gen = old / nloc;
;         if (old + 1u == (gen + 1u) * nloc) {
;             __builtin_amdgcn_fence(__ATOMIC_RELEASE, "agent");
;             asm volatile("s_waitcnt vmcnt(0)" ::: "memory");
;             const unsigned og = xb_add(&bar[XB_TOP], 1u);
;             const unsigned tg = og / nx;
;             if (og + 1u == (tg + 1u) * nx) xb_add(&bar[XB_TOPGEN], 1u);
;             else XB_SPIN(xb_ld(&bar[XB_TOPGEN]) == tg, bar);
;             __builtin_amdgcn_fence(__ATOMIC_ACQUIRE, "agent");
;             xb_add(&bar[XB_XGEN(b.x)], 1u);
;             asm volatile("s_waitcnt vmcnt(0)" ::: "memory");
;         } else {
;             XB_SPIN(xb_ld(&bar[XB_XGEN(b.x)]) == gen, bar);
;             __builtin_amdgcn_fence(__ATOMIC_ACQUIRE, "agent");
;             asm volatile("s_waitcnt vmcnt(0)" ::: "memory");
;         }
.LBB0_94:
	s_lshl_b32 s2, s36, 8
	s_add_u32 s2, s1, s2
	s_addc_u32 s3, s0, 0
	v_mov_b32_e32 v1, s2
	v_add_co_u32_e32 v4, vcc, 0x2000, v1
	v_mov_b32_e32 v1, s3
	s_nop 0
	v_addc_co_u32_e32 v5, vcc, 0, v1, vcc
	v_mov_b32_e32 v1, 1
	global_atomic_add v1, v[4:5], v1, off offset:1024 sc0
	v_cvt_f32_u32_e32 v3, v2
	v_sub_u32_e32 v4, 0, v2
	s_add_u32 s25, s2, 0x1000
	s_addc_u32 s24, s3, 0
	v_rcp_iflag_f32_e32 v3, v3
	s_nop 0
	v_mul_f32_e32 v3, 0x4f7ffffe, v3
	v_cvt_u32_f32_e32 v3, v3
	v_mul_lo_u32 v4, v4, v3
	v_mul_hi_u32 v4, v3, v4
	v_add_u32_e32 v3, v3, v4
	s_waitcnt vmcnt(0) lgkmcnt(0)
	v_mul_hi_u32 v3, v1, v3
	v_mul_lo_u32 v5, v3, v2
	v_add_u32_e32 v4, 1, v1
	v_sub_u32_e32 v1, v1, v5
	v_add_u32_e32 v6, 1, v3
	v_cmp_ge_u32_e32 vcc, v1, v2
	v_sub_u32_e32 v5, v1, v2
	s_nop 0
	v_cndmask_b32_e32 v3, v3, v6, vcc
	v_cndmask_b32_e32 v1, v1, v5, vcc
	v_add_u32_e32 v5, 1, v3
	v_cmp_ge_u32_e32 vcc, v1, v2
	s_nop 1
	v_cndmask_b32_e32 v1, v3, v5, vcc
	v_mad_u64_u32 v[2:3], s[2:3], v2, v1, v[2:3]
	v_cmp_ne_u32_e32 vcc, v4, v2
	s_and_saveexec_b64 s[2:3], vcc
	s_xor_b64 s[2:3], exec, s[2:3]
	s_cbranch_execz .LBB0_107
	v_mov_b32_e32 v0, s25
	v_add_co_u32_e32 v2, vcc, 0x2000, v0
	v_mov_b32_e32 v0, s24
	s_nop 0
	v_addc_co_u32_e32 v3, vcc, 0, v0, vcc
	global_load_dword v0, v[2:3], off offset:1024 sc1
	s_add_u32 s8, s25, 0x2400
	s_addc_u32 s9, s24, 0
	s_waitcnt vmcnt(0) lgkmcnt(0)
	v_cmp_eq_u32_e32 vcc, v0, v1
	s_and_saveexec_b64 s[4:5], vcc
	s_cbranch_execz .LBB0_106
	s_add_u32 s6, s1, 0x1200
	s_addc_u32 s7, s0, 0
	s_mov_b32 s26, 1
	s_mov_b64 s[10:11], 0
	s_branch .LBB0_98

; __device__ __forceinline__ unsigned xb_ld(unsigned* p)              { return __hip_atomic_load(p, __ATOMIC_RELAXED, __HIP_MEMORY_SCOPE_AGENT); }
; #define XB_SPIN(cond, bar) do { unsigned _sp = 0; while (cond) { __builtin_amdgcn_s_sleep(1); \
;     if ((++_sp & 255u) == 0u) { if (xb_ld(&(bar)[XB_TMO])) break; if (_sp > XB_SPIN_CAP) { atomicAdd(&(bar)[XB_TMO], 1u); break; } } } } while (0)
; __device__ __forceinline__ void xcd_barrier(const XcdBarrier& b, bool leader) {
;     ...
;             XB_SPIN(xb_ld(&bar[XB_XGEN(b.x)]) == gen, bar);
.LBB0_98:
	s_and_b32 s18, s26, 0xff
	s_mov_b64 s[16:17], -1
	s_cmp_lg_u32 s18, 0
	s_mov_b64 s[18:19], -1
	s_sleep 1
	s_cbranch_scc1 .LBB0_102
	v_mov_b64_e32 v[2:3], s[6:7]
	global_load_dword v0, v[2:3], off sc1
	s_mov_b64 s[18:19], 0
	s_mov_b64 s[20:21], -1
	s_waitcnt vmcnt(0) lgkmcnt(0)
	v_cmp_eq_u32_e32 vcc, 0, v0
	s_and_saveexec_b64 s[22:23], vcc
	s_cmp_lt_u32 s26, 0x400001
	s_cselect_b64 s[18:19], -1, 0
	s_xor_b64 s[20:21], exec, -1
	s_and_b64 s[18:19], s[18:19], exec
	s_or_b64 exec, exec, s[22:23]
.LBB0_102:
	s_andn2_b64 s[14:15], s[14:15], exec
	s_and_b64 s[20:21], s[20:21], exec
	s_or_b64 s[14:15], s[14:15], s[20:21]
	s_and_saveexec_b64 s[20:21], s[18:19]
	s_cbranch_execz .LBB0_97
	v_mov_b64_e32 v[2:3], s[8:9]
	global_load_dword v0, v[2:3], off sc1
	s_add_i32 s26, s26, 1
	s_or_b64 s[14:15], s[14:15], exec
	s_waitcnt vmcnt(0) lgkmcnt(0)
	v_cmp_ne_u32_e32 vcc, v0, v1
	s_orn2_b64 s[16:17], vcc, exec
	s_branch .LBB0_97
.LBB0_104:
	s_or_b64 exec, exec, s[10:11]
	s_xor_b64 s[8:9], s[12:13], -1
	s_and_saveexec_b64 s[10:11], s[8:9]
	s_xor_b64 s[10:11], exec, s[10:11]
	s_cbranch_execz .LBB0_106
	v_mov_b32_e32 v2, 1
	v_mov_b64_e32 v[0:1], s[6:7]
	global_atomic_add v[0:1], v2, off

; __device__ __forceinline__ unsigned xb_ld(unsigned* p)              { return __hip_atomic_load(p, __ATOMIC_RELAXED, __HIP_MEMORY_SCOPE_AGENT); }
; __device__ __forceinline__ unsigned xb_add(unsigned* p, unsigned v) { return __hip_atomic_fetch_add(p, v, __ATOMIC_RELAXED, __HIP_MEMORY_SCOPE_AGENT); }
; #define XB_SPIN(cond, bar) do { unsigned _sp = 0; while (cond) { __builtin_amdgcn_s_sleep(1); \
;     if ((++_sp & 255u) == 0u) { if (xb_ld(&(bar)[XB_TMO])) break; if (_sp > XB_SPIN_CAP) { atomicAdd(&(bar)[XB_TMO], 1u); break; } } } } while (0)
; __device__ __forceinline__ void xcd_barrier(const XcdBarrier& b, bool leader) {
;     ...
;         if (old + 1u == (gen + 1u) * nloc) {
;             __builtin_amdgcn_fence(__ATOMIC_RELEASE, "agent");
;             asm volatile("s_waitcnt vmcnt(0)" ::: "memory");
;             const unsigned og = xb_add(&bar[XB_TOP], 1u);
;             const unsigned tg = og / nx;
;             if (og + 1u == (tg + 1u) * nx) xb_add(&bar[XB_TOPGEN], 1u);
;             else XB_SPIN(xb_ld(&bar[XB_TOPGEN]) == tg, bar);
.LBB0_107:
	s_andn2_saveexec_b64 s[2:3], s[2:3]
	s_cbranch_execz .LBB0_123
	v_mov_b32_e32 v1, s1
	v_add_co_u32_e32 v2, vcc, 0x4000, v1
	v_mov_b32_e32 v1, s0
	buffer_wbl2 sc1
	s_waitcnt vmcnt(0)
	v_addc_co_u32_e32 v3, vcc, 0, v1, vcc
	v_mov_b32_e32 v1, 1
	global_atomic_add v1, v[2:3], v1, off offset:1024 sc0
	v_cvt_f32_u32_e32 v2, v0
	v_sub_u32_e32 v3, 0, v0
	s_add_u32 s2, s1, 0x4500
	s_addc_u32 s3, s0, 0
	v_rcp_iflag_f32_e32 v2, v2
	s_mov_b64 s[6:7], -1
	v_mul_f32_e32 v2, 0x4f7ffffe, v2
	v_cvt_u32_f32_e32 v2, v2
	v_mul_lo_u32 v3, v3, v2
	v_mul_hi_u32 v3, v2, v3
	v_add_u32_e32 v2, v2, v3
	s_waitcnt vmcnt(0) lgkmcnt(0)
	v_mul_hi_u32 v2, v1, v2
	v_mul_lo_u32 v4, v2, v0
	v_add_u32_e32 v3, 1, v1
	v_sub_u32_e32 v1, v1, v4
	v_add_u32_e32 v5, 1, v2
	v_cmp_ge_u32_e32 vcc, v1, v0
	v_sub_u32_e32 v4, v1, v0
	s_nop 0
	v_cndmask_b32_e32 v2, v2, v5, vcc
	v_cndmask_b32_e32 v1, v1, v4, vcc
	v_add_u32_e32 v4, 1, v2
	v_cmp_ge_u32_e32 vcc, v1, v0
	s_nop 1
	v_cndmask_b32_e32 v2, v2, v4, vcc
	v_mad_u64_u32 v[0:1], s[4:5], v0, v2, v[0:1]
	v_cmp_ne_u32_e32 vcc, v3, v0
	v_mov_b64_e32 v[0:1], s[2:3]
	s_and_saveexec_b64 s[4:5], vcc
	s_cbranch_execz .LBB0_120
	v_mov_b64_e32 v[0:1], s[2:3]
	global_load_dword v0, v[0:1], off sc1
	s_mov_b64 s[10:11], 0
	s_waitcnt vmcnt(0) lgkmcnt(0)
	v_cmp_eq_u32_e32 vcc, v0, v2
	s_and_saveexec_b64 s[8:9], vcc
	s_cbranch_execz .LBB0_119
	s_add_u32 s6, s1, 0x1200
	s_addc_u32 s7, s0, 0
	s_mov_b32 s0, 1
	s_branch .LBB0_112

; __device__ __forceinline__ unsigned xb_ld(unsigned* p)              { return __hip_atomic_load(p, __ATOMIC_RELAXED, __HIP_MEMORY_SCOPE_AGENT); }
; #define XB_SPIN(cond, bar) do { unsigned _sp = 0; while (cond) { __builtin_amdgcn_s_sleep(1); \
;     if ((++_sp & 255u) == 0u) { if (xb_ld(&(bar)[XB_TMO])) break; if (_sp > XB_SPIN_CAP) { atomicAdd(&(bar)[XB_TMO], 1u); break; } } } } while (0)
; __device__ __forceinline__ void xcd_barrier(const XcdBarrier& b, bool leader) {
;     ...
;             else XB_SPIN(xb_ld(&bar[XB_TOPGEN]) == tg, bar);
.LBB0_114:
	v_mov_b64_e32 v[0:1], s[6:7]
	global_load_dword v0, v[0:1], off sc1
	s_mov_b64 s[16:17], 0
	s_mov_b64 s[14:15], -1
	s_waitcnt vmcnt(0) lgkmcnt(0)
	v_cmp_eq_u32_e32 vcc, 0, v0
	s_and_saveexec_b64 s[18:19], vcc
	s_cmp_lt_u32 s0, 0x400001
	s_cselect_b64 s[16:17], -1, 0
	s_xor_b64 s[14:15], exec, -1
	s_and_b64 s[16:17], s[16:17], exec
	s_or_b64 exec, exec, s[18:19]
	s_mov_b64 s[18:19], -1
	s_and_saveexec_b64 s[20:21], s[16:17]
	s_cbranch_execz .LBB0_111
.LBB0_117:
	v_mov_b64_e32 v[0:1], s[2:3]
	global_load_dword v0, v[0:1], off sc1
	s_add_i32 s0, s0, 1
	s_or_b64 s[14:15], s[14:15], exec
	s_waitcnt vmcnt(0) lgkmcnt(0)
	v_cmp_ne_u32_e32 vcc, v0, v2
	s_orn2_b64 s[18:19], vcc, exec
	s_branch .LBB0_111

; __device__ __forceinline__ unsigned xb_ld(unsigned* p)              { return __hip_atomic_load(p, __ATOMIC_RELAXED, __HIP_MEMORY_SCOPE_AGENT); }
; __device__ __forceinline__ unsigned xb_add(unsigned* p, unsigned v) { return __hip_atomic_fetch_add(p, v, __ATOMIC_RELAXED, __HIP_MEMORY_SCOPE_AGENT); }
; #define XB_SPIN(cond, bar) do { unsigned _sp = 0; while (cond) { __builtin_amdgcn_s_sleep(1); \
;     if ((++_sp & 255u) == 0u) { if (xb_ld(&(bar)[XB_TMO])) break; if (_sp > XB_SPIN_CAP) { atomicAdd(&(bar)[XB_TMO], 1u); break; } } } } while (0)
; __device__ __forceinline__ void xcd_barrier(const XcdBarrier& b, bool leader) {
;     ...
;             if (og + 1u == (tg + 1u) * nx) xb_add(&bar[XB_TOPGEN], 1u);
;             else XB_SPIN(xb_ld(&bar[XB_TOPGEN]) == tg, bar);
;             __builtin_amdgcn_fence(__ATOMIC_ACQUIRE, "agent");
;             xb_add(&bar[XB_XGEN(b.x)], 1u);
;             asm volatile("s_waitcnt vmcnt(0)" ::: "memory");
.LBB0_120:
	s_or_b64 exec, exec, s[4:5]
	s_and_saveexec_b64 s[2:3], s[6:7]
	s_cbranch_execz .LBB0_122
	v_mov_b32_e32 v2, 1
	global_atomic_add v[0:1], v2, off
.LBB0_122:
	s_or_b64 exec, exec, s[2:3]
	v_mov_b32_e32 v0, s25
	v_add_co_u32_e32 v0, vcc, 0x2000, v0
	v_mov_b32_e32 v1, s24
	s_nop 0
	v_addc_co_u32_e32 v1, vcc, 0, v1, vcc
	v_mov_b32_e32 v2, 1
	s_waitcnt vmcnt(0) lgkmcnt(0)
	buffer_inv sc1
	global_atomic_add v[0:1], v2, off offset:1024
	s_waitcnt vmcnt(0)

; __device__ __forceinline__ unsigned pk2(float lo, float hi) { const f32x2 v = {lo, hi}; return __builtin_bit_cast(unsigned, __builtin_convertvector(v, bf16x2_t)); }
;     __device__ __forceinline__ void operator()(EPI_ARGS) const {
;         const int row0 = u.pm * BM + wr * 64 + fr, col0 = u.pn * BM + wc * 32 + 8 * fq;
; #pragma unroll
;         for (int ai = 0; ai < 2; ++ai)
; #pragma unroll
;             for (int m = 0; m < 4; ++m) { bf16* rowp = O + (size_t)(row0 + ai * HALF + m * 16) * ldc + col0;
; #pragma unroll
;                 for (int bj = 0; bj < 2; ++bj) { const f32x4 v0 = acc[ai][bj][m][0], v1 = acc[ai][bj][m][1];
;                     u32x4 w; w.x = pk2(v0[0], v0[1]); w.y = pk2(v0[2], v0[3]); w.z = pk2(v1[0], v1[1]); w.w = pk2(v1[2], v1[3]);
;                     *(u32x4*)(rowp + bj * HALF) = w; } }
.LBB0_135:
	v_lshl_add_u32 v156, s12, 8, v144
	v_lshl_or_b32 v150, s49, 8, v146
	v_ashrrev_i32_e32 v151, 31, v150
	v_mov_b64_e32 v[152:153], s[6:7]
	v_cvt_pk_bf16_f32 v68, v68, v69
	v_cvt_pk_bf16_f32 v69, v70, v71
	v_cvt_pk_bf16_f32 v70, v64, v65
	v_add_u32_e32 v64, 0x80, v156
	v_mad_i64_i32 v[154:155], s[22:23], v156, s48, v[152:153]
	v_lshlrev_b64 v[150:151], 1, v[150:151]
	v_cvt_pk_bf16_f32 v108, v108, v109
	v_cvt_pk_bf16_f32 v109, v110, v111
	v_cvt_pk_bf16_f32 v110, v104, v105
	v_or_b32_e32 v104, 16, v156
	v_mad_i64_i32 v[64:65], s[22:23], v64, s48, v[152:153]
	v_cvt_pk_bf16_f32 v44, v44, v45
	v_cvt_pk_bf16_f32 v45, v46, v47
	v_cvt_pk_bf16_f32 v46, v40, v41
	v_add_u32_e32 v40, 0x90, v156
	v_lshl_add_u64 v[154:155], v[154:155], 0, v[150:151]
	v_cvt_pk_bf16_f32 v111, v106, v107
	v_mad_i64_i32 v[104:105], s[22:23], v104, s48, v[152:153]
	v_cvt_pk_bf16_f32 v92, v92, v93
	v_cvt_pk_bf16_f32 v93, v94, v95
	v_cvt_pk_bf16_f32 v94, v88, v89
	v_or_b32_e32 v88, 32, v156
	v_lshl_add_u64 v[64:65], v[64:65], 0, v[150:151]
	v_cvt_pk_bf16_f32 v47, v42, v43
	v_mad_i64_i32 v[40:41], s[22:23], v40, s48, v[152:153]
	v_cvt_pk_bf16_f32 v28, v28, v29
	v_cvt_pk_bf16_f32 v29, v30, v31
	v_cvt_pk_bf16_f32 v30, v24, v25
	v_add_u32_e32 v24, 0xa0, v156
	global_store_dwordx4 v[154:155], v[108:111], off offset:256
	v_cvt_pk_bf16_f32 v95, v90, v91
	v_mad_i64_i32 v[88:89], s[22:23], v88, s48, v[152:153]
	v_lshl_add_u64 v[108:109], v[104:105], 0, v[150:151]
	v_cvt_pk_bf16_f32 v76, v76, v77
	v_cvt_pk_bf16_f32 v77, v78, v79
	v_cvt_pk_bf16_f32 v78, v72, v73
	v_or_b32_e32 v72, 48, v156
	global_store_dwordx4 v[64:65], v[44:47], off offset:256
	v_cvt_pk_bf16_f32 v31, v26, v27
	v_mad_i64_i32 v[24:25], s[22:23], v24, s48, v[152:153]
	v_lshl_add_u64 v[44:45], v[40:41], 0, v[150:151]
	v_cvt_pk_bf16_f32 v12, v12, v13
	v_cvt_pk_bf16_f32 v13, v14, v15
	v_cvt_pk_bf16_f32 v14, v8, v9
	v_add_u32_e32 v8, 0xb0, v156
	global_store_dwordx4 v[108:109], v[92:95], off offset:256
	v_cvt_pk_bf16_f32 v79, v74, v75
	v_mad_i64_i32 v[72:73], s[22:23], v72, s48, v[152:153]
	v_lshl_add_u64 v[92:93], v[88:89], 0, v[150:151]
	global_store_dwordx4 v[44:45], v[28:31], off offset:256
	v_cvt_pk_bf16_f32 v15, v10, v11
	v_mad_i64_i32 v[8:9], s[22:23], v8, s48, v[152:153]
	v_lshl_add_u64 v[28:29], v[24:25], 0, v[150:151]
	v_cvt_pk_bf16_f32 v124, v124, v125
	v_cvt_pk_bf16_f32 v125, v126, v127
	v_cvt_pk_bf16_f32 v126, v120, v121
	v_cvt_pk_bf16_f32 v127, v122, v123
	v_cvt_pk_bf16_f32 v104, v116, v117
	v_cvt_pk_bf16_f32 v105, v118, v119
	v_cvt_pk_bf16_f32 v106, v112, v113
	v_cvt_pk_bf16_f32 v107, v114, v115
	v_cvt_pk_bf16_f32 v88, v100, v101
	v_cvt_pk_bf16_f32 v89, v102, v103
	v_cvt_pk_bf16_f32 v90, v96, v97
	v_cvt_pk_bf16_f32 v91, v98, v99
	global_store_dwordx4 v[92:93], v[76:79], off offset:256
	v_cvt_pk_bf16_f32 v74, v80, v81
	v_cvt_pk_bf16_f32 v75, v82, v83
	v_lshl_add_u64 v[76:77], v[72:73], 0, v[150:151]
	v_cvt_pk_bf16_f32 v72, v84, v85
	v_cvt_pk_bf16_f32 v73, v86, v87
	v_cvt_pk_bf16_f32 v71, v66, v67
	v_cvt_pk_bf16_f32 v60, v60, v61
	v_cvt_pk_bf16_f32 v61, v62, v63
	v_cvt_pk_bf16_f32 v62, v56, v57
	v_cvt_pk_bf16_f32 v63, v58, v59
	v_cvt_pk_bf16_f32 v40, v52, v53
	v_cvt_pk_bf16_f32 v41, v54, v55
	v_cvt_pk_bf16_f32 v42, v48, v49
	v_cvt_pk_bf16_f32 v43, v50, v51
	v_cvt_pk_bf16_f32 v24, v36, v37
	v_cvt_pk_bf16_f32 v25, v38, v39
	v_cvt_pk_bf16_f32 v26, v32, v33
	v_cvt_pk_bf16_f32 v27, v34, v35
	global_store_dwordx4 v[28:29], v[12:15], off offset:256
	v_cvt_pk_bf16_f32 v10, v16, v17
	v_cvt_pk_bf16_f32 v11, v18, v19
	v_lshl_add_u64 v[12:13], v[8:9], 0, v[150:151]
	v_cvt_pk_bf16_f32 v8, v20, v21
	v_cvt_pk_bf16_f32 v9, v22, v23
	v_cvt_pk_bf16_f32 v4, v4, v5
	v_cvt_pk_bf16_f32 v5, v6, v7
	v_cvt_pk_bf16_f32 v6, v0, v1
	v_cvt_pk_bf16_f32 v7, v2, v3
	s_andn2_b64 vcc, exec, s[2:3]
	s_mov_b64 s[2:3], -1
	global_store_dwordx4 v[154:155], v[124:127], off
	global_store_dwordx4 v[108:109], v[104:107], off
	global_store_dwordx4 v[92:93], v[88:91], off
	global_store_dwordx4 v[76:77], v[72:75], off
	global_store_dwordx4 v[76:77], v[68:71], off offset:256
	global_store_dwordx4 v[64:65], v[60:63], off
	global_store_dwordx4 v[44:45], v[40:43], off
	global_store_dwordx4 v[28:29], v[24:27], off
	global_store_dwordx4 v[12:13], v[8:11], off
	global_store_dwordx4 v[12:13], v[4:7], off offset:256
	s_cbranch_vccnz .LBB0_128
	s_andn2_b64 vcc, exec, s[4:5]
	s_cbranch_vccnz .LBB0_127
	s_barrier
	s_branch .LBB0_127

; __device__ __forceinline__ unsigned pk2(float lo, float hi) { const f32x2 v = {lo, hi}; return __builtin_bit_cast(unsigned, __builtin_convertvector(v, bf16x2_t)); }
;     __device__ __forceinline__ void operator()(EPI_ARGS) const {
;         const int row0 = u.pm * BM + wr * 64 + fr, col0 = u.pn * BM + wc * 32 + 8 * fq;
; #pragma unroll
;         for (int ai = 0; ai < 2; ++ai)
; #pragma unroll
;             for (int m = 0; m < 4; ++m) { bf16* rowp = O + (size_t)(row0 + ai * HALF + m * 16) * ldc + col0;
; #pragma unroll
;                 for (int bj = 0; bj < 2; ++bj) { const f32x4 v0 = acc[ai][bj][m][0], v1 = acc[ai][bj][m][1];
;                     u32x4 w; w.x = pk2(v0[0], v0[1]); w.y = pk2(v0[2], v0[3]); w.z = pk2(v1[0], v1[1]); w.w = pk2(v1[2], v1[3]);
;                     *(u32x4*)(rowp + bj * HALF) = w; } }
.LBB0_203:
	v_lshl_add_u32 v152, s10, 8, v140
	v_lshl_or_b32 v146, s11, 8, v142
	v_ashrrev_i32_e32 v147, 31, v146
	v_mov_b64_e32 v[148:149], s[4:5]
	v_cvt_pk_bf16_f32 v68, v68, v69
	v_cvt_pk_bf16_f32 v69, v70, v71
	v_cvt_pk_bf16_f32 v70, v64, v65
	v_add_u32_e32 v64, 0x80, v152
	v_mad_i64_i32 v[150:151], s[10:11], v152, s48, v[148:149]
	v_lshlrev_b64 v[146:147], 1, v[146:147]
	v_cvt_pk_bf16_f32 v108, v108, v109
	v_cvt_pk_bf16_f32 v109, v110, v111
	v_cvt_pk_bf16_f32 v110, v104, v105
	v_or_b32_e32 v104, 16, v152
	v_mad_i64_i32 v[64:65], s[10:11], v64, s48, v[148:149]
	v_cvt_pk_bf16_f32 v44, v44, v45
	v_cvt_pk_bf16_f32 v45, v46, v47
	v_cvt_pk_bf16_f32 v46, v40, v41
	v_add_u32_e32 v40, 0x90, v152
	v_lshl_add_u64 v[150:151], v[150:151], 0, v[146:147]
	v_cvt_pk_bf16_f32 v111, v106, v107
	v_mad_i64_i32 v[104:105], s[10:11], v104, s48, v[148:149]
	v_cvt_pk_bf16_f32 v92, v92, v93
	v_cvt_pk_bf16_f32 v93, v94, v95
	v_cvt_pk_bf16_f32 v94, v88, v89
	v_or_b32_e32 v88, 32, v152
	v_lshl_add_u64 v[64:65], v[64:65], 0, v[146:147]
	v_cvt_pk_bf16_f32 v47, v42, v43
	v_mad_i64_i32 v[40:41], s[10:11], v40, s48, v[148:149]
	v_cvt_pk_bf16_f32 v28, v28, v29
	v_cvt_pk_bf16_f32 v29, v30, v31
	v_cvt_pk_bf16_f32 v30, v24, v25
	v_add_u32_e32 v24, 0xa0, v152
	global_store_dwordx4 v[150:151], v[108:111], off offset:256
	v_cvt_pk_bf16_f32 v95, v90, v91
	v_mad_i64_i32 v[88:89], s[10:11], v88, s48, v[148:149]
	v_lshl_add_u64 v[108:109], v[104:105], 0, v[146:147]
	v_cvt_pk_bf16_f32 v76, v76, v77
	v_cvt_pk_bf16_f32 v77, v78, v79
	v_cvt_pk_bf16_f32 v78, v72, v73
	v_or_b32_e32 v72, 48, v152
	global_store_dwordx4 v[64:65], v[44:47], off offset:256
	v_cvt_pk_bf16_f32 v31, v26, v27
	v_mad_i64_i32 v[24:25], s[10:11], v24, s48, v[148:149]
	v_lshl_add_u64 v[44:45], v[40:41], 0, v[146:147]
	v_cvt_pk_bf16_f32 v12, v12, v13
	v_cvt_pk_bf16_f32 v13, v14, v15
	v_cvt_pk_bf16_f32 v14, v8, v9
	v_add_u32_e32 v8, 0xb0, v152
	global_store_dwordx4 v[108:109], v[92:95], off offset:256
	v_cvt_pk_bf16_f32 v79, v74, v75
	v_mad_i64_i32 v[72:73], s[10:11], v72, s48, v[148:149]
	v_lshl_add_u64 v[92:93], v[88:89], 0, v[146:147]
	global_store_dwordx4 v[44:45], v[28:31], off offset:256
	v_cvt_pk_bf16_f32 v15, v10, v11
	v_mad_i64_i32 v[8:9], s[10:11], v8, s48, v[148:149]
	v_lshl_add_u64 v[28:29], v[24:25], 0, v[146:147]
	v_cvt_pk_bf16_f32 v124, v124, v125
	v_cvt_pk_bf16_f32 v125, v126, v127
	v_cvt_pk_bf16_f32 v126, v120, v121
	v_cvt_pk_bf16_f32 v127, v122, v123
	v_cvt_pk_bf16_f32 v104, v116, v117
	v_cvt_pk_bf16_f32 v105, v118, v119
	v_cvt_pk_bf16_f32 v106, v112, v113
	v_cvt_pk_bf16_f32 v107, v114, v115
	v_cvt_pk_bf16_f32 v88, v100, v101
	v_cvt_pk_bf16_f32 v89, v102, v103
	v_cvt_pk_bf16_f32 v90, v96, v97
	v_cvt_pk_bf16_f32 v91, v98, v99
	global_store_dwordx4 v[92:93], v[76:79], off offset:256
	v_cvt_pk_bf16_f32 v74, v80, v81
	v_cvt_pk_bf16_f32 v75, v82, v83
	v_lshl_add_u64 v[76:77], v[72:73], 0, v[146:147]
	v_cvt_pk_bf16_f32 v72, v84, v85
	v_cvt_pk_bf16_f32 v73, v86, v87
	v_cvt_pk_bf16_f32 v71, v66, v67
	v_cvt_pk_bf16_f32 v60, v60, v61
	v_cvt_pk_bf16_f32 v61, v62, v63
	v_cvt_pk_bf16_f32 v62, v56, v57
	v_cvt_pk_bf16_f32 v63, v58, v59
	v_cvt_pk_bf16_f32 v40, v52, v53
	v_cvt_pk_bf16_f32 v41, v54, v55
	v_cvt_pk_bf16_f32 v42, v48, v49
	v_cvt_pk_bf16_f32 v43, v50, v51
	v_cvt_pk_bf16_f32 v24, v36, v37
	v_cvt_pk_bf16_f32 v25, v38, v39
	v_cvt_pk_bf16_f32 v26, v32, v33
	v_cvt_pk_bf16_f32 v27, v34, v35
	global_store_dwordx4 v[28:29], v[12:15], off offset:256
	v_cvt_pk_bf16_f32 v10, v16, v17
	v_cvt_pk_bf16_f32 v11, v18, v19
	v_lshl_add_u64 v[12:13], v[8:9], 0, v[146:147]
	v_cvt_pk_bf16_f32 v8, v20, v21
	v_cvt_pk_bf16_f32 v9, v22, v23
	v_cvt_pk_bf16_f32 v4, v4, v5
	v_cvt_pk_bf16_f32 v5, v6, v7
	v_cvt_pk_bf16_f32 v6, v0, v1
	v_cvt_pk_bf16_f32 v7, v2, v3
	s_andn2_b64 vcc, exec, s[12:13]
	s_mov_b64 s[10:11], -1
	global_store_dwordx4 v[150:151], v[124:127], off
	global_store_dwordx4 v[108:109], v[104:107], off
	global_store_dwordx4 v[92:93], v[88:91], off
	global_store_dwordx4 v[76:77], v[72:75], off
	global_store_dwordx4 v[76:77], v[68:71], off offset:256
	global_store_dwordx4 v[64:65], v[60:63], off
	global_store_dwordx4 v[44:45], v[40:43], off
	global_store_dwordx4 v[28:29], v[24:27], off
	global_store_dwordx4 v[12:13], v[8:11], off
	global_store_dwordx4 v[12:13], v[4:7], off offset:256
	s_cbranch_vccnz .LBB0_192
	s_andn2_b64 vcc, exec, s[2:3]
	s_cbranch_vccnz .LBB0_191
	s_barrier
	s_branch .LBB0_191

; __device__ __forceinline__ unsigned pk2(float lo, float hi) { const f32x2 v = {lo, hi}; return __builtin_bit_cast(unsigned, __builtin_convertvector(v, bf16x2_t)); }
;     __device__ __forceinline__ void operator()(EPI_ARGS) const {
;         const int row0 = u.pm * BM + wr * 64 + fr;
; #pragma unroll
;         for (int ai = 0; ai < 2; ++ai)
; #pragma unroll
;             for (int m = 0; m < 4; ++m) { const int row = row0 + ai * HALF + m * 16;
; #pragma unroll
;                 for (int bj = 0; bj < 2; ++bj) { const int col = u.pn * BM + bj * HALF + wc * 32 + 8 * fq; const f32x4 v0 = acc[ai][bj][m][0], v1 = acc[ai][bj][m][1];
;                     if (col < 1024) { float* o = out + O_PMK + (size_t)row * 1024 + col; *(f32x4*)o = v0; *(f32x4*)(o + 4) = v1;
;                         u32x4 w; w.x = pk2(v0[0], v0[1]); w.y = pk2(v0[2], v0[3]); w.z = pk2(v1[0], v1[1]); w.w = pk2(v1[2], v1[3]);
;                         *(u32x4*)(MK + (size_t)row * 1024 + col) = w;
;                     } else { float* o = out + O_PMV + (size_t)row * 1024 + (col - 1024); *(f32x4*)o = v0; *(f32x4*)(o + 4) = v1; } } }
;     }
.LBB0_229:
	v_lshl_add_u32 v144, s4, 8, v152
	v_ashrrev_i32_e32 v145, 31, v144
	v_lshl_or_b32 v142, s2, 8, v154
	v_lshlrev_b64 v[146:147], 12, v[144:145]
	v_cmp_lt_i32_e64 s[2:3], s58, v142
	v_lshl_add_u64 v[146:147], s[6:7], 0, v[146:147]
	s_and_saveexec_b64 s[4:5], s[2:3]
	s_xor_b64 s[4:5], exec, s[4:5]
	s_cbranch_execz .LBB0_231
	v_mov_b32_e32 v143, v137
	v_lshl_add_u64 v[148:149], v[142:143], 2, v[146:147]
	v_add_co_u32_e32 v148, vcc, 0x9895000, v148
	s_nop 1
	v_addc_co_u32_e32 v149, vcc, 0, v149, vcc
	global_store_dwordx4 v[148:149], v[124:127], off
	global_store_dwordx4 v[148:149], v[120:123], off offset:16
.LBB0_231:
	s_or_saveexec_b64 s[4:5], s[4:5]
	v_lshlrev_b64 v[148:149], 10, v[144:145]
	v_ashrrev_i32_e32 v143, 31, v142
	v_lshl_add_u64 v[150:151], v[148:149], 2, s[16:17]
	v_lshl_add_u64 v[148:149], v[148:149], 1, s[10:11]
	s_xor_b64 exec, exec, s[4:5]
	s_cbranch_execz .LBB0_233
	v_lshl_add_u64 v[158:159], v[142:143], 2, v[150:151]
	global_store_dwordx4 v[158:159], v[124:127], off
	global_store_dwordx4 v[158:159], v[120:123], off offset:16
	s_nop 0
	v_cvt_pk_bf16_f32 v124, v124, v125
	v_cvt_pk_bf16_f32 v125, v126, v127
	v_cvt_pk_bf16_f32 v126, v120, v121
	v_cvt_pk_bf16_f32 v127, v122, v123
	v_lshl_add_u64 v[120:121], v[142:143], 1, v[148:149]
	global_store_dwordx4 v[120:121], v[124:127], off
.LBB0_233:
	s_or_b64 exec, exec, s[4:5]
	v_or_b32_e32 v120, 0x80, v142
	v_cmp_lt_i32_e64 s[4:5], s58, v120
	s_and_saveexec_b64 s[28:29], s[4:5]
	s_xor_b64 s[28:29], exec, s[28:29]
	s_cbranch_execz .LBB0_235
	v_mov_b32_e32 v136, v142
	v_lshl_add_u64 v[120:121], v[136:137], 2, v[146:147]
	v_add_co_u32_e32 v120, vcc, 0x9895000, v120
	s_nop 1
	v_addc_co_u32_e32 v121, vcc, 0, v121, vcc
	global_store_dwordx4 v[120:121], v[116:119], off offset:512
	global_store_dwordx4 v[120:121], v[112:115], off offset:528
.LBB0_235:
	s_andn2_saveexec_b64 s[28:29], s[28:29]
	s_cbranch_execz .LBB0_237
	v_lshl_add_u64 v[120:121], v[142:143], 2, v[150:151]
	global_store_dwordx4 v[120:121], v[116:119], off offset:512
	global_store_dwordx4 v[120:121], v[112:115], off offset:528
	s_nop 0
	v_cvt_pk_bf16_f32 v116, v116, v117
	v_cvt_pk_bf16_f32 v117, v118, v119
	v_cvt_pk_bf16_f32 v118, v112, v113
	v_cvt_pk_bf16_f32 v119, v114, v115
	v_lshl_add_u64 v[112:113], v[142:143], 1, v[148:149]
	global_store_dwordx4 v[112:113], v[116:119], off offset:256
.LBB0_237:
	s_or_b64 exec, exec, s[28:29]
	v_or_b32_e32 v114, 16, v144
	v_ashrrev_i32_e32 v115, 31, v114
	v_lshlrev_b64 v[112:113], 12, v[114:115]
	v_lshl_add_u64 v[112:113], s[6:7], 0, v[112:113]
	s_and_saveexec_b64 s[28:29], s[2:3]
	s_xor_b64 s[28:29], exec, s[28:29]
	s_cbranch_execz .LBB0_239
	v_mov_b32_e32 v136, v142
	v_lshl_add_u64 v[116:117], v[136:137], 2, v[112:113]
	v_add_co_u32_e32 v116, vcc, 0x9895000, v116
	s_nop 1
	v_addc_co_u32_e32 v117, vcc, 0, v117, vcc
	global_store_dwordx4 v[116:117], v[108:111], off
	global_store_dwordx4 v[116:117], v[104:107], off offset:16
.LBB0_239:
	s_or_saveexec_b64 s[28:29], s[28:29]
	v_lshlrev_b64 v[114:115], 10, v[114:115]
	v_lshl_add_u64 v[116:117], v[114:115], 2, s[16:17]
	v_lshl_add_u64 v[114:115], v[114:115], 1, s[10:11]
	s_xor_b64 exec, exec, s[28:29]
	s_cbranch_execz .LBB0_279
	v_lshl_add_u64 v[118:119], v[142:143], 2, v[116:117]
	global_store_dwordx4 v[118:119], v[108:111], off
	global_store_dwordx4 v[118:119], v[104:107], off offset:16
	s_nop 0
	v_cvt_pk_bf16_f32 v108, v108, v109
	v_cvt_pk_bf16_f32 v109, v110, v111
	v_cvt_pk_bf16_f32 v110, v104, v105
	v_cvt_pk_bf16_f32 v111, v106, v107
	v_lshl_add_u64 v[104:105], v[142:143], 1, v[114:115]
	global_store_dwordx4 v[104:105], v[108:111], off
	s_or_b64 exec, exec, s[28:29]
	s_and_saveexec_b64 s[28:29], s[4:5]
	s_xor_b64 s[28:29], exec, s[28:29]
	s_cbranch_execnz .LBB0_280

; __device__ __forceinline__ unsigned pk2(float lo, float hi) { const f32x2 v = {lo, hi}; return __builtin_bit_cast(unsigned, __builtin_convertvector(v, bf16x2_t)); }
;     __device__ __forceinline__ void operator()(EPI_ARGS) const {
;         const int row0 = u.pm * BM + wr * 64 + fr;
; #pragma unroll
;         for (int ai = 0; ai < 2; ++ai)
; #pragma unroll
;             for (int m = 0; m < 4; ++m) { const int row = row0 + ai * HALF + m * 16;
; #pragma unroll
;                 for (int bj = 0; bj < 2; ++bj) { const int col = u.pn * BM + bj * HALF + wc * 32 + 8 * fq; const f32x4 v0 = acc[ai][bj][m][0], v1 = acc[ai][bj][m][1];
;                     if (col < 1024) { float* o = out + O_PMK + (size_t)row * 1024 + col; *(f32x4*)o = v0; *(f32x4*)(o + 4) = v1;
;                         u32x4 w; w.x = pk2(v0[0], v0[1]); w.y = pk2(v0[2], v0[3]); w.z = pk2(v1[0], v1[1]); w.w = pk2(v1[2], v1[3]);
;                         *(u32x4*)(MK + (size_t)row * 1024 + col) = w;
;                     } else { float* o = out + O_PMV + (size_t)row * 1024 + (col - 1024); *(f32x4*)o = v0; *(f32x4*)(o + 4) = v1; } } }
;     }
.LBB0_242:
	v_lshl_add_u64 v[104:105], v[142:143], 2, v[116:117]
	global_store_dwordx4 v[104:105], v[100:103], off offset:512
	global_store_dwordx4 v[104:105], v[96:99], off offset:528
	s_nop 0
	v_cvt_pk_bf16_f32 v100, v100, v101
	v_cvt_pk_bf16_f32 v101, v102, v103
	v_cvt_pk_bf16_f32 v102, v96, v97
	v_cvt_pk_bf16_f32 v103, v98, v99
	v_lshl_add_u64 v[96:97], v[142:143], 1, v[114:115]
	global_store_dwordx4 v[96:97], v[100:103], off offset:256
.LBB0_243:
	s_or_b64 exec, exec, s[28:29]
	v_or_b32_e32 v98, 32, v144
	v_ashrrev_i32_e32 v99, 31, v98
	v_lshlrev_b64 v[96:97], 12, v[98:99]
	v_lshl_add_u64 v[96:97], s[6:7], 0, v[96:97]
	s_and_saveexec_b64 s[28:29], s[2:3]
	s_xor_b64 s[28:29], exec, s[28:29]
	s_cbranch_execz .LBB0_245
	v_mov_b32_e32 v136, v142
	v_lshl_add_u64 v[100:101], v[136:137], 2, v[96:97]
	v_add_co_u32_e32 v100, vcc, 0x9895000, v100
	s_nop 1
	v_addc_co_u32_e32 v101, vcc, 0, v101, vcc
	global_store_dwordx4 v[100:101], v[92:95], off
	global_store_dwordx4 v[100:101], v[88:91], off offset:16
.LBB0_245:
	s_or_saveexec_b64 s[28:29], s[28:29]
	v_lshlrev_b64 v[98:99], 10, v[98:99]
	v_lshl_add_u64 v[100:101], v[98:99], 2, s[16:17]
	v_lshl_add_u64 v[98:99], v[98:99], 1, s[10:11]
	s_xor_b64 exec, exec, s[28:29]
	s_cbranch_execz .LBB0_281
	v_lshl_add_u64 v[102:103], v[142:143], 2, v[100:101]
	global_store_dwordx4 v[102:103], v[92:95], off
	global_store_dwordx4 v[102:103], v[88:91], off offset:16
	s_nop 0
	v_cvt_pk_bf16_f32 v92, v92, v93
	v_cvt_pk_bf16_f32 v93, v94, v95
	v_cvt_pk_bf16_f32 v94, v88, v89
	v_cvt_pk_bf16_f32 v95, v90, v91
	v_lshl_add_u64 v[88:89], v[142:143], 1, v[98:99]
	global_store_dwordx4 v[88:89], v[92:95], off
	s_or_b64 exec, exec, s[28:29]
	s_and_saveexec_b64 s[28:29], s[4:5]
	s_xor_b64 s[28:29], exec, s[28:29]
	s_cbranch_execnz .LBB0_282

; __device__ __forceinline__ unsigned pk2(float lo, float hi) { const f32x2 v = {lo, hi}; return __builtin_bit_cast(unsigned, __builtin_convertvector(v, bf16x2_t)); }
;     __device__ __forceinline__ void operator()(EPI_ARGS) const {
;         const int row0 = u.pm * BM + wr * 64 + fr;
; #pragma unroll
;         for (int ai = 0; ai < 2; ++ai)
; #pragma unroll
;             for (int m = 0; m < 4; ++m) { const int row = row0 + ai * HALF + m * 16;
; #pragma unroll
;                 for (int bj = 0; bj < 2; ++bj) { const int col = u.pn * BM + bj * HALF + wc * 32 + 8 * fq; const f32x4 v0 = acc[ai][bj][m][0], v1 = acc[ai][bj][m][1];
;                     if (col < 1024) { float* o = out + O_PMK + (size_t)row * 1024 + col; *(f32x4*)o = v0; *(f32x4*)(o + 4) = v1;
;                         u32x4 w; w.x = pk2(v0[0], v0[1]); w.y = pk2(v0[2], v0[3]); w.z = pk2(v1[0], v1[1]); w.w = pk2(v1[2], v1[3]);
;                         *(u32x4*)(MK + (size_t)row * 1024 + col) = w;
;                     } else { float* o = out + O_PMV + (size_t)row * 1024 + (col - 1024); *(f32x4*)o = v0; *(f32x4*)(o + 4) = v1; } } }
;     }
.LBB0_248:
	v_lshl_add_u64 v[88:89], v[142:143], 2, v[100:101]
	global_store_dwordx4 v[88:89], v[84:87], off offset:512
	global_store_dwordx4 v[88:89], v[80:83], off offset:528
	s_nop 0
	v_cvt_pk_bf16_f32 v84, v84, v85
	v_cvt_pk_bf16_f32 v85, v86, v87
	v_cvt_pk_bf16_f32 v86, v80, v81
	v_cvt_pk_bf16_f32 v87, v82, v83
	v_lshl_add_u64 v[80:81], v[142:143], 1, v[98:99]
	global_store_dwordx4 v[80:81], v[84:87], off offset:256
.LBB0_249:
	s_or_b64 exec, exec, s[28:29]
	v_or_b32_e32 v82, 48, v144
	v_ashrrev_i32_e32 v83, 31, v82
	v_lshlrev_b64 v[80:81], 12, v[82:83]
	v_lshl_add_u64 v[80:81], s[6:7], 0, v[80:81]
	s_and_saveexec_b64 s[28:29], s[2:3]
	s_xor_b64 s[28:29], exec, s[28:29]
	s_cbranch_execz .LBB0_251
	v_mov_b32_e32 v136, v142
	v_lshl_add_u64 v[84:85], v[136:137], 2, v[80:81]
	v_add_co_u32_e32 v84, vcc, 0x9895000, v84
	s_nop 1
	v_addc_co_u32_e32 v85, vcc, 0, v85, vcc
	global_store_dwordx4 v[84:85], v[76:79], off
	global_store_dwordx4 v[84:85], v[72:75], off offset:16
.LBB0_251:
	s_or_saveexec_b64 s[28:29], s[28:29]
	v_lshlrev_b64 v[82:83], 10, v[82:83]
	v_lshl_add_u64 v[84:85], v[82:83], 2, s[16:17]
	v_lshl_add_u64 v[82:83], v[82:83], 1, s[10:11]
	s_xor_b64 exec, exec, s[28:29]
	s_cbranch_execz .LBB0_283
	v_lshl_add_u64 v[86:87], v[142:143], 2, v[84:85]
	global_store_dwordx4 v[86:87], v[76:79], off
	global_store_dwordx4 v[86:87], v[72:75], off offset:16
	s_nop 0
	v_cvt_pk_bf16_f32 v76, v76, v77
	v_cvt_pk_bf16_f32 v77, v78, v79
	v_cvt_pk_bf16_f32 v78, v72, v73
	v_cvt_pk_bf16_f32 v79, v74, v75
	v_lshl_add_u64 v[72:73], v[142:143], 1, v[82:83]
	global_store_dwordx4 v[72:73], v[76:79], off
	s_or_b64 exec, exec, s[28:29]
	s_and_saveexec_b64 s[28:29], s[4:5]
	s_xor_b64 s[28:29], exec, s[28:29]
	s_cbranch_execnz .LBB0_284

; __device__ __forceinline__ unsigned pk2(float lo, float hi) { const f32x2 v = {lo, hi}; return __builtin_bit_cast(unsigned, __builtin_convertvector(v, bf16x2_t)); }
;     __device__ __forceinline__ void operator()(EPI_ARGS) const {
;         const int row0 = u.pm * BM + wr * 64 + fr;
; #pragma unroll
;         for (int ai = 0; ai < 2; ++ai)
; #pragma unroll
;             for (int m = 0; m < 4; ++m) { const int row = row0 + ai * HALF + m * 16;
; #pragma unroll
;                 for (int bj = 0; bj < 2; ++bj) { const int col = u.pn * BM + bj * HALF + wc * 32 + 8 * fq; const f32x4 v0 = acc[ai][bj][m][0], v1 = acc[ai][bj][m][1];
;                     if (col < 1024) { float* o = out + O_PMK + (size_t)row * 1024 + col; *(f32x4*)o = v0; *(f32x4*)(o + 4) = v1;
;                         u32x4 w; w.x = pk2(v0[0], v0[1]); w.y = pk2(v0[2], v0[3]); w.z = pk2(v1[0], v1[1]); w.w = pk2(v1[2], v1[3]);
;                         *(u32x4*)(MK + (size_t)row * 1024 + col) = w;
;                     } else { float* o = out + O_PMV + (size_t)row * 1024 + (col - 1024); *(f32x4*)o = v0; *(f32x4*)(o + 4) = v1; } } }
;     }
.LBB0_254:
	v_lshl_add_u64 v[72:73], v[142:143], 2, v[84:85]
	global_store_dwordx4 v[72:73], v[68:71], off offset:512
	global_store_dwordx4 v[72:73], v[64:67], off offset:528
	s_nop 0
	v_cvt_pk_bf16_f32 v68, v68, v69
	v_cvt_pk_bf16_f32 v69, v70, v71
	v_cvt_pk_bf16_f32 v70, v64, v65
	v_cvt_pk_bf16_f32 v71, v66, v67
	v_lshl_add_u64 v[64:65], v[142:143], 1, v[82:83]
	global_store_dwordx4 v[64:65], v[68:71], off offset:256
.LBB0_255:
	s_or_b64 exec, exec, s[28:29]
	v_add_u32_e32 v66, 0x80, v144
	v_ashrrev_i32_e32 v67, 31, v66
	v_lshlrev_b64 v[64:65], 12, v[66:67]
	v_lshl_add_u64 v[64:65], s[6:7], 0, v[64:65]
	s_and_saveexec_b64 s[28:29], s[2:3]
	s_xor_b64 s[28:29], exec, s[28:29]
	s_cbranch_execz .LBB0_257
	v_mov_b32_e32 v136, v142
	v_lshl_add_u64 v[68:69], v[136:137], 2, v[64:65]
	v_add_co_u32_e32 v68, vcc, 0x9895000, v68
	s_nop 1
	v_addc_co_u32_e32 v69, vcc, 0, v69, vcc
	global_store_dwordx4 v[68:69], v[60:63], off
	global_store_dwordx4 v[68:69], v[56:59], off offset:16
.LBB0_257:
	s_or_saveexec_b64 s[28:29], s[28:29]
	v_lshlrev_b64 v[66:67], 10, v[66:67]
	v_lshl_add_u64 v[68:69], v[66:67], 2, s[16:17]
	v_lshl_add_u64 v[66:67], v[66:67], 1, s[10:11]
	s_xor_b64 exec, exec, s[28:29]
	s_cbranch_execz .LBB0_285
	v_lshl_add_u64 v[70:71], v[142:143], 2, v[68:69]
	global_store_dwordx4 v[70:71], v[60:63], off
	global_store_dwordx4 v[70:71], v[56:59], off offset:16
	s_nop 0
	v_cvt_pk_bf16_f32 v60, v60, v61
	v_cvt_pk_bf16_f32 v61, v62, v63
	v_cvt_pk_bf16_f32 v62, v56, v57
	v_cvt_pk_bf16_f32 v63, v58, v59
	v_lshl_add_u64 v[56:57], v[142:143], 1, v[66:67]
	global_store_dwordx4 v[56:57], v[60:63], off
	s_or_b64 exec, exec, s[28:29]
	s_and_saveexec_b64 s[28:29], s[4:5]
	s_xor_b64 s[28:29], exec, s[28:29]
	s_cbranch_execnz .LBB0_286

; __device__ __forceinline__ unsigned pk2(float lo, float hi) { const f32x2 v = {lo, hi}; return __builtin_bit_cast(unsigned, __builtin_convertvector(v, bf16x2_t)); }
;     __device__ __forceinline__ void operator()(EPI_ARGS) const {
;         const int row0 = u.pm * BM + wr * 64 + fr;
; #pragma unroll
;         for (int ai = 0; ai < 2; ++ai)
; #pragma unroll
;             for (int m = 0; m < 4; ++m) { const int row = row0 + ai * HALF + m * 16;
; #pragma unroll
;                 for (int bj = 0; bj < 2; ++bj) { const int col = u.pn * BM + bj * HALF + wc * 32 + 8 * fq; const f32x4 v0 = acc[ai][bj][m][0], v1 = acc[ai][bj][m][1];
;                     if (col < 1024) { float* o = out + O_PMK + (size_t)row * 1024 + col; *(f32x4*)o = v0; *(f32x4*)(o + 4) = v1;
;                         u32x4 w; w.x = pk2(v0[0], v0[1]); w.y = pk2(v0[2], v0[3]); w.z = pk2(v1[0], v1[1]); w.w = pk2(v1[2], v1[3]);
;                         *(u32x4*)(MK + (size_t)row * 1024 + col) = w;
;                     } else { float* o = out + O_PMV + (size_t)row * 1024 + (col - 1024); *(f32x4*)o = v0; *(f32x4*)(o + 4) = v1; } } }
;     }
.LBB0_260:
	v_lshl_add_u64 v[56:57], v[142:143], 2, v[68:69]
	global_store_dwordx4 v[56:57], v[52:55], off offset:512
	global_store_dwordx4 v[56:57], v[48:51], off offset:528
	s_nop 0
	v_cvt_pk_bf16_f32 v52, v52, v53
	v_cvt_pk_bf16_f32 v53, v54, v55
	v_cvt_pk_bf16_f32 v54, v48, v49
	v_cvt_pk_bf16_f32 v55, v50, v51
	v_lshl_add_u64 v[48:49], v[142:143], 1, v[66:67]
	global_store_dwordx4 v[48:49], v[52:55], off offset:256
.LBB0_261:
	s_or_b64 exec, exec, s[28:29]
	v_add_u32_e32 v50, 0x90, v144
	v_ashrrev_i32_e32 v51, 31, v50
	v_lshlrev_b64 v[48:49], 12, v[50:51]
	v_lshl_add_u64 v[48:49], s[6:7], 0, v[48:49]
	s_and_saveexec_b64 s[28:29], s[2:3]
	s_xor_b64 s[28:29], exec, s[28:29]
	s_cbranch_execz .LBB0_263
	v_mov_b32_e32 v136, v142
	v_lshl_add_u64 v[52:53], v[136:137], 2, v[48:49]
	v_add_co_u32_e32 v52, vcc, 0x9895000, v52
	s_nop 1
	v_addc_co_u32_e32 v53, vcc, 0, v53, vcc
	global_store_dwordx4 v[52:53], v[44:47], off
	global_store_dwordx4 v[52:53], v[40:43], off offset:16
.LBB0_263:
	s_or_saveexec_b64 s[28:29], s[28:29]
	v_lshlrev_b64 v[50:51], 10, v[50:51]
	v_lshl_add_u64 v[52:53], v[50:51], 2, s[16:17]
	v_lshl_add_u64 v[50:51], v[50:51], 1, s[10:11]
	s_xor_b64 exec, exec, s[28:29]
	s_cbranch_execz .LBB0_287
	v_lshl_add_u64 v[54:55], v[142:143], 2, v[52:53]
	global_store_dwordx4 v[54:55], v[44:47], off
	global_store_dwordx4 v[54:55], v[40:43], off offset:16
	s_nop 0
	v_cvt_pk_bf16_f32 v44, v44, v45
	v_cvt_pk_bf16_f32 v45, v46, v47
	v_cvt_pk_bf16_f32 v46, v40, v41
	v_cvt_pk_bf16_f32 v47, v42, v43
	v_lshl_add_u64 v[40:41], v[142:143], 1, v[50:51]
	global_store_dwordx4 v[40:41], v[44:47], off
	s_or_b64 exec, exec, s[28:29]
	s_and_saveexec_b64 s[28:29], s[4:5]
	s_xor_b64 s[28:29], exec, s[28:29]
	s_cbranch_execnz .LBB0_288

; __device__ __forceinline__ unsigned pk2(float lo, float hi) { const f32x2 v = {lo, hi}; return __builtin_bit_cast(unsigned, __builtin_convertvector(v, bf16x2_t)); }
;     __device__ __forceinline__ void operator()(EPI_ARGS) const {
;         const int row0 = u.pm * BM + wr * 64 + fr;
; #pragma unroll
;         for (int ai = 0; ai < 2; ++ai)
; #pragma unroll
;             for (int m = 0; m < 4; ++m) { const int row = row0 + ai * HALF + m * 16;
; #pragma unroll
;                 for (int bj = 0; bj < 2; ++bj) { const int col = u.pn * BM + bj * HALF + wc * 32 + 8 * fq; const f32x4 v0 = acc[ai][bj][m][0], v1 = acc[ai][bj][m][1];
;                     if (col < 1024) { float* o = out + O_PMK + (size_t)row * 1024 + col; *(f32x4*)o = v0; *(f32x4*)(o + 4) = v1;
;                         u32x4 w; w.x = pk2(v0[0], v0[1]); w.y = pk2(v0[2], v0[3]); w.z = pk2(v1[0], v1[1]); w.w = pk2(v1[2], v1[3]);
;                         *(u32x4*)(MK + (size_t)row * 1024 + col) = w;
;                     } else { float* o = out + O_PMV + (size_t)row * 1024 + (col - 1024); *(f32x4*)o = v0; *(f32x4*)(o + 4) = v1; } } }
;     }
.LBB0_266:
	v_lshl_add_u64 v[40:41], v[142:143], 2, v[52:53]
	global_store_dwordx4 v[40:41], v[36:39], off offset:512
	global_store_dwordx4 v[40:41], v[32:35], off offset:528
	s_nop 0
	v_cvt_pk_bf16_f32 v36, v36, v37
	v_cvt_pk_bf16_f32 v37, v38, v39
	v_cvt_pk_bf16_f32 v38, v32, v33
	v_cvt_pk_bf16_f32 v39, v34, v35
	v_lshl_add_u64 v[32:33], v[142:143], 1, v[50:51]
	global_store_dwordx4 v[32:33], v[36:39], off offset:256
.LBB0_267:
	s_or_b64 exec, exec, s[28:29]
	v_add_u32_e32 v34, 0xa0, v144
	v_ashrrev_i32_e32 v35, 31, v34
	v_lshlrev_b64 v[32:33], 12, v[34:35]
	v_lshl_add_u64 v[32:33], s[6:7], 0, v[32:33]
	s_and_saveexec_b64 s[28:29], s[2:3]
	s_xor_b64 s[28:29], exec, s[28:29]
	s_cbranch_execz .LBB0_269
	v_mov_b32_e32 v136, v142
	v_lshl_add_u64 v[36:37], v[136:137], 2, v[32:33]
	v_add_co_u32_e32 v36, vcc, 0x9895000, v36
	s_nop 1
	v_addc_co_u32_e32 v37, vcc, 0, v37, vcc
	global_store_dwordx4 v[36:37], v[28:31], off
	global_store_dwordx4 v[36:37], v[24:27], off offset:16
.LBB0_269:
	s_or_saveexec_b64 s[28:29], s[28:29]
	v_lshlrev_b64 v[34:35], 10, v[34:35]
	v_lshl_add_u64 v[36:37], v[34:35], 2, s[16:17]
	v_lshl_add_u64 v[34:35], v[34:35], 1, s[10:11]
	s_xor_b64 exec, exec, s[28:29]
	s_cbranch_execz .LBB0_289
	v_lshl_add_u64 v[38:39], v[142:143], 2, v[36:37]
	global_store_dwordx4 v[38:39], v[28:31], off
	global_store_dwordx4 v[38:39], v[24:27], off offset:16
	s_nop 0
	v_cvt_pk_bf16_f32 v28, v28, v29
	v_cvt_pk_bf16_f32 v29, v30, v31
	v_cvt_pk_bf16_f32 v30, v24, v25
	v_cvt_pk_bf16_f32 v31, v26, v27
	v_lshl_add_u64 v[24:25], v[142:143], 1, v[34:35]
	global_store_dwordx4 v[24:25], v[28:31], off
	s_or_b64 exec, exec, s[28:29]
	s_and_saveexec_b64 s[28:29], s[4:5]
	s_xor_b64 s[28:29], exec, s[28:29]
	s_cbranch_execnz .LBB0_290

; __device__ __forceinline__ unsigned pk2(float lo, float hi) { const f32x2 v = {lo, hi}; return __builtin_bit_cast(unsigned, __builtin_convertvector(v, bf16x2_t)); }
;     __device__ __forceinline__ void operator()(EPI_ARGS) const {
;         const int row0 = u.pm * BM + wr * 64 + fr;
; #pragma unroll
;         for (int ai = 0; ai < 2; ++ai)
; #pragma unroll
;             for (int m = 0; m < 4; ++m) { const int row = row0 + ai * HALF + m * 16;
; #pragma unroll
;                 for (int bj = 0; bj < 2; ++bj) { const int col = u.pn * BM + bj * HALF + wc * 32 + 8 * fq; const f32x4 v0 = acc[ai][bj][m][0], v1 = acc[ai][bj][m][1];
;                     if (col < 1024) { float* o = out + O_PMK + (size_t)row * 1024 + col; *(f32x4*)o = v0; *(f32x4*)(o + 4) = v1;
;                         u32x4 w; w.x = pk2(v0[0], v0[1]); w.y = pk2(v0[2], v0[3]); w.z = pk2(v1[0], v1[1]); w.w = pk2(v1[2], v1[3]);
;                         *(u32x4*)(MK + (size_t)row * 1024 + col) = w;
;                     } else { float* o = out + O_PMV + (size_t)row * 1024 + (col - 1024); *(f32x4*)o = v0; *(f32x4*)(o + 4) = v1; } } }
;     }
.LBB0_272:
	v_lshl_add_u64 v[24:25], v[142:143], 2, v[36:37]
	global_store_dwordx4 v[24:25], v[20:23], off offset:512
	global_store_dwordx4 v[24:25], v[16:19], off offset:528
	s_nop 0
	v_cvt_pk_bf16_f32 v20, v20, v21
	v_cvt_pk_bf16_f32 v21, v22, v23
	v_cvt_pk_bf16_f32 v22, v16, v17
	v_cvt_pk_bf16_f32 v23, v18, v19
	v_lshl_add_u64 v[16:17], v[142:143], 1, v[34:35]
	global_store_dwordx4 v[16:17], v[20:23], off offset:256
.LBB0_273:
	s_or_b64 exec, exec, s[28:29]
	v_add_u32_e32 v18, 0xb0, v144
	v_ashrrev_i32_e32 v19, 31, v18
	v_lshlrev_b64 v[16:17], 12, v[18:19]
	v_lshl_add_u64 v[16:17], s[6:7], 0, v[16:17]
	s_and_saveexec_b64 s[28:29], s[2:3]
	s_xor_b64 s[2:3], exec, s[28:29]
	s_cbranch_execz .LBB0_275
	v_mov_b32_e32 v136, v142
	v_lshl_add_u64 v[20:21], v[136:137], 2, v[16:17]
	v_add_co_u32_e32 v20, vcc, 0x9895000, v20
	s_nop 1
	v_addc_co_u32_e32 v21, vcc, 0, v21, vcc
	global_store_dwordx4 v[20:21], v[12:15], off
	global_store_dwordx4 v[20:21], v[8:11], off offset:16
.LBB0_275:
	s_or_saveexec_b64 s[2:3], s[2:3]
	v_lshlrev_b64 v[18:19], 10, v[18:19]
	v_lshl_add_u64 v[20:21], v[18:19], 2, s[16:17]
	v_lshl_add_u64 v[18:19], v[18:19], 1, s[10:11]
	s_xor_b64 exec, exec, s[2:3]
	s_cbranch_execz .LBB0_291
	v_lshl_add_u64 v[22:23], v[142:143], 2, v[20:21]
	global_store_dwordx4 v[22:23], v[12:15], off
	global_store_dwordx4 v[22:23], v[8:11], off offset:16
	s_nop 0
	v_cvt_pk_bf16_f32 v12, v12, v13
	v_cvt_pk_bf16_f32 v13, v14, v15
	v_cvt_pk_bf16_f32 v14, v8, v9
	v_cvt_pk_bf16_f32 v15, v10, v11
	v_lshl_add_u64 v[8:9], v[142:143], 1, v[18:19]
	global_store_dwordx4 v[8:9], v[12:15], off
	s_or_b64 exec, exec, s[2:3]
	s_and_saveexec_b64 s[2:3], s[4:5]
	s_xor_b64 s[2:3], exec, s[2:3]
	s_cbranch_execnz .LBB0_292

; __device__ __forceinline__ unsigned pk2(float lo, float hi) { const f32x2 v = {lo, hi}; return __builtin_bit_cast(unsigned, __builtin_convertvector(v, bf16x2_t)); }
;     __device__ __forceinline__ void operator()(EPI_ARGS) const {
;         const int row0 = u.pm * BM + wr * 64 + fr;
; #pragma unroll
;         for (int ai = 0; ai < 2; ++ai)
; #pragma unroll
;             for (int m = 0; m < 4; ++m) { const int row = row0 + ai * HALF + m * 16;
; #pragma unroll
;                 for (int bj = 0; bj < 2; ++bj) { const int col = u.pn * BM + bj * HALF + wc * 32 + 8 * fq; const f32x4 v0 = acc[ai][bj][m][0], v1 = acc[ai][bj][m][1];
;                     if (col < 1024) { float* o = out + O_PMK + (size_t)row * 1024 + col; *(f32x4*)o = v0; *(f32x4*)(o + 4) = v1;
;                         u32x4 w; w.x = pk2(v0[0], v0[1]); w.y = pk2(v0[2], v0[3]); w.z = pk2(v1[0], v1[1]); w.w = pk2(v1[2], v1[3]);
;                         *(u32x4*)(MK + (size_t)row * 1024 + col) = w;
;                     } else { float* o = out + O_PMV + (size_t)row * 1024 + (col - 1024); *(f32x4*)o = v0; *(f32x4*)(o + 4) = v1; } } }
;     }
.LBB0_278:
	v_lshl_add_u64 v[8:9], v[142:143], 2, v[20:21]
	global_store_dwordx4 v[8:9], v[4:7], off offset:512
	global_store_dwordx4 v[8:9], v[0:3], off offset:528
	s_nop 0
	v_cvt_pk_bf16_f32 v4, v4, v5
	v_cvt_pk_bf16_f32 v5, v6, v7
	v_cvt_pk_bf16_f32 v6, v0, v1
	v_cvt_pk_bf16_f32 v7, v2, v3
	v_lshl_add_u64 v[0:1], v[142:143], 1, v[18:19]
	global_store_dwordx4 v[0:1], v[4:7], off offset:256
	s_or_b64 exec, exec, s[2:3]
	s_andn2_b64 vcc, exec, s[18:19]
	s_mov_b64 s[2:3], -1
	s_cbranch_vccnz .LBB0_218
	s_branch .LBB0_294

;     __device__ __forceinline__ void operator()(EPI_ARGS) const {
;     ...
;                     } else { float* o = out + O_PMV + (size_t)row * 1024 + (col - 1024); *(f32x4*)o = v0; *(f32x4*)(o + 4) = v1; } } }
.LBB0_280:
	v_mov_b32_e32 v136, v142
	v_lshl_add_u64 v[104:105], v[136:137], 2, v[112:113]
	v_add_co_u32_e32 v104, vcc, 0x9895000, v104
	s_nop 1
	v_addc_co_u32_e32 v105, vcc, 0, v105, vcc
	global_store_dwordx4 v[104:105], v[100:103], off offset:512
	global_store_dwordx4 v[104:105], v[96:99], off offset:528
	s_andn2_saveexec_b64 s[28:29], s[28:29]
	s_cbranch_execnz .LBB0_242
	s_branch .LBB0_243

;     __device__ __forceinline__ void operator()(EPI_ARGS) const {
;     ...
;                     } else { float* o = out + O_PMV + (size_t)row * 1024 + (col - 1024); *(f32x4*)o = v0; *(f32x4*)(o + 4) = v1; } } }
.LBB0_282:
	v_mov_b32_e32 v136, v142
	v_lshl_add_u64 v[88:89], v[136:137], 2, v[96:97]
	v_add_co_u32_e32 v88, vcc, 0x9895000, v88
	s_nop 1
	v_addc_co_u32_e32 v89, vcc, 0, v89, vcc
	global_store_dwordx4 v[88:89], v[84:87], off offset:512
	global_store_dwordx4 v[88:89], v[80:83], off offset:528
	s_andn2_saveexec_b64 s[28:29], s[28:29]
	s_cbranch_execnz .LBB0_248
	s_branch .LBB0_249

;     __device__ __forceinline__ void operator()(EPI_ARGS) const {
;     ...
;                     } else { float* o = out + O_PMV + (size_t)row * 1024 + (col - 1024); *(f32x4*)o = v0; *(f32x4*)(o + 4) = v1; } } }
.LBB0_284:
	v_mov_b32_e32 v136, v142
	v_lshl_add_u64 v[72:73], v[136:137], 2, v[80:81]
	v_add_co_u32_e32 v72, vcc, 0x9895000, v72
	s_nop 1
	v_addc_co_u32_e32 v73, vcc, 0, v73, vcc
	global_store_dwordx4 v[72:73], v[68:71], off offset:512
	global_store_dwordx4 v[72:73], v[64:67], off offset:528
	s_andn2_saveexec_b64 s[28:29], s[28:29]
	s_cbranch_execnz .LBB0_254
	s_branch .LBB0_255

;     __device__ __forceinline__ void operator()(EPI_ARGS) const {
;     ...
;                     } else { float* o = out + O_PMV + (size_t)row * 1024 + (col - 1024); *(f32x4*)o = v0; *(f32x4*)(o + 4) = v1; } } }
.LBB0_286:
	v_mov_b32_e32 v136, v142
	v_lshl_add_u64 v[56:57], v[136:137], 2, v[64:65]
	v_add_co_u32_e32 v56, vcc, 0x9895000, v56
	s_nop 1
	v_addc_co_u32_e32 v57, vcc, 0, v57, vcc
	global_store_dwordx4 v[56:57], v[52:55], off offset:512
	global_store_dwordx4 v[56:57], v[48:51], off offset:528
	s_andn2_saveexec_b64 s[28:29], s[28:29]
	s_cbranch_execnz .LBB0_260
	s_branch .LBB0_261

;     __device__ __forceinline__ void operator()(EPI_ARGS) const {
;     ...
;                     } else { float* o = out + O_PMV + (size_t)row * 1024 + (col - 1024); *(f32x4*)o = v0; *(f32x4*)(o + 4) = v1; } } }
.LBB0_288:
	v_mov_b32_e32 v136, v142
	v_lshl_add_u64 v[40:41], v[136:137], 2, v[48:49]
	v_add_co_u32_e32 v40, vcc, 0x9895000, v40
	s_nop 1
	v_addc_co_u32_e32 v41, vcc, 0, v41, vcc
	global_store_dwordx4 v[40:41], v[36:39], off offset:512
	global_store_dwordx4 v[40:41], v[32:35], off offset:528
	s_andn2_saveexec_b64 s[28:29], s[28:29]
	s_cbranch_execnz .LBB0_266
	s_branch .LBB0_267

;     __device__ __forceinline__ void operator()(EPI_ARGS) const {
;     ...
;                     } else { float* o = out + O_PMV + (size_t)row * 1024 + (col - 1024); *(f32x4*)o = v0; *(f32x4*)(o + 4) = v1; } } }
.LBB0_290:
	v_mov_b32_e32 v136, v142
	v_lshl_add_u64 v[24:25], v[136:137], 2, v[32:33]
	v_add_co_u32_e32 v24, vcc, 0x9895000, v24
	s_nop 1
	v_addc_co_u32_e32 v25, vcc, 0, v25, vcc
	global_store_dwordx4 v[24:25], v[20:23], off offset:512
	global_store_dwordx4 v[24:25], v[16:19], off offset:528
	s_andn2_saveexec_b64 s[28:29], s[28:29]
	s_cbranch_execnz .LBB0_272
	s_branch .LBB0_273

;     __device__ __forceinline__ void operator()(EPI_ARGS) const {
;     ...
;                     } else { float* o = out + O_PMV + (size_t)row * 1024 + (col - 1024); *(f32x4*)o = v0; *(f32x4*)(o + 4) = v1; } } }
.LBB0_292:
	v_mov_b32_e32 v143, v137
	v_lshl_add_u64 v[8:9], v[142:143], 2, v[16:17]
	v_add_co_u32_e32 v8, vcc, 0x9895000, v8
	s_nop 1
	v_addc_co_u32_e32 v9, vcc, 0, v9, vcc
	global_store_dwordx4 v[8:9], v[4:7], off offset:512
	global_store_dwordx4 v[8:9], v[0:3], off offset:528
	s_andn2_saveexec_b64 s[2:3], s[2:3]
	s_cbranch_execnz .LBB0_278

; __device__ __forceinline__ unsigned pk2(float lo, float hi) { const f32x2 v = {lo, hi}; return __builtin_bit_cast(unsigned, __builtin_convertvector(v, bf16x2_t)); }
;     __device__ __forceinline__ void operator()(EPI_ARGS) const {
;         const int row0 = u.pm * BM + wr * 64 + fr, col0 = u.pn * BM + wc * 32 + 8 * fq;
; #pragma unroll
;         for (int ai = 0; ai < 2; ++ai)
; #pragma unroll
;             for (int m = 0; m < 4; ++m) { bf16* rowp = O + (size_t)(row0 + ai * HALF + m * 16) * ldc + col0;
; #pragma unroll
;                 for (int bj = 0; bj < 2; ++bj) { const f32x4 v0 = acc[ai][bj][m][0], v1 = acc[ai][bj][m][1];
;                     u32x4 w; w.x = pk2(v0[0], v0[1]); w.y = pk2(v0[2], v0[3]); w.z = pk2(v1[0], v1[1]); w.w = pk2(v1[2], v1[3]);
;                     *(u32x4*)(rowp + bj * HALF) = w; } }
;     }
.LBB0_309:
	v_lshl_add_u32 v146, s20, 8, v140
	v_lshl_or_b32 v148, s21, 8, v142
	v_ashrrev_i32_e32 v147, 31, v146
	v_ashrrev_i32_e32 v149, 31, v148
	v_lshlrev_b64 v[150:151], 10, v[146:147]
	v_lshl_add_u64 v[150:151], s[6:7], 0, v[150:151]
	v_lshlrev_b64 v[148:149], 1, v[148:149]
	v_lshl_add_u64 v[150:151], v[150:151], 0, v[148:149]
	v_cvt_pk_bf16_f32 v60, v60, v61
	v_cvt_pk_bf16_f32 v61, v62, v63
	v_cvt_pk_bf16_f32 v62, v56, v57
	v_add_co_u32_e32 v56, vcc, s62, v150
	v_cvt_pk_bf16_f32 v68, v68, v69
	v_cvt_pk_bf16_f32 v69, v70, v71
	v_cvt_pk_bf16_f32 v70, v64, v65
	v_lshl_add_u64 v[64:65], v[150:151], 0, s[12:13]
	v_addc_co_u32_e32 v57, vcc, 0, v151, vcc
	v_cvt_pk_bf16_f32 v44, v44, v45
	v_cvt_pk_bf16_f32 v45, v46, v47
	v_cvt_pk_bf16_f32 v46, v40, v41
	v_cvt_pk_bf16_f32 v47, v42, v43
	v_cvt_pk_bf16_f32 v108, v108, v109
	v_cvt_pk_bf16_f32 v109, v110, v111
	v_cvt_pk_bf16_f32 v110, v104, v105
	v_or_b32_e32 v104, 16, v146
	global_store_dwordx4 v[64:65], v[44:47], off offset:256
	v_ashrrev_i32_e32 v105, 31, v104
	v_cvt_pk_bf16_f32 v92, v92, v93
	v_add_co_u32_e32 v46, vcc, s63, v150
	v_cvt_pk_bf16_f32 v93, v94, v95
	v_cvt_pk_bf16_f32 v94, v88, v89
	v_or_b32_e32 v88, 32, v146
	v_lshl_add_u64 v[44:45], v[150:151], 0, s[14:15]
	v_addc_co_u32_e32 v47, vcc, 0, v151, vcc
	v_cvt_pk_bf16_f32 v28, v28, v29
	v_cvt_pk_bf16_f32 v29, v30, v31
	v_cvt_pk_bf16_f32 v30, v24, v25
	v_cvt_pk_bf16_f32 v31, v26, v27
	v_lshlrev_b64 v[104:105], 10, v[104:105]
	v_ashrrev_i32_e32 v89, 31, v88
	v_cvt_pk_bf16_f32 v76, v76, v77
	v_cvt_pk_bf16_f32 v77, v78, v79
	v_cvt_pk_bf16_f32 v78, v72, v73
	v_or_b32_e32 v72, 48, v146
	global_store_dwordx4 v[44:45], v[28:31], off offset:256
	v_cvt_pk_bf16_f32 v111, v106, v107
	v_lshl_add_u64 v[104:105], s[6:7], 0, v[104:105]
	v_add_co_u32_e32 v30, vcc, s64, v150
	v_lshlrev_b64 v[88:89], 10, v[88:89]
	v_ashrrev_i32_e32 v73, 31, v72
	v_lshl_add_u64 v[28:29], v[150:151], 0, s[16:17]
	v_addc_co_u32_e32 v31, vcc, 0, v151, vcc
	v_cvt_pk_bf16_f32 v12, v12, v13
	v_cvt_pk_bf16_f32 v13, v14, v15
	v_cvt_pk_bf16_f32 v14, v8, v9
	v_cvt_pk_bf16_f32 v15, v10, v11
	global_store_dwordx4 v[150:151], v[108:111], off offset:256
	v_cvt_pk_bf16_f32 v95, v90, v91
	v_lshl_add_u64 v[88:89], s[6:7], 0, v[88:89]
	v_lshl_add_u64 v[108:109], v[104:105], 0, v[148:149]
	v_lshlrev_b64 v[72:73], 10, v[72:73]
	global_store_dwordx4 v[28:29], v[12:15], off offset:256
	global_store_dwordx4 v[108:109], v[92:95], off offset:256
	v_cvt_pk_bf16_f32 v79, v74, v75
	v_add_co_u32_e32 v14, vcc, s65, v150
	v_lshl_add_u64 v[92:93], v[88:89], 0, v[148:149]
	v_lshl_add_u64 v[72:73], s[6:7], 0, v[72:73]
	v_addc_co_u32_e32 v15, vcc, 0, v151, vcc
	v_cvt_pk_bf16_f32 v124, v124, v125
	v_cvt_pk_bf16_f32 v125, v126, v127
	v_cvt_pk_bf16_f32 v126, v120, v121
	v_cvt_pk_bf16_f32 v127, v122, v123
	v_cvt_pk_bf16_f32 v104, v116, v117
	v_cvt_pk_bf16_f32 v105, v118, v119
	v_cvt_pk_bf16_f32 v106, v112, v113
	v_cvt_pk_bf16_f32 v107, v114, v115
	v_cvt_pk_bf16_f32 v88, v100, v101
	v_cvt_pk_bf16_f32 v89, v102, v103
	v_cvt_pk_bf16_f32 v90, v96, v97
	v_cvt_pk_bf16_f32 v91, v98, v99
	global_store_dwordx4 v[92:93], v[76:79], off offset:256
	v_cvt_pk_bf16_f32 v74, v80, v81
	v_cvt_pk_bf16_f32 v75, v82, v83
	v_lshl_add_u64 v[76:77], v[72:73], 0, v[148:149]
	v_cvt_pk_bf16_f32 v72, v84, v85
	v_cvt_pk_bf16_f32 v73, v86, v87
	v_cvt_pk_bf16_f32 v71, v66, v67
	v_cvt_pk_bf16_f32 v63, v58, v59
	v_cvt_pk_bf16_f32 v40, v52, v53
	v_cvt_pk_bf16_f32 v41, v54, v55
	v_cvt_pk_bf16_f32 v42, v48, v49
	v_cvt_pk_bf16_f32 v43, v50, v51
	v_cvt_pk_bf16_f32 v24, v36, v37
	v_cvt_pk_bf16_f32 v25, v38, v39
	v_cvt_pk_bf16_f32 v26, v32, v33
	v_cvt_pk_bf16_f32 v27, v34, v35
	v_lshl_add_u64 v[12:13], v[150:151], 0, s[18:19]
	v_cvt_pk_bf16_f32 v8, v20, v21
	v_cvt_pk_bf16_f32 v9, v22, v23
	v_cvt_pk_bf16_f32 v10, v16, v17
	v_cvt_pk_bf16_f32 v11, v18, v19
	v_cvt_pk_bf16_f32 v4, v4, v5
	v_cvt_pk_bf16_f32 v5, v6, v7
	v_cvt_pk_bf16_f32 v6, v0, v1
	v_cvt_pk_bf16_f32 v7, v2, v3
	s_andn2_b64 vcc, exec, s[26:27]
	s_mov_b64 s[20:21], -1
	global_store_dwordx4 v[150:151], v[124:127], off
	global_store_dwordx4 v[108:109], v[104:107], off
	global_store_dwordx4 v[92:93], v[88:91], off
	global_store_dwordx4 v[76:77], v[72:75], off
	global_store_dwordx4 v[76:77], v[68:71], off offset:256
	global_store_dwordx4 v[56:57], v[60:63], off
	global_store_dwordx4 v[46:47], v[40:43], off
	global_store_dwordx4 v[30:31], v[24:27], off
	global_store_dwordx4 v[14:15], v[8:11], off
	global_store_dwordx4 v[12:13], v[4:7], off offset:256
	s_cbranch_vccnz .LBB0_302
	s_andn2_b64 vcc, exec, s[2:3]
	s_cbranch_vccnz .LBB0_301
	s_barrier
	s_branch .LBB0_301

; #define QNEXT(ctrw, dst) do { __syncthreads(); if (my_tid(lds) == 0) *(volatile LAS int*)(lds + TAB_OFF + 264) = (int)atomicAdd((unsigned*)tab_get(lds, 31) + 8192 + 64 * (ctrw), 1u); \
;         __syncthreads(); dst = __builtin_amdgcn_readfirstlane(*(volatile LAS int*)(lds + TAB_OFF + 264)); } while (0)
; __global__ void __launch_bounds__(512, 2) mega_fwd(Params p) {
;     ...
;           for (;;) { int it; QNEXT(0, it); if (it >= MP / 64) break;
.LBB0_316:
	s_waitcnt vmcnt(0)
	s_barrier
	s_getreg_b32 s4, hwreg(HW_REG_HW_ID, 0, 6)
	s_lshl_b32 s4, s4, 2
	s_and_b32 s4, s4, 0xfc
	s_add_i32 s4, s4, 0
	s_add_i32 s4, s4, 0x25a00
	v_mov_b32_e32 v20, s4
	ds_read_b32 v20, v20
	v_mbcnt_lo_u32_b32 v21, -1, 0
	v_mbcnt_hi_u32_b32 v21, -1, v21
	s_waitcnt lgkmcnt(0)
	v_readfirstlane_b32 s4, v20
	s_lshl_b32 s4, s4, 6
	v_sub_u32_e32 v20, 0, v21
	v_cmp_eq_u32_e32 vcc, s4, v20
	s_and_saveexec_b64 s[8:9], vcc
	s_cbranch_execz .LBB0_318
	ds_read_b64 v[20:21], v34
	s_waitcnt lgkmcnt(0)
	v_readfirstlane_b32 s10, v20
	v_readfirstlane_b32 s4, v21
	s_nop 0
	v_mov_b32_e32 v20, s10
	v_add_co_u32_e32 v20, vcc, 0x8000, v20
	v_mov_b32_e32 v21, s4
	s_nop 0
	v_addc_co_u32_e32 v21, vcc, 0, v21, vcc
	global_atomic_add v20, v[20:21], v37, off sc0
	s_waitcnt vmcnt(0) lgkmcnt(0)
	ds_write_b32 v38, v20

; __device__ __forceinline__ float bf2f(unsigned b) { return __uint_as_float(b << 16); }
; __device__ __forceinline__ bf16 f2bf(float f) { return (bf16)(pk2(f, 0.f) & 0xffffu); }
; __device__ __forceinline__ float ex2f(float x) { return __builtin_amdgcn_exp2f(x); }
; __device__ __forceinline__ void row_post(bf16* Z, bf16* CQN, bf16* CKV, bf16* KR, float* out, const float* qg, const float* kvg, int r, int lane) {
;     ...
;     { const float inv = ex2f(-(float)lane * (1.0f / 63.0f) * LG2_10000); float s, c; sincos_rev(pos * inv, s, c);
; #pragma unroll
;       for (int hh = 0; hh < 4; ++hh) {
;           bf16* q = z + ZC_RQ + hh * 128; const float a1 = bf2f(q[lane]), a2 = bf2f(q[64 + lane]); q[lane] = f2bf(a1 * c - a2 * s); q[64 + lane] = f2bf(a2 * c + a1 * s);
;           bf16* k = z + ZC_RK + hh * 128; const float b1 = bf2f(k[lane]), b2 = bf2f(k[64 + lane]); const float ks = 0.08838834764831845f;
;           k[lane] = f2bf((b1 * c - b2 * s) * ks); k[64 + lane] = f2bf((b2 * c + b1 * s) * ks); } }
.LBB0_320:
	s_or_b64 exec, exec, s[18:19]
	v_add_co_u32_e32 v32, vcc, 0x6800000, v32
	v_mul_f32_e32 v41, v36, v41
	s_nop 0
	v_addc_co_u32_e32 v33, vcc, 0, v33, vcc
	global_load_ushort v42, v[32:33], off offset:832
	global_load_ushort v43, v[32:33], off offset:960
	global_load_ushort v44, v[32:33], off offset:1856
	global_load_ushort v45, v[32:33], off offset:1984
	global_load_ushort v46, v[32:33], off offset:1088
	global_load_ushort v47, v[32:33], off offset:1216
	global_load_ushort v48, v[32:33], off offset:2112
	global_load_ushort v49, v[32:33], off offset:2240
	global_load_ushort v50, v[32:33], off offset:1344
	global_load_ushort v51, v[32:33], off offset:1472
	global_load_ushort v52, v[32:33], off offset:2368
	global_load_ushort v53, v[32:33], off offset:2496
	global_load_ushort v54, v[32:33], off offset:1600
	global_load_ushort v55, v[32:33], off offset:1728
	global_load_ushort v57, v[32:33], off offset:2624
	global_load_ushort v58, v[32:33], off offset:2752
	v_mul_f32_e32 v56, 0.15915494, v41
	v_floor_f32_e32 v56, v56
	v_fma_f32 v41, v41, 0.15915494, -v56
	v_sin_f32_e32 v56, v41
	v_cos_f32_e32 v41, v41
	s_add_u32 s14, s14, 0x1400
	s_addc_u32 s15, s15, 0
	s_add_u32 s12, s12, 1
	s_addc_u32 s13, s13, 0
	s_add_u32 s10, s10, 0x200
	s_addc_u32 s11, s11, 0
	v_lshl_add_u64 v[20:21], v[20:21], 0, s[6:7]
	s_cmpk_eq_u32 s14, 0xa000
	v_lshl_add_u64 v[22:23], v[22:23], 0, 64
	s_waitcnt vmcnt(0) lgkmcnt(0)
	v_lshlrev_b32_e32 v42, 16, v42
	v_lshlrev_b32_e32 v43, 16, v43
	v_lshlrev_b32_e32 v44, 16, v44
	v_lshlrev_b32_e32 v45, 16, v45
	v_mul_f32_e32 v59, v56, v43
	v_lshlrev_b32_e32 v47, 16, v47
	v_mul_f32_e32 v43, v41, v43
	v_lshlrev_b32_e32 v49, 16, v49
	v_mul_f32_e32 v60, v56, v45
	v_lshlrev_b32_e32 v51, 16, v51
	v_lshlrev_b32_e32 v46, 16, v46
	v_lshlrev_b32_e32 v53, 16, v53
	v_lshlrev_b32_e32 v48, 16, v48
	v_lshlrev_b32_e32 v50, 16, v50
	v_lshlrev_b32_e32 v52, 16, v52
	v_mul_f32_e32 v45, v41, v45
	v_mul_f32_e32 v61, v56, v47
	v_mul_f32_e32 v47, v41, v47
	v_mul_f32_e32 v62, v56, v49
	v_mul_f32_e32 v49, v41, v49
	v_mul_f32_e32 v63, v56, v51
	v_mul_f32_e32 v51, v41, v51
	v_mul_f32_e32 v64, v56, v53
	v_fma_f32 v59, v41, v42, -v59
	v_fmac_f32_e32 v43, v56, v42
	v_fma_f32 v42, v41, v44, -v60
	v_fmac_f32_e32 v45, v56, v44
	v_fma_f32 v44, v41, v46, -v61
	v_fmac_f32_e32 v47, v56, v46
	v_fma_f32 v46, v41, v48, -v62
	v_fmac_f32_e32 v49, v56, v48
	v_fma_f32 v48, v41, v50, -v63
	v_fmac_f32_e32 v51, v56, v50
	v_fma_f32 v50, v41, v52, -v64
	v_mul_f32_e32 v42, 0x3db504f3, v42
	v_cvt_pk_bf16_f32 v59, v59, s0
	v_cvt_pk_bf16_f32 v43, v43, s0
	v_mul_f32_e32 v45, 0x3db504f3, v45
	v_cvt_pk_bf16_f32 v44, v44, s0
	v_mul_f32_e32 v46, 0x3db504f3, v46
	v_mul_f32_e32 v49, 0x3db504f3, v49
	v_cvt_pk_bf16_f32 v48, v48, s0
	v_mul_f32_e32 v50, 0x3db504f3, v50
	v_cvt_pk_bf16_f32 v42, v42, s0
	v_cvt_pk_bf16_f32 v47, v47, s0
	v_cvt_pk_bf16_f32 v51, v51, s0
	global_store_short v[32:33], v59, off offset:832
	global_store_short v[32:33], v43, off offset:960
	v_cvt_pk_bf16_f32 v43, v45, s0
	global_store_short v[32:33], v44, off offset:1088
	global_store_short v[32:33], v47, off offset:1216
	v_cvt_pk_bf16_f32 v44, v46, s0
	v_cvt_pk_bf16_f32 v45, v49, s0
	global_store_short v[32:33], v48, off offset:1344
	global_store_short v[32:33], v51, off offset:1472
	v_cvt_pk_bf16_f32 v46, v50, s0
	global_store_short v[32:33], v42, off offset:1856
	global_store_short v[32:33], v43, off offset:1984
	global_store_short v[32:33], v44, off offset:2112
	global_store_short v[32:33], v45, off offset:2240
	global_store_short v[32:33], v46, off offset:2368
	v_mul_f32_e32 v42, v41, v53
	v_fmac_f32_e32 v42, v56, v52
	v_mul_f32_e32 v42, 0x3db504f3, v42
	v_cvt_pk_bf16_f32 v42, v42, s0
	v_lshlrev_b32_e32 v43, 16, v55
	global_store_short v[32:33], v42, off offset:2496
	v_lshlrev_b32_e32 v42, 16, v54
	v_mul_f32_e32 v44, v56, v43
	v_mul_f32_e32 v43, v41, v43
	v_fma_f32 v44, v41, v42, -v44
	v_fmac_f32_e32 v43, v56, v42
	v_cvt_pk_bf16_f32 v44, v44, s0
	v_cvt_pk_bf16_f32 v42, v43, s0
	v_lshlrev_b32_e32 v43, 16, v58
	global_store_short v[32:33], v44, off offset:1600
	global_store_short v[32:33], v42, off offset:1728
	v_lshlrev_b32_e32 v42, 16, v57
	v_mul_f32_e32 v44, v56, v43
	v_fma_f32 v44, v41, v42, -v44
	v_mul_f32_e32 v41, v41, v43
	v_fmac_f32_e32 v41, v56, v42
	v_mul_f32_e32 v44, 0x3db504f3, v44
	v_mul_f32_e32 v41, 0x3db504f3, v41
	v_cvt_pk_bf16_f32 v44, v44, s0
	v_cvt_pk_bf16_f32 v41, v41, s0
	global_store_short v[32:33], v44, off offset:2624
	global_store_short v[32:33], v41, off offset:2752
	s_cbranch_scc1 .LBB0_314
; __device__ __forceinline__ float bf2f(unsigned b) { return __uint_as_float(b << 16); }
; __device__ __forceinline__ float bflo(unsigned w) { return __uint_as_float(w << 16); }
; __device__ __forceinline__ float bfhi(unsigned w) { return __uint_as_float(w & 0xffff0000u); }
; __device__ __forceinline__ unsigned pk2(float lo, float hi) { const f32x2 v = {lo, hi}; return __builtin_bit_cast(unsigned, __builtin_convertvector(v, bf16x2_t)); }
; __device__ __forceinline__ bf16 f2bf(float f) { return (bf16)(pk2(f, 0.f) & 0xffffu); }
; __device__ __forceinline__ float ex2f(float x) { return __builtin_amdgcn_exp2f(x); }
; __device__ __forceinline__ void row_post(bf16* Z, bf16* CQN, bf16* CKV, bf16* KR, float* out, const float* qg, const float* kvg, int r, int lane) {
;     bf16* z = Z + (size_t)r * NZ; const float pos = (float)row_pos(r);
;     { const u32x2 raw = *(const u32x2*)(z + 4 * lane); const float v0 = bflo(raw.x), v1 = bfhi(raw.x), v2 = bflo(raw.y), v3 = bfhi(raw.y);
;       const float rstd = rsqrtf(wave_sum((v0 * v0 + v1 * v1) + (v2 * v2 + v3 * v3)) * (1.f / 256.f) + EPS); const f32x4 g = *(const f32x4*)(qg + 4 * lane);
;       u32x2 w; w.x = pk2(v0 * rstd * g.x, v1 * rstd * g.y); w.y = pk2(v2 * rstd * g.z, v3 * rstd * g.w); *(u32x2*)(CQN + (size_t)r * 256 + 4 * lane) = w; }
;     { const unsigned raw = *(const unsigned*)(z + ZC_CKV + 2 * lane); const float v0 = bflo(raw), v1 = bfhi(raw);
;       const float rstd = rsqrtf(wave_sum(v0 * v0 + v1 * v1) * (1.f / 128.f) + EPS); const f32x2 g = *(const f32x2*)(kvg + 2 * lane);
;       const float y0 = v0 * rstd * g.x, y1 = v1 * rstd * g.y;
;       float* o = (r < MP ? out + O_PCKV + (size_t)r * 128 : out + O_SCKV + (size_t)(r - MP) * 128) + 2 * lane; *(f32x2*)o = (f32x2){y0, y1};
;       if (r < MP) *(unsigned*)(CKV + (size_t)r * 128 + 2 * lane) = pk2(y0, y1); }
;     if (lane < 16) { const float x1 = bf2f(z[ZC_KR + lane]), x2 = bf2f(z[ZC_KR + 16 + lane]); const float inv = ex2f(-(float)lane * (2.0f / 32.0f) * LG2_10000);
;       float s, c; sincos_rev(pos * inv, s, c); const float o1 = x1 * c - x2 * s, o2 = x2 * c + x1 * s;
;       float* o = (r < MP ? out + O_PKR + (size_t)r * 32 : out + O_SKR + (size_t)(r - MP) * 32); o[lane] = o1; o[16 + lane] = o2;
;       if (r < MP) { KR[(size_t)r * 32 + lane] = f2bf(o1); KR[(size_t)r * 32 + 16 + lane] = f2bf(o2); } }
.LBB0_321:
	v_lshl_add_u64 v[32:33], v[30:31], 0, s[14:15]
	global_load_dwordx2 v[46:47], v[32:33], off
	global_load_dwordx4 v[42:45], v[2:3], off
	s_add_i32 s35, s8, s12
	s_cmp_lt_i32 s35, 0x8000
	s_cselect_b64 s[16:17], -1, 0
	s_add_u32 s36, s28, s10
	s_addc_u32 s37, s29, s11
	s_add_u32 s38, s31, s10
	s_addc_u32 s39, s34, s11
	s_and_b64 s[18:19], s[16:17], exec
	s_cselect_b32 s18, s36, s38
	s_cselect_b32 s19, s37, s39
	s_cmpk_gt_i32 s35, 0x7fff
	s_waitcnt vmcnt(0) lgkmcnt(0)
	v_lshlrev_b32_e32 v32, 16, v47
	v_and_b32_e32 v33, 0xffff0000, v47
	v_lshlrev_b32_e32 v48, 16, v46
	v_and_b32_e32 v49, 0xffff0000, v46
	v_pk_mul_f32 v[46:47], v[32:33], v[32:33]
	v_pk_mul_f32 v[50:51], v[48:49], v[48:49]
	v_add_f32_e32 v41, v46, v47
	v_add_f32_e32 v46, v50, v51
	v_add_f32_e32 v41, v46, v41
	ds_swizzle_b32 v46, v41 offset:swizzle(SWAP,1)
	v_lshl_add_u64 v[50:51], v[28:29], 0, s[14:15]
	s_waitcnt lgkmcnt(0)
	v_add_f32_e32 v41, v41, v46
	ds_swizzle_b32 v46, v41 offset:swizzle(SWAP,2)
	s_waitcnt lgkmcnt(0)
	v_add_f32_e32 v41, v41, v46
	ds_swizzle_b32 v46, v41 offset:swizzle(SWAP,4)
	s_waitcnt lgkmcnt(0)
	v_add_f32_e32 v41, v41, v46
	ds_swizzle_b32 v46, v41 offset:swizzle(SWAP,8)
	s_waitcnt lgkmcnt(0)
	v_add_f32_e32 v41, v41, v46
	ds_swizzle_b32 v46, v41 offset:swizzle(SWAP,16)
	s_waitcnt lgkmcnt(0)
	v_add_f32_e32 v41, v41, v46
	v_mov_b32_e32 v46, v41
	s_nop 1
	v_permlane32_swap_b32_e32 v41, v46
	v_add_f32_e32 v41, v41, v46
	v_fmamk_f32 v41, v41, 0x3b800000, v39
	v_mul_f32_e32 v46, 0x4b800000, v41
	v_cmp_gt_f32_e32 vcc, s26, v41
	s_nop 1
	v_cndmask_b32_e32 v41, v41, v46, vcc
	v_rsq_f32_e32 v41, v41
	v_lshl_add_u64 v[46:47], v[24:25], 0, s[10:11]
	v_mul_f32_e32 v52, 0x45800000, v41
	v_cndmask_b32_e32 v52, v41, v52, vcc
	v_pk_mul_f32 v[48:49], v[52:53], v[48:49] op_sel_hi:[0,1]
	v_pk_mul_f32 v[32:33], v[52:53], v[32:33] op_sel_hi:[0,1]
	v_pk_mul_f32 v[42:43], v[42:43], v[48:49]
	v_pk_mul_f32 v[32:33], v[44:45], v[32:33]
	v_cvt_pk_bf16_f32 v42, v42, v43
	v_cvt_pk_bf16_f32 v43, v32, v33
	global_store_dwordx2 v[46:47], v[42:43], off
	global_load_dword v41, v[50:51], off
	global_load_dwordx2 v[32:33], v[4:5], off
	s_waitcnt vmcnt(0) lgkmcnt(0)
	v_lshlrev_b32_e32 v42, 16, v41
	v_and_b32_e32 v43, 0xffff0000, v41
	v_pk_mul_f32 v[44:45], v[42:43], v[42:43]
	s_nop 0
	v_add_f32_e32 v41, v44, v45
	ds_swizzle_b32 v44, v41 offset:swizzle(SWAP,1)
	s_waitcnt lgkmcnt(0)
	v_add_f32_e32 v41, v41, v44
	ds_swizzle_b32 v44, v41 offset:swizzle(SWAP,2)
	s_waitcnt lgkmcnt(0)
	v_add_f32_e32 v41, v41, v44
	ds_swizzle_b32 v44, v41 offset:swizzle(SWAP,4)
	s_waitcnt lgkmcnt(0)
	v_add_f32_e32 v41, v41, v44
	ds_swizzle_b32 v44, v41 offset:swizzle(SWAP,8)
	s_waitcnt lgkmcnt(0)
	v_add_f32_e32 v41, v41, v44
	ds_swizzle_b32 v44, v41 offset:swizzle(SWAP,16)
	s_waitcnt lgkmcnt(0)
	v_add_f32_e32 v41, v41, v44
	v_mov_b32_e32 v44, v41
	s_nop 1
	v_permlane32_swap_b32_e32 v41, v44
	v_add_f32_e32 v41, v41, v44
	v_fmamk_f32 v41, v41, 0x3c000000, v39
	v_mul_f32_e32 v44, 0x4b800000, v41
	v_cmp_gt_f32_e32 vcc, s26, v41
	s_nop 1
	v_cndmask_b32_e32 v41, v41, v44, vcc
	v_rsq_f32_e32 v41, v41
	s_nop 0
	v_mul_f32_e32 v44, 0x45800000, v41
	v_cndmask_b32_e32 v44, v41, v44, vcc
	v_pk_mul_f32 v[42:43], v[44:45], v[42:43] op_sel_hi:[0,1]
	v_pk_mul_f32 v[32:33], v[32:33], v[42:43]
	v_lshl_add_u64 v[42:43], s[18:19], 0, v[18:19]
	global_store_dwordx2 v[42:43], v[32:33], off
	s_cbranch_scc1 .LBB0_323
	v_cvt_pk_bf16_f32 v32, v32, v33
	global_store_dword v[20:21], v32, off
.LBB0_323:
	s_and_b64 s[18:19], s[16:17], exec
	s_cselect_b32 s18, s30, s22
	s_add_i32 s18, s18, s12
	v_cvt_f32_u32_e32 v41, s18
	v_lshl_add_u64 v[32:33], v[26:27], 0, s[14:15]
	s_and_saveexec_b64 s[18:19], s[2:3]
	s_cbranch_execz .LBB0_320
	v_add_co_u32_e32 v42, vcc, 0x6800000, v32
	s_add_u32 s35, s8, s12
	s_nop 0
	v_addc_co_u32_e32 v43, vcc, 0, v33, vcc
	global_load_ushort v46, v[42:43], off offset:768
	global_load_ushort v47, v[42:43], off offset:800
	v_mul_f32_e32 v42, v35, v41
	s_addc_u32 s36, s9, s13
	v_cndmask_b32_e64 v43, 0, 1, s[16:17]
	v_mul_f32_e32 v44, 0.15915494, v42
	s_add_u32 s37, s4, s12
	v_cmp_ne_u32_e32 vcc, 1, v43
	v_floor_f32_e32 v43, v44
	s_addc_u32 s38, 0, s13
	v_fma_f32 v42, v42, 0.15915494, -v43
	s_and_b64 s[16:17], s[16:17], exec
	v_sin_f32_e32 v48, v42
	v_cos_f32_e32 v43, v42
	s_cselect_b32 s16, s35, s37
	s_cselect_b32 s35, s27, 0x9ad6000
	s_cselect_b32 s17, s36, s38
	s_add_u32 s35, s1, s35
	s_addc_u32 s36, s0, 0
	s_lshl_b64 s[16:17], s[16:17], 7
	s_add_u32 s16, s35, s16
	s_addc_u32 s17, s36, s17
	s_and_b64 vcc, exec, vcc
	v_lshl_add_u64 v[44:45], s[16:17], 0, v[0:1]
	s_waitcnt vmcnt(0) lgkmcnt(0)
	v_lshlrev_b32_e32 v46, 16, v46
	v_lshlrev_b32_e32 v42, 16, v47
	v_mul_f32_e32 v47, v48, v42
	v_mul_f32_e32 v42, v43, v42
	v_fma_f32 v43, v43, v46, -v47
	v_fmac_f32_e32 v42, v48, v46
	global_store_dword v[44:45], v43, off
	global_store_dword v[44:45], v42, off offset:64
	s_cbranch_vccnz .LBB0_320
	v_cvt_pk_bf16_f32 v45, v42, s0
	v_add_co_u32_e32 v42, vcc, 0xffffffe0, v22
	v_cvt_pk_bf16_f32 v44, v43, s0
	s_nop 0
	v_addc_co_u32_e32 v43, vcc, -1, v23, vcc
	global_store_short v[42:43], v44, off
	global_store_short v[22:23], v45, off
	s_branch .LBB0_320

; __device__ __forceinline__ float bf2f(unsigned b) { return __uint_as_float(b << 16); }
; __device__ __forceinline__ bf16 f2bf(float f) { return (bf16)(pk2(f, 0.f) & 0xffffu); }
; __device__ __forceinline__ float ex2f(float x) { return __builtin_amdgcn_exp2f(x); }
; __device__ __forceinline__ void row_post(bf16* Z, bf16* CQN, bf16* CKV, bf16* KR, float* out, const float* qg, const float* kvg, int r, int lane) {
;     ...
;     { const float inv = ex2f(-(float)lane * (1.0f / 63.0f) * LG2_10000); float s, c; sincos_rev(pos * inv, s, c);
; #pragma unroll
;       for (int hh = 0; hh < 4; ++hh) {
;           bf16* q = z + ZC_RQ + hh * 128; const float a1 = bf2f(q[lane]), a2 = bf2f(q[64 + lane]); q[lane] = f2bf(a1 * c - a2 * s); q[64 + lane] = f2bf(a2 * c + a1 * s);
;           bf16* k = z + ZC_RK + hh * 128; const float b1 = bf2f(k[lane]), b2 = bf2f(k[64 + lane]); const float ks = 0.08838834764831845f;
;           k[lane] = f2bf((b1 * c - b2 * s) * ks); k[64 + lane] = f2bf((b2 * c + b1 * s) * ks); } }
.LBB0_372:
	s_or_b64 exec, exec, s[22:23]
	v_add_co_u32_e32 v18, vcc, 0x6800000, v18
	v_mul_f32_e32 v23, v21, v23
	s_nop 0
	v_addc_co_u32_e32 v19, vcc, 0, v19, vcc
	global_load_ushort v24, v[18:19], off offset:832
	global_load_ushort v25, v[18:19], off offset:960
	global_load_ushort v26, v[18:19], off offset:1856
	global_load_ushort v27, v[18:19], off offset:1984
	global_load_ushort v28, v[18:19], off offset:1088
	global_load_ushort v29, v[18:19], off offset:1216
	global_load_ushort v30, v[18:19], off offset:2112
	global_load_ushort v31, v[18:19], off offset:2240
	global_load_ushort v32, v[18:19], off offset:1344
	global_load_ushort v33, v[18:19], off offset:1472
	global_load_ushort v34, v[18:19], off offset:2368
	global_load_ushort v35, v[18:19], off offset:2496
	global_load_ushort v36, v[18:19], off offset:1600
	global_load_ushort v37, v[18:19], off offset:1728
	global_load_ushort v39, v[18:19], off offset:2624
	global_load_ushort v40, v[18:19], off offset:2752
	v_mul_f32_e32 v38, 0.15915494, v23
	v_floor_f32_e32 v38, v38
	v_fma_f32 v23, v23, 0.15915494, -v38
	v_sin_f32_e32 v38, v23
	v_cos_f32_e32 v23, v23
	s_add_i32 s6, s6, s44
	s_add_u32 s12, s12, s14
	s_addc_u32 s13, s13, s15
	s_add_u32 s8, s8, s44
	s_addc_u32 s9, s9, s45
	s_add_u32 s16, s16, s18
	s_addc_u32 s17, s17, s19
	s_add_u32 s20, s20, s30
	s_addc_u32 s21, s21, s29
	s_cmpk_gt_i32 s6, 0x1ff
	v_lshl_add_u64 v[12:13], v[12:13], 0, s[10:11]
	s_waitcnt vmcnt(0) lgkmcnt(0)
	v_lshlrev_b32_e32 v24, 16, v24
	v_lshlrev_b32_e32 v25, 16, v25
	v_lshlrev_b32_e32 v26, 16, v26
	v_lshlrev_b32_e32 v27, 16, v27
	v_mul_f32_e32 v41, v38, v25
	v_lshlrev_b32_e32 v29, 16, v29
	v_mul_f32_e32 v25, v23, v25
	v_lshlrev_b32_e32 v31, 16, v31
	v_mul_f32_e32 v42, v38, v27
	v_lshlrev_b32_e32 v33, 16, v33
	v_lshlrev_b32_e32 v28, 16, v28
	v_lshlrev_b32_e32 v35, 16, v35
	v_lshlrev_b32_e32 v30, 16, v30
	v_lshlrev_b32_e32 v32, 16, v32
	v_lshlrev_b32_e32 v34, 16, v34
	v_mul_f32_e32 v27, v23, v27
	v_mul_f32_e32 v43, v38, v29
	v_mul_f32_e32 v29, v23, v29
	v_mul_f32_e32 v44, v38, v31
	v_mul_f32_e32 v31, v23, v31
	v_mul_f32_e32 v45, v38, v33
	v_mul_f32_e32 v33, v23, v33
	v_mul_f32_e32 v46, v38, v35
	v_fma_f32 v41, v23, v24, -v41
	v_fmac_f32_e32 v25, v38, v24
	v_fma_f32 v24, v23, v26, -v42
	v_fmac_f32_e32 v27, v38, v26
	v_fma_f32 v26, v23, v28, -v43
	v_fmac_f32_e32 v29, v38, v28
	v_fma_f32 v28, v23, v30, -v44
	v_fmac_f32_e32 v31, v38, v30
	v_fma_f32 v30, v23, v32, -v45
	v_fmac_f32_e32 v33, v38, v32
	v_fma_f32 v32, v23, v34, -v46
	v_mul_f32_e32 v24, 0x3db504f3, v24
	v_cvt_pk_bf16_f32 v41, v41, s0
	v_cvt_pk_bf16_f32 v25, v25, s0
	v_mul_f32_e32 v27, 0x3db504f3, v27
	v_cvt_pk_bf16_f32 v26, v26, s0
	v_mul_f32_e32 v28, 0x3db504f3, v28
	v_mul_f32_e32 v31, 0x3db504f3, v31
	v_cvt_pk_bf16_f32 v30, v30, s0
	v_mul_f32_e32 v32, 0x3db504f3, v32
	v_cvt_pk_bf16_f32 v24, v24, s0
	v_cvt_pk_bf16_f32 v29, v29, s0
	v_cvt_pk_bf16_f32 v33, v33, s0
	global_store_short v[18:19], v41, off offset:832
	global_store_short v[18:19], v25, off offset:960
	v_cvt_pk_bf16_f32 v25, v27, s0
	global_store_short v[18:19], v26, off offset:1088
	global_store_short v[18:19], v29, off offset:1216
	v_cvt_pk_bf16_f32 v26, v28, s0
	v_cvt_pk_bf16_f32 v27, v31, s0
	global_store_short v[18:19], v30, off offset:1344
	global_store_short v[18:19], v33, off offset:1472
	v_cvt_pk_bf16_f32 v28, v32, s0
	global_store_short v[18:19], v24, off offset:1856
	global_store_short v[18:19], v25, off offset:1984
	global_store_short v[18:19], v26, off offset:2112
	global_store_short v[18:19], v27, off offset:2240
	global_store_short v[18:19], v28, off offset:2368
	v_mul_f32_e32 v24, v23, v35
	v_fmac_f32_e32 v24, v38, v34
	v_mul_f32_e32 v24, 0x3db504f3, v24
	v_cvt_pk_bf16_f32 v24, v24, s0
	v_lshlrev_b32_e32 v25, 16, v37
	global_store_short v[18:19], v24, off offset:2496
	v_lshlrev_b32_e32 v24, 16, v36
	v_mul_f32_e32 v26, v38, v25
	v_mul_f32_e32 v25, v23, v25
	v_fma_f32 v26, v23, v24, -v26
	v_fmac_f32_e32 v25, v38, v24
	v_cvt_pk_bf16_f32 v26, v26, s0
	v_cvt_pk_bf16_f32 v24, v25, s0
	v_lshlrev_b32_e32 v25, 16, v40
	global_store_short v[18:19], v26, off offset:1600
	global_store_short v[18:19], v24, off offset:1728
	v_lshlrev_b32_e32 v24, 16, v39
	v_mul_f32_e32 v26, v38, v25
	v_fma_f32 v26, v23, v24, -v26
	v_mul_f32_e32 v23, v23, v25
	v_fmac_f32_e32 v23, v38, v24
	v_mul_f32_e32 v26, 0x3db504f3, v26
	v_mul_f32_e32 v23, 0x3db504f3, v23
	v_cvt_pk_bf16_f32 v26, v26, s0
	v_cvt_pk_bf16_f32 v23, v23, s0
	global_store_short v[18:19], v26, off offset:2624
	global_store_short v[18:19], v23, off offset:2752
	s_cbranch_scc1 .LBB0_378
; __device__ __forceinline__ float bf2f(unsigned b) { return __uint_as_float(b << 16); }
; __device__ __forceinline__ float bflo(unsigned w) { return __uint_as_float(w << 16); }
; __device__ __forceinline__ float bfhi(unsigned w) { return __uint_as_float(w & 0xffff0000u); }
; __device__ __forceinline__ unsigned pk2(float lo, float hi) { const f32x2 v = {lo, hi}; return __builtin_bit_cast(unsigned, __builtin_convertvector(v, bf16x2_t)); }
; __device__ __forceinline__ bf16 f2bf(float f) { return (bf16)(pk2(f, 0.f) & 0xffffu); }
; __device__ __forceinline__ float ex2f(float x) { return __builtin_amdgcn_exp2f(x); }
; __device__ __forceinline__ void row_post(bf16* Z, bf16* CQN, bf16* CKV, bf16* KR, float* out, const float* qg, const float* kvg, int r, int lane) {
;     bf16* z = Z + (size_t)r * NZ; const float pos = (float)row_pos(r);
;     { const u32x2 raw = *(const u32x2*)(z + 4 * lane); const float v0 = bflo(raw.x), v1 = bfhi(raw.x), v2 = bflo(raw.y), v3 = bfhi(raw.y);
;       const float rstd = rsqrtf(wave_sum((v0 * v0 + v1 * v1) + (v2 * v2 + v3 * v3)) * (1.f / 256.f) + EPS); const f32x4 g = *(const f32x4*)(qg + 4 * lane);
;       u32x2 w; w.x = pk2(v0 * rstd * g.x, v1 * rstd * g.y); w.y = pk2(v2 * rstd * g.z, v3 * rstd * g.w); *(u32x2*)(CQN + (size_t)r * 256 + 4 * lane) = w; }
;     { const unsigned raw = *(const unsigned*)(z + ZC_CKV + 2 * lane); const float v0 = bflo(raw), v1 = bfhi(raw);
;       const float rstd = rsqrtf(wave_sum(v0 * v0 + v1 * v1) * (1.f / 128.f) + EPS); const f32x2 g = *(const f32x2*)(kvg + 2 * lane);
;       const float y0 = v0 * rstd * g.x, y1 = v1 * rstd * g.y;
;       float* o = (r < MP ? out + O_PCKV + (size_t)r * 128 : out + O_SCKV + (size_t)(r - MP) * 128) + 2 * lane; *(f32x2*)o = (f32x2){y0, y1};
;       if (r < MP) *(unsigned*)(CKV + (size_t)r * 128 + 2 * lane) = pk2(y0, y1); }
;     if (lane < 16) { const float x1 = bf2f(z[ZC_KR + lane]), x2 = bf2f(z[ZC_KR + 16 + lane]); const float inv = ex2f(-(float)lane * (2.0f / 32.0f) * LG2_10000);
;       float s, c; sincos_rev(pos * inv, s, c); const float o1 = x1 * c - x2 * s, o2 = x2 * c + x1 * s;
;       float* o = (r < MP ? out + O_PKR + (size_t)r * 32 : out + O_SKR + (size_t)(r - MP) * 32); o[lane] = o1; o[16 + lane] = o2;
;       if (r < MP) { KR[(size_t)r * 32 + lane] = f2bf(o1); KR[(size_t)r * 32 + 16 + lane] = f2bf(o2); } }
.LBB0_373:
	v_lshl_add_u64 v[18:19], s[20:21], 0, v[14:15]
	global_load_dwordx2 v[28:29], v[18:19], off
	global_load_dwordx4 v[24:27], v[4:5], off
	s_add_u32 s36, s27, s16
	s_addc_u32 s37, s28, s17
	s_waitcnt vmcnt(0) lgkmcnt(0)
	v_lshlrev_b32_e32 v18, 16, v29
	v_and_b32_e32 v19, 0xffff0000, v29
	v_lshlrev_b32_e32 v30, 16, v28
	v_and_b32_e32 v31, 0xffff0000, v28
	v_pk_mul_f32 v[28:29], v[18:19], v[18:19]
	v_pk_mul_f32 v[32:33], v[30:31], v[30:31]
	v_add_f32_e32 v23, v28, v29
	v_add_f32_e32 v28, v32, v33
	v_add_f32_e32 v23, v28, v23
	ds_swizzle_b32 v28, v23 offset:swizzle(SWAP,1)
	v_lshl_add_u64 v[32:33], s[20:21], 0, v[0:1]
	v_add_co_u32_e64 v32, s[4:5], s31, v32
	s_waitcnt lgkmcnt(0)
	v_add_f32_e32 v23, v23, v28
	ds_swizzle_b32 v28, v23 offset:swizzle(SWAP,2)
	v_addc_co_u32_e64 v33, s[4:5], 0, v33, s[4:5]
	s_lshl_b64 s[4:5], s[6:7], 9
	s_add_u32 s38, s25, s4
	s_waitcnt lgkmcnt(0)
	v_add_f32_e32 v23, v23, v28
	ds_swizzle_b32 v28, v23 offset:swizzle(SWAP,4)
	s_addc_u32 s39, s26, s5
	s_cmp_lt_i32 s6, 0
	s_cselect_b64 s[4:5], -1, 0
	s_and_b64 s[22:23], s[4:5], exec
	s_waitcnt lgkmcnt(0)
	v_add_f32_e32 v23, v23, v28
	ds_swizzle_b32 v28, v23 offset:swizzle(SWAP,8)
	s_cselect_b32 s22, s36, s38
	s_cselect_b32 s23, s37, s39
	s_cmp_gt_i32 s6, -1
	s_waitcnt lgkmcnt(0)
	v_add_f32_e32 v23, v23, v28
	ds_swizzle_b32 v34, v23 offset:swizzle(SWAP,16)
	v_lshl_add_u64 v[28:29], v[6:7], 0, s[16:17]
	s_waitcnt lgkmcnt(0)
	v_add_f32_e32 v23, v23, v34
	v_mov_b32_e32 v34, v23
	s_nop 1
	v_permlane32_swap_b32_e32 v23, v34
	v_add_f32_e32 v23, v23, v34
	v_fmamk_f32 v23, v23, 0x3b800000, v22
	v_mul_f32_e32 v34, 0x4b800000, v23
	v_cmp_gt_f32_e32 vcc, s34, v23
	s_nop 1
	v_cndmask_b32_e32 v23, v23, v34, vcc
	v_rsq_f32_e32 v23, v23
	s_nop 0
	v_mul_f32_e32 v34, 0x45800000, v23
	v_cndmask_b32_e32 v34, v23, v34, vcc
	v_pk_mul_f32 v[30:31], v[34:35], v[30:31] op_sel_hi:[0,1]
	v_pk_mul_f32 v[18:19], v[34:35], v[18:19] op_sel_hi:[0,1]
	v_pk_mul_f32 v[24:25], v[24:25], v[30:31]
	v_pk_mul_f32 v[18:19], v[26:27], v[18:19]
	v_cvt_pk_bf16_f32 v24, v24, v25
	v_cvt_pk_bf16_f32 v25, v18, v19
	global_store_dwordx2 v[28:29], v[24:25], off
	global_load_dword v23, v[32:33], off offset:512
	global_load_dwordx2 v[18:19], v[10:11], off
	s_waitcnt vmcnt(0) lgkmcnt(0)
	v_lshlrev_b32_e32 v24, 16, v23
	v_and_b32_e32 v25, 0xffff0000, v23
	v_pk_mul_f32 v[26:27], v[24:25], v[24:25]
	s_nop 0
	v_add_f32_e32 v23, v26, v27
	ds_swizzle_b32 v26, v23 offset:swizzle(SWAP,1)
	s_waitcnt lgkmcnt(0)
	v_add_f32_e32 v23, v23, v26
	ds_swizzle_b32 v26, v23 offset:swizzle(SWAP,2)
	s_waitcnt lgkmcnt(0)
	v_add_f32_e32 v23, v23, v26
	ds_swizzle_b32 v26, v23 offset:swizzle(SWAP,4)
	s_waitcnt lgkmcnt(0)
	v_add_f32_e32 v23, v23, v26
	ds_swizzle_b32 v26, v23 offset:swizzle(SWAP,8)
	s_waitcnt lgkmcnt(0)
	v_add_f32_e32 v23, v23, v26
	ds_swizzle_b32 v26, v23 offset:swizzle(SWAP,16)
	s_waitcnt lgkmcnt(0)
	v_add_f32_e32 v23, v23, v26
	v_mov_b32_e32 v26, v23
	s_nop 1
	v_permlane32_swap_b32_e32 v23, v26
	v_add_f32_e32 v23, v23, v26
	v_fmamk_f32 v23, v23, 0x3c000000, v22
	v_mul_f32_e32 v26, 0x4b800000, v23
	v_cmp_gt_f32_e32 vcc, s34, v23
	s_nop 1
	v_cndmask_b32_e32 v23, v23, v26, vcc
	v_rsq_f32_e32 v23, v23
	s_nop 0
	v_mul_f32_e32 v26, 0x45800000, v23
	v_cndmask_b32_e32 v26, v23, v26, vcc
	v_pk_mul_f32 v[24:25], v[26:27], v[24:25] op_sel_hi:[0,1]
	v_pk_mul_f32 v[18:19], v[18:19], v[24:25]
	v_lshl_add_u64 v[24:25], s[22:23], 0, v[16:17]
	global_store_dwordx2 v[24:25], v[18:19], off
	s_cbranch_scc1 .LBB0_375
	v_cvt_pk_bf16_f32 v18, v18, v19
	global_store_dword v[12:13], v18, off
.LBB0_375:
	s_and_b32 s22, s6, 15
	s_and_b32 s36, s6, 0x3fff
	s_or_b32 s37, s22, 0x800
	s_and_b64 s[22:23], s[4:5], exec
	s_cselect_b32 s22, s36, s37
	v_cvt_f32_u32_e32 v23, s22
	v_lshl_add_u64 v[18:19], s[20:21], 0, v[8:9]
	s_and_saveexec_b64 s[22:23], s[2:3]
	s_cbranch_execz .LBB0_372
	v_add_co_u32_e32 v24, vcc, 0x6800000, v18
	s_and_b64 s[36:37], s[4:5], exec
	s_nop 0
	v_addc_co_u32_e32 v25, vcc, 0, v19, vcc
	global_load_ushort v28, v[24:25], off offset:768
	global_load_ushort v29, v[24:25], off offset:800
	v_mul_f32_e32 v24, v20, v23
	v_mul_f32_e32 v25, 0.15915494, v24
	v_floor_f32_e32 v25, v25
	v_fma_f32 v24, v24, 0.15915494, -v25
	s_cselect_b32 s38, s35, 0x9ad6000
	v_sin_f32_e32 v30, v24
	v_cos_f32_e32 v25, v24
	s_cselect_b32 s37, s9, 0
	s_cselect_b32 s36, s8, s6
	s_add_u32 s38, s24, s38
	s_addc_u32 s39, s1, 0
	s_lshl_b64 s[36:37], s[36:37], 7
	s_add_u32 s36, s38, s36
	s_addc_u32 s37, s39, s37
	s_andn2_b64 vcc, exec, s[4:5]
	v_lshl_add_u64 v[26:27], s[36:37], 0, v[2:3]
	s_waitcnt vmcnt(0) lgkmcnt(0)
	v_lshlrev_b32_e32 v28, 16, v28
	v_lshlrev_b32_e32 v24, 16, v29
	v_mul_f32_e32 v29, v30, v24
	v_mul_f32_e32 v24, v25, v24
	v_fma_f32 v25, v25, v28, -v29
	v_fmac_f32_e32 v24, v30, v28
	global_store_dword v[26:27], v25, off
	global_store_dword v[26:27], v24, off offset:64
	s_cbranch_vccnz .LBB0_372
	v_cvt_pk_bf16_f32 v26, v25, s0
	v_cvt_pk_bf16_f32 v27, v24, s0
	v_lshl_add_u64 v[24:25], s[12:13], 0, v[8:9]
	v_add_co_u32_e32 v24, vcc, 0x10b00000, v24
	s_nop 1
	v_addc_co_u32_e32 v25, vcc, 0, v25, vcc
	global_store_short v[24:25], v26, off
	global_store_short v[24:25], v27, off offset:32
	s_branch .LBB0_372

; __device__ __forceinline__ unsigned pk2(float lo, float hi) { const f32x2 v = {lo, hi}; return __builtin_bit_cast(unsigned, __builtin_convertvector(v, bf16x2_t)); }
;     __device__ __forceinline__ void operator()(EPI_ARGS) const {
;         const int row0 = u.pm * BM + wr * 64 + fr, col0 = u.pn * BM + wc * 32 + 8 * fq;
; #pragma unroll
;         for (int ai = 0; ai < 2; ++ai)
; #pragma unroll
;             for (int m = 0; m < 4; ++m) { bf16* rowp = O + (size_t)(row0 + ai * HALF + m * 16) * ldc + col0;
; #pragma unroll
;                 for (int bj = 0; bj < 2; ++bj) { const f32x4 v0 = acc[ai][bj][m][0], v1 = acc[ai][bj][m][1];
;                     u32x4 w; w.x = pk2(v0[0], v0[1]); w.y = pk2(v0[2], v0[3]); w.z = pk2(v1[0], v1[1]); w.w = pk2(v1[2], v1[3]);
;                     *(u32x4*)(rowp + bj * HALF) = w; } }
;     }
.LBB0_390:
	v_lshl_add_u32 v152, s12, 8, v140
	v_lshl_or_b32 v146, s62, 8, v142
	v_ashrrev_i32_e32 v147, 31, v146
	v_mov_b64_e32 v[148:149], s[6:7]
	v_cvt_pk_bf16_f32 v68, v68, v69
	v_cvt_pk_bf16_f32 v69, v70, v71
	v_cvt_pk_bf16_f32 v70, v64, v65
	v_add_u32_e32 v64, 0x80, v152
	v_mad_i64_i32 v[150:151], s[18:19], v152, s61, v[148:149]
	v_lshlrev_b64 v[146:147], 1, v[146:147]
	v_cvt_pk_bf16_f32 v108, v108, v109
	v_cvt_pk_bf16_f32 v109, v110, v111
	v_cvt_pk_bf16_f32 v110, v104, v105
	v_or_b32_e32 v104, 16, v152
	v_mad_i64_i32 v[64:65], s[18:19], v64, s61, v[148:149]
	v_cvt_pk_bf16_f32 v44, v44, v45
	v_cvt_pk_bf16_f32 v45, v46, v47
	v_cvt_pk_bf16_f32 v46, v40, v41
	v_add_u32_e32 v40, 0x90, v152
	v_lshl_add_u64 v[150:151], v[150:151], 0, v[146:147]
	v_cvt_pk_bf16_f32 v111, v106, v107
	v_mad_i64_i32 v[104:105], s[18:19], v104, s61, v[148:149]
	v_cvt_pk_bf16_f32 v92, v92, v93
	v_cvt_pk_bf16_f32 v93, v94, v95
	v_cvt_pk_bf16_f32 v94, v88, v89
	v_or_b32_e32 v88, 32, v152
	v_lshl_add_u64 v[64:65], v[64:65], 0, v[146:147]
	v_cvt_pk_bf16_f32 v47, v42, v43
	v_mad_i64_i32 v[40:41], s[18:19], v40, s61, v[148:149]
	v_cvt_pk_bf16_f32 v28, v28, v29
	v_cvt_pk_bf16_f32 v29, v30, v31
	v_cvt_pk_bf16_f32 v30, v24, v25
	v_add_u32_e32 v24, 0xa0, v152
	global_store_dwordx4 v[150:151], v[108:111], off offset:256
	v_cvt_pk_bf16_f32 v95, v90, v91
	v_mad_i64_i32 v[88:89], s[18:19], v88, s61, v[148:149]
	v_lshl_add_u64 v[108:109], v[104:105], 0, v[146:147]
	v_cvt_pk_bf16_f32 v76, v76, v77
	v_cvt_pk_bf16_f32 v77, v78, v79
	v_cvt_pk_bf16_f32 v78, v72, v73
	v_or_b32_e32 v72, 48, v152
	global_store_dwordx4 v[64:65], v[44:47], off offset:256
	v_cvt_pk_bf16_f32 v31, v26, v27
	v_mad_i64_i32 v[24:25], s[18:19], v24, s61, v[148:149]
	v_lshl_add_u64 v[44:45], v[40:41], 0, v[146:147]
	v_cvt_pk_bf16_f32 v12, v12, v13
	v_cvt_pk_bf16_f32 v13, v14, v15
	v_cvt_pk_bf16_f32 v14, v8, v9
	v_add_u32_e32 v8, 0xb0, v152
	global_store_dwordx4 v[108:109], v[92:95], off offset:256
	v_cvt_pk_bf16_f32 v79, v74, v75
	v_mad_i64_i32 v[72:73], s[18:19], v72, s61, v[148:149]
	v_lshl_add_u64 v[92:93], v[88:89], 0, v[146:147]
	global_store_dwordx4 v[44:45], v[28:31], off offset:256
	v_cvt_pk_bf16_f32 v15, v10, v11
	v_mad_i64_i32 v[8:9], s[18:19], v8, s61, v[148:149]
	v_lshl_add_u64 v[28:29], v[24:25], 0, v[146:147]
	v_cvt_pk_bf16_f32 v124, v124, v125
	v_cvt_pk_bf16_f32 v125, v126, v127
	v_cvt_pk_bf16_f32 v126, v120, v121
	v_cvt_pk_bf16_f32 v127, v122, v123
	v_cvt_pk_bf16_f32 v104, v116, v117
	v_cvt_pk_bf16_f32 v105, v118, v119
	v_cvt_pk_bf16_f32 v106, v112, v113
	v_cvt_pk_bf16_f32 v107, v114, v115
	v_cvt_pk_bf16_f32 v88, v100, v101
	v_cvt_pk_bf16_f32 v89, v102, v103
	v_cvt_pk_bf16_f32 v90, v96, v97
	v_cvt_pk_bf16_f32 v91, v98, v99
	global_store_dwordx4 v[92:93], v[76:79], off offset:256
	v_cvt_pk_bf16_f32 v74, v80, v81
	v_cvt_pk_bf16_f32 v75, v82, v83
	v_lshl_add_u64 v[76:77], v[72:73], 0, v[146:147]
	v_cvt_pk_bf16_f32 v72, v84, v85
	v_cvt_pk_bf16_f32 v73, v86, v87
	v_cvt_pk_bf16_f32 v71, v66, v67
	v_cvt_pk_bf16_f32 v60, v60, v61
	v_cvt_pk_bf16_f32 v61, v62, v63
	v_cvt_pk_bf16_f32 v62, v56, v57
	v_cvt_pk_bf16_f32 v63, v58, v59
	v_cvt_pk_bf16_f32 v40, v52, v53
	v_cvt_pk_bf16_f32 v41, v54, v55
	v_cvt_pk_bf16_f32 v42, v48, v49
	v_cvt_pk_bf16_f32 v43, v50, v51
	v_cvt_pk_bf16_f32 v24, v36, v37
	v_cvt_pk_bf16_f32 v25, v38, v39
	v_cvt_pk_bf16_f32 v26, v32, v33
	v_cvt_pk_bf16_f32 v27, v34, v35
	global_store_dwordx4 v[28:29], v[12:15], off offset:256
	v_cvt_pk_bf16_f32 v10, v16, v17
	v_cvt_pk_bf16_f32 v11, v18, v19
	v_lshl_add_u64 v[12:13], v[8:9], 0, v[146:147]
	v_cvt_pk_bf16_f32 v8, v20, v21
	v_cvt_pk_bf16_f32 v9, v22, v23
	v_cvt_pk_bf16_f32 v4, v4, v5
	v_cvt_pk_bf16_f32 v5, v6, v7
	v_cvt_pk_bf16_f32 v6, v0, v1
	v_cvt_pk_bf16_f32 v7, v2, v3
	s_andn2_b64 vcc, exec, s[2:3]
	s_mov_b64 s[2:3], -1
	global_store_dwordx4 v[150:151], v[124:127], off
	global_store_dwordx4 v[108:109], v[104:107], off
	global_store_dwordx4 v[92:93], v[88:91], off
	global_store_dwordx4 v[76:77], v[72:75], off
	global_store_dwordx4 v[76:77], v[68:71], off offset:256
	global_store_dwordx4 v[64:65], v[60:63], off
	global_store_dwordx4 v[44:45], v[40:43], off
	global_store_dwordx4 v[28:29], v[24:27], off
	global_store_dwordx4 v[12:13], v[8:11], off
	global_store_dwordx4 v[12:13], v[4:7], off offset:256
	s_cbranch_vccnz .LBB0_383
	s_andn2_b64 vcc, exec, s[4:5]
	s_cbranch_vccnz .LBB0_382
	s_barrier
	s_branch .LBB0_382

; __device__ __forceinline__ unsigned pk2(float lo, float hi) { const f32x2 v = {lo, hi}; return __builtin_bit_cast(unsigned, __builtin_convertvector(v, bf16x2_t)); }
;     __device__ __forceinline__ void operator()(EPI_ARGS) const {
;         const int row0 = u.pm * BM + wr * 64 + fr, col0 = u.pn * BM + wc * 32 + 8 * fq;
; #pragma unroll
;         for (int ai = 0; ai < 2; ++ai)
; #pragma unroll
;             for (int m = 0; m < 4; ++m) { bf16* rowp = O + (size_t)(row0 + ai * HALF + m * 16) * ldc + col0;
; #pragma unroll
;                 for (int bj = 0; bj < 2; ++bj) { const f32x4 v0 = acc[ai][bj][m][0], v1 = acc[ai][bj][m][1];
;                     u32x4 w; w.x = pk2(v0[0], v0[1]); w.y = pk2(v0[2], v0[3]); w.z = pk2(v1[0], v1[1]); w.w = pk2(v1[2], v1[3]);
;                     *(u32x4*)(rowp + bj * HALF) = w; } }
;     }
.LBB0_412:
	v_lshl_add_u32 v136, s24, 8, v140
	v_lshl_or_b32 v138, s65, 8, v142
	v_ashrrev_i32_e32 v137, 31, v136
	v_ashrrev_i32_e32 v139, 31, v138
	v_lshlrev_b64 v[146:147], 10, v[136:137]
	v_lshl_add_u64 v[146:147], s[8:9], 0, v[146:147]
	v_lshlrev_b64 v[138:139], 1, v[138:139]
	v_lshl_add_u64 v[146:147], v[146:147], 0, v[138:139]
	v_cvt_pk_bf16_f32 v112, v112, v113
	v_cvt_pk_bf16_f32 v113, v114, v115
	v_cvt_pk_bf16_f32 v114, v116, v117
	v_cvt_pk_bf16_f32 v115, v118, v119
	global_store_dwordx4 v[146:147], v[112:115], off
	v_cvt_pk_bf16_f32 v80, v80, v81
	v_cvt_pk_bf16_f32 v81, v82, v83
	v_cvt_pk_bf16_f32 v112, v120, v121
	v_cvt_pk_bf16_f32 v113, v122, v123
	v_cvt_pk_bf16_f32 v114, v124, v125
	v_cvt_pk_bf16_f32 v115, v126, v127
	global_store_dwordx4 v[146:147], v[112:115], off offset:256
	v_cvt_pk_bf16_f32 v82, v84, v85
	v_cvt_pk_bf16_f32 v83, v86, v87
	v_or_b32_e32 v112, 16, v136
	v_ashrrev_i32_e32 v113, 31, v112
	v_lshlrev_b64 v[112:113], 10, v[112:113]
	v_lshl_add_u64 v[112:113], s[8:9], 0, v[112:113]
	v_lshl_add_u64 v[112:113], v[112:113], 0, v[138:139]
	global_store_dwordx4 v[112:113], v[80:83], off
	v_cvt_pk_bf16_f32 v48, v48, v49
	v_cvt_pk_bf16_f32 v49, v50, v51
	v_cvt_pk_bf16_f32 v80, v104, v105
	v_cvt_pk_bf16_f32 v81, v106, v107
	v_cvt_pk_bf16_f32 v82, v108, v109
	v_cvt_pk_bf16_f32 v83, v110, v111
	global_store_dwordx4 v[112:113], v[80:83], off offset:256
	v_cvt_pk_bf16_f32 v50, v52, v53
	v_cvt_pk_bf16_f32 v51, v54, v55
	v_or_b32_e32 v80, 32, v136
	v_ashrrev_i32_e32 v81, 31, v80
	v_lshlrev_b64 v[80:81], 10, v[80:81]
	v_lshl_add_u64 v[80:81], s[8:9], 0, v[80:81]
	v_lshl_add_u64 v[80:81], v[80:81], 0, v[138:139]
	global_store_dwordx4 v[80:81], v[48:51], off
	v_cvt_pk_bf16_f32 v16, v16, v17
	v_cvt_pk_bf16_f32 v17, v18, v19
	v_cvt_pk_bf16_f32 v48, v64, v65
	v_cvt_pk_bf16_f32 v49, v66, v67
	v_cvt_pk_bf16_f32 v50, v68, v69
	v_cvt_pk_bf16_f32 v51, v70, v71
	global_store_dwordx4 v[80:81], v[48:51], off offset:256
	v_cvt_pk_bf16_f32 v18, v20, v21
	v_cvt_pk_bf16_f32 v19, v22, v23
	v_or_b32_e32 v48, 48, v136
	v_ashrrev_i32_e32 v49, 31, v48
	v_lshlrev_b64 v[48:49], 10, v[48:49]
	v_lshl_add_u64 v[48:49], s[8:9], 0, v[48:49]
	v_lshl_add_u64 v[48:49], v[48:49], 0, v[138:139]
	global_store_dwordx4 v[48:49], v[16:19], off
	v_add_co_u32_e32 v22, vcc, s61, v146
	s_nop 0
	v_cvt_pk_bf16_f32 v16, v32, v33
	v_cvt_pk_bf16_f32 v17, v34, v35
	v_cvt_pk_bf16_f32 v18, v36, v37
	v_cvt_pk_bf16_f32 v19, v38, v39
	global_store_dwordx4 v[48:49], v[16:19], off offset:256
	v_addc_co_u32_e32 v23, vcc, 0, v147, vcc
	s_nop 0
	v_cvt_pk_bf16_f32 v16, v88, v89
	v_cvt_pk_bf16_f32 v17, v90, v91
	v_cvt_pk_bf16_f32 v18, v92, v93
	v_cvt_pk_bf16_f32 v19, v94, v95
	v_lshl_add_u64 v[20:21], v[146:147], 0, s[16:17]
	global_store_dwordx4 v[22:23], v[16:19], off
	v_add_co_u32_e32 v22, vcc, s62, v146
	s_nop 0
	v_cvt_pk_bf16_f32 v16, v96, v97
	v_cvt_pk_bf16_f32 v17, v98, v99
	v_cvt_pk_bf16_f32 v18, v100, v101
	v_cvt_pk_bf16_f32 v19, v102, v103
	global_store_dwordx4 v[20:21], v[16:19], off offset:256
	v_addc_co_u32_e32 v23, vcc, 0, v147, vcc
	s_nop 0
	v_cvt_pk_bf16_f32 v16, v56, v57
	v_cvt_pk_bf16_f32 v17, v58, v59
	v_cvt_pk_bf16_f32 v18, v60, v61
	v_cvt_pk_bf16_f32 v19, v62, v63
	global_store_dwordx4 v[22:23], v[16:19], off
	v_add_co_u32_e32 v22, vcc, s63, v146
	v_lshl_add_u64 v[20:21], v[146:147], 0, s[18:19]
	v_cvt_pk_bf16_f32 v16, v72, v73
	v_cvt_pk_bf16_f32 v17, v74, v75
	v_cvt_pk_bf16_f32 v18, v76, v77
	v_cvt_pk_bf16_f32 v19, v78, v79
	v_addc_co_u32_e32 v23, vcc, 0, v147, vcc
	global_store_dwordx4 v[20:21], v[16:19], off offset:256
	v_cvt_pk_bf16_f32 v0, v0, v1
	v_cvt_pk_bf16_f32 v1, v2, v3
	v_cvt_pk_bf16_f32 v16, v24, v25
	v_cvt_pk_bf16_f32 v17, v26, v27
	v_cvt_pk_bf16_f32 v18, v28, v29
	v_cvt_pk_bf16_f32 v19, v30, v31
	v_cvt_pk_bf16_f32 v2, v4, v5
	v_add_co_u32_e32 v4, vcc, s64, v146
	v_lshl_add_u64 v[20:21], v[146:147], 0, s[20:21]
	global_store_dwordx4 v[22:23], v[16:19], off
	v_cvt_pk_bf16_f32 v3, v6, v7
	v_addc_co_u32_e32 v5, vcc, 0, v147, vcc
	v_cvt_pk_bf16_f32 v16, v40, v41
	v_cvt_pk_bf16_f32 v17, v42, v43
	v_cvt_pk_bf16_f32 v18, v44, v45
	v_cvt_pk_bf16_f32 v19, v46, v47
	global_store_dwordx4 v[20:21], v[16:19], off offset:256
	global_store_dwordx4 v[4:5], v[0:3], off
	s_andn2_b64 vcc, exec, s[2:3]
	v_lshl_add_u64 v[16:17], v[146:147], 0, s[22:23]
	v_cvt_pk_bf16_f32 v0, v8, v9
	v_cvt_pk_bf16_f32 v1, v10, v11
	v_cvt_pk_bf16_f32 v2, v12, v13
	v_cvt_pk_bf16_f32 v3, v14, v15
	s_mov_b64 s[2:3], -1
	global_store_dwordx4 v[16:17], v[0:3], off offset:256
	s_cbranch_vccnz .LBB0_403
	s_andn2_b64 vcc, exec, s[6:7]
	s_cbranch_vccnz .LBB0_402
	s_barrier
	s_branch .LBB0_402

; __device__ __forceinline__ unsigned pk2(float lo, float hi) { const f32x2 v = {lo, hi}; return __builtin_bit_cast(unsigned, __builtin_convertvector(v, bf16x2_t)); }
;     __device__ __forceinline__ void operator()(EPI_ARGS) const {
;         const int row0 = u.pm * BM + wr * 64 + fr, col0 = u.pn * BM + wc * 32 + 8 * fq;
; #pragma unroll
;         for (int ai = 0; ai < 2; ++ai)
; #pragma unroll
;             for (int m = 0; m < 4; ++m) { bf16* rowp = O + (size_t)(row0 + ai * HALF + m * 16) * ldc + col0;
; #pragma unroll
;                 for (int bj = 0; bj < 2; ++bj) { const f32x4 v0 = acc[ai][bj][m][0], v1 = acc[ai][bj][m][1];
;                     u32x4 w; w.x = pk2(v0[0], v0[1]); w.y = pk2(v0[2], v0[3]); w.z = pk2(v1[0], v1[1]); w.w = pk2(v1[2], v1[3]);
;                     *(u32x4*)(rowp + bj * HALF) = w; } }
;     }
.LBB0_434:
	v_lshl_add_u32 v136, s22, 8, v140
	v_lshl_or_b32 v138, s61, 8, v142
	v_ashrrev_i32_e32 v137, 31, v136
	v_ashrrev_i32_e32 v139, 31, v138
	v_lshlrev_b64 v[146:147], 16, v[136:137]
	v_lshl_add_u64 v[146:147], s[6:7], 0, v[146:147]
	v_lshlrev_b64 v[138:139], 1, v[138:139]
	v_lshl_add_u64 v[146:147], v[146:147], 0, v[138:139]
	v_cvt_pk_bf16_f32 v112, v112, v113
	v_cvt_pk_bf16_f32 v113, v114, v115
	v_cvt_pk_bf16_f32 v114, v116, v117
	v_cvt_pk_bf16_f32 v115, v118, v119
	global_store_dwordx4 v[146:147], v[112:115], off
	v_cvt_pk_bf16_f32 v80, v80, v81
	v_cvt_pk_bf16_f32 v81, v82, v83
	v_cvt_pk_bf16_f32 v112, v120, v121
	v_cvt_pk_bf16_f32 v113, v122, v123
	v_cvt_pk_bf16_f32 v114, v124, v125
	v_cvt_pk_bf16_f32 v115, v126, v127
	global_store_dwordx4 v[146:147], v[112:115], off offset:256
	v_cvt_pk_bf16_f32 v82, v84, v85
	v_cvt_pk_bf16_f32 v83, v86, v87
	v_or_b32_e32 v112, 16, v136
	v_ashrrev_i32_e32 v113, 31, v112
	v_lshlrev_b64 v[112:113], 16, v[112:113]
	v_lshl_add_u64 v[112:113], s[6:7], 0, v[112:113]
	v_lshl_add_u64 v[112:113], v[112:113], 0, v[138:139]
	global_store_dwordx4 v[112:113], v[80:83], off
	v_cvt_pk_bf16_f32 v48, v48, v49
	v_cvt_pk_bf16_f32 v49, v50, v51
	v_cvt_pk_bf16_f32 v80, v104, v105
	v_cvt_pk_bf16_f32 v81, v106, v107
	v_cvt_pk_bf16_f32 v82, v108, v109
	v_cvt_pk_bf16_f32 v83, v110, v111
	global_store_dwordx4 v[112:113], v[80:83], off offset:256
	v_cvt_pk_bf16_f32 v50, v52, v53
	v_cvt_pk_bf16_f32 v51, v54, v55
	v_or_b32_e32 v80, 32, v136
	v_ashrrev_i32_e32 v81, 31, v80
	v_lshlrev_b64 v[80:81], 16, v[80:81]
	v_lshl_add_u64 v[80:81], s[6:7], 0, v[80:81]
	v_lshl_add_u64 v[80:81], v[80:81], 0, v[138:139]
	global_store_dwordx4 v[80:81], v[48:51], off
	v_cvt_pk_bf16_f32 v16, v16, v17
	v_cvt_pk_bf16_f32 v17, v18, v19
	v_cvt_pk_bf16_f32 v48, v64, v65
	v_cvt_pk_bf16_f32 v49, v66, v67
	v_cvt_pk_bf16_f32 v50, v68, v69
	v_cvt_pk_bf16_f32 v51, v70, v71
	global_store_dwordx4 v[80:81], v[48:51], off offset:256
	v_cvt_pk_bf16_f32 v18, v20, v21
	v_cvt_pk_bf16_f32 v19, v22, v23
	v_or_b32_e32 v48, 48, v136
	v_ashrrev_i32_e32 v49, 31, v48
	v_lshlrev_b64 v[48:49], 16, v[48:49]
	v_lshl_add_u64 v[48:49], s[6:7], 0, v[48:49]
	v_lshl_add_u64 v[48:49], v[48:49], 0, v[138:139]
	global_store_dwordx4 v[48:49], v[16:19], off
	v_add_co_u32_e32 v22, vcc, s57, v146
	s_nop 0
	v_cvt_pk_bf16_f32 v16, v32, v33
	v_cvt_pk_bf16_f32 v17, v34, v35
	v_cvt_pk_bf16_f32 v18, v36, v37
	v_cvt_pk_bf16_f32 v19, v38, v39
	global_store_dwordx4 v[48:49], v[16:19], off offset:256
	v_addc_co_u32_e32 v23, vcc, 0, v147, vcc
	s_nop 0
	v_cvt_pk_bf16_f32 v16, v88, v89
	v_cvt_pk_bf16_f32 v17, v90, v91
	v_cvt_pk_bf16_f32 v18, v92, v93
	v_cvt_pk_bf16_f32 v19, v94, v95
	v_lshl_add_u64 v[20:21], v[146:147], 0, s[14:15]
	global_store_dwordx4 v[22:23], v[16:19], off
	v_add_co_u32_e32 v22, vcc, s58, v146
	s_nop 0
	v_cvt_pk_bf16_f32 v16, v96, v97
	v_cvt_pk_bf16_f32 v17, v98, v99
	v_cvt_pk_bf16_f32 v18, v100, v101
	v_cvt_pk_bf16_f32 v19, v102, v103
	global_store_dwordx4 v[20:21], v[16:19], off offset:256
	v_addc_co_u32_e32 v23, vcc, 0, v147, vcc
	s_nop 0
	v_cvt_pk_bf16_f32 v16, v56, v57
	v_cvt_pk_bf16_f32 v17, v58, v59
	v_cvt_pk_bf16_f32 v18, v60, v61
	v_cvt_pk_bf16_f32 v19, v62, v63
	global_store_dwordx4 v[22:23], v[16:19], off
	v_add_co_u32_e32 v22, vcc, s59, v146
	v_lshl_add_u64 v[20:21], v[146:147], 0, s[16:17]
	v_cvt_pk_bf16_f32 v16, v72, v73
	v_cvt_pk_bf16_f32 v17, v74, v75
	v_cvt_pk_bf16_f32 v18, v76, v77
	v_cvt_pk_bf16_f32 v19, v78, v79
	v_addc_co_u32_e32 v23, vcc, 0, v147, vcc
	global_store_dwordx4 v[20:21], v[16:19], off offset:256
	v_cvt_pk_bf16_f32 v0, v0, v1
	v_cvt_pk_bf16_f32 v1, v2, v3
	v_cvt_pk_bf16_f32 v16, v24, v25
	v_cvt_pk_bf16_f32 v17, v26, v27
	v_cvt_pk_bf16_f32 v18, v28, v29
	v_cvt_pk_bf16_f32 v19, v30, v31
	v_cvt_pk_bf16_f32 v2, v4, v5
	v_add_co_u32_e32 v4, vcc, s60, v146
	v_lshl_add_u64 v[20:21], v[146:147], 0, s[18:19]
	global_store_dwordx4 v[22:23], v[16:19], off
	v_cvt_pk_bf16_f32 v3, v6, v7
	v_addc_co_u32_e32 v5, vcc, 0, v147, vcc
	v_cvt_pk_bf16_f32 v16, v40, v41
	v_cvt_pk_bf16_f32 v17, v42, v43
	v_cvt_pk_bf16_f32 v18, v44, v45
	v_cvt_pk_bf16_f32 v19, v46, v47
	global_store_dwordx4 v[20:21], v[16:19], off offset:256
	global_store_dwordx4 v[4:5], v[0:3], off
	s_andn2_b64 vcc, exec, s[2:3]
	v_lshl_add_u64 v[16:17], v[146:147], 0, s[20:21]
	v_cvt_pk_bf16_f32 v0, v8, v9
	v_cvt_pk_bf16_f32 v1, v10, v11
	v_cvt_pk_bf16_f32 v2, v12, v13
	v_cvt_pk_bf16_f32 v3, v14, v15
	s_mov_b64 s[2:3], -1
	global_store_dwordx4 v[16:17], v[0:3], off offset:256
	s_cbranch_vccnz .LBB0_425
	s_andn2_b64 vcc, exec, s[4:5]
	s_cbranch_vccnz .LBB0_424
	s_barrier
	s_branch .LBB0_424

; #define LAS __attribute__((address_space(3)))
; __device__ __forceinline__ float bflo(unsigned w) { return __uint_as_float(w << 16); }
; __device__ __forceinline__ float bfhi(unsigned w) { return __uint_as_float(w & 0xffff0000u); }
; __device__ __forceinline__ bf16 f2bf(float f) { return (bf16)(pk2(f, 0.f) & 0xffffu); }
; __device__ __forceinline__ float ex2f(float x) { return __builtin_amdgcn_exp2f(x); }
; __device__ __forceinline__ void ret_kv_item(LAS unsigned char* lds, const bf16* Z, bf16* AT, int b, int c, int hh, float lg) {
;     LAS bf16* KT = (LAS bf16*)lds; LAS bf16* VTt = KT + 128 * 72;
;     const int tid_ = my_tid(lds); const int tid = tid_, lane = tid & 63, r32 = lane & 31, hi = lane >> 5; const int wid = __builtin_amdgcn_readfirstlane(tid >> 6);
;     const int rowbase = b * SEQ + 64 * c;
; #pragma unroll
;     for (int i = 0; i < 2; ++i) { const int ci = tid + 512 * i, l = ci & 63, dc = ci >> 6; const bf16* zr = Z + (size_t)(rowbase + l) * NZ + hh * 128 + dc * 8;
;         const u32x4 kr = *(const u32x4*)(zr + ZC_RK), vr = *(const u32x4*)(zr + ZC_RV); const float dec = ex2f((float)(63 - l) * lg);
; #pragma unroll
;         for (int e = 0; e < 4; ++e) { const unsigned kw = kr[e], vw = vr[e]; const int d = 8 * dc + 2 * e;
;             KT[d * 72 + l] = f2bf(bflo(kw) * dec); KT[(d + 1) * 72 + l] = f2bf(bfhi(kw) * dec);
;             VTt[d * 72 + l] = (bf16)(vw & 0xffffu); VTt[(d + 1) * 72 + l] = (bf16)(vw >> 16); } }
;     __syncthreads();
.LBB0_440:
	s_and_b32 s12, s11, 3
	s_bfe_u32 s13, s11, 0x80002
	s_cmp_eq_u32 s12, 1
	s_cselect_b64 vcc, -1, 0
	s_cmp_lg_u32 s12, 2
	s_getreg_b32 s2, hwreg(HW_REG_HW_ID, 0, 6)
	v_cndmask_b32_e32 v0, v34, v35, vcc
	s_cselect_b64 vcc, -1, 0
	s_cmp_lg_u32 s12, 3
	v_cndmask_b32_e32 v0, v36, v0, vcc
	s_cselect_b64 vcc, -1, 0
	s_lshl_b32 s14, s2, 2
	s_and_b32 s14, s14, 0xfc
	s_add_i32 s14, s14, 0
	s_add_i32 s14, s14, 0x25a00
	v_cndmask_b32_e32 v2, v37, v0, vcc
	v_mov_b32_e32 v0, s14
	ds_read_b32 v3, v0
	s_and_b32 s15, s5, 0xffffc000
	s_lshl_b32 s16, s13, 6
	s_or_b32 s15, s16, s15
	v_mbcnt_lo_u32_b32 v4, -1, 0
	v_mbcnt_hi_u32_b32 v4, -1, v4
	s_lshl_b32 s2, s12, 8
	v_and_b32_e32 v14, 63, v4
	v_bitop3_b32 v0, v4, 63, v4 bitop3:0xc
	v_or_b32_e32 v1, s15, v14
	v_cvt_f32_ubyte0_e32 v6, v0
	v_mad_i64_i32 v[0:1], s[14:15], v1, s7, v[32:33]
	v_lshl_add_u64 v[8:9], v[0:1], 0, s[2:3]
	s_waitcnt lgkmcnt(0)
	v_readfirstlane_b32 s2, v3
	v_mul_f32_e32 v2, v2, v6
	v_and_b32_e32 v5, 31, v4
	v_lshl_add_u32 v0, s2, 6, v4
	v_ashrrev_i32_e32 v1, 3, v0
	v_exp_f32_e32 v17, v2
	v_add_u32_e32 v2, 0x200, v0
	v_readfirstlane_b32 s2, v0
	v_and_b32_e32 v0, -8, v1
	v_bfe_u32 v58, v4, 5, 1
	v_ashrrev_i32_e32 v2, 3, v2
	s_ashr_i32 s14, s2, 7
	v_and_or_b32 v59, s2, 64, v5
	v_ashrrev_i32_e32 v1, 31, v0
	v_add_u32_e32 v15, 0x48, v14
	v_lshlrev_b32_e32 v16, 4, v58
	v_mul_lo_u32 v3, v0, s8
	v_and_b32_e32 v10, -8, v2
	v_lshl_or_b32 v2, s14, 5, v5
	v_mul_u32_u24_e32 v4, 0x90, v59
	v_lshl_add_u64 v[12:13], v[0:1], 1, v[8:9]
	v_or_b32_e32 v18, v3, v14
	v_add_u32_e32 v19, v3, v15
	v_mul_lo_u32 v21, v2, s9
	v_add3_u32 v54, 0, v4, v16
	global_load_dwordx4 v[0:3], v[12:13], off offset:1856
	global_load_dwordx4 v[4:7], v[12:13], off offset:2880
	v_ashrrev_i32_e32 v11, 31, v10
	v_mul_lo_u32 v20, v10, s8
	v_lshl_add_u32 v12, v18, 1, 0
	v_lshl_add_u64 v[8:9], v[10:11], 1, v[8:9]
	v_or_b32_e32 v10, v20, v14
	v_add_u32_e32 v11, v20, v15
	v_add3_u32 v50, 0, v21, v16
	v_lshl_add_u32 v13, v19, 1, 0
	v_lshl_add_u32 v10, v10, 1, 0
	v_lshl_add_u32 v11, v11, 1, 0
	s_and_b32 s2, s11, 0xfffffc00
	s_lshl_b32 s13, s13, 2
	s_or_b32 s2, s13, s2
	s_or_b32 s12, s2, s12
	s_ashr_i32 s13, s12, 31
	s_lshl_b64 s[12:13], s[12:13], 15
	s_add_u32 s12, s1, s12
	s_addc_u32 s13, s4, s13
	s_lshl_b32 s2, s14, 12
	s_add_i32 s11, s11, s68
	s_add_i32 s5, s5, s6
	s_cmpk_gt_i32 s11, 0x7ff
	s_waitcnt vmcnt(0) lgkmcnt(0)
	ds_write_b16 v12, v4 offset:18432
	ds_write_b16_d16_hi v12, v4 offset:18576
	v_lshlrev_b32_e32 v14, 16, v0
	v_and_b32_e32 v0, 0xffff0000, v0
	v_lshlrev_b32_e32 v4, 16, v1
	v_and_b32_e32 v1, 0xffff0000, v1
	v_lshlrev_b32_e32 v15, 16, v2
	v_and_b32_e32 v2, 0xffff0000, v2
	v_lshlrev_b32_e32 v16, 16, v3
	v_and_b32_e32 v3, 0xffff0000, v3
	v_mul_f32_e32 v14, v17, v14
	v_mul_f32_e32 v0, v17, v0
	v_mul_f32_e32 v4, v17, v4
	v_mul_f32_e32 v1, v17, v1
	v_mul_f32_e32 v15, v17, v15
	v_mul_f32_e32 v2, v17, v2
	v_mul_f32_e32 v16, v17, v16
	v_mul_f32_e32 v3, v17, v3
	v_cvt_pk_bf16_f32 v14, v14, s0
	v_cvt_pk_bf16_f32 v0, v0, s0
	v_cvt_pk_bf16_f32 v4, v4, s0
	v_cvt_pk_bf16_f32 v1, v1, s0
	v_cvt_pk_bf16_f32 v15, v15, s0
	v_cvt_pk_bf16_f32 v2, v2, s0
	v_cvt_pk_bf16_f32 v16, v16, s0
	v_cvt_pk_bf16_f32 v3, v3, s0
	ds_write_b16 v12, v14
	ds_write_b16 v12, v0 offset:144
	ds_write_b16 v12, v4 offset:288
	ds_write_b16 v13, v1 offset:288
	ds_write_b16 v12, v5 offset:18720
	ds_write_b16_d16_hi v13, v5 offset:18720
	ds_write_b16 v12, v15 offset:576
	ds_write_b16 v13, v2 offset:576
	ds_write_b16 v12, v6 offset:19008
	ds_write_b16_d16_hi v13, v6 offset:19008
	ds_write_b16 v12, v16 offset:864
	ds_write_b16 v13, v3 offset:864
	ds_write_b16 v12, v7 offset:19296
	ds_write_b16_d16_hi v13, v7 offset:19296
	global_load_dwordx4 v[0:3], v[8:9], off offset:1856
	global_load_dwordx4 v[4:7], v[8:9], off offset:2880
	s_waitcnt vmcnt(0) lgkmcnt(0)
	ds_write_b16 v10, v4 offset:18432
	ds_write_b16_d16_hi v10, v4 offset:18576
	v_lshlrev_b32_e32 v8, 16, v0
	v_and_b32_e32 v0, 0xffff0000, v0
	v_lshlrev_b32_e32 v4, 16, v1
	v_and_b32_e32 v1, 0xffff0000, v1
	v_lshlrev_b32_e32 v9, 16, v2
	v_and_b32_e32 v2, 0xffff0000, v2
	v_lshlrev_b32_e32 v12, 16, v3
	v_and_b32_e32 v3, 0xffff0000, v3
	v_mul_f32_e32 v8, v17, v8
	v_mul_f32_e32 v0, v17, v0
	v_mul_f32_e32 v1, v17, v1
	v_mul_f32_e32 v2, v17, v2
	v_mul_f32_e32 v3, v17, v3
	v_mul_f32_e32 v4, v17, v4
	v_mul_f32_e32 v9, v17, v9
	v_mul_f32_e32 v12, v17, v12
	v_cvt_pk_bf16_f32 v8, v8, s0
	v_cvt_pk_bf16_f32 v0, v0, s0
	v_cvt_pk_bf16_f32 v1, v1, s0
	v_cvt_pk_bf16_f32 v2, v2, s0
	v_cvt_pk_bf16_f32 v3, v3, s0
	v_cvt_pk_bf16_f32 v4, v4, s0
	v_cvt_pk_bf16_f32 v9, v9, s0
	v_cvt_pk_bf16_f32 v12, v12, s0
	ds_write_b16 v10, v8
	ds_write_b16 v10, v0 offset:144
	ds_write_b16 v10, v4 offset:288
	ds_write_b16 v11, v1 offset:288
	ds_write_b16 v10, v5 offset:18720
	ds_write_b16_d16_hi v11, v5 offset:18720
	ds_write_b16 v10, v9 offset:576
	ds_write_b16 v11, v2 offset:576
	ds_write_b16 v10, v6 offset:19008
	ds_write_b16_d16_hi v11, v6 offset:19008
	ds_write_b16 v10, v12 offset:864
	ds_write_b16 v11, v3 offset:864
	ds_write_b16 v10, v7 offset:19296
	ds_write_b16_d16_hi v11, v7 offset:19296
	s_waitcnt lgkmcnt(0)
	s_barrier
; #define LAS __attribute__((address_space(3)))
; __device__ __forceinline__ bf16 f2bf(float f) { return (bf16)(pk2(f, 0.f) & 0xffffu); }
; __device__ __forceinline__ int crow(int r, int hi) { return (r & 3) + 8 * (r >> 2) + 4 * hi; }
; #define MFMA32(a, b, c) __builtin_amdgcn_mfma_f32_32x32x16_bf16((a), (b), (c), 0, 0, 0)
; __device__ __forceinline__ void ret_kv_item(LAS unsigned char* lds, const bf16* Z, bf16* AT, int b, int c, int hh, float lg) {
;     ...
;     const int eb = wid >> 1, db0 = 2 * (wid & 1);
;     f32x16 a0, a1;
; #pragma unroll
;     for (int r = 0; r < 16; ++r) { a0[r] = 0.f; a1[r] = 0.f; }
; #pragma unroll
;     for (int ks = 0; ks < 4; ++ks) {
;         const bf16x8 af = *(const LAS bf16x8*)(VTt + (32 * eb + r32) * 72 + 16 * ks + 8 * hi);
;         const bf16x8 b0 = *(const LAS bf16x8*)(KT + (32 * db0 + r32) * 72 + 16 * ks + 8 * hi), b1 = *(const LAS bf16x8*)(KT + (32 * db0 + 32 + r32) * 72 + 16 * ks + 8 * hi);
;         a0 = MFMA32(af, b0, a0); a1 = MFMA32(af, b1, a1);
;     }
;     bf16* o = AT + (size_t)((b * 256 + c) * 4 + hh) * 16384;
; #pragma unroll
;     for (int r = 0; r < 16; ++r) { const int e = 32 * eb + crow(r, hi); o[e * 128 + 32 * db0 + r32] = f2bf(a0[r]); o[e * 128 + 32 * db0 + 32 + r32] = f2bf(a1[r]); }
;     __syncthreads();
	ds_read_b128 v[16:19], v50 offset:18432
	ds_read_b128 v[0:3], v54
	ds_read_b128 v[38:41], v50 offset:18464
	ds_read_b128 v[42:45], v54 offset:32
	s_waitcnt lgkmcnt(2)
	v_mfma_f32_32x32x16_bf16 v[0:15], v[16:19], v[0:3], 0
	ds_read_b128 v[20:23], v54 offset:4608
	ds_read_b128 v[46:49], v54 offset:4640
	s_waitcnt lgkmcnt(1)
	v_mfma_f32_32x32x16_bf16 v[16:31], v[16:19], v[20:23], 0
	v_mfma_f32_32x32x16_bf16 v[0:15], v[38:41], v[42:45], v[0:15]
	s_waitcnt lgkmcnt(0)
	v_mfma_f32_32x32x16_bf16 v[16:31], v[38:41], v[46:49], v[16:31]
	ds_read_b128 v[38:41], v50 offset:18496
	ds_read_b128 v[42:45], v54 offset:64
	ds_read_b128 v[46:49], v50 offset:18528
	ds_read_b128 v[50:53], v54 offset:96
	s_waitcnt lgkmcnt(2)
	v_mfma_f32_32x32x16_bf16 v[0:15], v[38:41], v[42:45], v[0:15]
	ds_read_b128 v[42:45], v54 offset:4672
	ds_read_b128 v[54:57], v54 offset:4704
	s_waitcnt lgkmcnt(1)
	v_mfma_f32_32x32x16_bf16 v[16:31], v[38:41], v[42:45], v[16:31]
	v_lshlrev_b32_e32 v38, 9, v58
	v_or3_b32 v38, s2, v38, v59
	v_ashrrev_i32_e32 v39, 31, v38
	v_lshl_add_u64 v[38:39], v[38:39], 1, s[12:13]
	v_add_co_u32_e32 v40, vcc, s10, v38
	v_mfma_f32_32x32x16_bf16 v[0:15], v[46:49], v[50:53], v[0:15]
	s_nop 0
	v_addc_co_u32_e32 v41, vcc, 0, v39, vcc
	s_waitcnt lgkmcnt(0)
	v_mfma_f32_32x32x16_bf16 v[16:31], v[46:49], v[54:57], v[16:31]
	s_nop 7
	v_cvt_pk_bf16_f32 v0, v0, s0
	v_cvt_pk_bf16_f32 v1, v1, s0
	v_cvt_pk_bf16_f32 v2, v2, s0
	v_cvt_pk_bf16_f32 v3, v3, s0
	v_cvt_pk_bf16_f32 v4, v4, s0
	v_cvt_pk_bf16_f32 v5, v5, s0
	v_cvt_pk_bf16_f32 v6, v6, s0
	v_cvt_pk_bf16_f32 v16, v16, s0
	v_cvt_pk_bf16_f32 v17, v17, s0
	v_cvt_pk_bf16_f32 v18, v18, s0
	v_cvt_pk_bf16_f32 v19, v19, s0
	v_cvt_pk_bf16_f32 v20, v20, s0
	v_cvt_pk_bf16_f32 v21, v21, s0
	v_cvt_pk_bf16_f32 v22, v22, s0
	v_cvt_pk_bf16_f32 v7, v7, s0
	v_cvt_pk_bf16_f32 v23, v23, s0
	v_cvt_pk_bf16_f32 v8, v8, s0
	v_cvt_pk_bf16_f32 v24, v24, s0
	v_cvt_pk_bf16_f32 v9, v9, s0
	v_cvt_pk_bf16_f32 v25, v25, s0
	v_cvt_pk_bf16_f32 v10, v10, s0
	v_cvt_pk_bf16_f32 v26, v26, s0
	v_cvt_pk_bf16_f32 v11, v11, s0
	v_cvt_pk_bf16_f32 v27, v27, s0
	v_cvt_pk_bf16_f32 v12, v12, s0
	v_cvt_pk_bf16_f32 v28, v28, s0
	v_cvt_pk_bf16_f32 v13, v13, s0
	v_cvt_pk_bf16_f32 v29, v29, s0
	v_cvt_pk_bf16_f32 v14, v14, s0
	v_cvt_pk_bf16_f32 v30, v30, s0
	v_cvt_pk_bf16_f32 v15, v15, s0
	v_cvt_pk_bf16_f32 v31, v31, s0
	global_store_short v[38:39], v0, off
	global_store_short v[38:39], v16, off offset:64
	global_store_short v[38:39], v1, off offset:256
	global_store_short v[38:39], v17, off offset:320
	global_store_short v[38:39], v2, off offset:512
	global_store_short v[38:39], v18, off offset:576
	global_store_short v[38:39], v3, off offset:768
	global_store_short v[38:39], v19, off offset:832
	global_store_short v[38:39], v4, off offset:2048
	global_store_short v[38:39], v20, off offset:2112
	global_store_short v[38:39], v5, off offset:2304
	global_store_short v[38:39], v21, off offset:2368
	global_store_short v[38:39], v6, off offset:2560
	global_store_short v[38:39], v22, off offset:2624
	global_store_short v[38:39], v7, off offset:2816
	global_store_short v[38:39], v23, off offset:2880
	global_store_short v[40:41], v8, off
	global_store_short v[40:41], v24, off offset:64
	global_store_short v[40:41], v9, off offset:256
	global_store_short v[40:41], v25, off offset:320
	global_store_short v[40:41], v10, off offset:512
	global_store_short v[40:41], v26, off offset:576
	global_store_short v[40:41], v11, off offset:768
	global_store_short v[40:41], v27, off offset:832
	global_store_short v[40:41], v12, off offset:2048
	global_store_short v[40:41], v28, off offset:2112
	global_store_short v[40:41], v13, off offset:2304
	global_store_short v[40:41], v29, off offset:2368
	global_store_short v[40:41], v14, off offset:2560
	global_store_short v[40:41], v30, off offset:2624
	global_store_short v[40:41], v15, off offset:2816
	global_store_short v[40:41], v31, off offset:2880
	s_waitcnt lgkmcnt(0)
	s_barrier
	s_cbranch_scc0 .LBB0_440

; __device__ __forceinline__ unsigned pk2(float lo, float hi) { const f32x2 v = {lo, hi}; return __builtin_bit_cast(unsigned, __builtin_convertvector(v, bf16x2_t)); }
;     __device__ __forceinline__ void operator()(EPI_ARGS) const {
;         const int row0 = u.pm * BM + wr * 64 + fr, col0 = u.pn * BM + wc * 32 + 8 * fq;
; #pragma unroll
;         for (int ai = 0; ai < 2; ++ai)
; #pragma unroll
;             for (int m = 0; m < 4; ++m) { bf16* rowp = O + (size_t)(row0 + ai * HALF + m * 16) * ldc + col0;
; #pragma unroll
;                 for (int bj = 0; bj < 2; ++bj) { const f32x4 v0 = acc[ai][bj][m][0], v1 = acc[ai][bj][m][1];
;                     u32x4 w; w.x = pk2(v0[0], v0[1]); w.y = pk2(v0[2], v0[3]); w.z = pk2(v1[0], v1[1]); w.w = pk2(v1[2], v1[3]);
;                     *(u32x4*)(rowp + bj * HALF) = w; } }
;     }
.LBB0_497:
	v_lshl_add_u32 v148, s10, 8, v136
	v_lshl_or_b32 v142, s11, 8, v138
	v_ashrrev_i32_e32 v143, 31, v142
	v_mov_b64_e32 v[144:145], s[4:5]
	v_cvt_pk_bf16_f32 v68, v68, v69
	v_cvt_pk_bf16_f32 v69, v70, v71
	v_cvt_pk_bf16_f32 v70, v64, v65
	v_add_u32_e32 v64, 0x80, v148
	v_mad_i64_i32 v[146:147], s[10:11], v148, s63, v[144:145]
	v_lshlrev_b64 v[142:143], 1, v[142:143]
	v_cvt_pk_bf16_f32 v108, v108, v109
	v_cvt_pk_bf16_f32 v109, v110, v111
	v_cvt_pk_bf16_f32 v110, v104, v105
	v_or_b32_e32 v104, 16, v148
	v_mad_i64_i32 v[64:65], s[10:11], v64, s63, v[144:145]
	v_cvt_pk_bf16_f32 v44, v44, v45
	v_cvt_pk_bf16_f32 v45, v46, v47
	v_cvt_pk_bf16_f32 v46, v40, v41
	v_add_u32_e32 v40, 0x90, v148
	v_lshl_add_u64 v[146:147], v[146:147], 0, v[142:143]
	v_cvt_pk_bf16_f32 v111, v106, v107
	v_mad_i64_i32 v[104:105], s[10:11], v104, s63, v[144:145]
	v_cvt_pk_bf16_f32 v92, v92, v93
	v_cvt_pk_bf16_f32 v93, v94, v95
	v_cvt_pk_bf16_f32 v94, v88, v89
	v_or_b32_e32 v88, 32, v148
	v_lshl_add_u64 v[64:65], v[64:65], 0, v[142:143]
	v_cvt_pk_bf16_f32 v47, v42, v43
	v_mad_i64_i32 v[40:41], s[10:11], v40, s63, v[144:145]
	v_cvt_pk_bf16_f32 v28, v28, v29
	v_cvt_pk_bf16_f32 v29, v30, v31
	v_cvt_pk_bf16_f32 v30, v24, v25
	v_add_u32_e32 v24, 0xa0, v148
	global_store_dwordx4 v[146:147], v[108:111], off offset:256
	v_cvt_pk_bf16_f32 v95, v90, v91
	v_mad_i64_i32 v[88:89], s[10:11], v88, s63, v[144:145]
	v_lshl_add_u64 v[108:109], v[104:105], 0, v[142:143]
	v_cvt_pk_bf16_f32 v76, v76, v77
	v_cvt_pk_bf16_f32 v77, v78, v79
	v_cvt_pk_bf16_f32 v78, v72, v73
	v_or_b32_e32 v72, 48, v148
	global_store_dwordx4 v[64:65], v[44:47], off offset:256
	v_cvt_pk_bf16_f32 v31, v26, v27
	v_mad_i64_i32 v[24:25], s[10:11], v24, s63, v[144:145]
	v_lshl_add_u64 v[44:45], v[40:41], 0, v[142:143]
	v_cvt_pk_bf16_f32 v12, v12, v13
	v_cvt_pk_bf16_f32 v13, v14, v15
	v_cvt_pk_bf16_f32 v14, v8, v9
	v_add_u32_e32 v8, 0xb0, v148
	global_store_dwordx4 v[108:109], v[92:95], off offset:256
	v_cvt_pk_bf16_f32 v79, v74, v75
	v_mad_i64_i32 v[72:73], s[10:11], v72, s63, v[144:145]
	v_lshl_add_u64 v[92:93], v[88:89], 0, v[142:143]
	global_store_dwordx4 v[44:45], v[28:31], off offset:256
	v_cvt_pk_bf16_f32 v15, v10, v11
	v_mad_i64_i32 v[8:9], s[10:11], v8, s63, v[144:145]
	v_lshl_add_u64 v[28:29], v[24:25], 0, v[142:143]
	v_cvt_pk_bf16_f32 v124, v124, v125
	v_cvt_pk_bf16_f32 v125, v126, v127
	v_cvt_pk_bf16_f32 v126, v120, v121
	v_cvt_pk_bf16_f32 v127, v122, v123
	v_cvt_pk_bf16_f32 v104, v116, v117
	v_cvt_pk_bf16_f32 v105, v118, v119
	v_cvt_pk_bf16_f32 v106, v112, v113
	v_cvt_pk_bf16_f32 v107, v114, v115
	v_cvt_pk_bf16_f32 v88, v100, v101
	v_cvt_pk_bf16_f32 v89, v102, v103
	v_cvt_pk_bf16_f32 v90, v96, v97
	v_cvt_pk_bf16_f32 v91, v98, v99
	global_store_dwordx4 v[92:93], v[76:79], off offset:256
	v_cvt_pk_bf16_f32 v74, v80, v81
	v_cvt_pk_bf16_f32 v75, v82, v83
	v_lshl_add_u64 v[76:77], v[72:73], 0, v[142:143]
	v_cvt_pk_bf16_f32 v72, v84, v85
	v_cvt_pk_bf16_f32 v73, v86, v87
	v_cvt_pk_bf16_f32 v71, v66, v67
	v_cvt_pk_bf16_f32 v60, v60, v61
	v_cvt_pk_bf16_f32 v61, v62, v63
	v_cvt_pk_bf16_f32 v62, v56, v57
	v_cvt_pk_bf16_f32 v63, v58, v59
	v_cvt_pk_bf16_f32 v40, v52, v53
	v_cvt_pk_bf16_f32 v41, v54, v55
	v_cvt_pk_bf16_f32 v42, v48, v49
	v_cvt_pk_bf16_f32 v43, v50, v51
	v_cvt_pk_bf16_f32 v24, v36, v37
	v_cvt_pk_bf16_f32 v25, v38, v39
	v_cvt_pk_bf16_f32 v26, v32, v33
	v_cvt_pk_bf16_f32 v27, v34, v35
	global_store_dwordx4 v[28:29], v[12:15], off offset:256
	v_cvt_pk_bf16_f32 v10, v16, v17
	v_cvt_pk_bf16_f32 v11, v18, v19
	v_lshl_add_u64 v[12:13], v[8:9], 0, v[142:143]
	v_cvt_pk_bf16_f32 v8, v20, v21
	v_cvt_pk_bf16_f32 v9, v22, v23
	v_cvt_pk_bf16_f32 v4, v4, v5
	v_cvt_pk_bf16_f32 v5, v6, v7
	v_cvt_pk_bf16_f32 v6, v0, v1
	v_cvt_pk_bf16_f32 v7, v2, v3
	s_andn2_b64 vcc, exec, s[16:17]
	s_mov_b64 s[10:11], -1
	global_store_dwordx4 v[146:147], v[124:127], off
	global_store_dwordx4 v[108:109], v[104:107], off
	global_store_dwordx4 v[92:93], v[88:91], off
	global_store_dwordx4 v[76:77], v[72:75], off
	global_store_dwordx4 v[76:77], v[68:71], off offset:256
	global_store_dwordx4 v[64:65], v[60:63], off
	global_store_dwordx4 v[44:45], v[40:43], off
	global_store_dwordx4 v[28:29], v[24:27], off
	global_store_dwordx4 v[12:13], v[8:11], off
	global_store_dwordx4 v[12:13], v[4:7], off offset:256
	s_cbranch_vccnz .LBB0_490
	s_andn2_b64 vcc, exec, s[2:3]
	s_cbranch_vccnz .LBB0_489
	s_barrier
	s_branch .LBB0_489

; #define LAS __attribute__((address_space(3)))
; __device__ __forceinline__ float bf2f(unsigned b) { return __uint_as_float(b << 16); }
; __device__ __forceinline__ bf16 f2bf(float f) { return (bf16)(pk2(f, 0.f) & 0xffffu); }
; __device__ __forceinline__ float ex2f(float x) { return __builtin_amdgcn_exp2f(x); }
; __device__ __forceinline__ void ret_scan(LAS unsigned char* lds, bf16* AT, float* out, int G, const float* lgs) {
;     const int t_ = my_tid(lds);
;     for (int idx = blockIdx.x * 512 + t_; idx < 2 * 4 * 128 * 128; idx += G * 512) {
;         const int d = idx & 127, e = (idx >> 7) & 127, hh = (idx >> 14) & 3, b = idx >> 16;
;         const float g64 = ex2f(64.f * lgs[hh]);
;         bf16* p = AT + (size_t)(b * 256 * 4 + hh) * 16384 + e * 128 + d; float S = 0.f;
;         for (int c = 0; c < 256; c += 8) { float a[8];
; #pragma unroll
;             for (int i = 0; i < 8; ++i) a[i] = bf2f(p[(size_t)(c + i) * 65536]);
; #pragma unroll
;             for (int i = 0; i < 8; ++i) { p[(size_t)(c + i) * 65536] = f2bf(S); S = g64 * S + a[i]; } }
;         out[O_PRET + (size_t)((b * 4 + hh) * 128 + d) * 128 + e] = S;
;     }
; }
.LBB0_504:
	v_add_co_u32_e32 v16, vcc, 0xffe20000, v4
	v_cvt_pk_bf16_f32 v61, v14, s0
	s_nop 0
	v_addc_co_u32_e32 v17, vcc, -1, v5, vcc
	v_add_co_u32_e32 v18, vcc, 0xffe40000, v4
	s_add_i32 s18, s18, 16
	s_nop 0
	v_addc_co_u32_e32 v19, vcc, -1, v5, vcc
	v_add_co_u32_e32 v20, vcc, 0xffe60000, v4
	s_cmpk_lt_u32 s18, 0xf8
	s_nop 0
	v_addc_co_u32_e32 v21, vcc, -1, v5, vcc
	v_add_co_u32_e32 v22, vcc, 0xffe80000, v4
	s_nop 1
	v_addc_co_u32_e32 v23, vcc, -1, v5, vcc
	v_add_co_u32_e32 v24, vcc, 0xffea0000, v4
	s_nop 1
	v_addc_co_u32_e32 v25, vcc, -1, v5, vcc
	v_add_co_u32_e32 v26, vcc, 0xffec0000, v4
	s_nop 1
	v_addc_co_u32_e32 v27, vcc, -1, v5, vcc
	v_add_co_u32_e32 v28, vcc, 0xffee0000, v4
	s_nop 1
	v_addc_co_u32_e32 v29, vcc, -1, v5, vcc
	v_add_co_u32_e32 v30, vcc, 0xfff00000, v4
	s_nop 1
	v_addc_co_u32_e32 v31, vcc, -1, v5, vcc
	v_add_co_u32_e32 v32, vcc, s10, v4
	global_load_ushort v15, v[16:17], off
	global_load_ushort v46, v[18:19], off
	global_load_ushort v47, v[20:21], off
	global_load_ushort v48, v[22:23], off
	global_load_ushort v49, v[24:25], off
	global_load_ushort v50, v[26:27], off
	global_load_ushort v51, v[28:29], off
	global_load_ushort v52, v[30:31], off
	v_addc_co_u32_e32 v33, vcc, -1, v5, vcc
	v_add_co_u32_e32 v34, vcc, s11, v4
	s_waitcnt vmcnt(0) lgkmcnt(0)
	v_lshlrev_b32_e32 v15, 16, v15
	v_addc_co_u32_e32 v35, vcc, -1, v5, vcc
	v_add_co_u32_e32 v36, vcc, s12, v4
	v_lshlrev_b32_e32 v46, 16, v46
	s_nop 0
	v_addc_co_u32_e32 v37, vcc, -1, v5, vcc
	v_add_co_u32_e32 v38, vcc, s13, v4
	v_fmac_f32_e32 v15, v13, v14
	s_nop 0
	v_addc_co_u32_e32 v39, vcc, -1, v5, vcc
	v_add_co_u32_e32 v40, vcc, s14, v4
	v_lshlrev_b32_e32 v47, 16, v47
	s_nop 0
	v_addc_co_u32_e32 v41, vcc, -1, v5, vcc
	v_add_co_u32_e32 v42, vcc, s15, v4
	v_fmac_f32_e32 v46, v13, v15
	s_nop 0
	v_addc_co_u32_e32 v43, vcc, -1, v5, vcc
	v_add_co_u32_e32 v44, vcc, s16, v4
	v_lshlrev_b32_e32 v48, 16, v48
	s_nop 0
	v_addc_co_u32_e32 v45, vcc, -1, v5, vcc
	global_load_ushort v53, v[32:33], off
	global_load_ushort v54, v[34:35], off
	global_load_ushort v55, v[36:37], off
	global_load_ushort v56, v[38:39], off
	global_load_ushort v57, v[40:41], off
	global_load_ushort v58, v[42:43], off
	global_load_ushort v59, v[44:45], off
	global_load_ushort v60, v[4:5], off
	v_fmac_f32_e32 v47, v13, v46
	v_lshlrev_b32_e32 v49, 16, v49
	v_fmac_f32_e32 v48, v13, v47
	v_lshlrev_b32_e32 v50, 16, v50
	v_fmac_f32_e32 v49, v13, v48
	v_lshlrev_b32_e32 v51, 16, v51
	v_fmac_f32_e32 v50, v13, v49
	v_lshlrev_b32_e32 v52, 16, v52
	v_cvt_pk_bf16_f32 v14, v15, s0
	v_fmac_f32_e32 v51, v13, v50
	global_store_short v[18:19], v14, off
	v_cvt_pk_bf16_f32 v14, v46, s0
	v_fmac_f32_e32 v52, v13, v51
	global_store_short v[16:17], v61, off
	global_store_short v[20:21], v14, off
	v_cvt_pk_bf16_f32 v14, v47, s0
	global_store_short v[22:23], v14, off
	v_cvt_pk_bf16_f32 v22, v52, s0
	global_store_short v[32:33], v22, off
	v_cvt_pk_bf16_f32 v14, v48, s0
	global_store_short v[24:25], v14, off
	v_cvt_pk_bf16_f32 v14, v49, s0
	global_store_short v[26:27], v14, off
	v_cvt_pk_bf16_f32 v14, v50, s0
	global_store_short v[28:29], v14, off
	v_cvt_pk_bf16_f32 v14, v51, s0
	global_store_short v[30:31], v14, off
	s_waitcnt vmcnt(0) lgkmcnt(0)
	v_lshlrev_b32_e32 v15, 16, v53
	v_lshlrev_b32_e32 v16, 16, v54
	v_fmac_f32_e32 v15, v13, v52
	v_lshlrev_b32_e32 v17, 16, v55
	v_fmac_f32_e32 v16, v13, v15
	v_lshlrev_b32_e32 v18, 16, v56
	v_cvt_pk_bf16_f32 v22, v15, s0
	v_cvt_pk_bf16_f32 v15, v16, s0
	v_fmac_f32_e32 v17, v13, v16
	v_lshlrev_b32_e32 v19, 16, v57
	global_store_short v[36:37], v15, off
	v_cvt_pk_bf16_f32 v15, v17, s0
	v_fmac_f32_e32 v18, v13, v17
	v_lshlrev_b32_e32 v20, 16, v58
	global_store_short v[38:39], v15, off
	v_cvt_pk_bf16_f32 v15, v18, s0
	v_fmac_f32_e32 v19, v13, v18
	v_lshlrev_b32_e32 v21, 16, v59
	global_store_short v[40:41], v15, off
	v_cvt_pk_bf16_f32 v15, v19, s0
	v_fmac_f32_e32 v20, v13, v19
	global_store_short v[42:43], v15, off
	v_cvt_pk_bf16_f32 v15, v20, s0
	v_fmac_f32_e32 v21, v13, v20
	v_lshlrev_b32_e32 v14, 16, v60
	global_store_short v[44:45], v15, off
	v_cvt_pk_bf16_f32 v15, v21, s0
	global_store_short v[4:5], v15, off
	v_fmac_f32_e32 v14, v13, v21
	v_lshl_add_u64 v[4:5], v[4:5], 0, s[8:9]
	global_store_short v[34:35], v22, off
	s_cbranch_scc1 .LBB0_504
	v_and_b32_e32 v4, 0x7f, v6
	v_lshlrev_b32_e32 v5, 9, v12
	v_lshlrev_b32_e32 v11, 7, v11
	v_or3_b32 v4, v11, v5, v4
	v_ashrrev_i32_e32 v5, 31, v4
	v_and_b32_e32 v0, 0x7f, v0
	v_lshlrev_b64 v[4:5], 9, v[4:5]
	v_lshl_add_u64 v[4:5], s[2:3], 0, v[4:5]
	v_lshlrev_b32_e32 v0, 2, v0
	v_lshl_add_u64 v[4:5], v[4:5], 0, v[0:1]
	v_add_co_u32_e32 v4, vcc, 0x9600000, v4
	v_add_u32_e32 v6, s0, v6
	s_nop 0
	v_addc_co_u32_e32 v5, vcc, 0, v5, vcc
	v_cmp_lt_i32_e32 vcc, s17, v6
	s_or_b64 s[6:7], vcc, s[6:7]
	global_store_dword v[4:5], v14, off
	s_andn2_b64 exec, exec, s[6:7]
	s_cbranch_execnz .LBB0_503

; __device__ __forceinline__ unsigned pk2(float lo, float hi) { const f32x2 v = {lo, hi}; return __builtin_bit_cast(unsigned, __builtin_convertvector(v, bf16x2_t)); }
; __device__ __forceinline__ float half_sum(float v) { auto rr = __builtin_amdgcn_permlane32_swap(__float_as_uint(v), __float_as_uint(v), false, false); return __uint_as_float(rr[0]) + __uint_as_float(rr[1]); }
; template <int DQK, int DV, int MODE>
; __device__ __forceinline__ void flash_unit(LAS unsigned char* lds, const bf16* Qp, int qpitch, const bf16* K0, int kpitch, const bf16* K1, const bf16* VT, int vpitch,
;                                            bf16* Op, int opitch, int NT, int jbase, int qpos0) {
;     ...
;     const int tid_ = my_tid(lds); const int tid = tid_, lane = tid & 63, r32 = lane & 31, hi = lane >> 5; const int wid = __builtin_amdgcn_readfirstlane(tid >> 6);
;     const bf16* Qrow = Qp + (size_t)(wid * 32 + r32) * qpitch + 8 * hi;
;     bf16x8 qf[QREG ? ND0 : 1];
;     if constexpr (QREG) {
; #pragma unroll
;         for (int d0 = 0; d0 < ND0; ++d0) qf[d0] = *(const bf16x8*)(Qrow + 16 * d0);
;     ...
;     { const float lt = half_sum(lrun), inv = 1.f / lt;
;       bf16* orow = Op + (size_t)(wid * 32 + r32) * opitch + 4 * hi;
; #pragma unroll
;       for (int db = 0; db < NDB; ++db)
; #pragma unroll
;           for (int rg = 0; rg < 4; ++rg) { u32x2 w; w.x = pk2(o[db][4 * rg] * inv, o[db][4 * rg + 1] * inv); w.y = pk2(o[db][4 * rg + 2] * inv, o[db][4 * rg + 3] * inv);
;               *(u32x2*)(orow + 32 * db + 8 * rg) = w; } }
.LBB0_511:
	v_mov_b32_e32 v0, v159
	s_nop 1
	v_permlane32_swap_b32_e32 v159, v0
	v_add_f32_e32 v0, v159, v0
	s_waitcnt vmcnt(0) lgkmcnt(0)
	v_div_scale_f32 v2, s[4:5], v0, v0, 1.0
	v_rcp_f32_e32 v3, v2
	s_lshl_b64 s[2:3], s[24:25], 11
	s_add_u32 s2, s61, s2
	s_addc_u32 s3, s62, s3
	v_fma_f32 v4, -v2, v3, 1.0
	v_fmac_f32_e32 v3, v4, v3
	v_div_scale_f32 v4, vcc, 1.0, v0, 1.0
	v_mul_f32_e32 v5, v4, v3
	v_fma_f32 v6, -v2, v5, v4
	v_fmac_f32_e32 v5, v6, v3
	v_fma_f32 v2, -v2, v5, v4
	v_div_fmas_f32 v2, v2, v3, v5
	v_div_fixup_f32 v0, v2, v0, 1.0
	v_lshlrev_b64 v[2:3], 11, v[152:153]
	v_lshl_add_u64 v[2:3], s[2:3], 0, v[2:3]
	v_mov_b32_e32 v155, v1
	v_pk_mul_f32 v[4:5], v[32:33], v[0:1] op_sel_hi:[1,0]
	v_pk_mul_f32 v[6:7], v[34:35], v[0:1] op_sel_hi:[1,0]
	v_lshl_add_u64 v[2:3], v[2:3], 0, v[154:155]
	v_cvt_pk_bf16_f32 v4, v4, v5
	v_cvt_pk_bf16_f32 v5, v6, v7
	s_barrier
	global_store_dwordx2 v[2:3], v[4:5], off
	v_pk_mul_f32 v[4:5], v[36:37], v[0:1] op_sel_hi:[1,0]
	v_pk_mul_f32 v[6:7], v[38:39], v[0:1] op_sel_hi:[1,0]
	v_cvt_pk_bf16_f32 v4, v4, v5
	v_cvt_pk_bf16_f32 v5, v6, v7
	global_store_dwordx2 v[2:3], v[4:5], off offset:16
	v_pk_mul_f32 v[4:5], v[40:41], v[0:1] op_sel_hi:[1,0]
	v_pk_mul_f32 v[6:7], v[42:43], v[0:1] op_sel_hi:[1,0]
	v_cvt_pk_bf16_f32 v4, v4, v5
	v_cvt_pk_bf16_f32 v5, v6, v7
	global_store_dwordx2 v[2:3], v[4:5], off offset:32
	v_pk_mul_f32 v[4:5], v[44:45], v[0:1] op_sel_hi:[1,0]
	v_pk_mul_f32 v[6:7], v[46:47], v[0:1] op_sel_hi:[1,0]
	v_cvt_pk_bf16_f32 v4, v4, v5
	v_cvt_pk_bf16_f32 v5, v6, v7
	global_store_dwordx2 v[2:3], v[4:5], off offset:48
	v_pk_mul_f32 v[4:5], v[16:17], v[0:1] op_sel_hi:[1,0]
	v_pk_mul_f32 v[6:7], v[18:19], v[0:1] op_sel_hi:[1,0]
	v_cvt_pk_bf16_f32 v4, v4, v5
	v_cvt_pk_bf16_f32 v5, v6, v7
	global_store_dwordx2 v[2:3], v[4:5], off offset:64
	v_pk_mul_f32 v[4:5], v[20:21], v[0:1] op_sel_hi:[1,0]
	v_pk_mul_f32 v[6:7], v[22:23], v[0:1] op_sel_hi:[1,0]
	v_cvt_pk_bf16_f32 v4, v4, v5
	v_cvt_pk_bf16_f32 v5, v6, v7
	global_store_dwordx2 v[2:3], v[4:5], off offset:80
	v_pk_mul_f32 v[4:5], v[24:25], v[0:1] op_sel_hi:[1,0]
	v_pk_mul_f32 v[6:7], v[26:27], v[0:1] op_sel_hi:[1,0]
	v_cvt_pk_bf16_f32 v4, v4, v5
	v_cvt_pk_bf16_f32 v5, v6, v7
	global_store_dwordx2 v[2:3], v[4:5], off offset:96
	v_pk_mul_f32 v[4:5], v[28:29], v[0:1] op_sel_hi:[1,0]
	v_pk_mul_f32 v[6:7], v[30:31], v[0:1] op_sel_hi:[1,0]
	v_cvt_pk_bf16_f32 v4, v4, v5
	v_cvt_pk_bf16_f32 v5, v6, v7
	s_mov_b64 s[4:5], 0
	s_and_b64 vcc, exec, s[22:23]
	global_store_dwordx2 v[2:3], v[4:5], off offset:112
	s_cbranch_vccnz .LBB0_508
.LBB0_512:
	s_and_b64 s[2:3], s[4:5], exec
	s_cselect_b32 s64, s58, s57
	s_lshl_b32 s8, s64, 8
	s_or_b32 s24, s12, s8
	s_mul_hi_u32 s3, s24, 0x600
	s_mul_i32 s2, s24, 0x600
	s_add_i32 s3, s3, s63
	s_add_u32 s2, s59, s2
	s_getreg_b32 s6, hwreg(HW_REG_HW_ID, 0, 6)
	s_addc_u32 s3, s60, s3
	s_lshl_b32 s6, s6, 2
	s_and_b32 s6, s6, 0xfc
	s_add_i32 s6, s6, 0
	s_add_i32 s6, s6, 0x25a00
	v_mov_b32_e32 v0, s6
	ds_read_b32 v0, v0
	v_mbcnt_lo_u32_b32 v85, -1, 0
	v_mbcnt_hi_u32_b32 v85, -1, v85
	v_mov_b64_e32 v[2:3], s[2:3]
	v_bfe_u32 v16, v85, 5, 1
	s_waitcnt lgkmcnt(0)
	v_readfirstlane_b32 s6, v0
	s_nop 1
	v_lshl_add_u32 v84, s6, 6, v85
	s_nop 0
	v_readfirstlane_b32 s65, v84
	s_ashr_i32 s26, s65, 1
	v_mov_b32_e32 v0, s26
	v_bfi_b32 v152, s42, v0, v85
	v_mad_i64_i32 v[2:3], s[2:3], v152, s41, v[2:3]
	v_lshlrev_b32_e32 v0, 4, v16
	v_lshl_add_u64 v[2:3], v[2:3], 0, v[0:1]
	global_load_dwordx4 v[116:119], v[2:3], off
	global_load_dwordx4 v[112:115], v[2:3], off offset:32
	global_load_dwordx4 v[108:111], v[2:3], off offset:64
	global_load_dwordx4 v[104:107], v[2:3], off offset:96
	global_load_dwordx4 v[6:9], v[2:3], off offset:128
	s_nop 0
	global_load_dwordx4 v[2:5], v[2:3], off offset:160
	v_mul_hi_i32 v0, v84, s45
	v_cmp_gt_i32_e64 s[2:3], s43, v84
	v_lshrrev_b32_e32 v87, 31, v0
	v_ashrrev_i32_e32 v90, 1, v0
	s_and_saveexec_b64 s[6:7], s[2:3]
	s_cbranch_execz .LBB0_518
	v_add_u32_e32 v10, v90, v87
	v_mad_u64_u32 v[12:13], s[22:23], v10, -12, v[84:85]
	v_cmp_gt_i32_e32 vcc, 8, v12
	v_ashrrev_i32_e32 v11, 31, v10
	v_lshlrev_b32_e32 v12, 3, v12
	s_and_saveexec_b64 s[22:23], vcc
	s_xor_b64 s[22:23], exec, s[22:23]
	v_lshlrev_b64 v[10:11], 10, v[10:11]
	v_lshl_add_u64 v[10:11], s[14:15], 0, v[10:11]
	v_ashrrev_i32_e32 v13, 31, v12
	v_lshl_add_u64 v[14:15], v[12:13], 1, v[10:11]
	s_andn2_saveexec_b64 s[22:23], s[22:23]
	v_lshlrev_b64 v[10:11], 6, v[10:11]
	v_lshl_add_u64 v[10:11], s[16:17], 0, v[10:11]
	v_subrev_u32_e32 v0, 64, v12
	v_lshl_add_u64 v[14:15], v[0:1], 1, v[10:11]
	s_or_b64 exec, exec, s[22:23]
	global_load_dwordx4 v[96:99], v[14:15], off
.LBB0_518:
	s_or_b64 exec, exec, s[6:7]
	v_add_u32_e32 v86, 0x200, v84
	v_mul_hi_i32 v0, v86, s45
	s_xor_b64 s[22:23], s[4:5], -1
	v_and_b32_e32 v17, 31, v85
	s_and_b32 s66, s26, 0xffffffe0
	v_ashrrev_i32_e32 v153, 31, v152
	v_lshlrev_b32_e32 v154, 3, v16
	s_mov_b32 s25, s13
	v_cmp_lt_i32_e32 vcc, s46, v84
	v_cmp_gt_i32_e64 s[4:5], s47, v84
	v_lshrrev_b32_e32 v92, 31, v0
	v_ashrrev_i32_e32 v91, 1, v0
	s_and_saveexec_b64 s[26:27], s[4:5]
	s_cbranch_execz .LBB0_524
	v_add_u32_e32 v10, v91, v92
	v_mad_u64_u32 v[12:13], s[6:7], v10, -12, v[86:87]
	v_cmp_gt_i32_e64 s[6:7], 8, v12
	v_ashrrev_i32_e32 v11, 31, v10
	v_lshlrev_b32_e32 v12, 3, v12
	s_and_saveexec_b64 s[72:73], s[6:7]
	s_xor_b64 s[6:7], exec, s[72:73]
	v_lshlrev_b64 v[10:11], 10, v[10:11]
	v_lshl_add_u64 v[10:11], s[14:15], 0, v[10:11]
	v_ashrrev_i32_e32 v13, 31, v12
	v_lshl_add_u64 v[14:15], v[12:13], 1, v[10:11]
	s_andn2_saveexec_b64 s[6:7], s[6:7]
	v_lshlrev_b64 v[10:11], 6, v[10:11]
	v_lshl_add_u64 v[10:11], s[16:17], 0, v[10:11]
	v_subrev_u32_e32 v0, 64, v12
	v_lshl_add_u64 v[14:15], v[0:1], 1, v[10:11]
	s_or_b64 exec, exec, s[6:7]
	global_load_dwordx4 v[100:103], v[14:15], off
.LBB0_524:
	s_or_b64 exec, exec, s[26:27]
	v_ashrrev_i32_e32 v14, 3, v84
	v_ashrrev_i32_e32 v15, 31, v14
	v_lshlrev_b32_e32 v0, 3, v85
	v_lshlrev_b64 v[88:89], 16, v[14:15]
	v_and_b32_e32 v16, 56, v0
	v_lshl_add_u64 v[10:11], s[18:19], 0, v[88:89]
	v_lshlrev_b32_e32 v0, 1, v16
	v_lshl_add_u64 v[156:157], v[10:11], 0, v[0:1]
	global_load_dwordx4 v[10:13], v[156:157], off
	s_and_saveexec_b64 s[6:7], s[2:3]
	s_cbranch_execz .LBB0_526
	v_add_u32_e32 v0, v90, v87
	v_mul_lo_u32 v15, v0, s48
	v_add_lshl_u32 v15, v15, v84, 4
	v_mul_lo_u32 v0, v0, s49
	v_add3_u32 v0, 0, v15, v0
	s_waitcnt vmcnt(0) lgkmcnt(0)
	ds_write_b128 v0, v[96:99]

; __device__ __forceinline__ float bflo(unsigned w) { return __uint_as_float(w << 16); }
; __device__ __forceinline__ float bfhi(unsigned w) { return __uint_as_float(w & 0xffff0000u); }
; __device__ __forceinline__ unsigned pk2(float lo, float hi) { const f32x2 v = {lo, hi}; return __builtin_bit_cast(unsigned, __builtin_convertvector(v, bf16x2_t)); }
; __device__ __forceinline__ float ex2f(float x) { return __builtin_amdgcn_exp2f(x); }
; #define FL_GLOADK(j) do { \
;     _Pragma("unroll") for (int i_ = 0; i_ < KPT; ++i_) { const int ci = tid + 512 * i_; if (ci < NKC) { const int key = ci / KCH, ch = ci - key * KCH; \
;         kreg[i_] = *(const u32x4*)(K0 + (size_t)(64 * (j) + key) * kpitch + ch * 8); } } } while (0)
; #define FL_LSTOREK(buf) do { \
;     _Pragma("unroll") for (int i_ = 0; i_ < KPT; ++i_) { const int ci = tid + 512 * i_; if (ci < NKC) { const int key = ci / KCH, ch = ci - key * KCH; \
;         *(LAS u32x4*)(lds + (buf) * KB + (key * KP + ch * 8) * 2) = kreg[i_]; } } } while (0)
; template <int DQK, int DV, int MODE>
; __device__ __forceinline__ void flash_unit(LAS unsigned char* lds, const bf16* Qp, int qpitch, const bf16* K0, int kpitch, const bf16* K1, const bf16* VT, int vpitch,
;                                            bf16* Op, int opitch, int NT, int jbase, int qpos0) {
;     ...
;         const float pos = (float)(qpos0 + wid * 32 + r32);
;         const u32x4 xa = __builtin_bit_cast(u32x4, qf[ND0 - 2]), xb = __builtin_bit_cast(u32x4, qf[ND0 - 1]); u32x4 ra, rb;
; #pragma unroll
;         for (int e = 0; e < 4; ++e) { const float a0 = bflo(xa[e]), a1 = bfhi(xa[e]), b0 = bflo(xb[e]), b1 = bfhi(xb[e]);
;             float s0_, c0_, s1_, c1_; sincos_rev(pos * ex2f(-(float)(8 * hi + 2 * e) * (2.0f / 32.0f) * LG2_10000), s0_, c0_); sincos_rev(pos * ex2f(-(float)(8 * hi + 2 * e + 1) * (2.0f / 32.0f) * LG2_10000), s1_, c1_);
;             ra[e] = pk2(a0 * c0_ - b0 * s0_, a1 * c1_ - b1 * s1_); rb[e] = pk2(b0 * c0_ + a0 * s0_, b1 * c1_ + a1 * s1_); }
;         qf[ND0 - 2] = __builtin_bit_cast(bf16x8, ra); qf[ND0 - 1] = __builtin_bit_cast(bf16x8, rb);
;     }
;     ...
;     for (int j = 0; j < NT; ++j) {
;         const int buf = j & 1;
;         if (j + 1 < NT) { if constexpr (MODE == 1) { FL_GLOADK(j + 1); FL_LSTOREK(buf ^ 1); FL_GLOADV(j + 1); FL_LSTOREV(buf ^ 1); } else { FL_GLOAD(j + 1); } }
.LBB0_528:
	s_or_b64 exec, exec, s[6:7]
	v_mad_u64_u32 v[14:15], s[6:7], v14, s50, v[16:17]
	v_lshl_add_u32 v155, v14, 1, 0
	v_add_u32_e32 v0, 0x6800, v155
	s_waitcnt vmcnt(0) lgkmcnt(0)
	ds_write2_b64 v0, v[10:11], v[12:13] offset1:1
	s_waitcnt lgkmcnt(0)
	s_barrier
	s_and_saveexec_b64 s[26:27], s[2:3]
	s_cbranch_execz .LBB0_534
	v_add_u32_e32 v0, v90, v87
	v_mad_u64_u32 v[10:11], s[6:7], v0, -12, v[84:85]
	v_add_u32_e32 v14, 64, v0
	v_cmp_gt_i32_e64 s[6:7], 8, v10
	v_ashrrev_i32_e32 v15, 31, v14
	v_lshlrev_b32_e32 v10, 3, v10
	s_and_saveexec_b64 s[72:73], s[6:7]
	s_xor_b64 s[6:7], exec, s[72:73]
	v_lshlrev_b64 v[12:13], 10, v[14:15]
	v_lshl_add_u64 v[12:13], s[14:15], 0, v[12:13]
	v_ashrrev_i32_e32 v11, 31, v10
	v_lshl_add_u64 v[12:13], v[10:11], 1, v[12:13]
	s_andn2_saveexec_b64 s[6:7], s[6:7]
	v_lshlrev_b64 v[12:13], 6, v[14:15]
	v_lshl_add_u64 v[12:13], s[16:17], 0, v[12:13]
	v_subrev_u32_e32 v0, 64, v10
	v_lshl_add_u64 v[12:13], v[0:1], 1, v[12:13]
	s_or_b64 exec, exec, s[6:7]
	global_load_dwordx4 v[96:99], v[12:13], off
.LBB0_534:
	s_or_b64 exec, exec, s[26:27]
	s_and_saveexec_b64 s[26:27], s[4:5]
	s_cbranch_execz .LBB0_540
	v_add_u32_e32 v0, v91, v92
	v_mad_u64_u32 v[10:11], s[6:7], v0, -12, v[86:87]
	v_add_u32_e32 v14, 64, v0
	v_cmp_gt_i32_e64 s[6:7], 8, v10
	v_ashrrev_i32_e32 v15, 31, v14
	v_lshlrev_b32_e32 v10, 3, v10
	s_and_saveexec_b64 s[72:73], s[6:7]
	s_xor_b64 s[6:7], exec, s[72:73]
	v_lshlrev_b64 v[12:13], 10, v[14:15]
	v_lshl_add_u64 v[12:13], s[14:15], 0, v[12:13]
	v_ashrrev_i32_e32 v11, 31, v10
	v_lshl_add_u64 v[12:13], v[10:11], 1, v[12:13]
	s_andn2_saveexec_b64 s[6:7], s[6:7]
	v_lshlrev_b64 v[12:13], 6, v[14:15]
	v_lshl_add_u64 v[12:13], s[16:17], 0, v[12:13]
	v_subrev_u32_e32 v0, 64, v10
	v_lshl_add_u64 v[12:13], v[0:1], 1, v[12:13]
	s_or_b64 exec, exec, s[6:7]
	global_load_dwordx4 v[100:103], v[12:13], off
.LBB0_540:
	s_or_b64 exec, exec, s[26:27]
	global_load_dwordx4 v[64:67], v[156:157], off offset:128
	v_or_b32_e32 v10, s8, v17
	v_add_u32_e32 v10, s66, v10
	v_cvt_f32_i32_e32 v20, v10
	v_cvt_f32_ubyte0_e32 v10, v154
	v_mul_f32_e32 v10, 0xbd800000, v10
	v_mul_f32_e32 v10, 0x41549a78, v10
	v_exp_f32_e32 v10, v10
	v_or_b32_e32 v11, 1, v154
	v_cvt_f32_ubyte0_e32 v11, v11
	v_mad_u32_u24 v0, v17, s51, v154
	v_mul_f32_e32 v11, 0xbd800000, v11
	v_lshl_add_u32 v169, v0, 1, 0
	v_mul_u32_u24_e32 v0, 0x88, v17
	v_mul_f32_e32 v11, 0x41549a78, v11
	v_add3_u32 v165, 0, v154, v0
	v_mul_f32_e32 v0, v10, v20
	v_exp_f32_e32 v11, v11
	v_mul_f32_e32 v10, 0.15915494, v0
	v_floor_f32_e32 v10, v10
	v_fma_f32 v0, v0, 0.15915494, -v10
	v_sin_f32_e32 v10, v0
	v_cos_f32_e32 v12, v0
	v_mul_f32_e32 v0, v11, v20
	v_mul_f32_e32 v11, 0.15915494, v0
	v_floor_f32_e32 v11, v11
	v_fma_f32 v0, v0, 0.15915494, -v11
	v_sin_f32_e32 v11, v0
	v_cos_f32_e32 v13, v0
	v_or_b32_e32 v0, 2, v154
	v_cvt_f32_ubyte0_e32 v0, v0
	v_mul_f32_e32 v0, 0xbd800000, v0
	v_mul_f32_e32 v0, 0x41549a78, v0
	v_lshlrev_b32_e32 v14, 16, v6
	v_and_b32_e32 v15, 0xffff0000, v6
	v_exp_f32_e32 v0, v0
	v_or_b32_e32 v6, 3, v154
	v_cvt_f32_ubyte0_e32 v6, v6
	v_mul_f32_e32 v6, 0xbd800000, v6
	v_mul_f32_e32 v6, 0x41549a78, v6
	v_mul_f32_e32 v0, v0, v20
	v_exp_f32_e32 v6, v6
	v_lshlrev_b32_e32 v16, 16, v2
	v_and_b32_e32 v17, 0xffff0000, v2
	v_mul_f32_e32 v2, 0.15915494, v0
	v_pk_mul_f32 v[18:19], v[10:11], v[16:17]
	v_pk_mul_f32 v[10:11], v[10:11], v[14:15]
	v_floor_f32_e32 v2, v2
	v_pk_fma_f32 v[10:11], v[12:13], v[16:17], v[10:11]
	v_fma_f32 v0, v0, 0.15915494, -v2
	v_pk_fma_f32 v[18:19], v[12:13], v[14:15], v[18:19] neg_lo:[0,0,1] neg_hi:[0,0,1]
	v_cvt_pk_bf16_f32 v124, v10, v11
	v_sin_f32_e32 v10, v0
	v_cos_f32_e32 v12, v0
	v_mul_f32_e32 v0, v6, v20
	v_mul_f32_e32 v2, 0.15915494, v0
	v_floor_f32_e32 v2, v2
	v_fma_f32 v0, v0, 0.15915494, -v2
	v_sin_f32_e32 v11, v0
	v_cos_f32_e32 v13, v0
	v_lshlrev_b32_e32 v2, 16, v3
	v_and_b32_e32 v3, 0xffff0000, v3
	v_or_b32_e32 v0, 4, v154
	v_lshlrev_b32_e32 v6, 16, v7
	v_and_b32_e32 v7, 0xffff0000, v7
	v_pk_mul_f32 v[14:15], v[10:11], v[2:3]
	v_cvt_f32_ubyte0_e32 v0, v0
	v_pk_fma_f32 v[14:15], v[12:13], v[6:7], v[14:15] neg_lo:[0,0,1] neg_hi:[0,0,1]
	v_mul_f32_e32 v0, 0xbd800000, v0
	v_pk_mul_f32 v[6:7], v[10:11], v[6:7]
	v_mul_f32_e32 v0, 0x41549a78, v0
	v_pk_fma_f32 v[2:3], v[12:13], v[2:3], v[6:7]
	v_exp_f32_e32 v0, v0
	v_cvt_pk_bf16_f32 v125, v2, v3
	v_or_b32_e32 v3, 5, v154
	v_cvt_f32_ubyte0_e32 v3, v3
	v_mul_f32_e32 v3, 0xbd800000, v3
	v_mul_f32_e32 v3, 0x41549a78, v3
	v_mul_f32_e32 v0, v0, v20
	v_exp_f32_e32 v3, v3
	v_mul_f32_e32 v2, 0.15915494, v0
	v_floor_f32_e32 v2, v2
	v_fma_f32 v0, v0, 0.15915494, -v2
	v_sin_f32_e32 v2, v0
	v_cos_f32_e32 v6, v0
	v_mul_f32_e32 v0, v3, v20
	v_mul_f32_e32 v3, 0.15915494, v0
	v_floor_f32_e32 v3, v3
	v_fma_f32 v0, v0, 0.15915494, -v3
	v_sin_f32_e32 v3, v0
	v_cos_f32_e32 v7, v0
	v_or_b32_e32 v0, 6, v154
	v_lshlrev_b32_e32 v10, 16, v8
	v_and_b32_e32 v11, 0xffff0000, v8
	v_lshlrev_b32_e32 v12, 16, v4
	v_and_b32_e32 v13, 0xffff0000, v4
	v_cvt_f32_ubyte0_e32 v0, v0
	v_cvt_pk_bf16_f32 v121, v14, v15
	v_pk_mul_f32 v[14:15], v[2:3], v[12:13]
	v_mul_f32_e32 v0, 0xbd800000, v0
	v_pk_mul_f32 v[2:3], v[2:3], v[10:11]
	v_mul_f32_e32 v0, 0x41549a78, v0
	v_pk_fma_f32 v[2:3], v[6:7], v[12:13], v[2:3]
	v_exp_f32_e32 v0, v0
	v_cvt_pk_bf16_f32 v126, v2, v3
	v_or_b32_e32 v3, 7, v154
	v_cvt_f32_ubyte0_e32 v3, v3
	v_mul_f32_e32 v3, 0xbd800000, v3
	v_mul_f32_e32 v3, 0x41549a78, v3
	v_mul_f32_e32 v0, v0, v20
	v_exp_f32_e32 v3, v3
	v_mul_f32_e32 v2, 0.15915494, v0
	v_floor_f32_e32 v2, v2
	v_fma_f32 v0, v0, 0.15915494, -v2
	v_pk_fma_f32 v[14:15], v[6:7], v[10:11], v[14:15] neg_lo:[0,0,1] neg_hi:[0,0,1]
	v_sin_f32_e32 v2, v0
	v_cos_f32_e32 v6, v0
	v_mul_f32_e32 v0, v3, v20
	v_mul_f32_e32 v3, 0.15915494, v0
	v_floor_f32_e32 v3, v3
	v_fma_f32 v0, v0, 0.15915494, -v3
	v_sin_f32_e32 v3, v0
	v_cos_f32_e32 v7, v0
	v_lshlrev_b32_e32 v8, 16, v9
	v_and_b32_e32 v9, 0xffff0000, v9
	v_lshlrev_b32_e32 v4, 16, v5
	v_and_b32_e32 v5, 0xffff0000, v5
	s_lshl_b32 s27, s64, 2
	s_ashr_i32 s26, s65, 7
	v_pk_mul_f32 v[10:11], v[2:3], v[4:5]
	v_pk_mul_f32 v[2:3], v[2:3], v[8:9]
	s_add_i32 s26, s26, s27
	v_pk_fma_f32 v[10:11], v[6:7], v[8:9], v[10:11] neg_lo:[0,0,1] neg_hi:[0,0,1]
	v_pk_fma_f32 v[2:3], v[6:7], v[4:5], v[2:3]
	v_cvt_pk_bf16_f32 v120, v18, v19
	v_cvt_pk_bf16_f32 v122, v14, v15
	v_cvt_pk_bf16_f32 v123, v10, v11
	s_cmp_lt_i32 s26, 0
	v_cvt_pk_bf16_f32 v127, v2, v3
	s_cbranch_scc1 .LBB0_542
	ds_read_b128 v[2:5], v169
	ds_read_b128 v[6:9], v169 offset:32
	ds_read_b128 v[10:13], v169 offset:6656
	ds_read_b128 v[48:51], v169 offset:6688
	ds_read_b128 v[52:55], v169 offset:64
	ds_read_b128 v[56:59], v169 offset:96
	ds_read_b128 v[60:63], v169 offset:6720
	ds_read_b128 v[68:71], v169 offset:6752
	ds_read_b128 v[72:75], v169 offset:128
	ds_read_b128 v[76:79], v169 offset:160
	ds_read_b128 v[80:83], v169 offset:6784
	ds_read_b128 v[128:131], v169 offset:6816
	s_waitcnt lgkmcnt(0)
	v_mfma_f32_32x32x16_bf16 v[32:47], v[2:5], v[116:119], 0
	v_mfma_f32_32x32x16_bf16 v[16:31], v[10:13], v[116:119], 0
	v_mfma_f32_32x32x16_bf16 v[32:47], v[6:9], v[112:115], v[32:47]
	v_mfma_f32_32x32x16_bf16 v[16:31], v[48:51], v[112:115], v[16:31]
	v_mfma_f32_32x32x16_bf16 v[32:47], v[52:55], v[108:111], v[32:47]
	v_mfma_f32_32x32x16_bf16 v[16:31], v[60:63], v[108:111], v[16:31]
	v_mfma_f32_32x32x16_bf16 v[32:47], v[56:59], v[104:107], v[32:47]
	v_mfma_f32_32x32x16_bf16 v[16:31], v[68:71], v[104:107], v[16:31]
	v_mfma_f32_32x32x16_bf16 v[32:47], v[72:75], v[120:123], v[32:47]
	v_mfma_f32_32x32x16_bf16 v[16:31], v[80:83], v[120:123], v[16:31]
	v_mfma_f32_32x32x16_bf16 v[32:47], v[76:79], v[124:127], v[32:47]
	v_mfma_f32_32x32x16_bf16 v[16:31], v[128:131], v[124:127], v[16:31]
	v_add_u32_e32 v0, 0x6800, v165
	ds_read2_b64 v[128:131], v0 offset1:2
	ds_read2_b64 v[80:83], v0 offset0:4 offset1:6
	ds_read2_b64 v[76:79], v0 offset0:8 offset1:10
	ds_read2_b64 v[72:75], v0 offset0:12 offset1:14
	v_add_u32_e32 v0, 0x7800, v165
	ds_read2_b64 v[60:63], v0 offset0:32 offset1:34
	ds_read2_b64 v[50:53], v0 offset0:36 offset1:38
	ds_read2_b64 v[56:59], v0 offset0:40 offset1:42
	ds_read2_b64 v[68:71], v0 offset0:44 offset1:46
	s_nop 1
	v_max_f32_e32 v2, v17, v17
	v_max_f32_e32 v3, v16, v16
	v_max_f32_e32 v2, v3, v2
	v_max3_f32 v0, v32, v33, v34
	v_max3_f32 v2, v2, v18, v19
	v_max3_f32 v0, v0, v35, v36
	v_max3_f32 v2, v2, v20, v21
	v_max3_f32 v0, v0, v37, v38
	v_max3_f32 v2, v2, v22, v23
	v_max3_f32 v0, v0, v39, v40
	v_max3_f32 v2, v2, v24, v25
	v_max3_f32 v0, v0, v41, v42
	v_max3_f32 v2, v2, v26, v27
	v_max3_f32 v0, v0, v43, v44
	v_max3_f32 v2, v2, v28, v29
	v_max3_f32 v0, v0, v45, v46
	v_max3_f32 v2, v2, v30, v31
	v_max3_f32 v0, v0, v47, v2
	v_mov_b32_e32 v2, v0
	s_nop 1
	v_permlane32_swap_b32_e32 v0, v2
	v_max_f32_e32 v2, v2, v2
	v_max_f32_e32 v0, v0, v0
	v_max_f32_e32 v48, v0, v2
	v_sub_f32_e32 v0, v32, v48
	v_sub_f32_e32 v16, v16, v48
	v_sub_f32_e32 v32, v33, v48
	v_sub_f32_e32 v17, v17, v48
	v_exp_f32_e32 v49, v0
	v_exp_f32_e32 v93, v16
	v_exp_f32_e32 v32, v32
	v_exp_f32_e32 v0, v17
	v_sub_f32_e32 v34, v34, v48
	v_add_f32_e32 v33, v49, v93
	v_sub_f32_e32 v54, v18, v48
	v_pk_add_f32 v[16:17], v[32:33], v[0:1]
	v_sub_f32_e32 v35, v35, v48
	v_sub_f32_e32 v55, v19, v48
	v_pk_add_f32 v[18:19], v[16:17], v[16:17] op_sel_hi:[0,1]
	v_exp_f32_e32 v33, v34
	v_exp_f32_e32 v94, v54
	v_exp_f32_e32 v34, v35
	v_exp_f32_e32 v18, v55
	v_sub_f32_e32 v36, v36, v48
	v_add_f32_e32 v35, v33, v94
	v_sub_f32_e32 v54, v20, v48
	v_pk_add_f32 v[16:17], v[34:35], v[18:19]
	v_sub_f32_e32 v37, v37, v48
	v_sub_f32_e32 v55, v21, v48
	v_pk_add_f32 v[20:21], v[16:17], v[16:17] op_sel_hi:[0,1]
	v_exp_f32_e32 v19, v36
	v_exp_f32_e32 v35, v54
	v_exp_f32_e32 v36, v37
	v_exp_f32_e32 v20, v55
	v_sub_f32_e32 v38, v38, v48
	v_add_f32_e32 v37, v19, v35
	v_sub_f32_e32 v54, v22, v48
	v_pk_add_f32 v[16:17], v[36:37], v[20:21]
	v_sub_f32_e32 v39, v39, v48
	v_sub_f32_e32 v55, v23, v48
	v_pk_add_f32 v[22:23], v[16:17], v[16:17] op_sel_hi:[0,1]
	v_exp_f32_e32 v21, v38
	v_exp_f32_e32 v37, v54
	v_exp_f32_e32 v38, v39
	v_exp_f32_e32 v22, v55
	v_sub_f32_e32 v40, v40, v48
	v_add_f32_e32 v39, v21, v37
	v_sub_f32_e32 v54, v24, v48
	v_pk_add_f32 v[16:17], v[38:39], v[22:23]
	v_sub_f32_e32 v41, v41, v48
	v_sub_f32_e32 v55, v25, v48
	v_pk_add_f32 v[24:25], v[16:17], v[16:17] op_sel_hi:[0,1]
	v_exp_f32_e32 v23, v40
	v_exp_f32_e32 v39, v54
	v_exp_f32_e32 v40, v41
	v_exp_f32_e32 v24, v55
	v_sub_f32_e32 v42, v42, v48
	v_add_f32_e32 v41, v23, v39
	v_sub_f32_e32 v54, v26, v48
	v_pk_add_f32 v[16:17], v[40:41], v[24:25]
	v_sub_f32_e32 v43, v43, v48
	v_sub_f32_e32 v55, v27, v48
	v_pk_add_f32 v[26:27], v[16:17], v[16:17] op_sel_hi:[0,1]
	v_exp_f32_e32 v25, v42
	v_exp_f32_e32 v41, v54
	v_exp_f32_e32 v42, v43
	v_exp_f32_e32 v26, v55
	v_sub_f32_e32 v44, v44, v48
	v_add_f32_e32 v43, v25, v41
	v_sub_f32_e32 v54, v28, v48
	v_pk_add_f32 v[16:17], v[42:43], v[26:27]
	v_sub_f32_e32 v45, v45, v48
	v_sub_f32_e32 v55, v29, v48
	v_pk_add_f32 v[28:29], v[16:17], v[16:17] op_sel_hi:[0,1]
	v_exp_f32_e32 v27, v44
	v_exp_f32_e32 v43, v54
	v_exp_f32_e32 v44, v45
	v_exp_f32_e32 v28, v55
	v_sub_f32_e32 v46, v46, v48
	v_add_f32_e32 v45, v27, v43
	v_sub_f32_e32 v54, v30, v48
	v_pk_add_f32 v[16:17], v[44:45], v[28:29]
	v_sub_f32_e32 v47, v47, v48
	v_sub_f32_e32 v55, v31, v48
	v_pk_add_f32 v[30:31], v[16:17], v[16:17] op_sel_hi:[0,1]
	v_exp_f32_e32 v29, v46
	v_exp_f32_e32 v45, v54
	v_exp_f32_e64 v2, -v48
	v_exp_f32_e32 v46, v47
	v_exp_f32_e32 v30, v55
	v_add_f32_e32 v47, v29, v45
	v_mul_f32_e32 v2, 0, v2
	v_mov_b32_e32 v16, v2
	v_pk_add_f32 v[54:55], v[46:47], v[30:31]
	v_mov_b32_e32 v17, v2
	v_pk_add_f32 v[54:55], v[54:55], v[54:55] op_sel_hi:[0,1]
	v_mov_b32_e32 v3, v2
	v_mov_b32_e32 v4, v2
	v_mov_b32_e32 v5, v2
	v_mov_b32_e32 v6, v2
	v_mov_b32_e32 v7, v2
	v_mov_b32_e32 v8, v2
	v_mov_b32_e32 v9, v2
	v_mov_b32_e32 v10, v2
	v_mov_b32_e32 v11, v2
	v_mov_b32_e32 v12, v2
	v_mov_b32_e32 v13, v2
	v_mov_b32_e32 v14, v2
	v_mov_b32_e32 v15, v2
	v_cvt_pk_bf16_f32 v132, v49, v32
	v_cvt_pk_bf16_f32 v133, v33, v34
	v_cvt_pk_bf16_f32 v134, v19, v36
	v_cvt_pk_bf16_f32 v135, v21, v38
	v_cvt_pk_bf16_f32 v136, v23, v40
	v_cvt_pk_bf16_f32 v137, v25, v42
	v_cvt_pk_bf16_f32 v138, v27, v44
	v_cvt_pk_bf16_f32 v139, v29, v46
	v_cvt_pk_bf16_f32 v140, v93, v0
	v_cvt_pk_bf16_f32 v141, v94, v18
	v_cvt_pk_bf16_f32 v142, v35, v20
	v_cvt_pk_bf16_f32 v143, v37, v22
	v_cvt_pk_bf16_f32 v144, v39, v24
	v_cvt_pk_bf16_f32 v145, v41, v26
	v_cvt_pk_bf16_f32 v146, v43, v28
	v_cvt_pk_bf16_f32 v147, v45, v30
	s_waitcnt lgkmcnt(0)
	v_mfma_f32_32x32x16_bf16 v[32:47], v[128:131], v[132:135], v[2:17]
	v_mov_b64_e32 v[30:31], v[16:17]
	v_mov_b64_e32 v[28:29], v[14:15]
	v_mov_b64_e32 v[26:27], v[12:13]
	v_mov_b64_e32 v[24:25], v[10:11]
	v_mov_b64_e32 v[22:23], v[8:9]
	v_mov_b64_e32 v[20:21], v[6:7]
	v_mov_b64_e32 v[18:19], v[4:5]
	v_mov_b64_e32 v[16:17], v[2:3]
	v_mfma_f32_32x32x16_bf16 v[32:47], v[80:83], v[136:139], v[32:47]
	v_mov_b32_e32 v49, v2
	v_mov_b32_e32 v54, v1
	v_add_f32_e64 v158, v48, v54
	v_add_f32_e64 v159, v49, v55
	v_xor_b32_e32 v48, 0x80000000, v158
	v_mov_b32_e32 v49, v48
	v_mov_b32_e32 v54, v48
	v_mfma_f32_32x32x16_bf16 v[16:31], v[60:63], v[132:135], v[16:31]
	v_mov_b32_e32 v55, v48
	v_mov_b32_e32 v60, v48
	v_mov_b32_e32 v61, v48
	v_mov_b32_e32 v62, v48
	v_mov_b32_e32 v63, v48
	v_mfma_f32_32x32x16_bf16 v[16:31], v[50:53], v[136:139], v[16:31]
	v_mov_b32_e32 v50, v48
	v_mov_b32_e32 v51, v48
	v_mov_b32_e32 v52, v48
	v_mov_b32_e32 v53, v48
	v_mfma_f32_32x32x16_bf16 v[32:47], v[76:79], v[140:143], v[32:47]
	v_mfma_f32_32x32x16_bf16 v[16:31], v[56:59], v[140:143], v[16:31]
	v_mov_b32_e32 v56, v48
	v_mov_b32_e32 v57, v48
	v_mov_b32_e32 v58, v48
	v_mov_b32_e32 v59, v48
	v_mfma_f32_32x32x16_bf16 v[32:47], v[72:75], v[144:147], v[32:47]
	v_mfma_f32_32x32x16_bf16 v[16:31], v[68:71], v[144:147], v[16:31]
	s_and_saveexec_b64 s[6:7], s[2:3]
	s_cbranch_execnz .LBB0_543
	s_branch .LBB0_544

; #define FL_GLOADK(j) do { \
;     _Pragma("unroll") for (int i_ = 0; i_ < KPT; ++i_) { const int ci = tid + 512 * i_; if (ci < NKC) { const int key = ci / KCH, ch = ci - key * KCH; \
;         kreg[i_] = *(const u32x4*)(K0 + (size_t)(64 * (j) + key) * kpitch + ch * 8); } } } while (0)
; #define FL_LSTOREK(buf) do { \
;     _Pragma("unroll") for (int i_ = 0; i_ < KPT; ++i_) { const int ci = tid + 512 * i_; if (ci < NKC) { const int key = ci / KCH, ch = ci - key * KCH; \
;         *(LAS u32x4*)(lds + (buf) * KB + (key * KP + ch * 8) * 2) = kreg[i_]; } } } while (0)
; #define FL_GLOADV(j) do { \
;     _Pragma("unroll") for (int i_ = 0; i_ < VPT; ++i_) { const int ci = tid + 512 * i_; const int d = ci >> 3, ch = ci & 7; kreg[i_] = *(const u32x4*)(VT + (size_t)d * vpitch + 64 * (j) + ch * 8); } } while (0)
; #define FL_LSTOREV(buf) do { \
;     _Pragma("unroll") for (int i_ = 0; i_ < VPT; ++i_) { const int ci = tid + 512 * i_; const int d = ci >> 3, ch = ci & 7; LAS u32x2* p_ = (LAS u32x2*)(lds + 2 * KB + (buf) * VB + (d * VP + ch * 8) * 2); \
;         p_[0] = (u32x2){kreg[i_].x, kreg[i_].y}; p_[1] = (u32x2){kreg[i_].z, kreg[i_].w}; } } while (0)
; template <int DQK, int DV, int MODE>
; __device__ __forceinline__ void flash_unit(LAS unsigned char* lds, const bf16* Qp, int qpitch, const bf16* K0, int kpitch, const bf16* K1, const bf16* VT, int vpitch,
;                                            bf16* Op, int opitch, int NT, int jbase, int qpos0) {
;     ...
;     for (int j = 0; j < NT; ++j) {
;         const int buf = j & 1;
;         if (j + 1 < NT) { if constexpr (MODE == 1) { FL_GLOADK(j + 1); FL_LSTOREK(buf ^ 1); FL_GLOADV(j + 1); FL_LSTOREV(buf ^ 1); } else { FL_GLOAD(j + 1); } }
;         if (MODE == 1 || j <= jmax) { FL_X(j); FL_Y(j); }
.LBB0_550:
	s_and_saveexec_b64 s[6:7], s[2:3]
	s_cbranch_execz .LBB0_552
	v_lshlrev_b64 v[2:3], v168, v[170:171]
	v_lshl_add_u64 v[2:3], v[166:167], 0, v[2:3]
	global_load_dwordx4 v[96:99], v[2:3], off
.LBB0_552:
	s_or_b64 exec, exec, s[6:7]
	s_and_saveexec_b64 s[6:7], s[4:5]
	s_cbranch_execz .LBB0_554
	v_lshlrev_b64 v[2:3], v164, v[172:173]
	v_lshl_add_u64 v[2:3], v[162:163], 0, v[2:3]
	global_load_dwordx4 v[100:103], v[2:3], off
.LBB0_554:
	s_or_b64 exec, exec, s[6:7]
	global_load_dwordx4 v[2:5], v[174:175], off
	s_add_i32 s7, s64, 3
	s_and_b32 s6, s7, 1
	s_cmp_gt_i32 s7, s26
	s_cbranch_scc1 .LBB0_558
	s_mul_i32 s7, s6, 0x3400
	v_add_u32_e32 v0, s7, v169
	ds_read_b128 v[6:9], v0
	ds_read_b128 v[10:13], v0 offset:32
	ds_read_b128 v[128:131], v0 offset:6656
	ds_read_b128 v[132:135], v0 offset:6688
	ds_read_b128 v[136:139], v0 offset:64
	ds_read_b128 v[140:143], v0 offset:96
	ds_read_b128 v[144:147], v0 offset:6720
	ds_read_b128 v[148:151], v0 offset:6752
	ds_read_b128 v[180:183], v0 offset:128
	ds_read_b128 v[184:187], v0 offset:160
	ds_read_b128 v[188:191], v0 offset:6784
	ds_read_b128 v[192:195], v0 offset:6816
	s_waitcnt lgkmcnt(0)
	v_mfma_f32_32x32x16_bf16 v[80:95], v[6:9], v[116:119], v[48:63]
	v_mfma_f32_32x32x16_bf16 v[64:79], v[128:131], v[116:119], v[48:63]
	v_mfma_f32_32x32x16_bf16 v[80:95], v[10:13], v[112:115], v[80:95]
	v_mfma_f32_32x32x16_bf16 v[64:79], v[132:135], v[112:115], v[64:79]
	v_mfma_f32_32x32x16_bf16 v[80:95], v[136:139], v[108:111], v[80:95]
	v_mfma_f32_32x32x16_bf16 v[64:79], v[144:147], v[108:111], v[64:79]
	v_mfma_f32_32x32x16_bf16 v[80:95], v[140:143], v[104:107], v[80:95]
	v_mfma_f32_32x32x16_bf16 v[64:79], v[148:151], v[104:107], v[64:79]
	v_mfma_f32_32x32x16_bf16 v[80:95], v[180:183], v[120:123], v[80:95]
	v_mfma_f32_32x32x16_bf16 v[64:79], v[188:191], v[120:123], v[64:79]
	v_mfma_f32_32x32x16_bf16 v[80:95], v[184:187], v[124:127], v[80:95]
	v_mfma_f32_32x32x16_bf16 v[64:79], v[192:195], v[124:127], v[64:79]
	s_mul_i32 s7, s6, 0x2200
	v_add_u32_e32 v0, s7, v165
	v_add_u32_e32 v6, 0x6800, v0
	v_add_u32_e32 v0, 0x7800, v0
	ds_read2_b64 v[148:151], v6 offset1:2
	ds_read2_b64 v[144:147], v6 offset0:4 offset1:6
	ds_read2_b64 v[140:143], v6 offset0:8 offset1:10
	ds_read2_b64 v[136:139], v6 offset0:12 offset1:14
	ds_read2_b64 v[132:135], v0 offset0:32 offset1:34
	ds_read2_b64 v[128:131], v0 offset0:36 offset1:38
	ds_read2_b64 v[10:13], v0 offset0:40 offset1:42
	ds_read2_b64 v[6:9], v0 offset0:44 offset1:46
	v_max_f32_e32 v15, v65, v65
	v_max_f32_e32 v161, v64, v64
	v_max_f32_e32 v15, v161, v15
	v_max3_f32 v0, v80, v81, v82
	v_max3_f32 v15, v15, v66, v67
	v_max3_f32 v0, v0, v83, v84
	v_max3_f32 v15, v15, v68, v69
	v_max3_f32 v0, v0, v85, v86
	v_max3_f32 v15, v15, v70, v71
	v_max3_f32 v0, v0, v87, v88
	v_max3_f32 v15, v15, v72, v73
	v_max3_f32 v0, v0, v89, v90
	v_max3_f32 v15, v15, v74, v75
	v_max3_f32 v0, v0, v91, v92
	v_max3_f32 v15, v15, v76, v77
	v_max3_f32 v0, v0, v93, v94
	v_max3_f32 v15, v15, v78, v79
	v_max3_f32 v0, v0, v95, v15
	v_mov_b32_e32 v15, v0
	s_nop 1
	v_permlane32_swap_b32_e32 v0, v15
	v_max_f32_e32 v15, v15, v15
	v_max_f32_e32 v0, v0, v0
	v_max_f32_e32 v0, v0, v15
	v_cmp_lt_f32_e32 vcc, s56, v0
	s_cbranch_vccz .LBB0_557
	s_nop 0
	v_cndmask_b32_e32 v0, 0, v0, vcc
	v_exp_f32_e64 v180, -v0
	v_add_f32_e32 v158, v158, v0
	v_xor_b32_e32 v48, 0x80000000, v158
	v_mov_b32_e32 v49, v48
	v_mov_b32_e32 v50, v48
	v_mov_b32_e32 v51, v48
	v_mov_b32_e32 v52, v48
	v_mov_b32_e32 v53, v48
	v_mov_b32_e32 v54, v48
	v_mov_b32_e32 v55, v48
	v_mov_b32_e32 v56, v48
	v_mov_b32_e32 v57, v48
	v_mov_b32_e32 v58, v48
	v_mov_b32_e32 v59, v48
	v_mov_b32_e32 v60, v48
	v_mov_b32_e32 v61, v48
	v_mov_b32_e32 v62, v48
	v_mov_b32_e32 v63, v48
	v_pk_add_f32 v[80:81], v[80:81], v[0:1] op_sel_hi:[1,0] neg_lo:[0,1] neg_hi:[0,1]
	v_pk_add_f32 v[64:65], v[64:65], v[0:1] op_sel_hi:[1,0] neg_lo:[0,1] neg_hi:[0,1]
	v_pk_add_f32 v[82:83], v[82:83], v[0:1] op_sel_hi:[1,0] neg_lo:[0,1] neg_hi:[0,1]
	v_pk_add_f32 v[66:67], v[66:67], v[0:1] op_sel_hi:[1,0] neg_lo:[0,1] neg_hi:[0,1]
	v_pk_add_f32 v[84:85], v[84:85], v[0:1] op_sel_hi:[1,0] neg_lo:[0,1] neg_hi:[0,1]
	v_pk_add_f32 v[68:69], v[68:69], v[0:1] op_sel_hi:[1,0] neg_lo:[0,1] neg_hi:[0,1]
	v_pk_add_f32 v[86:87], v[86:87], v[0:1] op_sel_hi:[1,0] neg_lo:[0,1] neg_hi:[0,1]
	v_pk_add_f32 v[70:71], v[70:71], v[0:1] op_sel_hi:[1,0] neg_lo:[0,1] neg_hi:[0,1]
	v_pk_add_f32 v[88:89], v[88:89], v[0:1] op_sel_hi:[1,0] neg_lo:[0,1] neg_hi:[0,1]
	v_pk_add_f32 v[72:73], v[72:73], v[0:1] op_sel_hi:[1,0] neg_lo:[0,1] neg_hi:[0,1]
	v_pk_add_f32 v[90:91], v[90:91], v[0:1] op_sel_hi:[1,0] neg_lo:[0,1] neg_hi:[0,1]
	v_pk_add_f32 v[74:75], v[74:75], v[0:1] op_sel_hi:[1,0] neg_lo:[0,1] neg_hi:[0,1]
	v_pk_add_f32 v[92:93], v[92:93], v[0:1] op_sel_hi:[1,0] neg_lo:[0,1] neg_hi:[0,1]
	v_pk_add_f32 v[76:77], v[76:77], v[0:1] op_sel_hi:[1,0] neg_lo:[0,1] neg_hi:[0,1]
	v_pk_add_f32 v[94:95], v[94:95], v[0:1] op_sel_hi:[1,0] neg_lo:[0,1] neg_hi:[0,1]
	v_pk_add_f32 v[78:79], v[78:79], v[0:1] op_sel_hi:[1,0] neg_lo:[0,1] neg_hi:[0,1]
	v_pk_mul_f32 v[46:47], v[46:47], v[180:181] op_sel_hi:[1,0]
	v_pk_mul_f32 v[44:45], v[44:45], v[180:181] op_sel_hi:[1,0]
	v_pk_mul_f32 v[42:43], v[42:43], v[180:181] op_sel_hi:[1,0]
	v_pk_mul_f32 v[40:41], v[40:41], v[180:181] op_sel_hi:[1,0]
	v_pk_mul_f32 v[38:39], v[38:39], v[180:181] op_sel_hi:[1,0]
	v_pk_mul_f32 v[36:37], v[36:37], v[180:181] op_sel_hi:[1,0]
	v_pk_mul_f32 v[34:35], v[34:35], v[180:181] op_sel_hi:[1,0]
	v_pk_mul_f32 v[32:33], v[32:33], v[180:181] op_sel_hi:[1,0]
	v_pk_mul_f32 v[30:31], v[30:31], v[180:181] op_sel_hi:[1,0]
	v_pk_mul_f32 v[28:29], v[28:29], v[180:181] op_sel_hi:[1,0]
	v_pk_mul_f32 v[26:27], v[26:27], v[180:181] op_sel_hi:[1,0]
	v_pk_mul_f32 v[24:25], v[24:25], v[180:181] op_sel_hi:[1,0]
	v_pk_mul_f32 v[22:23], v[22:23], v[180:181] op_sel_hi:[1,0]
	v_pk_mul_f32 v[20:21], v[20:21], v[180:181] op_sel_hi:[1,0]
	v_pk_mul_f32 v[18:19], v[18:19], v[180:181] op_sel_hi:[1,0]
	v_pk_mul_f32 v[16:17], v[16:17], v[180:181] op_sel_hi:[1,0]
	v_mul_f32_e32 v159, v159, v180

; #define FL_GLOADK(j) do { \
;     _Pragma("unroll") for (int i_ = 0; i_ < KPT; ++i_) { const int ci = tid + 512 * i_; if (ci < NKC) { const int key = ci / KCH, ch = ci - key * KCH; \
;         kreg[i_] = *(const u32x4*)(K0 + (size_t)(64 * (j) + key) * kpitch + ch * 8); } } } while (0)
; #define FL_LSTOREK(buf) do { \
;     _Pragma("unroll") for (int i_ = 0; i_ < KPT; ++i_) { const int ci = tid + 512 * i_; if (ci < NKC) { const int key = ci / KCH, ch = ci - key * KCH; \
;         *(LAS u32x4*)(lds + (buf) * KB + (key * KP + ch * 8) * 2) = kreg[i_]; } } } while (0)
; #define FL_GLOADV(j) do { \
;     _Pragma("unroll") for (int i_ = 0; i_ < VPT; ++i_) { const int ci = tid + 512 * i_; const int d = ci >> 3, ch = ci & 7; kreg[i_] = *(const u32x4*)(VT + (size_t)d * vpitch + 64 * (j) + ch * 8); } } while (0)
; #define FL_LSTOREV(buf) do { \
;     _Pragma("unroll") for (int i_ = 0; i_ < VPT; ++i_) { const int ci = tid + 512 * i_; const int d = ci >> 3, ch = ci & 7; LAS u32x2* p_ = (LAS u32x2*)(lds + 2 * KB + (buf) * VB + (d * VP + ch * 8) * 2); \
;         p_[0] = (u32x2){kreg[i_].x, kreg[i_].y}; p_[1] = (u32x2){kreg[i_].z, kreg[i_].w}; } } while (0)
; template <int DQK, int DV, int MODE>
; __device__ __forceinline__ void flash_unit(LAS unsigned char* lds, const bf16* Qp, int qpitch, const bf16* K0, int kpitch, const bf16* K1, const bf16* VT, int vpitch,
;                                            bf16* Op, int opitch, int NT, int jbase, int qpos0) {
;     ...
;         if (j + 1 < NT) { if constexpr (MODE == 1) { FL_GLOADK(j + 1); FL_LSTOREK(buf ^ 1); FL_GLOADV(j + 1); FL_LSTOREV(buf ^ 1); } else { FL_GLOAD(j + 1); } }
.LBB0_562:
	s_cbranch_execnz .LBB0_568
	s_add_i32 s6, s27, 4
	s_lshl_b32 s8, s6, 6
	s_and_saveexec_b64 s[6:7], s[2:3]
	s_cbranch_execz .LBB0_565
	v_add_u32_e32 v2, s8, v160
	v_ashrrev_i32_e32 v3, 31, v2
	v_lshlrev_b64 v[2:3], v168, v[2:3]
	v_lshl_add_u64 v[2:3], v[166:167], 0, v[2:3]
	global_load_dwordx4 v[96:99], v[2:3], off
.LBB0_565:
	s_or_b64 exec, exec, s[6:7]
	s_and_saveexec_b64 s[6:7], s[4:5]
	s_cbranch_execz .LBB0_567
	v_add_u32_e32 v2, s8, v14
	v_ashrrev_i32_e32 v3, 31, v2
	v_lshlrev_b64 v[2:3], v164, v[2:3]
	v_lshl_add_u64 v[2:3], v[162:163], 0, v[2:3]
	global_load_dwordx4 v[100:103], v[2:3], off
.LBB0_567:
	s_or_b64 exec, exec, s[6:7]
	s_lshl_b32 s8, s8, 1
	v_lshl_add_u64 v[2:3], v[156:157], 0, s[8:9]
	global_load_dwordx4 v[2:5], v[2:3], off

; #define LAS __attribute__((address_space(3)))
; __device__ __forceinline__ float bf2f(unsigned b) { return __uint_as_float(b << 16); }
; __device__ __forceinline__ float ex2f(float x) { return __builtin_amdgcn_exp2f(x); }
; #define INP(i) ((const float*)tab_get(lds, (i)))
; #define OUTP() ((float*)tab_get(lds, 30))
; #define WSB(off) ((bf16*)((unsigned char*)tab_get(lds, 31) + (off)))
; #define LGS(a) float a[4]; _Pragma("unroll") for (int i_ = 0; i_ < 4; ++i_) a[i_] = log2f(1.0f - exp2f(-5.0f - (float)i_))
; __device__ __forceinline__ void ret_sample_item(LAS unsigned char* lds, const bf16* Z, const float* S0, const float* gn, float* out, bf16* MIXED, int b, int hh, float lg) {
;     LAS float* qT = (LAS float*)lds;
;     LAS float* kT = qT + 2048;
;     LAS float* vS = kT + 2048;
;     LAS float* inn = vS + 2048;
;     LAS float* QSp = inn + 256;
;     LAS float* oS = QSp + 8192;
;     const int tid_ = my_tid(lds); const int tid = tid_, lane = tid & 63; const int wid = __builtin_amdgcn_readfirstlane(tid >> 6);
;     const int rowbase = MP + b * 16;
; #pragma unroll
;     for (int i = 0; i < 4; ++i) { const int idx = tid + 512 * i, l = idx >> 7, d = idx & 127; const bf16* zr = Z + (size_t)(rowbase + l) * NZ + hh * 128 + d;
;         qT[d * 16 + l] = bf2f(zr[ZC_RQ]); kT[d * 16 + l] = bf2f(zr[ZC_RK]); vS[l * 128 + d] = bf2f(zr[ZC_RV]); }
;     __syncthreads();
;     if (tid < 256) { const int l = tid >> 4, m = tid & 15; float s = 0.f;
;         if (m <= l) { for (int d = 0; d < 128; ++d) s += qT[d * 16 + l] * kT[d * 16 + m]; s *= ex2f((float)(l - m) * lg); }
;         inn[l * 16 + m] = s; }
; __global__ void __launch_bounds__(512, 2) mega_fwd(Params p) {
;     ...
;         for (;;) { int it; QNEXT(5, it); if (it >= 32 + 512 + 128) break;
;             if (it < 32) mla_sample_unit(lds, WS_Q, WS_OLAT, WS_MIXED, it);
;             else if (it < 32 + 512) { LGS(lgs); const int i2 = it - 32; ret_out_item(lds, WSB(WS_Z), WSB(WS_AT), INP(16), WSB(WS_MIXED), i2 >> 8, i2 & 255, lgs); }
;             else { LGS(lgs); const int i3 = it - 32 - 512, hh = i3 & 3; ret_sample_item(lds, WSB(WS_Z), INP(4), INP(16), OUTP(), WSB(WS_MIXED), i3 >> 2, hh, lgs[hh]); } }
.LBB0_624:
	s_barrier
	s_getreg_b32 s2, hwreg(HW_REG_HW_ID, 0, 6)
	s_lshl_b32 s2, s2, 2
	s_and_b32 s2, s2, 0xfc
	s_add_i32 s2, s2, 0
	s_add_i32 s2, s2, 0x25a00
	v_mov_b32_e32 v1, s2
	ds_read_b32 v1, v1
	s_waitcnt lgkmcnt(0)
	v_readfirstlane_b32 s2, v1
	v_mbcnt_lo_u32_b32 v1, -1, 0
	v_mbcnt_hi_u32_b32 v1, -1, v1
	s_lshl_b32 s2, s2, 6
	v_sub_u32_e32 v1, 0, v1
	v_cmp_eq_u32_e32 vcc, s2, v1
	s_and_saveexec_b64 s[2:3], vcc
	s_cbranch_execz .LBB0_626
	v_mov_b32_e32 v1, s45
	ds_read_b64 v[2:3], v1
	s_waitcnt lgkmcnt(0)
	v_readfirstlane_b32 s5, v2
	v_readfirstlane_b32 s4, v3
	s_nop 0
	v_mov_b32_e32 v1, s5
	v_add_co_u32_e32 v2, vcc, 0x8000, v1
	v_mov_b32_e32 v3, s4
	s_nop 0
	v_addc_co_u32_e32 v3, vcc, 0, v3, vcc
	global_atomic_add v1, v[2:3], v153, off offset:1280 sc0
	s_waitcnt vmcnt(0) lgkmcnt(0)
	ds_write_b32 v157, v1
.LBB0_626:
	s_or_b64 exec, exec, s[2:3]
	s_waitcnt lgkmcnt(0)
	s_barrier
	ds_read_b32 v1, v157
	s_mov_b64 s[2:3], -1
	s_waitcnt lgkmcnt(0)
	v_readfirstlane_b32 s57, v1
	s_cmpk_gt_i32 s57, 0x29f
	s_cbranch_scc1 .LBB0_623
	s_cmp_gt_i32 s57, 31
	s_cbranch_scc0 .LBB0_683
	s_cmpk_lt_u32 s57, 0x220
	s_cbranch_scc1 .LBB0_678
	v_mov_b32_e32 v1, s45
	ds_read_b64 v[2:3], v1
	s_add_i32 s2, s57, 0xfffffde0
	s_and_b32 s19, s57, 3
	v_readlane_b32 s3, v254, 9
	v_mov_b32_e32 v13, v0
	s_waitcnt lgkmcnt(0)
	v_readfirstlane_b32 s4, v2
	v_mov_b32_e32 v4, s3
	v_readfirstlane_b32 s3, v3
	s_add_u32 s13, s4, 0x6800000
	s_addc_u32 s12, s3, 0
	v_readlane_b32 s3, v254, 10
	s_lshr_b32 s20, s2, 2
	s_cmp_eq_u32 s19, 1
	v_mov_b32_e32 v2, s3
	ds_read_b64 v[4:5], v4
	ds_read_b64 v[6:7], v2
	v_mov_b32_e32 v2, s73
	s_cselect_b64 vcc, -1, 0
	s_cmp_lg_u32 s19, 2
	ds_read_b64 v[8:9], v2
	ds_read_b64 v[10:11], v1
	v_cndmask_b32_e32 v1, v161, v162, vcc
	s_cselect_b64 vcc, -1, 0
	s_cmp_lg_u32 s19, 3
	s_getreg_b32 s2, hwreg(HW_REG_HW_ID, 0, 6)
	v_cndmask_b32_e32 v2, v163, v1, vcc
	s_cselect_b64 vcc, -1, 0
	s_lshl_b32 s2, s2, 2
	s_and_b32 s2, s2, 0xfc
	s_add_i32 s2, s2, 0
	s_add_i32 s2, s2, 0x25a00
	v_mov_b32_e32 v1, s2
	ds_read_b32 v1, v1
	s_lshl_b32 s14, s20, 4
	s_add_i32 s14, s14, 0x8000
	s_waitcnt lgkmcnt(0)
	v_readfirstlane_b32 s5, v7
	v_readfirstlane_b32 s4, v6
	v_readfirstlane_b32 s2, v1
	v_mbcnt_lo_u32_b32 v1, -1, 0
	v_mbcnt_hi_u32_b32 v1, -1, v1
	v_readfirstlane_b32 s7, v9
	v_readfirstlane_b32 s6, v8
	v_lshl_add_u32 v3, s2, 6, v1
	s_lshl_b32 s2, s19, 8
	v_and_b32_e32 v51, 0x7f, v3
	s_add_u32 s2, s13, s2
	v_add_u32_e32 v16, 0x200, v3
	v_add_u32_e32 v18, 0x400, v3
	v_add_u32_e32 v26, 0x600, v3
	s_addc_u32 s3, s12, 0
	v_lshlrev_b32_e32 v12, 1, v51
	v_ashrrev_i32_e32 v50, 7, v3
	v_ashrrev_i32_e32 v20, 7, v16
	v_ashrrev_i32_e32 v21, 7, v18
	v_ashrrev_i32_e32 v26, 7, v26
	v_lshl_add_u64 v[12:13], s[2:3], 0, v[12:13]
	v_add_u32_e32 v14, s14, v50
	v_add_u32_e32 v16, s14, v20
	v_add_u32_e32 v18, s14, v21
	v_add_u32_e32 v27, s14, v26
	v_mad_i64_i32 v[14:15], s[2:3], v14, s74, v[12:13]
	v_mad_i64_i32 v[16:17], s[2:3], v16, s74, v[12:13]
	v_mad_i64_i32 v[18:19], s[2:3], v18, s74, v[12:13]
	v_mad_i64_i32 v[12:13], s[2:3], v27, s74, v[12:13]
	global_load_ushort v22, v[14:15], off offset:832
	global_load_ushort v23, v[14:15], off offset:1856
	s_nop 0
	global_load_ushort v14, v[14:15], off offset:2880
	s_nop 0
	global_load_ushort v15, v[16:17], off offset:832
	global_load_ushort v24, v[16:17], off offset:1856
	s_nop 0
	global_load_ushort v16, v[16:17], off offset:2880
	s_nop 0
	global_load_ushort v17, v[18:19], off offset:832
	global_load_ushort v25, v[18:19], off offset:1856
	s_nop 0
	global_load_ushort v18, v[18:19], off offset:2880
	s_nop 0
	global_load_ushort v19, v[12:13], off offset:832
	global_load_ushort v27, v[12:13], off offset:1856
	s_nop 0
	global_load_ushort v12, v[12:13], off offset:2880
	v_readfirstlane_b32 s2, v4
	v_lshlrev_b32_e32 v4, 4, v51
	v_readfirstlane_b32 s3, v5
	v_add_u32_e32 v5, v4, v50
	v_add_u32_e32 v6, v20, v4
	v_add_u32_e32 v7, v21, v4
	v_add_u32_e32 v4, v26, v4
	v_lshl_add_u32 v5, v5, 2, 0
	v_lshl_add_u32 v4, v4, 2, 0
	s_movk_i32 s8, 0x100
	v_readfirstlane_b32 s15, v11
	v_readfirstlane_b32 s16, v10
	v_cndmask_b32_e32 v52, v164, v2, vcc
	v_lshl_add_u32 v2, v3, 2, 0
	v_lshl_add_u32 v6, v6, 2, 0
	v_lshl_add_u32 v7, v7, 2, 0
	v_readfirstlane_b32 s17, v3
	v_cmp_gt_i32_e32 vcc, s8, v3
	s_waitcnt vmcnt(0) lgkmcnt(0)
	v_lshlrev_b32_e32 v8, 16, v22
	v_lshlrev_b32_e32 v9, 16, v23
	v_lshlrev_b32_e32 v10, 16, v14
	v_lshlrev_b32_e32 v11, 16, v15
	v_lshlrev_b32_e32 v13, 16, v24
	v_lshlrev_b32_e32 v14, 16, v16
	v_lshlrev_b32_e32 v15, 16, v17
	v_lshlrev_b32_e32 v16, 16, v25
	v_lshlrev_b32_e32 v17, 16, v18
	v_lshlrev_b32_e32 v18, 16, v19
	v_lshlrev_b32_e32 v19, 16, v27
	ds_write2st64_b32 v5, v8, v9 offset1:32
	ds_write_b32 v2, v10 offset:16384
	ds_write2st64_b32 v6, v11, v13 offset1:32
	ds_write_b32 v2, v14 offset:18432
	ds_write2st64_b32 v7, v15, v16 offset1:32
	ds_write_b32 v2, v17 offset:20480
	ds_write2st64_b32 v4, v18, v19 offset1:32
	v_lshlrev_b32_e32 v4, 16, v12
	ds_write_b32 v2, v4 offset:22528
	s_waitcnt lgkmcnt(0)
	s_barrier
	s_and_saveexec_b64 s[8:9], vcc
	s_cbranch_execz .LBB0_635
	v_ashrrev_i32_e32 v3, 4, v3
	v_and_b32_e32 v4, 15, v1
	v_cmp_ge_i32_e32 vcc, v3, v4
	v_mov_b32_e32 v5, 0
	s_and_saveexec_b64 s[10:11], vcc
	s_cbranch_execz .LBB0_634
	v_readlane_b32 s18, v254, 11
	v_lshl_add_u32 v6, v3, 2, 0
	v_mov_b32_e32 v5, 0
	v_lshl_add_u32 v7, v4, 2, s18
	s_mov_b32 s18, 0

; #define LAS __attribute__((address_space(3)))
; __device__ __forceinline__ float ex2f(float x) { return __builtin_amdgcn_exp2f(x); }
; __device__ __forceinline__ void ret_sample_item(LAS unsigned char* lds, const bf16* Z, const float* S0, const float* gn, float* out, bf16* MIXED, int b, int hh, float lg) {
;     ...
;     { const int e = tid & 127, dg = tid >> 7; float vr[16], qs[16], gk[16];
; #pragma unroll
;       for (int l = 0; l < 16; ++l) { vr[l] = vS[l * 128 + e]; qs[l] = 0.f; gk[l] = ex2f((float)(15 - l) * lg); }
;       const float g16 = ex2f(16.f * lg); const size_t sb = (size_t)((b * 4 + hh) * 128) * 128;
;       for (int dd = 0; dd < 32; ++dd) { const int d = dg * 32 + dd; const float s0 = S0[sb + (size_t)d * 128 + e]; float kv = 0.f;
; #pragma unroll
;           for (int l4 = 0; l4 < 4; ++l4) { const f32x4 k4 = *(const LAS f32x4*)(kT + d * 16 + 4 * l4), q4 = *(const LAS f32x4*)(qT + d * 16 + 4 * l4);
; #pragma unroll
;               for (int j = 0; j < 4; ++j) { kv += k4[j] * gk[4 * l4 + j] * vr[4 * l4 + j]; qs[4 * l4 + j] += q4[j] * s0; } }
;           out[O_SRET + sb + (size_t)d * 128 + e] = g16 * s0 + kv; }
; #pragma unroll
;       for (int l = 0; l < 16; ++l) QSp[(dg * 16 + l) * 128 + e] = qs[l]; }
.LBB0_636:
	v_lshl_add_u64 v[92:93], v[32:33], 0, s[2:3]
	global_load_dword v94, v[92:93], off
	ds_read_b128 v[60:63], v59
	ds_read_b128 v[64:67], v59 offset:16
	ds_read_b128 v[68:71], v59 offset:32
	ds_read_b128 v[72:75], v59 offset:48
	ds_read_b128 v[76:79], v59 offset:8192
	ds_read_b128 v[80:83], v59 offset:8208
	ds_read_b128 v[84:87], v59 offset:8224
	ds_read_b128 v[88:91], v59 offset:8240
	v_lshl_add_u64 v[96:97], v[30:31], 0, s[2:3]
	s_waitcnt lgkmcnt(0)
	v_mul_f32_e32 v95, v54, v76
	v_mul_f32_e32 v98, v55, v77
	v_mul_f32_e32 v100, v57, v79
	v_mov_b32_e32 v79, v86
	v_mov_b32_e32 v86, v88
	v_fma_f32 v88, v2, v95, 0
	v_mul_f32_e32 v99, v56, v78
	v_fmac_f32_e32 v88, v3, v98
	v_mov_b32_e32 v76, v81
	v_mov_b32_e32 v77, v82
	v_fmac_f32_e32 v88, v4, v99
	v_mul_f32_e32 v101, v58, v80
	v_pk_mul_f32 v[76:77], v[8:9], v[76:77]
	v_fmac_f32_e32 v88, v5, v100
	v_mov_b32_e32 v82, v84
	v_pk_mul_f32 v[76:77], v[28:29], v[76:77]
	v_fmac_f32_e32 v88, v6, v101
	v_pk_mul_f32 v[82:83], v[10:11], v[82:83]
	v_add_f32_e32 v76, v76, v88
	v_mov_b32_e32 v78, v85
	v_pk_mul_f32 v[82:83], v[12:13], v[82:83]
	v_add_f32_e32 v76, v77, v76
	v_pk_mul_f32 v[78:79], v[14:15], v[78:79]
	v_add_f32_e32 v76, v83, v76
	v_pk_mul_f32 v[78:79], v[26:27], v[78:79]
	v_add_f32_e32 v76, v82, v76
	v_pk_mul_f32 v[84:85], v[16:17], v[86:87]
	v_add_f32_e32 v76, v78, v76
	v_mov_b32_e32 v80, v89
	v_mov_b32_e32 v81, v90
	v_pk_mul_f32 v[84:85], v[18:19], v[84:85]
	v_add_f32_e32 v76, v79, v76
	v_pk_mul_f32 v[80:81], v[20:21], v[80:81]
	v_add_f32_e32 v76, v85, v76
	v_pk_mul_f32 v[80:81], v[24:25], v[80:81]
	v_add_f32_e32 v76, v84, v76
	v_add_f32_e32 v76, v80, v76
	v_add_f32_e32 v76, v81, v76
	s_mov_b32 s6, 0x9ae6000
	v_add_co_u32_e32 v96, vcc, s6, v96
	s_add_u32 s2, s2, 0x400
	s_nop 0
	v_addc_co_u32_e32 v97, vcc, 0, v97, vcc
	s_addc_u32 s3, s3, 0
	s_cmpk_eq_i32 s2, 0x4000
	s_waitcnt vmcnt(0)
	v_pk_fma_f32 v[80:81], v[94:95], v[60:61], v[36:37] op_sel_hi:[0,1,1]
	v_pk_fma_f32 v[82:83], v[94:95], v[62:63], v[38:39] op_sel_hi:[0,1,1]
	v_pk_fma_f32 v[84:85], v[94:95], v[64:65], v[40:41] op_sel_hi:[0,1,1]
	v_pk_fma_f32 v[86:87], v[94:95], v[66:67], v[42:43] op_sel_hi:[0,1,1]
	v_pk_fma_f32 v[88:89], v[94:95], v[68:69], v[44:45] op_sel_hi:[0,1,1]
	v_pk_fma_f32 v[98:99], v[94:95], v[70:71], v[46:47] op_sel_hi:[0,1,1]
	v_pk_fma_f32 v[48:49], v[94:95], v[72:73], v[48:49] op_sel_hi:[0,1,1]
	v_pk_fma_f32 v[34:35], v[94:95], v[74:75], v[34:35] op_sel_hi:[0,1,1]
	v_mov_b32_e32 v95, v91
	v_pk_mul_f32 v[36:37], v[22:23], v[94:95]
	s_nop 0
	v_add_f32_e32 v37, v37, v76
	v_add_f32_e32 v36, v36, v37
	global_store_dword v[96:97], v36, off
	global_load_dword v90, v[92:93], off offset:512
	ds_read_b128 v[36:39], v59 offset:64
	ds_read_b128 v[40:43], v59 offset:80
	ds_read_b128 v[44:47], v59 offset:96
	ds_read_b128 v[60:63], v59 offset:112
	ds_read_b128 v[64:67], v59 offset:8256
	ds_read_b128 v[68:71], v59 offset:8272
	ds_read_b128 v[72:75], v59 offset:8288
	ds_read_b128 v[76:79], v59 offset:8304
	v_add_u32_e32 v59, 0x80, v59
	s_waitcnt lgkmcnt(0)
	v_mul_f32_e32 v91, v54, v64
	v_mul_f32_e32 v92, v55, v65
	v_mul_f32_e32 v94, v57, v67
	v_mov_b32_e32 v67, v74
	v_mov_b32_e32 v74, v76
	v_fma_f32 v76, v2, v91, 0
	v_mul_f32_e32 v93, v56, v66
	v_fmac_f32_e32 v76, v3, v92
	v_mov_b32_e32 v64, v69
	v_mov_b32_e32 v65, v70
	v_fmac_f32_e32 v76, v4, v93
	v_mul_f32_e32 v95, v58, v68
	v_pk_mul_f32 v[64:65], v[8:9], v[64:65]
	v_fmac_f32_e32 v76, v5, v94
	v_mov_b32_e32 v70, v72
	v_pk_mul_f32 v[64:65], v[28:29], v[64:65]
	v_fmac_f32_e32 v76, v6, v95
	v_pk_mul_f32 v[70:71], v[10:11], v[70:71]
	v_add_f32_e32 v64, v64, v76
	v_mov_b32_e32 v66, v73
	v_pk_mul_f32 v[70:71], v[12:13], v[70:71]
	v_add_f32_e32 v64, v65, v64
	v_pk_mul_f32 v[66:67], v[14:15], v[66:67]
	v_add_f32_e32 v64, v71, v64
	v_pk_mul_f32 v[66:67], v[26:27], v[66:67]
	v_add_f32_e32 v64, v70, v64
	v_pk_mul_f32 v[72:73], v[16:17], v[74:75]
	v_add_f32_e32 v64, v66, v64
	v_mov_b32_e32 v68, v77
	v_mov_b32_e32 v69, v78
	v_pk_mul_f32 v[72:73], v[18:19], v[72:73]
	v_add_f32_e32 v64, v67, v64
	v_pk_mul_f32 v[68:69], v[20:21], v[68:69]
	v_add_f32_e32 v64, v73, v64
	v_pk_mul_f32 v[68:69], v[24:25], v[68:69]
	v_add_f32_e32 v64, v72, v64
	v_add_f32_e32 v64, v68, v64
	v_add_f32_e32 v64, v69, v64
	s_waitcnt vmcnt(0)
	v_pk_fma_f32 v[36:37], v[90:91], v[36:37], v[80:81] op_sel_hi:[0,1,1]
	v_pk_fma_f32 v[38:39], v[90:91], v[38:39], v[82:83] op_sel_hi:[0,1,1]
	v_pk_fma_f32 v[40:41], v[90:91], v[40:41], v[84:85] op_sel_hi:[0,1,1]
	v_pk_fma_f32 v[42:43], v[90:91], v[42:43], v[86:87] op_sel_hi:[0,1,1]
	v_pk_fma_f32 v[44:45], v[90:91], v[44:45], v[88:89] op_sel_hi:[0,1,1]
	v_pk_fma_f32 v[46:47], v[90:91], v[46:47], v[98:99] op_sel_hi:[0,1,1]
	v_pk_fma_f32 v[48:49], v[90:91], v[60:61], v[48:49] op_sel_hi:[0,1,1]
	v_pk_fma_f32 v[34:35], v[90:91], v[62:63], v[34:35] op_sel_hi:[0,1,1]
	v_mov_b32_e32 v91, v79
	v_pk_mul_f32 v[60:61], v[22:23], v[90:91]
	s_nop 0
	v_add_f32_e32 v61, v61, v64
	v_add_f32_e32 v60, v60, v61
	global_store_dword v[96:97], v60, off offset:512
	s_cbranch_scc0 .LBB0_636
	v_lshlrev_b32_e32 v2, 13, v50
	v_add3_u32 v2, 0, v2, v53
	ds_write2st64_b32 v2, v36, v37 offset0:100 offset1:102
	ds_write2st64_b32 v2, v38, v39 offset0:104 offset1:106
	ds_write2st64_b32 v2, v40, v41 offset0:108 offset1:110
	ds_write2st64_b32 v2, v42, v43 offset0:112 offset1:114
	ds_write2st64_b32 v2, v44, v45 offset0:116 offset1:118
	ds_write2st64_b32 v2, v46, v47 offset0:120 offset1:122
	ds_write2st64_b32 v2, v48, v49 offset0:124 offset1:126
	ds_write2st64_b32 v2, v34, v35 offset0:128 offset1:130
	v_lshlrev_b32_e32 v2, 2, v50
	v_add_u32_e32 v5, v7, v53
	s_waitcnt lgkmcnt(0)
	s_barrier
	v_or_b32_e32 v4, 1, v2
	ds_read2st64_b32 v[6:7], v5 offset0:132 offset1:164
	v_cvt_f32_i32_e32 v10, v4
	v_lshl_or_b32 v3, v50, 11, v53
	v_add_u32_e32 v3, 0, v3
	ds_read_b32 v5, v5 offset:50176
	ds_read_b32 v8, v3 offset:25600
	s_waitcnt lgkmcnt(0)
	v_mov_b32_e32 v9, v7
	v_mul_f32_e32 v7, v52, v10
	v_exp_f32_e32 v10, v7
	v_mov_b32_e32 v7, v5
	v_pk_add_f32 v[6:7], v[8:9], v[6:7]
	v_cmp_lt_i32_e32 vcc, -1, v50
	v_add_f32_e32 v5, v6, v7
	v_mul_f32_e32 v5, v10, v5
	s_and_saveexec_b64 s[6:7], vcc
	s_cbranch_execz .LBB0_647
	v_lshlrev_b32_e32 v6, 8, v50
	v_cmp_lt_u32_e64 s[2:3], 6, v2
	s_and_saveexec_b64 s[8:9], s[2:3]
	s_xor_b64 s[8:9], exec, s[8:9]
	s_cbranch_execz .LBB0_642
	v_readlane_b32 s2, v254, 12
	v_lshlrev_b32_e32 v8, 2, v51
	v_and_b32_e32 v7, 0x7ffffff8, v2
	v_add_u32_e32 v9, s2, v6
	s_add_i32 s2, 0, 0x4000
	v_add_u32_e32 v10, s2, v8
	s_mov_b32 s19, 0
	s_mov_b64 s[10:11], 0

; __device__ __forceinline__ float bf2f(unsigned b) { return __uint_as_float(b << 16); }
; __device__ __forceinline__ bf16 f2bf(float f) { return (bf16)(pk2(f, 0.f) & 0xffffu); }
; __device__ __forceinline__ float wave_sum(float v) { v += swz_xor<1>(v); v += swz_xor<2>(v); v += swz_xor<4>(v); v += swz_xor<8>(v); v += swz_xor<16>(v); return half_sum(v); }
; __device__ __forceinline__ float silu(float x) { return x * __builtin_amdgcn_rcpf(1.f + __builtin_amdgcn_exp2f(-1.4426950408889634f * x)); }
; __device__ __forceinline__ void ret_sample_item(LAS unsigned char* lds, const bf16* Z, const float* S0, const float* gn, float* out, bf16* MIXED, int b, int hh, float lg) {
;     ...
; #pragma unroll
;     for (int li = 0; li < 2; ++li) { const int l = 2 * wid + li, row = rowbase + l; const float x0 = oS[l * 128 + lane], x1 = oS[l * 128 + 64 + lane];
;         const float mean = wave_sum(x0 + x1) * (1.f / 128.f); const float d0 = x0 - mean, d1 = x1 - mean; const float rstd = rsqrtf(wave_sum(d0 * d0 + d1 * d1) * (1.f / 128.f) + EPS);
;         const bf16* zg = Z + (size_t)row * NZ + ZC_RG + hh * 128; bf16* mo = MIXED + (size_t)row * 1024 + 512 + hh * 128;
;         mo[lane] = f2bf(d0 * rstd * gn[hh * 128 + lane] * silu(bf2f(zg[lane]))); mo[64 + lane] = f2bf(d1 * rstd * gn[hh * 128 + 64 + lane] * silu(bf2f(zg[64 + lane]))); }
;     __syncthreads();
.LBB0_677:
	s_or_b64 exec, exec, s[2:3]
	s_add_u32 s2, s16, 0x2600000
	s_addc_u32 s3, s15, 0
	v_and_b32_e32 v1, 63, v1
	s_ashr_i32 s10, s17, 5
	s_and_b32 s6, s10, -2
	v_lshl_add_u32 v8, v1, 2, 0
	ds_write_b32 v3, v2 offset:58368
	v_lshl_add_u32 v2, s6, 9, v8
	s_waitcnt lgkmcnt(0)
	s_barrier
	ds_read2st64_b32 v[2:3], v2 offset0:228 offset1:229
	s_add_i32 s6, s6, s14
	s_ashr_i32 s7, s6, 31
	s_mul_i32 s9, s6, 0x1400
	s_mul_hi_i32 s8, s6, 0x1400
	s_waitcnt lgkmcnt(0)
	v_add_f32_e32 v4, v2, v3
	ds_swizzle_b32 v5, v4 offset:swizzle(SWAP,1)
	s_add_u32 s9, s13, s9
	s_addc_u32 s11, s12, s8
	s_lshl_b32 s15, s18, 1
	s_add_u32 s8, s9, s15
	s_waitcnt lgkmcnt(0)
	v_add_f32_e32 v9, v4, v5
	s_addc_u32 s9, s11, 0
	v_lshlrev_b32_e32 v4, 1, v1
	v_mov_b32_e32 v5, v0
	v_lshl_add_u64 v[6:7], s[8:9], 0, v[4:5]
	global_load_ushort v14, v[6:7], off offset:3904
	ds_swizzle_b32 v10, v9 offset:swizzle(SWAP,2)
	s_lshl_b64 s[6:7], s[6:7], 11
	s_add_u32 s6, s2, s6
	s_addc_u32 s7, s3, s7
	s_add_u32 s6, s6, s15
	s_waitcnt lgkmcnt(0)
	v_add_f32_e32 v9, v9, v10
	ds_swizzle_b32 v10, v9 offset:swizzle(SWAP,4)
	s_addc_u32 s7, s7, 0
	s_or_b32 s8, s10, 1
	v_lshl_add_u32 v8, s8, 9, v8
	v_or_b32_e32 v1, s18, v1
	s_waitcnt lgkmcnt(0)
	v_add_f32_e32 v12, v9, v10
	ds_swizzle_b32 v13, v12 offset:swizzle(SWAP,8)
	ds_read2st64_b32 v[8:9], v8 offset0:228 offset1:229
	v_lshlrev_b32_e32 v10, 2, v1
	v_mov_b32_e32 v11, v0
	v_lshl_add_u64 v[10:11], s[4:5], 0, v[10:11]
	s_waitcnt lgkmcnt(0)
	v_add_f32_e32 v1, v12, v13
	v_add_f32_e32 v13, v8, v9
	ds_swizzle_b32 v15, v13 offset:swizzle(SWAP,1)
	global_load_dword v16, v[10:11], off
	ds_swizzle_b32 v12, v1 offset:swizzle(SWAP,16)
	s_brev_b32 s4, 60
	s_mov_b32 s9, 0x800000
	s_waitcnt lgkmcnt(0)
	v_add_f32_e32 v13, v13, v15
	ds_swizzle_b32 v15, v13 offset:swizzle(SWAP,2)
	v_add_f32_e32 v1, v1, v12
	v_mov_b32_e32 v12, v1
	s_nop 1
	v_permlane32_swap_b32_e32 v1, v12
	v_add_f32_e32 v1, v1, v12
	v_mul_f32_e32 v12, 0x3c000000, v1
	s_waitcnt lgkmcnt(0)
	v_add_f32_e32 v1, v13, v15
	ds_swizzle_b32 v15, v1 offset:swizzle(SWAP,4)
	v_pk_add_f32 v[2:3], v[2:3], v[12:13] op_sel_hi:[1,0] neg_lo:[0,1] neg_hi:[0,1]
	s_mov_b32 s66, 0x800000
	v_pk_mul_f32 v[12:13], v[2:3], v[2:3]
	s_waitcnt lgkmcnt(0)
	v_add_f32_e32 v1, v1, v15
	v_add_f32_e32 v12, v12, v13
	ds_swizzle_b32 v15, v1 offset:swizzle(SWAP,8)
	ds_swizzle_b32 v13, v12 offset:swizzle(SWAP,1)
	s_waitcnt lgkmcnt(0)
	v_add_f32_e32 v1, v1, v15
	v_add_f32_e32 v12, v12, v13
	ds_swizzle_b32 v15, v1 offset:swizzle(SWAP,16)
	ds_swizzle_b32 v13, v12 offset:swizzle(SWAP,2)
	s_waitcnt lgkmcnt(0)
	v_add_f32_e32 v1, v1, v15
	v_add_f32_e32 v17, v12, v13
	v_mov_b32_e32 v12, v1
	s_nop 1
	v_permlane32_swap_b32_e32 v1, v12
	v_add_f32_e32 v1, v1, v12
	v_mul_f32_e32 v12, 0x3c000000, v1
	v_pk_add_f32 v[8:9], v[8:9], v[12:13] op_sel_hi:[1,0] neg_lo:[0,1] neg_hi:[0,1]
	ds_swizzle_b32 v18, v17 offset:swizzle(SWAP,4)
	v_pk_mul_f32 v[12:13], v[8:9], v[8:9]
	s_nop 0
	v_add_f32_e32 v1, v12, v13
	ds_swizzle_b32 v12, v1 offset:swizzle(SWAP,1)
	s_waitcnt lgkmcnt(0)
	v_add_f32_e32 v13, v17, v18
	ds_swizzle_b32 v15, v13 offset:swizzle(SWAP,8)
	v_add_f32_e32 v1, v1, v12
	ds_swizzle_b32 v12, v1 offset:swizzle(SWAP,2)
	s_waitcnt lgkmcnt(0)
	v_add_f32_e32 v13, v13, v15
	ds_swizzle_b32 v15, v13 offset:swizzle(SWAP,16)
	v_add_f32_e32 v1, v1, v12
	ds_swizzle_b32 v12, v1 offset:swizzle(SWAP,4)
	s_waitcnt lgkmcnt(0)
	v_add_f32_e32 v13, v13, v15
	v_mov_b32_e32 v15, v13
	s_waitcnt vmcnt(0)
	v_lshlrev_b32_e32 v17, 16, v14
	v_mul_f32_e32 v14, 0xbfb8aa3b, v17
	v_add_f32_e32 v1, v1, v12
	ds_swizzle_b32 v12, v1 offset:swizzle(SWAP,8)
	v_exp_f32_e32 v14, v14
	v_permlane32_swap_b32_e32 v13, v15
	s_waitcnt lgkmcnt(0)
	v_add_f32_e32 v1, v1, v12
	ds_swizzle_b32 v12, v1 offset:swizzle(SWAP,16)
	v_add_f32_e32 v14, 1.0, v14
	v_rcp_f32_e32 v18, v14
	s_waitcnt lgkmcnt(0)
	v_add_f32_e32 v12, v1, v12
	v_mov_b32_e32 v14, v12
	s_nop 1
	v_permlane32_swap_b32_e32 v12, v14
	v_pk_add_f32 v[12:13], v[12:13], v[14:15]
	v_mul_f32_e32 v14, v18, v17
	v_pk_fma_f32 v[12:13], v[12:13], s[4:5], v[152:153] op_sel_hi:[1,0,0]
	s_add_i32 s4, s8, s14
	v_mul_f32_e32 v1, 0x4b800000, v13
	v_cmp_gt_f32_e32 vcc, s9, v13
	s_ashr_i32 s5, s4, 31
	s_nop 0
	v_cndmask_b32_e32 v1, v13, v1, vcc
	v_rsq_f32_e32 v1, v1
	global_load_dword v13, v[10:11], off offset:256
	v_lshl_add_u64 v[10:11], s[6:7], 0, v[4:5]
	s_mul_i32 s7, s4, 0x1400
	v_mul_f32_e32 v15, 0x45800000, v1
	v_cndmask_b32_e32 v1, v1, v15, vcc
	v_mul_f32_e32 v2, v2, v1
	v_mul_f32_e32 v2, v16, v2
	v_mul_f32_e32 v2, v14, v2
	v_cvt_pk_bf16_f32 v2, v2, s0
	global_store_short v[10:11], v2, off offset:1024
	global_load_ushort v2, v[6:7], off offset:4032
	s_mul_hi_i32 s6, s4, 0x1400
	s_add_u32 s7, s13, s7
	v_mul_f32_e32 v1, v3, v1
	s_addc_u32 s8, s12, s6
	s_add_u32 s6, s7, s15
	s_addc_u32 s7, s8, 0
	v_cmp_gt_f32_e32 vcc, s9, v12
	s_lshl_b64 s[4:5], s[4:5], 11
	s_add_u32 s2, s2, s4
	s_addc_u32 s3, s3, s5
	s_add_u32 s2, s2, s15
	s_addc_u32 s3, s3, 0
	s_waitcnt vmcnt(0) lgkmcnt(0)
	v_mul_f32_e32 v1, v13, v1
	v_lshlrev_b32_e32 v2, 16, v2
	v_mul_f32_e32 v6, 0xbfb8aa3b, v2
	v_exp_f32_e32 v6, v6
	s_nop 0
	v_add_f32_e32 v6, 1.0, v6
	v_rcp_f32_e32 v14, v6
	v_lshl_add_u64 v[6:7], s[6:7], 0, v[4:5]
	v_mul_f32_e32 v2, v14, v2
	v_mul_f32_e32 v1, v2, v1
	v_cvt_pk_bf16_f32 v1, v1, s0
	global_store_short v[10:11], v1, off offset:1152
	global_load_ushort v1, v[6:7], off offset:3904
	v_mul_f32_e32 v2, 0x4b800000, v12
	v_cndmask_b32_e32 v2, v12, v2, vcc
	v_rsq_f32_e32 v10, v2
	s_waitcnt vmcnt(0) lgkmcnt(0)
	v_lshlrev_b32_e32 v1, 16, v1
	v_mul_f32_e32 v2, 0xbfb8aa3b, v1
	v_exp_f32_e32 v11, v2
	v_lshl_add_u64 v[2:3], s[2:3], 0, v[4:5]
	v_mul_f32_e32 v4, 0x45800000, v10
	v_cndmask_b32_e32 v4, v10, v4, vcc
	v_add_f32_e32 v5, 1.0, v11
	v_rcp_f32_e32 v5, v5
	v_mul_f32_e32 v8, v8, v4
	v_mul_f32_e32 v8, v16, v8
	v_mul_f32_e32 v4, v9, v4
	v_mul_f32_e32 v1, v5, v1
	v_mul_f32_e32 v1, v1, v8
	v_cvt_pk_bf16_f32 v1, v1, s0
	global_store_short v[2:3], v1, off offset:1024
	global_load_ushort v1, v[6:7], off offset:4032
	v_mul_f32_e32 v4, v13, v4
	s_mov_b64 s[2:3], 0
	s_waitcnt vmcnt(0) lgkmcnt(0)
	v_lshlrev_b32_e32 v1, 16, v1
	v_mul_f32_e32 v5, 0xbfb8aa3b, v1
	v_exp_f32_e32 v5, v5
	s_nop 0
	v_add_f32_e32 v5, 1.0, v5
	v_rcp_f32_e32 v5, v5
	s_nop 0
	v_mul_f32_e32 v1, v5, v1
	v_mul_f32_e32 v1, v1, v4
	v_cvt_pk_bf16_f32 v1, v1, s0
	global_store_short v[2:3], v1, off offset:1152
	s_waitcnt lgkmcnt(0)
	s_barrier
; #define LAS __attribute__((address_space(3)))
; __device__ __forceinline__ void ret_out_item(LAS unsigned char* lds, const bf16* Z, const bf16* AT, const float* gn, bf16* MIXED, int b, int c, const float* lgs) {
;     LAS bf16* VT4 = (LAS bf16*)lds;
;     const int tid_ = my_tid(lds); const int tid = tid_, lane = tid & 63, r32 = lane & 31, hi = lane >> 5; const int wid = __builtin_amdgcn_readfirstlane(tid >> 6);
;     const int rowbase = b * SEQ + 64 * c;
; #pragma unroll
;     for (int i = 0; i < 8; ++i) { const int ci = tid + 512 * i, l = ci & 63, ec = ci >> 6; const u32x4 vr = *(const u32x4*)(Z + (size_t)(rowbase + l) * NZ + ZC_RV + ec * 8);
; #pragma unroll
;         for (int e = 0; e < 4; ++e) { const unsigned vw = vr[e]; VT4[(8 * ec + 2 * e) * 72 + l] = (bf16)(vw & 0xffffu); VT4[(8 * ec + 2 * e + 1) * 72 + l] = (bf16)(vw >> 16); } }
;     __syncthreads();
.LBB0_678:
	s_and_b64 vcc, exec, s[2:3]
	s_cbranch_vccz .LBB0_682
	v_mov_b32_e32 v1, s45
	ds_read_b64 v[2:3], v1
	s_sub_i32 s3, s57, 32
	v_readlane_b32 s2, v254, 10
	ds_read_b64 v[6:7], v1
	s_movk_i32 s16, 0xa00
	s_waitcnt lgkmcnt(0)
	v_readfirstlane_b32 s4, v2
	v_mov_b32_e32 v4, s2
	v_readfirstlane_b32 s2, v3
	s_add_u32 s4, s4, 0x6800000
	s_addc_u32 s5, s2, 0
	ds_read_b64 v[2:3], v4
	ds_read_b64 v[4:5], v1
	s_getreg_b32 s2, hwreg(HW_REG_HW_ID, 0, 6)
	s_lshl_b32 s2, s2, 2
	s_and_b32 s2, s2, 0xfc
	s_add_i32 s2, s2, 0
	s_add_i32 s2, s2, 0x25a00
	v_mov_b32_e32 v1, s2
	ds_read_b32 v1, v1
	s_lshr_b32 s2, s3, 8
	s_and_b32 s3, s3, 0xff
	s_lshl_b32 s7, s3, 6
	v_mov_b32_e32 v9, v0
	s_waitcnt lgkmcnt(0)
	v_readfirstlane_b32 s6, v1
	v_mbcnt_lo_u32_b32 v1, -1, 0
	v_mbcnt_hi_u32_b32 v1, -1, v1
	v_readfirstlane_b32 s14, v6
	v_and_b32_e32 v16, 63, v1
	v_lshl_add_u32 v18, s6, 6, v1
	s_lshl_b32 s6, s2, 14
	s_or_b32 s13, s7, s6
	v_or_b32_e32 v8, s13, v16
	v_mul_lo_u32 v8, v8, s16
	v_lshl_add_u64 v[12:13], v[8:9], 1, s[4:5]
	v_ashrrev_i32_e32 v8, 3, v18
	v_and_b32_e32 v14, -8, v8
	v_ashrrev_i32_e32 v15, 31, v14
	v_lshl_add_u64 v[8:9], v[14:15], 1, v[12:13]
	global_load_dwordx4 v[8:11], v[8:9], off offset:2880
	v_add_u32_e32 v15, 0x200, v18
	v_ashrrev_i32_e32 v15, 3, v15
	v_lshlrev_b32_e32 v19, 1, v16
	v_mul_lo_u32 v16, v14, s87
	v_and_b32_e32 v14, -8, v15
	v_add3_u32 v20, 0, v16, v19
	v_ashrrev_i32_e32 v15, 31, v14
	v_lshl_add_u64 v[16:17], v[14:15], 1, v[12:13]
	v_add_u32_e32 v15, 0x400, v18
	v_ashrrev_i32_e32 v15, 3, v15
	v_mul_lo_u32 v14, v14, s87
	v_readfirstlane_b32 s6, v18
	s_ashr_i32 s15, s6, 7
	s_bfe_u32 s12, s6, 0x10006
	s_cmp_eq_u32 s15, 1
	s_cselect_b64 vcc, -1, 0
	s_cmp_lg_u32 s15, 2
	v_cndmask_b32_e32 v6, v161, v162, vcc
	s_cselect_b64 vcc, -1, 0
	s_cmp_lg_u32 s15, 3
	v_cndmask_b32_e32 v42, v163, v6, vcc
	s_cselect_b64 vcc, -1, 0
	s_lshl_b32 s2, s2, 10
	s_lshl_b32 s3, s3, 2
	s_or_b32 s2, s3, s2
	s_and_b32 s6, s6, 0xffffff80
	s_add_i32 s2, s2, s15
	s_ashr_i32 s7, s6, 31
	s_ashr_i32 s3, s2, 31
	s_lshl_b64 s[8:9], s[6:7], 1
	s_lshl_b64 s[2:3], s[2:3], 15
	v_readfirstlane_b32 s11, v7
	v_bfe_u32 v143, v1, 5, 1
	s_add_u32 s2, s14, s2
	v_mov_b32_e32 v141, v0
	v_and_b32_e32 v62, 31, v1
	v_lshlrev_b32_e32 v140, 4, v143
	s_addc_u32 s3, s11, s3
	v_lshl_add_u64 v[6:7], s[2:3], 0, v[140:141]
	s_mov_b32 s10, 0x17e00000
	v_lshl_or_b32 v144, s12, 5, v62
	v_or_b32_e32 v142, s13, v144
	v_readfirstlane_b32 s11, v2
	v_lshlrev_b32_e32 v138, 3, v143
	v_mov_b32_e32 v139, v0
	s_waitcnt vmcnt(0) lgkmcnt(0)
	ds_write_b16 v20, v8
	ds_write_b16_d16_hi v20, v8 offset:144
	ds_write_b16 v20, v9 offset:288
	ds_write_b16_d16_hi v20, v9 offset:432
	ds_write_b16 v20, v10 offset:576
	ds_write_b16_d16_hi v20, v10 offset:720
	ds_write_b16 v20, v11 offset:864
	ds_write_b16_d16_hi v20, v11 offset:1008
	global_load_dwordx4 v[8:11], v[16:17], off offset:2880
	v_and_b32_e32 v16, -8, v15
	v_ashrrev_i32_e32 v17, 31, v16
	v_add3_u32 v20, 0, v14, v19
	v_lshl_add_u64 v[14:15], v[16:17], 1, v[12:13]
	v_mul_lo_u32 v16, v16, s87
	s_waitcnt vmcnt(0) lgkmcnt(0)
	ds_write_b16 v20, v8
	ds_write_b16_d16_hi v20, v8 offset:144
	ds_write_b16 v20, v9 offset:288
	ds_write_b16_d16_hi v20, v9 offset:432
	ds_write_b16 v20, v10 offset:576
	ds_write_b16_d16_hi v20, v10 offset:720
	ds_write_b16 v20, v11 offset:864
	ds_write_b16_d16_hi v20, v11 offset:1008
	global_load_dwordx4 v[8:11], v[14:15], off offset:2880
	v_add_u32_e32 v14, 0x600, v18
	v_ashrrev_i32_e32 v14, 3, v14
	v_and_b32_e32 v14, -8, v14
	v_ashrrev_i32_e32 v15, 31, v14
	v_add3_u32 v20, 0, v16, v19
	v_lshl_add_u64 v[16:17], v[14:15], 1, v[12:13]
	v_add_u32_e32 v15, 0x800, v18
	v_ashrrev_i32_e32 v15, 3, v15
	v_mul_lo_u32 v14, v14, s87
	s_waitcnt vmcnt(0) lgkmcnt(0)
	ds_write_b16 v20, v8
	ds_write_b16_d16_hi v20, v8 offset:144
	ds_write_b16 v20, v9 offset:288
	ds_write_b16_d16_hi v20, v9 offset:432
	ds_write_b16 v20, v10 offset:576
	ds_write_b16_d16_hi v20, v10 offset:720
	ds_write_b16 v20, v11 offset:864
	ds_write_b16_d16_hi v20, v11 offset:1008
	global_load_dwordx4 v[8:11], v[16:17], off offset:2880
	v_and_b32_e32 v16, -8, v15
	v_ashrrev_i32_e32 v17, 31, v16
	v_add3_u32 v20, 0, v14, v19
	v_lshl_add_u64 v[14:15], v[16:17], 1, v[12:13]
	v_mul_lo_u32 v16, v16, s87
	s_waitcnt vmcnt(0) lgkmcnt(0)
	ds_write_b16 v20, v8
	ds_write_b16_d16_hi v20, v8 offset:144
	ds_write_b16 v20, v9 offset:288
	ds_write_b16_d16_hi v20, v9 offset:432
	ds_write_b16 v20, v10 offset:576
	ds_write_b16_d16_hi v20, v10 offset:720
	ds_write_b16 v20, v11 offset:864
	ds_write_b16_d16_hi v20, v11 offset:1008
	global_load_dwordx4 v[8:11], v[14:15], off offset:2880
	v_add_u32_e32 v14, 0xa00, v18
	v_ashrrev_i32_e32 v14, 3, v14
	v_and_b32_e32 v14, -8, v14
	v_ashrrev_i32_e32 v15, 31, v14
	v_add3_u32 v20, 0, v16, v19
	v_lshl_add_u64 v[16:17], v[14:15], 1, v[12:13]
	v_add_u32_e32 v15, 0xc00, v18
	v_ashrrev_i32_e32 v15, 3, v15
	v_mul_lo_u32 v14, v14, s87
	s_waitcnt vmcnt(0) lgkmcnt(0)
	ds_write_b16 v20, v8
	ds_write_b16_d16_hi v20, v8 offset:144
	ds_write_b16 v20, v9 offset:288
	ds_write_b16_d16_hi v20, v9 offset:432
	ds_write_b16 v20, v10 offset:576
	ds_write_b16_d16_hi v20, v10 offset:720
	ds_write_b16 v20, v11 offset:864
	ds_write_b16_d16_hi v20, v11 offset:1008
	global_load_dwordx4 v[8:11], v[16:17], off offset:2880
	v_and_b32_e32 v16, -8, v15
	v_ashrrev_i32_e32 v17, 31, v16
	v_add3_u32 v20, 0, v14, v19
	v_lshl_add_u64 v[14:15], v[16:17], 1, v[12:13]
	v_mul_lo_u32 v16, v16, s87
	v_add3_u32 v16, 0, v16, v19
	v_mov_b32_e32 v17, v0
	s_waitcnt vmcnt(0) lgkmcnt(0)
; #define MFMA32(a, b, c) __builtin_amdgcn_mfma_f32_32x32x16_bf16((a), (b), (c), 0, 0, 0)
; __device__ __forceinline__ void ret_out_item(LAS unsigned char* lds, const bf16* Z, const bf16* AT, const float* gn, bf16* MIXED, int b, int c, const float* lgs) {
;     ...
;     for (int i = 0; i < 8; ++i) { const int ci = tid + 512 * i, l = ci & 63, ec = ci >> 6; const u32x4 vr = *(const u32x4*)(Z + (size_t)(rowbase + l) * NZ + ZC_RV + ec * 8);
; #pragma unroll
;         for (int e = 0; e < 4; ++e) { const unsigned vw = vr[e]; VT4[(8 * ec + 2 * e) * 72 + l] = (bf16)(vw & 0xffffu); VT4[(8 * ec + 2 * e + 1) * 72 + l] = (bf16)(vw >> 16); } }
;     __syncthreads();
;     const int hh = wid >> 1, lb = wid & 1, l = 32 * lb + r32, row = rowbase + l; const float lg = lgs[hh];
;     bf16x8 qf[8];
; #pragma unroll
;     for (int ds = 0; ds < 8; ++ds) qf[ds] = *(const bf16x8*)(Z + (size_t)row * NZ + ZC_RQ + hh * 128 + 16 * ds + 8 * hi);
;     f32x16 acc[4];
; #pragma unroll
;     for (int i = 0; i < 4; ++i)
; #pragma unroll
;         for (int r = 0; r < 16; ++r) acc[i][r] = 0.f;
;     const bf16* Sp = AT + (size_t)((b * 256 + c) * 4 + hh) * 16384;
; #pragma unroll
;     for (int eb = 0; eb < 4; ++eb)
; #pragma unroll
;         for (int ds = 0; ds < 8; ++ds) { const bf16x8 w = *(const bf16x8*)(Sp + (32 * eb + r32) * 128 + 16 * ds + 8 * hi);
;             acc[eb] = MFMA32(w, qf[ds], acc[eb]); if (ds == 3 || ds == 7) __builtin_amdgcn_sched_barrier(0); }
	ds_write_b16 v20, v8
	ds_write_b16_d16_hi v20, v8 offset:144
	ds_write_b16 v20, v9 offset:288
	ds_write_b16_d16_hi v20, v9 offset:432
	ds_write_b16 v20, v10 offset:576
	ds_write_b16_d16_hi v20, v10 offset:720
	ds_write_b16 v20, v11 offset:864
	ds_write_b16_d16_hi v20, v11 offset:1008
	global_load_dwordx4 v[8:11], v[14:15], off offset:2880
	v_add_u32_e32 v14, 0xe00, v18
	v_ashrrev_i32_e32 v14, 3, v14
	v_and_b32_e32 v14, -8, v14
	v_ashrrev_i32_e32 v15, 31, v14
	v_lshl_add_u64 v[12:13], v[14:15], 1, v[12:13]
	v_mul_lo_u32 v1, v14, s87
	v_add3_u32 v1, 0, v1, v19
	s_waitcnt vmcnt(0) lgkmcnt(0)
	ds_write_b16 v16, v8
	ds_write_b16_d16_hi v16, v8 offset:144
	ds_write_b16 v16, v9 offset:288
	ds_write_b16_d16_hi v16, v9 offset:432
	ds_write_b16 v16, v10 offset:576
	ds_write_b16_d16_hi v16, v10 offset:720
	ds_write_b16 v16, v11 offset:864
	ds_write_b16_d16_hi v16, v11 offset:1008
	global_load_dwordx4 v[8:11], v[12:13], off offset:2880
	v_lshlrev_b32_e32 v16, 8, v62
	v_lshl_add_u64 v[58:59], v[6:7], 0, v[16:17]
	v_add_co_u32_e64 v6, s[2:3], s10, v58
	v_mov_b32_e32 v13, v0
	s_nop 0
	v_addc_co_u32_e64 v7, s[2:3], 0, v59, s[2:3]
	v_mul_lo_u32 v12, v142, s16
	s_mov_b64 s[2:3], 0x17e00000
	v_lshl_add_u64 v[40:41], v[58:59], 0, s[2:3]
	v_readfirstlane_b32 s10, v3
	v_readfirstlane_b32 s3, v5
	v_readfirstlane_b32 s2, v4
	s_waitcnt vmcnt(0) lgkmcnt(0)
	ds_write_b16 v1, v8
	ds_write_b16_d16_hi v1, v8 offset:144
	ds_write_b16 v1, v9 offset:288
	ds_write_b16_d16_hi v1, v9 offset:432
	ds_write_b16 v1, v10 offset:576
	ds_write_b16_d16_hi v1, v10 offset:720
	ds_write_b16 v1, v11 offset:864
	ds_write_b16_d16_hi v1, v11 offset:1008
	s_waitcnt lgkmcnt(0)
	s_barrier
	global_load_dwordx4 v[6:9], v[6:7], off
	v_lshl_add_u64 v[10:11], v[12:13], 1, s[4:5]
	v_lshl_add_u64 v[10:11], v[10:11], 0, s[8:9]
	v_lshl_add_u64 v[38:39], v[10:11], 0, v[140:141]
	global_load_dwordx4 v[110:113], v[38:39], off offset:832
	global_load_dwordx4 v[10:13], v[40:41], off offset:32
	global_load_dwordx4 v[102:105], v[38:39], off offset:864
	global_load_dwordx4 v[14:17], v[40:41], off offset:64
	global_load_dwordx4 v[34:37], v[40:41], off offset:96
	global_load_dwordx4 v[106:109], v[38:39], off offset:896
	global_load_dwordx4 v[98:101], v[38:39], off offset:928
	global_load_dwordx4 v[94:97], v[38:39], off offset:960
	global_load_dwordx4 v[90:93], v[38:39], off offset:992
	global_load_dwordx4 v[86:89], v[38:39], off offset:1024
	global_load_dwordx4 v[82:85], v[38:39], off offset:1056
	v_cndmask_b32_e32 v1, v164, v42, vcc
	s_waitcnt vmcnt(0) lgkmcnt(0)
	v_mfma_f32_32x32x16_bf16 v[18:33], v[6:9], v[110:113], 0
	v_mfma_f32_32x32x16_bf16 v[18:33], v[10:13], v[102:105], v[18:33]
	v_mfma_f32_32x32x16_bf16 v[18:33], v[14:17], v[106:109], v[18:33]
	v_mfma_f32_32x32x16_bf16 v[18:33], v[34:37], v[98:101], v[18:33]
	global_load_dwordx4 v[2:5], v[40:41], off offset:128
	global_load_dwordx4 v[6:9], v[40:41], off offset:160
	s_waitcnt vmcnt(0) lgkmcnt(0)
	v_mfma_f32_32x32x16_bf16 v[18:33], v[2:5], v[94:97], v[18:33]
	global_load_dwordx4 v[2:5], v[40:41], off offset:192
	v_mfma_f32_32x32x16_bf16 v[18:33], v[6:9], v[90:93], v[18:33]
	global_load_dwordx4 v[6:9], v[40:41], off offset:224
	s_waitcnt vmcnt(0) lgkmcnt(0)
	v_mfma_f32_32x32x16_bf16 v[18:33], v[2:5], v[86:89], v[18:33]
	v_mfma_f32_32x32x16_bf16 v[18:33], v[6:9], v[82:85], v[18:33]
	s_mov_b32 s14, 0x17e02000
	v_add_co_u32_e32 v42, vcc, s14, v58
	s_nop 1
	v_addc_co_u32_e32 v43, vcc, 0, v59, vcc
	global_load_dwordx4 v[2:5], v[42:43], off
	global_load_dwordx4 v[34:37], v[42:43], off offset:32
	global_load_dwordx4 v[38:41], v[42:43], off offset:64
	s_waitcnt vmcnt(0) lgkmcnt(0)
	v_mfma_f32_32x32x16_bf16 v[2:17], v[2:5], v[110:113], 0
	v_mfma_f32_32x32x16_bf16 v[2:17], v[34:37], v[102:105], v[2:17]
	global_load_dwordx4 v[34:37], v[42:43], off offset:96
	v_mfma_f32_32x32x16_bf16 v[2:17], v[38:41], v[106:109], v[2:17]
	s_waitcnt vmcnt(0) lgkmcnt(0)
	v_mfma_f32_32x32x16_bf16 v[2:17], v[34:37], v[98:101], v[2:17]
	global_load_dwordx4 v[34:37], v[42:43], off offset:128
	global_load_dwordx4 v[38:41], v[42:43], off offset:160
	s_waitcnt vmcnt(0) lgkmcnt(0)
	v_mfma_f32_32x32x16_bf16 v[2:17], v[34:37], v[94:97], v[2:17]
	global_load_dwordx4 v[34:37], v[42:43], off offset:192
	v_mfma_f32_32x32x16_bf16 v[2:17], v[38:41], v[90:93], v[2:17]
	global_load_dwordx4 v[38:41], v[42:43], off offset:224
	s_waitcnt vmcnt(0) lgkmcnt(0)
	v_mfma_f32_32x32x16_bf16 v[2:17], v[34:37], v[86:89], v[2:17]
	v_mfma_f32_32x32x16_bf16 v[2:17], v[38:41], v[82:85], v[2:17]
	s_mov_b32 s14, 0x17e04000
	v_add_co_u32_e32 v60, vcc, s14, v58
	s_nop 1
	v_addc_co_u32_e32 v61, vcc, 0, v59, vcc
	global_load_dwordx4 v[34:37], v[60:61], off
	global_load_dwordx4 v[50:53], v[60:61], off offset:32
	global_load_dwordx4 v[54:57], v[60:61], off offset:64
	s_waitcnt vmcnt(0) lgkmcnt(0)
	v_mfma_f32_32x32x16_bf16 v[34:49], v[34:37], v[110:113], 0
	v_mfma_f32_32x32x16_bf16 v[34:49], v[50:53], v[102:105], v[34:49]
	global_load_dwordx4 v[50:53], v[60:61], off offset:96
	v_mfma_f32_32x32x16_bf16 v[34:49], v[54:57], v[106:109], v[34:49]
	s_waitcnt vmcnt(0) lgkmcnt(0)
	v_mfma_f32_32x32x16_bf16 v[34:49], v[50:53], v[98:101], v[34:49]
	global_load_dwordx4 v[50:53], v[60:61], off offset:128
	global_load_dwordx4 v[54:57], v[60:61], off offset:160
	s_waitcnt vmcnt(0) lgkmcnt(0)
	v_mfma_f32_32x32x16_bf16 v[34:49], v[50:53], v[94:97], v[34:49]
	global_load_dwordx4 v[50:53], v[60:61], off offset:192
	v_mfma_f32_32x32x16_bf16 v[34:49], v[54:57], v[90:93], v[34:49]
	global_load_dwordx4 v[54:57], v[60:61], off offset:224
	s_waitcnt vmcnt(0) lgkmcnt(0)
; __device__ __forceinline__ int crow(int r, int hi) { return (r & 3) + 8 * (r >> 2) + 4 * hi; }
; __device__ __forceinline__ float ex2f(float x) { return __builtin_amdgcn_exp2f(x); }
; #define MFMA32(a, b, c) __builtin_amdgcn_mfma_f32_32x32x16_bf16((a), (b), (c), 0, 0, 0)
; __device__ __forceinline__ void ret_out_item(LAS unsigned char* lds, const bf16* Z, const bf16* AT, const float* gn, bf16* MIXED, int b, int c, const float* lgs) {
;     ...
;     const bf16* Sp = AT + (size_t)((b * 256 + c) * 4 + hh) * 16384;
; #pragma unroll
;     for (int eb = 0; eb < 4; ++eb)
; #pragma unroll
;         for (int ds = 0; ds < 8; ++ds) { const bf16x8 w = *(const bf16x8*)(Sp + (32 * eb + r32) * 128 + 16 * ds + 8 * hi);
;             acc[eb] = MFMA32(w, qf[ds], acc[eb]); if (ds == 3 || ds == 7) __builtin_amdgcn_sched_barrier(0); }
;     { const float qd = ex2f((float)(l + 1) * lg);
; #pragma unroll
;       for (int i = 0; i < 4; ++i)
; #pragma unroll
;           for (int r = 0; r < 16; ++r) acc[i][r] *= qd; }
; #pragma unroll
;     for (int mb = 0; mb < 2; ++mb) {
;         if (mb <= lb) {
;             f32x16 st;
; #pragma unroll
;             for (int r = 0; r < 16; ++r) st[r] = 0.f;
; #pragma unroll
;             for (int ds = 0; ds < 8; ++ds) { const bf16x8 kf = *(const bf16x8*)(Z + (size_t)(rowbase + 32 * mb + r32) * NZ + ZC_RK + hh * 128 + 16 * ds + 8 * hi); st = MFMA32(kf, qf[ds], st); }
; #pragma unroll
;             for (int r = 0; r < 16; ++r) { const int m = 32 * mb + crow(r, hi), diff = l - m; st[r] = diff >= 0 ? st[r] * ex2f((float)diff * lg) : 0.f; }
	v_mfma_f32_32x32x16_bf16 v[34:49], v[50:53], v[86:89], v[34:49]
	v_mfma_f32_32x32x16_bf16 v[34:49], v[54:57], v[82:85], v[34:49]
	s_mov_b32 s14, 0x17e06000
	v_add_co_u32_e32 v58, vcc, s14, v58
	s_nop 1
	v_addc_co_u32_e32 v59, vcc, 0, v59, vcc
	global_load_dwordx4 v[50:53], v[58:59], off
	global_load_dwordx4 v[54:57], v[58:59], off offset:32
	s_waitcnt vmcnt(0) lgkmcnt(0)
	v_mfma_f32_32x32x16_bf16 v[66:81], v[50:53], v[110:113], 0
	global_load_dwordx4 v[50:53], v[58:59], off offset:64
	v_mfma_f32_32x32x16_bf16 v[66:81], v[54:57], v[102:105], v[66:81]
	global_load_dwordx4 v[54:57], v[58:59], off offset:96
	s_waitcnt vmcnt(0) lgkmcnt(0)
	v_mfma_f32_32x32x16_bf16 v[66:81], v[50:53], v[106:109], v[66:81]
	v_mfma_f32_32x32x16_bf16 v[66:81], v[54:57], v[98:101], v[66:81]
	global_load_dwordx4 v[50:53], v[58:59], off offset:128
	global_load_dwordx4 v[54:57], v[58:59], off offset:160
	s_waitcnt vmcnt(0) lgkmcnt(0)
	v_mfma_f32_32x32x16_bf16 v[66:81], v[50:53], v[94:97], v[66:81]
	global_load_dwordx4 v[50:53], v[58:59], off offset:192
	v_mfma_f32_32x32x16_bf16 v[66:81], v[54:57], v[90:93], v[66:81]
	global_load_dwordx4 v[54:57], v[58:59], off offset:224
	s_waitcnt vmcnt(0) lgkmcnt(0)
	v_mfma_f32_32x32x16_bf16 v[66:81], v[50:53], v[86:89], v[66:81]
	v_mfma_f32_32x32x16_bf16 v[66:81], v[54:57], v[82:85], v[66:81]
	v_or_b32_e32 v50, s13, v62
	v_mul_lo_u32 v50, v50, s16
	v_mov_b32_e32 v51, v0
	v_lshl_add_u64 v[114:115], v[50:51], 1, s[4:5]
	v_lshl_add_u64 v[50:51], v[114:115], 0, s[8:9]
	v_lshl_add_u64 v[54:55], v[50:51], 0, v[140:141]
	global_load_dwordx4 v[50:53], v[54:55], off offset:1856
	global_load_dwordx4 v[116:119], v[54:55], off offset:1888
	global_load_dwordx4 v[120:123], v[54:55], off offset:1920
	global_load_dwordx4 v[124:127], v[54:55], off offset:1952
	global_load_dwordx4 v[128:131], v[54:55], off offset:1984
	global_load_dwordx4 v[132:135], v[54:55], off offset:2016
	global_load_dwordx4 v[178:181], v[54:55], off offset:2048
	global_load_dwordx4 v[182:185], v[54:55], off offset:2080
	v_add_u32_e32 v56, 1, v144
	v_cvt_f32_ubyte0_e32 v54, v56
	v_or_b32_e32 v137, s6, v62
	v_mul_f32_e32 v136, v1, v54
	v_mad_i32_i24 v145, v143, -4, -1
	v_mad_i32_i24 v187, v143, -4, v144
	v_mad_i32_i24 v146, v143, -4, -3
	v_mad_i32_i24 v147, v143, -4, -2
	v_mad_i32_i24 v148, v143, -4, -9
	v_mad_i32_i24 v149, v143, -4, -8
	v_add_u32_e32 v188, v144, v145
	v_mad_i32_i24 v150, v143, -4, -11
	v_mad_i32_i24 v151, v143, -4, -10
	v_cvt_f32_u32_e32 v189, v187
	v_add_u32_e32 v190, v144, v146
	v_add_u32_e32 v191, v144, v147
	v_add_u32_e32 v192, v144, v148
	v_add_u32_e32 v193, v144, v149
	v_cvt_f32_u32_e32 v204, v188
	v_add_u32_e32 v194, v144, v150
	v_add_u32_e32 v195, v144, v151
	v_cvt_f32_u32_e32 v205, v191
	v_cvt_f32_u32_e32 v206, v190
	v_cvt_f32_u32_e32 v207, v193
	v_cvt_f32_u32_e32 v208, v192
	v_mad_i32_i24 v154, v143, -4, v165
	v_mad_i32_i24 v155, v143, -4, -16
	v_cvt_f32_u32_e32 v209, v195
	v_cvt_f32_u32_e32 v210, v194
	v_add_u32_e32 v196, v144, v154
	v_add_u32_e32 v197, v144, v155
	v_cvt_f32_u32_e32 v211, v197
	v_cvt_f32_u32_e32 v212, v196
	v_mad_i32_i24 v156, v143, -4, v166
	v_mad_i32_i24 v158, v143, -4, v167
	v_add_u32_e32 v198, v144, v156
	v_add_u32_e32 v199, v144, v158
	v_cvt_f32_u32_e32 v213, v199
	v_cvt_f32_u32_e32 v214, v198
	v_cmp_lt_i32_e32 vcc, -1, v187
	v_mad_i32_i24 v159, v143, -4, v168
	v_mad_i32_i24 v160, v143, -4, v169
	v_add_u32_e32 v200, v144, v159
	v_add_u32_e32 v201, v144, v160
	v_mad_i32_i24 v176, v143, -4, v170
	v_mad_i32_i24 v177, v143, -4, v171
	v_cvt_f32_u32_e32 v215, v201
	v_cvt_f32_u32_e32 v216, v200
	v_add_u32_e32 v202, v144, v176
	v_add_u32_e32 v203, v144, v177
	v_add_u32_e32 v186, 0, v138
	v_cvt_f32_u32_e32 v217, v203
	v_cvt_f32_u32_e32 v218, v202
	v_exp_f32_e32 v136, v136
	s_cmp_eq_u32 s12, 0
	s_waitcnt vmcnt(0) lgkmcnt(0)
	v_mfma_f32_32x32x16_bf16 v[50:65], v[50:53], v[110:113], 0
	v_mul_f32_e64 v32, v136, v32
	v_mul_f32_e64 v33, v136, v33
	v_mul_f32_e64 v30, v136, v30
	v_mul_f32_e64 v31, v136, v31
	v_mul_f32_e64 v28, v136, v28
	v_mul_f32_e64 v29, v136, v29
	v_pk_mul_f32 v[26:27], v[136:137], v[26:27] op_sel_hi:[0,1]
	v_pk_mul_f32 v[24:25], v[136:137], v[24:25] op_sel_hi:[0,1]
	v_pk_mul_f32 v[22:23], v[136:137], v[22:23] op_sel_hi:[0,1]
	v_pk_mul_f32 v[20:21], v[136:137], v[20:21] op_sel_hi:[0,1]
	v_mfma_f32_32x32x16_bf16 v[50:65], v[116:119], v[102:105], v[50:65]
	v_mul_f32_e32 v116, v1, v189
	v_mul_f32_e32 v117, v1, v204
	v_exp_f32_e32 v116, v116
	v_mul_f32_e32 v118, v1, v205
	v_mul_f32_e32 v119, v1, v206
	v_mul_f32_e32 v189, v1, v207
	v_exp_f32_e32 v117, v117
	v_mfma_f32_32x32x16_bf16 v[50:65], v[120:123], v[106:109], v[50:65]
	v_mul_f32_e32 v121, v1, v208
	v_mul_f32_e32 v122, v1, v209
	v_mul_f32_e32 v123, v1, v210
	v_exp_f32_e32 v118, v118
	v_exp_f32_e32 v119, v119
	v_exp_f32_e32 v120, v189
	v_exp_f32_e32 v121, v121
	v_mfma_f32_32x32x16_bf16 v[50:65], v[124:127], v[98:101], v[50:65]
	v_exp_f32_e32 v122, v122
	v_exp_f32_e32 v123, v123
	v_mul_f32_e32 v204, v1, v211
	v_mul_f32_e32 v205, v1, v212
	v_exp_f32_e32 v124, v204
	v_exp_f32_e32 v125, v205
	v_mul_f32_e32 v206, v1, v213
	v_mfma_f32_32x32x16_bf16 v[50:65], v[128:131], v[94:97], v[50:65]
	v_mul_f32_e32 v207, v1, v214
	v_exp_f32_e32 v126, v206
	v_exp_f32_e32 v127, v207
	v_mul_f32_e32 v208, v1, v215
	v_mul_f32_e32 v209, v1, v216
	v_exp_f32_e32 v128, v208
	v_exp_f32_e32 v129, v209
	v_mfma_f32_32x32x16_bf16 v[50:65], v[132:135], v[90:93], v[50:65]
	v_mul_f32_e32 v210, v1, v217
	v_mul_f32_e32 v211, v1, v218
	v_exp_f32_e32 v130, v210
	v_exp_f32_e32 v131, v211
	v_pk_mul_f32 v[18:19], v[136:137], v[18:19] op_sel_hi:[0,1]
	v_pk_mul_f32 v[16:17], v[136:137], v[16:17] op_sel_hi:[0,1]
; #define LAS __attribute__((address_space(3)))
; __device__ __forceinline__ int crow(int r, int hi) { return (r & 3) + 8 * (r >> 2) + 4 * hi; }
; __device__ __forceinline__ float ex2f(float x) { return __builtin_amdgcn_exp2f(x); }
; #define MFMA32(a, b, c) __builtin_amdgcn_mfma_f32_32x32x16_bf16((a), (b), (c), 0, 0, 0)
; __device__ __forceinline__ void ret_out_item(LAS unsigned char* lds, const bf16* Z, const bf16* AT, const float* gn, bf16* MIXED, int b, int c, const float* lgs) {
;     ...
;     { const float qd = ex2f((float)(l + 1) * lg);
; #pragma unroll
;       for (int i = 0; i < 4; ++i)
; #pragma unroll
;           for (int r = 0; r < 16; ++r) acc[i][r] *= qd; }
; #pragma unroll
;     for (int mb = 0; mb < 2; ++mb) {
;         if (mb <= lb) {
;             f32x16 st;
; #pragma unroll
;             for (int r = 0; r < 16; ++r) st[r] = 0.f;
; #pragma unroll
;             for (int ds = 0; ds < 8; ++ds) { const bf16x8 kf = *(const bf16x8*)(Z + (size_t)(rowbase + 32 * mb + r32) * NZ + ZC_RK + hh * 128 + 16 * ds + 8 * hi); st = MFMA32(kf, qf[ds], st); }
; #pragma unroll
;             for (int r = 0; r < 16; ++r) { const int m = 32 * mb + crow(r, hi), diff = l - m; st[r] = diff >= 0 ? st[r] * ex2f((float)diff * lg) : 0.f; }
;             const bf16x8 pf0 = pack8(st, 0), pf1 = pack8(st, 8);
; #pragma unroll
;             for (int eb = 0; eb < 4; ++eb)
; #pragma unroll
;                 for (int kk = 0; kk < 2; ++kk) { const LAS bf16* vp = VT4 + (hh * 128 + 32 * eb + r32) * 72 + 16 * (2 * mb + kk) + 4 * hi;
;                     const u32x2 lo = *(const LAS u32x2*)vp, h2 = *(const LAS u32x2*)(vp + 8); const u32x4 v4 = (u32x4){lo.x, lo.y, h2.x, h2.y};
;                     acc[eb] = MFMA32(__builtin_bit_cast(bf16x8, v4), kk ? pf1 : pf0, acc[eb]); }
	v_pk_mul_f32 v[14:15], v[136:137], v[14:15] op_sel_hi:[0,1]
	v_mfma_f32_32x32x16_bf16 v[50:65], v[178:181], v[86:89], v[50:65]
	v_mul_f32_e64 v12, v136, v12
	v_mul_f32_e64 v13, v136, v13
	v_mul_f32_e64 v10, v136, v10
	v_mul_f32_e64 v11, v136, v11
	v_mul_f32_e64 v8, v136, v8
	v_mul_f32_e64 v9, v136, v9
	v_pk_mul_f32 v[6:7], v[136:137], v[6:7] op_sel_hi:[0,1]
	v_pk_mul_f32 v[4:5], v[136:137], v[4:5] op_sel_hi:[0,1]
	v_pk_mul_f32 v[2:3], v[136:137], v[2:3] op_sel_hi:[0,1]
	v_mfma_f32_32x32x16_bf16 v[50:65], v[182:185], v[82:85], v[50:65]
	s_nop 11
	v_pk_mul_f32 v[50:51], v[116:117], v[50:51]
	v_pk_mul_f32 v[52:53], v[118:119], v[52:53]
	v_pk_mul_f32 v[54:55], v[120:121], v[54:55]
	v_cvt_pk_bf16_f32 v50, v50, v51
	v_pk_mul_f32 v[56:57], v[122:123], v[56:57]
	v_cvt_pk_bf16_f32 v51, v52, v53
	v_cvt_pk_bf16_f32 v52, v54, v55
	v_cndmask_b32_e32 v55, 0, v50, vcc
	v_cmp_lt_i32_e32 vcc, -1, v191
	v_cvt_pk_bf16_f32 v53, v56, v57
	v_pk_mul_f32 v[58:59], v[124:125], v[58:59]
	v_cndmask_b32_e32 v56, 0, v51, vcc
	v_cmp_lt_i32_e32 vcc, -1, v193
	v_cvt_pk_bf16_f32 v54, v58, v59
	v_lshrrev_b32_e32 v50, 16, v50
	v_cndmask_b32_e32 v57, 0, v52, vcc
	v_cmp_lt_i32_e32 vcc, -1, v195
	v_lshrrev_b32_e32 v51, 16, v51
	v_lshrrev_b32_e32 v52, 16, v52
	v_cndmask_b32_e32 v58, 0, v53, vcc
	v_cmp_lt_i32_e32 vcc, -1, v197
	v_lshrrev_b32_e32 v53, 16, v53
	v_pk_mul_f32 v[60:61], v[126:127], v[60:61]
	v_cndmask_b32_e32 v59, 0, v54, vcc
	v_cmp_lt_i32_e32 vcc, -1, v188
	v_lshrrev_b32_e32 v54, 16, v54
	v_pk_mul_f32 v[62:63], v[128:129], v[62:63]
	v_cndmask_b32_e32 v50, 0, v50, vcc
	v_cmp_lt_i32_e32 vcc, -1, v190
	v_perm_b32 v116, v50, v55, s91
	v_cvt_pk_bf16_f32 v50, v60, v61
	v_cndmask_b32_e32 v51, 0, v51, vcc
	v_cmp_lt_i32_e32 vcc, -1, v192
	v_perm_b32 v117, v51, v56, s91
	v_pk_mul_f32 v[64:65], v[130:131], v[64:65]
	v_cndmask_b32_e32 v52, 0, v52, vcc
	v_cmp_lt_i32_e32 vcc, -1, v194
	v_perm_b32 v118, v52, v57, s91
	v_pk_mul_f32 v[60:61], v[136:137], v[44:45] op_sel_hi:[0,1]
	v_cndmask_b32_e32 v53, 0, v53, vcc
	v_cmp_lt_i32_e32 vcc, -1, v196
	v_perm_b32 v119, v53, v58, s91
	v_cvt_pk_bf16_f32 v58, v64, v65
	v_cndmask_b32_e32 v54, 0, v54, vcc
	v_cmp_lt_i32_e32 vcc, -1, v199
	v_perm_b32 v120, v54, v59, s91
	v_cvt_pk_bf16_f32 v54, v62, v63
	v_cndmask_b32_e32 v51, 0, v50, vcc
	v_lshrrev_b32_e32 v50, 16, v50
	v_cmp_lt_i32_e32 vcc, -1, v198
	v_pk_mul_f32 v[64:65], v[136:137], v[48:49] op_sel_hi:[0,1]
	v_pk_mul_f32 v[62:63], v[136:137], v[46:47] op_sel_hi:[0,1]
	v_cndmask_b32_e32 v50, 0, v50, vcc
	v_perm_b32 v121, v50, v51, s91
	v_mul_lo_u32 v50, v137, s87
	v_add_u32_e32 v181, v186, v50
	ds_read2_b64 v[50:53], v181 offset1:2
	v_cmp_lt_i32_e32 vcc, -1, v201
	s_waitcnt lgkmcnt(0)
	v_mfma_f32_32x32x16_bf16 v[18:33], v[50:53], v[116:119], v[18:33]
	v_cndmask_b32_e32 v55, 0, v54, vcc
	v_lshrrev_b32_e32 v54, 16, v54
	v_cmp_lt_i32_e32 vcc, -1, v200
	v_lshrrev_b32_e32 v51, 16, v58
	v_add_u32_e32 v178, 0x1000, v181
	v_cndmask_b32_e32 v54, 0, v54, vcc
	v_cmp_lt_i32_e32 vcc, -1, v203
	v_perm_b32 v122, v54, v55, s91
	ds_read2_b64 v[54:57], v181 offset0:4 offset1:6
	v_cndmask_b32_e32 v50, 0, v58, vcc
	v_cmp_lt_i32_e32 vcc, -1, v202
	v_add_u32_e32 v179, 0x2000, v181
	ds_read2_b64 v[124:127], v179 offset0:128 offset1:130
	v_cndmask_b32_e32 v51, 0, v51, vcc
	v_perm_b32 v123, v51, v50, s91
	ds_read2_b64 v[50:53], v178 offset0:64 offset1:66
	s_waitcnt lgkmcnt(0)
	v_mfma_f32_32x32x16_bf16 v[2:17], v[50:53], v[116:119], v[2:17]
	ds_read2_b64 v[50:53], v178 offset0:68 offset1:70
	v_mul_f32_e64 v58, v136, v42
	v_mul_f32_e64 v59, v136, v43
	v_add_u32_e32 v180, 0x3000, v181
	v_mul_f32_e64 v48, v136, v80
	v_mul_f32_e64 v49, v136, v81
	v_pk_mul_f32 v[46:47], v[136:137], v[78:79] op_sel_hi:[0,1]
	v_pk_mul_f32 v[44:45], v[136:137], v[76:77] op_sel_hi:[0,1]
	v_pk_mul_f32 v[42:43], v[136:137], v[74:75] op_sel_hi:[0,1]
	v_mfma_f32_32x32x16_bf16 v[18:33], v[54:57], v[120:123], v[18:33]
	v_mul_f32_e64 v56, v136, v40
	v_mul_f32_e64 v57, v136, v41
	v_mul_f32_e64 v54, v136, v38
	v_mul_f32_e64 v55, v136, v39
	v_mul_f32_e64 v40, v136, v72
	v_mul_f32_e64 v41, v136, v73
	v_pk_mul_f32 v[38:39], v[136:137], v[70:71] op_sel_hi:[0,1]
	s_waitcnt lgkmcnt(0)
	v_mfma_f32_32x32x16_bf16 v[2:17], v[50:53], v[120:123], v[2:17]
	v_mul_f32_e64 v52, v136, v36
	v_mul_f32_e64 v53, v136, v37
	v_mul_f32_e64 v50, v136, v34
	v_mul_f32_e64 v51, v136, v35
	ds_read2_b64 v[34:37], v179 offset0:132 offset1:134
	s_nop 0
	v_mfma_f32_32x32x16_bf16 v[50:65], v[124:127], v[116:119], v[50:65]
	ds_read2_b64 v[124:127], v180 offset0:192 offset1:194
	s_waitcnt lgkmcnt(1)
	v_mfma_f32_32x32x16_bf16 v[50:65], v[34:37], v[120:123], v[50:65]
	v_mul_f32_e64 v36, v136, v68
	v_mul_f32_e64 v37, v136, v69
	v_mul_f32_e64 v34, v136, v66
	v_mul_f32_e64 v35, v136, v67
	ds_read2_b64 v[66:69], v180 offset0:196 offset1:198
	s_waitcnt lgkmcnt(1)
	v_mfma_f32_32x32x16_bf16 v[34:49], v[124:127], v[116:119], v[34:49]
	s_waitcnt lgkmcnt(0)
	v_mfma_f32_32x32x16_bf16 v[34:49], v[66:69], v[120:123], v[34:49]
	s_cbranch_scc1 .LBB0_681
; #define LAS __attribute__((address_space(3)))
; __device__ __forceinline__ int crow(int r, int hi) { return (r & 3) + 8 * (r >> 2) + 4 * hi; }
; __device__ __forceinline__ float ex2f(float x) { return __builtin_amdgcn_exp2f(x); }
; #define MFMA32(a, b, c) __builtin_amdgcn_mfma_f32_32x32x16_bf16((a), (b), (c), 0, 0, 0)
; __device__ __forceinline__ void ret_out_item(LAS unsigned char* lds, const bf16* Z, const bf16* AT, const float* gn, bf16* MIXED, int b, int c, const float* lgs) {
;     ...
;     for (int mb = 0; mb < 2; ++mb) {
;         if (mb <= lb) {
;             f32x16 st;
; #pragma unroll
;             for (int r = 0; r < 16; ++r) st[r] = 0.f;
; #pragma unroll
;             for (int ds = 0; ds < 8; ++ds) { const bf16x8 kf = *(const bf16x8*)(Z + (size_t)(rowbase + 32 * mb + r32) * NZ + ZC_RK + hh * 128 + 16 * ds + 8 * hi); st = MFMA32(kf, qf[ds], st); }
; #pragma unroll
;             for (int r = 0; r < 16; ++r) { const int m = 32 * mb + crow(r, hi), diff = l - m; st[r] = diff >= 0 ? st[r] * ex2f((float)diff * lg) : 0.f; }
;             const bf16x8 pf0 = pack8(st, 0), pf1 = pack8(st, 8);
; #pragma unroll
;             for (int eb = 0; eb < 4; ++eb)
; #pragma unroll
;                 for (int kk = 0; kk < 2; ++kk) { const LAS bf16* vp = VT4 + (hh * 128 + 32 * eb + r32) * 72 + 16 * (2 * mb + kk) + 4 * hi;
;                     const u32x2 lo = *(const LAS u32x2*)vp, h2 = *(const LAS u32x2*)(vp + 8); const u32x4 v4 = (u32x4){lo.x, lo.y, h2.x, h2.y};
;                     acc[eb] = MFMA32(__builtin_bit_cast(bf16x8, v4), kk ? pf1 : pf0, acc[eb]); }
	v_lshl_add_u64 v[66:67], s[6:7], 1, v[114:115]
	v_lshlrev_b32_e32 v68, 1, v138
	v_mov_b32_e32 v69, v0
	v_lshl_add_u64 v[70:71], v[66:67], 0, v[68:69]
	v_add_co_u32_e32 v66, vcc, 0x28000, v70
	s_mov_b64 s[12:13], 0x28740
	s_nop 0
	v_addc_co_u32_e32 v67, vcc, 0, v71, vcc
	global_load_dwordx4 v[66:69], v[66:67], off offset:1856
	v_lshl_add_u64 v[70:71], v[70:71], 0, s[12:13]
	global_load_dwordx4 v[182:185], v[70:71], off offset:32
	global_load_dwordx4 v[134:137], v[70:71], off offset:64
	global_load_dwordx4 v[130:133], v[70:71], off offset:96
	global_load_dwordx4 v[126:129], v[70:71], off offset:128
	global_load_dwordx4 v[122:125], v[70:71], off offset:160
	global_load_dwordx4 v[118:121], v[70:71], off offset:192
	global_load_dwordx4 v[114:117], v[70:71], off offset:224
	v_mul_i32_i24_e32 v70, -4, v143
	v_subrev_u32_e32 v143, 32, v144
	v_add_u32_e32 v144, v143, v145
	v_add_u32_e32 v145, v143, v70
	v_add_u32_e32 v146, v143, v146
	v_add_u32_e32 v147, v143, v147
	v_add_u32_e32 v148, v143, v148
	v_add_u32_e32 v149, v143, v149
	v_add_u32_e32 v150, v143, v150
	v_add_u32_e32 v151, v143, v151
	v_add_u32_e32 v154, v143, v154
	v_add_u32_e32 v155, v143, v155
	v_add_u32_e32 v156, v143, v156
	v_add_u32_e32 v158, v143, v158
	v_add_u32_e32 v159, v143, v159
	v_add_u32_e32 v160, v143, v160
	v_add_u32_e32 v176, v143, v176
	ds_read2_b64 v[186:189], v181 offset0:8 offset1:10
	ds_read2_b64 v[190:193], v181 offset0:12 offset1:14
	ds_read2_b64 v[194:197], v178 offset0:72 offset1:74
	ds_read2_b64 v[198:201], v179 offset0:136 offset1:138
	v_cvt_f32_u32_e32 v181, v148
	v_cmp_lt_i32_e32 vcc, -1, v145
	s_waitcnt vmcnt(0) lgkmcnt(0)
	v_mfma_f32_32x32x16_bf16 v[66:81], v[66:69], v[110:113], 0
	v_cvt_f32_u32_e32 v111, v145
	v_cvt_f32_u32_e32 v112, v144
	v_add_u32_e32 v110, v143, v177
	v_cvt_f32_u32_e32 v113, v147
	v_cvt_f32_u32_e32 v143, v146
	v_cvt_f32_u32_e32 v177, v149
	v_mfma_f32_32x32x16_bf16 v[66:81], v[182:185], v[102:105], v[66:81]
	v_cvt_f32_u32_e32 v102, v151
	v_cvt_f32_u32_e32 v103, v150
	v_cvt_f32_u32_e32 v104, v155
	v_cvt_f32_u32_e32 v105, v154
	v_cvt_f32_u32_e32 v182, v158
	v_cvt_f32_u32_e32 v183, v156
	v_cvt_f32_u32_e32 v184, v160
	v_mfma_f32_32x32x16_bf16 v[66:81], v[134:137], v[106:109], v[66:81]
	v_mul_f32_e32 v109, v1, v111
	v_mul_f32_e32 v111, v1, v112
	v_cvt_f32_u32_e32 v106, v159
	v_cvt_f32_u32_e32 v107, v110
	v_cvt_f32_u32_e32 v108, v176
	v_mul_f32_e32 v112, v1, v113
	v_mul_f32_e32 v113, v1, v143
	v_mfma_f32_32x32x16_bf16 v[66:81], v[130:133], v[98:101], v[66:81]
	v_mul_f32_e32 v98, v1, v177
	v_mul_f32_e32 v99, v1, v181
	v_mul_f32_e32 v100, v1, v102
	v_mul_f32_e32 v101, v1, v103
	v_mul_f32_e32 v102, v1, v104
	v_mul_f32_e32 v103, v1, v105
	v_mul_f32_e32 v104, v1, v182
	v_mfma_f32_32x32x16_bf16 v[66:81], v[126:129], v[94:97], v[66:81]
	v_exp_f32_e32 v94, v109
	v_exp_f32_e32 v95, v111
	v_mul_f32_e32 v105, v1, v183
	v_exp_f32_e32 v96, v100
	v_exp_f32_e32 v97, v101
	v_mul_f32_e32 v126, v1, v184
	v_mul_f32_e32 v106, v1, v106
	v_mfma_f32_32x32x16_bf16 v[66:81], v[122:125], v[90:93], v[66:81]
	v_exp_f32_e32 v90, v112
	v_exp_f32_e32 v91, v113
	v_exp_f32_e32 v92, v98
	v_exp_f32_e32 v93, v99
	v_exp_f32_e32 v98, v102
	v_exp_f32_e32 v99, v103
	v_mul_f32_e32 v107, v1, v107
	v_mfma_f32_32x32x16_bf16 v[66:81], v[118:121], v[86:89], v[66:81]
	v_mul_f32_e32 v1, v1, v108
	v_exp_f32_e32 v86, v104
	v_exp_f32_e32 v87, v105
	v_exp_f32_e32 v101, v1
	v_exp_f32_e32 v88, v126
	v_exp_f32_e32 v89, v106
	v_exp_f32_e32 v100, v107
	v_mfma_f32_32x32x16_bf16 v[66:81], v[114:117], v[82:85], v[66:81]
	s_nop 11
	v_pk_mul_f32 v[66:67], v[94:95], v[66:67]
	v_pk_mul_f32 v[68:69], v[90:91], v[68:69]
	v_cvt_pk_bf16_f32 v1, v66, v67
	v_pk_mul_f32 v[70:71], v[92:93], v[70:71]
	v_pk_mul_f32 v[74:75], v[98:99], v[74:75]
	v_cvt_pk_bf16_f32 v66, v68, v69
	v_cndmask_b32_e32 v69, 0, v1, vcc
	v_cmp_lt_i32_e32 vcc, -1, v147
	v_pk_mul_f32 v[72:73], v[96:97], v[72:73]
	v_cvt_pk_bf16_f32 v67, v70, v71
	v_cvt_pk_bf16_f32 v70, v74, v75
	v_cndmask_b32_e32 v74, 0, v66, vcc
	v_cmp_lt_i32_e32 vcc, -1, v149
	v_pk_mul_f32 v[76:77], v[86:87], v[76:77]
	v_cvt_pk_bf16_f32 v68, v72, v73
	v_cndmask_b32_e32 v75, 0, v67, vcc
	v_cmp_lt_i32_e32 vcc, -1, v151
	v_cvt_pk_bf16_f32 v71, v76, v77
	v_lshrrev_b32_e32 v1, 16, v1
	v_cndmask_b32_e32 v76, 0, v68, vcc
	v_cmp_lt_i32_e32 vcc, -1, v155
	v_pk_mul_f32 v[78:79], v[88:89], v[78:79]
	v_lshrrev_b32_e32 v66, 16, v66
	v_cndmask_b32_e32 v77, 0, v70, vcc
	v_cmp_lt_i32_e32 vcc, -1, v144
	v_cvt_pk_bf16_f32 v72, v78, v79
	v_lshrrev_b32_e32 v67, 16, v67
	v_cndmask_b32_e32 v1, 0, v1, vcc
	v_cmp_lt_i32_e32 vcc, -1, v146
	v_pk_mul_f32 v[80:81], v[100:101], v[80:81]
	v_lshrrev_b32_e32 v68, 16, v68
	v_cndmask_b32_e32 v78, 0, v66, vcc
	v_cmp_lt_i32_e32 vcc, -1, v148
	v_cvt_pk_bf16_f32 v73, v80, v81
	v_perm_b32 v66, v1, v69, s91
	v_cndmask_b32_e32 v79, 0, v67, vcc
	v_cmp_lt_i32_e32 vcc, -1, v150
	v_perm_b32 v67, v78, v74, s91
	v_lshrrev_b32_e32 v1, 16, v70
	v_cndmask_b32_e32 v80, 0, v68, vcc
	v_cmp_lt_i32_e32 vcc, -1, v158
	v_perm_b32 v68, v79, v75, s91
	v_perm_b32 v69, v80, v76, s91
	v_cndmask_b32_e32 v74, 0, v71, vcc
	v_cmp_lt_i32_e32 vcc, -1, v160
	v_lshrrev_b32_e32 v70, 16, v71
	v_lshrrev_b32_e32 v71, 16, v72
	v_cndmask_b32_e32 v75, 0, v72, vcc
	v_cmp_lt_i32_e32 vcc, -1, v110
	v_lshrrev_b32_e32 v72, 16, v73
	v_mfma_f32_32x32x16_bf16 v[2:17], v[194:197], v[66:69], v[2:17]
	v_cndmask_b32_e32 v76, 0, v73, vcc
	v_cmp_lt_i32_e32 vcc, -1, v154
	s_nop 1
	v_cndmask_b32_e32 v1, 0, v1, vcc
	v_cmp_lt_i32_e32 vcc, -1, v156
	v_mfma_f32_32x32x16_bf16 v[50:65], v[198:201], v[66:69], v[50:65]
	s_nop 0
	v_cndmask_b32_e32 v73, 0, v70, vcc
	v_cmp_lt_i32_e32 vcc, -1, v159
	v_perm_b32 v70, v1, v77, s91
	s_nop 0
	v_cndmask_b32_e32 v78, 0, v71, vcc
	v_cmp_lt_i32_e32 vcc, -1, v176
	v_perm_b32 v71, v73, v74, s91
	v_mfma_f32_32x32x16_bf16 v[18:33], v[186:189], v[66:69], v[18:33]
	v_cndmask_b32_e32 v79, 0, v72, vcc
	v_perm_b32 v72, v78, v75, s91
	v_perm_b32 v73, v79, v76, s91
	ds_read2_b64 v[74:77], v178 offset0:76 offset1:78
	s_waitcnt lgkmcnt(0)
	v_mfma_f32_32x32x16_bf16 v[2:17], v[74:77], v[70:73], v[2:17]
	ds_read2_b64 v[74:77], v179 offset0:140 offset1:142
	s_waitcnt lgkmcnt(0)
	v_mfma_f32_32x32x16_bf16 v[50:65], v[74:77], v[70:73], v[50:65]
	ds_read2_b64 v[74:77], v180 offset0:200 offset1:202
	s_waitcnt lgkmcnt(0)
	v_mfma_f32_32x32x16_bf16 v[34:49], v[74:77], v[66:69], v[34:49]
	ds_read2_b64 v[66:69], v180 offset0:204 offset1:206
	v_mfma_f32_32x32x16_bf16 v[18:33], v[190:193], v[70:73], v[18:33]
	s_waitcnt lgkmcnt(0)
	v_mfma_f32_32x32x16_bf16 v[34:49], v[66:69], v[70:73], v[34:49]
; __device__ __forceinline__ float half_sum(float v) { auto rr = __builtin_amdgcn_permlane32_swap(__float_as_uint(v), __float_as_uint(v), false, false); return __uint_as_float(rr[0]) + __uint_as_float(rr[1]); }
; __device__ __forceinline__ void ret_out_item(LAS unsigned char* lds, const bf16* Z, const bf16* AT, const float* gn, bf16* MIXED, int b, int c, const float* lgs) {
;     ...
;     float s = 0.f;
; #pragma unroll
;     for (int i = 0; i < 4; ++i)
; #pragma unroll
;         for (int r = 0; r < 16; ++r) s += acc[i][r];
;     s = half_sum(s); const float mean = s * (1.f / 128.f); float v = 0.f;
; #pragma unroll
;     for (int i = 0; i < 4; ++i)
; #pragma unroll
;         for (int r = 0; r < 16; ++r) { const float dd = acc[i][r] - mean; v += dd * dd; }
;     v = half_sum(v); const float rstd = rsqrtf(v * (1.f / 128.f) + EPS);
; #pragma unroll
;     for (int eb = 0; eb < 4; ++eb)
; #pragma unroll
;         for (int rg = 0; rg < 4; ++rg) { const int e0 = 32 * eb + 8 * rg + 4 * hi;
;             const u32x2 gt = *(const u32x2*)(Z + (size_t)row * NZ + ZC_RG + hh * 128 + e0); const f32x4 gg = *(const f32x4*)(gn + hh * 128 + e0);
.LBB0_681:
	v_mov_b64_e32 v[66:67], s[4:5]
	v_mad_u64_u32 v[66:67], s[4:5], v142, s74, v[66:67]
	v_lshl_add_u64 v[72:73], v[66:67], 0, s[8:9]
	v_lshl_add_u64 v[74:75], v[72:73], 0, v[138:139]
	global_load_dwordx2 v[76:77], v[74:75], off offset:3904
	s_nop 4
	v_add_f32_e32 v1, 0, v18
	v_add_f32_e32 v1, v19, v1
	v_add_f32_e32 v1, v20, v1
	v_add_f32_e32 v1, v21, v1
	v_add_f32_e32 v1, v22, v1
	v_add_f32_e32 v1, v23, v1
	v_add_f32_e32 v1, v24, v1
	v_add_f32_e32 v1, v25, v1
	v_add_f32_e32 v1, v26, v1
	v_add_f32_e32 v1, v27, v1
	v_add_f32_e32 v1, v28, v1
	v_add_f32_e32 v1, v29, v1
	v_add_f32_e32 v1, v30, v1
	v_add_f32_e32 v1, v31, v1
	v_add_f32_e32 v1, v32, v1
	v_add_f32_e32 v1, v33, v1
	v_add_f32_e32 v1, v2, v1
	v_add_f32_e32 v1, v3, v1
	v_add_f32_e32 v1, v4, v1
	v_add_f32_e32 v1, v5, v1
	v_add_f32_e32 v1, v6, v1
	v_add_f32_e32 v1, v7, v1
	v_add_f32_e32 v1, v8, v1
	v_add_f32_e32 v1, v9, v1
	v_add_f32_e32 v1, v10, v1
	v_add_f32_e32 v1, v11, v1
	v_add_f32_e32 v1, v12, v1
	v_add_f32_e32 v1, v13, v1
	v_add_f32_e32 v1, v14, v1
	v_add_f32_e32 v1, v15, v1
	v_add_f32_e32 v1, v16, v1
	v_add_f32_e32 v1, v17, v1
	v_add_f32_e32 v1, v50, v1
	v_add_f32_e32 v1, v51, v1
	v_add_f32_e32 v1, v52, v1
	v_add_f32_e32 v1, v53, v1
	v_add_f32_e32 v1, v54, v1
	v_add_f32_e32 v1, v55, v1
	v_add_f32_e32 v1, v56, v1
	v_add_f32_e32 v1, v57, v1
	v_add_f32_e32 v1, v58, v1
	v_add_f32_e32 v1, v59, v1
	v_add_f32_e32 v1, v60, v1
	v_add_f32_e32 v1, v61, v1
	v_add_f32_e32 v1, v62, v1
	v_add_f32_e32 v1, v63, v1
	v_add_f32_e32 v1, v64, v1
	v_add_f32_e32 v1, v65, v1
	v_add_f32_e32 v1, v34, v1
	v_add_f32_e32 v1, v35, v1
	v_add_f32_e32 v1, v36, v1
	v_add_f32_e32 v1, v37, v1
	v_add_f32_e32 v1, v38, v1
	v_add_f32_e32 v1, v39, v1
	v_add_f32_e32 v1, v40, v1
	v_add_f32_e32 v1, v41, v1
	v_add_f32_e32 v1, v42, v1
	v_add_f32_e32 v1, v43, v1
	v_add_f32_e32 v1, v44, v1
	v_add_f32_e32 v1, v45, v1
	v_add_f32_e32 v1, v46, v1
	v_add_f32_e32 v1, v47, v1
	v_add_f32_e32 v1, v48, v1
	v_add_f32_e32 v1, v49, v1
	v_mov_b32_e32 v66, v1
	s_lshl_b64 s[4:5], s[6:7], 2
	s_nop 0
	v_permlane32_swap_b32_e32 v1, v66
	v_mov_b32_e32 v143, v0
	s_add_u32 s4, s11, s4
	v_add_f32_e32 v1, v1, v66
	s_addc_u32 s5, s10, s5
	v_lshlrev_b64 v[66:67], 11, v[142:143]
	v_mul_f32_e32 v110, 0x3c000000, v1
	v_lshl_add_u64 v[66:67], s[2:3], 0, v[66:67]
	v_lshl_add_u64 v[70:71], s[4:5], 0, v[140:141]
	v_lshl_add_u64 v[104:105], v[66:67], 0, s[8:9]
	global_load_dwordx4 v[66:69], v[70:71], off
	v_pk_add_f32 v[106:107], v[18:19], v[110:111] op_sel_hi:[1,0] neg_lo:[0,1] neg_hi:[0,1]
	s_waitcnt vmcnt(0) lgkmcnt(0)
	v_lshlrev_b32_e32 v108, 16, v76
	v_and_b32_e32 v109, 0xffff0000, v76
	v_mul_f32_e32 v1, 0xbfb8aa3b, v108
	v_exp_f32_e32 v1, v1
	v_mul_f32_e32 v19, 0xbfb8aa3b, v109
	v_and_b32_e32 v117, 0xffff0000, v77
	v_pk_add_f32 v[102:103], v[20:21], v[110:111] op_sel_hi:[1,0] neg_lo:[0,1] neg_hi:[0,1]
	v_exp_f32_e32 v20, v19
	v_mul_f32_e32 v21, 0xbfb8aa3b, v117
	v_exp_f32_e32 v21, v21
	v_mul_f32_e32 v18, v107, v107
	v_pk_fma_f32 v[18:19], v[106:107], v[106:107], v[18:19] op_sel_hi:[1,1,0]
	v_add_f32_e32 v1, 1.0, v1
	v_rcp_f32_e32 v114, v1
	v_add_f32_e32 v1, 1.0, v20
	v_pk_fma_f32 v[18:19], v[102:103], v[102:103], v[18:19]
	v_mul_f32_e32 v20, v103, v103
	v_pk_add_f32 v[18:19], v[20:21], v[18:19] op_sel_hi:[0,1]
	v_pk_add_f32 v[112:113], v[22:23], v[110:111] op_sel_hi:[1,0] neg_lo:[0,1] neg_hi:[0,1]
	v_pk_add_f32 v[100:101], v[24:25], v[110:111] op_sel_hi:[1,0] neg_lo:[0,1] neg_hi:[0,1]
	v_pk_fma_f32 v[18:19], v[112:113], v[112:113], v[18:19]
	v_mul_f32_e32 v20, v113, v113
	v_pk_add_f32 v[18:19], v[20:21], v[18:19] op_sel_hi:[0,1]
	v_pk_fma_f32 v[18:19], v[100:101], v[100:101], v[18:19]
	v_mul_f32_e32 v20, v101, v101
	v_pk_add_f32 v[18:19], v[20:21], v[18:19] op_sel_hi:[0,1]
	v_pk_add_f32 v[98:99], v[26:27], v[110:111] op_sel_hi:[1,0] neg_lo:[0,1] neg_hi:[0,1]
	v_pk_add_f32 v[96:97], v[28:29], v[110:111] op_sel_hi:[1,0] neg_lo:[0,1] neg_hi:[0,1]
	v_pk_fma_f32 v[18:19], v[98:99], v[98:99], v[18:19]
	v_mul_f32_e32 v20, v99, v99
	v_pk_add_f32 v[18:19], v[20:21], v[18:19] op_sel_hi:[0,1]
	v_pk_fma_f32 v[18:19], v[96:97], v[96:97], v[18:19]
	v_mul_f32_e32 v20, v97, v97
	v_pk_add_f32 v[18:19], v[20:21], v[18:19] op_sel_hi:[0,1]
	v_pk_add_f32 v[94:95], v[30:31], v[110:111] op_sel_hi:[1,0] neg_lo:[0,1] neg_hi:[0,1]
	v_pk_add_f32 v[92:93], v[32:33], v[110:111] op_sel_hi:[1,0] neg_lo:[0,1] neg_hi:[0,1]
	v_pk_fma_f32 v[18:19], v[94:95], v[94:95], v[18:19]
	v_mul_f32_e32 v20, v95, v95
	v_pk_add_f32 v[18:19], v[20:21], v[18:19] op_sel_hi:[0,1]
	v_pk_fma_f32 v[18:19], v[92:93], v[92:93], v[18:19]
	v_mul_f32_e32 v20, v93, v93
	v_pk_add_f32 v[18:19], v[20:21], v[18:19] op_sel_hi:[0,1]
	v_pk_add_f32 v[90:91], v[2:3], v[110:111] op_sel_hi:[1,0] neg_lo:[0,1] neg_hi:[0,1]
	v_pk_add_f32 v[88:89], v[4:5], v[110:111] op_sel_hi:[1,0] neg_lo:[0,1] neg_hi:[0,1]
	v_pk_fma_f32 v[2:3], v[90:91], v[90:91], v[18:19]
	v_mul_f32_e32 v4, v91, v91
	v_pk_add_f32 v[2:3], v[4:5], v[2:3] op_sel_hi:[0,1]
	v_pk_fma_f32 v[2:3], v[88:89], v[88:89], v[2:3]
	v_mul_f32_e32 v4, v89, v89
	v_pk_add_f32 v[2:3], v[4:5], v[2:3] op_sel_hi:[0,1]
	v_pk_add_f32 v[86:87], v[6:7], v[110:111] op_sel_hi:[1,0] neg_lo:[0,1] neg_hi:[0,1]
	v_pk_add_f32 v[84:85], v[8:9], v[110:111] op_sel_hi:[1,0] neg_lo:[0,1] neg_hi:[0,1]
	v_pk_fma_f32 v[2:3], v[86:87], v[86:87], v[2:3]
	v_mul_f32_e32 v4, v87, v87
	v_pk_add_f32 v[2:3], v[4:5], v[2:3] op_sel_hi:[0,1]
	v_pk_fma_f32 v[2:3], v[84:85], v[84:85], v[2:3]
	v_mul_f32_e32 v4, v85, v85
	v_pk_add_f32 v[2:3], v[4:5], v[2:3] op_sel_hi:[0,1]
	v_pk_add_f32 v[82:83], v[10:11], v[110:111] op_sel_hi:[1,0] neg_lo:[0,1] neg_hi:[0,1]
	v_pk_add_f32 v[80:81], v[12:13], v[110:111] op_sel_hi:[1,0] neg_lo:[0,1] neg_hi:[0,1]
; __device__ __forceinline__ float bflo(unsigned w) { return __uint_as_float(w << 16); }
; __device__ __forceinline__ float bfhi(unsigned w) { return __uint_as_float(w & 0xffff0000u); }
; __device__ __forceinline__ unsigned pk2(float lo, float hi) { const f32x2 v = {lo, hi}; return __builtin_bit_cast(unsigned, __builtin_convertvector(v, bf16x2_t)); }
; __device__ __forceinline__ float half_sum(float v) { auto rr = __builtin_amdgcn_permlane32_swap(__float_as_uint(v), __float_as_uint(v), false, false); return __uint_as_float(rr[0]) + __uint_as_float(rr[1]); }
; __device__ __forceinline__ float silu(float x) { return x * __builtin_amdgcn_rcpf(1.f + __builtin_amdgcn_exp2f(-1.4426950408889634f * x)); }
; __device__ __forceinline__ void ret_out_item(LAS unsigned char* lds, const bf16* Z, const bf16* AT, const float* gn, bf16* MIXED, int b, int c, const float* lgs) {
;     ...
;     s = half_sum(s); const float mean = s * (1.f / 128.f); float v = 0.f;
; #pragma unroll
;     for (int i = 0; i < 4; ++i)
; #pragma unroll
;         for (int r = 0; r < 16; ++r) { const float dd = acc[i][r] - mean; v += dd * dd; }
;     v = half_sum(v); const float rstd = rsqrtf(v * (1.f / 128.f) + EPS);
; #pragma unroll
;     for (int eb = 0; eb < 4; ++eb)
; #pragma unroll
;         for (int rg = 0; rg < 4; ++rg) { const int e0 = 32 * eb + 8 * rg + 4 * hi;
;             const u32x2 gt = *(const u32x2*)(Z + (size_t)row * NZ + ZC_RG + hh * 128 + e0); const f32x4 gg = *(const f32x4*)(gn + hh * 128 + e0);
;             const float y0 = (acc[eb][4 * rg] - mean) * rstd * gg.x * silu(bflo(gt.x)), y1 = (acc[eb][4 * rg + 1] - mean) * rstd * gg.y * silu(bfhi(gt.x));
;             const float y2 = (acc[eb][4 * rg + 2] - mean) * rstd * gg.z * silu(bflo(gt.y)), y3 = (acc[eb][4 * rg + 3] - mean) * rstd * gg.w * silu(bfhi(gt.y));
;             u32x2 w; w.x = pk2(y0, y1); w.y = pk2(y2, y3); *(u32x2*)(MIXED + (size_t)row * 1024 + 512 + hh * 128 + e0) = w; }
	v_pk_fma_f32 v[2:3], v[82:83], v[82:83], v[2:3]
	v_mul_f32_e32 v4, v83, v83
	v_pk_add_f32 v[2:3], v[4:5], v[2:3] op_sel_hi:[0,1]
	v_pk_fma_f32 v[2:3], v[80:81], v[80:81], v[2:3]
	v_mul_f32_e32 v4, v81, v81
	v_pk_add_f32 v[2:3], v[4:5], v[2:3] op_sel_hi:[0,1]
	v_pk_add_f32 v[78:79], v[14:15], v[110:111] op_sel_hi:[1,0] neg_lo:[0,1] neg_hi:[0,1]
	v_lshlrev_b32_e32 v116, 16, v77
	v_pk_fma_f32 v[2:3], v[78:79], v[78:79], v[2:3]
	v_mul_f32_e32 v4, v79, v79
	v_pk_add_f32 v[76:77], v[16:17], v[110:111] op_sel_hi:[1,0] neg_lo:[0,1] neg_hi:[0,1]
	v_pk_add_f32 v[2:3], v[4:5], v[2:3] op_sel_hi:[0,1]
	v_pk_fma_f32 v[2:3], v[76:77], v[76:77], v[2:3]
	v_mul_f32_e32 v4, v77, v77
	v_pk_add_f32 v[2:3], v[4:5], v[2:3] op_sel_hi:[0,1]
	v_pk_add_f32 v[50:51], v[50:51], v[110:111] op_sel_hi:[1,0] neg_lo:[0,1] neg_hi:[0,1]
	v_pk_add_f32 v[32:33], v[52:53], v[110:111] op_sel_hi:[1,0] neg_lo:[0,1] neg_hi:[0,1]
	v_pk_fma_f32 v[2:3], v[50:51], v[50:51], v[2:3]
	v_mul_f32_e32 v4, v51, v51
	v_pk_add_f32 v[2:3], v[4:5], v[2:3] op_sel_hi:[0,1]
	v_pk_fma_f32 v[2:3], v[32:33], v[32:33], v[2:3]
	v_mul_f32_e32 v4, v33, v33
	v_pk_add_f32 v[2:3], v[4:5], v[2:3] op_sel_hi:[0,1]
	v_pk_add_f32 v[30:31], v[54:55], v[110:111] op_sel_hi:[1,0] neg_lo:[0,1] neg_hi:[0,1]
	v_pk_add_f32 v[28:29], v[56:57], v[110:111] op_sel_hi:[1,0] neg_lo:[0,1] neg_hi:[0,1]
	v_pk_fma_f32 v[2:3], v[30:31], v[30:31], v[2:3]
	v_mul_f32_e32 v4, v31, v31
	v_pk_add_f32 v[2:3], v[4:5], v[2:3] op_sel_hi:[0,1]
	v_pk_fma_f32 v[2:3], v[28:29], v[28:29], v[2:3]
	v_mul_f32_e32 v4, v29, v29
	v_rcp_f32_e32 v115, v1
	v_mul_f32_e32 v1, 0xbfb8aa3b, v116
	v_pk_add_f32 v[2:3], v[4:5], v[2:3] op_sel_hi:[0,1]
	v_pk_add_f32 v[26:27], v[58:59], v[110:111] op_sel_hi:[1,0] neg_lo:[0,1] neg_hi:[0,1]
	v_exp_f32_e32 v1, v1
	v_pk_fma_f32 v[2:3], v[26:27], v[26:27], v[2:3]
	v_mul_f32_e32 v4, v27, v27
	v_pk_add_f32 v[24:25], v[60:61], v[110:111] op_sel_hi:[1,0] neg_lo:[0,1] neg_hi:[0,1]
	v_pk_add_f32 v[2:3], v[4:5], v[2:3] op_sel_hi:[0,1]
	v_pk_fma_f32 v[2:3], v[24:25], v[24:25], v[2:3]
	v_mul_f32_e32 v4, v25, v25
	v_pk_add_f32 v[2:3], v[4:5], v[2:3] op_sel_hi:[0,1]
	v_pk_add_f32 v[22:23], v[62:63], v[110:111] op_sel_hi:[1,0] neg_lo:[0,1] neg_hi:[0,1]
	v_add_f32_e32 v1, 1.0, v1
	v_pk_fma_f32 v[2:3], v[22:23], v[22:23], v[2:3]
	v_mul_f32_e32 v4, v23, v23
	v_rcp_f32_e32 v118, v1
	v_add_f32_e32 v1, 1.0, v21
	v_pk_add_f32 v[20:21], v[64:65], v[110:111] op_sel_hi:[1,0] neg_lo:[0,1] neg_hi:[0,1]
	v_pk_add_f32 v[2:3], v[4:5], v[2:3] op_sel_hi:[0,1]
	v_pk_fma_f32 v[2:3], v[20:21], v[20:21], v[2:3]
	v_mul_f32_e32 v4, v21, v21
	v_pk_add_f32 v[2:3], v[4:5], v[2:3] op_sel_hi:[0,1]
	v_pk_add_f32 v[18:19], v[34:35], v[110:111] op_sel_hi:[1,0] neg_lo:[0,1] neg_hi:[0,1]
	v_pk_add_f32 v[16:17], v[36:37], v[110:111] op_sel_hi:[1,0] neg_lo:[0,1] neg_hi:[0,1]
	v_pk_fma_f32 v[2:3], v[18:19], v[18:19], v[2:3]
	v_mul_f32_e32 v4, v19, v19
	v_pk_add_f32 v[2:3], v[4:5], v[2:3] op_sel_hi:[0,1]
	v_pk_fma_f32 v[2:3], v[16:17], v[16:17], v[2:3]
	v_mul_f32_e32 v4, v17, v17
	v_pk_add_f32 v[2:3], v[4:5], v[2:3] op_sel_hi:[0,1]
	v_pk_add_f32 v[14:15], v[38:39], v[110:111] op_sel_hi:[1,0] neg_lo:[0,1] neg_hi:[0,1]
	v_pk_add_f32 v[12:13], v[40:41], v[110:111] op_sel_hi:[1,0] neg_lo:[0,1] neg_hi:[0,1]
	v_pk_fma_f32 v[2:3], v[14:15], v[14:15], v[2:3]
	v_mul_f32_e32 v4, v15, v15
	v_pk_add_f32 v[2:3], v[4:5], v[2:3] op_sel_hi:[0,1]
	v_pk_fma_f32 v[2:3], v[12:13], v[12:13], v[2:3]
	v_mul_f32_e32 v4, v13, v13
	v_pk_add_f32 v[2:3], v[4:5], v[2:3] op_sel_hi:[0,1]
	v_pk_add_f32 v[10:11], v[42:43], v[110:111] op_sel_hi:[1,0] neg_lo:[0,1] neg_hi:[0,1]
	v_pk_add_f32 v[8:9], v[44:45], v[110:111] op_sel_hi:[1,0] neg_lo:[0,1] neg_hi:[0,1]
	v_pk_fma_f32 v[2:3], v[10:11], v[10:11], v[2:3]
	v_mul_f32_e32 v4, v11, v11
	v_pk_add_f32 v[2:3], v[4:5], v[2:3] op_sel_hi:[0,1]
	v_pk_fma_f32 v[2:3], v[8:9], v[8:9], v[2:3]
	v_mul_f32_e32 v4, v9, v9
	v_pk_add_f32 v[2:3], v[4:5], v[2:3] op_sel_hi:[0,1]
	v_pk_add_f32 v[4:5], v[46:47], v[110:111] op_sel_hi:[1,0] neg_lo:[0,1] neg_hi:[0,1]
	v_pk_add_f32 v[48:49], v[48:49], v[110:111] op_sel_hi:[1,0] neg_lo:[0,1] neg_hi:[0,1]
	v_pk_fma_f32 v[2:3], v[4:5], v[4:5], v[2:3]
	v_mul_f32_e32 v6, v5, v5
	v_pk_add_f32 v[2:3], v[6:7], v[2:3] op_sel_hi:[0,1]
	v_pk_fma_f32 v[2:3], v[48:49], v[48:49], v[2:3]
	v_mul_f32_e32 v6, v49, v49
	v_pk_add_f32 v[2:3], v[6:7], v[2:3] op_sel_hi:[0,1]
	v_rcp_f32_e32 v119, v1
	v_mov_b32_e32 v1, v2
	s_nop 1
	v_permlane32_swap_b32_e32 v2, v1
	v_add_f32_e32 v1, v2, v1
	v_fmamk_f32 v1, v1, 0x3c000000, v152
	v_mul_f32_e32 v2, 0x4b800000, v1
	v_cmp_gt_f32_e32 vcc, s66, v1
	v_pk_mul_f32 v[34:35], v[118:119], v[116:117]
	v_lshl_add_u64 v[38:39], v[104:105], 0, v[138:139]
	v_cndmask_b32_e32 v1, v1, v2, vcc
	v_rsq_f32_e32 v1, v1
	v_pk_mul_f32 v[2:3], v[114:115], v[108:109]
	s_mov_b32 s2, 0x2600000
	v_mul_f32_e32 v6, 0x45800000, v1
	v_cndmask_b32_e32 v6, v1, v6, vcc
	v_pk_mul_f32 v[36:37], v[106:107], v[6:7] op_sel_hi:[1,0]
	s_nop 0
	v_pk_mul_f32 v[36:37], v[66:67], v[36:37]
	s_nop 0
	v_pk_mul_f32 v[2:3], v[2:3], v[36:37]
	v_pk_mul_f32 v[36:37], v[102:103], v[6:7] op_sel_hi:[1,0]
	v_cvt_pk_bf16_f32 v2, v2, v3
	v_pk_mul_f32 v[36:37], v[68:69], v[36:37]
	s_nop 0
	v_pk_mul_f32 v[34:35], v[34:35], v[36:37]
	s_nop 0
	v_cvt_pk_bf16_f32 v3, v34, v35
	v_add_co_u32_e32 v34, vcc, s2, v38
	s_mov_b64 s[2:3], 0x2600400
	s_nop 0
	v_addc_co_u32_e32 v35, vcc, 0, v39, vcc
	global_store_dwordx2 v[34:35], v[2:3], off offset:1024
	global_load_dwordx2 v[40:41], v[74:75], off offset:3920
	s_nop 0
	global_load_dwordx4 v[34:37], v[70:71], off offset:32
	v_lshl_add_u64 v[2:3], v[38:39], 0, s[2:3]
	s_mov_b64 s[2:3], 0xf40
	s_waitcnt vmcnt(0) lgkmcnt(0)
; __device__ __forceinline__ float bflo(unsigned w) { return __uint_as_float(w << 16); }
; __device__ __forceinline__ float bfhi(unsigned w) { return __uint_as_float(w & 0xffff0000u); }
; __device__ __forceinline__ unsigned pk2(float lo, float hi) { const f32x2 v = {lo, hi}; return __builtin_bit_cast(unsigned, __builtin_convertvector(v, bf16x2_t)); }
; __device__ __forceinline__ float silu(float x) { return x * __builtin_amdgcn_rcpf(1.f + __builtin_amdgcn_exp2f(-1.4426950408889634f * x)); }
; __device__ __forceinline__ void ret_out_item(LAS unsigned char* lds, const bf16* Z, const bf16* AT, const float* gn, bf16* MIXED, int b, int c, const float* lgs) {
;     ...
; #pragma unroll
;     for (int eb = 0; eb < 4; ++eb)
; #pragma unroll
;         for (int rg = 0; rg < 4; ++rg) { const int e0 = 32 * eb + 8 * rg + 4 * hi;
;             const u32x2 gt = *(const u32x2*)(Z + (size_t)row * NZ + ZC_RG + hh * 128 + e0); const f32x4 gg = *(const f32x4*)(gn + hh * 128 + e0);
;             const float y0 = (acc[eb][4 * rg] - mean) * rstd * gg.x * silu(bflo(gt.x)), y1 = (acc[eb][4 * rg + 1] - mean) * rstd * gg.y * silu(bfhi(gt.x));
;             const float y2 = (acc[eb][4 * rg + 2] - mean) * rstd * gg.z * silu(bflo(gt.y)), y3 = (acc[eb][4 * rg + 3] - mean) * rstd * gg.w * silu(bfhi(gt.y));
;             u32x2 w; w.x = pk2(y0, y1); w.y = pk2(y2, y3); *(u32x2*)(MIXED + (size_t)row * 1024 + 512 + hh * 128 + e0) = w; }
	v_lshlrev_b32_e32 v42, 16, v40
	v_mul_f32_e32 v1, 0xbfb8aa3b, v42
	v_and_b32_e32 v43, 0xffff0000, v40
	v_exp_f32_e32 v1, v1
	v_mul_f32_e32 v7, 0xbfb8aa3b, v43
	v_exp_f32_e32 v7, v7
	v_lshlrev_b32_e32 v40, 16, v41
	v_add_f32_e32 v1, 1.0, v1
	v_rcp_f32_e32 v38, v1
	v_add_f32_e32 v1, 1.0, v7
	v_rcp_f32_e32 v39, v1
	v_and_b32_e32 v41, 0xffff0000, v41
	v_mul_f32_e32 v1, 0xbfb8aa3b, v40
	v_pk_mul_f32 v[44:45], v[112:113], v[6:7] op_sel_hi:[1,0]
	v_exp_f32_e32 v1, v1
	v_mul_f32_e32 v7, 0xbfb8aa3b, v41
	v_exp_f32_e32 v7, v7
	v_pk_mul_f32 v[38:39], v[38:39], v[42:43]
	v_add_f32_e32 v1, 1.0, v1
	v_rcp_f32_e32 v42, v1
	v_add_f32_e32 v1, 1.0, v7
	v_rcp_f32_e32 v43, v1
	v_pk_mul_f32 v[34:35], v[34:35], v[44:45]
	s_nop 0
	v_pk_mul_f32 v[34:35], v[34:35], v[38:39]
	v_pk_mul_f32 v[38:39], v[100:101], v[6:7] op_sel_hi:[1,0]
	v_cvt_pk_bf16_f32 v34, v34, v35
	v_pk_mul_f32 v[36:37], v[36:37], v[38:39]
	v_pk_mul_f32 v[38:39], v[42:43], v[40:41]
	v_pk_mul_f32 v[40:41], v[98:99], v[6:7] op_sel_hi:[1,0]
	v_pk_mul_f32 v[36:37], v[36:37], v[38:39]
	v_pk_mul_f32 v[42:43], v[96:97], v[6:7] op_sel_hi:[1,0]
	v_cvt_pk_bf16_f32 v35, v36, v37
	global_store_dwordx2 v[2:3], v[34:35], off offset:16
	global_load_dwordx2 v[38:39], v[74:75], off offset:3936
	s_nop 0
	global_load_dwordx4 v[34:37], v[70:71], off offset:64
	s_waitcnt vmcnt(0) lgkmcnt(0)
	v_lshlrev_b32_e32 v44, 16, v38
	v_and_b32_e32 v45, 0xffff0000, v38
	v_lshlrev_b32_e32 v38, 16, v39
	v_and_b32_e32 v39, 0xffff0000, v39
	v_mul_f32_e32 v1, 0xbfb8aa3b, v44
	v_mul_f32_e32 v7, 0xbfb8aa3b, v45
	v_mul_f32_e32 v46, 0xbfb8aa3b, v38
	v_mul_f32_e32 v47, 0xbfb8aa3b, v39
	v_exp_f32_e32 v1, v1
	v_exp_f32_e32 v7, v7
	v_exp_f32_e32 v46, v46
	v_exp_f32_e32 v47, v47
	v_add_f32_e32 v1, 1.0, v1
	v_add_f32_e32 v7, 1.0, v7
	v_add_f32_e32 v52, 1.0, v46
	v_add_f32_e32 v53, 1.0, v47
	v_rcp_f32_e32 v46, v1
	v_rcp_f32_e32 v47, v7
	v_rcp_f32_e32 v52, v52
	v_rcp_f32_e32 v53, v53
	v_pk_mul_f32 v[34:35], v[34:35], v[40:41]
	v_pk_mul_f32 v[36:37], v[36:37], v[42:43]
	v_pk_mul_f32 v[40:41], v[46:47], v[44:45]
	v_pk_mul_f32 v[38:39], v[52:53], v[38:39]
	v_pk_mul_f32 v[34:35], v[34:35], v[40:41]
	v_pk_mul_f32 v[36:37], v[36:37], v[38:39]
	v_cvt_pk_bf16_f32 v34, v34, v35
	v_cvt_pk_bf16_f32 v35, v36, v37
	global_store_dwordx2 v[2:3], v[34:35], off offset:32
	global_load_dwordx2 v[38:39], v[74:75], off offset:3952
	s_nop 0
	global_load_dwordx4 v[34:37], v[70:71], off offset:96
	v_pk_mul_f32 v[40:41], v[94:95], v[6:7] op_sel_hi:[1,0]
	v_pk_mul_f32 v[42:43], v[92:93], v[6:7] op_sel_hi:[1,0]
	s_waitcnt vmcnt(0) lgkmcnt(0)
	v_lshlrev_b32_e32 v44, 16, v38
	v_and_b32_e32 v45, 0xffff0000, v38
	v_lshlrev_b32_e32 v38, 16, v39
	v_and_b32_e32 v39, 0xffff0000, v39
	v_mul_f32_e32 v1, 0xbfb8aa3b, v44
	v_mul_f32_e32 v7, 0xbfb8aa3b, v45
	v_mul_f32_e32 v46, 0xbfb8aa3b, v38
	v_mul_f32_e32 v47, 0xbfb8aa3b, v39
	v_exp_f32_e32 v1, v1
	v_exp_f32_e32 v7, v7
	v_exp_f32_e32 v46, v46
	v_exp_f32_e32 v47, v47
	v_add_f32_e32 v1, 1.0, v1
	v_add_f32_e32 v7, 1.0, v7
	v_add_f32_e32 v52, 1.0, v46
	v_add_f32_e32 v53, 1.0, v47
	v_rcp_f32_e32 v46, v1
	v_rcp_f32_e32 v47, v7
	v_rcp_f32_e32 v52, v52
	v_rcp_f32_e32 v53, v53
	v_pk_mul_f32 v[34:35], v[40:41], v[34:35]
	v_pk_mul_f32 v[36:37], v[42:43], v[36:37]
	v_pk_mul_f32 v[40:41], v[46:47], v[44:45]
	v_pk_mul_f32 v[38:39], v[52:53], v[38:39]
	v_pk_mul_f32 v[34:35], v[34:35], v[40:41]
	v_pk_mul_f32 v[36:37], v[36:37], v[38:39]
	v_cvt_pk_bf16_f32 v34, v34, v35
	v_cvt_pk_bf16_f32 v35, v36, v37
	global_store_dwordx2 v[2:3], v[34:35], off offset:48
	global_load_dwordx2 v[38:39], v[74:75], off offset:3968
	s_nop 0
	global_load_dwordx4 v[34:37], v[70:71], off offset:128
	v_pk_mul_f32 v[40:41], v[90:91], v[6:7] op_sel_hi:[1,0]
	v_pk_mul_f32 v[42:43], v[88:89], v[6:7] op_sel_hi:[1,0]
	s_waitcnt vmcnt(0) lgkmcnt(0)
	v_lshlrev_b32_e32 v44, 16, v38
	v_and_b32_e32 v45, 0xffff0000, v38
	v_lshlrev_b32_e32 v38, 16, v39
	v_and_b32_e32 v39, 0xffff0000, v39
	v_mul_f32_e32 v1, 0xbfb8aa3b, v44
	v_mul_f32_e32 v7, 0xbfb8aa3b, v45
	v_mul_f32_e32 v46, 0xbfb8aa3b, v38
	v_mul_f32_e32 v47, 0xbfb8aa3b, v39
	v_exp_f32_e32 v1, v1
	v_exp_f32_e32 v7, v7
	v_exp_f32_e32 v46, v46
	v_exp_f32_e32 v47, v47
	v_add_f32_e32 v1, 1.0, v1
	v_add_f32_e32 v7, 1.0, v7
	v_add_f32_e32 v52, 1.0, v46
	v_add_f32_e32 v53, 1.0, v47
	v_rcp_f32_e32 v46, v1
	v_rcp_f32_e32 v47, v7
	v_rcp_f32_e32 v52, v52
	v_rcp_f32_e32 v53, v53
	v_pk_mul_f32 v[34:35], v[40:41], v[34:35]
	v_pk_mul_f32 v[36:37], v[42:43], v[36:37]
	v_pk_mul_f32 v[40:41], v[46:47], v[44:45]
	v_pk_mul_f32 v[38:39], v[52:53], v[38:39]
	v_pk_mul_f32 v[34:35], v[34:35], v[40:41]
	v_pk_mul_f32 v[36:37], v[36:37], v[38:39]
	v_cvt_pk_bf16_f32 v34, v34, v35
	v_cvt_pk_bf16_f32 v35, v36, v37
	global_store_dwordx2 v[2:3], v[34:35], off offset:64
	global_load_dwordx2 v[38:39], v[74:75], off offset:3984
	s_nop 0
	global_load_dwordx4 v[34:37], v[70:71], off offset:160
	v_pk_mul_f32 v[40:41], v[86:87], v[6:7] op_sel_hi:[1,0]
	v_pk_mul_f32 v[42:43], v[84:85], v[6:7] op_sel_hi:[1,0]
	s_waitcnt vmcnt(0) lgkmcnt(0)
	v_lshlrev_b32_e32 v44, 16, v38
	v_and_b32_e32 v45, 0xffff0000, v38
	v_lshlrev_b32_e32 v38, 16, v39
	v_and_b32_e32 v39, 0xffff0000, v39
	v_mul_f32_e32 v1, 0xbfb8aa3b, v44
	v_mul_f32_e32 v7, 0xbfb8aa3b, v45
	v_mul_f32_e32 v46, 0xbfb8aa3b, v38
	v_mul_f32_e32 v47, 0xbfb8aa3b, v39
	v_exp_f32_e32 v1, v1
	v_exp_f32_e32 v7, v7
	v_exp_f32_e32 v46, v46
	v_exp_f32_e32 v47, v47
	v_add_f32_e32 v1, 1.0, v1
	v_add_f32_e32 v7, 1.0, v7
	v_add_f32_e32 v52, 1.0, v46
	v_add_f32_e32 v53, 1.0, v47
	v_rcp_f32_e32 v46, v1
	v_rcp_f32_e32 v47, v7
	v_rcp_f32_e32 v52, v52
	v_rcp_f32_e32 v53, v53
	v_pk_mul_f32 v[34:35], v[40:41], v[34:35]
	v_pk_mul_f32 v[36:37], v[42:43], v[36:37]
	v_pk_mul_f32 v[40:41], v[46:47], v[44:45]
	v_pk_mul_f32 v[38:39], v[52:53], v[38:39]
	v_pk_mul_f32 v[34:35], v[34:35], v[40:41]
	v_pk_mul_f32 v[36:37], v[36:37], v[38:39]
	v_cvt_pk_bf16_f32 v34, v34, v35
	v_cvt_pk_bf16_f32 v35, v36, v37
	global_store_dwordx2 v[2:3], v[34:35], off offset:80
	global_load_dwordx2 v[38:39], v[74:75], off offset:4000
	s_nop 0
	global_load_dwordx4 v[34:37], v[70:71], off offset:192
	v_pk_mul_f32 v[40:41], v[82:83], v[6:7] op_sel_hi:[1,0]
	v_pk_mul_f32 v[42:43], v[80:81], v[6:7] op_sel_hi:[1,0]
	s_waitcnt vmcnt(0) lgkmcnt(0)
; __device__ __forceinline__ float bflo(unsigned w) { return __uint_as_float(w << 16); }
; __device__ __forceinline__ float bfhi(unsigned w) { return __uint_as_float(w & 0xffff0000u); }
; __device__ __forceinline__ unsigned pk2(float lo, float hi) { const f32x2 v = {lo, hi}; return __builtin_bit_cast(unsigned, __builtin_convertvector(v, bf16x2_t)); }
; __device__ __forceinline__ float silu(float x) { return x * __builtin_amdgcn_rcpf(1.f + __builtin_amdgcn_exp2f(-1.4426950408889634f * x)); }
; __device__ __forceinline__ void ret_out_item(LAS unsigned char* lds, const bf16* Z, const bf16* AT, const float* gn, bf16* MIXED, int b, int c, const float* lgs) {
;     ...
; #pragma unroll
;     for (int eb = 0; eb < 4; ++eb)
; #pragma unroll
;         for (int rg = 0; rg < 4; ++rg) { const int e0 = 32 * eb + 8 * rg + 4 * hi;
;             const u32x2 gt = *(const u32x2*)(Z + (size_t)row * NZ + ZC_RG + hh * 128 + e0); const f32x4 gg = *(const f32x4*)(gn + hh * 128 + e0);
;             const float y0 = (acc[eb][4 * rg] - mean) * rstd * gg.x * silu(bflo(gt.x)), y1 = (acc[eb][4 * rg + 1] - mean) * rstd * gg.y * silu(bfhi(gt.x));
;             const float y2 = (acc[eb][4 * rg + 2] - mean) * rstd * gg.z * silu(bflo(gt.y)), y3 = (acc[eb][4 * rg + 3] - mean) * rstd * gg.w * silu(bfhi(gt.y));
;             u32x2 w; w.x = pk2(y0, y1); w.y = pk2(y2, y3); *(u32x2*)(MIXED + (size_t)row * 1024 + 512 + hh * 128 + e0) = w; }
	v_lshlrev_b32_e32 v44, 16, v38
	v_and_b32_e32 v45, 0xffff0000, v38
	v_lshlrev_b32_e32 v38, 16, v39
	v_and_b32_e32 v39, 0xffff0000, v39
	v_mul_f32_e32 v1, 0xbfb8aa3b, v44
	v_mul_f32_e32 v7, 0xbfb8aa3b, v45
	v_mul_f32_e32 v46, 0xbfb8aa3b, v38
	v_mul_f32_e32 v47, 0xbfb8aa3b, v39
	v_exp_f32_e32 v1, v1
	v_exp_f32_e32 v7, v7
	v_exp_f32_e32 v46, v46
	v_exp_f32_e32 v47, v47
	v_add_f32_e32 v1, 1.0, v1
	v_add_f32_e32 v7, 1.0, v7
	v_add_f32_e32 v52, 1.0, v46
	v_add_f32_e32 v53, 1.0, v47
	v_rcp_f32_e32 v46, v1
	v_rcp_f32_e32 v47, v7
	v_rcp_f32_e32 v52, v52
	v_rcp_f32_e32 v53, v53
	v_pk_mul_f32 v[34:35], v[40:41], v[34:35]
	v_pk_mul_f32 v[36:37], v[42:43], v[36:37]
	v_pk_mul_f32 v[40:41], v[46:47], v[44:45]
	v_pk_mul_f32 v[38:39], v[52:53], v[38:39]
	v_pk_mul_f32 v[34:35], v[34:35], v[40:41]
	v_pk_mul_f32 v[36:37], v[36:37], v[38:39]
	v_cvt_pk_bf16_f32 v34, v34, v35
	v_cvt_pk_bf16_f32 v35, v36, v37
	global_store_dwordx2 v[2:3], v[34:35], off offset:96
	global_load_dwordx2 v[38:39], v[74:75], off offset:4016
	s_nop 0
	global_load_dwordx4 v[34:37], v[70:71], off offset:224
	v_pk_mul_f32 v[40:41], v[78:79], v[6:7] op_sel_hi:[1,0]
	v_pk_mul_f32 v[42:43], v[76:77], v[6:7] op_sel_hi:[1,0]
	s_waitcnt vmcnt(0) lgkmcnt(0)
	v_lshlrev_b32_e32 v44, 16, v38
	v_and_b32_e32 v45, 0xffff0000, v38
	v_lshlrev_b32_e32 v38, 16, v39
	v_and_b32_e32 v39, 0xffff0000, v39
	v_mul_f32_e32 v1, 0xbfb8aa3b, v44
	v_mul_f32_e32 v7, 0xbfb8aa3b, v45
	v_mul_f32_e32 v46, 0xbfb8aa3b, v38
	v_mul_f32_e32 v47, 0xbfb8aa3b, v39
	v_exp_f32_e32 v1, v1
	v_exp_f32_e32 v7, v7
	v_exp_f32_e32 v46, v46
	v_exp_f32_e32 v47, v47
	v_add_f32_e32 v1, 1.0, v1
	v_add_f32_e32 v7, 1.0, v7
	v_add_f32_e32 v52, 1.0, v46
	v_add_f32_e32 v53, 1.0, v47
	v_rcp_f32_e32 v46, v1
	v_rcp_f32_e32 v47, v7
	v_rcp_f32_e32 v52, v52
	v_rcp_f32_e32 v53, v53
	v_pk_mul_f32 v[34:35], v[40:41], v[34:35]
	v_pk_mul_f32 v[36:37], v[42:43], v[36:37]
	v_pk_mul_f32 v[40:41], v[46:47], v[44:45]
	v_pk_mul_f32 v[38:39], v[52:53], v[38:39]
	v_pk_mul_f32 v[34:35], v[34:35], v[40:41]
	v_pk_mul_f32 v[36:37], v[36:37], v[38:39]
	v_cvt_pk_bf16_f32 v34, v34, v35
	v_cvt_pk_bf16_f32 v35, v36, v37
	global_store_dwordx2 v[2:3], v[34:35], off offset:112
	global_load_dwordx2 v[38:39], v[74:75], off offset:4032
	s_nop 0
	global_load_dwordx4 v[34:37], v[70:71], off offset:256
	v_pk_mul_f32 v[40:41], v[50:51], v[6:7] op_sel_hi:[1,0]
	v_pk_mul_f32 v[32:33], v[32:33], v[6:7] op_sel_hi:[1,0]
	s_waitcnt vmcnt(0) lgkmcnt(0)
	v_lshlrev_b32_e32 v42, 16, v38
	v_and_b32_e32 v43, 0xffff0000, v38
	v_lshlrev_b32_e32 v38, 16, v39
	v_and_b32_e32 v39, 0xffff0000, v39
	v_mul_f32_e32 v1, 0xbfb8aa3b, v42
	v_mul_f32_e32 v7, 0xbfb8aa3b, v43
	v_mul_f32_e32 v44, 0xbfb8aa3b, v38
	v_mul_f32_e32 v45, 0xbfb8aa3b, v39
	v_exp_f32_e32 v1, v1
	v_exp_f32_e32 v7, v7
	v_exp_f32_e32 v44, v44
	v_exp_f32_e32 v45, v45
	v_add_f32_e32 v1, 1.0, v1
	v_add_f32_e32 v7, 1.0, v7
	v_add_f32_e32 v46, 1.0, v44
	v_add_f32_e32 v47, 1.0, v45
	v_rcp_f32_e32 v44, v1
	v_rcp_f32_e32 v45, v7
	v_rcp_f32_e32 v46, v46
	v_rcp_f32_e32 v47, v47
	v_pk_mul_f32 v[34:35], v[40:41], v[34:35]
	v_pk_mul_f32 v[32:33], v[32:33], v[36:37]
	v_pk_mul_f32 v[36:37], v[44:45], v[42:43]
	v_pk_mul_f32 v[38:39], v[46:47], v[38:39]
	v_pk_mul_f32 v[34:35], v[34:35], v[36:37]
	v_pk_mul_f32 v[32:33], v[32:33], v[38:39]
	v_cvt_pk_bf16_f32 v34, v34, v35
	v_cvt_pk_bf16_f32 v35, v32, v33
	global_store_dwordx2 v[2:3], v[34:35], off offset:128
	global_load_dwordx2 v[36:37], v[74:75], off offset:4048
	s_nop 0
	global_load_dwordx4 v[32:35], v[70:71], off offset:288
	v_pk_mul_f32 v[30:31], v[30:31], v[6:7] op_sel_hi:[1,0]
	v_pk_mul_f32 v[28:29], v[28:29], v[6:7] op_sel_hi:[1,0]
	s_waitcnt vmcnt(0) lgkmcnt(0)
	v_lshlrev_b32_e32 v38, 16, v36
	v_and_b32_e32 v39, 0xffff0000, v36
	v_lshlrev_b32_e32 v36, 16, v37
	v_and_b32_e32 v37, 0xffff0000, v37
	v_mul_f32_e32 v1, 0xbfb8aa3b, v38
	v_mul_f32_e32 v7, 0xbfb8aa3b, v39
	v_mul_f32_e32 v40, 0xbfb8aa3b, v36
	v_mul_f32_e32 v41, 0xbfb8aa3b, v37
	v_exp_f32_e32 v1, v1
	v_exp_f32_e32 v7, v7
	v_exp_f32_e32 v40, v40
	v_exp_f32_e32 v41, v41
	v_add_f32_e32 v1, 1.0, v1
	v_add_f32_e32 v7, 1.0, v7
	v_add_f32_e32 v42, 1.0, v40
	v_add_f32_e32 v43, 1.0, v41
	v_rcp_f32_e32 v40, v1
	v_rcp_f32_e32 v41, v7
	v_rcp_f32_e32 v42, v42
	v_rcp_f32_e32 v43, v43
	v_pk_mul_f32 v[30:31], v[30:31], v[32:33]
	v_pk_mul_f32 v[28:29], v[28:29], v[34:35]
	v_pk_mul_f32 v[32:33], v[40:41], v[38:39]
	v_pk_mul_f32 v[34:35], v[42:43], v[36:37]
	v_pk_mul_f32 v[30:31], v[30:31], v[32:33]
	v_pk_mul_f32 v[28:29], v[28:29], v[34:35]
	v_cvt_pk_bf16_f32 v30, v30, v31
	v_cvt_pk_bf16_f32 v31, v28, v29
	global_store_dwordx2 v[2:3], v[30:31], off offset:144
	global_load_dwordx2 v[32:33], v[74:75], off offset:4064
	s_nop 0
	global_load_dwordx4 v[28:31], v[70:71], off offset:320
	v_pk_mul_f32 v[26:27], v[26:27], v[6:7] op_sel_hi:[1,0]
	v_pk_mul_f32 v[24:25], v[24:25], v[6:7] op_sel_hi:[1,0]
	s_waitcnt vmcnt(0) lgkmcnt(0)
	v_lshlrev_b32_e32 v34, 16, v32
	v_and_b32_e32 v35, 0xffff0000, v32
	v_lshlrev_b32_e32 v32, 16, v33
	v_and_b32_e32 v33, 0xffff0000, v33
	v_mul_f32_e32 v1, 0xbfb8aa3b, v34
	v_mul_f32_e32 v7, 0xbfb8aa3b, v35
	v_mul_f32_e32 v36, 0xbfb8aa3b, v32
	v_mul_f32_e32 v37, 0xbfb8aa3b, v33
	v_exp_f32_e32 v1, v1
	v_exp_f32_e32 v7, v7
	v_exp_f32_e32 v36, v36
	v_exp_f32_e32 v37, v37
	v_add_f32_e32 v1, 1.0, v1
	v_add_f32_e32 v7, 1.0, v7
	v_add_f32_e32 v38, 1.0, v36
	v_add_f32_e32 v39, 1.0, v37
	v_rcp_f32_e32 v36, v1
	v_rcp_f32_e32 v37, v7
	v_rcp_f32_e32 v38, v38
	v_rcp_f32_e32 v39, v39
	v_pk_mul_f32 v[26:27], v[26:27], v[28:29]
	v_pk_mul_f32 v[24:25], v[24:25], v[30:31]
	v_pk_mul_f32 v[28:29], v[36:37], v[34:35]
	v_pk_mul_f32 v[30:31], v[38:39], v[32:33]
	v_pk_mul_f32 v[26:27], v[26:27], v[28:29]
	v_pk_mul_f32 v[24:25], v[24:25], v[30:31]
	v_cvt_pk_bf16_f32 v26, v26, v27
	v_cvt_pk_bf16_f32 v27, v24, v25
	global_store_dwordx2 v[2:3], v[26:27], off offset:160
	global_load_dwordx2 v[28:29], v[74:75], off offset:4080
	s_nop 0
	global_load_dwordx4 v[24:27], v[70:71], off offset:352
	v_pk_mul_f32 v[22:23], v[22:23], v[6:7] op_sel_hi:[1,0]
	v_pk_mul_f32 v[20:21], v[20:21], v[6:7] op_sel_hi:[1,0]
	v_or_b32_e32 v30, 0xc0, v138
	v_mov_b32_e32 v31, v0
	v_lshl_add_u64 v[32:33], v[72:73], 0, s[2:3]
	v_lshl_add_u64 v[30:31], v[32:33], 0, v[30:31]
	s_waitcnt vmcnt(0) lgkmcnt(0)
; __device__ __forceinline__ float bflo(unsigned w) { return __uint_as_float(w << 16); }
; __device__ __forceinline__ float bfhi(unsigned w) { return __uint_as_float(w & 0xffff0000u); }
; __device__ __forceinline__ unsigned pk2(float lo, float hi) { const f32x2 v = {lo, hi}; return __builtin_bit_cast(unsigned, __builtin_convertvector(v, bf16x2_t)); }
; __device__ __forceinline__ float silu(float x) { return x * __builtin_amdgcn_rcpf(1.f + __builtin_amdgcn_exp2f(-1.4426950408889634f * x)); }
; __device__ __forceinline__ void ret_out_item(LAS unsigned char* lds, const bf16* Z, const bf16* AT, const float* gn, bf16* MIXED, int b, int c, const float* lgs) {
;     ...
; #pragma unroll
;     for (int eb = 0; eb < 4; ++eb)
; #pragma unroll
;         for (int rg = 0; rg < 4; ++rg) { const int e0 = 32 * eb + 8 * rg + 4 * hi;
;             const u32x2 gt = *(const u32x2*)(Z + (size_t)row * NZ + ZC_RG + hh * 128 + e0); const f32x4 gg = *(const f32x4*)(gn + hh * 128 + e0);
;             const float y0 = (acc[eb][4 * rg] - mean) * rstd * gg.x * silu(bflo(gt.x)), y1 = (acc[eb][4 * rg + 1] - mean) * rstd * gg.y * silu(bfhi(gt.x));
;             const float y2 = (acc[eb][4 * rg + 2] - mean) * rstd * gg.z * silu(bflo(gt.y)), y3 = (acc[eb][4 * rg + 3] - mean) * rstd * gg.w * silu(bfhi(gt.y));
;             u32x2 w; w.x = pk2(y0, y1); w.y = pk2(y2, y3); *(u32x2*)(MIXED + (size_t)row * 1024 + 512 + hh * 128 + e0) = w; }
;     __syncthreads();
	v_lshlrev_b32_e32 v34, 16, v28
	v_and_b32_e32 v35, 0xffff0000, v28
	v_lshlrev_b32_e32 v28, 16, v29
	v_and_b32_e32 v29, 0xffff0000, v29
	v_mul_f32_e32 v1, 0xbfb8aa3b, v34
	v_mul_f32_e32 v7, 0xbfb8aa3b, v35
	v_mul_f32_e32 v36, 0xbfb8aa3b, v28
	v_mul_f32_e32 v37, 0xbfb8aa3b, v29
	v_exp_f32_e32 v1, v1
	v_exp_f32_e32 v7, v7
	v_exp_f32_e32 v36, v36
	v_exp_f32_e32 v37, v37
	v_add_f32_e32 v1, 1.0, v1
	v_add_f32_e32 v7, 1.0, v7
	v_add_f32_e32 v38, 1.0, v36
	v_add_f32_e32 v39, 1.0, v37
	v_rcp_f32_e32 v36, v1
	v_rcp_f32_e32 v37, v7
	v_rcp_f32_e32 v38, v38
	v_rcp_f32_e32 v39, v39
	v_pk_mul_f32 v[22:23], v[22:23], v[24:25]
	v_pk_mul_f32 v[20:21], v[20:21], v[26:27]
	v_pk_mul_f32 v[24:25], v[36:37], v[34:35]
	v_pk_mul_f32 v[26:27], v[38:39], v[28:29]
	v_pk_mul_f32 v[22:23], v[22:23], v[24:25]
	v_pk_mul_f32 v[20:21], v[20:21], v[26:27]
	v_cvt_pk_bf16_f32 v22, v22, v23
	v_cvt_pk_bf16_f32 v23, v20, v21
	global_store_dwordx2 v[2:3], v[22:23], off offset:176
	global_load_dwordx2 v[24:25], v[30:31], off
	s_nop 0
	global_load_dwordx4 v[20:23], v[70:71], off offset:384
	v_pk_mul_f32 v[18:19], v[18:19], v[6:7] op_sel_hi:[1,0]
	v_pk_mul_f32 v[16:17], v[16:17], v[6:7] op_sel_hi:[1,0]
	v_or_b32_e32 v26, 0xd0, v138
	v_mov_b32_e32 v27, v0
	v_lshl_add_u64 v[26:27], v[32:33], 0, v[26:27]
	s_waitcnt vmcnt(0) lgkmcnt(0)
	v_lshlrev_b32_e32 v28, 16, v24
	v_and_b32_e32 v29, 0xffff0000, v24
	v_lshlrev_b32_e32 v24, 16, v25
	v_and_b32_e32 v25, 0xffff0000, v25
	v_mul_f32_e32 v1, 0xbfb8aa3b, v28
	v_mul_f32_e32 v7, 0xbfb8aa3b, v29
	v_mul_f32_e32 v30, 0xbfb8aa3b, v24
	v_mul_f32_e32 v31, 0xbfb8aa3b, v25
	v_exp_f32_e32 v1, v1
	v_exp_f32_e32 v7, v7
	v_exp_f32_e32 v30, v30
	v_exp_f32_e32 v31, v31
	v_add_f32_e32 v1, 1.0, v1
	v_add_f32_e32 v7, 1.0, v7
	v_add_f32_e32 v34, 1.0, v30
	v_add_f32_e32 v35, 1.0, v31
	v_rcp_f32_e32 v30, v1
	v_rcp_f32_e32 v31, v7
	v_rcp_f32_e32 v34, v34
	v_rcp_f32_e32 v35, v35
	v_pk_mul_f32 v[18:19], v[18:19], v[20:21]
	v_pk_mul_f32 v[16:17], v[16:17], v[22:23]
	v_pk_mul_f32 v[20:21], v[30:31], v[28:29]
	v_pk_mul_f32 v[22:23], v[34:35], v[24:25]
	v_pk_mul_f32 v[18:19], v[18:19], v[20:21]
	v_pk_mul_f32 v[16:17], v[16:17], v[22:23]
	v_cvt_pk_bf16_f32 v18, v18, v19
	v_cvt_pk_bf16_f32 v19, v16, v17
	global_store_dwordx2 v[2:3], v[18:19], off offset:192
	global_load_dwordx2 v[20:21], v[26:27], off
	s_nop 0
	global_load_dwordx4 v[16:19], v[70:71], off offset:416
	v_pk_mul_f32 v[14:15], v[14:15], v[6:7] op_sel_hi:[1,0]
	v_pk_mul_f32 v[12:13], v[12:13], v[6:7] op_sel_hi:[1,0]
	v_or_b32_e32 v22, 0xe0, v138
	v_mov_b32_e32 v23, v0
	v_lshl_add_u64 v[22:23], v[32:33], 0, v[22:23]
	s_waitcnt vmcnt(0) lgkmcnt(0)
	v_lshlrev_b32_e32 v24, 16, v20
	v_and_b32_e32 v25, 0xffff0000, v20
	v_lshlrev_b32_e32 v20, 16, v21
	v_and_b32_e32 v21, 0xffff0000, v21
	v_mul_f32_e32 v1, 0xbfb8aa3b, v24
	v_mul_f32_e32 v7, 0xbfb8aa3b, v25
	v_mul_f32_e32 v26, 0xbfb8aa3b, v20
	v_mul_f32_e32 v27, 0xbfb8aa3b, v21
	v_exp_f32_e32 v1, v1
	v_exp_f32_e32 v7, v7
	v_exp_f32_e32 v26, v26
	v_exp_f32_e32 v27, v27
	v_add_f32_e32 v1, 1.0, v1
	v_add_f32_e32 v7, 1.0, v7
	v_add_f32_e32 v28, 1.0, v26
	v_add_f32_e32 v29, 1.0, v27
	v_rcp_f32_e32 v26, v1
	v_rcp_f32_e32 v27, v7
	v_rcp_f32_e32 v28, v28
	v_rcp_f32_e32 v29, v29
	v_pk_mul_f32 v[14:15], v[14:15], v[16:17]
	v_pk_mul_f32 v[12:13], v[12:13], v[18:19]
	v_pk_mul_f32 v[16:17], v[26:27], v[24:25]
	v_pk_mul_f32 v[18:19], v[28:29], v[20:21]
	v_pk_mul_f32 v[14:15], v[14:15], v[16:17]
	v_pk_mul_f32 v[12:13], v[12:13], v[18:19]
	v_cvt_pk_bf16_f32 v14, v14, v15
	v_cvt_pk_bf16_f32 v15, v12, v13
	global_store_dwordx2 v[2:3], v[14:15], off offset:208
	global_load_dwordx2 v[16:17], v[22:23], off
	s_nop 0
	global_load_dwordx4 v[12:15], v[70:71], off offset:448
	v_pk_mul_f32 v[10:11], v[10:11], v[6:7] op_sel_hi:[1,0]
	v_pk_mul_f32 v[8:9], v[8:9], v[6:7] op_sel_hi:[1,0]
	v_or_b32_e32 v18, 0xf0, v138
	v_mov_b32_e32 v19, v0
	v_lshl_add_u64 v[18:19], v[32:33], 0, v[18:19]
	s_waitcnt vmcnt(0) lgkmcnt(0)
	v_lshlrev_b32_e32 v20, 16, v16
	v_and_b32_e32 v21, 0xffff0000, v16
	v_lshlrev_b32_e32 v16, 16, v17
	v_and_b32_e32 v17, 0xffff0000, v17
	v_mul_f32_e32 v1, 0xbfb8aa3b, v20
	v_mul_f32_e32 v7, 0xbfb8aa3b, v21
	v_mul_f32_e32 v22, 0xbfb8aa3b, v16
	v_mul_f32_e32 v23, 0xbfb8aa3b, v17
	v_exp_f32_e32 v1, v1
	v_exp_f32_e32 v7, v7
	v_exp_f32_e32 v22, v22
	v_exp_f32_e32 v23, v23
	v_add_f32_e32 v1, 1.0, v1
	v_add_f32_e32 v7, 1.0, v7
	v_add_f32_e32 v24, 1.0, v22
	v_add_f32_e32 v25, 1.0, v23
	v_rcp_f32_e32 v22, v1
	v_rcp_f32_e32 v23, v7
	v_rcp_f32_e32 v24, v24
	v_rcp_f32_e32 v25, v25
	v_pk_mul_f32 v[10:11], v[10:11], v[12:13]
	v_pk_mul_f32 v[8:9], v[8:9], v[14:15]
	v_pk_mul_f32 v[12:13], v[22:23], v[20:21]
	v_pk_mul_f32 v[14:15], v[24:25], v[16:17]
	v_pk_mul_f32 v[10:11], v[10:11], v[12:13]
	v_pk_mul_f32 v[8:9], v[8:9], v[14:15]
	v_cvt_pk_bf16_f32 v10, v10, v11
	v_cvt_pk_bf16_f32 v11, v8, v9
	global_store_dwordx2 v[2:3], v[10:11], off offset:224
	global_load_dwordx2 v[12:13], v[18:19], off
	s_nop 0
	global_load_dwordx4 v[8:11], v[70:71], off offset:480
	v_pk_mul_f32 v[4:5], v[4:5], v[6:7] op_sel_hi:[1,0]
	v_pk_mul_f32 v[6:7], v[48:49], v[6:7] op_sel_hi:[1,0]
	s_waitcnt vmcnt(0) lgkmcnt(0)
	v_lshlrev_b32_e32 v14, 16, v12
	v_and_b32_e32 v15, 0xffff0000, v12
	v_lshlrev_b32_e32 v12, 16, v13
	v_and_b32_e32 v13, 0xffff0000, v13
	v_mul_f32_e32 v1, 0xbfb8aa3b, v14
	v_mul_f32_e32 v16, 0xbfb8aa3b, v15
	v_mul_f32_e32 v17, 0xbfb8aa3b, v12
	v_mul_f32_e32 v18, 0xbfb8aa3b, v13
	v_exp_f32_e32 v1, v1
	v_exp_f32_e32 v16, v16
	v_exp_f32_e32 v17, v17
	v_exp_f32_e32 v18, v18
	v_add_f32_e32 v1, 1.0, v1
	v_add_f32_e32 v19, 1.0, v16
	v_add_f32_e32 v20, 1.0, v17
	v_add_f32_e32 v21, 1.0, v18
	v_rcp_f32_e32 v16, v1
	v_rcp_f32_e32 v17, v19
	v_rcp_f32_e32 v18, v20
	v_rcp_f32_e32 v19, v21
	v_pk_mul_f32 v[4:5], v[4:5], v[8:9]
	v_pk_mul_f32 v[6:7], v[6:7], v[10:11]
	v_pk_mul_f32 v[8:9], v[16:17], v[14:15]
	v_pk_mul_f32 v[10:11], v[18:19], v[12:13]
	v_pk_mul_f32 v[4:5], v[4:5], v[8:9]
	v_pk_mul_f32 v[6:7], v[6:7], v[10:11]
	v_cvt_pk_bf16_f32 v4, v4, v5
	v_cvt_pk_bf16_f32 v5, v6, v7
	global_store_dwordx2 v[2:3], v[4:5], off offset:240
	s_waitcnt lgkmcnt(0)
	s_barrier

; #define LAS __attribute__((address_space(3)))
; __device__ __forceinline__ float bf2f(unsigned b) { return __uint_as_float(b << 16); }
; #define INP(i) ((const float*)tab_get(lds, (i)))
; #define WSB(off) ((bf16*)((unsigned char*)tab_get(lds, 31) + (off)))
; __device__ __forceinline__ void mla_sample_unit(LAS unsigned char* lds, size_t ws_q, size_t ws_olat, size_t ws_mixed, int b) {
;     ...
;     { const bf16* Q = WSB(ws_q); const float* w_uk = INP(14); LAS bf16* QA = (LAS bf16*)lds;
; #pragma unroll
;     for (int i = 0; i < 24; ++i) { const int idx = tid + 512 * i, t = idx / 768, c = idx - t * 768; QS[idx] = bf2f(Q[(size_t)(rowbase + t) * 768 + c]); }
;     __syncthreads();
.LBB0_683:
	s_andn2_b64 vcc, exec, s[2:3]
	s_cbranch_vccnz .LBB0_622
	s_getreg_b32 s2, hwreg(HW_REG_HW_ID, 0, 6)
	s_lshl_b32 s2, s2, 2
	s_and_b32 s2, s2, 0xfc
	s_add_i32 s2, s2, 0
	s_add_i32 s2, s2, 0x25a00
	v_mov_b32_e32 v1, s2
	ds_read_b32 v1, v1
	v_mov_b32_e32 v2, s45
	v_mbcnt_lo_u32_b32 v179, -1, 0
	v_mbcnt_hi_u32_b32 v179, -1, v179
	ds_read_b64 v[2:3], v2
	v_readlane_b32 s4, v254, 16
	s_waitcnt lgkmcnt(0)
	v_readfirstlane_b32 s2, v1
	s_lshl_b32 s48, s57, 4
	v_mov_b32_e32 v1, s4
	v_lshl_add_u32 v176, s2, 6, v179
	s_add_i32 s58, s48, 0x8000
	v_readfirstlane_b32 s3, v3
	v_readfirstlane_b32 s2, v2
	ds_read_b64 v[2:3], v1
	v_mul_hi_i32 v1, v176, s93
	s_add_u32 s2, s2, 0x10d00000
	v_lshrrev_b32_e32 v4, 31, v1
	v_ashrrev_i32_e32 v1, 7, v1
	s_addc_u32 s3, s3, 0
	v_add_u32_e32 v1, v1, v4
	v_mad_i32_i24 v6, v1, s94, v176
	v_add_u32_e32 v1, s58, v1
	v_mov_b64_e32 v[4:5], s[2:3]
	v_add_u32_e32 v178, 0x200, v176
	v_ashrrev_i32_e32 v7, 31, v6
	v_mad_i64_i32 v[8:9], s[2:3], v1, s77, v[4:5]
	v_mul_hi_i32 v1, v178, s93
	v_lshl_add_u64 v[6:7], v[6:7], 1, v[8:9]
	v_lshrrev_b32_e32 v8, 31, v1
	v_ashrrev_i32_e32 v1, 7, v1
	v_add_u32_e32 v1, v1, v8
	v_mad_i32_i24 v8, v1, s94, v178
	v_add_u32_e32 v1, s58, v1
	v_add_u32_e32 v177, 0x400, v176
	v_ashrrev_i32_e32 v9, 31, v8
	v_mad_i64_i32 v[10:11], s[2:3], v1, s77, v[4:5]
	v_mul_hi_i32 v1, v177, s93
	v_lshl_add_u64 v[8:9], v[8:9], 1, v[10:11]
	v_lshrrev_b32_e32 v10, 31, v1
	v_ashrrev_i32_e32 v1, 7, v1
	v_add_u32_e32 v1, v1, v10
	v_mad_i32_i24 v10, v1, s94, v177
	v_add_u32_e32 v1, s58, v1
	v_add_u32_e32 v155, 0x600, v176
	v_ashrrev_i32_e32 v11, 31, v10
	v_mad_i64_i32 v[12:13], s[2:3], v1, s77, v[4:5]
	v_mul_hi_i32 v1, v155, s93
	v_lshl_add_u64 v[10:11], v[10:11], 1, v[12:13]
	v_lshrrev_b32_e32 v12, 31, v1
	v_ashrrev_i32_e32 v1, 7, v1
	v_add_u32_e32 v1, v1, v12
	v_mad_i32_i24 v12, v1, s94, v155
	v_add_u32_e32 v1, s58, v1
	v_add_u32_e32 v49, 0x800, v176
	v_ashrrev_i32_e32 v13, 31, v12
	v_mad_i64_i32 v[14:15], s[2:3], v1, s77, v[4:5]
	v_mul_hi_i32 v1, v49, s93
	v_lshl_add_u64 v[12:13], v[12:13], 1, v[14:15]
	v_lshrrev_b32_e32 v14, 31, v1
	v_ashrrev_i32_e32 v1, 7, v1
	v_add_u32_e32 v1, v1, v14
	v_mad_i32_i24 v14, v1, s94, v49
	v_add_u32_e32 v1, s58, v1
	v_add_u32_e32 v48, 0xa00, v176
	v_ashrrev_i32_e32 v15, 31, v14
	v_mad_i64_i32 v[16:17], s[2:3], v1, s77, v[4:5]
	v_mul_hi_i32 v1, v48, s93
	v_lshl_add_u64 v[14:15], v[14:15], 1, v[16:17]
	v_lshrrev_b32_e32 v16, 31, v1
	v_ashrrev_i32_e32 v1, 7, v1
	v_add_u32_e32 v1, v1, v16
	v_mad_i32_i24 v16, v1, s94, v48
	v_add_u32_e32 v1, s58, v1
	v_ashrrev_i32_e32 v17, 31, v16
	v_mad_i64_i32 v[18:19], s[2:3], v1, s77, v[4:5]
	v_lshl_add_u64 v[16:17], v[16:17], 1, v[18:19]
	v_add_u32_e32 v19, 0xc00, v176
	v_mul_hi_i32 v1, v19, s93
	v_lshrrev_b32_e32 v18, 31, v1
	v_ashrrev_i32_e32 v1, 7, v1
	v_add_u32_e32 v1, v1, v18
	v_mad_i32_i24 v20, v1, s94, v19
	v_add_u32_e32 v1, s58, v1
	v_mad_i64_i32 v[22:23], s[2:3], v1, s77, v[4:5]
	v_add_u32_e32 v1, 0xe00, v176
	v_ashrrev_i32_e32 v21, 31, v20
	v_mul_hi_i32 v18, v1, s93
	v_lshl_add_u64 v[20:21], v[20:21], 1, v[22:23]
	v_lshrrev_b32_e32 v22, 31, v18
	v_ashrrev_i32_e32 v18, 7, v18
	v_add_u32_e32 v18, v18, v22
	v_mad_i32_i24 v22, v18, s94, v1
	v_add_u32_e32 v18, s58, v18
	v_ashrrev_i32_e32 v23, 31, v22
	v_mad_i64_i32 v[24:25], s[2:3], v18, s77, v[4:5]
	v_lshl_add_u64 v[22:23], v[22:23], 1, v[24:25]
	global_load_ushort v18, v[6:7], off
	global_load_ushort v26, v[8:9], off
	global_load_ushort v27, v[10:11], off
	global_load_ushort v28, v[12:13], off
	global_load_ushort v29, v[14:15], off
	global_load_ushort v30, v[16:17], off
	global_load_ushort v31, v[20:21], off
	global_load_ushort v32, v[22:23], off
	v_add_u32_e32 v6, 0x1000, v176
	v_mul_hi_i32 v7, v6, s93
	v_lshrrev_b32_e32 v8, 31, v7
	v_ashrrev_i32_e32 v7, 7, v7
	v_add_u32_e32 v7, v7, v8
	v_mad_i32_i24 v6, v7, s94, v6
	v_add_u32_e32 v8, s58, v7
	v_ashrrev_i32_e32 v7, 31, v6
	v_mad_i64_i32 v[8:9], s[2:3], v8, s77, v[4:5]
	v_lshl_add_u64 v[6:7], v[6:7], 1, v[8:9]
	v_add_u32_e32 v8, 0x1200, v176
	v_mul_hi_i32 v9, v8, s93
	v_lshrrev_b32_e32 v10, 31, v9
	v_ashrrev_i32_e32 v9, 7, v9
	v_add_u32_e32 v9, v9, v10
	v_mad_i32_i24 v8, v9, s94, v8
	v_add_u32_e32 v10, s58, v9
	v_ashrrev_i32_e32 v9, 31, v8
	v_mad_i64_i32 v[10:11], s[2:3], v10, s77, v[4:5]
	v_lshl_add_u64 v[8:9], v[8:9], 1, v[10:11]
	v_add_u32_e32 v10, 0x1400, v176
	v_mul_hi_i32 v11, v10, s93
	v_lshrrev_b32_e32 v12, 31, v11
	v_ashrrev_i32_e32 v11, 7, v11
	v_add_u32_e32 v11, v11, v12
	v_mad_i32_i24 v10, v11, s94, v10
	v_add_u32_e32 v12, s58, v11
	v_ashrrev_i32_e32 v11, 31, v10
	v_mad_i64_i32 v[12:13], s[2:3], v12, s77, v[4:5]
	v_lshl_add_u64 v[10:11], v[10:11], 1, v[12:13]
	v_add_u32_e32 v12, 0x1600, v176
	v_mul_hi_i32 v13, v12, s93
	v_lshrrev_b32_e32 v14, 31, v13
	v_ashrrev_i32_e32 v13, 7, v13
	v_add_u32_e32 v13, v13, v14
	v_mad_i32_i24 v12, v13, s94, v12
	v_add_u32_e32 v14, s58, v13
	v_ashrrev_i32_e32 v13, 31, v12
	v_mad_i64_i32 v[14:15], s[2:3], v14, s77, v[4:5]
	v_lshl_add_u64 v[12:13], v[12:13], 1, v[14:15]
	v_add_u32_e32 v14, 0x1800, v176
	v_mul_hi_i32 v15, v14, s93
	v_lshrrev_b32_e32 v16, 31, v15
	v_ashrrev_i32_e32 v15, 7, v15
	v_add_u32_e32 v15, v15, v16
	v_mad_i32_i24 v14, v15, s94, v14
	v_add_u32_e32 v16, s58, v15
	v_ashrrev_i32_e32 v15, 31, v14
	v_mad_i64_i32 v[16:17], s[2:3], v16, s77, v[4:5]
	v_lshl_add_u64 v[14:15], v[14:15], 1, v[16:17]
	v_add_u32_e32 v16, 0x1a00, v176
	v_mul_hi_i32 v17, v16, s93
	v_lshrrev_b32_e32 v20, 31, v17
	v_ashrrev_i32_e32 v17, 7, v17
	v_add_u32_e32 v17, v17, v20
	v_mad_i32_i24 v16, v17, s94, v16
	v_add_u32_e32 v20, s58, v17
	v_ashrrev_i32_e32 v17, 31, v16
	v_mad_i64_i32 v[20:21], s[2:3], v20, s77, v[4:5]
; __device__ __forceinline__ float bf2f(unsigned b) { return __uint_as_float(b << 16); }
; __device__ __forceinline__ void mla_sample_unit(LAS unsigned char* lds, size_t ws_q, size_t ws_olat, size_t ws_mixed, int b) {
;     ...
; #pragma unroll
;     for (int i = 0; i < 24; ++i) { const int idx = tid + 512 * i, t = idx / 768, c = idx - t * 768; QS[idx] = bf2f(Q[(size_t)(rowbase + t) * 768 + c]); }
;     __syncthreads();
	v_lshl_add_u64 v[16:17], v[16:17], 1, v[20:21]
	v_add_u32_e32 v20, 0x1c00, v176
	v_mul_hi_i32 v21, v20, s93
	v_lshrrev_b32_e32 v22, 31, v21
	v_ashrrev_i32_e32 v21, 7, v21
	v_add_u32_e32 v21, v21, v22
	v_mad_i32_i24 v20, v21, s94, v20
	v_add_u32_e32 v22, s58, v21
	v_ashrrev_i32_e32 v21, 31, v20
	v_mad_i64_i32 v[22:23], s[2:3], v22, s77, v[4:5]
	v_lshl_add_u64 v[20:21], v[20:21], 1, v[22:23]
	v_add_u32_e32 v22, 0x1e00, v176
	v_mul_hi_i32 v23, v22, s93
	v_lshrrev_b32_e32 v24, 31, v23
	v_ashrrev_i32_e32 v23, 7, v23
	v_add_u32_e32 v23, v23, v24
	v_mad_i32_i24 v22, v23, s94, v22
	v_add_u32_e32 v24, s58, v23
	v_ashrrev_i32_e32 v23, 31, v22
	v_mad_i64_i32 v[24:25], s[2:3], v24, s77, v[4:5]
	v_lshl_add_u64 v[22:23], v[22:23], 1, v[24:25]
	global_load_ushort v24, v[6:7], off
	global_load_ushort v25, v[8:9], off
	global_load_ushort v33, v[10:11], off
	global_load_ushort v34, v[12:13], off
	global_load_ushort v35, v[14:15], off
	global_load_ushort v36, v[16:17], off
	global_load_ushort v37, v[20:21], off
	global_load_ushort v38, v[22:23], off
	v_add_u32_e32 v6, 0x2000, v176
	v_mul_hi_i32 v7, v6, s93
	v_lshrrev_b32_e32 v8, 31, v7
	v_ashrrev_i32_e32 v7, 7, v7
	v_add_u32_e32 v7, v7, v8
	v_mad_i32_i24 v6, v7, s94, v6
	v_add_u32_e32 v8, s58, v7
	v_ashrrev_i32_e32 v7, 31, v6
	v_mad_i64_i32 v[8:9], s[2:3], v8, s77, v[4:5]
	v_lshl_add_u64 v[6:7], v[6:7], 1, v[8:9]
	v_add_u32_e32 v8, 0x2200, v176
	v_mul_hi_i32 v9, v8, s93
	v_lshrrev_b32_e32 v10, 31, v9
	v_ashrrev_i32_e32 v9, 7, v9
	v_add_u32_e32 v9, v9, v10
	v_mad_i32_i24 v8, v9, s94, v8
	v_add_u32_e32 v10, s58, v9
	v_ashrrev_i32_e32 v9, 31, v8
	v_mad_i64_i32 v[10:11], s[2:3], v10, s77, v[4:5]
	v_lshl_add_u64 v[8:9], v[8:9], 1, v[10:11]
	v_add_u32_e32 v10, 0x2400, v176
	v_mul_hi_i32 v11, v10, s93
	v_lshrrev_b32_e32 v12, 31, v11
	v_ashrrev_i32_e32 v11, 7, v11
	v_add_u32_e32 v11, v11, v12
	v_mad_i32_i24 v10, v11, s94, v10
	v_add_u32_e32 v12, s58, v11
	v_ashrrev_i32_e32 v11, 31, v10
	v_mad_i64_i32 v[12:13], s[2:3], v12, s77, v[4:5]
	v_lshl_add_u64 v[10:11], v[10:11], 1, v[12:13]
	v_add_u32_e32 v12, 0x2600, v176
	v_mul_hi_i32 v13, v12, s93
	v_lshrrev_b32_e32 v14, 31, v13
	v_ashrrev_i32_e32 v13, 7, v13
	v_add_u32_e32 v13, v13, v14
	v_mad_i32_i24 v12, v13, s94, v12
	v_add_u32_e32 v14, s58, v13
	v_ashrrev_i32_e32 v13, 31, v12
	v_mad_i64_i32 v[14:15], s[2:3], v14, s77, v[4:5]
	v_lshl_add_u64 v[12:13], v[12:13], 1, v[14:15]
	v_add_u32_e32 v14, 0x2800, v176
	v_mul_hi_i32 v15, v14, s93
	v_lshrrev_b32_e32 v16, 31, v15
	v_ashrrev_i32_e32 v15, 7, v15
	v_add_u32_e32 v15, v15, v16
	v_mad_i32_i24 v14, v15, s94, v14
	v_add_u32_e32 v16, s58, v15
	v_ashrrev_i32_e32 v15, 31, v14
	v_mad_i64_i32 v[16:17], s[2:3], v16, s77, v[4:5]
	v_lshl_add_u64 v[14:15], v[14:15], 1, v[16:17]
	v_add_u32_e32 v16, 0x2a00, v176
	v_mul_hi_i32 v17, v16, s93
	v_lshrrev_b32_e32 v20, 31, v17
	v_ashrrev_i32_e32 v17, 7, v17
	v_add_u32_e32 v17, v17, v20
	v_mad_i32_i24 v16, v17, s94, v16
	v_add_u32_e32 v20, s58, v17
	v_ashrrev_i32_e32 v17, 31, v16
	v_mad_i64_i32 v[20:21], s[2:3], v20, s77, v[4:5]
	v_lshl_add_u64 v[16:17], v[16:17], 1, v[20:21]
	v_add_u32_e32 v20, 0x2c00, v176
	v_mul_hi_i32 v21, v20, s93
	v_lshrrev_b32_e32 v22, 31, v21
	v_ashrrev_i32_e32 v21, 7, v21
	v_add_u32_e32 v21, v21, v22
	v_mad_i32_i24 v20, v21, s94, v20
	v_add_u32_e32 v22, s58, v21
	v_ashrrev_i32_e32 v21, 31, v20
	v_mad_i64_i32 v[22:23], s[2:3], v22, s77, v[4:5]
	v_lshl_add_u64 v[20:21], v[20:21], 1, v[22:23]
	global_load_ushort v22, v[6:7], off
	s_nop 0
	global_load_ushort v8, v[8:9], off
	s_nop 0
	global_load_ushort v9, v[10:11], off
	s_nop 0
	global_load_ushort v10, v[12:13], off
	global_load_ushort v11, v[14:15], off
	s_nop 0
	global_load_ushort v12, v[16:17], off
	global_load_ushort v13, v[20:21], off
	v_add_u32_e32 v6, 0x2e00, v176
	v_mul_hi_i32 v7, v6, s93
	v_lshrrev_b32_e32 v14, 31, v7
	v_ashrrev_i32_e32 v7, 7, v7
	v_add_u32_e32 v7, v7, v14
	v_mad_i32_i24 v6, v7, s94, v6
	v_add_u32_e32 v14, s58, v7
	v_ashrrev_i32_e32 v7, 31, v6
	v_mad_i64_i32 v[4:5], s[2:3], v14, s77, v[4:5]
	v_lshl_add_u64 v[4:5], v[6:7], 1, v[4:5]
	global_load_ushort v4, v[4:5], off
	s_waitcnt lgkmcnt(0)
	v_readfirstlane_b32 s3, v3
	v_readfirstlane_b32 s2, v2
	s_waitcnt vmcnt(0)
	v_lshlrev_b32_e32 v2, 16, v18
	v_lshl_add_u32 v3, v176, 2, 0
	v_lshlrev_b32_e32 v6, 16, v26
	ds_write2st64_b32 v3, v2, v6 offset0:168 offset1:176
	v_lshlrev_b32_e32 v2, 16, v27
	v_lshlrev_b32_e32 v6, 16, v28
	ds_write2st64_b32 v3, v2, v6 offset0:184 offset1:192
	v_lshlrev_b32_e32 v2, 16, v29
	v_lshlrev_b32_e32 v6, 16, v30
	ds_write2st64_b32 v3, v2, v6 offset0:200 offset1:208
	v_lshlrev_b32_e32 v2, 16, v31
	v_lshlrev_b32_e32 v6, 16, v32
	ds_write2st64_b32 v3, v2, v6 offset0:216 offset1:224
	v_lshlrev_b32_e32 v2, 16, v24
	v_lshlrev_b32_e32 v6, 16, v25
	ds_write2st64_b32 v3, v2, v6 offset0:232 offset1:240
	v_lshlrev_b32_e32 v2, 16, v33
	v_add_u32_e32 v5, 0xa800, v3
	ds_write_b32 v3, v2 offset:63488
	v_lshlrev_b32_e32 v2, 16, v34
	v_lshlrev_b32_e32 v3, 16, v35
	ds_write2st64_b32 v5, v2, v3 offset0:88 offset1:96
	v_lshlrev_b32_e32 v2, 16, v36
	v_lshlrev_b32_e32 v3, 16, v37
	ds_write2st64_b32 v5, v2, v3 offset0:104 offset1:112
	v_lshlrev_b32_e32 v2, 16, v38
	v_ashrrev_i32_e32 v154, 6, v176
	v_and_b32_e32 v50, -2, v154
	s_mov_b32 s8, 0
	s_mov_b64 s[6:7], -1
	v_lshlrev_b32_e32 v3, 16, v22
	ds_write2st64_b32 v5, v2, v3 offset0:120 offset1:128
	v_lshlrev_b32_e32 v2, 16, v8
	v_lshlrev_b32_e32 v3, 16, v9
	ds_write2st64_b32 v5, v2, v3 offset0:136 offset1:144
	v_lshlrev_b32_e32 v2, 16, v10
	v_lshlrev_b32_e32 v3, 16, v11
	ds_write2st64_b32 v5, v2, v3 offset0:152 offset1:160
	v_lshlrev_b32_e32 v2, 16, v12
	v_lshlrev_b32_e32 v3, 16, v13
	ds_write2st64_b32 v5, v2, v3 offset0:168 offset1:176
	v_lshlrev_b32_e32 v2, 16, v4
	ds_write_b32 v5, v2 offset:47104
	v_and_b32_e32 v2, 0x7f, v176
	v_lshlrev_b32_e32 v51, 3, v2
	v_lshl_add_u32 v18, v2, 1, 0
	s_waitcnt lgkmcnt(0)
	s_barrier

; #define LAS __attribute__((address_space(3)))
; __device__ __forceinline__ bf16 f2bf(float f) { return (bf16)(pk2(f, 0.f) & 0xffffu); }
; __device__ __forceinline__ void mla_sample_unit(LAS unsigned char* lds, size_t ws_q, size_t ws_olat, size_t ws_mixed, int b) {
;     ...
;     { const int r = tid & 127, hg = tid >> 7;
; #pragma unroll 1
;       for (int h2 = 0; h2 < 2; ++h2) { const int h = 2 * hg + h2; const float* wr = w_uk + (size_t)(r * 8 + h) * 64; float a[16];
; #pragma unroll
;           for (int t = 0; t < 16; ++t) a[t] = 0.f;
; #pragma unroll 4
;           for (int d4 = 0; d4 < 16; ++d4) { const f32x4 w = *(const f32x4*)(wr + 4 * d4);
; #pragma unroll
;               for (int t = 0; t < 16; ++t) { const f32x4 q = *(const LAS f32x4*)(QS + t * 768 + h * 96 + 4 * d4); a[t] += (w.x * q.x + w.y * q.y) + (w.z * q.z + w.w * q.w); } }
; #pragma unroll
;           for (int t = 0; t < 16; ++t) QA[(h * 16 + t) * KP + r] = f2bf(a[t]); }
.LBB0_686:
	global_load_dwordx4 v[14:17], v[20:21], off
	v_add_u32_e32 v54, s6, v53
	ds_read_b128 v[38:41], v54 offset:43008
	ds_read_b128 v[10:13], v54 offset:43024
	ds_read_b128 v[6:9], v54 offset:43040
	ds_read_b128 v[2:5], v54 offset:43056
	ds_read_b128 v[42:45], v54 offset:46080
	s_waitcnt lgkmcnt(0)
	v_mov_b32_e32 v47, v39
	s_add_i32 s6, s6, 64
	s_cmpk_eq_i32 s6, 0x100
	v_mov_b32_e32 v46, v42
	v_pk_mov_b32 v[38:39], v[42:43], v[38:39] op_sel:[1,0]
	v_mov_b32_e32 v42, v44
	v_mov_b32_e32 v43, v41
	v_pk_mov_b32 v[40:41], v[44:45], v[40:41] op_sel:[1,0]
	s_waitcnt vmcnt(0)
	v_pk_mul_f32 v[42:43], v[16:17], v[42:43]
	s_nop 0
	v_pk_fma_f32 v[40:41], v[16:17], v[40:41], v[42:43] op_sel:[1,0,0] op_sel_hi:[0,1,1]
	ds_read_b128 v[42:45], v54 offset:49152
	ds_read_b128 v[56:59], v54 offset:52224
	v_pk_mul_f32 v[46:47], v[14:15], v[46:47]
	s_nop 0
	v_pk_fma_f32 v[38:39], v[14:15], v[38:39], v[46:47] op_sel:[1,0,0] op_sel_hi:[0,1,1]
	v_pk_add_f32 v[38:39], v[38:39], v[40:41]
	s_nop 0
	v_pk_add_f32 v[40:41], v[22:23], v[38:39]
	s_waitcnt lgkmcnt(0)
	v_mov_b32_e32 v22, v56
	v_mov_b32_e32 v23, v43
	v_pk_mul_f32 v[22:23], v[14:15], v[22:23]
	v_pk_mov_b32 v[38:39], v[56:57], v[42:43] op_sel:[1,0]
	v_pk_mov_b32 v[42:43], v[58:59], v[44:45] op_sel:[1,0]
	v_pk_fma_f32 v[22:23], v[14:15], v[38:39], v[22:23] op_sel:[1,0,0] op_sel_hi:[0,1,1]
	v_mov_b32_e32 v38, v58
	v_mov_b32_e32 v39, v45
	v_pk_mul_f32 v[38:39], v[16:17], v[38:39]
	s_nop 0
	v_pk_fma_f32 v[38:39], v[16:17], v[42:43], v[38:39] op_sel:[1,0,0] op_sel_hi:[0,1,1]
	v_pk_add_f32 v[22:23], v[22:23], v[38:39]
	s_nop 0
	v_pk_add_f32 v[38:39], v[24:25], v[22:23]
	ds_read_b128 v[22:25], v54 offset:55296
	ds_read_b128 v[42:45], v54 offset:58368
	s_waitcnt lgkmcnt(1)
	v_mov_b32_e32 v47, v23
	s_waitcnt lgkmcnt(0)
	v_mov_b32_e32 v46, v42
	v_pk_mov_b32 v[22:23], v[42:43], v[22:23] op_sel:[1,0]
	v_mov_b32_e32 v42, v44
	v_mov_b32_e32 v43, v25
	v_pk_mul_f32 v[42:43], v[16:17], v[42:43]
	v_pk_mov_b32 v[24:25], v[44:45], v[24:25] op_sel:[1,0]
	v_pk_mul_f32 v[46:47], v[14:15], v[46:47]
	v_pk_fma_f32 v[24:25], v[16:17], v[24:25], v[42:43] op_sel:[1,0,0] op_sel_hi:[0,1,1]
	ds_read_b128 v[42:45], v54 offset:61440
	ds_read_b128 v[56:59], v54 offset:64512
	v_pk_fma_f32 v[22:23], v[14:15], v[22:23], v[46:47] op_sel:[1,0,0] op_sel_hi:[0,1,1]
	v_pk_add_f32 v[22:23], v[22:23], v[24:25]
	s_nop 0
	v_pk_add_f32 v[24:25], v[26:27], v[22:23]
	s_waitcnt lgkmcnt(0)
	v_mov_b32_e32 v22, v56
	v_mov_b32_e32 v23, v43
	v_pk_mul_f32 v[22:23], v[14:15], v[22:23]
	v_pk_mov_b32 v[26:27], v[56:57], v[42:43] op_sel:[1,0]
	v_pk_mov_b32 v[42:43], v[58:59], v[44:45] op_sel:[1,0]
	v_pk_fma_f32 v[22:23], v[14:15], v[26:27], v[22:23] op_sel:[1,0,0] op_sel_hi:[0,1,1]
	v_mov_b32_e32 v26, v58
	v_mov_b32_e32 v27, v45
	v_pk_mul_f32 v[26:27], v[16:17], v[26:27]
	s_nop 0
	v_pk_fma_f32 v[26:27], v[16:17], v[42:43], v[26:27] op_sel:[1,0,0] op_sel_hi:[0,1,1]
	v_pk_add_f32 v[22:23], v[22:23], v[26:27]
	v_add_u32_e32 v26, 0x10800, v54
	v_add_u32_e32 v42, 0x11400, v54
	v_pk_add_f32 v[22:23], v[28:29], v[22:23]
	ds_read_b128 v[26:29], v26
	ds_read_b128 v[42:45], v42
	s_waitcnt lgkmcnt(1)
	v_mov_b32_e32 v47, v27
	s_waitcnt lgkmcnt(0)
	v_mov_b32_e32 v46, v42
	v_pk_mov_b32 v[26:27], v[42:43], v[26:27] op_sel:[1,0]
	v_mov_b32_e32 v42, v44
	v_mov_b32_e32 v43, v29
	v_pk_mul_f32 v[46:47], v[14:15], v[46:47]
	v_pk_mul_f32 v[42:43], v[16:17], v[42:43]
	v_pk_mov_b32 v[28:29], v[44:45], v[28:29] op_sel:[1,0]
	v_pk_fma_f32 v[26:27], v[14:15], v[26:27], v[46:47] op_sel:[1,0,0] op_sel_hi:[0,1,1]
	v_pk_fma_f32 v[28:29], v[16:17], v[28:29], v[42:43] op_sel:[1,0,0] op_sel_hi:[0,1,1]
	v_pk_add_f32 v[26:27], v[26:27], v[28:29]
	v_add_u32_e32 v28, 0x12000, v54
	v_add_u32_e32 v42, 0x12c00, v54
	v_pk_add_f32 v[26:27], v[30:31], v[26:27]
	ds_read_b128 v[28:31], v28
	ds_read_b128 v[42:45], v42
	s_waitcnt lgkmcnt(1)
	v_mov_b32_e32 v47, v29
	s_waitcnt lgkmcnt(0)
	v_mov_b32_e32 v46, v42
	v_pk_mov_b32 v[28:29], v[42:43], v[28:29] op_sel:[1,0]
	v_mov_b32_e32 v42, v44
	v_mov_b32_e32 v43, v31
	v_pk_mul_f32 v[46:47], v[14:15], v[46:47]
	v_pk_mul_f32 v[42:43], v[16:17], v[42:43]
	v_pk_mov_b32 v[30:31], v[44:45], v[30:31] op_sel:[1,0]
	v_pk_fma_f32 v[28:29], v[14:15], v[28:29], v[46:47] op_sel:[1,0,0] op_sel_hi:[0,1,1]
	v_pk_fma_f32 v[30:31], v[16:17], v[30:31], v[42:43] op_sel:[1,0,0] op_sel_hi:[0,1,1]
	v_pk_add_f32 v[28:29], v[28:29], v[30:31]
	v_add_u32_e32 v30, 0x13800, v54
	v_add_u32_e32 v42, 0x14400, v54
	v_pk_add_f32 v[28:29], v[32:33], v[28:29]
	ds_read_b128 v[30:33], v30
	ds_read_b128 v[42:45], v42
	s_waitcnt lgkmcnt(0)
	v_pk_mov_b32 v[46:47], v[30:31], v[42:43] op_sel:[1,0]
	v_mov_b32_e32 v31, v43
	v_pk_mov_b32 v[42:43], v[32:33], v[44:45] op_sel:[1,0]
	v_mov_b32_e32 v33, v45
	v_pk_mul_f32 v[30:31], v[14:15], v[30:31]
	v_pk_mul_f32 v[32:33], v[16:17], v[32:33]
	v_pk_fma_f32 v[30:31], v[14:15], v[46:47], v[30:31] op_sel:[1,0,0] op_sel_hi:[0,1,1]
	v_pk_fma_f32 v[32:33], v[16:17], v[42:43], v[32:33] op_sel:[1,0,0] op_sel_hi:[0,1,1]
	v_pk_add_f32 v[30:31], v[30:31], v[32:33]
	v_add_u32_e32 v32, 0x15000, v54
	v_add_u32_e32 v42, 0x15c00, v54
	v_pk_add_f32 v[30:31], v[34:35], v[30:31]
	ds_read_b128 v[32:35], v32
	ds_read_b128 v[42:45], v42
	s_waitcnt lgkmcnt(0)
	v_pk_mov_b32 v[46:47], v[32:33], v[42:43] op_sel:[1,0]
	v_mov_b32_e32 v33, v43
	v_pk_mul_f32 v[32:33], v[14:15], v[32:33]
	v_mov_b32_e32 v43, v11
	v_pk_fma_f32 v[14:15], v[14:15], v[46:47], v[32:33] op_sel:[1,0,0] op_sel_hi:[0,1,1]
	v_pk_mov_b32 v[32:33], v[34:35], v[44:45] op_sel:[1,0]
	v_mov_b32_e32 v35, v45
	v_pk_mul_f32 v[34:35], v[16:17], v[34:35]
	s_nop 0
	v_pk_fma_f32 v[16:17], v[16:17], v[32:33], v[34:35] op_sel:[1,0,0] op_sel_hi:[0,1,1]
	v_pk_add_f32 v[14:15], v[14:15], v[16:17]
	s_nop 0
	v_pk_add_f32 v[32:33], v[36:37], v[14:15]
	global_load_dwordx4 v[14:17], v[20:21], off offset:16
	ds_read_b128 v[34:37], v54 offset:46096
	s_waitcnt lgkmcnt(0)
; #define LAS __attribute__((address_space(3)))
; __device__ __forceinline__ bf16 f2bf(float f) { return (bf16)(pk2(f, 0.f) & 0xffffu); }
; __device__ __forceinline__ void mla_sample_unit(LAS unsigned char* lds, size_t ws_q, size_t ws_olat, size_t ws_mixed, int b) {
;     ...
;       for (int h2 = 0; h2 < 2; ++h2) { const int h = 2 * hg + h2; const float* wr = w_uk + (size_t)(r * 8 + h) * 64; float a[16];
; #pragma unroll
;           for (int t = 0; t < 16; ++t) a[t] = 0.f;
; #pragma unroll 4
;           for (int d4 = 0; d4 < 16; ++d4) { const f32x4 w = *(const f32x4*)(wr + 4 * d4);
; #pragma unroll
;               for (int t = 0; t < 16; ++t) { const f32x4 q = *(const LAS f32x4*)(QS + t * 768 + h * 96 + 4 * d4); a[t] += (w.x * q.x + w.y * q.y) + (w.z * q.z + w.w * q.w); } }
; #pragma unroll
;           for (int t = 0; t < 16; ++t) QA[(h * 16 + t) * KP + r] = f2bf(a[t]); }
	v_mov_b32_e32 v42, v34
	v_pk_mov_b32 v[10:11], v[34:35], v[10:11] op_sel:[1,0]
	v_mov_b32_e32 v34, v36
	v_mov_b32_e32 v35, v13
	v_pk_mov_b32 v[12:13], v[36:37], v[12:13] op_sel:[1,0]
	s_waitcnt vmcnt(0)
	v_pk_mul_f32 v[42:43], v[14:15], v[42:43]
	v_pk_mul_f32 v[34:35], v[16:17], v[34:35]
	v_pk_fma_f32 v[10:11], v[14:15], v[10:11], v[42:43] op_sel:[1,0,0] op_sel_hi:[0,1,1]
	v_pk_fma_f32 v[12:13], v[16:17], v[12:13], v[34:35] op_sel:[1,0,0] op_sel_hi:[0,1,1]
	v_pk_add_f32 v[10:11], v[10:11], v[12:13]
	s_nop 0
	v_pk_add_f32 v[40:41], v[40:41], v[10:11]
	ds_read_b128 v[10:13], v54 offset:49168
	ds_read_b128 v[34:37], v54 offset:52240
	s_waitcnt lgkmcnt(1)
	v_mov_b32_e32 v43, v11
	s_waitcnt lgkmcnt(0)
	v_mov_b32_e32 v42, v34
	v_pk_mov_b32 v[10:11], v[34:35], v[10:11] op_sel:[1,0]
	v_mov_b32_e32 v34, v36
	v_mov_b32_e32 v35, v13
	v_pk_mul_f32 v[42:43], v[14:15], v[42:43]
	v_pk_mul_f32 v[34:35], v[16:17], v[34:35]
	v_pk_mov_b32 v[12:13], v[36:37], v[12:13] op_sel:[1,0]
	v_pk_fma_f32 v[10:11], v[14:15], v[10:11], v[42:43] op_sel:[1,0,0] op_sel_hi:[0,1,1]
	v_pk_fma_f32 v[12:13], v[16:17], v[12:13], v[34:35] op_sel:[1,0,0] op_sel_hi:[0,1,1]
	v_pk_add_f32 v[10:11], v[10:11], v[12:13]
	s_nop 0
	v_pk_add_f32 v[42:43], v[38:39], v[10:11]
	ds_read_b128 v[10:13], v54 offset:55312
	ds_read_b128 v[34:37], v54 offset:58384
	s_waitcnt lgkmcnt(1)
	v_mov_b32_e32 v39, v11
	s_waitcnt lgkmcnt(0)
	v_mov_b32_e32 v38, v34
	v_pk_mov_b32 v[10:11], v[34:35], v[10:11] op_sel:[1,0]
	v_mov_b32_e32 v34, v36
	v_mov_b32_e32 v35, v13
	v_pk_mul_f32 v[38:39], v[14:15], v[38:39]
	v_pk_mul_f32 v[34:35], v[16:17], v[34:35]
	v_pk_mov_b32 v[12:13], v[36:37], v[12:13] op_sel:[1,0]
	v_pk_fma_f32 v[10:11], v[14:15], v[10:11], v[38:39] op_sel:[1,0,0] op_sel_hi:[0,1,1]
	v_pk_fma_f32 v[12:13], v[16:17], v[12:13], v[34:35] op_sel:[1,0,0] op_sel_hi:[0,1,1]
	v_pk_add_f32 v[10:11], v[10:11], v[12:13]
	s_nop 0
	v_pk_add_f32 v[44:45], v[24:25], v[10:11]
	ds_read_b128 v[10:13], v54 offset:61456
	ds_read_b128 v[34:37], v54 offset:64528
	s_waitcnt lgkmcnt(1)
	v_mov_b32_e32 v25, v11
	s_waitcnt lgkmcnt(0)
	v_mov_b32_e32 v24, v34
	v_pk_mul_f32 v[24:25], v[14:15], v[24:25]
	v_pk_mov_b32 v[10:11], v[34:35], v[10:11] op_sel:[1,0]
	s_nop 0
	v_pk_fma_f32 v[10:11], v[14:15], v[10:11], v[24:25] op_sel:[1,0,0] op_sel_hi:[0,1,1]
	v_mov_b32_e32 v24, v36
	v_mov_b32_e32 v25, v13
	v_pk_mul_f32 v[24:25], v[16:17], v[24:25]
	v_pk_mov_b32 v[12:13], v[36:37], v[12:13] op_sel:[1,0]
	s_nop 0
	v_pk_fma_f32 v[12:13], v[16:17], v[12:13], v[24:25] op_sel:[1,0,0] op_sel_hi:[0,1,1]
	v_pk_add_f32 v[10:11], v[10:11], v[12:13]
	s_nop 0
	v_pk_add_f32 v[46:47], v[22:23], v[10:11]
	v_add_u32_e32 v10, 0x10810, v54
	v_add_u32_e32 v22, 0x11410, v54
	ds_read_b128 v[10:13], v10
	ds_read_b128 v[22:25], v22
	s_waitcnt lgkmcnt(1)
	v_mov_b32_e32 v35, v11
	s_waitcnt lgkmcnt(0)
	v_mov_b32_e32 v34, v22
	v_pk_mov_b32 v[10:11], v[22:23], v[10:11] op_sel:[1,0]
	v_mov_b32_e32 v22, v24
	v_mov_b32_e32 v23, v13
	v_pk_mul_f32 v[34:35], v[14:15], v[34:35]
	v_pk_mul_f32 v[22:23], v[16:17], v[22:23]
	v_pk_mov_b32 v[12:13], v[24:25], v[12:13] op_sel:[1,0]
	v_pk_fma_f32 v[10:11], v[14:15], v[10:11], v[34:35] op_sel:[1,0,0] op_sel_hi:[0,1,1]
	v_pk_fma_f32 v[12:13], v[16:17], v[12:13], v[22:23] op_sel:[1,0,0] op_sel_hi:[0,1,1]
	v_pk_add_f32 v[10:11], v[10:11], v[12:13]
	v_add_u32_e32 v22, 0x12c10, v54
	v_pk_add_f32 v[34:35], v[26:27], v[10:11]
	v_add_u32_e32 v10, 0x12010, v54
	ds_read_b128 v[10:13], v10
	ds_read_b128 v[22:25], v22
	s_waitcnt lgkmcnt(1)
	v_mov_b32_e32 v27, v11
	s_waitcnt lgkmcnt(0)
	v_mov_b32_e32 v26, v22
	v_pk_mov_b32 v[10:11], v[22:23], v[10:11] op_sel:[1,0]
	v_mov_b32_e32 v22, v24
	v_mov_b32_e32 v23, v13
	v_pk_mul_f32 v[26:27], v[14:15], v[26:27]
	v_pk_mul_f32 v[22:23], v[16:17], v[22:23]
	v_pk_mov_b32 v[12:13], v[24:25], v[12:13] op_sel:[1,0]
	v_pk_fma_f32 v[10:11], v[14:15], v[10:11], v[26:27] op_sel:[1,0,0] op_sel_hi:[0,1,1]
	v_pk_fma_f32 v[12:13], v[16:17], v[12:13], v[22:23] op_sel:[1,0,0] op_sel_hi:[0,1,1]
	v_pk_add_f32 v[10:11], v[10:11], v[12:13]
	v_add_u32_e32 v22, 0x14410, v54
	v_pk_add_f32 v[36:37], v[28:29], v[10:11]
	v_add_u32_e32 v10, 0x13810, v54
	ds_read_b128 v[10:13], v10
	ds_read_b128 v[22:25], v22
	s_waitcnt lgkmcnt(0)
	v_pk_mov_b32 v[26:27], v[10:11], v[22:23] op_sel:[1,0]
	v_mov_b32_e32 v11, v23
	v_pk_mov_b32 v[22:23], v[12:13], v[24:25] op_sel:[1,0]
	v_mov_b32_e32 v13, v25
	v_pk_mul_f32 v[10:11], v[14:15], v[10:11]
	v_pk_mul_f32 v[12:13], v[16:17], v[12:13]
	v_pk_fma_f32 v[10:11], v[14:15], v[26:27], v[10:11] op_sel:[1,0,0] op_sel_hi:[0,1,1]
	v_pk_fma_f32 v[12:13], v[16:17], v[22:23], v[12:13] op_sel:[1,0,0] op_sel_hi:[0,1,1]
	v_pk_add_f32 v[10:11], v[10:11], v[12:13]
	v_add_u32_e32 v22, 0x15c10, v54
	v_pk_add_f32 v[38:39], v[30:31], v[10:11]
	v_add_u32_e32 v10, 0x15010, v54
	ds_read_b128 v[10:13], v10
	ds_read_b128 v[22:25], v22
	s_waitcnt lgkmcnt(0)
	v_pk_mov_b32 v[26:27], v[10:11], v[22:23] op_sel:[1,0]
	v_mov_b32_e32 v11, v23
	v_pk_mul_f32 v[10:11], v[14:15], v[10:11]
	v_mov_b32_e32 v23, v7
	v_pk_fma_f32 v[10:11], v[14:15], v[26:27], v[10:11] op_sel:[1,0,0] op_sel_hi:[0,1,1]
	v_pk_mov_b32 v[14:15], v[12:13], v[24:25] op_sel:[1,0]
	v_mov_b32_e32 v13, v25
	v_pk_mul_f32 v[12:13], v[16:17], v[12:13]
	s_nop 0
	v_pk_fma_f32 v[12:13], v[16:17], v[14:15], v[12:13] op_sel:[1,0,0] op_sel_hi:[0,1,1]
	v_pk_add_f32 v[10:11], v[10:11], v[12:13]
	ds_read_b128 v[14:17], v54 offset:46112
	v_pk_add_f32 v[32:33], v[32:33], v[10:11]
	global_load_dwordx4 v[10:13], v[20:21], off offset:32
	s_waitcnt lgkmcnt(0)
	v_mov_b32_e32 v22, v14
	v_pk_mov_b32 v[6:7], v[14:15], v[6:7] op_sel:[1,0]
	v_mov_b32_e32 v14, v16
	v_mov_b32_e32 v15, v9
	v_pk_mov_b32 v[8:9], v[16:17], v[8:9] op_sel:[1,0]
	s_waitcnt vmcnt(0)
; #define LAS __attribute__((address_space(3)))
; __device__ __forceinline__ bf16 f2bf(float f) { return (bf16)(pk2(f, 0.f) & 0xffffu); }
; __device__ __forceinline__ void mla_sample_unit(LAS unsigned char* lds, size_t ws_q, size_t ws_olat, size_t ws_mixed, int b) {
;     ...
;       for (int h2 = 0; h2 < 2; ++h2) { const int h = 2 * hg + h2; const float* wr = w_uk + (size_t)(r * 8 + h) * 64; float a[16];
; #pragma unroll
;           for (int t = 0; t < 16; ++t) a[t] = 0.f;
; #pragma unroll 4
;           for (int d4 = 0; d4 < 16; ++d4) { const f32x4 w = *(const f32x4*)(wr + 4 * d4);
; #pragma unroll
;               for (int t = 0; t < 16; ++t) { const f32x4 q = *(const LAS f32x4*)(QS + t * 768 + h * 96 + 4 * d4); a[t] += (w.x * q.x + w.y * q.y) + (w.z * q.z + w.w * q.w); } }
; #pragma unroll
;           for (int t = 0; t < 16; ++t) QA[(h * 16 + t) * KP + r] = f2bf(a[t]); }
	v_pk_mul_f32 v[22:23], v[10:11], v[22:23]
	v_pk_mul_f32 v[14:15], v[12:13], v[14:15]
	v_pk_fma_f32 v[6:7], v[10:11], v[6:7], v[22:23] op_sel:[1,0,0] op_sel_hi:[0,1,1]
	v_pk_fma_f32 v[8:9], v[12:13], v[8:9], v[14:15] op_sel:[1,0,0] op_sel_hi:[0,1,1]
	v_pk_add_f32 v[6:7], v[6:7], v[8:9]
	s_nop 0
	v_pk_add_f32 v[22:23], v[40:41], v[6:7]
	ds_read_b128 v[6:9], v54 offset:49184
	ds_read_b128 v[14:17], v54 offset:52256
	s_waitcnt lgkmcnt(1)
	v_mov_b32_e32 v25, v7
	s_waitcnt lgkmcnt(0)
	v_mov_b32_e32 v24, v14
	v_pk_mov_b32 v[6:7], v[14:15], v[6:7] op_sel:[1,0]
	v_mov_b32_e32 v14, v16
	v_mov_b32_e32 v15, v9
	v_pk_mul_f32 v[24:25], v[10:11], v[24:25]
	v_pk_mul_f32 v[14:15], v[12:13], v[14:15]
	v_pk_mov_b32 v[8:9], v[16:17], v[8:9] op_sel:[1,0]
	v_pk_fma_f32 v[6:7], v[10:11], v[6:7], v[24:25] op_sel:[1,0,0] op_sel_hi:[0,1,1]
	v_pk_fma_f32 v[8:9], v[12:13], v[8:9], v[14:15] op_sel:[1,0,0] op_sel_hi:[0,1,1]
	v_pk_add_f32 v[6:7], v[6:7], v[8:9]
	s_nop 0
	v_pk_add_f32 v[24:25], v[42:43], v[6:7]
	ds_read_b128 v[6:9], v54 offset:55328
	ds_read_b128 v[14:17], v54 offset:58400
	s_waitcnt lgkmcnt(1)
	v_mov_b32_e32 v27, v7
	s_waitcnt lgkmcnt(0)
	v_mov_b32_e32 v26, v14
	v_pk_mov_b32 v[6:7], v[14:15], v[6:7] op_sel:[1,0]
	v_mov_b32_e32 v14, v16
	v_mov_b32_e32 v15, v9
	v_pk_mul_f32 v[26:27], v[10:11], v[26:27]
	v_pk_mul_f32 v[14:15], v[12:13], v[14:15]
	v_pk_mov_b32 v[8:9], v[16:17], v[8:9] op_sel:[1,0]
	v_pk_fma_f32 v[6:7], v[10:11], v[6:7], v[26:27] op_sel:[1,0,0] op_sel_hi:[0,1,1]
	v_pk_fma_f32 v[8:9], v[12:13], v[8:9], v[14:15] op_sel:[1,0,0] op_sel_hi:[0,1,1]
	v_pk_add_f32 v[6:7], v[6:7], v[8:9]
	s_nop 0
	v_pk_add_f32 v[26:27], v[44:45], v[6:7]
	ds_read_b128 v[6:9], v54 offset:61472
	ds_read_b128 v[14:17], v54 offset:64544
	s_waitcnt lgkmcnt(1)
	v_mov_b32_e32 v29, v7
	s_waitcnt lgkmcnt(0)
	v_mov_b32_e32 v28, v14
	v_pk_mov_b32 v[6:7], v[14:15], v[6:7] op_sel:[1,0]
	v_mov_b32_e32 v14, v16
	v_mov_b32_e32 v15, v9
	v_pk_mul_f32 v[28:29], v[10:11], v[28:29]
	v_pk_mul_f32 v[14:15], v[12:13], v[14:15]
	v_pk_mov_b32 v[8:9], v[16:17], v[8:9] op_sel:[1,0]
	v_pk_fma_f32 v[6:7], v[10:11], v[6:7], v[28:29] op_sel:[1,0,0] op_sel_hi:[0,1,1]
	v_pk_fma_f32 v[8:9], v[12:13], v[8:9], v[14:15] op_sel:[1,0,0] op_sel_hi:[0,1,1]
	v_pk_add_f32 v[6:7], v[6:7], v[8:9]
	v_add_u32_e32 v14, 0x11420, v54
	v_pk_add_f32 v[28:29], v[46:47], v[6:7]
	v_add_u32_e32 v6, 0x10820, v54
	ds_read_b128 v[6:9], v6
	ds_read_b128 v[14:17], v14
	s_waitcnt lgkmcnt(1)
	v_mov_b32_e32 v31, v7
	s_waitcnt lgkmcnt(0)
	v_mov_b32_e32 v30, v14
	v_pk_mov_b32 v[6:7], v[14:15], v[6:7] op_sel:[1,0]
	v_mov_b32_e32 v14, v16
	v_mov_b32_e32 v15, v9
	v_pk_mul_f32 v[30:31], v[10:11], v[30:31]
	v_pk_mul_f32 v[14:15], v[12:13], v[14:15]
	v_pk_mov_b32 v[8:9], v[16:17], v[8:9] op_sel:[1,0]
	v_pk_fma_f32 v[6:7], v[10:11], v[6:7], v[30:31] op_sel:[1,0,0] op_sel_hi:[0,1,1]
	v_pk_fma_f32 v[8:9], v[12:13], v[8:9], v[14:15] op_sel:[1,0,0] op_sel_hi:[0,1,1]
	v_pk_add_f32 v[6:7], v[6:7], v[8:9]
	v_add_u32_e32 v14, 0x12c20, v54
	v_pk_add_f32 v[30:31], v[34:35], v[6:7]
	v_add_u32_e32 v6, 0x12020, v54
	ds_read_b128 v[6:9], v6
	ds_read_b128 v[14:17], v14
	s_waitcnt lgkmcnt(1)
	v_mov_b32_e32 v35, v7
	s_waitcnt lgkmcnt(0)
	v_mov_b32_e32 v34, v14
	v_pk_mov_b32 v[6:7], v[14:15], v[6:7] op_sel:[1,0]
	v_mov_b32_e32 v14, v16
	v_mov_b32_e32 v15, v9
	v_pk_mul_f32 v[34:35], v[10:11], v[34:35]
	v_pk_mul_f32 v[14:15], v[12:13], v[14:15]
	v_pk_mov_b32 v[8:9], v[16:17], v[8:9] op_sel:[1,0]
	v_pk_fma_f32 v[6:7], v[10:11], v[6:7], v[34:35] op_sel:[1,0,0] op_sel_hi:[0,1,1]
	v_pk_fma_f32 v[8:9], v[12:13], v[8:9], v[14:15] op_sel:[1,0,0] op_sel_hi:[0,1,1]
	v_pk_add_f32 v[6:7], v[6:7], v[8:9]
	v_add_u32_e32 v14, 0x14420, v54
	v_pk_add_f32 v[16:17], v[36:37], v[6:7]
	v_add_u32_e32 v6, 0x13820, v54
	ds_read_b128 v[6:9], v6
	ds_read_b128 v[34:37], v14
	s_waitcnt lgkmcnt(0)
	v_pk_mov_b32 v[14:15], v[6:7], v[34:35] op_sel:[1,0]
	v_mov_b32_e32 v7, v35
	v_pk_mul_f32 v[6:7], v[10:11], v[6:7]
	v_add_u32_e32 v34, 0x15c20, v54
	v_pk_fma_f32 v[6:7], v[10:11], v[14:15], v[6:7] op_sel:[1,0,0] op_sel_hi:[0,1,1]
	v_pk_mov_b32 v[14:15], v[8:9], v[36:37] op_sel:[1,0]
	v_mov_b32_e32 v9, v37
	v_pk_mul_f32 v[8:9], v[12:13], v[8:9]
	ds_read_b128 v[34:37], v34
	v_pk_fma_f32 v[8:9], v[12:13], v[14:15], v[8:9] op_sel:[1,0,0] op_sel_hi:[0,1,1]
	v_pk_add_f32 v[6:7], v[6:7], v[8:9]
	s_nop 0
	v_pk_add_f32 v[14:15], v[38:39], v[6:7]
	v_add_u32_e32 v6, 0x15020, v54
	ds_read_b128 v[6:9], v6
	s_waitcnt lgkmcnt(0)
	v_pk_mov_b32 v[38:39], v[6:7], v[34:35] op_sel:[1,0]
	v_mov_b32_e32 v7, v35
	v_pk_mul_f32 v[6:7], v[10:11], v[6:7]
	s_nop 0
	v_pk_fma_f32 v[6:7], v[10:11], v[38:39], v[6:7] op_sel:[1,0,0] op_sel_hi:[0,1,1]
	v_pk_mov_b32 v[10:11], v[8:9], v[36:37] op_sel:[1,0]
	v_mov_b32_e32 v9, v37
	v_pk_mul_f32 v[8:9], v[12:13], v[8:9]
	s_nop 0
	v_pk_fma_f32 v[8:9], v[12:13], v[10:11], v[8:9] op_sel:[1,0,0] op_sel_hi:[0,1,1]
	v_pk_add_f32 v[6:7], v[6:7], v[8:9]
	v_mov_b32_e32 v13, v3
	v_pk_add_f32 v[10:11], v[32:33], v[6:7]
	global_load_dwordx4 v[6:9], v[20:21], off offset:48
	ds_read_b128 v[32:35], v54 offset:46128
	v_lshl_add_u64 v[20:21], v[20:21], 0, 64
	s_waitcnt lgkmcnt(0)
	v_mov_b32_e32 v12, v32
	v_pk_mov_b32 v[2:3], v[32:33], v[2:3] op_sel:[1,0]
	s_waitcnt vmcnt(0)
	v_pk_mul_f32 v[12:13], v[6:7], v[12:13]
	s_nop 0
	v_pk_fma_f32 v[2:3], v[6:7], v[2:3], v[12:13] op_sel:[1,0,0] op_sel_hi:[0,1,1]
	v_mov_b32_e32 v12, v34
	v_mov_b32_e32 v13, v5
	v_pk_mul_f32 v[12:13], v[8:9], v[12:13]
	v_pk_mov_b32 v[4:5], v[34:35], v[4:5] op_sel:[1,0]
	s_nop 0
	v_pk_fma_f32 v[4:5], v[8:9], v[4:5], v[12:13] op_sel:[1,0,0] op_sel_hi:[0,1,1]
	v_pk_add_f32 v[2:3], v[2:3], v[4:5]
	s_nop 0
	v_pk_add_f32 v[22:23], v[22:23], v[2:3]
	ds_read_b128 v[2:5], v54 offset:49200
	ds_read_b128 v[32:35], v54 offset:52272
	s_waitcnt lgkmcnt(1)
; #define LAS __attribute__((address_space(3)))
; __device__ __forceinline__ bf16 f2bf(float f) { return (bf16)(pk2(f, 0.f) & 0xffffu); }
; __device__ __forceinline__ void mla_sample_unit(LAS unsigned char* lds, size_t ws_q, size_t ws_olat, size_t ws_mixed, int b) {
;     ...
;       for (int h2 = 0; h2 < 2; ++h2) { const int h = 2 * hg + h2; const float* wr = w_uk + (size_t)(r * 8 + h) * 64; float a[16];
; #pragma unroll
;           for (int t = 0; t < 16; ++t) a[t] = 0.f;
; #pragma unroll 4
;           for (int d4 = 0; d4 < 16; ++d4) { const f32x4 w = *(const f32x4*)(wr + 4 * d4);
; #pragma unroll
;               for (int t = 0; t < 16; ++t) { const f32x4 q = *(const LAS f32x4*)(QS + t * 768 + h * 96 + 4 * d4); a[t] += (w.x * q.x + w.y * q.y) + (w.z * q.z + w.w * q.w); } }
; #pragma unroll
;           for (int t = 0; t < 16; ++t) QA[(h * 16 + t) * KP + r] = f2bf(a[t]); }
	v_mov_b32_e32 v13, v3
	s_waitcnt lgkmcnt(0)
	v_mov_b32_e32 v12, v32
	v_pk_mul_f32 v[12:13], v[6:7], v[12:13]
	v_pk_mov_b32 v[2:3], v[32:33], v[2:3] op_sel:[1,0]
	s_nop 0
	v_pk_fma_f32 v[2:3], v[6:7], v[2:3], v[12:13] op_sel:[1,0,0] op_sel_hi:[0,1,1]
	v_mov_b32_e32 v12, v34
	v_mov_b32_e32 v13, v5
	v_pk_mul_f32 v[12:13], v[8:9], v[12:13]
	v_pk_mov_b32 v[4:5], v[34:35], v[4:5] op_sel:[1,0]
	s_nop 0
	v_pk_fma_f32 v[4:5], v[8:9], v[4:5], v[12:13] op_sel:[1,0,0] op_sel_hi:[0,1,1]
	v_pk_add_f32 v[2:3], v[2:3], v[4:5]
	s_nop 0
	v_pk_add_f32 v[24:25], v[24:25], v[2:3]
	ds_read_b128 v[2:5], v54 offset:55344
	ds_read_b128 v[32:35], v54 offset:58416
	s_waitcnt lgkmcnt(1)
	v_mov_b32_e32 v13, v3
	s_waitcnt lgkmcnt(0)
	v_mov_b32_e32 v12, v32
	v_pk_mul_f32 v[12:13], v[6:7], v[12:13]
	v_pk_mov_b32 v[2:3], v[32:33], v[2:3] op_sel:[1,0]
	s_nop 0
	v_pk_fma_f32 v[2:3], v[6:7], v[2:3], v[12:13] op_sel:[1,0,0] op_sel_hi:[0,1,1]
	v_mov_b32_e32 v12, v34
	v_mov_b32_e32 v13, v5
	v_pk_mul_f32 v[12:13], v[8:9], v[12:13]
	v_pk_mov_b32 v[4:5], v[34:35], v[4:5] op_sel:[1,0]
	s_nop 0
	v_pk_fma_f32 v[4:5], v[8:9], v[4:5], v[12:13] op_sel:[1,0,0] op_sel_hi:[0,1,1]
	v_pk_add_f32 v[2:3], v[2:3], v[4:5]
	s_nop 0
	v_pk_add_f32 v[26:27], v[26:27], v[2:3]
	ds_read_b128 v[2:5], v54 offset:61488
	ds_read_b128 v[32:35], v54 offset:64560
	s_waitcnt lgkmcnt(1)
	v_mov_b32_e32 v13, v3
	s_waitcnt lgkmcnt(0)
	v_mov_b32_e32 v12, v32
	v_pk_mul_f32 v[12:13], v[6:7], v[12:13]
	v_pk_mov_b32 v[2:3], v[32:33], v[2:3] op_sel:[1,0]
	s_nop 0
	v_pk_fma_f32 v[2:3], v[6:7], v[2:3], v[12:13] op_sel:[1,0,0] op_sel_hi:[0,1,1]
	v_mov_b32_e32 v12, v34
	v_mov_b32_e32 v13, v5
	v_pk_mul_f32 v[12:13], v[8:9], v[12:13]
	v_pk_mov_b32 v[4:5], v[34:35], v[4:5] op_sel:[1,0]
	s_nop 0
	v_pk_fma_f32 v[4:5], v[8:9], v[4:5], v[12:13] op_sel:[1,0,0] op_sel_hi:[0,1,1]
	v_pk_add_f32 v[2:3], v[2:3], v[4:5]
	v_add_u32_e32 v12, 0x11430, v54
	v_pk_add_f32 v[28:29], v[28:29], v[2:3]
	v_add_u32_e32 v2, 0x10830, v54
	ds_read_b128 v[2:5], v2
	ds_read_b128 v[32:35], v12
	s_waitcnt lgkmcnt(1)
	v_mov_b32_e32 v13, v3
	s_waitcnt lgkmcnt(0)
	v_mov_b32_e32 v12, v32
	v_pk_mul_f32 v[12:13], v[6:7], v[12:13]
	v_pk_mov_b32 v[2:3], v[32:33], v[2:3] op_sel:[1,0]
	s_nop 0
	v_pk_fma_f32 v[2:3], v[6:7], v[2:3], v[12:13] op_sel:[1,0,0] op_sel_hi:[0,1,1]
	v_mov_b32_e32 v12, v34
	v_mov_b32_e32 v13, v5
	v_pk_mul_f32 v[12:13], v[8:9], v[12:13]
	v_pk_mov_b32 v[4:5], v[34:35], v[4:5] op_sel:[1,0]
	s_nop 0
	v_pk_fma_f32 v[4:5], v[8:9], v[4:5], v[12:13] op_sel:[1,0,0] op_sel_hi:[0,1,1]
	v_pk_add_f32 v[2:3], v[2:3], v[4:5]
	v_add_u32_e32 v12, 0x12c30, v54
	v_pk_add_f32 v[30:31], v[30:31], v[2:3]
	v_add_u32_e32 v2, 0x12030, v54
	ds_read_b128 v[2:5], v2
	ds_read_b128 v[32:35], v12
	s_waitcnt lgkmcnt(1)
	v_mov_b32_e32 v13, v3
	s_waitcnt lgkmcnt(0)
	v_mov_b32_e32 v12, v32
	v_pk_mul_f32 v[12:13], v[6:7], v[12:13]
	v_pk_mov_b32 v[2:3], v[32:33], v[2:3] op_sel:[1,0]
	s_nop 0
	v_pk_fma_f32 v[2:3], v[6:7], v[2:3], v[12:13] op_sel:[1,0,0] op_sel_hi:[0,1,1]
	v_mov_b32_e32 v12, v34
	v_mov_b32_e32 v13, v5
	v_pk_mul_f32 v[12:13], v[8:9], v[12:13]
	v_pk_mov_b32 v[4:5], v[34:35], v[4:5] op_sel:[1,0]
	s_nop 0
	v_pk_fma_f32 v[4:5], v[8:9], v[4:5], v[12:13] op_sel:[1,0,0] op_sel_hi:[0,1,1]
	v_pk_add_f32 v[2:3], v[2:3], v[4:5]
	v_add_u32_e32 v12, 0x14430, v54
	v_pk_add_f32 v[32:33], v[16:17], v[2:3]
	v_add_u32_e32 v2, 0x13830, v54
	ds_read_b128 v[2:5], v2
	ds_read_b128 v[34:37], v12
	s_waitcnt lgkmcnt(0)
	v_pk_mov_b32 v[12:13], v[2:3], v[34:35] op_sel:[1,0]
	v_mov_b32_e32 v3, v35
	v_pk_mul_f32 v[2:3], v[6:7], v[2:3]
	s_nop 0
	v_pk_fma_f32 v[2:3], v[6:7], v[12:13], v[2:3] op_sel:[1,0,0] op_sel_hi:[0,1,1]
	v_pk_mov_b32 v[12:13], v[4:5], v[36:37] op_sel:[1,0]
	v_mov_b32_e32 v5, v37
	v_pk_mul_f32 v[4:5], v[8:9], v[4:5]
	s_nop 0
	v_pk_fma_f32 v[4:5], v[8:9], v[12:13], v[4:5] op_sel:[1,0,0] op_sel_hi:[0,1,1]
	v_pk_add_f32 v[2:3], v[2:3], v[4:5]
	v_add_u32_e32 v12, 0x15c30, v54
	v_pk_add_f32 v[34:35], v[14:15], v[2:3]
	v_add_u32_e32 v2, 0x15030, v54
	ds_read_b128 v[2:5], v2
	ds_read_b128 v[12:15], v12
	s_waitcnt lgkmcnt(0)
	v_pk_mov_b32 v[16:17], v[2:3], v[12:13] op_sel:[1,0]
	v_mov_b32_e32 v3, v13
	v_pk_mul_f32 v[2:3], v[6:7], v[2:3]
	s_nop 0
	v_pk_fma_f32 v[2:3], v[6:7], v[16:17], v[2:3] op_sel:[1,0,0] op_sel_hi:[0,1,1]
	v_pk_mov_b32 v[6:7], v[4:5], v[14:15] op_sel:[1,0]
	v_mov_b32_e32 v5, v15
	v_pk_mul_f32 v[4:5], v[8:9], v[4:5]
	s_nop 0
	v_pk_fma_f32 v[4:5], v[8:9], v[6:7], v[4:5] op_sel:[1,0,0] op_sel_hi:[0,1,1]
	v_pk_add_f32 v[2:3], v[2:3], v[4:5]
	s_nop 0
	v_pk_add_f32 v[36:37], v[10:11], v[2:3]
	s_cbranch_scc0 .LBB0_686
	s_movk_i32 s6, 0x1500
	v_mad_u64_u32 v[2:3], s[6:7], v52, s6, v[18:19]
	v_cvt_pk_bf16_f32 v3, v22, s0
	ds_write_b16 v2, v3 offset:336
	v_cvt_pk_bf16_f32 v3, v25, s0
	ds_write_b16 v2, v3 offset:672
	v_cvt_pk_bf16_f32 v3, v24, s0
	ds_write_b16 v2, v3 offset:1008
	v_cvt_pk_bf16_f32 v3, v27, s0
	ds_write_b16 v2, v3 offset:1344
	v_cvt_pk_bf16_f32 v3, v26, s0
	ds_write_b16 v2, v3 offset:1680
	v_cvt_pk_bf16_f32 v3, v29, s0
	ds_write_b16 v2, v3 offset:2016
	v_cvt_pk_bf16_f32 v3, v28, s0
	ds_write_b16 v2, v3 offset:2352
	v_cvt_pk_bf16_f32 v3, v31, s0
	ds_write_b16 v2, v3 offset:2688
	v_cvt_pk_bf16_f32 v3, v30, s0
	ds_write_b16 v2, v3 offset:3024
	v_cvt_pk_bf16_f32 v3, v33, s0
	ds_write_b16 v2, v3 offset:3360
	v_cvt_pk_bf16_f32 v3, v32, s0
	ds_write_b16 v2, v3 offset:3696
	v_cvt_pk_bf16_f32 v3, v34, s0
	ds_write_b16 v2, v3 offset:4032
	v_cvt_pk_bf16_f32 v3, v35, s0
	ds_write_b16 v2, v3 offset:4368
	v_cvt_pk_bf16_f32 v3, v36, s0
	v_cvt_pk_bf16_f32 v4, v23, s0
	ds_write_b16 v2, v3 offset:4704
	v_cvt_pk_bf16_f32 v3, v37, s0
	s_mov_b32 s8, 1
	s_mov_b64 s[6:7], 0
	s_and_b64 vcc, exec, s[4:5]
	ds_write_b16 v2, v4
	ds_write_b16 v2, v3 offset:5040
	s_cbranch_vccz .LBB0_685
; __device__ __forceinline__ bf16 f2bf(float f) { return (bf16)(pk2(f, 0.f) & 0xffffu); }
; __device__ __forceinline__ float ex2f(float x) { return __builtin_amdgcn_exp2f(x); }
; __device__ __forceinline__ void mla_sample_unit(LAS unsigned char* lds, size_t ws_q, size_t ws_olat, size_t ws_mixed, int b) {
;     ...
; #pragma unroll
;       for (int i = 0; i < 8; ++i) { const int idx = tid + 512 * i, row = idx >> 5, i32 = idx & 31, ii = i32 & 15, h = row >> 4, t = row & 15;
;           const float x1 = QS[t * 768 + h * 96 + 64 + ii], x2 = QS[t * 768 + h * 96 + 80 + ii]; float sn, cs; sincos_rev((float)(PAST + t) * ex2f(-(float)ii * (2.0f / 32.0f) * LG2_10000), sn, cs);
;           QA[row * KP + 128 + i32] = f2bf(i32 < 16 ? x1 * cs - x2 * sn : x2 * cs + x1 * sn); } }
;     }
;     __syncthreads();
	v_and_b32_e32 v2, 15, v179
	v_cvt_f32_ubyte0_e32 v3, v2
	v_ashrrev_i32_e32 v5, 5, v176
	v_mul_f32_e32 v3, 0xbd800000, v3
	v_and_b32_e32 v6, 15, v5
	v_mul_f32_e32 v3, 0x41549a78, v3
	v_lshlrev_b32_e32 v8, 2, v2
	v_or_b32_e32 v2, 0x800, v6
	v_exp_f32_e32 v4, v3
	v_mad_u32_u24 v7, v6, s89, 0
	v_cvt_f32_u32_e32 v6, v2
	v_ashrrev_i32_e32 v3, 9, v176
	v_mul_i32_i24_e32 v3, 0x180, v3
	v_add3_u32 v2, v7, v3, v8
	v_mul_f32_e32 v6, v4, v6
	v_mul_f32_e32 v7, 0.15915494, v6
	v_add_u32_e32 v2, 0xa800, v2
	v_floor_f32_e32 v7, v7
	ds_read2_b32 v[2:3], v2 offset0:64 offset1:80
	v_fma_f32 v6, v6, 0.15915494, -v7
	v_sin_f32_e32 v7, v6
	v_cos_f32_e32 v6, v6
	v_and_b32_e32 v159, 31, v179
	v_cmp_gt_u32_e32 vcc, 16, v159
	s_waitcnt lgkmcnt(0)
	v_mul_f32_e32 v9, v7, v3
	v_mul_f32_e32 v3, v6, v3
	v_fma_f32 v9, v6, v2, -v9
	v_fmac_f32_e32 v3, v7, v2
	v_cndmask_b32_e32 v2, v3, v9, vcc
	v_ashrrev_i32_e32 v9, 5, v178
	v_and_b32_e32 v3, 15, v9
	v_mad_u32_u24 v10, v3, s89, 0
	v_or_b32_e32 v3, 0x800, v3
	v_cvt_f32_u32_e32 v11, v3
	v_cvt_pk_bf16_f32 v6, v2, s0
	v_ashrrev_i32_e32 v2, 9, v178
	v_mul_i32_i24_e32 v2, 0x180, v2
	v_add3_u32 v2, v10, v2, v8
	v_mul_f32_e32 v10, v4, v11
	v_mul_f32_e32 v11, 0.15915494, v10
	v_add_u32_e32 v2, 0xa800, v2
	v_floor_f32_e32 v11, v11
	ds_read2_b32 v[2:3], v2 offset0:64 offset1:80
	v_fma_f32 v10, v10, 0.15915494, -v11
	v_sin_f32_e32 v11, v10
	v_cos_f32_e32 v10, v10
	v_mul_lo_u32 v5, v5, s96
	v_lshlrev_b32_e32 v7, 1, v159
	v_add3_u32 v5, 0, v5, v7
	ds_write_b16 v5, v6 offset:256
	s_waitcnt lgkmcnt(1)
	v_mul_f32_e32 v5, v11, v3
	v_mul_f32_e32 v3, v10, v3
	v_fma_f32 v5, v10, v2, -v5
	v_fmac_f32_e32 v3, v11, v2
	v_mul_lo_u32 v6, v9, s96
	v_ashrrev_i32_e32 v9, 5, v177
	v_cndmask_b32_e32 v2, v3, v5, vcc
	v_and_b32_e32 v3, 15, v9
	v_mad_u32_u24 v10, v3, s89, 0
	v_or_b32_e32 v3, 0x800, v3
	v_cvt_f32_u32_e32 v11, v3
	v_cvt_pk_bf16_f32 v5, v2, s0
	v_ashrrev_i32_e32 v2, 9, v177
	v_mul_i32_i24_e32 v2, 0x180, v2
	v_add3_u32 v2, v10, v2, v8
	v_mul_f32_e32 v10, v4, v11
	v_mul_f32_e32 v11, 0.15915494, v10
	v_add_u32_e32 v2, 0xa800, v2
	v_floor_f32_e32 v11, v11
	ds_read2_b32 v[2:3], v2 offset0:64 offset1:80
	v_fma_f32 v10, v10, 0.15915494, -v11
	v_sin_f32_e32 v11, v10
	v_cos_f32_e32 v10, v10
	v_add3_u32 v6, 0, v6, v7
	ds_write_b16 v6, v5 offset:256
	s_waitcnt lgkmcnt(1)
	v_mul_f32_e32 v5, v11, v3
	v_mul_f32_e32 v3, v10, v3
	v_fma_f32 v5, v10, v2, -v5
	v_fmac_f32_e32 v3, v11, v2
	v_mul_lo_u32 v6, v9, s96
	v_ashrrev_i32_e32 v9, 5, v155
	v_cndmask_b32_e32 v2, v3, v5, vcc
	v_and_b32_e32 v3, 15, v9
	v_mad_u32_u24 v10, v3, s89, 0
	v_or_b32_e32 v3, 0x800, v3
	v_cvt_f32_u32_e32 v11, v3
	v_cvt_pk_bf16_f32 v5, v2, s0
	v_ashrrev_i32_e32 v2, 9, v155
	v_mul_i32_i24_e32 v2, 0x180, v2
	v_add3_u32 v2, v10, v2, v8
	v_mul_f32_e32 v10, v4, v11
	v_mul_f32_e32 v11, 0.15915494, v10
	v_add_u32_e32 v2, 0xa800, v2
	v_floor_f32_e32 v11, v11
	ds_read2_b32 v[2:3], v2 offset0:64 offset1:80
	v_fma_f32 v10, v10, 0.15915494, -v11
	v_sin_f32_e32 v11, v10
	v_cos_f32_e32 v10, v10
	v_add3_u32 v6, 0, v6, v7
	ds_write_b16 v6, v5 offset:256
	s_waitcnt lgkmcnt(1)
	v_mul_f32_e32 v5, v11, v3
	v_mul_f32_e32 v3, v10, v3
	v_fma_f32 v5, v10, v2, -v5
	v_fmac_f32_e32 v3, v11, v2
	v_mul_lo_u32 v6, v9, s96
	v_ashrrev_i32_e32 v9, 5, v49
	v_cndmask_b32_e32 v2, v3, v5, vcc
	v_and_b32_e32 v3, 15, v9
	v_mad_u32_u24 v10, v3, s89, 0
	v_or_b32_e32 v3, 0x800, v3
	v_cvt_f32_u32_e32 v11, v3
	v_cvt_pk_bf16_f32 v5, v2, s0
	v_ashrrev_i32_e32 v2, 9, v49
	v_mul_i32_i24_e32 v2, 0x180, v2
	v_add3_u32 v2, v10, v2, v8
	v_mul_f32_e32 v10, v4, v11
	v_mul_f32_e32 v11, 0.15915494, v10
	v_add_u32_e32 v2, 0xa800, v2
	v_floor_f32_e32 v11, v11
	ds_read2_b32 v[2:3], v2 offset0:64 offset1:80
	v_fma_f32 v10, v10, 0.15915494, -v11
	v_sin_f32_e32 v11, v10
	v_cos_f32_e32 v10, v10
	v_add3_u32 v6, 0, v6, v7
	ds_write_b16 v6, v5 offset:256
	s_waitcnt lgkmcnt(1)
	v_mul_f32_e32 v5, v11, v3
	v_mul_f32_e32 v3, v10, v3
	v_fma_f32 v5, v10, v2, -v5
	v_fmac_f32_e32 v3, v11, v2
	v_mul_lo_u32 v6, v9, s96
	v_ashrrev_i32_e32 v9, 5, v48
	v_cndmask_b32_e32 v2, v3, v5, vcc
	v_and_b32_e32 v3, 15, v9
	v_mad_u32_u24 v10, v3, s89, 0
	v_or_b32_e32 v3, 0x800, v3
	v_cvt_f32_u32_e32 v11, v3
	v_cvt_pk_bf16_f32 v5, v2, s0
	v_ashrrev_i32_e32 v2, 9, v48
	v_mul_i32_i24_e32 v2, 0x180, v2
	v_add3_u32 v2, v10, v2, v8
	v_mul_f32_e32 v10, v4, v11
	v_mul_f32_e32 v11, 0.15915494, v10
	v_add_u32_e32 v2, 0xa800, v2
	v_floor_f32_e32 v11, v11
	ds_read2_b32 v[2:3], v2 offset0:64 offset1:80
	v_fma_f32 v10, v10, 0.15915494, -v11
	v_sin_f32_e32 v11, v10
	v_cos_f32_e32 v10, v10
	v_add3_u32 v6, 0, v6, v7
	ds_write_b16 v6, v5 offset:256
	s_waitcnt lgkmcnt(1)
	v_mul_f32_e32 v5, v11, v3
	v_mul_f32_e32 v3, v10, v3
	v_fma_f32 v5, v10, v2, -v5
	v_fmac_f32_e32 v3, v11, v2
	v_mul_lo_u32 v6, v9, s96
	v_ashrrev_i32_e32 v9, 5, v19
	v_cndmask_b32_e32 v2, v3, v5, vcc
	v_and_b32_e32 v3, 15, v9
	v_mad_u32_u24 v10, v3, s89, 0
	v_or_b32_e32 v3, 0x800, v3
	v_cvt_f32_u32_e32 v11, v3
	v_cvt_pk_bf16_f32 v5, v2, s0
	v_ashrrev_i32_e32 v2, 9, v19
	v_mul_i32_i24_e32 v2, 0x180, v2
	v_add3_u32 v2, v10, v2, v8
	v_mul_f32_e32 v10, v4, v11
	v_mul_f32_e32 v11, 0.15915494, v10
	v_add_u32_e32 v2, 0xa800, v2
	v_floor_f32_e32 v11, v11
	ds_read2_b32 v[2:3], v2 offset0:64 offset1:80
	v_fma_f32 v10, v10, 0.15915494, -v11
	v_sin_f32_e32 v11, v10
	v_cos_f32_e32 v10, v10
	v_add3_u32 v6, 0, v6, v7
	ds_write_b16 v6, v5 offset:256
	s_waitcnt lgkmcnt(1)
	v_mul_f32_e32 v5, v11, v3
	v_mul_f32_e32 v3, v10, v3
	v_fma_f32 v5, v10, v2, -v5
	v_fmac_f32_e32 v3, v11, v2
	v_cndmask_b32_e32 v2, v3, v5, vcc
	v_mul_lo_u32 v6, v9, s96
	v_ashrrev_i32_e32 v9, 5, v1
	v_cvt_pk_bf16_f32 v5, v2, s0
	v_and_b32_e32 v2, 15, v9
	v_mad_u32_u24 v3, v2, s89, 0
	v_or_b32_e32 v2, 0x800, v2
	v_ashrrev_i32_e32 v1, 9, v1
	v_cvt_f32_u32_e32 v10, v2
	v_mul_i32_i24_e32 v1, 0x180, v1
	v_add3_u32 v1, v3, v1, v8
	v_add_u32_e32 v1, 0xa800, v1
	ds_read2_b32 v[2:3], v1 offset0:64 offset1:80
	v_mul_f32_e32 v1, v4, v10
	v_mul_f32_e32 v4, 0.15915494, v1
	v_floor_f32_e32 v4, v4
	v_fma_f32 v1, v1, 0.15915494, -v4
	v_sin_f32_e32 v4, v1
	v_cos_f32_e32 v1, v1
	v_add3_u32 v6, 0, v6, v7
	ds_write_b16 v6, v5 offset:256
	s_waitcnt lgkmcnt(1)
	v_mul_f32_e32 v5, v4, v3
	v_fma_f32 v5, v1, v2, -v5
	v_mul_f32_e32 v1, v1, v3
	v_fmac_f32_e32 v1, v4, v2
	v_cndmask_b32_e32 v1, v1, v5, vcc
	v_mul_lo_u32 v2, v9, s96
	v_cvt_pk_bf16_f32 v1, v1, s0
	v_add3_u32 v2, 0, v2, v7
	v_readlane_b32 s2, v254, 17
	ds_write_b16 v2, v1 offset:256
	s_waitcnt lgkmcnt(0)
	v_mov_b32_e32 v1, s2
	s_barrier
; #define LAS __attribute__((address_space(3)))
; #define INP(i) ((const float*)tab_get(lds, (i)))
; #define OUTP() ((float*)tab_get(lds, 30))
; __device__ __forceinline__ void mla_sample_unit(LAS unsigned char* lds, size_t ws_q, size_t ws_olat, size_t ws_mixed, int b) {
;     ...
;     const float *c_ckv = INP(2), *c_kr = INP(3); const float* n_ckv = OUTP() + O_SCKV; const float* n_kr = OUTP() + O_SKR;
;     const LAS unsigned char* qb_ = lds + (((wid & 3) * 32 + r32) * KP + 8 * hi) * 2;
;     f32x4 pre[10];
;     ...
;     AS_GLOAD(0); AS_LSTORE(); __syncthreads();
	ds_read_b64 v[2:3], v1
	v_readlane_b32 s2, v254, 18
	v_mov_b32_e32 v180, v176
	s_lshl_b32 s72, s57, 11
	v_mov_b32_e32 v1, s2
	ds_read_b64 v[4:5], v1
	v_mov_b32_e32 v1, s73
	s_waitcnt lgkmcnt(1)
	v_readfirstlane_b32 s61, v3
	ds_read_b64 v[6:7], v1
	v_readfirstlane_b32 s60, v2
	ds_read_b64 v[2:3], v1
	s_waitcnt lgkmcnt(2)
	v_readfirstlane_b32 s62, v4
	v_and_b32_e32 v1, 15, v180
	v_cmp_lt_i32_e32 vcc, s0, v180
	s_waitcnt lgkmcnt(0)
	v_readfirstlane_b32 s64, v2
	v_lshrrev_b32_e32 v2, 2, v180
	v_and_or_b32 v8, v2, 48, v1
	v_cndmask_b32_e32 v2, 0, v172, vcc
	v_add_u32_e32 v2, v2, v180
	v_lshrrev_b32_e32 v1, 4, v180
	v_ashrrev_i32_e32 v2, 6, v2
	v_bfi_b32 v1, -4, v2, v1
	v_cndmask_b32_e64 v2, 0, 64, vcc
	v_or3_b32 v4, s72, v2, v8
	v_readfirstlane_b32 s59, v154
	v_readfirstlane_b32 s63, v5
	v_readfirstlane_b32 s92, v7
	v_readfirstlane_b32 s97, v6
	v_readfirstlane_b32 s65, v3
	v_cmp_gt_i32_e64 s[2:3], 32, v1
	v_cmp_lt_i32_e64 s[4:5], 31, v1
	v_ashrrev_i32_e32 v5, 31, v4
	v_lshlrev_b32_e32 v2, 2, v1
	s_and_saveexec_b64 s[6:7], s[4:5]
	s_xor_b64 s[4:5], exec, s[6:7]
	v_lshlrev_b64 v[4:5], 7, v[4:5]
	v_lshl_add_u64 v[4:5], s[62:63], 0, v[4:5]
	v_mov_b32_e32 v3, v0
	v_lshl_add_u64 v[2:3], v[2:3], 2, v[4:5]
	v_lshl_add_u64 v[6:7], v[2:3], 0, s[50:51]
	s_andn2_saveexec_b64 s[4:5], s[4:5]
	v_lshlrev_b64 v[4:5], 9, v[4:5]
	v_ashrrev_i32_e32 v3, 31, v2
	v_lshl_add_u64 v[4:5], s[60:61], 0, v[4:5]
	v_lshl_add_u64 v[6:7], v[2:3], 2, v[4:5]
	s_or_b64 exec, exec, s[4:5]
	global_load_dwordx4 v[112:115], v[6:7], off
	v_cmp_lt_i32_e64 s[4:5], s1, v180
	v_bfe_u32 v13, v180, 4, 2
	s_nop 0
	v_cndmask_b32_e64 v2, 0, v172, s[4:5]
	v_add3_u32 v2, v180, v2, s75
	v_ashrrev_i32_e32 v2, 6, v2
	v_and_or_b32 v9, v2, -4, v13
	v_cndmask_b32_e64 v2, 0, 64, s[4:5]
	v_or3_b32 v4, v2, s72, v8
	v_cmp_gt_i32_e64 s[6:7], 32, v9
	v_cmp_lt_i32_e64 s[8:9], 31, v9
	v_ashrrev_i32_e32 v5, 31, v4
	v_lshlrev_b32_e32 v2, 2, v9
	s_and_saveexec_b64 s[10:11], s[8:9]
	s_xor_b64 s[8:9], exec, s[10:11]
	v_lshlrev_b64 v[4:5], 7, v[4:5]
	v_lshl_add_u64 v[4:5], s[62:63], 0, v[4:5]
	v_mov_b32_e32 v3, v0
	v_lshl_add_u64 v[2:3], v[2:3], 2, v[4:5]
	v_lshl_add_u64 v[6:7], v[2:3], 0, s[50:51]
	s_andn2_saveexec_b64 s[8:9], s[8:9]
	v_lshlrev_b64 v[4:5], 9, v[4:5]
	v_ashrrev_i32_e32 v3, 31, v2
	v_lshl_add_u64 v[4:5], s[60:61], 0, v[4:5]
	v_lshl_add_u64 v[6:7], v[2:3], 2, v[4:5]
	s_or_b64 exec, exec, s[8:9]
	global_load_dwordx4 v[116:119], v[6:7], off
	v_cmp_lt_i32_e64 s[8:9], s78, v180
	s_nop 1
	v_cndmask_b32_e64 v2, 0, v172, s[8:9]
	v_add3_u32 v2, v180, v2, s76
	v_ashrrev_i32_e32 v2, 6, v2
	v_and_or_b32 v10, v2, -4, v13
	v_cndmask_b32_e64 v2, 0, 64, s[8:9]
	v_or3_b32 v4, v2, s72, v8
	v_cmp_gt_i32_e64 s[10:11], 32, v10
	v_cmp_lt_i32_e64 s[12:13], 31, v10
	v_ashrrev_i32_e32 v5, 31, v4
	v_lshlrev_b32_e32 v2, 2, v10
	s_and_saveexec_b64 s[14:15], s[12:13]
	s_xor_b64 s[12:13], exec, s[14:15]
	v_lshlrev_b64 v[4:5], 7, v[4:5]
	v_lshl_add_u64 v[4:5], s[62:63], 0, v[4:5]
	v_mov_b32_e32 v3, v0
	v_lshl_add_u64 v[2:3], v[2:3], 2, v[4:5]
	v_lshl_add_u64 v[6:7], v[2:3], 0, s[50:51]
	s_andn2_saveexec_b64 s[12:13], s[12:13]
	v_lshlrev_b64 v[4:5], 9, v[4:5]
	v_ashrrev_i32_e32 v3, 31, v2
	v_lshl_add_u64 v[4:5], s[60:61], 0, v[4:5]
	v_lshl_add_u64 v[6:7], v[2:3], 2, v[4:5]
	s_or_b64 exec, exec, s[12:13]
	global_load_dwordx4 v[120:123], v[6:7], off
	v_cmp_lt_i32_e64 s[12:13], s84, v180
	s_nop 1
	v_cndmask_b32_e64 v2, 0, v172, s[12:13]
	v_add3_u32 v2, v180, v2, s77
	v_ashrrev_i32_e32 v2, 6, v2
	v_and_or_b32 v11, v2, -4, v13
	v_cndmask_b32_e64 v2, 0, 64, s[12:13]
	v_or3_b32 v4, v2, s72, v8
	v_cmp_gt_i32_e64 s[14:15], 32, v11
	v_cmp_lt_i32_e64 s[16:17], 31, v11
	v_ashrrev_i32_e32 v5, 31, v4
	v_lshlrev_b32_e32 v2, 2, v11
	s_and_saveexec_b64 s[18:19], s[16:17]
	s_xor_b64 s[16:17], exec, s[18:19]
	v_lshlrev_b64 v[4:5], 7, v[4:5]
	v_lshl_add_u64 v[4:5], s[62:63], 0, v[4:5]
	v_mov_b32_e32 v3, v0
	v_lshl_add_u64 v[2:3], v[2:3], 2, v[4:5]
	v_lshl_add_u64 v[6:7], v[2:3], 0, s[50:51]
	s_andn2_saveexec_b64 s[16:17], s[16:17]
	v_lshlrev_b64 v[4:5], 9, v[4:5]
	v_ashrrev_i32_e32 v3, 31, v2
	v_lshl_add_u64 v[4:5], s[60:61], 0, v[4:5]
	v_lshl_add_u64 v[6:7], v[2:3], 2, v[4:5]
	s_or_b64 exec, exec, s[16:17]
	global_load_dwordx4 v[124:127], v[6:7], off
	v_cmp_lt_i32_e64 s[16:17], s80, v180
	s_nop 1
	v_cndmask_b32_e64 v2, 0, v172, s[16:17]
	v_add3_u32 v2, v180, v2, s88
	v_ashrrev_i32_e32 v2, 6, v2
	v_and_or_b32 v12, v2, -4, v13
	v_cndmask_b32_e64 v2, 0, 64, s[16:17]
	v_or3_b32 v4, v2, s72, v8
	v_cmp_gt_i32_e64 s[18:19], 32, v12
	v_cmp_lt_i32_e64 s[20:21], 31, v12
	v_ashrrev_i32_e32 v5, 31, v4
	v_lshlrev_b32_e32 v2, 2, v12
	s_and_saveexec_b64 s[22:23], s[20:21]
	s_xor_b64 s[20:21], exec, s[22:23]
	v_lshlrev_b64 v[4:5], 7, v[4:5]
	v_lshl_add_u64 v[4:5], s[62:63], 0, v[4:5]
	v_mov_b32_e32 v3, v0
	v_lshl_add_u64 v[2:3], v[2:3], 2, v[4:5]
	v_lshl_add_u64 v[6:7], v[2:3], 0, s[50:51]
	s_andn2_saveexec_b64 s[20:21], s[20:21]
	v_lshlrev_b64 v[4:5], 9, v[4:5]
	v_ashrrev_i32_e32 v3, 31, v2
	v_lshl_add_u64 v[4:5], s[60:61], 0, v[4:5]
	v_lshl_add_u64 v[6:7], v[2:3], 2, v[4:5]
	s_or_b64 exec, exec, s[20:21]
	global_load_dwordx4 v[128:131], v[6:7], off
	v_add_u32_e32 v2, 0xa00, v180
	v_cmp_lt_i32_e64 s[20:21], -1, v180
	s_nop 1
	v_cndmask_b32_e64 v2, v2, v180, s[20:21]
	v_ashrrev_i32_e32 v2, 6, v2
	v_and_or_b32 v14, v2, -4, v13
	v_cndmask_b32_e64 v2, 0, 64, s[20:21]
	v_or3_b32 v4, v2, s72, v8
	v_cmp_gt_i32_e64 s[22:23], 32, v14
	v_cmp_lt_i32_e64 s[24:25], 31, v14
	v_ashrrev_i32_e32 v5, 31, v4
	v_lshlrev_b32_e32 v2, 2, v14
	s_and_saveexec_b64 s[26:27], s[24:25]
	s_xor_b64 s[24:25], exec, s[26:27]
	v_lshlrev_b64 v[4:5], 7, v[4:5]
	v_lshl_add_u64 v[4:5], s[62:63], 0, v[4:5]
	v_mov_b32_e32 v3, v0
	v_lshl_add_u64 v[2:3], v[2:3], 2, v[4:5]
	v_lshl_add_u64 v[6:7], v[2:3], 0, s[50:51]
	s_andn2_saveexec_b64 s[24:25], s[24:25]
	v_lshlrev_b64 v[4:5], 9, v[4:5]
	v_ashrrev_i32_e32 v3, 31, v2
	v_lshl_add_u64 v[4:5], s[60:61], 0, v[4:5]
	v_lshl_add_u64 v[6:7], v[2:3], 2, v[4:5]
	s_or_b64 exec, exec, s[24:25]
	global_load_dwordx4 v[132:135], v[6:7], off
	v_cmp_lt_i32_e64 s[24:25], s82, v180
	s_nop 1
	v_cndmask_b32_e64 v2, 0, v172, s[24:25]
	v_add3_u32 v2, v180, v2, s89
	v_ashrrev_i32_e32 v2, 6, v2
	v_and_or_b32 v15, v2, -4, v13
	v_cndmask_b32_e64 v2, 0, 64, s[24:25]
	v_or3_b32 v4, v2, s72, v8
	v_cmp_gt_i32_e64 s[26:27], 32, v15
	v_cmp_lt_i32_e64 s[28:29], 31, v15
	v_ashrrev_i32_e32 v5, 31, v4
	v_lshlrev_b32_e32 v2, 2, v15
	s_and_saveexec_b64 s[30:31], s[28:29]
	s_xor_b64 s[28:29], exec, s[30:31]
	v_lshlrev_b64 v[4:5], 7, v[4:5]
	v_lshl_add_u64 v[4:5], s[62:63], 0, v[4:5]
	v_mov_b32_e32 v3, v0
	v_lshl_add_u64 v[2:3], v[2:3], 2, v[4:5]
	v_lshl_add_u64 v[6:7], v[2:3], 0, s[50:51]
	s_andn2_saveexec_b64 s[28:29], s[28:29]
	v_lshlrev_b64 v[4:5], 9, v[4:5]
	v_ashrrev_i32_e32 v3, 31, v2
	v_lshl_add_u64 v[4:5], s[60:61], 0, v[4:5]
	v_lshl_add_u64 v[6:7], v[2:3], 2, v[4:5]
	s_or_b64 exec, exec, s[28:29]
	global_load_dwordx4 v[136:139], v[6:7], off
	v_cmp_lt_i32_e64 s[28:29], s83, v180
	s_nop 1
	v_cndmask_b32_e64 v2, 0, v172, s[28:29]
	v_add3_u32 v2, v180, v2, s90
	v_ashrrev_i32_e32 v2, 6, v2
	v_and_or_b32 v16, v2, -4, v13
	v_cndmask_b32_e64 v2, 0, 64, s[28:29]
	v_or3_b32 v4, v2, s72, v8
	v_cmp_gt_i32_e64 s[30:31], 32, v16
	v_cmp_lt_i32_e64 s[34:35], 31, v16
	v_ashrrev_i32_e32 v5, 31, v4
	v_lshlrev_b32_e32 v2, 2, v16
	s_and_saveexec_b64 s[36:37], s[34:35]
	s_xor_b64 s[34:35], exec, s[36:37]
	v_lshlrev_b64 v[4:5], 7, v[4:5]
	v_lshl_add_u64 v[4:5], s[62:63], 0, v[4:5]
	v_mov_b32_e32 v3, v0
	v_lshl_add_u64 v[2:3], v[2:3], 2, v[4:5]
	v_lshl_add_u64 v[6:7], v[2:3], 0, s[50:51]
	s_andn2_saveexec_b64 s[34:35], s[34:35]
	v_lshlrev_b64 v[4:5], 9, v[4:5]
	v_ashrrev_i32_e32 v3, 31, v2
	v_lshl_add_u64 v[4:5], s[60:61], 0, v[4:5]
	v_lshl_add_u64 v[6:7], v[2:3], 2, v[4:5]
	s_or_b64 exec, exec, s[34:35]
	global_load_dwordx4 v[140:143], v[6:7], off
	v_cmp_lt_i32_e64 s[34:35], s46, v180
	s_nop 1
	v_cndmask_b32_e64 v2, 0, v172, s[34:35]
	v_add3_u32 v2, v180, v2, s81
	v_ashrrev_i32_e32 v2, 6, v2
	v_and_or_b32 v17, v2, -4, v13
	v_cndmask_b32_e64 v2, 0, 64, s[34:35]
	v_or3_b32 v4, v2, s72, v8
	v_cmp_gt_i32_e64 s[36:37], 32, v17
	v_cmp_lt_i32_e64 s[38:39], 31, v17
	v_ashrrev_i32_e32 v5, 31, v4
	v_lshlrev_b32_e32 v2, 2, v17
	s_and_saveexec_b64 s[40:41], s[38:39]
	s_xor_b64 s[38:39], exec, s[40:41]
	v_lshlrev_b64 v[4:5], 7, v[4:5]
	v_lshl_add_u64 v[4:5], s[62:63], 0, v[4:5]
	v_mov_b32_e32 v3, v0
	v_lshl_add_u64 v[2:3], v[2:3], 2, v[4:5]
	v_lshl_add_u64 v[6:7], v[2:3], 0, s[50:51]
	s_andn2_saveexec_b64 s[38:39], s[38:39]
	v_lshlrev_b64 v[4:5], 9, v[4:5]
	v_ashrrev_i32_e32 v3, 31, v2
	v_lshl_add_u64 v[4:5], s[60:61], 0, v[4:5]
	v_lshl_add_u64 v[6:7], v[2:3], 2, v[4:5]
	s_or_b64 exec, exec, s[38:39]
	global_load_dwordx4 v[144:147], v[6:7], off
	v_cmp_lt_i32_e64 s[38:39], s71, v180
	s_nop 1
	v_cndmask_b32_e64 v2, 0, v172, s[38:39]
	v_add3_u32 v2, v180, v2, s95
	v_ashrrev_i32_e32 v2, 6, v2
	v_and_or_b32 v13, v2, -4, v13
	v_cndmask_b32_e64 v2, 0, 64, s[38:39]
	v_or3_b32 v4, v2, s72, v8
	v_cmp_gt_i32_e64 s[40:41], 32, v13
	v_cmp_lt_i32_e64 s[42:43], 31, v13
	v_ashrrev_i32_e32 v5, 31, v4
	v_lshlrev_b32_e32 v2, 2, v13
	s_and_saveexec_b64 s[52:53], s[42:43]
	s_xor_b64 s[42:43], exec, s[52:53]
	v_lshlrev_b64 v[4:5], 7, v[4:5]
	v_lshl_add_u64 v[4:5], s[62:63], 0, v[4:5]
	v_mov_b32_e32 v3, v0
	v_lshl_add_u64 v[2:3], v[2:3], 2, v[4:5]
	v_lshl_add_u64 v[6:7], v[2:3], 0, s[50:51]
	s_andn2_saveexec_b64 s[42:43], s[42:43]
	v_lshlrev_b64 v[4:5], 9, v[4:5]
	v_ashrrev_i32_e32 v3, 31, v2
	v_lshl_add_u64 v[4:5], s[60:61], 0, v[4:5]
	v_lshl_add_u64 v[6:7], v[2:3], 2, v[4:5]
	s_or_b64 exec, exec, s[42:43]
	global_load_dwordx4 v[148:151], v[6:7], off
	v_cndmask_b32_e32 v4, 0, v173, vcc
	v_mul_u32_u24_e32 v5, 0x150, v8
	v_add_u32_e32 v4, 0, v4
	v_lshlrev_b32_e32 v6, 3, v1
	s_waitcnt vmcnt(0) lgkmcnt(0)
	v_cvt_pk_bf16_f32 v2, v112, v113
	v_cvt_pk_bf16_f32 v3, v114, v115
	v_add3_u32 v4, v4, v6, v5
	ds_write_b64 v4, v[2:3] offset:43008
	v_lshlrev_b32_e32 v4, 1, v8
	s_and_saveexec_b64 s[42:43], s[2:3]
	s_cbranch_execz .LBB0_730
	v_cndmask_b32_e32 v6, 0, v174, vcc
	s_add_i32 s2, 0, 0x15000
	v_add_u32_e32 v6, s2, v6
	v_mul_lo_u32 v1, v1, s47
	v_add3_u32 v1, v6, v1, v4
	ds_write_b16 v1, v2
	ds_write_b16_d16_hi v1, v2 offset:136
	ds_write_b16 v1, v3 offset:272
	ds_write_b16_d16_hi v1, v3 offset:408

; __device__ __forceinline__ void mla_sample_unit(LAS unsigned char* lds, size_t ws_q, size_t ws_olat, size_t ws_mixed, int b) {
;     ...
;         if (2 * pi + 2 < AS_NT) AS_GLOAD(pi + 1);
.LBB0_764:
	v_mov_b32_e32 v2, v0
	v_mov_b32_e32 v3, v0
	v_cmp_gt_u32_e32 vcc, s85, v1
	v_mov_b32_e32 v1, v0
	s_waitcnt vmcnt(0)
	v_mov_b64_e32 v[114:115], v[2:3]
	v_mov_b64_e32 v[112:113], v[0:1]
	s_and_saveexec_b64 s[2:3], vcc
	s_cbranch_execz .LBB0_766
	global_load_dwordx4 v[112:115], v[4:5], off

; __device__ __forceinline__ void mla_sample_unit(LAS unsigned char* lds, size_t ws_q, size_t ws_olat, size_t ws_mixed, int b) {
;     ...
;         if (2 * pi + 2 < AS_NT) AS_GLOAD(pi + 1);
.LBB0_778:
	v_mov_b32_e32 v2, v0
	v_mov_b32_e32 v3, v0
	v_cmp_gt_u32_e32 vcc, s85, v1
	v_mov_b32_e32 v1, v0
	v_mov_b64_e32 v[118:119], v[2:3]
	v_mov_b64_e32 v[116:117], v[0:1]
	s_and_saveexec_b64 s[4:5], vcc
	s_cbranch_execz .LBB0_780
	global_load_dwordx4 v[116:119], v[4:5], off

; __device__ __forceinline__ void mla_sample_unit(LAS unsigned char* lds, size_t ws_q, size_t ws_olat, size_t ws_mixed, int b) {
;     ...
;         if (2 * pi + 2 < AS_NT) AS_GLOAD(pi + 1);
.LBB0_792:
	v_mov_b32_e32 v2, v0
	v_mov_b32_e32 v3, v0
	v_cmp_gt_u32_e32 vcc, s85, v1
	v_mov_b32_e32 v1, v0
	v_mov_b64_e32 v[122:123], v[2:3]
	v_mov_b64_e32 v[120:121], v[0:1]
	s_and_saveexec_b64 s[4:5], vcc
	s_cbranch_execz .LBB0_794
	global_load_dwordx4 v[120:123], v[4:5], off

; __device__ __forceinline__ void mla_sample_unit(LAS unsigned char* lds, size_t ws_q, size_t ws_olat, size_t ws_mixed, int b) {
;     ...
;         if (2 * pi + 2 < AS_NT) AS_GLOAD(pi + 1);
.LBB0_806:
	v_mov_b32_e32 v2, v0
	v_mov_b32_e32 v3, v0
	v_cmp_gt_u32_e32 vcc, s85, v1
	v_mov_b32_e32 v1, v0
	v_mov_b64_e32 v[126:127], v[2:3]
	v_mov_b64_e32 v[124:125], v[0:1]
	s_and_saveexec_b64 s[4:5], vcc
	s_cbranch_execz .LBB0_808
	global_load_dwordx4 v[124:127], v[4:5], off

; __device__ __forceinline__ void mla_sample_unit(LAS unsigned char* lds, size_t ws_q, size_t ws_olat, size_t ws_mixed, int b) {
;     ...
;         if (2 * pi + 2 < AS_NT) AS_GLOAD(pi + 1);
.LBB0_820:
	v_mov_b32_e32 v2, v0
	v_mov_b32_e32 v3, v0
	v_cmp_gt_u32_e32 vcc, s85, v1
	v_mov_b32_e32 v1, v0
	v_mov_b64_e32 v[130:131], v[2:3]
	v_mov_b64_e32 v[128:129], v[0:1]
	s_and_saveexec_b64 s[4:5], vcc
	s_cbranch_execz .LBB0_822
	global_load_dwordx4 v[128:131], v[4:5], off

; __device__ __forceinline__ void mla_sample_unit(LAS unsigned char* lds, size_t ws_q, size_t ws_olat, size_t ws_mixed, int b) {
;     ...
;         if (2 * pi + 2 < AS_NT) AS_GLOAD(pi + 1);
.LBB0_834:
	v_mov_b32_e32 v2, v0
	v_mov_b32_e32 v3, v0
	v_cmp_gt_u32_e32 vcc, s85, v1
	v_mov_b32_e32 v1, v0
	v_mov_b64_e32 v[134:135], v[2:3]
	v_mov_b64_e32 v[132:133], v[0:1]
	s_and_saveexec_b64 s[4:5], vcc
	s_cbranch_execz .LBB0_836
	global_load_dwordx4 v[132:135], v[4:5], off

; __device__ __forceinline__ void mla_sample_unit(LAS unsigned char* lds, size_t ws_q, size_t ws_olat, size_t ws_mixed, int b) {
;     ...
;         if (2 * pi + 2 < AS_NT) AS_GLOAD(pi + 1);
.LBB0_848:
	v_mov_b32_e32 v2, v0
	v_mov_b32_e32 v3, v0
	v_cmp_gt_u32_e32 vcc, s85, v1
	v_mov_b32_e32 v1, v0
	v_mov_b64_e32 v[138:139], v[2:3]
	v_mov_b64_e32 v[136:137], v[0:1]
	s_and_saveexec_b64 s[4:5], vcc
	s_cbranch_execz .LBB0_850
	global_load_dwordx4 v[136:139], v[4:5], off

; __device__ __forceinline__ void mla_sample_unit(LAS unsigned char* lds, size_t ws_q, size_t ws_olat, size_t ws_mixed, int b) {
;     ...
;         if (2 * pi + 2 < AS_NT) AS_GLOAD(pi + 1);
.LBB0_862:
	v_mov_b32_e32 v2, v0
	v_mov_b32_e32 v3, v0
	v_cmp_gt_u32_e32 vcc, s85, v1
	v_mov_b32_e32 v1, v0
	v_mov_b64_e32 v[142:143], v[2:3]
	v_mov_b64_e32 v[140:141], v[0:1]
	s_and_saveexec_b64 s[4:5], vcc
	s_cbranch_execz .LBB0_864
	global_load_dwordx4 v[140:143], v[4:5], off

; __device__ __forceinline__ void mla_sample_unit(LAS unsigned char* lds, size_t ws_q, size_t ws_olat, size_t ws_mixed, int b) {
;     ...
;         if (2 * pi + 2 < AS_NT) AS_GLOAD(pi + 1);
.LBB0_876:
	v_mov_b32_e32 v2, v0
	v_mov_b32_e32 v3, v0
	v_cmp_gt_u32_e32 vcc, s85, v1
	v_mov_b32_e32 v1, v0
	v_mov_b64_e32 v[146:147], v[2:3]
	v_mov_b64_e32 v[144:145], v[0:1]
	s_and_saveexec_b64 s[4:5], vcc
	s_cbranch_execz .LBB0_878
	global_load_dwordx4 v[144:147], v[4:5], off

; __device__ __forceinline__ void mla_sample_unit(LAS unsigned char* lds, size_t ws_q, size_t ws_olat, size_t ws_mixed, int b) {
;     ...
;         if (2 * pi + 2 < AS_NT) AS_GLOAD(pi + 1);
.LBB0_890:
	v_mov_b32_e32 v2, v0
	v_mov_b32_e32 v3, v0
	v_cmp_gt_u32_e32 vcc, s85, v1
	v_mov_b32_e32 v1, v0
	v_mov_b64_e32 v[150:151], v[2:3]
	v_mov_b64_e32 v[148:149], v[0:1]
	s_and_saveexec_b64 s[2:3], vcc
	s_cbranch_execz .LBB0_892
	global_load_dwordx4 v[148:151], v[4:5], off

; __device__ __forceinline__ unsigned pk2(float lo, float hi) { const f32x2 v = {lo, hi}; return __builtin_bit_cast(unsigned, __builtin_convertvector(v, bf16x2_t)); }
; __device__ __forceinline__ float half_sum(float v) { auto rr = __builtin_amdgcn_permlane32_swap(__float_as_uint(v), __float_as_uint(v), false, false); return __uint_as_float(rr[0]) + __uint_as_float(rr[1]); }
; #define WSB(off) ((bf16*)((unsigned char*)tab_get(lds, 31) + (off)))
; __device__ __forceinline__ void mla_sample_unit(LAS unsigned char* lds, size_t ws_q, size_t ws_olat, size_t ws_mixed, int b) {
;     ...
;     if (wid < 4) { const float lt = half_sum(lrun), inv = 1.f / lt; bf16* OLAT = WSB(ws_olat);
;         bf16* orow = OLAT + (size_t)(b * 128 + wid * 32 + r32) * 128 + 4 * hi;
; #pragma unroll
;         for (int db = 0; db < NDB; ++db)
; #pragma unroll
;             for (int rg = 0; rg < 4; ++rg) { u32x2 w; w.x = pk2(o[db][4 * rg] * inv, o[db][4 * rg + 1] * inv); w.y = pk2(o[db][4 * rg + 2] * inv, o[db][4 * rg + 3] * inv);
;                 *(u32x2*)(orow + 32 * db + 8 * rg) = w; } }
.LBB0_928:
	s_andn2_b64 vcc, exec, s[2:3]
	s_cbranch_vccnz .LBB0_930
	v_mov_b32_e32 v1, v7
	s_nop 1
	v_permlane32_swap_b32_e32 v7, v1
	v_add_f32_e32 v1, v7, v1
	v_div_scale_f32 v4, s[2:3], v1, v1, 1.0
	v_rcp_f32_e32 v5, v4
	v_div_scale_f32 v6, vcc, 1.0, v1, 1.0
	s_lshl_b32 s4, s57, 7
	v_fma_f32 v2, -v4, v5, 1.0
	v_fmac_f32_e32 v5, v2, v5
	v_mul_f32_e32 v7, v6, v5
	v_fma_f32 v2, -v4, v7, v6
	v_fmac_f32_e32 v7, v2, v5
	v_mov_b32_e32 v2, s45
	ds_read_b64 v[2:3], v2
	s_lshl_b32 s5, s59, 5
	s_add_i32 s5, s5, s4
	v_fma_f32 v4, -v4, v7, v6
	v_div_fmas_f32 v4, v4, v5, v7
	s_waitcnt lgkmcnt(0)
	v_readfirstlane_b32 s2, v2
	v_or_b32_e32 v2, s5, v159
	v_readfirstlane_b32 s3, v3
	v_ashrrev_i32_e32 v3, 31, v2
	v_lshlrev_b64 v[2:3], 8, v[2:3]
	v_lshl_add_u64 v[2:3], s[2:3], 0, v[2:3]
	v_mov_b32_e32 v159, v0
	v_lshl_add_u64 v[2:3], v[2:3], 0, v[158:159]
	s_mov_b64 s[2:3], 0x12080000
	v_div_fixup_f32 v4, v4, v1, 1.0
	v_lshl_add_u64 v[6:7], v[2:3], 0, s[2:3]
	s_mov_b32 s2, 0x12080000
	v_pk_mul_f32 v[8:9], v[64:65], v[4:5] op_sel_hi:[1,0]
	v_pk_mul_f32 v[10:11], v[66:67], v[4:5] op_sel_hi:[1,0]
	v_add_co_u32_e32 v2, vcc, s2, v2
	v_cvt_pk_bf16_f32 v8, v8, v9
	v_cvt_pk_bf16_f32 v9, v10, v11
	v_addc_co_u32_e32 v3, vcc, 0, v3, vcc
	global_store_dwordx2 v[2:3], v[8:9], off
	v_pk_mul_f32 v[2:3], v[68:69], v[4:5] op_sel_hi:[1,0]
	v_pk_mul_f32 v[8:9], v[70:71], v[4:5] op_sel_hi:[1,0]
	v_cvt_pk_bf16_f32 v2, v2, v3
	v_cvt_pk_bf16_f32 v3, v8, v9
	global_store_dwordx2 v[6:7], v[2:3], off offset:16
	v_pk_mul_f32 v[2:3], v[72:73], v[4:5] op_sel_hi:[1,0]
	v_pk_mul_f32 v[8:9], v[74:75], v[4:5] op_sel_hi:[1,0]
	v_cvt_pk_bf16_f32 v2, v2, v3
	v_cvt_pk_bf16_f32 v3, v8, v9
	global_store_dwordx2 v[6:7], v[2:3], off offset:32
	v_pk_mul_f32 v[2:3], v[76:77], v[4:5] op_sel_hi:[1,0]
	v_pk_mul_f32 v[8:9], v[78:79], v[4:5] op_sel_hi:[1,0]
	v_cvt_pk_bf16_f32 v2, v2, v3
	v_cvt_pk_bf16_f32 v3, v8, v9
	global_store_dwordx2 v[6:7], v[2:3], off offset:48
	v_pk_mul_f32 v[2:3], v[48:49], v[4:5] op_sel_hi:[1,0]
	v_pk_mul_f32 v[8:9], v[50:51], v[4:5] op_sel_hi:[1,0]
	v_cvt_pk_bf16_f32 v2, v2, v3
	v_cvt_pk_bf16_f32 v3, v8, v9
	global_store_dwordx2 v[6:7], v[2:3], off offset:64
	v_pk_mul_f32 v[2:3], v[52:53], v[4:5] op_sel_hi:[1,0]
	v_pk_mul_f32 v[8:9], v[54:55], v[4:5] op_sel_hi:[1,0]
	v_cvt_pk_bf16_f32 v2, v2, v3
	v_cvt_pk_bf16_f32 v3, v8, v9
	global_store_dwordx2 v[6:7], v[2:3], off offset:80
	v_pk_mul_f32 v[2:3], v[56:57], v[4:5] op_sel_hi:[1,0]
	v_pk_mul_f32 v[8:9], v[58:59], v[4:5] op_sel_hi:[1,0]
	v_cvt_pk_bf16_f32 v2, v2, v3
	v_cvt_pk_bf16_f32 v3, v8, v9
	global_store_dwordx2 v[6:7], v[2:3], off offset:96
	v_pk_mul_f32 v[2:3], v[60:61], v[4:5] op_sel_hi:[1,0]
	v_pk_mul_f32 v[8:9], v[62:63], v[4:5] op_sel_hi:[1,0]
	v_cvt_pk_bf16_f32 v2, v2, v3
	v_cvt_pk_bf16_f32 v3, v8, v9
	global_store_dwordx2 v[6:7], v[2:3], off offset:112
	v_pk_mul_f32 v[2:3], v[32:33], v[4:5] op_sel_hi:[1,0]
	v_pk_mul_f32 v[8:9], v[34:35], v[4:5] op_sel_hi:[1,0]
	v_cvt_pk_bf16_f32 v2, v2, v3
	v_cvt_pk_bf16_f32 v3, v8, v9
	global_store_dwordx2 v[6:7], v[2:3], off offset:128
	v_pk_mul_f32 v[2:3], v[36:37], v[4:5] op_sel_hi:[1,0]
	v_pk_mul_f32 v[8:9], v[38:39], v[4:5] op_sel_hi:[1,0]
	v_cvt_pk_bf16_f32 v2, v2, v3
	v_cvt_pk_bf16_f32 v3, v8, v9
	global_store_dwordx2 v[6:7], v[2:3], off offset:144
	v_pk_mul_f32 v[2:3], v[40:41], v[4:5] op_sel_hi:[1,0]
	v_pk_mul_f32 v[8:9], v[42:43], v[4:5] op_sel_hi:[1,0]
	v_cvt_pk_bf16_f32 v2, v2, v3
	v_cvt_pk_bf16_f32 v3, v8, v9
	global_store_dwordx2 v[6:7], v[2:3], off offset:160
	v_pk_mul_f32 v[2:3], v[44:45], v[4:5] op_sel_hi:[1,0]
	v_pk_mul_f32 v[8:9], v[46:47], v[4:5] op_sel_hi:[1,0]
	v_cvt_pk_bf16_f32 v2, v2, v3
	v_cvt_pk_bf16_f32 v3, v8, v9
	global_store_dwordx2 v[6:7], v[2:3], off offset:176
	v_pk_mul_f32 v[2:3], v[16:17], v[4:5] op_sel_hi:[1,0]
	v_pk_mul_f32 v[8:9], v[18:19], v[4:5] op_sel_hi:[1,0]
	v_cvt_pk_bf16_f32 v2, v2, v3
	v_cvt_pk_bf16_f32 v3, v8, v9
	global_store_dwordx2 v[6:7], v[2:3], off offset:192
	v_pk_mul_f32 v[2:3], v[20:21], v[4:5] op_sel_hi:[1,0]
	v_pk_mul_f32 v[8:9], v[22:23], v[4:5] op_sel_hi:[1,0]
	v_cvt_pk_bf16_f32 v2, v2, v3
	v_cvt_pk_bf16_f32 v3, v8, v9
	global_store_dwordx2 v[6:7], v[2:3], off offset:208
	v_pk_mul_f32 v[2:3], v[24:25], v[4:5] op_sel_hi:[1,0]
	v_pk_mul_f32 v[8:9], v[26:27], v[4:5] op_sel_hi:[1,0]
	v_cvt_pk_bf16_f32 v2, v2, v3
	v_cvt_pk_bf16_f32 v3, v8, v9
	global_store_dwordx2 v[6:7], v[2:3], off offset:224
	v_pk_mul_f32 v[2:3], v[28:29], v[4:5] op_sel_hi:[1,0]
	v_pk_mul_f32 v[4:5], v[30:31], v[4:5] op_sel_hi:[1,0]
	v_cvt_pk_bf16_f32 v2, v2, v3
	v_cvt_pk_bf16_f32 v3, v4, v5
	global_store_dwordx2 v[6:7], v[2:3], off offset:240
; #define LAS __attribute__((address_space(3)))
; __device__ __forceinline__ float bflo(unsigned w) { return __uint_as_float(w << 16); }
; __device__ __forceinline__ float bfhi(unsigned w) { return __uint_as_float(w & 0xffff0000u); }
; #define INP(i) ((const float*)tab_get(lds, (i)))
; #define WSB(off) ((bf16*)((unsigned char*)tab_get(lds, 31) + (off)))
; __device__ __forceinline__ void mla_sample_unit(LAS unsigned char* lds, size_t ws_q, size_t ws_olat, size_t ws_mixed, int b) {
;     ...
;     __threadfence(); __syncthreads();
;     { LAS float* OLT = (LAS float*)(lds + KV0);
;       const bf16* OLAT = WSB(ws_olat); const float* w_uv = INP(15); bf16* MIXED = WSB(ws_mixed);
; #pragma unroll
;       for (int i = 0; i < 4; ++i) { const int idx = tid + 512 * i, row = idx >> 4, c8 = idx & 15; const u32x4 v = *(const u32x4*)(OLAT + (size_t)(b * 128 + row) * 128 + 8 * c8);
;           LAS float* d = OLT + ((row >> 4) * 128 + 8 * c8) * 16 + (row & 15);
; #pragma unroll
;           for (int e = 0; e < 4; ++e) { d[(2 * e) * 16] = bflo(v[e]); d[(2 * e + 1) * 16] = bfhi(v[e]); } }
;       __syncthreads();
;       const int d = tid & 63, h = tid >> 6; float acc[16];
.LBB0_930:
	v_mov_b32_e32 v1, s45
	buffer_wbl2 sc1
	s_waitcnt vmcnt(0) lgkmcnt(0)
	buffer_inv sc1
	s_barrier
	ds_read_b64 v[2:3], v1
	v_mov_b32_e32 v5, v0
	v_lshrrev_b32_e32 v11, 1, v176
	v_ashrrev_i32_e32 v12, 4, v178
	v_add_u32_e32 v10, s4, v12
	s_waitcnt lgkmcnt(0)
	v_readfirstlane_b32 s2, v2
	v_mov_b32_e32 v2, s86
	v_readfirstlane_b32 s3, v3
	ds_read_b64 v[16:17], v2
	ds_read_b64 v[2:3], v1
	v_lshlrev_b32_e32 v1, 3, v179
	v_and_b32_e32 v21, 0x78, v1
	v_lshlrev_b32_e32 v4, 1, v21
	v_lshl_add_u64 v[4:5], s[2:3], 0, v[4:5]
	s_mov_b64 s[2:3], 0x12080000
	v_ashrrev_i32_e32 v1, 4, v176
	v_lshl_add_u64 v[8:9], v[4:5], 0, s[2:3]
	v_add_u32_e32 v4, s4, v1
	v_ashrrev_i32_e32 v5, 31, v4
	v_lshlrev_b64 v[4:5], 8, v[4:5]
	v_lshl_add_u64 v[4:5], v[8:9], 0, v[4:5]
	global_load_dwordx4 v[4:7], v[4:5], off
	v_lshlrev_b32_e32 v1, 2, v1
	v_and_or_b32 v13, v11, s56, v21
	v_and_b32_e32 v1, 60, v1
	v_lshlrev_b32_e32 v13, 6, v13
	v_ashrrev_i32_e32 v11, 31, v10
	v_add3_u32 v1, 0, v13, v1
	v_lshlrev_b64 v[10:11], 8, v[10:11]
	v_add_u32_e32 v1, 0xa800, v1
	v_lshl_add_u64 v[10:11], v[8:9], 0, v[10:11]
	v_lshrrev_b32_e32 v28, 1, v155
	s_waitcnt lgkmcnt(0)
	v_readfirstlane_b32 s5, v17
	s_mov_b64 s[2:3], 0
	s_waitcnt vmcnt(0)
	v_lshlrev_b32_e32 v13, 16, v4
	v_and_b32_e32 v4, 0xffff0000, v4
	v_lshlrev_b32_e32 v14, 16, v5
	v_and_b32_e32 v5, 0xffff0000, v5
	v_lshlrev_b32_e32 v15, 16, v6
	v_and_b32_e32 v6, 0xffff0000, v6
	v_lshlrev_b32_e32 v18, 16, v7
	v_and_b32_e32 v7, 0xffff0000, v7
	ds_write2_b32 v1, v13, v4 offset1:16
	ds_write2_b32 v1, v14, v5 offset0:32 offset1:48
	ds_write2_b32 v1, v15, v6 offset0:64 offset1:80
	ds_write2_b32 v1, v18, v7 offset0:96 offset1:112
	global_load_dwordx4 v[4:7], v[10:11], off
	v_lshrrev_b32_e32 v1, 1, v178
	v_ashrrev_i32_e32 v13, 4, v177
	v_lshlrev_b32_e32 v11, 2, v12
	v_and_or_b32 v1, v1, s56, v21
	v_add_u32_e32 v10, s4, v13
	v_and_b32_e32 v12, 60, v11
	v_lshlrev_b32_e32 v1, 6, v1
	v_ashrrev_i32_e32 v11, 31, v10
	v_add3_u32 v1, 0, v1, v12
	v_lshlrev_b64 v[10:11], 8, v[10:11]
	v_add_u32_e32 v1, 0xa800, v1
	v_lshl_add_u64 v[10:11], v[8:9], 0, v[10:11]
	s_waitcnt vmcnt(0) lgkmcnt(0)
	v_lshlrev_b32_e32 v12, 16, v4
	v_and_b32_e32 v4, 0xffff0000, v4
	v_lshlrev_b32_e32 v14, 16, v5
	v_and_b32_e32 v5, 0xffff0000, v5
	v_lshlrev_b32_e32 v15, 16, v6
	v_and_b32_e32 v6, 0xffff0000, v6
	v_lshlrev_b32_e32 v18, 16, v7
	v_and_b32_e32 v7, 0xffff0000, v7
	ds_write2_b32 v1, v12, v4 offset1:16
	ds_write2_b32 v1, v14, v5 offset0:32 offset1:48
	ds_write2_b32 v1, v15, v6 offset0:64 offset1:80
	ds_write2_b32 v1, v18, v7 offset0:96 offset1:112
	global_load_dwordx4 v[4:7], v[10:11], off
	v_lshrrev_b32_e32 v1, 1, v177
	v_ashrrev_i32_e32 v12, 4, v155
	v_lshlrev_b32_e32 v11, 2, v13
	v_add_u32_e32 v10, s4, v12
	v_and_or_b32 v1, v1, s56, v21
	v_and_b32_e32 v13, 60, v11
	v_ashrrev_i32_e32 v11, 31, v10
	v_lshlrev_b32_e32 v1, 6, v1
	v_lshlrev_b64 v[10:11], 8, v[10:11]
	v_add3_u32 v1, 0, v1, v13
	v_add_u32_e32 v1, 0xa800, v1
	v_lshl_add_u64 v[8:9], v[8:9], 0, v[10:11]
	v_ashrrev_i32_e32 v155, 31, v154
	v_lshlrev_b32_e32 v29, 2, v12
	v_and_or_b32 v21, v28, s56, v21
	s_add_i32 s4, 0, 0xa800
	v_lshlrev_b64 v[26:27], 8, v[154:155]
	v_and_b32_e32 v28, 60, v29
	v_lshlrev_b32_e32 v21, 6, v21
	v_lshl_or_b32 v26, v156, 2, v26
	v_add3_u32 v21, 0, v21, v28
	v_add_u32_e32 v21, 0xa800, v21
	s_waitcnt vmcnt(0) lgkmcnt(0)
	v_lshlrev_b32_e32 v10, 16, v4
	v_and_b32_e32 v4, 0xffff0000, v4
	v_lshlrev_b32_e32 v11, 16, v5
	v_and_b32_e32 v5, 0xffff0000, v5
	v_lshlrev_b32_e32 v13, 16, v6
	v_and_b32_e32 v6, 0xffff0000, v6
	v_lshlrev_b32_e32 v14, 16, v7
	v_and_b32_e32 v7, 0xffff0000, v7
	ds_write2_b32 v1, v10, v4 offset1:16
	ds_write2_b32 v1, v11, v5 offset0:32 offset1:48
	ds_write2_b32 v1, v13, v6 offset0:64 offset1:80
	ds_write2_b32 v1, v14, v7 offset0:96 offset1:112
	global_load_dwordx4 v[22:25], v[8:9], off
	v_lshl_add_u32 v1, v154, 13, s4
	v_readfirstlane_b32 s4, v16
	v_mov_b32_e32 v4, 0
	v_mov_b32_e32 v5, v4
	v_lshl_add_u64 v[16:17], s[4:5], 0, v[26:27]
	v_mov_b32_e32 v6, v4
	v_mov_b32_e32 v7, v4
	v_mov_b32_e32 v8, v4
	v_mov_b32_e32 v9, v4
	v_mov_b32_e32 v10, v4
	v_mov_b32_e32 v11, v4
	v_mov_b32_e32 v12, v4
	v_mov_b32_e32 v13, v4
	v_mov_b32_e32 v14, v4
	v_mov_b32_e32 v15, v4
	v_mov_b32_e32 v18, v4
	v_mov_b32_e32 v19, v4
	v_mov_b32_e32 v20, v4
	s_waitcnt vmcnt(0) lgkmcnt(0)
	v_lshlrev_b32_e32 v26, 16, v22
	v_and_b32_e32 v22, 0xffff0000, v22
	v_lshlrev_b32_e32 v27, 16, v23
	v_and_b32_e32 v23, 0xffff0000, v23
	v_lshlrev_b32_e32 v28, 16, v24
	v_and_b32_e32 v24, 0xffff0000, v24
	v_lshlrev_b32_e32 v29, 16, v25
	v_and_b32_e32 v25, 0xffff0000, v25
	ds_write2_b32 v21, v26, v22 offset1:16
	ds_write2_b32 v21, v27, v23 offset0:32 offset1:48
	ds_write2_b32 v21, v28, v24 offset0:64 offset1:80
	ds_write2_b32 v21, v29, v25 offset0:96 offset1:112
	v_mov_b32_e32 v21, v4
	s_waitcnt lgkmcnt(0)
	s_barrier
; #define LAS __attribute__((address_space(3)))
; __device__ __forceinline__ void mla_sample_unit(LAS unsigned char* lds, size_t ws_q, size_t ws_olat, size_t ws_mixed, int b) {
;     ...
; #pragma unroll 8
;       for (int r = 0; r < 128; ++r) { const float w = w_uv[(size_t)(r * 8 + h) * 64 + d]; const LAS float* ol = OLT + (h * 128 + r) * 16;
; #pragma unroll
;           for (int t4 = 0; t4 < 4; ++t4) { const f32x4 x = *(const LAS f32x4*)(ol + 4 * t4); acc[4 * t4] += x.x * w; acc[4 * t4 + 1] += x.y * w; acc[4 * t4 + 2] += x.z * w; acc[4 * t4 + 3] += x.w * w; } }
.LBB0_931:
	v_lshl_add_u64 v[102:103], v[16:17], 0, s[2:3]
	ds_read_b128 v[22:25], v1
	ds_read_b128 v[26:29], v1 offset:16
	ds_read_b128 v[30:33], v1 offset:32
	ds_read_b128 v[34:37], v1 offset:48
	ds_read_b128 v[38:41], v1 offset:64
	ds_read_b128 v[42:45], v1 offset:80
	ds_read_b128 v[46:49], v1 offset:96
	ds_read_b128 v[50:53], v1 offset:112
	ds_read_b128 v[54:57], v1 offset:128
	ds_read_b128 v[58:61], v1 offset:144
	ds_read_b128 v[62:65], v1 offset:160
	ds_read_b128 v[66:69], v1 offset:176
	ds_read_b128 v[70:73], v1 offset:192
	ds_read_b128 v[74:77], v1 offset:208
	ds_read_b128 v[78:81], v1 offset:224
	ds_read_b128 v[82:85], v1 offset:240
	ds_read_b128 v[86:89], v1 offset:256
	ds_read_b128 v[90:93], v1 offset:272
	ds_read_b128 v[94:97], v1 offset:288
	ds_read_b128 v[98:101], v1 offset:304
	global_load_dword v150, v[102:103], off
	global_load_dword v154, v[102:103], off offset:2048
	v_add_co_u32_e32 v104, vcc, s81, v102
	s_movk_i32 s4, 0x2000
	s_nop 0
	v_addc_co_u32_e32 v105, vcc, 0, v103, vcc
	v_add_co_u32_e32 v106, vcc, s4, v102
	s_movk_i32 s5, 0x3000
	s_nop 0
	v_addc_co_u32_e32 v107, vcc, 0, v103, vcc
	v_add_co_u32_e32 v102, vcc, s5, v102
	s_add_u32 s2, s2, 0x4000
	s_nop 0
	v_addc_co_u32_e32 v103, vcc, 0, v103, vcc
	global_load_dword v158, v[104:105], off
	global_load_dword v160, v[104:105], off offset:2048
	global_load_dword v178, v[106:107], off
	global_load_dword v180, v[106:107], off offset:2048
	global_load_dword v182, v[102:103], off
	global_load_dword v184, v[102:103], off offset:2048
	ds_read_b128 v[102:105], v1 offset:320
	ds_read_b128 v[106:109], v1 offset:336
	ds_read_b128 v[110:113], v1 offset:352
	ds_read_b128 v[114:117], v1 offset:368
	ds_read_b128 v[118:121], v1 offset:384
	ds_read_b128 v[122:125], v1 offset:400
	ds_read_b128 v[126:129], v1 offset:416
	ds_read_b128 v[130:133], v1 offset:432
	ds_read_b128 v[134:137], v1 offset:448
	ds_read_b128 v[138:141], v1 offset:464
	ds_read_b128 v[142:145], v1 offset:480
	ds_read_b128 v[146:149], v1 offset:496
	s_addc_u32 s3, s3, 0
	v_add_u32_e32 v1, 0x200, v1
	s_cmp_lg_u32 s2, 0x40000
	s_waitcnt vmcnt(0) lgkmcnt(0)
	v_pk_fma_f32 v[20:21], v[150:151], v[22:23], v[20:21] op_sel_hi:[0,1,1]
	v_pk_fma_f32 v[18:19], v[150:151], v[24:25], v[18:19] op_sel_hi:[0,1,1]
	v_pk_fma_f32 v[14:15], v[150:151], v[26:27], v[14:15] op_sel_hi:[0,1,1]
	v_pk_fma_f32 v[12:13], v[150:151], v[28:29], v[12:13] op_sel_hi:[0,1,1]
	v_pk_fma_f32 v[10:11], v[150:151], v[30:31], v[10:11] op_sel_hi:[0,1,1]
	v_pk_fma_f32 v[8:9], v[150:151], v[32:33], v[8:9] op_sel_hi:[0,1,1]
	v_pk_fma_f32 v[6:7], v[150:151], v[34:35], v[6:7] op_sel_hi:[0,1,1]
	v_pk_fma_f32 v[4:5], v[150:151], v[36:37], v[4:5] op_sel_hi:[0,1,1]
	v_pk_fma_f32 v[20:21], v[154:155], v[38:39], v[20:21] op_sel_hi:[0,1,1]
	v_pk_fma_f32 v[18:19], v[154:155], v[40:41], v[18:19] op_sel_hi:[0,1,1]
	v_pk_fma_f32 v[14:15], v[154:155], v[42:43], v[14:15] op_sel_hi:[0,1,1]
	v_pk_fma_f32 v[12:13], v[154:155], v[44:45], v[12:13] op_sel_hi:[0,1,1]
	v_pk_fma_f32 v[10:11], v[154:155], v[46:47], v[10:11] op_sel_hi:[0,1,1]
	v_pk_fma_f32 v[8:9], v[154:155], v[48:49], v[8:9] op_sel_hi:[0,1,1]
	v_pk_fma_f32 v[6:7], v[154:155], v[50:51], v[6:7] op_sel_hi:[0,1,1]
	v_pk_fma_f32 v[4:5], v[154:155], v[52:53], v[4:5] op_sel_hi:[0,1,1]
	v_pk_fma_f32 v[20:21], v[158:159], v[54:55], v[20:21] op_sel_hi:[0,1,1]
	v_pk_fma_f32 v[18:19], v[158:159], v[56:57], v[18:19] op_sel_hi:[0,1,1]
	v_pk_fma_f32 v[14:15], v[158:159], v[58:59], v[14:15] op_sel_hi:[0,1,1]
	v_pk_fma_f32 v[12:13], v[158:159], v[60:61], v[12:13] op_sel_hi:[0,1,1]
	v_pk_fma_f32 v[10:11], v[158:159], v[62:63], v[10:11] op_sel_hi:[0,1,1]
	v_pk_fma_f32 v[8:9], v[158:159], v[64:65], v[8:9] op_sel_hi:[0,1,1]
	v_pk_fma_f32 v[6:7], v[158:159], v[66:67], v[6:7] op_sel_hi:[0,1,1]
	v_pk_fma_f32 v[4:5], v[158:159], v[68:69], v[4:5] op_sel_hi:[0,1,1]
	v_pk_fma_f32 v[20:21], v[160:161], v[70:71], v[20:21] op_sel_hi:[0,1,1]
	v_pk_fma_f32 v[18:19], v[160:161], v[72:73], v[18:19] op_sel_hi:[0,1,1]
	v_pk_fma_f32 v[14:15], v[160:161], v[74:75], v[14:15] op_sel_hi:[0,1,1]
	v_pk_fma_f32 v[12:13], v[160:161], v[76:77], v[12:13] op_sel_hi:[0,1,1]
	v_pk_fma_f32 v[10:11], v[160:161], v[78:79], v[10:11] op_sel_hi:[0,1,1]
	v_pk_fma_f32 v[8:9], v[160:161], v[80:81], v[8:9] op_sel_hi:[0,1,1]
	v_pk_fma_f32 v[6:7], v[160:161], v[82:83], v[6:7] op_sel_hi:[0,1,1]
	v_pk_fma_f32 v[4:5], v[160:161], v[84:85], v[4:5] op_sel_hi:[0,1,1]
	v_pk_fma_f32 v[20:21], v[178:179], v[86:87], v[20:21] op_sel_hi:[0,1,1]
	v_pk_fma_f32 v[18:19], v[178:179], v[88:89], v[18:19] op_sel_hi:[0,1,1]
	v_pk_fma_f32 v[14:15], v[178:179], v[90:91], v[14:15] op_sel_hi:[0,1,1]
	v_pk_fma_f32 v[12:13], v[178:179], v[92:93], v[12:13] op_sel_hi:[0,1,1]
	v_pk_fma_f32 v[10:11], v[178:179], v[94:95], v[10:11] op_sel_hi:[0,1,1]
	v_pk_fma_f32 v[8:9], v[178:179], v[96:97], v[8:9] op_sel_hi:[0,1,1]
	v_pk_fma_f32 v[6:7], v[178:179], v[98:99], v[6:7] op_sel_hi:[0,1,1]
	v_pk_fma_f32 v[4:5], v[178:179], v[100:101], v[4:5] op_sel_hi:[0,1,1]
	v_pk_fma_f32 v[20:21], v[180:181], v[102:103], v[20:21] op_sel_hi:[0,1,1]
	v_pk_fma_f32 v[18:19], v[180:181], v[104:105], v[18:19] op_sel_hi:[0,1,1]
	v_pk_fma_f32 v[14:15], v[180:181], v[106:107], v[14:15] op_sel_hi:[0,1,1]
	v_pk_fma_f32 v[12:13], v[180:181], v[108:109], v[12:13] op_sel_hi:[0,1,1]
	v_pk_fma_f32 v[10:11], v[180:181], v[110:111], v[10:11] op_sel_hi:[0,1,1]
	v_pk_fma_f32 v[8:9], v[180:181], v[112:113], v[8:9] op_sel_hi:[0,1,1]
	v_pk_fma_f32 v[6:7], v[180:181], v[114:115], v[6:7] op_sel_hi:[0,1,1]
	v_pk_fma_f32 v[4:5], v[180:181], v[116:117], v[4:5] op_sel_hi:[0,1,1]
	v_pk_fma_f32 v[20:21], v[182:183], v[118:119], v[20:21] op_sel_hi:[0,1,1]
	v_pk_fma_f32 v[18:19], v[182:183], v[120:121], v[18:19] op_sel_hi:[0,1,1]
	v_pk_fma_f32 v[14:15], v[182:183], v[122:123], v[14:15] op_sel_hi:[0,1,1]
	v_pk_fma_f32 v[12:13], v[182:183], v[124:125], v[12:13] op_sel_hi:[0,1,1]
	v_pk_fma_f32 v[10:11], v[182:183], v[126:127], v[10:11] op_sel_hi:[0,1,1]
	v_pk_fma_f32 v[8:9], v[182:183], v[128:129], v[8:9] op_sel_hi:[0,1,1]
	v_pk_fma_f32 v[6:7], v[182:183], v[130:131], v[6:7] op_sel_hi:[0,1,1]
	v_pk_fma_f32 v[4:5], v[182:183], v[132:133], v[4:5] op_sel_hi:[0,1,1]
	v_pk_fma_f32 v[20:21], v[184:185], v[134:135], v[20:21] op_sel_hi:[0,1,1]
	v_pk_fma_f32 v[18:19], v[184:185], v[136:137], v[18:19] op_sel_hi:[0,1,1]
	v_pk_fma_f32 v[14:15], v[184:185], v[138:139], v[14:15] op_sel_hi:[0,1,1]
	v_pk_fma_f32 v[12:13], v[184:185], v[140:141], v[12:13] op_sel_hi:[0,1,1]
	v_pk_fma_f32 v[10:11], v[184:185], v[142:143], v[10:11] op_sel_hi:[0,1,1]
	v_pk_fma_f32 v[8:9], v[184:185], v[144:145], v[8:9] op_sel_hi:[0,1,1]
	v_pk_fma_f32 v[6:7], v[184:185], v[146:147], v[6:7] op_sel_hi:[0,1,1]
	v_pk_fma_f32 v[4:5], v[184:185], v[148:149], v[4:5] op_sel_hi:[0,1,1]
	s_cbranch_scc1 .LBB0_931
; __device__ __forceinline__ bf16 f2bf(float f) { return (bf16)(pk2(f, 0.f) & 0xffffu); }
; __device__ __forceinline__ void mla_sample_unit(LAS unsigned char* lds, size_t ws_q, size_t ws_olat, size_t ws_mixed, int b) {
;     ...
; #pragma unroll
;       for (int t = 0; t < 16; ++t) MIXED[(size_t)(rowbase + t) * 1024 + h * 64 + d] = f2bf(acc[t]); }
;     __syncthreads();
	v_readfirstlane_b32 s2, v3
	v_readfirstlane_b32 s3, v2
	v_and_b32_e32 v16, 0xffffffc0, v176
	v_mov_b32_e32 v3, s2
	v_mov_b32_e32 v2, s3
	v_ashrrev_i32_e32 v17, 31, v16
	v_lshl_add_u64 v[2:3], v[16:17], 1, v[2:3]
	v_lshlrev_b32_e32 v16, 1, v156
	v_mov_b32_e32 v17, v0
	v_lshl_add_u64 v[2:3], v[2:3], 0, v[16:17]
	s_mov_b64 s[2:3], 0x2600000
	s_ashr_i32 s59, s58, 31
	v_lshl_add_u64 v[2:3], v[2:3], 0, s[2:3]
	s_lshl_b64 s[2:3], s[58:59], 11
	v_lshl_add_u64 v[16:17], v[2:3], 0, s[2:3]
	s_or_b32 s2, s58, 1
	s_ashr_i32 s3, s2, 31
	v_cvt_pk_bf16_f32 v1, v20, s0
	s_lshl_b64 s[2:3], s[2:3], 11
	global_store_short v[16:17], v1, off
	v_lshl_add_u64 v[16:17], v[2:3], 0, s[2:3]
	s_or_b32 s2, s58, 2
	s_ashr_i32 s3, s2, 31
	v_cvt_pk_bf16_f32 v1, v21, s0
	s_lshl_b64 s[2:3], s[2:3], 11
	global_store_short v[16:17], v1, off
	v_lshl_add_u64 v[16:17], v[2:3], 0, s[2:3]
	s_or_b32 s2, s58, 3
	s_ashr_i32 s3, s2, 31
	v_cvt_pk_bf16_f32 v1, v18, s0
	s_lshl_b64 s[2:3], s[2:3], 11
	global_store_short v[16:17], v1, off
	v_lshl_add_u64 v[16:17], v[2:3], 0, s[2:3]
	s_or_b32 s2, s58, 4
	s_ashr_i32 s3, s2, 31
	v_cvt_pk_bf16_f32 v1, v19, s0
	s_lshl_b64 s[2:3], s[2:3], 11
	global_store_short v[16:17], v1, off
	v_lshl_add_u64 v[16:17], v[2:3], 0, s[2:3]
	s_or_b32 s2, s58, 5
	s_ashr_i32 s3, s2, 31
	v_cvt_pk_bf16_f32 v1, v14, s0
	s_lshl_b64 s[2:3], s[2:3], 11
	global_store_short v[16:17], v1, off
	v_cvt_pk_bf16_f32 v1, v15, s0
	v_lshl_add_u64 v[14:15], v[2:3], 0, s[2:3]
	s_or_b32 s2, s58, 6
	s_ashr_i32 s3, s2, 31
	s_lshl_b64 s[2:3], s[2:3], 11
	global_store_short v[14:15], v1, off
	v_lshl_add_u64 v[14:15], v[2:3], 0, s[2:3]
	s_or_b32 s2, s58, 7
	s_ashr_i32 s3, s2, 31
	v_cvt_pk_bf16_f32 v1, v12, s0
	s_lshl_b64 s[2:3], s[2:3], 11
	global_store_short v[14:15], v1, off
	v_cvt_pk_bf16_f32 v1, v13, s0
	v_lshl_add_u64 v[12:13], v[2:3], 0, s[2:3]
	s_or_b32 s2, s58, 8
	s_ashr_i32 s3, s2, 31
	s_lshl_b64 s[2:3], s[2:3], 11
	global_store_short v[12:13], v1, off
	v_lshl_add_u64 v[12:13], v[2:3], 0, s[2:3]
	s_or_b32 s2, s58, 9
	s_ashr_i32 s3, s2, 31
	v_cvt_pk_bf16_f32 v1, v10, s0
	s_lshl_b64 s[2:3], s[2:3], 11
	global_store_short v[12:13], v1, off
	v_cvt_pk_bf16_f32 v1, v11, s0
	v_lshl_add_u64 v[10:11], v[2:3], 0, s[2:3]
	s_or_b32 s2, s58, 10
	s_ashr_i32 s3, s2, 31
	s_lshl_b64 s[2:3], s[2:3], 11
	global_store_short v[10:11], v1, off
	v_lshl_add_u64 v[10:11], v[2:3], 0, s[2:3]
	s_or_b32 s2, s58, 11
	s_ashr_i32 s3, s2, 31
	v_cvt_pk_bf16_f32 v1, v8, s0
	s_lshl_b64 s[2:3], s[2:3], 11
	global_store_short v[10:11], v1, off
	v_cvt_pk_bf16_f32 v1, v9, s0
	v_lshl_add_u64 v[8:9], v[2:3], 0, s[2:3]
	s_or_b32 s2, s58, 12
	s_ashr_i32 s3, s2, 31
	s_lshl_b64 s[2:3], s[2:3], 11
	global_store_short v[8:9], v1, off
	v_lshl_add_u64 v[8:9], v[2:3], 0, s[2:3]
	s_or_b32 s2, s58, 13
	s_ashr_i32 s3, s2, 31
	v_cvt_pk_bf16_f32 v1, v6, s0
	s_lshl_b64 s[2:3], s[2:3], 11
	global_store_short v[8:9], v1, off
	v_cvt_pk_bf16_f32 v1, v7, s0
	v_lshl_add_u64 v[6:7], v[2:3], 0, s[2:3]
	s_or_b32 s2, s58, 14
	s_ashr_i32 s3, s2, 31
	s_lshl_b64 s[2:3], s[2:3], 11
	global_store_short v[6:7], v1, off
	v_lshl_add_u64 v[6:7], v[2:3], 0, s[2:3]
	s_or_b32 s2, s58, 15
	s_ashr_i32 s3, s2, 31
	v_cvt_pk_bf16_f32 v1, v4, s0
	s_lshl_b64 s[2:3], s[2:3], 11
	global_store_short v[6:7], v1, off
	v_cvt_pk_bf16_f32 v1, v5, s0
	v_lshl_add_u64 v[2:3], v[2:3], 0, s[2:3]
	global_store_short v[2:3], v1, off
	s_waitcnt lgkmcnt(0)
	s_barrier
	s_branch .LBB0_622

; #define INP(i) ((const float*)tab_get(lds, (i)))
; #define OUTP() ((float*)tab_get(lds, 30))
; #define WSB(off) ((bf16*)((unsigned char*)tab_get(lds, 31) + (off)))
;     __device__ __forceinline__ void operator()(EPI_ARGS) const {
;         const int row0 = u.pm * BM + wr * 64 + fr, col0 = u.pn * BM + wc * 32 + 8 * fq;
; #pragma unroll
;         for (int ai = 0; ai < 2; ++ai)
; #pragma unroll
;             for (int m = 0; m < 4; ++m) { const int row = row0 + ai * HALF + m * 16;
;                 const float* b = base + (size_t)row * DM + col0; float* o = X + (size_t)row * DM + col0;
; #pragma unroll
;                 for (int bj = 0; bj < 2; ++bj) { const f32x4 b0 = *(const f32x4*)(b + bj * HALF), b1 = *(const f32x4*)(b + bj * HALF + 4);
;                     *(f32x4*)(o + bj * HALF) = b0 + acc[ai][bj][m][0]; *(f32x4*)(o + bj * HALF + 4) = b1 + acc[ai][bj][m][1]; } }
;     }
; __global__ void __launch_bounds__(512, 2) mega_fwd(Params p) {
;     ...
;     { pg8::Gemm g{WSB(WS_MIXED), WSB(WS_WO), MP, 1024, 1024, 1024, 1024}; pg8::StaticOrder S; S.init(MP, 1024, G, bx); pg8::EpiResid E{INP(0), OUTP()}; pg8::gemm_phase(lds, g, S, E); }
.LBB0_997:
	v_lshl_add_u32 v162, s30, 8, v148
	v_lshl_or_b32 v144, s60, 8, v150
	v_ashrrev_i32_e32 v163, 31, v162
	v_ashrrev_i32_e32 v145, 31, v144
	v_lshlrev_b64 v[146:147], 12, v[162:163]
	v_lshl_add_u64 v[154:155], s[4:5], 0, v[146:147]
	v_lshlrev_b64 v[144:145], 2, v[144:145]
	v_lshl_add_u64 v[164:165], v[154:155], 0, v[144:145]
	global_load_dwordx4 v[154:157], v[164:165], off
	global_load_dwordx4 v[158:161], v[164:165], off offset:16
	v_lshl_add_u64 v[166:167], s[6:7], 0, v[146:147]
	v_lshl_add_u64 v[166:167], v[166:167], 0, v[144:145]
	s_andn2_b64 vcc, exec, s[2:3]
	s_mov_b64 s[2:3], -1
	s_waitcnt vmcnt(0) lgkmcnt(0)
	v_pk_add_f32 v[126:127], v[126:127], v[156:157]
	v_pk_add_f32 v[124:125], v[124:125], v[154:155]
	v_pk_add_f32 v[122:123], v[122:123], v[160:161]
	v_pk_add_f32 v[120:121], v[120:121], v[158:159]
	global_store_dwordx4 v[166:167], v[124:127], off
	global_store_dwordx4 v[166:167], v[120:123], off offset:16
	global_load_dwordx4 v[120:123], v[164:165], off offset:512
	s_nop 0
	global_load_dwordx4 v[124:127], v[164:165], off offset:528
	v_or_b32_e32 v154, 16, v162
	v_ashrrev_i32_e32 v155, 31, v154
	v_lshlrev_b64 v[154:155], 12, v[154:155]
	v_lshl_add_u64 v[156:157], s[4:5], 0, v[154:155]
	v_lshl_add_u64 v[156:157], v[156:157], 0, v[144:145]
	s_waitcnt vmcnt(0) lgkmcnt(0)
	v_pk_add_f32 v[114:115], v[114:115], v[122:123]
	v_pk_add_f32 v[112:113], v[112:113], v[120:121]
	v_pk_add_f32 v[110:111], v[110:111], v[126:127]
	v_pk_add_f32 v[108:109], v[108:109], v[124:125]
	global_store_dwordx4 v[166:167], v[112:115], off offset:512
	global_store_dwordx4 v[166:167], v[108:111], off offset:528
	global_load_dwordx4 v[108:111], v[156:157], off
	s_nop 0
	global_load_dwordx4 v[112:115], v[156:157], off offset:16
	v_lshl_add_u64 v[120:121], s[6:7], 0, v[154:155]
	v_lshl_add_u64 v[120:121], v[120:121], 0, v[144:145]
	s_waitcnt vmcnt(0) lgkmcnt(0)
	v_pk_add_f32 v[110:111], v[118:119], v[110:111]
	v_pk_add_f32 v[108:109], v[116:117], v[108:109]
	v_pk_add_f32 v[106:107], v[106:107], v[114:115]
	v_pk_add_f32 v[104:105], v[104:105], v[112:113]
	global_store_dwordx4 v[120:121], v[108:111], off
	global_store_dwordx4 v[120:121], v[104:107], off offset:16
	global_load_dwordx4 v[104:107], v[156:157], off offset:512
	s_nop 0
	global_load_dwordx4 v[108:111], v[156:157], off offset:528
	v_or_b32_e32 v112, 32, v162
	v_ashrrev_i32_e32 v113, 31, v112
	v_lshlrev_b64 v[112:113], 12, v[112:113]
	v_lshl_add_u64 v[114:115], s[4:5], 0, v[112:113]
	v_lshl_add_u64 v[114:115], v[114:115], 0, v[144:145]
	s_waitcnt vmcnt(0) lgkmcnt(0)
	v_pk_add_f32 v[98:99], v[98:99], v[106:107]
	v_pk_add_f32 v[96:97], v[96:97], v[104:105]
	v_pk_add_f32 v[94:95], v[94:95], v[110:111]
	v_pk_add_f32 v[92:93], v[92:93], v[108:109]
	global_store_dwordx4 v[120:121], v[96:99], off offset:512
	global_store_dwordx4 v[120:121], v[92:95], off offset:528
	global_load_dwordx4 v[92:95], v[114:115], off
	s_nop 0
	global_load_dwordx4 v[96:99], v[114:115], off offset:16
	v_lshl_add_u64 v[104:105], s[6:7], 0, v[112:113]
	v_lshl_add_u64 v[104:105], v[104:105], 0, v[144:145]
	s_waitcnt vmcnt(0) lgkmcnt(0)
	v_pk_add_f32 v[94:95], v[102:103], v[94:95]
	v_pk_add_f32 v[92:93], v[100:101], v[92:93]
	v_pk_add_f32 v[90:91], v[90:91], v[98:99]
	v_pk_add_f32 v[88:89], v[88:89], v[96:97]
	global_store_dwordx4 v[104:105], v[92:95], off
	global_store_dwordx4 v[104:105], v[88:91], off offset:16
	global_load_dwordx4 v[88:91], v[114:115], off offset:512
	s_nop 0
	global_load_dwordx4 v[92:95], v[114:115], off offset:528
	v_or_b32_e32 v96, 48, v162
	v_ashrrev_i32_e32 v97, 31, v96
	v_lshlrev_b64 v[96:97], 12, v[96:97]
	v_lshl_add_u64 v[98:99], s[4:5], 0, v[96:97]
	v_lshl_add_u64 v[98:99], v[98:99], 0, v[144:145]
	s_waitcnt vmcnt(0) lgkmcnt(0)
	v_pk_add_f32 v[82:83], v[82:83], v[90:91]
	v_pk_add_f32 v[80:81], v[80:81], v[88:89]
	v_pk_add_f32 v[78:79], v[78:79], v[94:95]
	v_pk_add_f32 v[76:77], v[76:77], v[92:93]
	global_store_dwordx4 v[104:105], v[80:83], off offset:512
	global_store_dwordx4 v[104:105], v[76:79], off offset:528
	global_load_dwordx4 v[76:79], v[98:99], off
	s_nop 0
	global_load_dwordx4 v[80:83], v[98:99], off offset:16
	v_lshl_add_u64 v[88:89], s[6:7], 0, v[96:97]
	v_lshl_add_u64 v[88:89], v[88:89], 0, v[144:145]
	s_waitcnt vmcnt(0) lgkmcnt(0)
	v_pk_add_f32 v[78:79], v[86:87], v[78:79]
	v_pk_add_f32 v[76:77], v[84:85], v[76:77]
	v_pk_add_f32 v[74:75], v[74:75], v[82:83]
	v_pk_add_f32 v[72:73], v[72:73], v[80:81]
	global_store_dwordx4 v[88:89], v[76:79], off
	global_store_dwordx4 v[88:89], v[72:75], off offset:16
	global_load_dwordx4 v[72:75], v[98:99], off offset:512
	s_nop 0
	global_load_dwordx4 v[76:79], v[98:99], off offset:528
	v_lshl_add_u64 v[80:81], v[146:147], 0, s[14:15]
	v_lshl_add_u64 v[82:83], s[4:5], 0, v[80:81]
	v_lshl_add_u64 v[82:83], v[82:83], 0, v[144:145]
	s_waitcnt vmcnt(0) lgkmcnt(0)
;     __device__ __forceinline__ void operator()(EPI_ARGS) const {
;         const int row0 = u.pm * BM + wr * 64 + fr, col0 = u.pn * BM + wc * 32 + 8 * fq;
; #pragma unroll
;         for (int ai = 0; ai < 2; ++ai)
; #pragma unroll
;             for (int m = 0; m < 4; ++m) { const int row = row0 + ai * HALF + m * 16;
;                 const float* b = base + (size_t)row * DM + col0; float* o = X + (size_t)row * DM + col0;
; #pragma unroll
;                 for (int bj = 0; bj < 2; ++bj) { const f32x4 b0 = *(const f32x4*)(b + bj * HALF), b1 = *(const f32x4*)(b + bj * HALF + 4);
;                     *(f32x4*)(o + bj * HALF) = b0 + acc[ai][bj][m][0]; *(f32x4*)(o + bj * HALF + 4) = b1 + acc[ai][bj][m][1]; } }
;     }
	v_pk_add_f32 v[70:71], v[70:71], v[74:75]
	v_pk_add_f32 v[68:69], v[68:69], v[72:73]
	v_pk_add_f32 v[66:67], v[66:67], v[78:79]
	v_pk_add_f32 v[64:65], v[64:65], v[76:77]
	global_store_dwordx4 v[88:89], v[68:71], off offset:512
	global_store_dwordx4 v[88:89], v[64:67], off offset:528
	global_load_dwordx4 v[64:67], v[82:83], off
	s_nop 0
	global_load_dwordx4 v[68:71], v[82:83], off offset:16
	v_lshl_add_u64 v[72:73], s[6:7], 0, v[80:81]
	v_lshl_add_u64 v[72:73], v[72:73], 0, v[144:145]
	s_waitcnt vmcnt(0) lgkmcnt(0)
	v_pk_add_f32 v[62:63], v[62:63], v[66:67]
	v_pk_add_f32 v[60:61], v[60:61], v[64:65]
	v_pk_add_f32 v[58:59], v[58:59], v[70:71]
	v_pk_add_f32 v[56:57], v[56:57], v[68:69]
	global_store_dwordx4 v[72:73], v[60:63], off
	global_store_dwordx4 v[72:73], v[56:59], off offset:16
	global_load_dwordx4 v[56:59], v[82:83], off offset:512
	s_nop 0
	global_load_dwordx4 v[60:63], v[82:83], off offset:528
	v_lshl_add_u64 v[64:65], v[146:147], 0, s[16:17]
	v_lshl_add_u64 v[66:67], s[4:5], 0, v[64:65]
	v_lshl_add_u64 v[66:67], v[66:67], 0, v[144:145]
	s_waitcnt vmcnt(0) lgkmcnt(0)
	v_pk_add_f32 v[50:51], v[50:51], v[58:59]
	v_pk_add_f32 v[48:49], v[48:49], v[56:57]
	v_pk_add_f32 v[46:47], v[46:47], v[62:63]
	v_pk_add_f32 v[44:45], v[44:45], v[60:61]
	global_store_dwordx4 v[72:73], v[48:51], off offset:512
	global_store_dwordx4 v[72:73], v[44:47], off offset:528
	global_load_dwordx4 v[44:47], v[66:67], off
	s_nop 0
	global_load_dwordx4 v[48:51], v[66:67], off offset:16
	v_lshl_add_u64 v[56:57], s[6:7], 0, v[64:65]
	v_lshl_add_u64 v[56:57], v[56:57], 0, v[144:145]
	s_waitcnt vmcnt(0) lgkmcnt(0)
	v_pk_add_f32 v[46:47], v[54:55], v[46:47]
	v_pk_add_f32 v[44:45], v[52:53], v[44:45]
	v_pk_add_f32 v[42:43], v[42:43], v[50:51]
	v_pk_add_f32 v[40:41], v[40:41], v[48:49]
	global_store_dwordx4 v[56:57], v[44:47], off
	global_store_dwordx4 v[56:57], v[40:43], off offset:16
	global_load_dwordx4 v[40:43], v[66:67], off offset:512
	s_nop 0
	global_load_dwordx4 v[44:47], v[66:67], off offset:528
	v_lshl_add_u64 v[48:49], v[146:147], 0, s[18:19]
	v_lshl_add_u64 v[50:51], s[4:5], 0, v[48:49]
	v_lshl_add_u64 v[50:51], v[50:51], 0, v[144:145]
	s_waitcnt vmcnt(0) lgkmcnt(0)
	v_pk_add_f32 v[34:35], v[34:35], v[42:43]
	v_pk_add_f32 v[32:33], v[32:33], v[40:41]
	v_pk_add_f32 v[30:31], v[30:31], v[46:47]
	v_pk_add_f32 v[28:29], v[28:29], v[44:45]
	global_store_dwordx4 v[56:57], v[32:35], off offset:512
	global_store_dwordx4 v[56:57], v[28:31], off offset:528
	global_load_dwordx4 v[28:31], v[50:51], off
	s_nop 0
	global_load_dwordx4 v[32:35], v[50:51], off offset:16
	v_lshl_add_u64 v[40:41], s[6:7], 0, v[48:49]
	v_lshl_add_u64 v[40:41], v[40:41], 0, v[144:145]
	s_waitcnt vmcnt(0) lgkmcnt(0)
	v_pk_add_f32 v[30:31], v[38:39], v[30:31]
	v_pk_add_f32 v[28:29], v[36:37], v[28:29]
	v_pk_add_f32 v[26:27], v[26:27], v[34:35]
	v_pk_add_f32 v[24:25], v[24:25], v[32:33]
	global_store_dwordx4 v[40:41], v[28:31], off
	global_store_dwordx4 v[40:41], v[24:27], off offset:16
	global_load_dwordx4 v[24:27], v[50:51], off offset:512
	s_nop 0
	global_load_dwordx4 v[28:31], v[50:51], off offset:528
	v_lshl_add_u64 v[32:33], v[146:147], 0, s[20:21]
	v_lshl_add_u64 v[34:35], s[4:5], 0, v[32:33]
	v_lshl_add_u64 v[34:35], v[34:35], 0, v[144:145]
	s_waitcnt vmcnt(0) lgkmcnt(0)
	v_pk_add_f32 v[18:19], v[18:19], v[26:27]
	v_pk_add_f32 v[16:17], v[16:17], v[24:25]
	v_pk_add_f32 v[14:15], v[14:15], v[30:31]
	v_pk_add_f32 v[12:13], v[12:13], v[28:29]
	global_store_dwordx4 v[40:41], v[16:19], off offset:512
	global_store_dwordx4 v[40:41], v[12:15], off offset:528
	global_load_dwordx4 v[12:15], v[34:35], off
	s_nop 0
	global_load_dwordx4 v[16:19], v[34:35], off offset:16
	v_lshl_add_u64 v[24:25], s[6:7], 0, v[32:33]
	v_lshl_add_u64 v[24:25], v[24:25], 0, v[144:145]
	s_waitcnt vmcnt(0) lgkmcnt(0)
	v_pk_add_f32 v[14:15], v[22:23], v[14:15]
	v_pk_add_f32 v[12:13], v[20:21], v[12:13]
	v_pk_add_f32 v[10:11], v[10:11], v[18:19]
	v_pk_add_f32 v[8:9], v[8:9], v[16:17]
	global_store_dwordx4 v[24:25], v[12:15], off
	global_store_dwordx4 v[24:25], v[8:11], off offset:16
	global_load_dwordx4 v[8:11], v[34:35], off offset:512
	s_nop 0
	global_load_dwordx4 v[12:15], v[34:35], off offset:528
	s_waitcnt vmcnt(0) lgkmcnt(0)
	v_pk_add_f32 v[6:7], v[6:7], v[10:11]
	v_pk_add_f32 v[4:5], v[4:5], v[8:9]
	v_pk_add_f32 v[2:3], v[2:3], v[14:15]
	v_pk_add_f32 v[0:1], v[0:1], v[12:13]
	global_store_dwordx4 v[24:25], v[4:7], off offset:512
	global_store_dwordx4 v[24:25], v[0:3], off offset:528
	s_cbranch_vccnz .LBB0_986
	s_andn2_b64 vcc, exec, s[8:9]
	s_cbranch_vccnz .LBB0_985
	s_barrier
	s_branch .LBB0_985

; __device__ __forceinline__ unsigned xb_ld(unsigned* p)              { return __hip_atomic_load(p, __ATOMIC_RELAXED, __HIP_MEMORY_SCOPE_AGENT); }
; __device__ __forceinline__ unsigned xb_add(unsigned* p, unsigned v) { return __hip_atomic_fetch_add(p, v, __ATOMIC_RELAXED, __HIP_MEMORY_SCOPE_AGENT); }
; #define XB_SPIN(cond, bar) do { unsigned _sp = 0; while (cond) { __builtin_amdgcn_s_sleep(1); \
;     if ((++_sp & 255u) == 0u) { if (xb_ld(&(bar)[XB_TMO])) break; if (_sp > XB_SPIN_CAP) { atomicAdd(&(bar)[XB_TMO], 1u); break; } } } } while (0)
; __device__ __forceinline__ void xcd_barrier(const XcdBarrier& b, bool leader) {
;     asm volatile("s_waitcnt vmcnt(0)" ::: "memory");
;     __syncthreads();
;     if (leader) {
;         unsigned* bar = b.bar;
;         __builtin_amdgcn_s_waitcnt(0);
;         unsigned nloc = b.st[0], nx = b.st[1];
;         if (nloc == 0u) { xcd_barrier_complete(bar, b.x, nloc, nx); b.st[0] = nloc; b.st[1] = nx; }
;         const unsigned old = xb_add(&bar[XB_XSUB(b.x)], 1u);
;         const unsigned gen = old / nloc;
;         if (old + 1u == (gen + 1u) * nloc) {
;             __builtin_amdgcn_fence(__ATOMIC_RELEASE, "agent");
;             asm volatile("s_waitcnt vmcnt(0)" ::: "memory");
;             const unsigned og = xb_add(&bar[XB_TOP], 1u);
;             const unsigned tg = og / nx;
;             if (og + 1u == (tg + 1u) * nx) xb_add(&bar[XB_TOPGEN], 1u);
;             else XB_SPIN(xb_ld(&bar[XB_TOPGEN]) == tg, bar);
;             __builtin_amdgcn_fence(__ATOMIC_ACQUIRE, "agent");
;             xb_add(&bar[XB_XGEN(b.x)], 1u);
;             asm volatile("s_waitcnt vmcnt(0)" ::: "memory");
;         } else {
;             XB_SPIN(xb_ld(&bar[XB_XGEN(b.x)]) == gen, bar);
.LBB0_1016:
	s_lshl_b32 s2, s38, 8
	s_add_u32 s2, s1, s2
	s_addc_u32 s3, s0, 0
	v_mov_b32_e32 v1, s2
	v_add_co_u32_e32 v4, vcc, 0x2000, v1
	v_mov_b32_e32 v1, s3
	s_nop 0
	v_addc_co_u32_e32 v5, vcc, 0, v1, vcc
	v_mov_b32_e32 v1, 1
	global_atomic_add v1, v[4:5], v1, off offset:1024 sc0
	v_cvt_f32_u32_e32 v3, v2
	v_sub_u32_e32 v4, 0, v2
	s_add_u32 s25, s2, 0x1000
	s_addc_u32 s24, s3, 0
	v_rcp_iflag_f32_e32 v3, v3
	s_nop 0
	v_mul_f32_e32 v3, 0x4f7ffffe, v3
	v_cvt_u32_f32_e32 v3, v3
	v_mul_lo_u32 v4, v4, v3
	v_mul_hi_u32 v4, v3, v4
	v_add_u32_e32 v3, v3, v4
	s_waitcnt vmcnt(0) lgkmcnt(0)
	v_mul_hi_u32 v3, v1, v3
	v_mul_lo_u32 v5, v3, v2
	v_add_u32_e32 v4, 1, v1
	v_sub_u32_e32 v1, v1, v5
	v_add_u32_e32 v6, 1, v3
	v_cmp_ge_u32_e32 vcc, v1, v2
	v_sub_u32_e32 v5, v1, v2
	s_nop 0
	v_cndmask_b32_e32 v3, v3, v6, vcc
	v_cndmask_b32_e32 v1, v1, v5, vcc
	v_add_u32_e32 v5, 1, v3
	v_cmp_ge_u32_e32 vcc, v1, v2
	s_nop 1
	v_cndmask_b32_e32 v1, v3, v5, vcc
	v_mad_u64_u32 v[2:3], s[2:3], v2, v1, v[2:3]
	v_cmp_ne_u32_e32 vcc, v4, v2
	s_and_saveexec_b64 s[2:3], vcc
	s_xor_b64 s[2:3], exec, s[2:3]
	s_cbranch_execz .LBB0_1029
	v_mov_b32_e32 v0, s25
	v_add_co_u32_e32 v2, vcc, 0x2000, v0
	v_mov_b32_e32 v0, s24
	s_nop 0
	v_addc_co_u32_e32 v3, vcc, 0, v0, vcc
	global_load_dword v0, v[2:3], off offset:1024 sc1
	s_add_u32 s8, s25, 0x2400
	s_addc_u32 s9, s24, 0
	s_waitcnt vmcnt(0) lgkmcnt(0)
	v_cmp_eq_u32_e32 vcc, v0, v1
	s_and_saveexec_b64 s[4:5], vcc
	s_cbranch_execz .LBB0_1028
	s_add_u32 s6, s1, 0x1200
	s_addc_u32 s7, s0, 0
	s_mov_b32 s26, 1
	s_mov_b64 s[10:11], 0
	s_branch .LBB0_1020

; #define INP(i) ((const float*)tab_get(lds, (i)))
; #define OUTP() ((float*)tab_get(lds, 30))
; #define WSB(off) ((bf16*)((unsigned char*)tab_get(lds, 31) + (off)))
;     __device__ __forceinline__ void operator()(EPI_ARGS) const {
;         const int row0 = u.pm * BM + wr * 64 + fr, col0 = u.pn * BM + wc * 32 + 8 * fq;
; #pragma unroll
;         for (int ai = 0; ai < 2; ++ai)
; #pragma unroll
;             for (int m = 0; m < 4; ++m) { const int row = row0 + ai * HALF + m * 16;
;                 const float* b = base + (size_t)row * DM + col0; float* o = X + (size_t)row * DM + col0;
; #pragma unroll
;                 for (int bj = 0; bj < 2; ++bj) { const f32x4 b0 = *(const f32x4*)(b + bj * HALF), b1 = *(const f32x4*)(b + bj * HALF + 4);
;                     *(f32x4*)(o + bj * HALF) = b0 + acc[ai][bj][m][0]; *(f32x4*)(o + bj * HALF + 4) = b1 + acc[ai][bj][m][1]; } }
;     }
; __global__ void __launch_bounds__(512, 2) mega_fwd(Params p) {
;     ...
;         { pg8::Gemm g{WSB(WS_MIXED) + SROWS * DM, WSB(WS_WO), MS, 1024, 1024, 1024, 1024}; pg8::StaticOrder S; S.init(MS, 1024, G, bx); pg8::EpiResid E{INP(1), OUTP() + SROWS * DM}; pg8::gemm_phase(lds, g, S, E); }
.LBB0_1057:
	v_lshl_add_u32 v158, s30, 8, v144
	v_lshl_or_b32 v140, s63, 8, v146
	v_ashrrev_i32_e32 v159, 31, v158
	v_ashrrev_i32_e32 v141, 31, v140
	v_lshlrev_b64 v[142:143], 12, v[158:159]
	v_lshl_add_u64 v[150:151], s[2:3], 0, v[142:143]
	v_lshlrev_b64 v[140:141], 2, v[140:141]
	v_lshl_add_u64 v[160:161], v[150:151], 0, v[140:141]
	global_load_dwordx4 v[150:153], v[160:161], off
	global_load_dwordx4 v[154:157], v[160:161], off offset:16
	v_lshl_add_u64 v[162:163], s[6:7], 0, v[142:143]
	v_lshl_add_u64 v[162:163], v[162:163], 0, v[140:141]
	s_andn2_b64 vcc, exec, s[24:25]
	s_mov_b64 s[24:25], -1
	s_waitcnt vmcnt(0) lgkmcnt(0)
	v_pk_add_f32 v[126:127], v[126:127], v[152:153]
	v_pk_add_f32 v[124:125], v[124:125], v[150:151]
	v_pk_add_f32 v[122:123], v[122:123], v[156:157]
	v_pk_add_f32 v[120:121], v[120:121], v[154:155]
	global_store_dwordx4 v[162:163], v[124:127], off
	global_store_dwordx4 v[162:163], v[120:123], off offset:16
	global_load_dwordx4 v[120:123], v[160:161], off offset:512
	s_nop 0
	global_load_dwordx4 v[124:127], v[160:161], off offset:528
	v_or_b32_e32 v150, 16, v158
	v_ashrrev_i32_e32 v151, 31, v150
	v_lshlrev_b64 v[150:151], 12, v[150:151]
	v_lshl_add_u64 v[152:153], s[2:3], 0, v[150:151]
	v_lshl_add_u64 v[152:153], v[152:153], 0, v[140:141]
	s_waitcnt vmcnt(0) lgkmcnt(0)
	v_pk_add_f32 v[114:115], v[114:115], v[122:123]
	v_pk_add_f32 v[112:113], v[112:113], v[120:121]
	v_pk_add_f32 v[110:111], v[110:111], v[126:127]
	v_pk_add_f32 v[108:109], v[108:109], v[124:125]
	global_store_dwordx4 v[162:163], v[112:115], off offset:512
	global_store_dwordx4 v[162:163], v[108:111], off offset:528
	global_load_dwordx4 v[108:111], v[152:153], off
	s_nop 0
	global_load_dwordx4 v[112:115], v[152:153], off offset:16
	v_lshl_add_u64 v[120:121], s[6:7], 0, v[150:151]
	v_lshl_add_u64 v[120:121], v[120:121], 0, v[140:141]
	s_waitcnt vmcnt(0) lgkmcnt(0)
	v_pk_add_f32 v[110:111], v[118:119], v[110:111]
	v_pk_add_f32 v[108:109], v[116:117], v[108:109]
	v_pk_add_f32 v[106:107], v[106:107], v[114:115]
	v_pk_add_f32 v[104:105], v[104:105], v[112:113]
	global_store_dwordx4 v[120:121], v[108:111], off
	global_store_dwordx4 v[120:121], v[104:107], off offset:16
	global_load_dwordx4 v[104:107], v[152:153], off offset:512
	s_nop 0
	global_load_dwordx4 v[108:111], v[152:153], off offset:528
	v_or_b32_e32 v112, 32, v158
	v_ashrrev_i32_e32 v113, 31, v112
	v_lshlrev_b64 v[112:113], 12, v[112:113]
	v_lshl_add_u64 v[114:115], s[2:3], 0, v[112:113]
	v_lshl_add_u64 v[114:115], v[114:115], 0, v[140:141]
	s_waitcnt vmcnt(0) lgkmcnt(0)
	v_pk_add_f32 v[98:99], v[98:99], v[106:107]
	v_pk_add_f32 v[96:97], v[96:97], v[104:105]
	v_pk_add_f32 v[94:95], v[94:95], v[110:111]
	v_pk_add_f32 v[92:93], v[92:93], v[108:109]
	global_store_dwordx4 v[120:121], v[96:99], off offset:512
	global_store_dwordx4 v[120:121], v[92:95], off offset:528
	global_load_dwordx4 v[92:95], v[114:115], off
	s_nop 0
	global_load_dwordx4 v[96:99], v[114:115], off offset:16
	v_lshl_add_u64 v[104:105], s[6:7], 0, v[112:113]
	v_lshl_add_u64 v[104:105], v[104:105], 0, v[140:141]
	s_waitcnt vmcnt(0) lgkmcnt(0)
	v_pk_add_f32 v[94:95], v[102:103], v[94:95]
	v_pk_add_f32 v[92:93], v[100:101], v[92:93]
	v_pk_add_f32 v[90:91], v[90:91], v[98:99]
	v_pk_add_f32 v[88:89], v[88:89], v[96:97]
	global_store_dwordx4 v[104:105], v[92:95], off
	global_store_dwordx4 v[104:105], v[88:91], off offset:16
	global_load_dwordx4 v[88:91], v[114:115], off offset:512
	s_nop 0
	global_load_dwordx4 v[92:95], v[114:115], off offset:528
	v_or_b32_e32 v96, 48, v158
	v_ashrrev_i32_e32 v97, 31, v96
	v_lshlrev_b64 v[96:97], 12, v[96:97]
	v_lshl_add_u64 v[98:99], s[2:3], 0, v[96:97]
	v_lshl_add_u64 v[98:99], v[98:99], 0, v[140:141]
	s_waitcnt vmcnt(0) lgkmcnt(0)
	v_pk_add_f32 v[82:83], v[82:83], v[90:91]
	v_pk_add_f32 v[80:81], v[80:81], v[88:89]
	v_pk_add_f32 v[78:79], v[78:79], v[94:95]
	v_pk_add_f32 v[76:77], v[76:77], v[92:93]
	global_store_dwordx4 v[104:105], v[80:83], off offset:512
	global_store_dwordx4 v[104:105], v[76:79], off offset:528
	global_load_dwordx4 v[76:79], v[98:99], off
	s_nop 0
	global_load_dwordx4 v[80:83], v[98:99], off offset:16
	v_lshl_add_u64 v[88:89], s[6:7], 0, v[96:97]
	v_lshl_add_u64 v[88:89], v[88:89], 0, v[140:141]
	s_waitcnt vmcnt(0) lgkmcnt(0)
	v_pk_add_f32 v[78:79], v[86:87], v[78:79]
	v_pk_add_f32 v[76:77], v[84:85], v[76:77]
	v_pk_add_f32 v[74:75], v[74:75], v[82:83]
	v_pk_add_f32 v[72:73], v[72:73], v[80:81]
	global_store_dwordx4 v[88:89], v[76:79], off
	global_store_dwordx4 v[88:89], v[72:75], off offset:16
	global_load_dwordx4 v[72:75], v[98:99], off offset:512
	s_nop 0
	global_load_dwordx4 v[76:79], v[98:99], off offset:528
	v_lshl_add_u64 v[80:81], v[142:143], 0, s[12:13]
	v_lshl_add_u64 v[82:83], s[2:3], 0, v[80:81]
	v_lshl_add_u64 v[82:83], v[82:83], 0, v[140:141]
	s_waitcnt vmcnt(0) lgkmcnt(0)
;     __device__ __forceinline__ void operator()(EPI_ARGS) const {
;         const int row0 = u.pm * BM + wr * 64 + fr, col0 = u.pn * BM + wc * 32 + 8 * fq;
; #pragma unroll
;         for (int ai = 0; ai < 2; ++ai)
; #pragma unroll
;             for (int m = 0; m < 4; ++m) { const int row = row0 + ai * HALF + m * 16;
;                 const float* b = base + (size_t)row * DM + col0; float* o = X + (size_t)row * DM + col0;
; #pragma unroll
;                 for (int bj = 0; bj < 2; ++bj) { const f32x4 b0 = *(const f32x4*)(b + bj * HALF), b1 = *(const f32x4*)(b + bj * HALF + 4);
;                     *(f32x4*)(o + bj * HALF) = b0 + acc[ai][bj][m][0]; *(f32x4*)(o + bj * HALF + 4) = b1 + acc[ai][bj][m][1]; } }
;     }
	v_pk_add_f32 v[70:71], v[70:71], v[74:75]
	v_pk_add_f32 v[68:69], v[68:69], v[72:73]
	v_pk_add_f32 v[66:67], v[66:67], v[78:79]
	v_pk_add_f32 v[64:65], v[64:65], v[76:77]
	global_store_dwordx4 v[88:89], v[68:71], off offset:512
	global_store_dwordx4 v[88:89], v[64:67], off offset:528
	global_load_dwordx4 v[64:67], v[82:83], off
	s_nop 0
	global_load_dwordx4 v[68:71], v[82:83], off offset:16
	v_lshl_add_u64 v[72:73], s[6:7], 0, v[80:81]
	v_lshl_add_u64 v[72:73], v[72:73], 0, v[140:141]
	s_waitcnt vmcnt(0) lgkmcnt(0)
	v_pk_add_f32 v[62:63], v[62:63], v[66:67]
	v_pk_add_f32 v[60:61], v[60:61], v[64:65]
	v_pk_add_f32 v[58:59], v[58:59], v[70:71]
	v_pk_add_f32 v[56:57], v[56:57], v[68:69]
	global_store_dwordx4 v[72:73], v[60:63], off
	global_store_dwordx4 v[72:73], v[56:59], off offset:16
	global_load_dwordx4 v[56:59], v[82:83], off offset:512
	s_nop 0
	global_load_dwordx4 v[60:63], v[82:83], off offset:528
	v_lshl_add_u64 v[64:65], v[142:143], 0, s[14:15]
	v_lshl_add_u64 v[66:67], s[2:3], 0, v[64:65]
	v_lshl_add_u64 v[66:67], v[66:67], 0, v[140:141]
	s_waitcnt vmcnt(0) lgkmcnt(0)
	v_pk_add_f32 v[50:51], v[50:51], v[58:59]
	v_pk_add_f32 v[48:49], v[48:49], v[56:57]
	v_pk_add_f32 v[46:47], v[46:47], v[62:63]
	v_pk_add_f32 v[44:45], v[44:45], v[60:61]
	global_store_dwordx4 v[72:73], v[48:51], off offset:512
	global_store_dwordx4 v[72:73], v[44:47], off offset:528
	global_load_dwordx4 v[44:47], v[66:67], off
	s_nop 0
	global_load_dwordx4 v[48:51], v[66:67], off offset:16
	v_lshl_add_u64 v[56:57], s[6:7], 0, v[64:65]
	v_lshl_add_u64 v[56:57], v[56:57], 0, v[140:141]
	s_waitcnt vmcnt(0) lgkmcnt(0)
	v_pk_add_f32 v[46:47], v[54:55], v[46:47]
	v_pk_add_f32 v[44:45], v[52:53], v[44:45]
	v_pk_add_f32 v[42:43], v[42:43], v[50:51]
	v_pk_add_f32 v[40:41], v[40:41], v[48:49]
	global_store_dwordx4 v[56:57], v[44:47], off
	global_store_dwordx4 v[56:57], v[40:43], off offset:16
	global_load_dwordx4 v[40:43], v[66:67], off offset:512
	s_nop 0
	global_load_dwordx4 v[44:47], v[66:67], off offset:528
	v_lshl_add_u64 v[48:49], v[142:143], 0, s[16:17]
	v_lshl_add_u64 v[50:51], s[2:3], 0, v[48:49]
	v_lshl_add_u64 v[50:51], v[50:51], 0, v[140:141]
	s_waitcnt vmcnt(0) lgkmcnt(0)
	v_pk_add_f32 v[34:35], v[34:35], v[42:43]
	v_pk_add_f32 v[32:33], v[32:33], v[40:41]
	v_pk_add_f32 v[30:31], v[30:31], v[46:47]
	v_pk_add_f32 v[28:29], v[28:29], v[44:45]
	global_store_dwordx4 v[56:57], v[32:35], off offset:512
	global_store_dwordx4 v[56:57], v[28:31], off offset:528
	global_load_dwordx4 v[28:31], v[50:51], off
	s_nop 0
	global_load_dwordx4 v[32:35], v[50:51], off offset:16
	v_lshl_add_u64 v[40:41], s[6:7], 0, v[48:49]
	v_lshl_add_u64 v[40:41], v[40:41], 0, v[140:141]
	s_waitcnt vmcnt(0) lgkmcnt(0)
	v_pk_add_f32 v[30:31], v[38:39], v[30:31]
	v_pk_add_f32 v[28:29], v[36:37], v[28:29]
	v_pk_add_f32 v[26:27], v[26:27], v[34:35]
	v_pk_add_f32 v[24:25], v[24:25], v[32:33]
	global_store_dwordx4 v[40:41], v[28:31], off
	global_store_dwordx4 v[40:41], v[24:27], off offset:16
	global_load_dwordx4 v[24:27], v[50:51], off offset:512
	s_nop 0
	global_load_dwordx4 v[28:31], v[50:51], off offset:528
	v_lshl_add_u64 v[32:33], v[142:143], 0, s[18:19]
	v_lshl_add_u64 v[34:35], s[2:3], 0, v[32:33]
	v_lshl_add_u64 v[34:35], v[34:35], 0, v[140:141]
	s_waitcnt vmcnt(0) lgkmcnt(0)
	v_pk_add_f32 v[18:19], v[18:19], v[26:27]
	v_pk_add_f32 v[16:17], v[16:17], v[24:25]
	v_pk_add_f32 v[14:15], v[14:15], v[30:31]
	v_pk_add_f32 v[12:13], v[12:13], v[28:29]
	global_store_dwordx4 v[40:41], v[16:19], off offset:512
	global_store_dwordx4 v[40:41], v[12:15], off offset:528
	global_load_dwordx4 v[12:15], v[34:35], off
	s_nop 0
	global_load_dwordx4 v[16:19], v[34:35], off offset:16
	v_lshl_add_u64 v[24:25], s[6:7], 0, v[32:33]
	v_lshl_add_u64 v[24:25], v[24:25], 0, v[140:141]
	s_waitcnt vmcnt(0) lgkmcnt(0)
	v_pk_add_f32 v[14:15], v[22:23], v[14:15]
	v_pk_add_f32 v[12:13], v[20:21], v[12:13]
	v_pk_add_f32 v[10:11], v[10:11], v[18:19]
	v_pk_add_f32 v[8:9], v[8:9], v[16:17]
	global_store_dwordx4 v[24:25], v[12:15], off
	global_store_dwordx4 v[24:25], v[8:11], off offset:16
	global_load_dwordx4 v[8:11], v[34:35], off offset:512
	s_nop 0
	global_load_dwordx4 v[12:15], v[34:35], off offset:528
	s_waitcnt vmcnt(0) lgkmcnt(0)
	v_pk_add_f32 v[6:7], v[6:7], v[10:11]
	v_pk_add_f32 v[4:5], v[4:5], v[8:9]
	v_pk_add_f32 v[2:3], v[2:3], v[14:15]
	v_pk_add_f32 v[0:1], v[0:1], v[12:13]
	global_store_dwordx4 v[24:25], v[4:7], off offset:512
	global_store_dwordx4 v[24:25], v[0:3], off offset:528
	s_cbranch_vccnz .LBB0_1050
	s_andn2_b64 vcc, exec, s[4:5]
	s_cbranch_vccnz .LBB0_1049
	s_barrier
	s_branch .LBB0_1049

; #define QNEXT(ctrw, dst) do { __syncthreads(); if (my_tid(lds) == 0) *(volatile LAS int*)(lds + TAB_OFF + 264) = (int)atomicAdd((unsigned*)tab_get(lds, 31) + 8192 + 64 * (ctrw), 1u); \
;         __syncthreads(); dst = __builtin_amdgcn_readfirstlane(*(volatile LAS int*)(lds + TAB_OFF + 264)); } while (0)
; __global__ void __launch_bounds__(512, 2) mega_fwd(Params p) {
;     ...
;           for (;;) { int it; QNEXT(1, it); if (it >= MP / 64) break;
.LBB0_1063:
	s_barrier
	s_getreg_b32 s1, hwreg(HW_REG_HW_ID, 0, 6)
	s_lshl_b32 s1, s1, 2
	s_and_b32 s1, s1, 0xfc
	s_add_i32 s1, s1, 0
	s_add_i32 s1, s1, 0x25a00
	v_mov_b32_e32 v0, s1
	ds_read_b32 v0, v0
	v_mbcnt_lo_u32_b32 v1, -1, 0
	v_mbcnt_hi_u32_b32 v1, -1, v1
	s_waitcnt lgkmcnt(0)
	v_readfirstlane_b32 s1, v0
	s_lshl_b32 s1, s1, 6
	v_sub_u32_e32 v0, 0, v1
	v_cmp_eq_u32_e32 vcc, s1, v0
	s_and_saveexec_b64 s[2:3], vcc
	s_cbranch_execz .LBB0_1065
	ds_read_b64 v[0:1], v19
	s_waitcnt lgkmcnt(0)
	v_readfirstlane_b32 s5, v0
	v_readfirstlane_b32 s1, v1
	s_nop 0
	v_mov_b32_e32 v0, s5
	v_add_co_u32_e32 v0, vcc, 0x8000, v0
	v_mov_b32_e32 v1, s1
	s_nop 0
	v_addc_co_u32_e32 v1, vcc, 0, v1, vcc
	global_atomic_add v0, v[0:1], v24, off offset:256 sc0
	s_waitcnt vmcnt(0) lgkmcnt(0)
	ds_write_b32 v25, v0

; __device__ __forceinline__ float wave_sum(float v) { v += swz_xor<1>(v); v += swz_xor<2>(v); v += swz_xor<4>(v); v += swz_xor<8>(v); v += swz_xor<16>(v); return half_sum(v); }
; __device__ __forceinline__ void rms_row2_to_bf16(const float* x0, const float* x1, const float* g, bf16* o0, bf16* o1, int lane) {
;     const f32x4* xr0 = (const f32x4*)x0 + lane; const f32x4* xr1 = (const f32x4*)x1 + lane; f32x4 v[4], w[4]; float s = 0.f, t = 0.f;
; #pragma unroll
;     for (int j = 0; j < 4; ++j) { v[j] = xr0[64 * j]; w[j] = xr1[64 * j]; }
; #pragma unroll
;     for (int j = 0; j < 4; ++j) { s += (v[j].x * v[j].x + v[j].y * v[j].y) + (v[j].z * v[j].z + v[j].w * v[j].w); t += (w[j].x * w[j].x + w[j].y * w[j].y) + (w[j].z * w[j].z + w[j].w * w[j].w); }
;     const float r0 = rsqrtf(wave_sum(s) * (1.f / DM) + EPS), r1 = rsqrtf(wave_sum(t) * (1.f / DM) + EPS);
.LBB0_1067:
	global_load_dwordx4 v[26:29], v[22:23], off
	global_load_dwordx4 v[8:11], v[22:23], off offset:1024
	global_load_dwordx4 v[0:3], v[22:23], off offset:3072
	global_load_dwordx4 v[4:7], v[22:23], off offset:2048
	v_add_co_u32_e32 v50, vcc, 0x1000, v22
	global_load_dwordx4 v[30:33], v[12:13], off
	s_nop 0
	v_addc_co_u32_e32 v51, vcc, 0, v23, vcc
	global_load_dwordx4 v[34:37], v[50:51], off
	global_load_dwordx4 v[38:41], v[50:51], off offset:1024
	global_load_dwordx4 v[42:45], v[50:51], off offset:3072
	global_load_dwordx4 v[46:49], v[50:51], off offset:2048
	s_add_i32 s1, s1, 2
	v_lshl_add_u64 v[22:23], v[22:23], 0, s[8:9]
	s_cmp_gt_u32 s1, 5
	s_waitcnt vmcnt(0) lgkmcnt(0)
	v_pk_mul_f32 v[50:51], v[28:29], v[28:29]
	v_pk_mul_f32 v[52:53], v[26:27], v[26:27]
	v_pk_mul_f32 v[54:55], v[10:11], v[10:11]
	v_pk_mul_f32 v[56:57], v[8:9], v[8:9]
	v_mul_f32_e32 v58, v5, v5
	v_mul_f32_e32 v60, v7, v7
	v_pk_mov_b32 v[62:63], v[52:53], v[50:51] op_sel:[1,0]
	v_mov_b32_e32 v53, v51
	v_pk_mov_b32 v[50:51], v[56:57], v[54:55] op_sel:[1,0]
	v_mov_b32_e32 v57, v55
	v_pk_fma_f32 v[54:55], v[4:5], v[4:5], v[58:59] op_sel_hi:[1,1,0]
	v_pk_fma_f32 v[58:59], v[6:7], v[6:7], v[60:61] op_sel_hi:[1,1,0]
	v_pk_add_f32 v[52:53], v[62:63], v[52:53]
	v_pk_mul_f32 v[60:61], v[36:37], v[36:37]
	v_pk_mul_f32 v[62:63], v[34:35], v[34:35]
	v_pk_add_f32 v[50:51], v[50:51], v[56:57]
	v_pk_mul_f32 v[56:57], v[40:41], v[40:41]
	v_pk_mul_f32 v[64:65], v[38:39], v[38:39]
	v_mul_f32_e32 v67, v0, v0
	v_mul_f32_e32 v69, v1, v1
	v_mul_f32_e32 v66, v2, v2
	v_mul_f32_e32 v68, v3, v3
	v_pk_mov_b32 v[70:71], v[62:63], v[60:61] op_sel:[1,0]
	v_mov_b32_e32 v63, v61
	v_pk_mov_b32 v[60:61], v[64:65], v[56:57] op_sel:[1,0]
	v_mov_b32_e32 v65, v57
	v_pk_add_f32 v[52:53], v[52:53], v[52:53] op_sel:[0,1] op_sel_hi:[1,0]
	v_pk_add_f32 v[50:51], v[50:51], v[50:51] op_sel:[0,1] op_sel_hi:[1,0]
	v_mov_b32_e32 v55, v66
	v_mov_b32_e32 v59, v68
	v_mul_f32_e32 v66, v47, v47
	v_mul_f32_e32 v68, v49, v49
	v_pk_add_f32 v[62:63], v[70:71], v[62:63]
	v_pk_add_f32 v[60:61], v[60:61], v[64:65]
	v_mov_b32_e32 v53, v67
	v_mov_b32_e32 v51, v69
	v_mul_f32_e32 v72, v42, v42
	v_mul_f32_e32 v73, v43, v43
	v_mul_f32_e32 v74, v44, v44
	v_mul_f32_e32 v75, v45, v45
	v_pk_add_f32 v[54:55], v[54:55], v[58:59]
	v_pk_fma_f32 v[56:57], v[46:47], v[46:47], v[66:67] op_sel_hi:[1,1,0]
	v_pk_fma_f32 v[58:59], v[48:49], v[48:49], v[68:69] op_sel_hi:[1,1,0]
	v_pk_add_f32 v[50:51], v[52:53], v[50:51]
	v_pk_add_f32 v[52:53], v[62:63], v[62:63] op_sel:[0,1] op_sel_hi:[1,0]
	v_pk_add_f32 v[60:61], v[60:61], v[60:61] op_sel:[0,1] op_sel_hi:[1,0]
	v_mov_b32_e32 v57, v74
	v_mov_b32_e32 v59, v75
	v_pk_add_f32 v[50:51], v[50:51], v[54:55]
	v_mov_b32_e32 v53, v72
	v_mov_b32_e32 v61, v73
	v_pk_add_f32 v[56:57], v[56:57], v[58:59]
	v_add_f32_e32 v54, v50, v51
	v_pk_add_f32 v[50:51], v[52:53], v[60:61]
	ds_swizzle_b32 v52, v54 offset:swizzle(SWAP,1)
	v_pk_add_f32 v[50:51], v[50:51], v[56:57]
	s_waitcnt lgkmcnt(0)
	v_add_f32_e32 v52, v54, v52
	v_add_f32_e32 v50, v50, v51
	ds_swizzle_b32 v51, v50 offset:swizzle(SWAP,1)
	ds_swizzle_b32 v53, v52 offset:swizzle(SWAP,2)
	s_waitcnt lgkmcnt(1)
	v_add_f32_e32 v50, v50, v51
	ds_swizzle_b32 v51, v50 offset:swizzle(SWAP,2)
	s_waitcnt lgkmcnt(1)
	v_add_f32_e32 v52, v52, v53
	ds_swizzle_b32 v53, v52 offset:swizzle(SWAP,4)
	s_waitcnt lgkmcnt(1)
	v_add_f32_e32 v50, v50, v51
	ds_swizzle_b32 v51, v50 offset:swizzle(SWAP,4)
	s_waitcnt lgkmcnt(1)
	v_add_f32_e32 v52, v52, v53
	ds_swizzle_b32 v53, v52 offset:swizzle(SWAP,8)
	s_waitcnt lgkmcnt(1)
	v_add_f32_e32 v50, v50, v51
	ds_swizzle_b32 v51, v50 offset:swizzle(SWAP,8)
	s_waitcnt lgkmcnt(1)
	v_add_f32_e32 v52, v52, v53
	ds_swizzle_b32 v53, v52 offset:swizzle(SWAP,16)
	s_waitcnt lgkmcnt(1)
; __device__ __forceinline__ unsigned pk2(float lo, float hi) { const f32x2 v = {lo, hi}; return __builtin_bit_cast(unsigned, __builtin_convertvector(v, bf16x2_t)); }
; __device__ __forceinline__ float wave_sum(float v) { v += swz_xor<1>(v); v += swz_xor<2>(v); v += swz_xor<4>(v); v += swz_xor<8>(v); v += swz_xor<16>(v); return half_sum(v); }
; __device__ __forceinline__ void rms_row2_to_bf16(const float* x0, const float* x1, const float* g, bf16* o0, bf16* o1, int lane) {
;     ...
;     const float r0 = rsqrtf(wave_sum(s) * (1.f / DM) + EPS), r1 = rsqrtf(wave_sum(t) * (1.f / DM) + EPS);
;     u32x2* p0 = (u32x2*)o0 + lane; u32x2* p1 = (u32x2*)o1 + lane;
; #pragma unroll
;     for (int j = 0; j < 4; ++j) { const f32x4 gg = ((const f32x4*)g)[lane + 64 * j]; u32x2 a, b;
;         a.x = pk2(v[j].x * r0 * gg.x, v[j].y * r0 * gg.y); a.y = pk2(v[j].z * r0 * gg.z, v[j].w * r0 * gg.w); b.x = pk2(w[j].x * r1 * gg.x, w[j].y * r1 * gg.y); b.y = pk2(w[j].z * r1 * gg.z, w[j].w * r1 * gg.w);
;         p0[64 * j] = a; p1[64 * j] = b; }
; }
	v_add_f32_e32 v50, v50, v51
	ds_swizzle_b32 v54, v50 offset:swizzle(SWAP,16)
	s_waitcnt lgkmcnt(1)
	v_add_f32_e32 v51, v52, v53
	v_mov_b32_e32 v53, v51
	s_nop 1
	v_permlane32_swap_b32_e32 v51, v53
	s_waitcnt lgkmcnt(0)
	v_add_f32_e32 v50, v50, v54
	v_mov_b32_e32 v52, v50
	s_nop 1
	v_permlane32_swap_b32_e32 v50, v52
	v_pk_add_f32 v[50:51], v[50:51], v[52:53]
	s_nop 0
	v_pk_fma_f32 v[50:51], v[50:51], s[4:5], v[18:19] op_sel_hi:[1,0,0]
	s_nop 0
	v_mul_f32_e32 v52, 0x4b800000, v51
	v_cmp_gt_f32_e64 s[2:3], s0, v51
	v_mul_f32_e32 v53, 0x4b800000, v50
	v_cmp_gt_f32_e32 vcc, s0, v50
	v_cndmask_b32_e64 v51, v51, v52, s[2:3]
	v_rsq_f32_e32 v51, v51
	v_cndmask_b32_e32 v50, v50, v53, vcc
	v_rsq_f32_e32 v52, v50
	v_mul_f32_e32 v50, 0x45800000, v51
	v_cndmask_b32_e64 v50, v51, v50, s[2:3]
	v_mul_f32_e32 v53, 0x45800000, v52
	v_cndmask_b32_e32 v52, v52, v53, vcc
	v_pk_mul_f32 v[26:27], v[26:27], v[50:51] op_sel_hi:[1,0]
	v_pk_mul_f32 v[28:29], v[28:29], v[50:51] op_sel_hi:[1,0]
	v_pk_mul_f32 v[34:35], v[34:35], v[52:53] op_sel_hi:[1,0]
	v_pk_mul_f32 v[36:37], v[36:37], v[52:53] op_sel_hi:[1,0]
	v_pk_mul_f32 v[26:27], v[30:31], v[26:27]
	v_pk_mul_f32 v[28:29], v[32:33], v[28:29]
	v_pk_mul_f32 v[30:31], v[30:31], v[34:35]
	v_pk_mul_f32 v[32:33], v[32:33], v[36:37]
	v_cvt_pk_bf16_f32 v26, v26, v27
	v_cvt_pk_bf16_f32 v27, v28, v29
	v_cvt_pk_bf16_f32 v28, v30, v31
	v_cvt_pk_bf16_f32 v29, v32, v33
	global_store_dwordx2 v[20:21], v[26:27], off
	global_store_dwordx2 v[20:21], v[28:29], off offset:2048
	global_load_dwordx4 v[26:29], v[12:13], off offset:1024
	v_pk_mul_f32 v[8:9], v[8:9], v[50:51] op_sel_hi:[1,0]
	v_pk_mul_f32 v[10:11], v[10:11], v[50:51] op_sel_hi:[1,0]
	v_pk_mul_f32 v[30:31], v[38:39], v[52:53] op_sel_hi:[1,0]
	v_pk_mul_f32 v[32:33], v[40:41], v[52:53] op_sel_hi:[1,0]
	v_pk_mul_f32 v[4:5], v[4:5], v[50:51] op_sel_hi:[1,0]
	v_pk_mul_f32 v[6:7], v[6:7], v[50:51] op_sel_hi:[1,0]
	v_pk_mul_f32 v[0:1], v[0:1], v[50:51] op_sel_hi:[1,0]
	v_pk_mul_f32 v[2:3], v[2:3], v[50:51] op_sel_hi:[1,0]
	s_waitcnt vmcnt(0) lgkmcnt(0)
	v_pk_mul_f32 v[8:9], v[8:9], v[26:27]
	v_pk_mul_f32 v[10:11], v[10:11], v[28:29]
	v_pk_mul_f32 v[26:27], v[26:27], v[30:31]
	v_pk_mul_f32 v[28:29], v[28:29], v[32:33]
	v_cvt_pk_bf16_f32 v8, v8, v9
	v_cvt_pk_bf16_f32 v9, v10, v11
	v_cvt_pk_bf16_f32 v10, v26, v27
	v_cvt_pk_bf16_f32 v11, v28, v29
	global_store_dwordx2 v[20:21], v[8:9], off offset:512
	global_store_dwordx2 v[20:21], v[10:11], off offset:2560
	global_load_dwordx4 v[8:11], v[12:13], off offset:2048
	v_pk_mul_f32 v[26:27], v[46:47], v[52:53] op_sel_hi:[1,0]
	v_pk_mul_f32 v[28:29], v[48:49], v[52:53] op_sel_hi:[1,0]
	s_waitcnt vmcnt(0) lgkmcnt(0)
	v_pk_mul_f32 v[4:5], v[4:5], v[8:9]
	v_pk_mul_f32 v[6:7], v[6:7], v[10:11]
	v_pk_mul_f32 v[8:9], v[8:9], v[26:27]
	v_pk_mul_f32 v[10:11], v[10:11], v[28:29]
	v_cvt_pk_bf16_f32 v4, v4, v5
	v_cvt_pk_bf16_f32 v5, v6, v7
	v_cvt_pk_bf16_f32 v6, v8, v9
	v_cvt_pk_bf16_f32 v7, v10, v11
	global_store_dwordx2 v[20:21], v[4:5], off offset:1024
	global_store_dwordx2 v[20:21], v[6:7], off offset:3072
	global_load_dwordx4 v[4:7], v[12:13], off offset:3072
	v_pk_mul_f32 v[8:9], v[42:43], v[52:53] op_sel_hi:[1,0]
	v_pk_mul_f32 v[10:11], v[44:45], v[52:53] op_sel_hi:[1,0]
	s_waitcnt vmcnt(0) lgkmcnt(0)
	v_pk_mul_f32 v[0:1], v[0:1], v[4:5]
	v_pk_mul_f32 v[2:3], v[2:3], v[6:7]
	v_pk_mul_f32 v[4:5], v[8:9], v[4:5]
	v_pk_mul_f32 v[6:7], v[10:11], v[6:7]
	v_cvt_pk_bf16_f32 v0, v0, v1
	v_cvt_pk_bf16_f32 v1, v2, v3
	v_cvt_pk_bf16_f32 v2, v4, v5
	v_cvt_pk_bf16_f32 v3, v6, v7
	global_store_dwordx2 v[20:21], v[0:1], off offset:1536
	global_store_dwordx2 v[20:21], v[2:3], off offset:3584
	v_lshl_add_u64 v[20:21], v[20:21], 0, s[6:7]
	s_cbranch_scc0 .LBB0_1067
	s_mov_b64 s[2:3], 0
	s_branch .LBB0_1062

; __device__ __forceinline__ unsigned xb_ld(unsigned* p)              { return __hip_atomic_load(p, __ATOMIC_RELAXED, __HIP_MEMORY_SCOPE_AGENT); }
; __device__ __forceinline__ unsigned xb_add(unsigned* p, unsigned v) { return __hip_atomic_fetch_add(p, v, __ATOMIC_RELAXED, __HIP_MEMORY_SCOPE_AGENT); }
; #define XB_SPIN(cond, bar) do { unsigned _sp = 0; while (cond) { __builtin_amdgcn_s_sleep(1); \
;     if ((++_sp & 255u) == 0u) { if (xb_ld(&(bar)[XB_TMO])) break; if (_sp > XB_SPIN_CAP) { atomicAdd(&(bar)[XB_TMO], 1u); break; } } } } while (0)
; __device__ __forceinline__ void xcd_barrier(const XcdBarrier& b, bool leader) {
;     asm volatile("s_waitcnt vmcnt(0)" ::: "memory");
;     __syncthreads();
;     if (leader) {
;         unsigned* bar = b.bar;
;         __builtin_amdgcn_s_waitcnt(0);
;         unsigned nloc = b.st[0], nx = b.st[1];
;         if (nloc == 0u) { xcd_barrier_complete(bar, b.x, nloc, nx); b.st[0] = nloc; b.st[1] = nx; }
;         const unsigned old = xb_add(&bar[XB_XSUB(b.x)], 1u);
;         const unsigned gen = old / nloc;
;         if (old + 1u == (gen + 1u) * nloc) {
;             __builtin_amdgcn_fence(__ATOMIC_RELEASE, "agent");
;             asm volatile("s_waitcnt vmcnt(0)" ::: "memory");
;             const unsigned og = xb_add(&bar[XB_TOP], 1u);
;             const unsigned tg = og / nx;
;             if (og + 1u == (tg + 1u) * nx) xb_add(&bar[XB_TOPGEN], 1u);
;             else XB_SPIN(xb_ld(&bar[XB_TOPGEN]) == tg, bar);
;             __builtin_amdgcn_fence(__ATOMIC_ACQUIRE, "agent");
;             xb_add(&bar[XB_XGEN(b.x)], 1u);
;             asm volatile("s_waitcnt vmcnt(0)" ::: "memory");
;         } else {
;             XB_SPIN(xb_ld(&bar[XB_XGEN(b.x)]) == gen, bar);
.LBB0_1084:
	s_lshl_b32 s2, s40, 8
	s_add_u32 s2, s1, s2
	s_addc_u32 s3, s0, 0
	v_mov_b32_e32 v1, s2
	v_add_co_u32_e32 v4, vcc, 0x2000, v1
	v_mov_b32_e32 v1, s3
	s_nop 0
	v_addc_co_u32_e32 v5, vcc, 0, v1, vcc
	v_mov_b32_e32 v1, 1
	global_atomic_add v1, v[4:5], v1, off offset:1024 sc0
	v_cvt_f32_u32_e32 v3, v2
	v_sub_u32_e32 v4, 0, v2
	s_add_u32 s25, s2, 0x1000
	s_addc_u32 s24, s3, 0
	v_rcp_iflag_f32_e32 v3, v3
	s_nop 0
	v_mul_f32_e32 v3, 0x4f7ffffe, v3
	v_cvt_u32_f32_e32 v3, v3
	v_mul_lo_u32 v4, v4, v3
	v_mul_hi_u32 v4, v3, v4
	v_add_u32_e32 v3, v3, v4
	s_waitcnt vmcnt(0) lgkmcnt(0)
	v_mul_hi_u32 v3, v1, v3
	v_mul_lo_u32 v5, v3, v2
	v_add_u32_e32 v4, 1, v1
	v_sub_u32_e32 v1, v1, v5
	v_add_u32_e32 v6, 1, v3
	v_cmp_ge_u32_e32 vcc, v1, v2
	v_sub_u32_e32 v5, v1, v2
	s_nop 0
	v_cndmask_b32_e32 v3, v3, v6, vcc
	v_cndmask_b32_e32 v1, v1, v5, vcc
	v_add_u32_e32 v5, 1, v3
	v_cmp_ge_u32_e32 vcc, v1, v2
	s_nop 1
	v_cndmask_b32_e32 v1, v3, v5, vcc
	v_mad_u64_u32 v[2:3], s[2:3], v2, v1, v[2:3]
	v_cmp_ne_u32_e32 vcc, v4, v2
	s_and_saveexec_b64 s[2:3], vcc
	s_xor_b64 s[2:3], exec, s[2:3]
	s_cbranch_execz .LBB0_1097
	v_mov_b32_e32 v0, s25
	v_add_co_u32_e32 v2, vcc, 0x2000, v0
	v_mov_b32_e32 v0, s24
	s_nop 0
	v_addc_co_u32_e32 v3, vcc, 0, v0, vcc
	global_load_dword v0, v[2:3], off offset:1024 sc1
	s_add_u32 s8, s25, 0x2400
	s_addc_u32 s9, s24, 0
	s_waitcnt vmcnt(0) lgkmcnt(0)
	v_cmp_eq_u32_e32 vcc, v0, v1
	s_and_saveexec_b64 s[4:5], vcc
	s_cbranch_execz .LBB0_1096
	s_add_u32 s6, s1, 0x1200
	s_addc_u32 s7, s0, 0
	s_mov_b32 s26, 1
	s_mov_b64 s[10:11], 0
	s_branch .LBB0_1088

; __device__ __forceinline__ unsigned pk2(float lo, float hi) { const f32x2 v = {lo, hi}; return __builtin_bit_cast(unsigned, __builtin_convertvector(v, bf16x2_t)); }
; #define WSB(off) ((bf16*)((unsigned char*)tab_get(lds, 31) + (off)))
;     __device__ __forceinline__ void operator()(EPI_ARGS) const {
;         const int row0 = u.pm * BM + wr * 64 + fr, col0 = u.pn * BM + wc * 32 + 8 * fq;
; #pragma unroll
;         for (int ai = 0; ai < 2; ++ai)
; #pragma unroll
;             for (int m = 0; m < 4; ++m) { bf16* rowp = O + (size_t)(row0 + ai * HALF + m * 16) * ldc + col0;
; #pragma unroll
;                 for (int bj = 0; bj < 2; ++bj) { const f32x4 v0 = acc[ai][bj][m][0], v1 = acc[ai][bj][m][1];
;                     u32x4 w; w.x = pk2(v0[0], v0[1]); w.y = pk2(v0[2], v0[3]); w.z = pk2(v1[0], v1[1]); w.w = pk2(v1[2], v1[3]);
;                     *(u32x4*)(rowp + bj * HALF) = w; } }
;     }
; __global__ void __launch_bounds__(512, 2) mega_fwd(Params p) {
;     ...
;         { pg8::Gemm g{WSB(WS_H), WSB(WS_WCQ), MP, 1024, 1024, 1024, 1024}; pg8::StaticOrder S; S.init(MP, 1024, G, bx); pg8::EpiStoreBf16 E{WSB(WS_QC), 1024}; pg8::gemm_phase(lds, g, S, E); }
.LBB0_1133:
	v_lshl_add_u32 v150, s22, 8, v144
	v_lshl_or_b32 v152, s64, 8, v146
	v_ashrrev_i32_e32 v151, 31, v150
	v_ashrrev_i32_e32 v153, 31, v152
	v_lshlrev_b64 v[154:155], 11, v[150:151]
	v_lshl_add_u64 v[154:155], s[10:11], 0, v[154:155]
	v_lshlrev_b64 v[152:153], 1, v[152:153]
	v_lshl_add_u64 v[154:155], v[154:155], 0, v[152:153]
	v_cvt_pk_bf16_f32 v60, v60, v61
	v_cvt_pk_bf16_f32 v61, v62, v63
	v_cvt_pk_bf16_f32 v62, v56, v57
	v_add_co_u32_e32 v56, vcc, s60, v154
	v_cvt_pk_bf16_f32 v68, v68, v69
	v_cvt_pk_bf16_f32 v69, v70, v71
	v_cvt_pk_bf16_f32 v70, v64, v65
	v_lshl_add_u64 v[64:65], v[154:155], 0, s[6:7]
	v_addc_co_u32_e32 v57, vcc, 0, v155, vcc
	v_cvt_pk_bf16_f32 v44, v44, v45
	v_cvt_pk_bf16_f32 v45, v46, v47
	v_cvt_pk_bf16_f32 v46, v40, v41
	v_cvt_pk_bf16_f32 v47, v42, v43
	v_cvt_pk_bf16_f32 v108, v108, v109
	v_cvt_pk_bf16_f32 v109, v110, v111
	v_cvt_pk_bf16_f32 v110, v104, v105
	v_or_b32_e32 v104, 16, v150
	global_store_dwordx4 v[64:65], v[44:47], off offset:256
	v_ashrrev_i32_e32 v105, 31, v104
	v_cvt_pk_bf16_f32 v92, v92, v93
	v_add_co_u32_e32 v46, vcc, s61, v154
	v_cvt_pk_bf16_f32 v93, v94, v95
	v_cvt_pk_bf16_f32 v94, v88, v89
	v_or_b32_e32 v88, 32, v150
	v_lshl_add_u64 v[44:45], v[154:155], 0, s[16:17]
	v_addc_co_u32_e32 v47, vcc, 0, v155, vcc
	v_cvt_pk_bf16_f32 v28, v28, v29
	v_cvt_pk_bf16_f32 v29, v30, v31
	v_cvt_pk_bf16_f32 v30, v24, v25
	v_cvt_pk_bf16_f32 v31, v26, v27
	v_lshlrev_b64 v[104:105], 11, v[104:105]
	v_ashrrev_i32_e32 v89, 31, v88
	v_cvt_pk_bf16_f32 v76, v76, v77
	v_cvt_pk_bf16_f32 v77, v78, v79
	v_cvt_pk_bf16_f32 v78, v72, v73
	v_or_b32_e32 v72, 48, v150
	global_store_dwordx4 v[44:45], v[28:31], off offset:256
	v_cvt_pk_bf16_f32 v111, v106, v107
	v_lshl_add_u64 v[104:105], s[10:11], 0, v[104:105]
	v_add_co_u32_e32 v30, vcc, s62, v154
	v_lshlrev_b64 v[88:89], 11, v[88:89]
	v_ashrrev_i32_e32 v73, 31, v72
	v_lshl_add_u64 v[28:29], v[154:155], 0, s[18:19]
	v_addc_co_u32_e32 v31, vcc, 0, v155, vcc
	v_cvt_pk_bf16_f32 v12, v12, v13
	v_cvt_pk_bf16_f32 v13, v14, v15
	v_cvt_pk_bf16_f32 v14, v8, v9
	v_cvt_pk_bf16_f32 v15, v10, v11
	global_store_dwordx4 v[154:155], v[108:111], off offset:256
	v_cvt_pk_bf16_f32 v95, v90, v91
	v_lshl_add_u64 v[88:89], s[10:11], 0, v[88:89]
	v_lshl_add_u64 v[108:109], v[104:105], 0, v[152:153]
	v_lshlrev_b64 v[72:73], 11, v[72:73]
	global_store_dwordx4 v[28:29], v[12:15], off offset:256
	global_store_dwordx4 v[108:109], v[92:95], off offset:256
	v_cvt_pk_bf16_f32 v79, v74, v75
	v_add_co_u32_e32 v14, vcc, s63, v154
	v_lshl_add_u64 v[92:93], v[88:89], 0, v[152:153]
	v_lshl_add_u64 v[72:73], s[10:11], 0, v[72:73]
	v_addc_co_u32_e32 v15, vcc, 0, v155, vcc
	v_cvt_pk_bf16_f32 v124, v124, v125
	v_cvt_pk_bf16_f32 v125, v126, v127
	v_cvt_pk_bf16_f32 v126, v120, v121
	v_cvt_pk_bf16_f32 v127, v122, v123
	v_cvt_pk_bf16_f32 v104, v116, v117
	v_cvt_pk_bf16_f32 v105, v118, v119
	v_cvt_pk_bf16_f32 v106, v112, v113
	v_cvt_pk_bf16_f32 v107, v114, v115
	v_cvt_pk_bf16_f32 v88, v100, v101
	v_cvt_pk_bf16_f32 v89, v102, v103
	v_cvt_pk_bf16_f32 v90, v96, v97
	v_cvt_pk_bf16_f32 v91, v98, v99
	global_store_dwordx4 v[92:93], v[76:79], off offset:256
	v_cvt_pk_bf16_f32 v74, v80, v81
	v_cvt_pk_bf16_f32 v75, v82, v83
	v_lshl_add_u64 v[76:77], v[72:73], 0, v[152:153]
	v_cvt_pk_bf16_f32 v72, v84, v85
	v_cvt_pk_bf16_f32 v73, v86, v87
	v_cvt_pk_bf16_f32 v71, v66, v67
	v_cvt_pk_bf16_f32 v63, v58, v59
	v_cvt_pk_bf16_f32 v40, v52, v53
	v_cvt_pk_bf16_f32 v41, v54, v55
	v_cvt_pk_bf16_f32 v42, v48, v49
	v_cvt_pk_bf16_f32 v43, v50, v51
	v_cvt_pk_bf16_f32 v24, v36, v37
	v_cvt_pk_bf16_f32 v25, v38, v39
	v_cvt_pk_bf16_f32 v26, v32, v33
	v_cvt_pk_bf16_f32 v27, v34, v35
	v_lshl_add_u64 v[12:13], v[154:155], 0, s[20:21]
	v_cvt_pk_bf16_f32 v8, v20, v21
	v_cvt_pk_bf16_f32 v9, v22, v23
	v_cvt_pk_bf16_f32 v10, v16, v17
	v_cvt_pk_bf16_f32 v11, v18, v19
	v_cvt_pk_bf16_f32 v4, v4, v5
	v_cvt_pk_bf16_f32 v5, v6, v7
	v_cvt_pk_bf16_f32 v6, v0, v1
	v_cvt_pk_bf16_f32 v7, v2, v3
	s_andn2_b64 vcc, exec, s[4:5]
	s_mov_b64 s[4:5], -1
	global_store_dwordx4 v[154:155], v[124:127], off
	global_store_dwordx4 v[108:109], v[104:107], off
	global_store_dwordx4 v[92:93], v[88:91], off
	global_store_dwordx4 v[76:77], v[72:75], off
	global_store_dwordx4 v[76:77], v[68:71], off offset:256
	global_store_dwordx4 v[56:57], v[60:63], off
	global_store_dwordx4 v[46:47], v[40:43], off
	global_store_dwordx4 v[30:31], v[24:27], off
	global_store_dwordx4 v[14:15], v[8:11], off
	global_store_dwordx4 v[12:13], v[4:7], off offset:256
	s_cbranch_vccnz .LBB0_1122
	s_andn2_b64 vcc, exec, s[8:9]
	s_cbranch_vccnz .LBB0_1121
	s_barrier
	s_branch .LBB0_1121

; __device__ __forceinline__ unsigned pk2(float lo, float hi) { const f32x2 v = {lo, hi}; return __builtin_bit_cast(unsigned, __builtin_convertvector(v, bf16x2_t)); }
; __device__ __forceinline__ float wave_sum(float v) { v += swz_xor<1>(v); v += swz_xor<2>(v); v += swz_xor<4>(v); v += swz_xor<8>(v); v += swz_xor<16>(v); return half_sum(v); }
; #define INP(i) ((const float*)tab_get(lds, (i)))
; #define OUTP() ((float*)tab_get(lds, 30))
; #define WSB(off) ((bf16*)((unsigned char*)tab_get(lds, 31) + (off)))
; #define fresh_lane() (my_tid(lds) & 63)
; __device__ __forceinline__ void rms_row_to_bf16(const float* xrow, const float* g, bf16* orow, int lane) {
;     const f32x4* xr = (const f32x4*)xrow + lane; f32x4 v[4]; float s = 0.f;
; #pragma unroll
;     for (int j = 0; j < 4; ++j) { v[j] = xr[64 * j]; s += (v[j].x * v[j].x + v[j].y * v[j].y) + (v[j].z * v[j].z + v[j].w * v[j].w); }
;     const float rstd = rsqrtf(wave_sum(s) * (1.f / DM) + EPS);
;     u32x2* o8 = (u32x2*)orow + lane;
; #pragma unroll
;     for (int j = 0; j < 4; ++j) { const f32x4 gg = ((const f32x4*)g)[lane + 64 * j]; u32x2 w; w.x = pk2(v[j].x * rstd * gg.x, v[j].y * rstd * gg.y); w.y = pk2(v[j].z * rstd * gg.z, v[j].w * rstd * gg.w); o8[64 * j] = w; }
; }
; __global__ void __launch_bounds__(512, 2) mega_fwd(Params p) {
;     ...
;         { const int lane = fresh_lane(); const float* X = OUTP(); const float* g = INP(18); bf16* H = WSB(WS_H);
;           for (int m = MP + gw; m < MT; m += NGW) rms_row_to_bf16(X + (size_t)m * DM, g, H + (size_t)m * DM, lane); }
.LBB0_1139:
	global_load_dwordx4 v[8:11], v[4:5], off
	global_load_dwordx4 v[12:15], v[4:5], off offset:1024
	global_load_dwordx4 v[16:19], v[4:5], off offset:2048
	global_load_dwordx4 v[20:23], v[4:5], off offset:3072
	global_load_dwordx4 v[24:27], v[0:1], off
	s_add_i32 s1, s1, s44
	v_lshl_add_u64 v[4:5], v[4:5], 0, s[6:7]
	s_cmp_gt_i32 s1, 0x81ff
	s_waitcnt vmcnt(0) lgkmcnt(0)
	v_mul_f32_e32 v7, v9, v9
	v_mul_f32_e32 v28, v11, v11
	v_mul_f32_e32 v29, v13, v13
	v_mul_f32_e32 v30, v15, v15
	v_mul_f32_e32 v31, v17, v17
	v_mul_f32_e32 v32, v19, v19
	v_fmac_f32_e32 v7, v8, v8
	v_fmac_f32_e32 v28, v10, v10
	v_fmac_f32_e32 v29, v12, v12
	v_fmac_f32_e32 v30, v14, v14
	v_mul_f32_e32 v33, v21, v21
	v_mul_f32_e32 v34, v23, v23
	v_fmac_f32_e32 v31, v16, v16
	v_fmac_f32_e32 v32, v18, v18
	v_add_f32_e32 v7, v7, v28
	v_add_f32_e32 v28, v29, v30
	v_fmac_f32_e32 v33, v20, v20
	v_fmac_f32_e32 v34, v22, v22
	v_add_f32_e32 v29, v31, v32
	v_add_f32_e32 v7, v7, v28
	v_add_f32_e32 v30, v33, v34
	v_add_f32_e32 v7, v7, v29
	v_add_f32_e32 v7, v7, v30
	ds_swizzle_b32 v28, v7 offset:swizzle(SWAP,1)
	s_waitcnt lgkmcnt(0)
	v_add_f32_e32 v7, v7, v28
	ds_swizzle_b32 v28, v7 offset:swizzle(SWAP,2)
	s_waitcnt lgkmcnt(0)
	v_add_f32_e32 v7, v7, v28
	ds_swizzle_b32 v28, v7 offset:swizzle(SWAP,4)
	s_waitcnt lgkmcnt(0)
	v_add_f32_e32 v7, v7, v28
	ds_swizzle_b32 v28, v7 offset:swizzle(SWAP,8)
	s_waitcnt lgkmcnt(0)
	v_add_f32_e32 v7, v7, v28
	ds_swizzle_b32 v28, v7 offset:swizzle(SWAP,16)
	s_waitcnt lgkmcnt(0)
	v_add_f32_e32 v7, v7, v28
	v_mov_b32_e32 v28, v7
	s_nop 1
	v_permlane32_swap_b32_e32 v7, v28
	v_add_f32_e32 v7, v7, v28
	v_fmamk_f32 v7, v7, 0x3a800000, v6
	v_mul_f32_e32 v28, 0x4b800000, v7
	v_cmp_gt_f32_e32 vcc, s0, v7
	s_nop 1
	v_cndmask_b32_e32 v7, v7, v28, vcc
	v_rsq_f32_e32 v7, v7
	s_nop 0
	v_mul_f32_e32 v28, 0x45800000, v7
	v_cndmask_b32_e32 v28, v7, v28, vcc
	v_pk_mul_f32 v[8:9], v[8:9], v[28:29] op_sel_hi:[1,0]
	v_pk_mul_f32 v[10:11], v[10:11], v[28:29] op_sel_hi:[1,0]
	v_pk_mul_f32 v[8:9], v[24:25], v[8:9]
	v_pk_mul_f32 v[10:11], v[26:27], v[10:11]
	v_cvt_pk_bf16_f32 v8, v8, v9
	v_cvt_pk_bf16_f32 v9, v10, v11
	global_store_dwordx2 v[2:3], v[8:9], off
	global_load_dwordx4 v[8:11], v[0:1], off offset:1024
	v_pk_mul_f32 v[12:13], v[12:13], v[28:29] op_sel_hi:[1,0]
	v_pk_mul_f32 v[14:15], v[14:15], v[28:29] op_sel_hi:[1,0]
	s_waitcnt vmcnt(0) lgkmcnt(0)
	v_pk_mul_f32 v[8:9], v[8:9], v[12:13]
	v_pk_mul_f32 v[10:11], v[10:11], v[14:15]
	v_cvt_pk_bf16_f32 v8, v8, v9
	v_cvt_pk_bf16_f32 v9, v10, v11
	global_store_dwordx2 v[2:3], v[8:9], off offset:512
	global_load_dwordx4 v[8:11], v[0:1], off offset:2048
	v_pk_mul_f32 v[12:13], v[16:17], v[28:29] op_sel_hi:[1,0]
	v_pk_mul_f32 v[14:15], v[18:19], v[28:29] op_sel_hi:[1,0]
	s_waitcnt vmcnt(0) lgkmcnt(0)
	v_pk_mul_f32 v[8:9], v[8:9], v[12:13]
	v_pk_mul_f32 v[10:11], v[10:11], v[14:15]
	v_cvt_pk_bf16_f32 v8, v8, v9
	v_cvt_pk_bf16_f32 v9, v10, v11
	global_store_dwordx2 v[2:3], v[8:9], off offset:1024
	global_load_dwordx4 v[8:11], v[0:1], off offset:3072
	v_pk_mul_f32 v[12:13], v[20:21], v[28:29] op_sel_hi:[1,0]
	v_pk_mul_f32 v[14:15], v[22:23], v[28:29] op_sel_hi:[1,0]
	s_waitcnt vmcnt(0) lgkmcnt(0)
	v_pk_mul_f32 v[8:9], v[8:9], v[12:13]
	v_pk_mul_f32 v[10:11], v[10:11], v[14:15]
	v_cvt_pk_bf16_f32 v8, v8, v9
	v_cvt_pk_bf16_f32 v9, v10, v11
	global_store_dwordx2 v[2:3], v[8:9], off offset:1536
	v_lshl_add_u64 v[2:3], v[2:3], 0, s[4:5]
	s_cbranch_scc0 .LBB0_1139

; __device__ __forceinline__ unsigned xb_ld(unsigned* p)              { return __hip_atomic_load(p, __ATOMIC_RELAXED, __HIP_MEMORY_SCOPE_AGENT); }
; __device__ __forceinline__ void xcd_barrier_complete(unsigned* bar, unsigned x, unsigned& nloc, unsigned& nx) {
;     const unsigned G = gridDim.x * gridDim.y * gridDim.z;
;     unsigned sum, cnt, mine, sp = 0u;
;     for (;;) {
;         sum = 0u; cnt = 0u; mine = 0u;
; #pragma unroll
;         for (unsigned j = 0; j < 16; ++j) { const unsigned c = xb_ld(&bar[XB_XCNT(j)]); sum += c; cnt += (c > 0u) ? 1u : 0u; mine = (j == x) ? c : mine; }
;         if (sum == G) break;
;         __builtin_amdgcn_s_sleep(1);
;         if ((++sp & 255u) == 0u) { if (xb_ld(&bar[XB_TMO])) break; if (sp > XB_SPIN_CAP) { atomicAdd(&bar[XB_TMO], 1u); break; } }
;     }
;     nloc = mine > 0u ? mine : 1u; nx = cnt > 0u ? cnt : 1u;
; }
.LBB0_1145:
	global_load_dword v47, v[0:1], off sc1
	global_load_dword v32, v[2:3], off sc1
	global_load_dword v33, v[4:5], off sc1
	global_load_dword v34, v[6:7], off sc1
	global_load_dword v35, v[8:9], off sc1
	global_load_dword v36, v[10:11], off sc1
	global_load_dword v37, v[12:13], off sc1
	global_load_dword v38, v[14:15], off sc1
	global_load_dword v39, v[16:17], off sc1
	global_load_dword v40, v[18:19], off sc1
	global_load_dword v41, v[20:21], off sc1
	global_load_dword v42, v[22:23], off sc1
	global_load_dword v43, v[24:25], off sc1
	global_load_dword v44, v[26:27], off sc1
	global_load_dword v45, v[28:29], off sc1
	global_load_dword v46, v[30:31], off sc1
	s_or_b64 s[12:13], s[12:13], exec
	s_or_b64 s[10:11], s[10:11], exec
	s_waitcnt vmcnt(0) lgkmcnt(0)
	v_add_u32_e32 v48, v32, v47
	v_add_u32_e32 v48, v48, v33
	v_add_u32_e32 v48, v48, v34
	v_add_u32_e32 v48, v48, v35
	v_add_u32_e32 v48, v48, v36
	v_add_u32_e32 v48, v48, v37
	v_add_u32_e32 v48, v48, v38
	v_add_u32_e32 v48, v48, v39
	v_add_u32_e32 v48, v48, v40
	v_add_u32_e32 v48, v48, v41
	v_add_u32_e32 v48, v48, v42
	v_add_u32_e32 v48, v48, v43
	v_add_u32_e32 v48, v48, v44
	v_add_u32_e32 v48, v48, v45
	v_add_u32_e32 v48, v48, v46
	v_cmp_ne_u32_e32 vcc, s24, v48
	s_and_saveexec_b64 s[14:15], vcc
	s_cbranch_execz .LBB0_1144
	s_and_b32 s18, s25, 0xff
	s_mov_b64 s[16:17], -1
	s_cmp_eq_u32 s18, 0
	s_mov_b64 s[20:21], -1
	s_mov_b64 s[18:19], -1
	s_sleep 1
	s_cbranch_scc1 .LBB0_1148
	s_and_saveexec_b64 s[22:23], s[20:21]
	s_cbranch_execz .LBB0_1143
	s_branch .LBB0_1151
.LBB0_1148:
	v_mov_b64_e32 v[48:49], s[4:5]
	global_load_dword v48, v[48:49], off sc1
	s_mov_b64 s[20:21], 0
	s_waitcnt vmcnt(0) lgkmcnt(0)
	v_cmp_eq_u32_e32 vcc, 0, v48
	s_and_saveexec_b64 s[22:23], vcc
	s_cmp_lt_u32 s25, 0x400001
	s_cselect_b64 s[20:21], -1, 0
	s_xor_b64 s[18:19], exec, -1
	s_and_b64 s[20:21], s[20:21], exec
	s_or_b64 exec, exec, s[22:23]
	s_and_saveexec_b64 s[22:23], s[20:21]
	s_cbranch_execz .LBB0_1143

; __device__ __forceinline__ unsigned xb_ld(unsigned* p)              { return __hip_atomic_load(p, __ATOMIC_RELAXED, __HIP_MEMORY_SCOPE_AGENT); }
; __device__ __forceinline__ void xcd_barrier_complete(unsigned* bar, unsigned x, unsigned& nloc, unsigned& nx) {
;     const unsigned G = gridDim.x * gridDim.y * gridDim.z;
;     unsigned sum, cnt, mine, sp = 0u;
;     for (;;) {
;         sum = 0u; cnt = 0u; mine = 0u;
; #pragma unroll
;         for (unsigned j = 0; j < 16; ++j) { const unsigned c = xb_ld(&bar[XB_XCNT(j)]); sum += c; cnt += (c > 0u) ? 1u : 0u; mine = (j == x) ? c : mine; }
;         if (sum == G) break;
;         __builtin_amdgcn_s_sleep(1);
;         if ((++sp & 255u) == 0u) { if (xb_ld(&bar[XB_TMO])) break; if (sp > XB_SPIN_CAP) { atomicAdd(&bar[XB_TMO], 1u); break; } }
;     }
;     nloc = mine > 0u ? mine : 1u; nx = cnt > 0u ? cnt : 1u;
; }
.LBB0_1152:
	s_or_b64 exec, exec, s[6:7]
	s_xor_b64 s[6:7], s[8:9], -1
	s_and_saveexec_b64 s[8:9], s[6:7]
	s_xor_b64 s[6:7], exec, s[8:9]
	s_cbranch_execz .LBB0_1154
	v_mov_b32_e32 v2, 1
	v_mov_b64_e32 v[0:1], s[4:5]
	global_atomic_add v[0:1], v2, off

; __device__ __forceinline__ unsigned xb_ld(unsigned* p)              { return __hip_atomic_load(p, __ATOMIC_RELAXED, __HIP_MEMORY_SCOPE_AGENT); }
; __device__ __forceinline__ unsigned xb_add(unsigned* p, unsigned v) { return __hip_atomic_fetch_add(p, v, __ATOMIC_RELAXED, __HIP_MEMORY_SCOPE_AGENT); }
; #define XB_SPIN(cond, bar) do { unsigned _sp = 0; while (cond) { __builtin_amdgcn_s_sleep(1); \
;     if ((++_sp & 255u) == 0u) { if (xb_ld(&(bar)[XB_TMO])) break; if (_sp > XB_SPIN_CAP) { atomicAdd(&(bar)[XB_TMO], 1u); break; } } } } while (0)
; __device__ __forceinline__ void xcd_barrier(const XcdBarrier& b, bool leader) {
;     asm volatile("s_waitcnt vmcnt(0)" ::: "memory");
;     __syncthreads();
;     if (leader) {
;         unsigned* bar = b.bar;
;         __builtin_amdgcn_s_waitcnt(0);
;         unsigned nloc = b.st[0], nx = b.st[1];
;         if (nloc == 0u) { xcd_barrier_complete(bar, b.x, nloc, nx); b.st[0] = nloc; b.st[1] = nx; }
;         const unsigned old = xb_add(&bar[XB_XSUB(b.x)], 1u);
;         const unsigned gen = old / nloc;
;         if (old + 1u == (gen + 1u) * nloc) {
;             __builtin_amdgcn_fence(__ATOMIC_RELEASE, "agent");
;             asm volatile("s_waitcnt vmcnt(0)" ::: "memory");
;             const unsigned og = xb_add(&bar[XB_TOP], 1u);
;             const unsigned tg = og / nx;
;             if (og + 1u == (tg + 1u) * nx) xb_add(&bar[XB_TOPGEN], 1u);
;             else XB_SPIN(xb_ld(&bar[XB_TOPGEN]) == tg, bar);
;             __builtin_amdgcn_fence(__ATOMIC_ACQUIRE, "agent");
;             xb_add(&bar[XB_XGEN(b.x)], 1u);
;             asm volatile("s_waitcnt vmcnt(0)" ::: "memory");
;         } else {
;             XB_SPIN(xb_ld(&bar[XB_XGEN(b.x)]) == gen, bar);
.LBB0_1155:
	s_lshl_b32 s4, s37, 8
	s_add_u32 s4, s1, s4
	s_addc_u32 s5, s0, 0
	v_mov_b32_e32 v1, s4
	v_add_co_u32_e32 v4, vcc, 0x2000, v1
	v_mov_b32_e32 v1, s5
	s_nop 0
	v_addc_co_u32_e32 v5, vcc, 0, v1, vcc
	v_mov_b32_e32 v1, 1
	global_atomic_add v1, v[4:5], v1, off offset:1024 sc0
	v_cvt_f32_u32_e32 v3, v2
	v_sub_u32_e32 v4, 0, v2
	s_add_u32 s27, s4, 0x1000
	s_addc_u32 s26, s5, 0
	v_rcp_iflag_f32_e32 v3, v3
	s_nop 0
	v_mul_f32_e32 v3, 0x4f7ffffe, v3
	v_cvt_u32_f32_e32 v3, v3
	v_mul_lo_u32 v4, v4, v3
	v_mul_hi_u32 v4, v3, v4
	v_add_u32_e32 v3, v3, v4
	s_waitcnt vmcnt(0) lgkmcnt(0)
	v_mul_hi_u32 v3, v1, v3
	v_mul_lo_u32 v5, v3, v2
	v_add_u32_e32 v4, 1, v1
	v_sub_u32_e32 v1, v1, v5
	v_add_u32_e32 v6, 1, v3
	v_cmp_ge_u32_e32 vcc, v1, v2
	v_sub_u32_e32 v5, v1, v2
	s_nop 0
	v_cndmask_b32_e32 v3, v3, v6, vcc
	v_cndmask_b32_e32 v1, v1, v5, vcc
	v_add_u32_e32 v5, 1, v3
	v_cmp_ge_u32_e32 vcc, v1, v2
	s_nop 1
	v_cndmask_b32_e32 v1, v3, v5, vcc
	v_mad_u64_u32 v[2:3], s[4:5], v2, v1, v[2:3]
	v_cmp_ne_u32_e32 vcc, v4, v2
	s_and_saveexec_b64 s[4:5], vcc
	s_xor_b64 s[4:5], exec, s[4:5]
	s_cbranch_execz .LBB0_1168
	v_mov_b32_e32 v0, s27
	v_add_co_u32_e32 v2, vcc, 0x2000, v0
	v_mov_b32_e32 v0, s26
	s_nop 0
	v_addc_co_u32_e32 v3, vcc, 0, v0, vcc
	global_load_dword v0, v[2:3], off offset:1024 sc1
	s_add_u32 s10, s27, 0x2400
	s_addc_u32 s11, s26, 0
	s_waitcnt vmcnt(0) lgkmcnt(0)
	v_cmp_eq_u32_e32 vcc, v0, v1
	s_and_saveexec_b64 s[6:7], vcc
	s_cbranch_execz .LBB0_1167
	s_add_u32 s8, s1, 0x1200
	s_addc_u32 s9, s0, 0
	s_mov_b32 s28, 1
	s_mov_b64 s[12:13], 0
	s_branch .LBB0_1159

; __device__ __forceinline__ unsigned xb_ld(unsigned* p)              { return __hip_atomic_load(p, __ATOMIC_RELAXED, __HIP_MEMORY_SCOPE_AGENT); }
; #define XB_SPIN(cond, bar) do { unsigned _sp = 0; while (cond) { __builtin_amdgcn_s_sleep(1); \
;     if ((++_sp & 255u) == 0u) { if (xb_ld(&(bar)[XB_TMO])) break; if (_sp > XB_SPIN_CAP) { atomicAdd(&(bar)[XB_TMO], 1u); break; } } } } while (0)
; __device__ __forceinline__ void xcd_barrier(const XcdBarrier& b, bool leader) {
;     ...
;             XB_SPIN(xb_ld(&bar[XB_XGEN(b.x)]) == gen, bar);
.LBB0_1159:
	s_and_b32 s20, s28, 0xff
	s_mov_b64 s[18:19], -1
	s_cmp_lg_u32 s20, 0
	s_mov_b64 s[20:21], -1
	s_sleep 1
	s_cbranch_scc1 .LBB0_1163
	v_mov_b64_e32 v[2:3], s[8:9]
	global_load_dword v0, v[2:3], off sc1
	s_mov_b64 s[20:21], 0
	s_mov_b64 s[22:23], -1
	s_waitcnt vmcnt(0) lgkmcnt(0)
	v_cmp_eq_u32_e32 vcc, 0, v0
	s_and_saveexec_b64 s[24:25], vcc
	s_cmp_lt_u32 s28, 0x400001
	s_cselect_b64 s[20:21], -1, 0
	s_xor_b64 s[22:23], exec, -1
	s_and_b64 s[20:21], s[20:21], exec
	s_or_b64 exec, exec, s[24:25]
.LBB0_1163:
	s_andn2_b64 s[16:17], s[16:17], exec
	s_and_b64 s[22:23], s[22:23], exec
	s_or_b64 s[16:17], s[16:17], s[22:23]
	s_and_saveexec_b64 s[22:23], s[20:21]
	s_cbranch_execz .LBB0_1158
	v_mov_b64_e32 v[2:3], s[10:11]
	global_load_dword v0, v[2:3], off sc1
	s_add_i32 s28, s28, 1
	s_or_b64 s[16:17], s[16:17], exec
	s_waitcnt vmcnt(0) lgkmcnt(0)
	v_cmp_ne_u32_e32 vcc, v0, v1
	s_orn2_b64 s[18:19], vcc, exec
	s_branch .LBB0_1158
.LBB0_1165:
	s_or_b64 exec, exec, s[12:13]
	s_xor_b64 s[10:11], s[14:15], -1
	s_and_saveexec_b64 s[12:13], s[10:11]
	s_xor_b64 s[12:13], exec, s[12:13]
	s_cbranch_execz .LBB0_1167
	v_mov_b32_e32 v2, 1
	v_mov_b64_e32 v[0:1], s[8:9]
	global_atomic_add v[0:1], v2, off

; __device__ __forceinline__ unsigned xb_ld(unsigned* p)              { return __hip_atomic_load(p, __ATOMIC_RELAXED, __HIP_MEMORY_SCOPE_AGENT); }
; __device__ __forceinline__ unsigned xb_add(unsigned* p, unsigned v) { return __hip_atomic_fetch_add(p, v, __ATOMIC_RELAXED, __HIP_MEMORY_SCOPE_AGENT); }
; #define XB_SPIN(cond, bar) do { unsigned _sp = 0; while (cond) { __builtin_amdgcn_s_sleep(1); \
;     if ((++_sp & 255u) == 0u) { if (xb_ld(&(bar)[XB_TMO])) break; if (_sp > XB_SPIN_CAP) { atomicAdd(&(bar)[XB_TMO], 1u); break; } } } } while (0)
; __device__ __forceinline__ void xcd_barrier(const XcdBarrier& b, bool leader) {
;     ...
;         if (old + 1u == (gen + 1u) * nloc) {
;             __builtin_amdgcn_fence(__ATOMIC_RELEASE, "agent");
;             asm volatile("s_waitcnt vmcnt(0)" ::: "memory");
;             const unsigned og = xb_add(&bar[XB_TOP], 1u);
;             const unsigned tg = og / nx;
;             if (og + 1u == (tg + 1u) * nx) xb_add(&bar[XB_TOPGEN], 1u);
;             else XB_SPIN(xb_ld(&bar[XB_TOPGEN]) == tg, bar);
.LBB0_1168:
	s_andn2_saveexec_b64 s[4:5], s[4:5]
	s_cbranch_execz .LBB0_1184
	v_mov_b32_e32 v1, s1
	v_add_co_u32_e32 v2, vcc, 0x4000, v1
	v_mov_b32_e32 v1, s0
	buffer_wbl2 sc1
	s_waitcnt vmcnt(0)
	v_addc_co_u32_e32 v3, vcc, 0, v1, vcc
	v_mov_b32_e32 v1, 1
	global_atomic_add v1, v[2:3], v1, off offset:1024 sc0
	v_cvt_f32_u32_e32 v2, v0
	v_sub_u32_e32 v3, 0, v0
	s_add_u32 s4, s1, 0x4500
	s_addc_u32 s5, s0, 0
	v_rcp_iflag_f32_e32 v2, v2
	s_mov_b64 s[8:9], -1
	v_mul_f32_e32 v2, 0x4f7ffffe, v2
	v_cvt_u32_f32_e32 v2, v2
	v_mul_lo_u32 v3, v3, v2
	v_mul_hi_u32 v3, v2, v3
	v_add_u32_e32 v2, v2, v3
	s_waitcnt vmcnt(0) lgkmcnt(0)
	v_mul_hi_u32 v2, v1, v2
	v_mul_lo_u32 v4, v2, v0
	v_add_u32_e32 v3, 1, v1
	v_sub_u32_e32 v1, v1, v4
	v_add_u32_e32 v5, 1, v2
	v_cmp_ge_u32_e32 vcc, v1, v0
	v_sub_u32_e32 v4, v1, v0
	s_nop 0
	v_cndmask_b32_e32 v2, v2, v5, vcc
	v_cndmask_b32_e32 v1, v1, v4, vcc
	v_add_u32_e32 v4, 1, v2
	v_cmp_ge_u32_e32 vcc, v1, v0
	s_nop 1
	v_cndmask_b32_e32 v2, v2, v4, vcc
	v_mad_u64_u32 v[0:1], s[6:7], v0, v2, v[0:1]
	v_cmp_ne_u32_e32 vcc, v3, v0
	v_mov_b64_e32 v[0:1], s[4:5]
	s_and_saveexec_b64 s[6:7], vcc
	s_cbranch_execz .LBB0_1181
	v_mov_b64_e32 v[0:1], s[4:5]
	global_load_dword v0, v[0:1], off sc1
	s_mov_b64 s[12:13], 0
	s_waitcnt vmcnt(0) lgkmcnt(0)
	v_cmp_eq_u32_e32 vcc, v0, v2
	s_and_saveexec_b64 s[10:11], vcc
	s_cbranch_execz .LBB0_1180
	s_add_u32 s8, s1, 0x1200
	s_addc_u32 s9, s0, 0
	s_mov_b32 s0, 1
	s_branch .LBB0_1173

; __device__ __forceinline__ unsigned xb_ld(unsigned* p)              { return __hip_atomic_load(p, __ATOMIC_RELAXED, __HIP_MEMORY_SCOPE_AGENT); }
; #define XB_SPIN(cond, bar) do { unsigned _sp = 0; while (cond) { __builtin_amdgcn_s_sleep(1); \
;     if ((++_sp & 255u) == 0u) { if (xb_ld(&(bar)[XB_TMO])) break; if (_sp > XB_SPIN_CAP) { atomicAdd(&(bar)[XB_TMO], 1u); break; } } } } while (0)
; __device__ __forceinline__ void xcd_barrier(const XcdBarrier& b, bool leader) {
;     ...
;             else XB_SPIN(xb_ld(&bar[XB_TOPGEN]) == tg, bar);
.LBB0_1175:
	v_mov_b64_e32 v[0:1], s[8:9]
	global_load_dword v0, v[0:1], off sc1
	s_mov_b64 s[18:19], 0
	s_mov_b64 s[16:17], -1
	s_waitcnt vmcnt(0) lgkmcnt(0)
	v_cmp_eq_u32_e32 vcc, 0, v0
	s_and_saveexec_b64 s[20:21], vcc
	s_cmp_lt_u32 s0, 0x400001
	s_cselect_b64 s[18:19], -1, 0
	s_xor_b64 s[16:17], exec, -1
	s_and_b64 s[18:19], s[18:19], exec
	s_or_b64 exec, exec, s[20:21]
	s_mov_b64 s[20:21], -1
	s_and_saveexec_b64 s[22:23], s[18:19]
	s_cbranch_execz .LBB0_1172
.LBB0_1178:
	v_mov_b64_e32 v[0:1], s[4:5]
	global_load_dword v0, v[0:1], off sc1
	s_add_i32 s0, s0, 1
	s_or_b64 s[16:17], s[16:17], exec
	s_waitcnt vmcnt(0) lgkmcnt(0)
	v_cmp_ne_u32_e32 vcc, v0, v2
	s_orn2_b64 s[20:21], vcc, exec
	s_branch .LBB0_1172

; __device__ __forceinline__ unsigned xb_ld(unsigned* p)              { return __hip_atomic_load(p, __ATOMIC_RELAXED, __HIP_MEMORY_SCOPE_AGENT); }
; __device__ __forceinline__ unsigned xb_add(unsigned* p, unsigned v) { return __hip_atomic_fetch_add(p, v, __ATOMIC_RELAXED, __HIP_MEMORY_SCOPE_AGENT); }
; #define XB_SPIN(cond, bar) do { unsigned _sp = 0; while (cond) { __builtin_amdgcn_s_sleep(1); \
;     if ((++_sp & 255u) == 0u) { if (xb_ld(&(bar)[XB_TMO])) break; if (_sp > XB_SPIN_CAP) { atomicAdd(&(bar)[XB_TMO], 1u); break; } } } } while (0)
; __device__ __forceinline__ void xcd_barrier(const XcdBarrier& b, bool leader) {
;     ...
;             const unsigned og = xb_add(&bar[XB_TOP], 1u);
;             const unsigned tg = og / nx;
;             if (og + 1u == (tg + 1u) * nx) xb_add(&bar[XB_TOPGEN], 1u);
;             else XB_SPIN(xb_ld(&bar[XB_TOPGEN]) == tg, bar);
;             __builtin_amdgcn_fence(__ATOMIC_ACQUIRE, "agent");
;             xb_add(&bar[XB_XGEN(b.x)], 1u);
;             asm volatile("s_waitcnt vmcnt(0)" ::: "memory");
.LBB0_1181:
	s_or_b64 exec, exec, s[6:7]
	s_and_saveexec_b64 s[4:5], s[8:9]
	s_cbranch_execz .LBB0_1183
	v_mov_b32_e32 v2, 1
	global_atomic_add v[0:1], v2, off
.LBB0_1183:
	s_or_b64 exec, exec, s[4:5]
	v_mov_b32_e32 v0, s27
	v_add_co_u32_e32 v0, vcc, 0x2000, v0
	v_mov_b32_e32 v1, s26
	s_nop 0
	v_addc_co_u32_e32 v1, vcc, 0, v1, vcc
	v_mov_b32_e32 v2, 1
	s_waitcnt vmcnt(0) lgkmcnt(0)
	buffer_inv sc1
	global_atomic_add v[0:1], v2, off offset:1024
	s_waitcnt vmcnt(0)

; __device__ __forceinline__ unsigned pk2(float lo, float hi) { const f32x2 v = {lo, hi}; return __builtin_bit_cast(unsigned, __builtin_convertvector(v, bf16x2_t)); }
; #define WSB(off) ((bf16*)((unsigned char*)tab_get(lds, 31) + (off)))
;     __device__ __forceinline__ void operator()(EPI_ARGS) const {
;         const int row0 = u.pm * BM + wr * 64 + fr, col0 = u.pn * BM + wc * 32 + 8 * fq;
; #pragma unroll
;         for (int ai = 0; ai < 2; ++ai)
; #pragma unroll
;             for (int m = 0; m < 4; ++m) { bf16* rowp = O + (size_t)(row0 + ai * HALF + m * 16) * ldc + col0;
; #pragma unroll
;                 for (int bj = 0; bj < 2; ++bj) { const f32x4 v0 = acc[ai][bj][m][0], v1 = acc[ai][bj][m][1];
;                     u32x4 w; w.x = pk2(v0[0], v0[1]); w.y = pk2(v0[2], v0[3]); w.z = pk2(v1[0], v1[1]); w.w = pk2(v1[2], v1[3]);
;                     *(u32x4*)(rowp + bj * HALF) = w; } }
;     }
; __global__ void __launch_bounds__(512, 2) mega_fwd(Params p) {
;     ...
;         { pg8::Gemm g{WSB(WS_H) + SROWS * DM, WSB(WS_WCQ), MS, 1024, 1024, 1024, 1024}; pg8::StaticOrder S; S.init(MS, 1024, G, bx); pg8::EpiStoreBf16 E{WSB(WS_QC) + SROWS * DM, 1024}; pg8::gemm_phase(lds, g, S, E); }
.LBB0_1196:
	v_lshl_add_u32 v146, s22, 8, v140
	v_lshl_or_b32 v148, s23, 8, v142
	v_ashrrev_i32_e32 v147, 31, v146
	v_ashrrev_i32_e32 v149, 31, v148
	v_lshlrev_b64 v[150:151], 11, v[146:147]
	v_lshl_add_u64 v[150:151], s[8:9], 0, v[150:151]
	v_lshlrev_b64 v[148:149], 1, v[148:149]
	v_lshl_add_u64 v[150:151], v[150:151], 0, v[148:149]
	v_cvt_pk_bf16_f32 v60, v60, v61
	v_cvt_pk_bf16_f32 v61, v62, v63
	v_cvt_pk_bf16_f32 v62, v56, v57
	v_add_co_u32_e32 v56, vcc, s61, v150
	v_cvt_pk_bf16_f32 v68, v68, v69
	v_cvt_pk_bf16_f32 v69, v70, v71
	v_cvt_pk_bf16_f32 v70, v64, v65
	v_lshl_add_u64 v[64:65], v[150:151], 0, s[4:5]
	v_addc_co_u32_e32 v57, vcc, 0, v151, vcc
	v_cvt_pk_bf16_f32 v44, v44, v45
	v_cvt_pk_bf16_f32 v45, v46, v47
	v_cvt_pk_bf16_f32 v46, v40, v41
	v_cvt_pk_bf16_f32 v47, v42, v43
	v_cvt_pk_bf16_f32 v108, v108, v109
	v_cvt_pk_bf16_f32 v109, v110, v111
	v_cvt_pk_bf16_f32 v110, v104, v105
	v_or_b32_e32 v104, 16, v146
	global_store_dwordx4 v[64:65], v[44:47], off offset:256
	v_ashrrev_i32_e32 v105, 31, v104
	v_cvt_pk_bf16_f32 v92, v92, v93
	v_add_co_u32_e32 v46, vcc, s62, v150
	v_cvt_pk_bf16_f32 v93, v94, v95
	v_cvt_pk_bf16_f32 v94, v88, v89
	v_or_b32_e32 v88, 32, v146
	v_lshl_add_u64 v[44:45], v[150:151], 0, s[16:17]
	v_addc_co_u32_e32 v47, vcc, 0, v151, vcc
	v_cvt_pk_bf16_f32 v28, v28, v29
	v_cvt_pk_bf16_f32 v29, v30, v31
	v_cvt_pk_bf16_f32 v30, v24, v25
	v_cvt_pk_bf16_f32 v31, v26, v27
	v_lshlrev_b64 v[104:105], 11, v[104:105]
	v_ashrrev_i32_e32 v89, 31, v88
	v_cvt_pk_bf16_f32 v76, v76, v77
	v_cvt_pk_bf16_f32 v77, v78, v79
	v_cvt_pk_bf16_f32 v78, v72, v73
	v_or_b32_e32 v72, 48, v146
	global_store_dwordx4 v[44:45], v[28:31], off offset:256
	v_cvt_pk_bf16_f32 v111, v106, v107
	v_lshl_add_u64 v[104:105], s[8:9], 0, v[104:105]
	v_add_co_u32_e32 v30, vcc, s63, v150
	v_lshlrev_b64 v[88:89], 11, v[88:89]
	v_ashrrev_i32_e32 v73, 31, v72
	v_lshl_add_u64 v[28:29], v[150:151], 0, s[18:19]
	v_addc_co_u32_e32 v31, vcc, 0, v151, vcc
	v_cvt_pk_bf16_f32 v12, v12, v13
	v_cvt_pk_bf16_f32 v13, v14, v15
	v_cvt_pk_bf16_f32 v14, v8, v9
	v_cvt_pk_bf16_f32 v15, v10, v11
	global_store_dwordx4 v[150:151], v[108:111], off offset:256
	v_cvt_pk_bf16_f32 v95, v90, v91
	v_lshl_add_u64 v[88:89], s[8:9], 0, v[88:89]
	v_lshl_add_u64 v[108:109], v[104:105], 0, v[148:149]
	v_lshlrev_b64 v[72:73], 11, v[72:73]
	global_store_dwordx4 v[28:29], v[12:15], off offset:256
	global_store_dwordx4 v[108:109], v[92:95], off offset:256
	v_cvt_pk_bf16_f32 v79, v74, v75
	v_add_co_u32_e32 v14, vcc, s64, v150
	v_lshl_add_u64 v[92:93], v[88:89], 0, v[148:149]
	v_lshl_add_u64 v[72:73], s[8:9], 0, v[72:73]
	v_addc_co_u32_e32 v15, vcc, 0, v151, vcc
	v_cvt_pk_bf16_f32 v124, v124, v125
	v_cvt_pk_bf16_f32 v125, v126, v127
	v_cvt_pk_bf16_f32 v126, v120, v121
	v_cvt_pk_bf16_f32 v127, v122, v123
	v_cvt_pk_bf16_f32 v104, v116, v117
	v_cvt_pk_bf16_f32 v105, v118, v119
	v_cvt_pk_bf16_f32 v106, v112, v113
	v_cvt_pk_bf16_f32 v107, v114, v115
	v_cvt_pk_bf16_f32 v88, v100, v101
	v_cvt_pk_bf16_f32 v89, v102, v103
	v_cvt_pk_bf16_f32 v90, v96, v97
	v_cvt_pk_bf16_f32 v91, v98, v99
	global_store_dwordx4 v[92:93], v[76:79], off offset:256
	v_cvt_pk_bf16_f32 v74, v80, v81
	v_cvt_pk_bf16_f32 v75, v82, v83
	v_lshl_add_u64 v[76:77], v[72:73], 0, v[148:149]
	v_cvt_pk_bf16_f32 v72, v84, v85
	v_cvt_pk_bf16_f32 v73, v86, v87
	v_cvt_pk_bf16_f32 v71, v66, v67
	v_cvt_pk_bf16_f32 v63, v58, v59
	v_cvt_pk_bf16_f32 v40, v52, v53
	v_cvt_pk_bf16_f32 v41, v54, v55
	v_cvt_pk_bf16_f32 v42, v48, v49
	v_cvt_pk_bf16_f32 v43, v50, v51
	v_cvt_pk_bf16_f32 v24, v36, v37
	v_cvt_pk_bf16_f32 v25, v38, v39
	v_cvt_pk_bf16_f32 v26, v32, v33
	v_cvt_pk_bf16_f32 v27, v34, v35
	v_lshl_add_u64 v[12:13], v[150:151], 0, s[20:21]
	v_cvt_pk_bf16_f32 v8, v20, v21
	v_cvt_pk_bf16_f32 v9, v22, v23
	v_cvt_pk_bf16_f32 v10, v16, v17
	v_cvt_pk_bf16_f32 v11, v18, v19
	v_cvt_pk_bf16_f32 v4, v4, v5
	v_cvt_pk_bf16_f32 v5, v6, v7
	v_cvt_pk_bf16_f32 v6, v0, v1
	v_cvt_pk_bf16_f32 v7, v2, v3
	s_andn2_b64 vcc, exec, s[28:29]
	s_mov_b64 s[22:23], -1
	global_store_dwordx4 v[150:151], v[124:127], off
	global_store_dwordx4 v[108:109], v[104:107], off
	global_store_dwordx4 v[92:93], v[88:91], off
	global_store_dwordx4 v[76:77], v[72:75], off
	global_store_dwordx4 v[76:77], v[68:71], off offset:256
	global_store_dwordx4 v[56:57], v[60:63], off
	global_store_dwordx4 v[46:47], v[40:43], off
	global_store_dwordx4 v[30:31], v[24:27], off
	global_store_dwordx4 v[14:15], v[8:11], off
	global_store_dwordx4 v[12:13], v[4:7], off offset:256
	s_cbranch_vccnz .LBB0_1189
	s_andn2_b64 vcc, exec, s[6:7]
	s_cbranch_vccnz .LBB0_1188
	s_barrier
	s_branch .LBB0_1188

; __device__ __forceinline__ unsigned pk2(float lo, float hi) { const f32x2 v = {lo, hi}; return __builtin_bit_cast(unsigned, __builtin_convertvector(v, bf16x2_t)); }
; __device__ __forceinline__ float half_sum(float v) { auto rr = __builtin_amdgcn_permlane32_swap(__float_as_uint(v), __float_as_uint(v), false, false); return __uint_as_float(rr[0]) + __uint_as_float(rr[1]); }
; template <int DQK, int DV, int MODE>
; __device__ __forceinline__ void flash_unit(LAS unsigned char* lds, const bf16* Qp, int qpitch, const bf16* K0, int kpitch, const bf16* K1, const bf16* VT, int vpitch,
;                                            bf16* Op, int opitch, int NT, int jbase, int qpos0) {
;     ...
;     { const float lt = half_sum(lrun), inv = 1.f / lt;
;       bf16* orow = Op + (size_t)(wid * 32 + r32) * opitch + 4 * hi;
; #pragma unroll
;       for (int db = 0; db < NDB; ++db)
; #pragma unroll
;           for (int rg = 0; rg < 4; ++rg) { u32x2 w; w.x = pk2(o[db][4 * rg] * inv, o[db][4 * rg + 1] * inv); w.y = pk2(o[db][4 * rg + 2] * inv, o[db][4 * rg + 3] * inv);
;               *(u32x2*)(orow + 32 * db + 8 * rg) = w; } }
.LBB0_1201:
	v_mov_b32_e32 v0, v229
	s_nop 1
	v_permlane32_swap_b32_e32 v229, v0
	v_add_f32_e32 v0, v229, v0
	v_div_scale_f32 v130, s[4:5], v0, v0, 1.0
	v_rcp_f32_e32 v131, v130
	s_add_u32 s6, s39, s22
	s_addc_u32 s5, s40, s23
	s_add_u32 s4, s6, s54
	v_fma_f32 v132, -v130, v131, 1.0
	v_fmac_f32_e32 v131, v132, v131
	v_div_scale_f32 v132, vcc, 1.0, v0, 1.0
	v_mul_f32_e32 v133, v132, v131
	v_fma_f32 v134, -v130, v133, v132
	v_fmac_f32_e32 v133, v134, v131
	v_fma_f32 v130, -v130, v133, v132
	v_div_fmas_f32 v130, v130, v131, v133
	s_addc_u32 s5, s5, 0
	v_div_fixup_f32 v0, v130, v0, 1.0
	v_lshl_add_u64 v[130:131], s[4:5], 0, v[196:197]
	v_mov_b32_e32 v195, v1
	v_pk_mul_f32 v[114:115], v[114:115], v[0:1] op_sel_hi:[1,0]
	v_pk_mul_f32 v[116:117], v[116:117], v[0:1] op_sel_hi:[1,0]
	v_pk_mul_f32 v[98:99], v[98:99], v[0:1] op_sel_hi:[1,0]
	v_pk_mul_f32 v[100:101], v[100:101], v[0:1] op_sel_hi:[1,0]
	v_pk_mul_f32 v[82:83], v[82:83], v[0:1] op_sel_hi:[1,0]
	v_pk_mul_f32 v[84:85], v[84:85], v[0:1] op_sel_hi:[1,0]
	v_pk_mul_f32 v[66:67], v[66:67], v[0:1] op_sel_hi:[1,0]
	v_pk_mul_f32 v[68:69], v[68:69], v[0:1] op_sel_hi:[1,0]
	v_pk_mul_f32 v[50:51], v[50:51], v[0:1] op_sel_hi:[1,0]
	v_pk_mul_f32 v[52:53], v[52:53], v[0:1] op_sel_hi:[1,0]
	v_pk_mul_f32 v[34:35], v[34:35], v[0:1] op_sel_hi:[1,0]
	v_pk_mul_f32 v[36:37], v[36:37], v[0:1] op_sel_hi:[1,0]
	v_pk_mul_f32 v[18:19], v[18:19], v[0:1] op_sel_hi:[1,0]
	v_pk_mul_f32 v[20:21], v[20:21], v[0:1] op_sel_hi:[1,0]
	v_pk_mul_f32 v[2:3], v[2:3], v[0:1] op_sel_hi:[1,0]
	v_pk_mul_f32 v[4:5], v[4:5], v[0:1] op_sel_hi:[1,0]
	v_lshl_add_u64 v[130:131], v[130:131], 0, v[194:195]
	v_cvt_pk_bf16_f32 v114, v114, v115
	v_cvt_pk_bf16_f32 v115, v116, v117
	v_cvt_pk_bf16_f32 v98, v98, v99
	v_cvt_pk_bf16_f32 v99, v100, v101
	v_cvt_pk_bf16_f32 v82, v82, v83
	v_cvt_pk_bf16_f32 v83, v84, v85
	v_cvt_pk_bf16_f32 v66, v66, v67
	v_cvt_pk_bf16_f32 v67, v68, v69
	v_cvt_pk_bf16_f32 v50, v50, v51
	v_cvt_pk_bf16_f32 v51, v52, v53
	v_cvt_pk_bf16_f32 v34, v34, v35
	v_cvt_pk_bf16_f32 v35, v36, v37
	v_cvt_pk_bf16_f32 v18, v18, v19
	v_cvt_pk_bf16_f32 v19, v20, v21
	v_cvt_pk_bf16_f32 v2, v2, v3
	v_cvt_pk_bf16_f32 v3, v4, v5
	global_store_dwordx2 v[130:131], v[114:115], off
	v_pk_mul_f32 v[114:115], v[118:119], v[0:1] op_sel_hi:[1,0]
	v_pk_mul_f32 v[116:117], v[120:121], v[0:1] op_sel_hi:[1,0]
	global_store_dwordx2 v[130:131], v[98:99], off offset:64
	v_pk_mul_f32 v[98:99], v[102:103], v[0:1] op_sel_hi:[1,0]
	v_pk_mul_f32 v[100:101], v[104:105], v[0:1] op_sel_hi:[1,0]
	global_store_dwordx2 v[130:131], v[82:83], off offset:128
	v_pk_mul_f32 v[82:83], v[86:87], v[0:1] op_sel_hi:[1,0]
	v_pk_mul_f32 v[84:85], v[88:89], v[0:1] op_sel_hi:[1,0]
	global_store_dwordx2 v[130:131], v[66:67], off offset:192
	v_pk_mul_f32 v[66:67], v[70:71], v[0:1] op_sel_hi:[1,0]
	v_pk_mul_f32 v[68:69], v[72:73], v[0:1] op_sel_hi:[1,0]
	global_store_dwordx2 v[130:131], v[50:51], off offset:256
	v_pk_mul_f32 v[50:51], v[54:55], v[0:1] op_sel_hi:[1,0]
	v_pk_mul_f32 v[52:53], v[56:57], v[0:1] op_sel_hi:[1,0]
	global_store_dwordx2 v[130:131], v[34:35], off offset:320
	v_pk_mul_f32 v[34:35], v[38:39], v[0:1] op_sel_hi:[1,0]
	v_pk_mul_f32 v[36:37], v[40:41], v[0:1] op_sel_hi:[1,0]
	global_store_dwordx2 v[130:131], v[18:19], off offset:384
	v_pk_mul_f32 v[18:19], v[22:23], v[0:1] op_sel_hi:[1,0]
	v_pk_mul_f32 v[20:21], v[24:25], v[0:1] op_sel_hi:[1,0]
	global_store_dwordx2 v[130:131], v[2:3], off offset:448
	v_pk_mul_f32 v[2:3], v[6:7], v[0:1] op_sel_hi:[1,0]
	v_pk_mul_f32 v[4:5], v[8:9], v[0:1] op_sel_hi:[1,0]
	v_cvt_pk_bf16_f32 v114, v114, v115
	v_cvt_pk_bf16_f32 v115, v116, v117
	v_cvt_pk_bf16_f32 v98, v98, v99
	v_cvt_pk_bf16_f32 v99, v100, v101
	v_cvt_pk_bf16_f32 v82, v82, v83
	v_cvt_pk_bf16_f32 v83, v84, v85
	v_cvt_pk_bf16_f32 v66, v66, v67
	v_cvt_pk_bf16_f32 v67, v68, v69
	v_cvt_pk_bf16_f32 v50, v50, v51
	v_cvt_pk_bf16_f32 v51, v52, v53
	v_cvt_pk_bf16_f32 v34, v34, v35
	v_cvt_pk_bf16_f32 v35, v36, v37
	v_cvt_pk_bf16_f32 v18, v18, v19
	v_cvt_pk_bf16_f32 v19, v20, v21
	v_cvt_pk_bf16_f32 v2, v2, v3
	v_cvt_pk_bf16_f32 v3, v4, v5
	global_store_dwordx2 v[130:131], v[114:115], off offset:16
	v_pk_mul_f32 v[114:115], v[122:123], v[0:1] op_sel_hi:[1,0]
; __device__ __forceinline__ unsigned pk2(float lo, float hi) { const f32x2 v = {lo, hi}; return __builtin_bit_cast(unsigned, __builtin_convertvector(v, bf16x2_t)); }
; __device__ __forceinline__ float half_sum(float v) { auto rr = __builtin_amdgcn_permlane32_swap(__float_as_uint(v), __float_as_uint(v), false, false); return __uint_as_float(rr[0]) + __uint_as_float(rr[1]); }
; template <int DQK, int DV, int MODE>
; __device__ __forceinline__ void flash_unit(LAS unsigned char* lds, const bf16* Qp, int qpitch, const bf16* K0, int kpitch, const bf16* K1, const bf16* VT, int vpitch,
;                                            bf16* Op, int opitch, int NT, int jbase, int qpos0) {
;     ...
;     { const float lt = half_sum(lrun), inv = 1.f / lt;
;       bf16* orow = Op + (size_t)(wid * 32 + r32) * opitch + 4 * hi;
; #pragma unroll
;       for (int db = 0; db < NDB; ++db)
; #pragma unroll
;           for (int rg = 0; rg < 4; ++rg) { u32x2 w; w.x = pk2(o[db][4 * rg] * inv, o[db][4 * rg + 1] * inv); w.y = pk2(o[db][4 * rg + 2] * inv, o[db][4 * rg + 3] * inv);
;               *(u32x2*)(orow + 32 * db + 8 * rg) = w; } }
	v_pk_mul_f32 v[116:117], v[124:125], v[0:1] op_sel_hi:[1,0]
	global_store_dwordx2 v[130:131], v[98:99], off offset:80
	v_pk_mul_f32 v[98:99], v[106:107], v[0:1] op_sel_hi:[1,0]
	v_pk_mul_f32 v[100:101], v[108:109], v[0:1] op_sel_hi:[1,0]
	global_store_dwordx2 v[130:131], v[82:83], off offset:144
	v_pk_mul_f32 v[82:83], v[90:91], v[0:1] op_sel_hi:[1,0]
	v_pk_mul_f32 v[84:85], v[92:93], v[0:1] op_sel_hi:[1,0]
	global_store_dwordx2 v[130:131], v[66:67], off offset:208
	v_pk_mul_f32 v[66:67], v[74:75], v[0:1] op_sel_hi:[1,0]
	v_pk_mul_f32 v[68:69], v[76:77], v[0:1] op_sel_hi:[1,0]
	global_store_dwordx2 v[130:131], v[50:51], off offset:272
	v_pk_mul_f32 v[50:51], v[58:59], v[0:1] op_sel_hi:[1,0]
	v_pk_mul_f32 v[52:53], v[60:61], v[0:1] op_sel_hi:[1,0]
	global_store_dwordx2 v[130:131], v[34:35], off offset:336
	v_pk_mul_f32 v[34:35], v[42:43], v[0:1] op_sel_hi:[1,0]
	v_pk_mul_f32 v[36:37], v[44:45], v[0:1] op_sel_hi:[1,0]
	global_store_dwordx2 v[130:131], v[18:19], off offset:400
	v_pk_mul_f32 v[18:19], v[26:27], v[0:1] op_sel_hi:[1,0]
	v_pk_mul_f32 v[20:21], v[28:29], v[0:1] op_sel_hi:[1,0]
	global_store_dwordx2 v[130:131], v[2:3], off offset:464
	v_pk_mul_f32 v[2:3], v[10:11], v[0:1] op_sel_hi:[1,0]
	v_pk_mul_f32 v[4:5], v[12:13], v[0:1] op_sel_hi:[1,0]
	v_cvt_pk_bf16_f32 v114, v114, v115
	v_cvt_pk_bf16_f32 v115, v116, v117
	v_cvt_pk_bf16_f32 v98, v98, v99
	v_cvt_pk_bf16_f32 v99, v100, v101
	v_cvt_pk_bf16_f32 v82, v82, v83
	v_cvt_pk_bf16_f32 v83, v84, v85
	v_cvt_pk_bf16_f32 v66, v66, v67
	v_cvt_pk_bf16_f32 v67, v68, v69
	v_cvt_pk_bf16_f32 v50, v50, v51
	v_cvt_pk_bf16_f32 v51, v52, v53
	v_cvt_pk_bf16_f32 v34, v34, v35
	v_cvt_pk_bf16_f32 v35, v36, v37
	v_cvt_pk_bf16_f32 v18, v18, v19
	v_cvt_pk_bf16_f32 v19, v20, v21
	v_cvt_pk_bf16_f32 v2, v2, v3
	v_cvt_pk_bf16_f32 v3, v4, v5
	global_store_dwordx2 v[130:131], v[114:115], off offset:32
	v_pk_mul_f32 v[114:115], v[126:127], v[0:1] op_sel_hi:[1,0]
	v_pk_mul_f32 v[116:117], v[128:129], v[0:1] op_sel_hi:[1,0]
	global_store_dwordx2 v[130:131], v[98:99], off offset:96
	v_pk_mul_f32 v[98:99], v[110:111], v[0:1] op_sel_hi:[1,0]
	v_pk_mul_f32 v[100:101], v[112:113], v[0:1] op_sel_hi:[1,0]
	global_store_dwordx2 v[130:131], v[82:83], off offset:160
	v_pk_mul_f32 v[82:83], v[94:95], v[0:1] op_sel_hi:[1,0]
	v_pk_mul_f32 v[84:85], v[96:97], v[0:1] op_sel_hi:[1,0]
	global_store_dwordx2 v[130:131], v[66:67], off offset:224
	v_pk_mul_f32 v[66:67], v[78:79], v[0:1] op_sel_hi:[1,0]
	v_pk_mul_f32 v[68:69], v[80:81], v[0:1] op_sel_hi:[1,0]
	global_store_dwordx2 v[130:131], v[50:51], off offset:288
	v_pk_mul_f32 v[50:51], v[62:63], v[0:1] op_sel_hi:[1,0]
	v_pk_mul_f32 v[52:53], v[64:65], v[0:1] op_sel_hi:[1,0]
	global_store_dwordx2 v[130:131], v[34:35], off offset:352
	v_pk_mul_f32 v[34:35], v[46:47], v[0:1] op_sel_hi:[1,0]
	v_pk_mul_f32 v[36:37], v[48:49], v[0:1] op_sel_hi:[1,0]
	global_store_dwordx2 v[130:131], v[18:19], off offset:416
	v_pk_mul_f32 v[18:19], v[30:31], v[0:1] op_sel_hi:[1,0]
	v_pk_mul_f32 v[20:21], v[32:33], v[0:1] op_sel_hi:[1,0]
	global_store_dwordx2 v[130:131], v[2:3], off offset:480
	v_pk_mul_f32 v[2:3], v[14:15], v[0:1] op_sel_hi:[1,0]
	v_pk_mul_f32 v[4:5], v[16:17], v[0:1] op_sel_hi:[1,0]
	v_cvt_pk_bf16_f32 v114, v114, v115
	v_cvt_pk_bf16_f32 v115, v116, v117
	v_cvt_pk_bf16_f32 v98, v98, v99
	v_cvt_pk_bf16_f32 v99, v100, v101
	v_cvt_pk_bf16_f32 v82, v82, v83
	v_cvt_pk_bf16_f32 v83, v84, v85
	v_cvt_pk_bf16_f32 v66, v66, v67
	v_cvt_pk_bf16_f32 v67, v68, v69
	v_cvt_pk_bf16_f32 v50, v50, v51
	v_cvt_pk_bf16_f32 v51, v52, v53
	v_cvt_pk_bf16_f32 v34, v34, v35
	v_cvt_pk_bf16_f32 v35, v36, v37
	v_cvt_pk_bf16_f32 v18, v18, v19
	v_cvt_pk_bf16_f32 v19, v20, v21
	v_cvt_pk_bf16_f32 v2, v2, v3
	v_cvt_pk_bf16_f32 v3, v4, v5
	s_mov_b64 s[4:5], 0
	global_store_dwordx2 v[130:131], v[114:115], off offset:48
	global_store_dwordx2 v[130:131], v[98:99], off offset:112
	global_store_dwordx2 v[130:131], v[82:83], off offset:176
	global_store_dwordx2 v[130:131], v[66:67], off offset:240
	global_store_dwordx2 v[130:131], v[50:51], off offset:304
	global_store_dwordx2 v[130:131], v[34:35], off offset:368
	global_store_dwordx2 v[130:131], v[18:19], off offset:432
	global_store_dwordx2 v[130:131], v[2:3], off offset:496

; #define QNEXT(ctrw, dst) do { __syncthreads(); if (my_tid(lds) == 0) *(volatile LAS int*)(lds + TAB_OFF + 264) = (int)atomicAdd((unsigned*)tab_get(lds, 31) + 8192 + 64 * (ctrw), 1u); \
;         __syncthreads(); dst = __builtin_amdgcn_readfirstlane(*(volatile LAS int*)(lds + TAB_OFF + 264)); } while (0)
; __global__ void __launch_bounds__(512, 2) mega_fwd(Params p) {
;     ...
;           for (;;) { int it; QNEXT(2, it); if (it >= 512) break;
;               const int bh = it >> 6, qb = it & 63, b = bh >> 2, hh = bh & 3; const size_t rb = (size_t)b * SEQ + 256 * qb;
;               flash_unit<256, 256, 1>(lds, QC + rb * 1024 + hh * 256, 1024, MK + (size_t)(b * 256) * 1024 + hh * 256, 1024, nullptr, MVT + (size_t)(hh * 256) * 512 + b * 256, 512,
;                                       OC + rb * 1024 + hh * 256, 1024, 4, 1000, 0); } }
.LBB0_1203:
	s_waitcnt vmcnt(0)
	s_barrier
	s_getreg_b32 s4, hwreg(HW_REG_HW_ID, 0, 6)
	s_lshl_b32 s4, s4, 2
	s_and_b32 s4, s4, 0xfc
	s_add_i32 s4, s4, 0
	s_add_i32 s4, s4, 0x25a00
	v_mov_b32_e32 v0, s4
	ds_read_b32 v0, v0
	v_mbcnt_lo_u32_b32 v2, -1, 0
	v_mbcnt_hi_u32_b32 v2, -1, v2
	s_waitcnt lgkmcnt(0)
	v_readfirstlane_b32 s4, v0
	s_lshl_b32 s4, s4, 6
	v_sub_u32_e32 v0, 0, v2
	v_cmp_eq_u32_e32 vcc, s4, v0
	s_and_saveexec_b64 s[4:5], vcc
	s_cbranch_execz .LBB0_1205
	ds_read_b64 v[2:3], v216
	s_waitcnt lgkmcnt(0)
	v_readfirstlane_b32 s7, v2
	v_readfirstlane_b32 s6, v3
	s_nop 0
	v_mov_b32_e32 v0, s7
	v_add_co_u32_e32 v2, vcc, 0x8000, v0
	v_mov_b32_e32 v3, s6
	s_nop 0
	v_addc_co_u32_e32 v3, vcc, 0, v3, vcc
	global_atomic_add v0, v[2:3], v217, off offset:512 sc0
	s_waitcnt vmcnt(0) lgkmcnt(0)
	ds_write_b32 v218, v0
.LBB0_1205:
	s_or_b64 exec, exec, s[4:5]
	s_waitcnt lgkmcnt(0)
	s_barrier
	ds_read_b32 v0, v218
	s_mov_b64 s[4:5], -1
	s_waitcnt lgkmcnt(0)
	v_readfirstlane_b32 s28, v0
	s_cmpk_gt_i32 s28, 0x1ff
	s_cbranch_scc1 .LBB0_1202
	s_and_b32 s20, s28, 0xffffff00
	s_lshl_b32 s4, s28, 2
	s_ashr_i32 s21, s20, 31
	s_and_b32 s12, s4, 0x300
	s_lshl_b64 s[24:25], s[20:21], 11
	s_add_u32 s4, s34, s24
	s_addc_u32 s5, s35, s25
	s_lshl_b32 s54, s12, 1
	s_add_u32 s22, s4, s54
	s_getreg_b32 s4, hwreg(HW_REG_HW_ID, 0, 6)
	s_addc_u32 s23, s5, 0
	s_lshl_b32 s4, s4, 2
	s_and_b32 s4, s4, 0xfc
	s_add_i32 s4, s4, 0
	s_add_i32 s4, s4, 0x25a00
	v_mov_b32_e32 v0, s4
	ds_read_b32 v0, v0
	v_mbcnt_lo_u32_b32 v38, -1, 0
	v_mbcnt_hi_u32_b32 v38, -1, v38
	s_waitcnt lgkmcnt(0)
	v_readfirstlane_b32 s4, v0
	s_nop 1
	v_lshl_add_u32 v27, s4, 6, v38
	v_ashrrev_i32_e32 v0, 31, v27
	v_readfirstlane_b32 s29, v27
	v_cmp_gt_i32_e64 s[4:5], s42, v27
	v_lshlrev_b32_e32 v29, 3, v27
	v_lshrrev_b32_e32 v39, 27, v0
	s_and_saveexec_b64 s[6:7], s[4:5]
	s_cbranch_execz .LBB0_1208
	v_add_u32_e32 v0, v27, v39
	v_ashrrev_i32_e32 v2, 5, v0
	v_ashrrev_i32_e32 v3, 31, v2
	v_lshlrev_b32_e32 v0, 8, v2
	v_lshlrev_b64 v[4:5], 11, v[2:3]
	v_sub_u32_e32 v2, v29, v0
	v_lshl_add_u64 v[4:5], s[22:23], 0, v[4:5]
	v_ashrrev_i32_e32 v3, 31, v2
	v_lshl_add_u64 v[2:3], v[2:3], 1, v[4:5]
	global_load_dwordx4 v[162:165], v[2:3], off
.LBB0_1208:
	s_or_b64 exec, exec, s[6:7]
	v_add_u32_e32 v40, 0x200, v27
	v_ashrrev_i32_e32 v0, 31, v40
	v_cmp_gt_i32_e64 s[6:7], s45, v27
	v_lshlrev_b32_e32 v41, 3, v40
	v_lshrrev_b32_e32 v42, 27, v0
	s_and_saveexec_b64 s[8:9], s[6:7]
	s_cbranch_execz .LBB0_1210
	v_add_u32_e32 v0, v40, v42
	v_ashrrev_i32_e32 v2, 5, v0
	v_ashrrev_i32_e32 v3, 31, v2
	v_lshlrev_b32_e32 v0, 8, v2
	v_lshlrev_b64 v[4:5], 11, v[2:3]
	v_sub_u32_e32 v2, v41, v0
	v_lshl_add_u64 v[4:5], s[22:23], 0, v[4:5]
	v_ashrrev_i32_e32 v3, 31, v2
	v_lshl_add_u64 v[2:3], v[2:3], 1, v[4:5]
	global_load_dwordx4 v[166:169], v[2:3], off
.LBB0_1210:
	s_or_b64 exec, exec, s[8:9]
	v_add_u32_e32 v43, 0x400, v27
	v_ashrrev_i32_e32 v0, 31, v43
	v_cmp_gt_i32_e64 s[8:9], s46, v27
	v_lshlrev_b32_e32 v44, 3, v43
	v_lshrrev_b32_e32 v45, 27, v0
	s_and_saveexec_b64 s[10:11], s[8:9]
	s_cbranch_execz .LBB0_1212
	v_add_u32_e32 v0, v43, v45
	v_ashrrev_i32_e32 v2, 5, v0
	v_ashrrev_i32_e32 v3, 31, v2
	v_lshlrev_b32_e32 v0, 8, v2
	v_lshlrev_b64 v[4:5], 11, v[2:3]
	v_sub_u32_e32 v2, v44, v0
	v_lshl_add_u64 v[4:5], s[22:23], 0, v[4:5]
	v_ashrrev_i32_e32 v3, 31, v2
	v_lshl_add_u64 v[2:3], v[2:3], 1, v[4:5]
	global_load_dwordx4 v[170:173], v[2:3], off
.LBB0_1212:
	s_or_b64 exec, exec, s[10:11]
	v_add_u32_e32 v47, 0x600, v27
	v_ashrrev_i32_e32 v0, 31, v47
	v_cmp_lt_i32_e32 vcc, s41, v27
	v_cmp_gt_i32_e64 s[10:11], s43, v27
	v_lshlrev_b32_e32 v48, 3, v47
	v_lshrrev_b32_e32 v49, 27, v0
	s_and_saveexec_b64 s[26:27], s[10:11]
	s_cbranch_execz .LBB0_1214
	v_add_u32_e32 v0, v47, v49
	v_ashrrev_i32_e32 v2, 5, v0
	v_ashrrev_i32_e32 v3, 31, v2
	v_lshlrev_b32_e32 v0, 8, v2
	v_lshlrev_b64 v[4:5], 11, v[2:3]
	v_sub_u32_e32 v2, v48, v0
	v_lshl_add_u64 v[4:5], s[22:23], 0, v[4:5]
	v_ashrrev_i32_e32 v3, 31, v2
	v_lshl_add_u64 v[2:3], v[2:3], 1, v[4:5]
	global_load_dwordx4 v[174:177], v[2:3], off
.LBB0_1214:
	s_or_b64 exec, exec, s[26:27]
	s_lshl_b32 s12, s12, 10
	s_add_u32 s22, s37, s12
	s_addc_u32 s23, s38, 0
	s_lshl_b64 s[20:21], s[20:21], 1
	v_lshlrev_b32_e32 v0, 3, v38
	s_add_u32 s22, s22, s20
	v_and_b32_e32 v46, 56, v0
	v_ashrrev_i32_e32 v30, 3, v27
	v_ashrrev_i32_e32 v32, 3, v40
	v_ashrrev_i32_e32 v34, 3, v43
	v_ashrrev_i32_e32 v36, 3, v47
	s_addc_u32 s23, s23, s21
	v_lshlrev_b32_e32 v0, 1, v46
	v_ashrrev_i32_e32 v31, 31, v30
	v_ashrrev_i32_e32 v33, 31, v32
	v_ashrrev_i32_e32 v35, 31, v34
	v_ashrrev_i32_e32 v37, 31, v36
	v_lshl_add_u64 v[10:11], s[22:23], 0, v[0:1]
	v_lshlrev_b64 v[18:19], 10, v[30:31]
	v_lshlrev_b64 v[20:21], 10, v[32:33]
	v_lshlrev_b64 v[22:23], 10, v[34:35]
	v_lshlrev_b64 v[24:25], 10, v[36:37]
	v_lshl_add_u64 v[2:3], v[10:11], 0, v[18:19]
	v_lshl_add_u64 v[4:5], v[10:11], 0, v[20:21]
	v_lshl_add_u64 v[12:13], v[10:11], 0, v[22:23]
	v_lshl_add_u64 v[10:11], v[10:11], 0, v[24:25]
	global_load_dwordx4 v[6:9], v[2:3], off
	s_nop 0
	global_load_dwordx4 v[2:5], v[4:5], off
	s_nop 0
	global_load_dwordx4 v[14:17], v[12:13], off
	s_nop 0
	global_load_dwordx4 v[10:13], v[10:11], off
	s_and_saveexec_b64 s[22:23], s[4:5]
	s_cbranch_execz .LBB0_1220
	v_add_u32_e32 v0, v27, v39
	v_ashrrev_i32_e32 v26, 5, v0
	v_lshlrev_b32_e32 v0, 8, v26
	v_sub_u32_e32 v0, v29, v0
	v_mad_u64_u32 v[50:51], s[26:27], v26, s47, v[0:1]
	v_lshl_add_u32 v0, v50, 1, 0
	s_waitcnt vmcnt(0) lgkmcnt(0)
	ds_write_b128 v0, v[162:165]
	s_or_b64 exec, exec, s[22:23]
	s_and_saveexec_b64 s[22:23], s[6:7]
	s_cbranch_execnz .LBB0_1221

; #define FL_GLOADK(j) do { \
;     _Pragma("unroll") for (int i_ = 0; i_ < KPT; ++i_) { const int ci = tid + 512 * i_; if (ci < NKC) { const int key = ci / KCH, ch = ci - key * KCH; \
;         kreg[i_] = *(const u32x4*)(K0 + (size_t)(64 * (j) + key) * kpitch + ch * 8); } } } while (0)
; #define FL_LSTOREK(buf) do { \
;     _Pragma("unroll") for (int i_ = 0; i_ < KPT; ++i_) { const int ci = tid + 512 * i_; if (ci < NKC) { const int key = ci / KCH, ch = ci - key * KCH; \
;         *(LAS u32x4*)(lds + (buf) * KB + (key * KP + ch * 8) * 2) = kreg[i_]; } } } while (0)
; #define FL_GLOADV(j) do { \
;     _Pragma("unroll") for (int i_ = 0; i_ < VPT; ++i_) { const int ci = tid + 512 * i_; const int d = ci >> 3, ch = ci & 7; kreg[i_] = *(const u32x4*)(VT + (size_t)d * vpitch + 64 * (j) + ch * 8); } } while (0)
; #define FL_LSTOREV(buf) do { \
;     _Pragma("unroll") for (int i_ = 0; i_ < VPT; ++i_) { const int ci = tid + 512 * i_; const int d = ci >> 3, ch = ci & 7; LAS u32x2* p_ = (LAS u32x2*)(lds + 2 * KB + (buf) * VB + (d * VP + ch * 8) * 2); \
;         p_[0] = (u32x2){kreg[i_].x, kreg[i_].y}; p_[1] = (u32x2){kreg[i_].z, kreg[i_].w}; } } while (0)
; template <int DQK, int DV, int MODE>
; __device__ __forceinline__ void flash_unit(LAS unsigned char* lds, const bf16* Qp, int qpitch, const bf16* K0, int kpitch, const bf16* K1, const bf16* VT, int vpitch,
;                                            bf16* Op, int opitch, int NT, int jbase, int qpos0) {
;     ...
;     for (int j = 0; j < NT; ++j) {
;         const int buf = j & 1;
;         if (j + 1 < NT) { if constexpr (MODE == 1) { FL_GLOADK(j + 1); FL_LSTOREK(buf ^ 1); FL_GLOADV(j + 1); FL_LSTOREV(buf ^ 1); } else { FL_GLOAD(j + 1); } }
.LBB0_1226:
	s_and_b32 s28, s12, 1
	s_cmp_eq_u32 s24, 0x60000
	s_cbranch_scc1 .LBB0_1244
	s_and_saveexec_b64 s[26:27], s[4:5]
	s_cbranch_execz .LBB0_1231
	v_lshl_add_u64 v[130:131], v[200:201], 0, s[24:25]
	global_load_dwordx4 v[162:165], v[130:131], off
	s_or_b64 exec, exec, s[26:27]
	s_and_saveexec_b64 s[26:27], s[6:7]
	s_cbranch_execnz .LBB0_1232

.LBB0_1230:
	v_lshl_add_u64 v[130:131], v[204:205], 0, s[24:25]
	global_load_dwordx4 v[170:173], v[130:131], off
	s_or_b64 exec, exec, s[26:27]
	s_and_saveexec_b64 s[26:27], s[10:11]
	s_cbranch_execnz .LBB0_1234
	s_branch .LBB0_1235

.LBB0_1232:
	v_lshl_add_u64 v[130:131], v[202:203], 0, s[24:25]
	global_load_dwordx4 v[166:169], v[130:131], off
	s_or_b64 exec, exec, s[26:27]
	s_and_saveexec_b64 s[26:27], s[8:9]
	s_cbranch_execnz .LBB0_1230

.LBB0_1234:
	v_lshl_add_u64 v[130:131], v[206:207], 0, s[24:25]
	global_load_dwordx4 v[174:177], v[130:131], off

; #define FL_GLOADK(j) do { \
;     _Pragma("unroll") for (int i_ = 0; i_ < KPT; ++i_) { const int ci = tid + 512 * i_; if (ci < NKC) { const int key = ci / KCH, ch = ci - key * KCH; \
;         kreg[i_] = *(const u32x4*)(K0 + (size_t)(64 * (j) + key) * kpitch + ch * 8); } } } while (0)
; #define FL_LSTOREK(buf) do { \
;     _Pragma("unroll") for (int i_ = 0; i_ < KPT; ++i_) { const int ci = tid + 512 * i_; if (ci < NKC) { const int key = ci / KCH, ch = ci - key * KCH; \
;         *(LAS u32x4*)(lds + (buf) * KB + (key * KP + ch * 8) * 2) = kreg[i_]; } } } while (0)
; #define FL_GLOADV(j) do { \
;     _Pragma("unroll") for (int i_ = 0; i_ < VPT; ++i_) { const int ci = tid + 512 * i_; const int d = ci >> 3, ch = ci & 7; kreg[i_] = *(const u32x4*)(VT + (size_t)d * vpitch + 64 * (j) + ch * 8); } } while (0)
; #define FL_LSTOREV(buf) do { \
;     _Pragma("unroll") for (int i_ = 0; i_ < VPT; ++i_) { const int ci = tid + 512 * i_; const int d = ci >> 3, ch = ci & 7; LAS u32x2* p_ = (LAS u32x2*)(lds + 2 * KB + (buf) * VB + (d * VP + ch * 8) * 2); \
;         p_[0] = (u32x2){kreg[i_].x, kreg[i_].y}; p_[1] = (u32x2){kreg[i_].z, kreg[i_].w}; } } while (0)
; template <int DQK, int DV, int MODE>
; __device__ __forceinline__ void flash_unit(LAS unsigned char* lds, const bf16* Qp, int qpitch, const bf16* K0, int kpitch, const bf16* K1, const bf16* VT, int vpitch,
;                                            bf16* Op, int opitch, int NT, int jbase, int qpos0) {
;     ...
;         if (j + 1 < NT) { if constexpr (MODE == 1) { FL_GLOADK(j + 1); FL_LSTOREK(buf ^ 1); FL_GLOADV(j + 1); FL_LSTOREV(buf ^ 1); } else { FL_GLOAD(j + 1); } }
.LBB0_1243:
	s_or_b64 exec, exec, s[26:27]
	v_lshl_add_u64 v[130:131], v[214:215], 0, s[20:21]
	s_waitcnt vmcnt(0) lgkmcnt(0)
	global_load_dwordx4 v[162:165], v[130:131], off
	v_lshl_add_u64 v[130:131], v[212:213], 0, s[20:21]
	global_load_dwordx4 v[166:169], v[130:131], off
	v_lshl_add_u64 v[130:131], v[210:211], 0, s[20:21]
	global_load_dwordx4 v[170:173], v[130:131], off
	v_lshl_add_u64 v[130:131], v[208:209], 0, s[20:21]
	global_load_dwordx4 v[174:177], v[130:131], off
	s_mul_i32 s29, s29, 0x8800
	s_add_i32 s26, s29, 0
	s_add_i32 s26, s26, 0x10800
	v_add_u32_e32 v0, s26, v219
	v_add_u32_e32 v130, s26, v220
	v_add_u32_e32 v131, s26, v221
	v_add_u32_e32 v132, s26, v222
	s_waitcnt vmcnt(0) lgkmcnt(0)
	ds_write2_b64 v0, v[162:163], v[164:165] offset1:1
	ds_write2_b64 v130, v[166:167], v[168:169] offset1:1
	ds_write2_b64 v131, v[170:171], v[172:173] offset1:1
	ds_write2_b64 v132, v[174:175], v[176:177] offset1:1
.LBB0_1244:
	global_load_dwordx4 v[178:181], v[198:199], off
	global_load_dwordx4 v[182:185], v[198:199], off offset:32
	s_mul_i32 s26, s28, 0x8400
	v_add_u32_e32 v0, s26, v223
	ds_read_b128 v[186:189], v0
	ds_read_b128 v[190:193], v0 offset:32
	ds_read_b128 v[230:233], v0 offset:16896
	ds_read_b128 v[234:237], v0 offset:16928
	v_xor_b32_e32 v130, 0x80000000, v228
	v_mov_b32_e32 v131, v130
	v_mov_b32_e32 v132, v130
	v_mov_b32_e32 v133, v130
	v_mov_b32_e32 v134, v130
	v_mov_b32_e32 v135, v130
	v_mov_b32_e32 v136, v130
	v_mov_b32_e32 v137, v130
	v_mov_b32_e32 v138, v130
	v_mov_b32_e32 v139, v130
	v_mov_b32_e32 v140, v130
	v_mov_b32_e32 v141, v130
	v_mov_b32_e32 v142, v130
	v_mov_b32_e32 v143, v130
	v_mov_b32_e32 v144, v130
	v_mov_b32_e32 v145, v130
	s_waitcnt vmcnt(0) lgkmcnt(0)
	s_nop 0
	v_mfma_f32_32x32x16_bf16 v[146:161], v[186:189], v[178:181], v[130:145]
	v_mfma_f32_32x32x16_bf16 v[130:145], v[230:233], v[178:181], v[130:145]
	v_mfma_f32_32x32x16_bf16 v[146:161], v[190:193], v[182:185], v[146:161]
	v_mfma_f32_32x32x16_bf16 v[130:145], v[234:237], v[182:185], v[130:145]
	global_load_dwordx4 v[178:181], v[198:199], off offset:64
	global_load_dwordx4 v[182:185], v[198:199], off offset:96
	ds_read_b128 v[186:189], v0 offset:64
	ds_read_b128 v[190:193], v0 offset:96
	ds_read_b128 v[230:233], v0 offset:16960
	ds_read_b128 v[234:237], v0 offset:16992
	s_waitcnt vmcnt(0) lgkmcnt(0)
	v_mfma_f32_32x32x16_bf16 v[146:161], v[186:189], v[178:181], v[146:161]
	v_mfma_f32_32x32x16_bf16 v[130:145], v[230:233], v[178:181], v[130:145]
	v_mfma_f32_32x32x16_bf16 v[146:161], v[190:193], v[182:185], v[146:161]
	v_mfma_f32_32x32x16_bf16 v[130:145], v[234:237], v[182:185], v[130:145]
	global_load_dwordx4 v[178:181], v[198:199], off offset:128
	global_load_dwordx4 v[182:185], v[198:199], off offset:160
	ds_read_b128 v[186:189], v0 offset:128
	ds_read_b128 v[190:193], v0 offset:160
	ds_read_b128 v[230:233], v0 offset:17024
	ds_read_b128 v[234:237], v0 offset:17056
	s_waitcnt vmcnt(0) lgkmcnt(0)
	v_mfma_f32_32x32x16_bf16 v[146:161], v[186:189], v[178:181], v[146:161]
	v_mfma_f32_32x32x16_bf16 v[130:145], v[230:233], v[178:181], v[130:145]
	v_mfma_f32_32x32x16_bf16 v[146:161], v[190:193], v[182:185], v[146:161]
	v_mfma_f32_32x32x16_bf16 v[130:145], v[234:237], v[182:185], v[130:145]
	global_load_dwordx4 v[178:181], v[198:199], off offset:192
	global_load_dwordx4 v[182:185], v[198:199], off offset:224
	ds_read_b128 v[186:189], v0 offset:192
	ds_read_b128 v[190:193], v0 offset:224
	ds_read_b128 v[230:233], v0 offset:17088
	ds_read_b128 v[234:237], v0 offset:17120
	s_waitcnt vmcnt(0) lgkmcnt(0)
	v_mfma_f32_32x32x16_bf16 v[146:161], v[186:189], v[178:181], v[146:161]
	v_mfma_f32_32x32x16_bf16 v[130:145], v[230:233], v[178:181], v[130:145]
	v_mfma_f32_32x32x16_bf16 v[146:161], v[190:193], v[182:185], v[146:161]
	v_mfma_f32_32x32x16_bf16 v[130:145], v[234:237], v[182:185], v[130:145]
	global_load_dwordx4 v[178:181], v[198:199], off offset:256
	global_load_dwordx4 v[182:185], v[198:199], off offset:288
	ds_read_b128 v[186:189], v0 offset:256
	ds_read_b128 v[190:193], v0 offset:288
	ds_read_b128 v[230:233], v0 offset:17152
	ds_read_b128 v[234:237], v0 offset:17184
	s_waitcnt vmcnt(0) lgkmcnt(0)
	v_mfma_f32_32x32x16_bf16 v[146:161], v[186:189], v[178:181], v[146:161]
	v_mfma_f32_32x32x16_bf16 v[130:145], v[230:233], v[178:181], v[130:145]
	v_mfma_f32_32x32x16_bf16 v[146:161], v[190:193], v[182:185], v[146:161]
	v_mfma_f32_32x32x16_bf16 v[130:145], v[234:237], v[182:185], v[130:145]
	global_load_dwordx4 v[178:181], v[198:199], off offset:320
	global_load_dwordx4 v[182:185], v[198:199], off offset:352
	ds_read_b128 v[186:189], v0 offset:320
	ds_read_b128 v[190:193], v0 offset:352
	ds_read_b128 v[230:233], v0 offset:17216
	ds_read_b128 v[234:237], v0 offset:17248
	s_waitcnt vmcnt(0) lgkmcnt(0)
	v_mfma_f32_32x32x16_bf16 v[146:161], v[186:189], v[178:181], v[146:161]
	v_mfma_f32_32x32x16_bf16 v[130:145], v[230:233], v[178:181], v[130:145]
	v_mfma_f32_32x32x16_bf16 v[146:161], v[190:193], v[182:185], v[146:161]
	v_mfma_f32_32x32x16_bf16 v[130:145], v[234:237], v[182:185], v[130:145]
	global_load_dwordx4 v[178:181], v[198:199], off offset:384
	global_load_dwordx4 v[182:185], v[198:199], off offset:416
	ds_read_b128 v[186:189], v0 offset:384
	ds_read_b128 v[190:193], v0 offset:416
	ds_read_b128 v[230:233], v0 offset:17280
	ds_read_b128 v[234:237], v0 offset:17312
	s_waitcnt vmcnt(0) lgkmcnt(0)
	v_mfma_f32_32x32x16_bf16 v[146:161], v[186:189], v[178:181], v[146:161]
	v_mfma_f32_32x32x16_bf16 v[130:145], v[230:233], v[178:181], v[130:145]
	v_mfma_f32_32x32x16_bf16 v[146:161], v[190:193], v[182:185], v[146:161]
	v_mfma_f32_32x32x16_bf16 v[130:145], v[234:237], v[182:185], v[130:145]
	global_load_dwordx4 v[178:181], v[198:199], off offset:448
	global_load_dwordx4 v[232:235], v[198:199], off offset:480
	ds_read_b128 v[182:185], v0 offset:448
	ds_read_b128 v[186:189], v0 offset:480
	ds_read_b128 v[190:193], v0 offset:17344
	ds_read_b128 v[236:239], v0 offset:17376
	s_waitcnt vmcnt(0) lgkmcnt(0)
	v_mfma_f32_32x32x16_bf16 v[146:161], v[182:185], v[178:181], v[146:161]
	s_mul_i32 s28, s28, 0x8800
	v_add_u32_e32 v230, s28, v224
	v_mfma_f32_32x32x16_bf16 v[130:145], v[190:193], v[178:181], v[130:145]
	v_mfma_f32_32x32x16_bf16 v[146:161], v[186:189], v[232:235], v[146:161]
	ds_read2_b64 v[190:193], v230 offset1:2
	ds_read2_b64 v[186:189], v230 offset0:4 offset1:6
	ds_read2_b64 v[182:185], v230 offset0:8 offset1:10
	ds_read2_b64 v[178:181], v230 offset0:12 offset1:14
	v_mfma_f32_32x32x16_bf16 v[130:145], v[236:239], v[232:235], v[130:145]
	s_nop 11
	v_max_f32_e32 v231, v131, v131
	v_max_f32_e32 v232, v130, v130
	v_max_f32_e32 v231, v232, v231
	v_max3_f32 v0, v146, v147, v148
	v_max3_f32 v231, v231, v132, v133
	v_max3_f32 v0, v0, v149, v150
	v_max3_f32 v231, v231, v134, v135
	v_max3_f32 v0, v0, v151, v152
	v_max3_f32 v231, v231, v136, v137
	v_max3_f32 v0, v0, v153, v154
	v_max3_f32 v231, v231, v138, v139
	v_max3_f32 v0, v0, v155, v156
	v_max3_f32 v231, v231, v140, v141
	v_max3_f32 v0, v0, v157, v158
	v_max3_f32 v231, v231, v142, v143
	v_max3_f32 v0, v0, v159, v160
	v_max3_f32 v231, v231, v144, v145
	v_max3_f32 v0, v0, v161, v231
	v_mov_b32_e32 v231, v0
	s_nop 1
	v_permlane32_swap_b32_e32 v0, v231
	v_max_f32_e32 v231, v231, v231
	v_max_f32_e32 v0, v0, v0
	v_max_f32_e32 v0, v0, v231
	s_cmp_eq_u32 s24, 0
	s_cselect_b64 s[26:27], -1, 0
	s_cmp_lg_u32 s24, 0
	v_cmp_lt_f32_e32 vcc, s51, v0
	s_cbranch_scc0 .LBB0_1246
	s_cmp_lg_u64 vcc, 0
	s_cselect_b64 s[28:29], -1, 0
	s_cbranch_execz .LBB0_1247
	s_branch .LBB0_1248

; #define OUTP() ((float*)tab_get(lds, 30))
; #define WSB(off) ((bf16*)((unsigned char*)tab_get(lds, 31) + (off)))
;     __device__ __forceinline__ void operator()(EPI_ARGS) const {
;         const int row0 = u.pm * BM + wr * 64 + fr, col0 = u.pn * BM + wc * 32 + 8 * fq;
; #pragma unroll
;         for (int ai = 0; ai < 2; ++ai)
; #pragma unroll
;             for (int m = 0; m < 4; ++m) { const int row = row0 + ai * HALF + m * 16;
;                 const float* b = base + (size_t)row * DM + col0; float* o = X + (size_t)row * DM + col0;
; #pragma unroll
;                 for (int bj = 0; bj < 2; ++bj) { const f32x4 b0 = *(const f32x4*)(b + bj * HALF), b1 = *(const f32x4*)(b + bj * HALF + 4);
;                     *(f32x4*)(o + bj * HALF) = b0 + acc[ai][bj][m][0]; *(f32x4*)(o + bj * HALF + 4) = b1 + acc[ai][bj][m][1]; } }
;     }
; __global__ void __launch_bounds__(512, 2) mega_fwd(Params p) {
;     ...
;     { float* X = OUTP(); pg8::Gemm g{WSB(WS_OC), WSB(WS_WCO), MP, 1024, 1024, 1024, 1024}; pg8::StaticOrder S; S.init(MP, 1024, G, bx); pg8::EpiResid E{X, X}; pg8::gemm_phase(lds, g, S, E); }
.LBB0_1314:
	v_lshl_add_u32 v148, s30, 8, v150
	v_lshl_or_b32 v144, s31, 8, v152
	v_ashrrev_i32_e32 v149, 31, v148
	v_ashrrev_i32_e32 v145, 31, v144
	v_lshlrev_b64 v[146:147], 12, v[148:149]
	v_lshl_add_u64 v[156:157], s[6:7], 0, v[146:147]
	v_lshlrev_b64 v[146:147], 2, v[144:145]
	v_lshl_add_u64 v[144:145], v[156:157], 0, v[146:147]
	global_load_dwordx4 v[156:159], v[144:145], off
	global_load_dwordx4 v[160:163], v[144:145], off offset:16
	s_mov_b64 s[30:31], -1
	s_waitcnt vmcnt(0) lgkmcnt(0)
	v_pk_add_f32 v[126:127], v[126:127], v[158:159]
	v_pk_add_f32 v[124:125], v[124:125], v[156:157]
	v_pk_add_f32 v[122:123], v[122:123], v[162:163]
	v_pk_add_f32 v[120:121], v[120:121], v[160:161]
	global_store_dwordx4 v[144:145], v[124:127], off
	global_store_dwordx4 v[144:145], v[120:123], off offset:16
	global_load_dwordx4 v[120:123], v[144:145], off offset:512
	s_nop 0
	global_load_dwordx4 v[124:127], v[144:145], off offset:528
	s_waitcnt vmcnt(0) lgkmcnt(0)
	v_pk_add_f32 v[118:119], v[118:119], v[122:123]
	v_pk_add_f32 v[114:115], v[114:115], v[126:127]
	v_pk_add_f32 v[112:113], v[112:113], v[124:125]
	global_store_dwordx4 v[144:145], v[112:115], off offset:528
	v_pk_add_f32 v[116:117], v[116:117], v[120:121]
	global_store_dwordx4 v[144:145], v[116:119], off offset:512
	v_or_b32_e32 v112, 16, v148
	v_ashrrev_i32_e32 v113, 31, v112
	v_lshlrev_b64 v[112:113], 12, v[112:113]
	v_lshl_add_u64 v[112:113], s[6:7], 0, v[112:113]
	v_lshl_add_u64 v[120:121], v[112:113], 0, v[146:147]
	global_load_dwordx4 v[112:115], v[120:121], off
	global_load_dwordx4 v[116:119], v[120:121], off offset:16
	s_waitcnt vmcnt(0) lgkmcnt(0)
	v_pk_add_f32 v[110:111], v[110:111], v[114:115]
	v_pk_add_f32 v[108:109], v[108:109], v[112:113]
	v_pk_add_f32 v[106:107], v[106:107], v[118:119]
	v_pk_add_f32 v[104:105], v[104:105], v[116:117]
	global_store_dwordx4 v[120:121], v[108:111], off
	global_store_dwordx4 v[120:121], v[104:107], off offset:16
	global_load_dwordx4 v[104:107], v[120:121], off offset:512
	s_nop 0
	global_load_dwordx4 v[108:111], v[120:121], off offset:528
	s_waitcnt vmcnt(0) lgkmcnt(0)
	v_pk_add_f32 v[102:103], v[102:103], v[106:107]
	v_pk_add_f32 v[98:99], v[98:99], v[110:111]
	v_pk_add_f32 v[96:97], v[96:97], v[108:109]
	global_store_dwordx4 v[120:121], v[96:99], off offset:528
	v_pk_add_f32 v[100:101], v[100:101], v[104:105]
	global_store_dwordx4 v[120:121], v[100:103], off offset:512
	v_or_b32_e32 v96, 32, v148
	v_ashrrev_i32_e32 v97, 31, v96
	v_lshlrev_b64 v[96:97], 12, v[96:97]
	v_lshl_add_u64 v[96:97], s[6:7], 0, v[96:97]
	v_lshl_add_u64 v[104:105], v[96:97], 0, v[146:147]
	global_load_dwordx4 v[96:99], v[104:105], off
	global_load_dwordx4 v[100:103], v[104:105], off offset:16
	s_waitcnt vmcnt(0) lgkmcnt(0)
	v_pk_add_f32 v[94:95], v[94:95], v[98:99]
	v_pk_add_f32 v[92:93], v[92:93], v[96:97]
	v_pk_add_f32 v[90:91], v[90:91], v[102:103]
	v_pk_add_f32 v[88:89], v[88:89], v[100:101]
	global_store_dwordx4 v[104:105], v[92:95], off
	global_store_dwordx4 v[104:105], v[88:91], off offset:16
	global_load_dwordx4 v[88:91], v[104:105], off offset:512
	s_nop 0
	global_load_dwordx4 v[92:95], v[104:105], off offset:528
	s_waitcnt vmcnt(0) lgkmcnt(0)
	v_pk_add_f32 v[86:87], v[86:87], v[90:91]
	v_pk_add_f32 v[82:83], v[82:83], v[94:95]
	v_pk_add_f32 v[80:81], v[80:81], v[92:93]
	global_store_dwordx4 v[104:105], v[80:83], off offset:528
	v_pk_add_f32 v[84:85], v[84:85], v[88:89]
	global_store_dwordx4 v[104:105], v[84:87], off offset:512
	v_or_b32_e32 v80, 48, v148
	v_ashrrev_i32_e32 v81, 31, v80
	v_lshlrev_b64 v[80:81], 12, v[80:81]
	v_lshl_add_u64 v[80:81], s[6:7], 0, v[80:81]
	v_lshl_add_u64 v[88:89], v[80:81], 0, v[146:147]
	global_load_dwordx4 v[80:83], v[88:89], off
	global_load_dwordx4 v[84:87], v[88:89], off offset:16
	s_waitcnt vmcnt(0) lgkmcnt(0)
	v_pk_add_f32 v[78:79], v[78:79], v[82:83]
	v_pk_add_f32 v[76:77], v[76:77], v[80:81]
	v_pk_add_f32 v[74:75], v[74:75], v[86:87]
	v_pk_add_f32 v[72:73], v[72:73], v[84:85]
	global_store_dwordx4 v[88:89], v[76:79], off
	global_store_dwordx4 v[88:89], v[72:75], off offset:16
	global_load_dwordx4 v[72:75], v[88:89], off offset:512
	s_nop 0
	global_load_dwordx4 v[76:79], v[88:89], off offset:528
	s_waitcnt vmcnt(0) lgkmcnt(0)
;     __device__ __forceinline__ void operator()(EPI_ARGS) const {
;         const int row0 = u.pm * BM + wr * 64 + fr, col0 = u.pn * BM + wc * 32 + 8 * fq;
; #pragma unroll
;         for (int ai = 0; ai < 2; ++ai)
; #pragma unroll
;             for (int m = 0; m < 4; ++m) { const int row = row0 + ai * HALF + m * 16;
;                 const float* b = base + (size_t)row * DM + col0; float* o = X + (size_t)row * DM + col0;
; #pragma unroll
;                 for (int bj = 0; bj < 2; ++bj) { const f32x4 b0 = *(const f32x4*)(b + bj * HALF), b1 = *(const f32x4*)(b + bj * HALF + 4);
;                     *(f32x4*)(o + bj * HALF) = b0 + acc[ai][bj][m][0]; *(f32x4*)(o + bj * HALF + 4) = b1 + acc[ai][bj][m][1]; } }
;     }
	v_pk_add_f32 v[70:71], v[70:71], v[74:75]
	v_pk_add_f32 v[68:69], v[68:69], v[72:73]
	v_pk_add_f32 v[66:67], v[66:67], v[78:79]
	v_pk_add_f32 v[64:65], v[64:65], v[76:77]
	v_add_co_u32_e32 v74, vcc, s60, v144
	global_store_dwordx4 v[88:89], v[68:71], off offset:512
	global_store_dwordx4 v[88:89], v[64:67], off offset:528
	v_addc_co_u32_e32 v75, vcc, 0, v145, vcc
	v_lshl_add_u64 v[72:73], v[144:145], 0, s[14:15]
	global_load_dwordx4 v[64:67], v[74:75], off
	global_load_dwordx4 v[68:71], v[72:73], off offset:16
	s_waitcnt vmcnt(0) lgkmcnt(0)
	v_pk_add_f32 v[62:63], v[62:63], v[66:67]
	v_pk_add_f32 v[60:61], v[60:61], v[64:65]
	v_pk_add_f32 v[58:59], v[58:59], v[70:71]
	v_pk_add_f32 v[56:57], v[56:57], v[68:69]
	global_store_dwordx4 v[74:75], v[60:63], off
	global_store_dwordx4 v[72:73], v[56:59], off offset:16
	global_load_dwordx4 v[56:59], v[72:73], off offset:512
	s_nop 0
	global_load_dwordx4 v[60:63], v[72:73], off offset:528
	s_waitcnt vmcnt(0) lgkmcnt(0)
	v_pk_add_f32 v[54:55], v[54:55], v[58:59]
	v_pk_add_f32 v[52:53], v[52:53], v[56:57]
	v_pk_add_f32 v[50:51], v[50:51], v[62:63]
	v_pk_add_f32 v[48:49], v[48:49], v[60:61]
	v_add_co_u32_e32 v58, vcc, s61, v144
	global_store_dwordx4 v[72:73], v[52:55], off offset:512
	global_store_dwordx4 v[72:73], v[48:51], off offset:528
	v_addc_co_u32_e32 v59, vcc, 0, v145, vcc
	v_lshl_add_u64 v[56:57], v[144:145], 0, s[16:17]
	global_load_dwordx4 v[48:51], v[58:59], off
	global_load_dwordx4 v[52:55], v[56:57], off offset:16
	s_waitcnt vmcnt(0) lgkmcnt(0)
	v_pk_add_f32 v[46:47], v[46:47], v[50:51]
	v_pk_add_f32 v[44:45], v[44:45], v[48:49]
	v_pk_add_f32 v[42:43], v[42:43], v[54:55]
	v_pk_add_f32 v[40:41], v[40:41], v[52:53]
	global_store_dwordx4 v[58:59], v[44:47], off
	global_store_dwordx4 v[56:57], v[40:43], off offset:16
	global_load_dwordx4 v[40:43], v[56:57], off offset:512
	s_nop 0
	global_load_dwordx4 v[44:47], v[56:57], off offset:528
	s_waitcnt vmcnt(0) lgkmcnt(0)
	v_pk_add_f32 v[38:39], v[38:39], v[42:43]
	v_pk_add_f32 v[36:37], v[36:37], v[40:41]
	v_pk_add_f32 v[34:35], v[34:35], v[46:47]
	v_pk_add_f32 v[32:33], v[32:33], v[44:45]
	v_add_co_u32_e32 v42, vcc, s62, v144
	global_store_dwordx4 v[56:57], v[36:39], off offset:512
	global_store_dwordx4 v[56:57], v[32:35], off offset:528
	v_addc_co_u32_e32 v43, vcc, 0, v145, vcc
	v_lshl_add_u64 v[40:41], v[144:145], 0, s[18:19]
	global_load_dwordx4 v[32:35], v[42:43], off
	global_load_dwordx4 v[36:39], v[40:41], off offset:16
	s_waitcnt vmcnt(0) lgkmcnt(0)
	v_pk_add_f32 v[30:31], v[30:31], v[34:35]
	v_pk_add_f32 v[28:29], v[28:29], v[32:33]
	v_pk_add_f32 v[26:27], v[26:27], v[38:39]
	v_pk_add_f32 v[24:25], v[24:25], v[36:37]
	global_store_dwordx4 v[42:43], v[28:31], off
	global_store_dwordx4 v[40:41], v[24:27], off offset:16
	global_load_dwordx4 v[24:27], v[40:41], off offset:512
	s_nop 0
	global_load_dwordx4 v[28:31], v[40:41], off offset:528
	s_waitcnt vmcnt(0) lgkmcnt(0)
	v_pk_add_f32 v[22:23], v[22:23], v[26:27]
	v_pk_add_f32 v[20:21], v[20:21], v[24:25]
	v_pk_add_f32 v[18:19], v[18:19], v[30:31]
	v_pk_add_f32 v[16:17], v[16:17], v[28:29]
	v_add_co_u32_e32 v26, vcc, s63, v144
	global_store_dwordx4 v[40:41], v[20:23], off offset:512
	global_store_dwordx4 v[40:41], v[16:19], off offset:528
	v_addc_co_u32_e32 v27, vcc, 0, v145, vcc
	s_nop 0
	v_lshl_add_u64 v[16:17], v[144:145], 0, s[20:21]
	global_load_dwordx4 v[18:21], v[26:27], off
	global_load_dwordx4 v[22:25], v[16:17], off offset:16
	s_andn2_b64 vcc, exec, s[4:5]
	s_waitcnt vmcnt(0) lgkmcnt(0)
	v_pk_add_f32 v[14:15], v[14:15], v[20:21]
	v_pk_add_f32 v[12:13], v[12:13], v[18:19]
	v_pk_add_f32 v[10:11], v[10:11], v[24:25]
	v_pk_add_f32 v[8:9], v[8:9], v[22:23]
	global_store_dwordx4 v[26:27], v[12:15], off
	global_store_dwordx4 v[16:17], v[8:11], off offset:16
	global_load_dwordx4 v[8:11], v[16:17], off offset:512
	s_nop 0
	global_load_dwordx4 v[12:15], v[16:17], off offset:528
	s_waitcnt vmcnt(0) lgkmcnt(0)
	v_pk_add_f32 v[6:7], v[6:7], v[10:11]
	v_pk_add_f32 v[4:5], v[4:5], v[8:9]
	v_pk_add_f32 v[2:3], v[2:3], v[14:15]
	v_pk_add_f32 v[0:1], v[0:1], v[12:13]
	global_store_dwordx4 v[16:17], v[4:7], off offset:512
	global_store_dwordx4 v[16:17], v[0:3], off offset:528
	s_cbranch_vccnz .LBB0_1303
	s_andn2_b64 vcc, exec, s[8:9]
	s_cbranch_vccnz .LBB0_1302
	s_barrier
	s_branch .LBB0_1302

; #define QNEXT(ctrw, dst) do { __syncthreads(); if (my_tid(lds) == 0) *(volatile LAS int*)(lds + TAB_OFF + 264) = (int)atomicAdd((unsigned*)tab_get(lds, 31) + 8192 + 64 * (ctrw), 1u); \
;         __syncthreads(); dst = __builtin_amdgcn_readfirstlane(*(volatile LAS int*)(lds + TAB_OFF + 264)); } while (0)
; __global__ void __launch_bounds__(512, 2) mega_fwd(Params p) {
;     ...
;         for (;;) { int it; QNEXT(3, it); if (it >= 128 + MP / 64) break;
.LBB0_1365:
	s_barrier
	s_getreg_b32 s4, hwreg(HW_REG_HW_ID, 0, 6)
	s_lshl_b32 s4, s4, 2
	s_and_b32 s4, s4, 0xfc
	s_add_i32 s4, s4, 0
	s_add_i32 s4, s4, 0x25a00
	v_mov_b32_e32 v0, s4
	ds_read_b32 v0, v0
	v_mbcnt_lo_u32_b32 v1, -1, 0
	v_mbcnt_hi_u32_b32 v1, -1, v1
	s_waitcnt lgkmcnt(0)
	v_readfirstlane_b32 s4, v0
	s_lshl_b32 s4, s4, 6
	v_sub_u32_e32 v0, 0, v1
	v_cmp_eq_u32_e32 vcc, s4, v0
	s_and_saveexec_b64 s[4:5], vcc
	s_cbranch_execz .LBB0_1367
	ds_read_b64 v[0:1], v21
	s_waitcnt lgkmcnt(0)
	v_readfirstlane_b32 s15, v0
	v_readfirstlane_b32 s14, v1
	s_nop 0
	v_mov_b32_e32 v0, s15
	v_add_co_u32_e32 v0, vcc, 0x8000, v0
	v_mov_b32_e32 v1, s14
	s_nop 0
	v_addc_co_u32_e32 v1, vcc, 0, v1, vcc
	global_atomic_add v0, v[0:1], v26, off offset:768 sc0
	s_waitcnt vmcnt(0) lgkmcnt(0)
	ds_write_b32 v27, v0

; __device__ __forceinline__ unsigned pk2(float lo, float hi) { const f32x2 v = {lo, hi}; return __builtin_bit_cast(unsigned, __builtin_convertvector(v, bf16x2_t)); }
; __device__ __forceinline__ float wave_sum(float v) { v += swz_xor<1>(v); v += swz_xor<2>(v); v += swz_xor<4>(v); v += swz_xor<8>(v); v += swz_xor<16>(v); return half_sum(v); }
; __device__ __forceinline__ void rms_row2_to_bf16(const float* x0, const float* x1, const float* g, bf16* o0, bf16* o1, int lane) {
;     const f32x4* xr0 = (const f32x4*)x0 + lane; const f32x4* xr1 = (const f32x4*)x1 + lane; f32x4 v[4], w[4]; float s = 0.f, t = 0.f;
; #pragma unroll
;     for (int j = 0; j < 4; ++j) { v[j] = xr0[64 * j]; w[j] = xr1[64 * j]; }
; #pragma unroll
;     for (int j = 0; j < 4; ++j) { s += (v[j].x * v[j].x + v[j].y * v[j].y) + (v[j].z * v[j].z + v[j].w * v[j].w); t += (w[j].x * w[j].x + w[j].y * w[j].y) + (w[j].z * w[j].z + w[j].w * w[j].w); }
;     const float r0 = rsqrtf(wave_sum(s) * (1.f / DM) + EPS), r1 = rsqrtf(wave_sum(t) * (1.f / DM) + EPS);
;     u32x2* p0 = (u32x2*)o0 + lane; u32x2* p1 = (u32x2*)o1 + lane;
; #pragma unroll
;     for (int j = 0; j < 4; ++j) { const f32x4 gg = ((const f32x4*)g)[lane + 64 * j]; u32x2 a, b;
;         a.x = pk2(v[j].x * r0 * gg.x, v[j].y * r0 * gg.y); a.y = pk2(v[j].z * r0 * gg.z, v[j].w * r0 * gg.w); b.x = pk2(w[j].x * r1 * gg.x, w[j].y * r1 * gg.y); b.y = pk2(w[j].z * r1 * gg.z, w[j].w * r1 * gg.w);
;         p0[64 * j] = a; p1[64 * j] = b; }
.LBB0_1370:
	global_load_dwordx4 v[28:31], v[24:25], off
	global_load_dwordx4 v[8:11], v[24:25], off offset:1024
	global_load_dwordx4 v[0:3], v[24:25], off offset:3072
	global_load_dwordx4 v[4:7], v[24:25], off offset:2048
	v_add_co_u32_e32 v52, vcc, 0x1000, v24
	global_load_dwordx4 v[32:35], v[14:15], off
	s_nop 0
	v_addc_co_u32_e32 v53, vcc, 0, v25, vcc
	global_load_dwordx4 v[36:39], v[52:53], off
	global_load_dwordx4 v[40:43], v[52:53], off offset:1024
	global_load_dwordx4 v[44:47], v[52:53], off offset:3072
	global_load_dwordx4 v[48:51], v[52:53], off offset:2048
	s_add_i32 s14, s14, 2
	v_lshl_add_u64 v[24:25], v[24:25], 0, s[10:11]
	s_cmp_gt_u32 s14, 5
	s_waitcnt vmcnt(0) lgkmcnt(0)
	v_pk_mul_f32 v[52:53], v[30:31], v[30:31]
	v_pk_mul_f32 v[54:55], v[28:29], v[28:29]
	v_pk_mul_f32 v[56:57], v[10:11], v[10:11]
	v_pk_mul_f32 v[58:59], v[8:9], v[8:9]
	v_mul_f32_e32 v60, v7, v7
	v_pk_mov_b32 v[62:63], v[54:55], v[52:53] op_sel:[1,0]
	v_mov_b32_e32 v55, v53
	v_pk_mov_b32 v[52:53], v[58:59], v[56:57] op_sel:[1,0]
	v_mov_b32_e32 v59, v57
	v_mul_f32_e32 v70, v3, v3
	v_mul_f32_e32 v12, v5, v5
	v_pk_fma_f32 v[60:61], v[6:7], v[6:7], v[60:61] op_sel_hi:[1,1,0]
	v_pk_add_f32 v[54:55], v[62:63], v[54:55]
	v_pk_mul_f32 v[62:63], v[38:39], v[38:39]
	v_pk_mul_f32 v[64:65], v[36:37], v[36:37]
	v_pk_add_f32 v[52:53], v[52:53], v[58:59]
	v_pk_mul_f32 v[58:59], v[42:43], v[42:43]
	v_pk_mul_f32 v[66:67], v[40:41], v[40:41]
	v_mul_f32_e32 v69, v0, v0
	v_mul_f32_e32 v72, v1, v1
	v_mul_f32_e32 v68, v2, v2
	v_pk_fma_f32 v[56:57], v[4:5], v[4:5], v[12:13] op_sel_hi:[1,1,0]
	v_mov_b32_e32 v61, v70
	v_pk_mov_b32 v[70:71], v[64:65], v[62:63] op_sel:[1,0]
	v_mov_b32_e32 v65, v63
	v_pk_mov_b32 v[62:63], v[66:67], v[58:59] op_sel:[1,0]
	v_mov_b32_e32 v67, v59
	v_pk_add_f32 v[54:55], v[54:55], v[54:55] op_sel:[0,1] op_sel_hi:[1,0]
	v_pk_add_f32 v[52:53], v[52:53], v[52:53] op_sel:[0,1] op_sel_hi:[1,0]
	v_mov_b32_e32 v57, v68
	v_mul_f32_e32 v12, v49, v49
	v_mul_f32_e32 v68, v51, v51
	v_pk_add_f32 v[64:65], v[70:71], v[64:65]
	v_pk_add_f32 v[62:63], v[62:63], v[66:67]
	v_mov_b32_e32 v55, v69
	v_mov_b32_e32 v53, v72
	v_mul_f32_e32 v73, v44, v44
	v_mul_f32_e32 v74, v45, v45
	v_mul_f32_e32 v75, v46, v46
	v_mul_f32_e32 v76, v47, v47
	v_pk_add_f32 v[56:57], v[56:57], v[60:61]
	v_pk_fma_f32 v[58:59], v[48:49], v[48:49], v[12:13] op_sel_hi:[1,1,0]
	v_pk_fma_f32 v[60:61], v[50:51], v[50:51], v[68:69] op_sel_hi:[1,1,0]
	v_pk_add_f32 v[52:53], v[54:55], v[52:53]
	v_pk_add_f32 v[54:55], v[64:65], v[64:65] op_sel:[0,1] op_sel_hi:[1,0]
	v_pk_add_f32 v[62:63], v[62:63], v[62:63] op_sel:[0,1] op_sel_hi:[1,0]
	v_mov_b32_e32 v59, v75
	v_mov_b32_e32 v61, v76
	v_pk_add_f32 v[52:53], v[52:53], v[56:57]
	v_mov_b32_e32 v55, v73
	v_mov_b32_e32 v63, v74
	v_pk_add_f32 v[58:59], v[58:59], v[60:61]
	v_add_f32_e32 v12, v52, v53
	v_pk_add_f32 v[52:53], v[54:55], v[62:63]
	ds_swizzle_b32 v54, v12 offset:swizzle(SWAP,1)
	v_pk_add_f32 v[52:53], v[52:53], v[58:59]
	s_waitcnt lgkmcnt(0)
	v_add_f32_e32 v12, v12, v54
	v_add_f32_e32 v52, v52, v53
	ds_swizzle_b32 v53, v52 offset:swizzle(SWAP,1)
	ds_swizzle_b32 v54, v12 offset:swizzle(SWAP,2)
	s_waitcnt lgkmcnt(1)
	v_add_f32_e32 v52, v52, v53
	ds_swizzle_b32 v53, v52 offset:swizzle(SWAP,2)
	s_waitcnt lgkmcnt(1)
	v_add_f32_e32 v12, v12, v54
	ds_swizzle_b32 v54, v12 offset:swizzle(SWAP,4)
	s_waitcnt lgkmcnt(1)
	v_add_f32_e32 v52, v52, v53
	ds_swizzle_b32 v53, v52 offset:swizzle(SWAP,4)
	s_waitcnt lgkmcnt(1)
	v_add_f32_e32 v12, v12, v54
	ds_swizzle_b32 v54, v12 offset:swizzle(SWAP,8)
	s_waitcnt lgkmcnt(1)
	v_add_f32_e32 v52, v52, v53
	ds_swizzle_b32 v53, v52 offset:swizzle(SWAP,8)
	s_waitcnt lgkmcnt(1)
	v_add_f32_e32 v12, v12, v54
	ds_swizzle_b32 v54, v12 offset:swizzle(SWAP,16)
	s_waitcnt lgkmcnt(1)
	v_add_f32_e32 v52, v52, v53
	ds_swizzle_b32 v56, v52 offset:swizzle(SWAP,16)
	s_waitcnt lgkmcnt(1)
	v_add_f32_e32 v53, v12, v54
	v_mov_b32_e32 v55, v53
	s_nop 1
	v_permlane32_swap_b32_e32 v53, v55
	s_waitcnt lgkmcnt(0)
	v_add_f32_e32 v52, v52, v56
	v_mov_b32_e32 v54, v52
	s_nop 1
	v_permlane32_swap_b32_e32 v52, v54
	v_pk_add_f32 v[52:53], v[52:53], v[54:55]
	s_nop 0
	v_pk_fma_f32 v[52:53], v[52:53], s[6:7], v[20:21] op_sel_hi:[1,0,0]
	s_nop 0
	v_mul_f32_e32 v12, 0x4b800000, v53
	v_cmp_gt_f32_e64 s[4:5], s23, v53
	v_mul_f32_e32 v54, 0x4b800000, v52
	v_cmp_gt_f32_e32 vcc, s23, v52
	v_cndmask_b32_e64 v12, v53, v12, s[4:5]
	v_rsq_f32_e32 v12, v12
	v_cndmask_b32_e32 v52, v52, v54, vcc
	v_rsq_f32_e32 v52, v52
	v_mul_f32_e32 v53, 0x45800000, v12
	v_cndmask_b32_e64 v12, v12, v53, s[4:5]
	v_mul_f32_e32 v54, 0x45800000, v52
	v_cndmask_b32_e32 v52, v52, v54, vcc
	v_pk_mul_f32 v[28:29], v[28:29], v[12:13] op_sel_hi:[1,0]
	v_pk_mul_f32 v[30:31], v[30:31], v[12:13] op_sel_hi:[1,0]
	v_pk_mul_f32 v[36:37], v[36:37], v[52:53] op_sel_hi:[1,0]
	v_pk_mul_f32 v[38:39], v[38:39], v[52:53] op_sel_hi:[1,0]
	v_pk_mul_f32 v[28:29], v[32:33], v[28:29]
	v_pk_mul_f32 v[30:31], v[34:35], v[30:31]
	v_pk_mul_f32 v[32:33], v[32:33], v[36:37]
	v_pk_mul_f32 v[34:35], v[34:35], v[38:39]
	v_cvt_pk_bf16_f32 v28, v28, v29
	v_cvt_pk_bf16_f32 v29, v30, v31
	v_cvt_pk_bf16_f32 v30, v32, v33
	v_cvt_pk_bf16_f32 v31, v34, v35
	global_store_dwordx2 v[22:23], v[28:29], off
	global_store_dwordx2 v[22:23], v[30:31], off offset:2048
	global_load_dwordx4 v[28:31], v[14:15], off offset:1024
	v_pk_mul_f32 v[8:9], v[8:9], v[12:13] op_sel_hi:[1,0]
	v_pk_mul_f32 v[10:11], v[10:11], v[12:13] op_sel_hi:[1,0]
	v_pk_mul_f32 v[32:33], v[40:41], v[52:53] op_sel_hi:[1,0]
	v_pk_mul_f32 v[34:35], v[42:43], v[52:53] op_sel_hi:[1,0]
	v_pk_mul_f32 v[4:5], v[4:5], v[12:13] op_sel_hi:[1,0]
	v_pk_mul_f32 v[6:7], v[6:7], v[12:13] op_sel_hi:[1,0]
	v_pk_mul_f32 v[0:1], v[0:1], v[12:13] op_sel_hi:[1,0]
	v_pk_mul_f32 v[2:3], v[2:3], v[12:13] op_sel_hi:[1,0]
	s_waitcnt vmcnt(0) lgkmcnt(0)
; #define LAS __attribute__((address_space(3)))
; __device__ __forceinline__ float bf2f(unsigned b) { return __uint_as_float(b << 16); }
; __device__ __forceinline__ unsigned pk2(float lo, float hi) { const f32x2 v = {lo, hi}; return __builtin_bit_cast(unsigned, __builtin_convertvector(v, bf16x2_t)); }
; __device__ __forceinline__ void rms_row2_to_bf16(const float* x0, const float* x1, const float* g, bf16* o0, bf16* o1, int lane) {
;     ...
;     for (int j = 0; j < 4; ++j) { const f32x4 gg = ((const f32x4*)g)[lane + 64 * j]; u32x2 a, b;
;         a.x = pk2(v[j].x * r0 * gg.x, v[j].y * r0 * gg.y); a.y = pk2(v[j].z * r0 * gg.z, v[j].w * r0 * gg.w); b.x = pk2(w[j].x * r1 * gg.x, w[j].y * r1 * gg.y); b.y = pk2(w[j].z * r1 * gg.z, w[j].w * r1 * gg.w);
;         p0[64 * j] = a; p1[64 * j] = b; }
; __device__ __forceinline__ void cross_sample_item(LAS unsigned char* lds, const bf16* QC, const float* mk, const float* mv, bf16* OC, int b, int hh) {
;     LAS float* qc = (LAS float*)lds;
;     LAS float* Pw = qc + 16 * 256;
;     LAS float* KT = Pw + 8 * 512;
;     const int tid_ = my_tid(lds); const int tid = tid_, lane = tid & 63; const int wid = __builtin_amdgcn_readfirstlane(tid >> 6);
;     const int rowbase = MP + b * 16;
; #pragma unroll
;     for (int i = 0; i < 8; ++i) { const int idx = tid + 512 * i, t = idx >> 8, e = idx & 255; qc[idx] = bf2f(QC[(size_t)(rowbase + t) * 1024 + hh * 256 + e]); }
;     const int t0 = 2 * wid; const LAS float* q0 = qc + t0 * 256; const LAS float* q1 = q0 + 256; LAS float* P = Pw + wid * 512;
;     float s0[4], s1[4];
; #pragma unroll 1
;     for (int jt = 0; jt < 4; ++jt) {
;         f32x4 st[8];
; #pragma unroll
;         for (int i = 0; i < 8; ++i) { const int ci = tid + 512 * i, key = ci >> 6, ch = ci & 63; st[i] = *(const f32x4*)(mk + ((size_t)(b * 256 + 64 * jt + key) * 4 + hh) * 256 + 4 * ch); }
;         __syncthreads();
; #pragma unroll
;         for (int i = 0; i < 8; ++i) { const int ci = tid + 512 * i, key = ci >> 6, ch = ci & 63; *(LAS f32x4*)(KT + key * 260 + 4 * ch) = st[i]; }
	v_pk_mul_f32 v[8:9], v[8:9], v[28:29]
	v_pk_mul_f32 v[10:11], v[10:11], v[30:31]
	v_pk_mul_f32 v[28:29], v[28:29], v[32:33]
	v_pk_mul_f32 v[30:31], v[30:31], v[34:35]
	v_cvt_pk_bf16_f32 v8, v8, v9
	v_cvt_pk_bf16_f32 v9, v10, v11
	v_cvt_pk_bf16_f32 v10, v28, v29
	v_cvt_pk_bf16_f32 v11, v30, v31
	global_store_dwordx2 v[22:23], v[8:9], off offset:512
	global_store_dwordx2 v[22:23], v[10:11], off offset:2560
	global_load_dwordx4 v[8:11], v[14:15], off offset:2048
	v_pk_mul_f32 v[28:29], v[48:49], v[52:53] op_sel_hi:[1,0]
	v_pk_mul_f32 v[30:31], v[50:51], v[52:53] op_sel_hi:[1,0]
	s_waitcnt vmcnt(0) lgkmcnt(0)
	v_pk_mul_f32 v[4:5], v[4:5], v[8:9]
	v_pk_mul_f32 v[6:7], v[6:7], v[10:11]
	v_pk_mul_f32 v[8:9], v[8:9], v[28:29]
	v_pk_mul_f32 v[10:11], v[10:11], v[30:31]
	v_cvt_pk_bf16_f32 v4, v4, v5
	v_cvt_pk_bf16_f32 v5, v6, v7
	v_cvt_pk_bf16_f32 v6, v8, v9
	v_cvt_pk_bf16_f32 v7, v10, v11
	global_store_dwordx2 v[22:23], v[4:5], off offset:1024
	global_store_dwordx2 v[22:23], v[6:7], off offset:3072
	global_load_dwordx4 v[4:7], v[14:15], off offset:3072
	v_pk_mul_f32 v[8:9], v[44:45], v[52:53] op_sel_hi:[1,0]
	v_pk_mul_f32 v[10:11], v[46:47], v[52:53] op_sel_hi:[1,0]
	s_waitcnt vmcnt(0) lgkmcnt(0)
	v_pk_mul_f32 v[0:1], v[0:1], v[4:5]
	v_pk_mul_f32 v[2:3], v[2:3], v[6:7]
	v_pk_mul_f32 v[4:5], v[8:9], v[4:5]
	v_pk_mul_f32 v[6:7], v[10:11], v[6:7]
	v_cvt_pk_bf16_f32 v0, v0, v1
	v_cvt_pk_bf16_f32 v1, v2, v3
	v_cvt_pk_bf16_f32 v2, v4, v5
	v_cvt_pk_bf16_f32 v3, v6, v7
	global_store_dwordx2 v[22:23], v[0:1], off offset:1536
	global_store_dwordx2 v[22:23], v[2:3], off offset:3584
	v_lshl_add_u64 v[22:23], v[22:23], 0, s[8:9]
	s_cbranch_scc0 .LBB0_1370
	s_mov_b64 s[4:5], 0
.LBB0_1372:
	s_and_b64 vcc, exec, s[4:5]
	s_cbranch_vccz .LBB0_1363
	s_getreg_b32 s4, hwreg(HW_REG_HW_ID, 0, 6)
	s_lshl_b32 s4, s4, 2
	s_and_b32 s4, s4, 0xfc
	s_add_i32 s4, s4, 0
	s_add_i32 s4, s4, 0x25a00
	v_mov_b32_e32 v0, s4
	ds_read_b32 v0, v0
	s_ashr_i32 s14, s28, 2
	v_mbcnt_lo_u32_b32 v30, -1, 0
	v_mbcnt_hi_u32_b32 v30, -1, v30
	s_lshl_b32 s27, s14, 4
	s_add_i32 s27, s27, 0x8000
	s_waitcnt lgkmcnt(0)
	v_readfirstlane_b32 s4, v0
	s_nop 1
	v_lshl_add_u32 v31, s4, 6, v30
	s_lshl_b32 s4, s28, 8
	s_and_b32 s26, s4, 0x300
	s_lshl_b32 s4, s26, 1
	s_add_u32 s4, s0, s4
	s_addc_u32 s5, s1, 0
	v_lshlrev_b32_sdwa v12, v26, v31 dst_sel:DWORD dst_unused:UNUSED_PAD src0_sel:DWORD src1_sel:BYTE_0
	v_add_u32_e32 v36, 0xa00, v31
	v_lshl_add_u64 v[0:1], s[4:5], 0, v[12:13]
	v_ashrrev_i32_e32 v12, 8, v36
	v_add_u32_e32 v37, 0xc00, v31
	v_ashrrev_i32_e32 v2, 8, v31
	v_add_u32_e32 v32, 0x200, v31
	v_add_u32_e32 v33, 0x400, v31
	v_add_u32_e32 v34, 0x600, v31
	v_add_u32_e32 v35, 0x800, v31
	v_add_u32_e32 v22, s27, v12
	v_ashrrev_i32_e32 v12, 8, v37
	v_add_u32_e32 v38, 0xe00, v31
	v_add_u32_e32 v2, s27, v2
	v_ashrrev_i32_e32 v4, 8, v32
	v_ashrrev_i32_e32 v6, 8, v33
	v_ashrrev_i32_e32 v8, 8, v34
	v_ashrrev_i32_e32 v10, 8, v35
	v_add_u32_e32 v24, s27, v12
	v_ashrrev_i32_e32 v12, 8, v38
	v_ashrrev_i32_e32 v3, 31, v2
	v_add_u32_e32 v4, s27, v4
	v_add_u32_e32 v6, s27, v6
	v_add_u32_e32 v8, s27, v8
	v_add_u32_e32 v10, s27, v10
	v_add_u32_e32 v28, s27, v12
	v_lshlrev_b64 v[2:3], 11, v[2:3]
	v_ashrrev_i32_e32 v5, 31, v4
	v_ashrrev_i32_e32 v7, 31, v6
	v_ashrrev_i32_e32 v9, 31, v8
	v_ashrrev_i32_e32 v11, 31, v10
	v_ashrrev_i32_e32 v23, 31, v22
	v_ashrrev_i32_e32 v25, 31, v24
	v_ashrrev_i32_e32 v29, 31, v28
	v_lshl_add_u64 v[2:3], v[0:1], 0, v[2:3]
	v_lshlrev_b64 v[4:5], 11, v[4:5]
	v_lshlrev_b64 v[6:7], 11, v[6:7]
	v_lshlrev_b64 v[8:9], 11, v[8:9]
	v_lshlrev_b64 v[10:11], 11, v[10:11]
	v_lshlrev_b64 v[22:23], 11, v[22:23]
	v_lshlrev_b64 v[24:25], 11, v[24:25]
	v_lshlrev_b64 v[28:29], 11, v[28:29]
	v_lshl_add_u64 v[4:5], v[0:1], 0, v[4:5]
	v_lshl_add_u64 v[6:7], v[0:1], 0, v[6:7]
	v_lshl_add_u64 v[8:9], v[0:1], 0, v[8:9]
	v_lshl_add_u64 v[10:11], v[0:1], 0, v[10:11]
	v_lshl_add_u64 v[22:23], v[0:1], 0, v[22:23]
	v_lshl_add_u64 v[24:25], v[0:1], 0, v[24:25]
	v_lshl_add_u64 v[0:1], v[0:1], 0, v[28:29]
	global_load_ushort v28, v[2:3], off
	global_load_ushort v29, v[4:5], off
	global_load_ushort v39, v[6:7], off
	global_load_ushort v40, v[8:9], off
	global_load_ushort v41, v[10:11], off
	global_load_ushort v42, v[22:23], off
	global_load_ushort v43, v[24:25], off
	global_load_ushort v44, v[0:1], off
	s_lshl_b32 s4, s14, 8
	v_readfirstlane_b32 s14, v31
	s_ashr_i32 s29, s14, 6
	s_lshl_b32 s14, s29, 11
	s_lshl_b32 s5, s26, 2
	s_add_i32 s30, s14, 0
	v_lshlrev_b32_e32 v0, 4, v30
	s_add_u32 s14, s18, s5
	v_and_b32_e32 v12, 0x3f0, v0
	s_addc_u32 s15, s17, 0
	v_and_b32_e32 v24, 63, v30
	v_lshl_add_u32 v2, v31, 2, 0
	v_add_u32_e32 v3, 0, v12
	v_lshl_add_u64 v[0:1], s[14:15], 0, v[12:13]
	v_ashrrev_i32_e32 v12, 6, v31
	v_ashrrev_i32_e32 v22, 6, v32
	v_ashrrev_i32_e32 v23, 6, v33
	v_ashrrev_i32_e32 v25, 6, v34
	v_ashrrev_i32_e32 v30, 6, v37
	v_ashrrev_i32_e32 v31, 6, v38
	s_mov_b32 s5, 0
	s_waitcnt vmcnt(0) lgkmcnt(0)
	v_lshlrev_b32_e32 v4, 16, v28
	v_lshlrev_b32_e32 v5, 16, v29
	v_lshlrev_b32_e32 v6, 16, v39
	v_lshlrev_b32_e32 v7, 16, v40
	v_lshlrev_b32_e32 v8, 16, v41
	v_lshlrev_b32_e32 v9, 16, v42
	v_lshlrev_b32_e32 v10, 16, v43
	v_lshlrev_b32_e32 v11, 16, v44
	v_ashrrev_i32_e32 v28, 6, v35
	v_ashrrev_i32_e32 v29, 6, v36
	ds_write2st64_b32 v2, v4, v5 offset1:8
	ds_write2st64_b32 v2, v6, v7 offset0:16 offset1:24
	ds_write2st64_b32 v2, v8, v9 offset0:32 offset1:40
	ds_write2st64_b32 v2, v10, v11 offset0:48 offset1:56
	v_mul_lo_u32 v2, v12, s24
	v_mul_lo_u32 v4, v22, s24
	v_mul_lo_u32 v5, v23, s24
	v_mul_lo_u32 v6, v25, s24
	v_mul_lo_u32 v7, v28, s24
	v_mul_lo_u32 v8, v29, s24
	v_mul_lo_u32 v9, v30, s24
	v_mul_lo_u32 v10, v31, s24
	v_mov_b32_e32 v11, s25
	v_mad_u32_u24 v33, v24, s24, v11
	v_add_u32_e32 v34, v3, v2
	v_add_u32_e32 v35, v3, v4
	v_add_u32_e32 v36, v3, v5
	v_add_u32_e32 v38, v3, v6
	v_add_u32_e32 v39, v3, v7
	v_add_u32_e32 v40, v3, v8
	v_add_u32_e32 v41, v3, v9
	v_add_u32_e32 v42, v3, v10
	s_branch .LBB0_1375

; #define LAS __attribute__((address_space(3)))
; __device__ __forceinline__ void cross_sample_item(LAS unsigned char* lds, const bf16* QC, const float* mk, const float* mv, bf16* OC, int b, int hh) {
;     ...
;     for (int jt = 0; jt < 4; ++jt) {
;         f32x4 st[8];
; #pragma unroll
;         for (int i = 0; i < 8; ++i) { const int ci = tid + 512 * i, key = ci >> 6, ch = ci & 63; st[i] = *(const f32x4*)(mk + ((size_t)(b * 256 + 64 * jt + key) * 4 + hh) * 256 + 4 * ch); }
;         __syncthreads();
; #pragma unroll
;         for (int i = 0; i < 8; ++i) { const int ci = tid + 512 * i, key = ci >> 6, ch = ci & 63; *(LAS f32x4*)(KT + key * 260 + 4 * ch) = st[i]; }
;         __syncthreads();
.LBB0_1375:
	s_lshl_b32 s14, s5, 6
	s_add_i32 s14, s14, s4
	v_add_u32_e32 v2, s14, v12
	v_ashrrev_i32_e32 v3, 31, v2
	v_add_u32_e32 v50, s14, v22
	v_lshlrev_b64 v[2:3], 12, v[2:3]
	v_ashrrev_i32_e32 v51, 31, v50
	v_lshl_add_u64 v[2:3], v[0:1], 0, v[2:3]
	v_lshlrev_b64 v[50:51], 12, v[50:51]
	v_lshl_add_u64 v[58:59], v[0:1], 0, v[50:51]
	global_load_dwordx4 v[50:53], v[2:3], off
	global_load_dwordx4 v[54:57], v[58:59], off
	v_add_u32_e32 v2, s14, v23
	v_ashrrev_i32_e32 v3, 31, v2
	v_add_u32_e32 v58, s14, v25
	v_lshlrev_b64 v[2:3], 12, v[2:3]
	v_ashrrev_i32_e32 v59, 31, v58
	v_lshl_add_u64 v[2:3], v[0:1], 0, v[2:3]
	v_lshlrev_b64 v[58:59], 12, v[58:59]
	v_lshl_add_u64 v[66:67], v[0:1], 0, v[58:59]
	global_load_dwordx4 v[58:61], v[2:3], off
	global_load_dwordx4 v[62:65], v[66:67], off
	v_add_u32_e32 v2, s14, v28
	v_ashrrev_i32_e32 v3, 31, v2
	v_add_u32_e32 v66, s14, v29
	v_lshlrev_b64 v[2:3], 12, v[2:3]
	v_ashrrev_i32_e32 v67, 31, v66
	v_lshl_add_u64 v[2:3], v[0:1], 0, v[2:3]
	v_lshlrev_b64 v[66:67], 12, v[66:67]
	v_lshl_add_u64 v[74:75], v[0:1], 0, v[66:67]
	global_load_dwordx4 v[66:69], v[2:3], off
	global_load_dwordx4 v[70:73], v[74:75], off
	v_add_u32_e32 v2, s14, v30
	v_ashrrev_i32_e32 v3, 31, v2
	v_add_u32_e32 v74, s14, v31
	v_lshlrev_b64 v[2:3], 12, v[2:3]
	v_ashrrev_i32_e32 v75, 31, v74
	v_lshl_add_u64 v[2:3], v[0:1], 0, v[2:3]
	v_lshlrev_b64 v[74:75], 12, v[74:75]
	v_lshl_add_u64 v[82:83], v[0:1], 0, v[74:75]
	global_load_dwordx4 v[74:77], v[2:3], off
	global_load_dwordx4 v[78:81], v[82:83], off
	v_mov_b32_e32 v2, 0
	s_mov_b32 s14, 0
	v_mov_b32_e32 v3, v2
	s_waitcnt lgkmcnt(0)
	s_barrier
	s_waitcnt vmcnt(0)
	ds_write_b128 v34, v[50:53] offset:32768
	ds_write_b128 v35, v[54:57] offset:32768
	ds_write_b128 v36, v[58:61] offset:32768
	ds_write_b128 v38, v[62:65] offset:32768
	ds_write_b128 v39, v[66:69] offset:32768
	ds_write_b128 v40, v[70:73] offset:32768
	ds_write_b128 v41, v[74:77] offset:32768
	ds_write_b128 v42, v[78:81] offset:32768
	s_waitcnt lgkmcnt(0)
	s_barrier

; __device__ __forceinline__ void cross_sample_item(LAS unsigned char* lds, const bf16* QC, const float* mk, const float* mv, bf16* OC, int b, int hh) {
;     ...
;     f32x4 o0 = {0.f, 0.f, 0.f, 0.f}, o1 = {0.f, 0.f, 0.f, 0.f};
;     const float* vbp = mv + ((size_t)(b * 256) * 4 + hh) * 256 + 4 * lane;
; #pragma unroll 1
;     for (int m0 = 0; m0 < 256; m0 += 16) { f32x4 vv[16];
; #pragma unroll
;         for (int i = 0; i < 16; ++i) vv[i] = *(const f32x4*)(vbp + (size_t)(m0 + i) * 1024);
; #pragma unroll
;         for (int i = 0; i < 16; ++i) { o0 += vv[i] * P[m0 + i]; o1 += vv[i] * P[256 + m0 + i]; } }
.LBB0_1388:
	v_add_co_u32_e32 v44, vcc, 0xffff1000, v6
	v_mov_b32_e32 v12, s4
	s_nop 0
	v_addc_co_u32_e32 v45, vcc, -1, v7, vcc
	v_add_co_u32_e32 v46, vcc, 0xffff2000, v6
	global_load_dwordx4 v[0:3], v[6:7], off
	s_nop 0
	v_addc_co_u32_e32 v47, vcc, -1, v7, vcc
	v_add_co_u32_e32 v52, vcc, 0xffff3000, v6
	ds_read_b128 v[32:35], v12
	s_nop 0
	v_addc_co_u32_e32 v53, vcc, -1, v7, vcc
	v_add_co_u32_e32 v54, vcc, 0xffff4000, v6
	global_load_dwordx4 v[36:39], v[44:45], off
	global_load_dwordx4 v[40:43], v[46:47], off
	v_addc_co_u32_e32 v55, vcc, -1, v7, vcc
	v_add_co_u32_e32 v60, vcc, 0xffff5000, v6
	global_load_dwordx4 v[44:47], v[52:53], off
	global_load_dwordx4 v[48:51], v[54:55], off
	v_addc_co_u32_e32 v61, vcc, -1, v7, vcc
	v_add_co_u32_e32 v62, vcc, 0xffff6000, v6
	s_add_i32 s4, s4, 64
	s_nop 0
	v_addc_co_u32_e32 v63, vcc, -1, v7, vcc
	v_add_co_u32_e32 v68, vcc, 0xffff7000, v6
	global_load_dwordx4 v[52:55], v[60:61], off
	global_load_dwordx4 v[56:59], v[62:63], off
	v_addc_co_u32_e32 v69, vcc, -1, v7, vcc
	v_add_co_u32_e32 v70, vcc, 0xffff8000, v6
	s_add_i32 s5, s5, 16
	s_nop 0
	v_addc_co_u32_e32 v71, vcc, -1, v7, vcc
	v_add_co_u32_e32 v76, vcc, 0xffff9000, v6
	global_load_dwordx4 v[60:63], v[68:69], off
	global_load_dwordx4 v[64:67], v[70:71], off
	v_addc_co_u32_e32 v77, vcc, -1, v7, vcc
	v_add_co_u32_e32 v78, vcc, 0xffffa000, v6
	s_cmpk_lt_u32 s5, 0xf0
	s_nop 0
	v_addc_co_u32_e32 v79, vcc, -1, v7, vcc
	v_add_co_u32_e32 v84, vcc, 0xffffb000, v6
	global_load_dwordx4 v[68:71], v[76:77], off
	global_load_dwordx4 v[72:75], v[78:79], off
	v_addc_co_u32_e32 v85, vcc, -1, v7, vcc
	v_add_co_u32_e32 v86, vcc, 0xffffc000, v6
	s_waitcnt vmcnt(0) lgkmcnt(0)
	v_pk_fma_f32 v[22:23], v[38:39], v[32:33], v[22:23] op_sel_hi:[1,0,1]
	v_addc_co_u32_e32 v87, vcc, -1, v7, vcc
	v_add_co_u32_e32 v88, vcc, 0xffffd000, v6
	global_load_dwordx4 v[76:79], v[84:85], off
	global_load_dwordx4 v[80:83], v[86:87], off
	v_addc_co_u32_e32 v89, vcc, -1, v7, vcc
	v_add_co_u32_e32 v90, vcc, s19, v6
	global_load_dwordx4 v[84:87], v[88:89], off
	s_nop 0
	v_addc_co_u32_e32 v91, vcc, -1, v7, vcc
	v_add_co_u32_e32 v92, vcc, 0xfffff000, v6
	v_pk_fma_f32 v[10:11], v[36:37], v[32:33], v[10:11] op_sel_hi:[1,0,1]
	s_nop 0
	v_addc_co_u32_e32 v93, vcc, -1, v7, vcc
	global_load_dwordx4 v[92:95], v[92:93], off
	v_pk_fma_f32 v[22:23], v[42:43], v[32:33], v[22:23] op_sel:[0,1,0]
	global_load_dwordx4 v[88:91], v[90:91], off
	ds_read_b128 v[96:99], v12 offset:16
	ds_read_b128 v[100:103], v12 offset:32
	ds_read_b128 v[104:107], v12 offset:48
	ds_read_b128 v[108:111], v12 offset:1024
	ds_read_b128 v[112:115], v12 offset:1040
	ds_read_b128 v[116:119], v12 offset:1056
	ds_read_b128 v[120:123], v12 offset:1072
	v_pk_fma_f32 v[10:11], v[40:41], v[32:33], v[10:11] op_sel:[0,1,0]
	s_waitcnt lgkmcnt(0)
	v_pk_fma_f32 v[8:9], v[38:39], v[108:109], v[8:9] op_sel_hi:[1,0,1]
	v_pk_fma_f32 v[4:5], v[36:37], v[108:109], v[4:5] op_sel_hi:[1,0,1]
	v_pk_fma_f32 v[8:9], v[42:43], v[108:109], v[8:9] op_sel:[0,1,0]
	v_pk_fma_f32 v[4:5], v[40:41], v[108:109], v[4:5] op_sel:[0,1,0]
	v_mov_b32_e32 v12, v35
	v_mov_b32_e32 v124, v111
	v_pk_fma_f32 v[22:23], v[46:47], v[34:35], v[22:23] op_sel_hi:[1,0,1]
	v_pk_fma_f32 v[10:11], v[44:45], v[34:35], v[10:11] op_sel_hi:[1,0,1]
	v_pk_fma_f32 v[8:9], v[46:47], v[110:111], v[8:9] op_sel_hi:[1,0,1]
	v_pk_fma_f32 v[4:5], v[44:45], v[110:111], v[4:5] op_sel_hi:[1,0,1]
	v_pk_fma_f32 v[22:23], v[50:51], v[12:13], v[22:23] op_sel_hi:[1,0,1]
	v_pk_fma_f32 v[10:11], v[48:49], v[12:13], v[10:11] op_sel_hi:[1,0,1]
	v_pk_fma_f32 v[8:9], v[50:51], v[124:125], v[8:9] op_sel_hi:[1,0,1]
	v_pk_fma_f32 v[4:5], v[48:49], v[124:125], v[4:5] op_sel_hi:[1,0,1]
	v_pk_fma_f32 v[22:23], v[54:55], v[96:97], v[22:23] op_sel_hi:[1,0,1]
	v_pk_fma_f32 v[10:11], v[52:53], v[96:97], v[10:11] op_sel_hi:[1,0,1]
	v_pk_fma_f32 v[8:9], v[54:55], v[112:113], v[8:9] op_sel_hi:[1,0,1]
	v_pk_fma_f32 v[4:5], v[52:53], v[112:113], v[4:5] op_sel_hi:[1,0,1]
	v_pk_fma_f32 v[22:23], v[58:59], v[96:97], v[22:23] op_sel:[0,1,0]
	v_pk_fma_f32 v[10:11], v[56:57], v[96:97], v[10:11] op_sel:[0,1,0]
	v_pk_fma_f32 v[8:9], v[58:59], v[112:113], v[8:9] op_sel:[0,1,0]
	v_pk_fma_f32 v[4:5], v[56:57], v[112:113], v[4:5] op_sel:[0,1,0]
	v_mov_b32_e32 v126, v99
	v_mov_b32_e32 v128, v115
	v_pk_fma_f32 v[22:23], v[62:63], v[98:99], v[22:23] op_sel_hi:[1,0,1]
	v_pk_fma_f32 v[10:11], v[60:61], v[98:99], v[10:11] op_sel_hi:[1,0,1]
	v_pk_fma_f32 v[8:9], v[62:63], v[114:115], v[8:9] op_sel_hi:[1,0,1]
	v_pk_fma_f32 v[4:5], v[60:61], v[114:115], v[4:5] op_sel_hi:[1,0,1]
	v_pk_fma_f32 v[22:23], v[66:67], v[126:127], v[22:23] op_sel_hi:[1,0,1]
	v_pk_fma_f32 v[10:11], v[64:65], v[126:127], v[10:11] op_sel_hi:[1,0,1]
	v_pk_fma_f32 v[8:9], v[66:67], v[128:129], v[8:9] op_sel_hi:[1,0,1]
	v_pk_fma_f32 v[4:5], v[64:65], v[128:129], v[4:5] op_sel_hi:[1,0,1]
	v_pk_fma_f32 v[22:23], v[70:71], v[100:101], v[22:23] op_sel_hi:[1,0,1]
	v_pk_fma_f32 v[10:11], v[68:69], v[100:101], v[10:11] op_sel_hi:[1,0,1]
	v_pk_fma_f32 v[8:9], v[70:71], v[116:117], v[8:9] op_sel_hi:[1,0,1]
	v_pk_fma_f32 v[4:5], v[68:69], v[116:117], v[4:5] op_sel_hi:[1,0,1]
	v_pk_fma_f32 v[22:23], v[74:75], v[100:101], v[22:23] op_sel:[0,1,0]
	v_pk_fma_f32 v[10:11], v[72:73], v[100:101], v[10:11] op_sel:[0,1,0]
	v_pk_fma_f32 v[8:9], v[74:75], v[116:117], v[8:9] op_sel:[0,1,0]
	v_pk_fma_f32 v[4:5], v[72:73], v[116:117], v[4:5] op_sel:[0,1,0]
	v_mov_b32_e32 v130, v103
	v_mov_b32_e32 v132, v119
	v_mov_b32_e32 v134, v107
	v_mov_b32_e32 v136, v123
	v_lshl_add_u64 v[6:7], v[6:7], 0, s[12:13]
	s_waitcnt vmcnt(0)
; __device__ __forceinline__ unsigned pk2(float lo, float hi) { const f32x2 v = {lo, hi}; return __builtin_bit_cast(unsigned, __builtin_convertvector(v, bf16x2_t)); }
; __device__ __forceinline__ float wave_sum(float v) { v += swz_xor<1>(v); v += swz_xor<2>(v); v += swz_xor<4>(v); v += swz_xor<8>(v); v += swz_xor<16>(v); return half_sum(v); }
; __device__ __forceinline__ void cross_sample_item(LAS unsigned char* lds, const bf16* QC, const float* mk, const float* mv, bf16* OC, int b, int hh) {
;     ...
;     sm0 = wave_sum(sm0); sm1 = wave_sum(sm1);
;     asm volatile("s_waitcnt lgkmcnt(0)" ::: "memory");
;     f32x4 o0 = {0.f, 0.f, 0.f, 0.f}, o1 = {0.f, 0.f, 0.f, 0.f};
;     const float* vbp = mv + ((size_t)(b * 256) * 4 + hh) * 256 + 4 * lane;
; #pragma unroll 1
;     for (int m0 = 0; m0 < 256; m0 += 16) { f32x4 vv[16];
; #pragma unroll
;         for (int i = 0; i < 16; ++i) vv[i] = *(const f32x4*)(vbp + (size_t)(m0 + i) * 1024);
; #pragma unroll
;         for (int i = 0; i < 16; ++i) { o0 += vv[i] * P[m0 + i]; o1 += vv[i] * P[256 + m0 + i]; } }
;     const float i0 = 1.f / sm0, i1 = 1.f / sm1; o0 = o0 * i0; o1 = o1 * i1;
;     u32x2 w0, w1; w0.x = pk2(o0.x, o0.y); w0.y = pk2(o0.z, o0.w); w1.x = pk2(o1.x, o1.y); w1.y = pk2(o1.z, o1.w);
;     *(u32x2*)(OC + (size_t)(rowbase + t0) * 1024 + hh * 256 + 4 * lane) = w0; *(u32x2*)(OC + (size_t)(rowbase + t0 + 1) * 1024 + hh * 256 + 4 * lane) = w1;
;     __syncthreads();
	v_pk_fma_f32 v[22:23], v[78:79], v[102:103], v[22:23] op_sel_hi:[1,0,1]
	v_pk_fma_f32 v[10:11], v[76:77], v[102:103], v[10:11] op_sel_hi:[1,0,1]
	v_pk_fma_f32 v[8:9], v[78:79], v[118:119], v[8:9] op_sel_hi:[1,0,1]
	v_pk_fma_f32 v[4:5], v[76:77], v[118:119], v[4:5] op_sel_hi:[1,0,1]
	v_pk_fma_f32 v[22:23], v[82:83], v[130:131], v[22:23] op_sel_hi:[1,0,1]
	v_pk_fma_f32 v[10:11], v[80:81], v[130:131], v[10:11] op_sel_hi:[1,0,1]
	v_pk_fma_f32 v[8:9], v[82:83], v[132:133], v[8:9] op_sel_hi:[1,0,1]
	v_pk_fma_f32 v[4:5], v[80:81], v[132:133], v[4:5] op_sel_hi:[1,0,1]
	v_pk_fma_f32 v[22:23], v[86:87], v[104:105], v[22:23] op_sel_hi:[1,0,1]
	v_pk_fma_f32 v[10:11], v[84:85], v[104:105], v[10:11] op_sel_hi:[1,0,1]
	v_pk_fma_f32 v[8:9], v[86:87], v[120:121], v[8:9] op_sel_hi:[1,0,1]
	v_pk_fma_f32 v[4:5], v[84:85], v[120:121], v[4:5] op_sel_hi:[1,0,1]
	v_pk_fma_f32 v[22:23], v[90:91], v[104:105], v[22:23] op_sel:[0,1,0]
	v_pk_fma_f32 v[10:11], v[88:89], v[104:105], v[10:11] op_sel:[0,1,0]
	v_pk_fma_f32 v[8:9], v[90:91], v[120:121], v[8:9] op_sel:[0,1,0]
	v_pk_fma_f32 v[4:5], v[88:89], v[120:121], v[4:5] op_sel:[0,1,0]
	v_pk_fma_f32 v[22:23], v[94:95], v[106:107], v[22:23] op_sel_hi:[1,0,1]
	v_pk_fma_f32 v[10:11], v[92:93], v[106:107], v[10:11] op_sel_hi:[1,0,1]
	v_pk_fma_f32 v[8:9], v[94:95], v[122:123], v[8:9] op_sel_hi:[1,0,1]
	v_pk_fma_f32 v[4:5], v[92:93], v[122:123], v[4:5] op_sel_hi:[1,0,1]
	v_pk_fma_f32 v[22:23], v[2:3], v[134:135], v[22:23] op_sel_hi:[1,0,1]
	v_pk_fma_f32 v[10:11], v[0:1], v[134:135], v[10:11] op_sel_hi:[1,0,1]
	v_pk_fma_f32 v[8:9], v[2:3], v[136:137], v[8:9] op_sel_hi:[1,0,1]
	v_pk_fma_f32 v[4:5], v[0:1], v[136:137], v[4:5] op_sel_hi:[1,0,1]
	s_cbranch_scc1 .LBB0_1388
	v_add_f32_e32 v0, v25, v28
	v_add_f32_e32 v1, v29, v30
	ds_swizzle_b32 v3, v0 offset:swizzle(SWAP,16)
	ds_swizzle_b32 v2, v1 offset:swizzle(SWAP,16)
	s_lshl_b32 s14, s29, 1
	s_waitcnt lgkmcnt(1)
	v_add_f32_e32 v0, v0, v3
	s_waitcnt lgkmcnt(0)
	v_add_f32_e32 v1, v1, v2
	v_mov_b32_e32 v2, v0
	s_nop 1
	v_permlane32_swap_b32_e32 v0, v2
	v_add_f32_e32 v0, v0, v2
	v_div_scale_f32 v2, s[4:5], v0, v0, 1.0
	v_rcp_f32_e32 v6, v2
	v_mov_b32_e32 v3, v1
	s_nop 1
	v_permlane32_swap_b32_e32 v1, v3
	v_add_f32_e32 v1, v1, v3
	v_fma_f32 v3, -v2, v6, 1.0
	v_fmac_f32_e32 v6, v3, v6
	v_div_scale_f32 v3, vcc, 1.0, v0, 1.0
	v_mul_f32_e32 v7, v3, v6
	v_fma_f32 v12, -v2, v7, v3
	v_fmac_f32_e32 v7, v12, v6
	v_fma_f32 v2, -v2, v7, v3
	v_div_scale_f32 v3, s[4:5], v1, v1, 1.0
	v_rcp_f32_e32 v12, v3
	s_add_i32 s4, s14, s27
	s_ashr_i32 s5, s4, 31
	s_lshl_b64 s[14:15], s[4:5], 11
	v_div_fmas_f32 v2, v2, v6, v7
	s_add_u32 s5, s7, s14
	v_div_fixup_f32 v0, v2, v0, 1.0
	v_fma_f32 v2, -v3, v12, 1.0
	s_addc_u32 s15, s16, s15
	s_lshl_b32 s26, s26, 1
	v_fmac_f32_e32 v12, v2, v12
	v_div_scale_f32 v2, vcc, 1.0, v1, 1.0
	s_add_u32 s14, s5, s26
	v_mul_f32_e32 v6, v2, v12
	s_addc_u32 s15, s15, 0
	s_or_b32 s4, s4, 1
	v_fma_f32 v7, -v3, v6, v2
	s_ashr_i32 s5, s4, 31
	v_fmac_f32_e32 v6, v7, v12
	s_lshl_b64 s[4:5], s[4:5], 11
	v_fma_f32 v2, -v3, v6, v2
	s_add_u32 s4, s7, s4
	v_div_fmas_f32 v2, v2, v12, v6
	s_addc_u32 s5, s16, s5
	v_div_fixup_f32 v2, v2, v1, 1.0
	v_pk_mul_f32 v[6:7], v[22:23], v[0:1] op_sel_hi:[1,0]
	v_pk_mul_f32 v[0:1], v[10:11], v[0:1] op_sel_hi:[1,0]
	v_lshlrev_b32_e32 v12, 3, v24
	s_add_u32 s4, s4, s26
	v_pk_mul_f32 v[8:9], v[8:9], v[2:3] op_sel_hi:[1,0]
	v_pk_mul_f32 v[2:3], v[4:5], v[2:3] op_sel_hi:[1,0]
	v_cvt_pk_bf16_f32 v0, v0, v1
	v_cvt_pk_bf16_f32 v1, v6, v7
	v_lshl_add_u64 v[4:5], s[14:15], 0, v[12:13]
	s_addc_u32 s5, s5, 0
	v_cvt_pk_bf16_f32 v2, v2, v3
	v_cvt_pk_bf16_f32 v3, v8, v9
	global_store_dwordx2 v[4:5], v[0:1], off
	v_lshl_add_u64 v[0:1], s[4:5], 0, v[12:13]
	global_store_dwordx2 v[0:1], v[2:3], off
	s_waitcnt lgkmcnt(0)
	s_barrier
	s_branch .LBB0_1363

; __device__ __forceinline__ unsigned pk2(float lo, float hi) { const f32x2 v = {lo, hi}; return __builtin_bit_cast(unsigned, __builtin_convertvector(v, bf16x2_t)); }
;     __device__ __forceinline__ void operator()(f32x4 (&acc)[2][2][4][2], const Unit& u, int, int, int, int) const {
;         const int tid = my_tid(lds), wid = __builtin_amdgcn_readfirstlane(tid >> 6), lane = tid & 63, wr = wid >> 2, wc = wid & 3, fr = lane & 15, fq = lane >> 4;
;         const int f0 = u.pn * 128 + wc * 32 + 8 * fq, rowt = u.pm * BM + wr * 64 + fr;
; #pragma unroll
;         for (int ai = 0; ai < 2; ++ai) { const int gidx = u.pm * 4 + ai * 2 + wr;
;             if (fr < 2) { bf16* h = HB + (size_t)(gidx * 4 + fr) * NUP + f0;
; #pragma unroll
;                 for (int bj = 0; bj < 2; ++bj) { const f32x4 v0 = acc[ai][bj][0][0], v1 = acc[ai][bj][0][1]; u32x4 w; w.x = pk2(v0[0], v0[1]); w.y = pk2(v0[2], v0[3]); w.z = pk2(v1[0], v1[1]); w.w = pk2(v1[2], v1[3]); *(u32x4*)(h + bj * NFF) = w; } }
;             if (fr >= 14) { bf16* h = HB + (size_t)(gidx * 4 + 2 + (fr - 14)) * NUP + f0; const int R = rowt + ai * HALF + 48, t = R & (SEQ - 1);
;                 float* co = (t >= SEQ - 2) ? out + O_PCONV + (size_t)((R >> 14) * 2 + (t - (SEQ - 2))) * NUP + f0 : nullptr;
; #pragma unroll
;                 for (int bj = 0; bj < 2; ++bj) { const f32x4 v0 = acc[ai][bj][3][0], v1 = acc[ai][bj][3][1]; u32x4 w; w.x = pk2(v0[0], v0[1]); w.y = pk2(v0[2], v0[3]); w.z = pk2(v1[0], v1[1]); w.w = pk2(v1[2], v1[3]); *(u32x4*)(h + bj * NFF) = w;
;                     if (co) { *(f32x4*)(co + bj * NFF) = v0; *(f32x4*)(co + bj * NFF + 4) = v1; } } }
;         }
.LBB0_1448:
	s_getreg_b32 s7, hwreg(HW_REG_HW_ID, 0, 6)
	s_lshl_b32 s7, s7, 2
	s_and_b32 s7, s7, 0xfc
	s_add_i32 s7, s7, 0
	s_add_i32 s7, s7, 0x25a00
	v_mov_b32_e32 v84, s7
	ds_read_b32 v84, v84
	v_mbcnt_lo_u32_b32 v85, -1, 0
	v_mbcnt_hi_u32_b32 v85, -1, v85
	s_lshl_b32 s6, s6, 7
	v_and_b32_e32 v89, 15, v85
	s_lshl_b32 s12, s10, 2
	s_waitcnt lgkmcnt(0)
	v_readfirstlane_b32 s7, v84
	v_cmp_gt_u32_e64 s[8:9], 2, v89
	s_nop 0
	v_lshl_add_u32 v84, s7, 6, v85
	s_nop 0
	v_readfirstlane_b32 s7, v84
	s_ashr_i32 s11, s7, 8
	s_lshr_b32 s7, s7, 1
	s_and_b32 s7, s7, 0x60
	s_or_b32 s6, s7, s6
	v_lshrrev_b32_e32 v84, 1, v85
	v_and_or_b32 v208, v84, 24, s6
	v_cmp_lt_u32_e64 s[6:7], 1, v89
	v_ashrrev_i32_e32 v209, 31, v208
	s_add_i32 s49, s11, s12
	s_and_saveexec_b64 s[12:13], s[8:9]
	s_cbranch_execz .LBB0_1450
	v_lshl_or_b32 v86, s49, 2, v89
	v_mov_b64_e32 v[84:85], s[22:23]
	v_mad_i64_i32 v[84:85], s[52:53], v86, s80, v[84:85]
	v_lshl_add_u64 v[90:91], v[208:209], 1, v[84:85]
	v_cvt_pk_bf16_f32 v84, v188, v189
	v_cvt_pk_bf16_f32 v85, v190, v191
	v_cvt_pk_bf16_f32 v86, v180, v181
	v_cvt_pk_bf16_f32 v87, v182, v183
	global_store_dwordx4 v[90:91], v[84:87], off
	v_add_co_u32_e32 v90, vcc, 0x1000, v90
	s_nop 0
	v_cvt_pk_bf16_f32 v84, v184, v185
	v_cvt_pk_bf16_f32 v85, v186, v187
	v_cvt_pk_bf16_f32 v86, v176, v177
	v_cvt_pk_bf16_f32 v87, v178, v179
	v_addc_co_u32_e32 v91, vcc, 0, v91, vcc
	global_store_dwordx4 v[90:91], v[84:87], off offset:1536
.LBB0_1450:
	s_or_b64 exec, exec, s[12:13]
	s_lshl_b32 s10, s10, 8
	s_lshl_b32 s51, s11, 6
	s_add_i32 s51, s51, s10
	v_or_b32_e32 v246, s51, v89
	v_cmp_lt_u32_e64 s[10:11], 13, v89
	v_add_u32_e32 v88, -12, v89
	s_and_saveexec_b64 s[58:59], s[10:11]
	s_cbranch_execz .LBB0_1457
	v_and_b32_e32 v86, 0x3fcf, v246
	v_cmp_lt_u32_e32 vcc, s81, v86
	v_mov_b64_e32 v[84:85], 0
	s_and_saveexec_b64 s[12:13], vcc
	s_ashr_i32 s51, s51, 13
	s_and_b32 s51, s51, 0xfffffe
	v_add_u32_e32 v84, s51, v86
	v_add_u32_e32 v84, 0xffffc032, v84
	v_mul_hi_i32_i24_e32 v85, 0x5800, v84
	v_mul_i32_i24_e32 v84, 0x5800, v84
	v_lshl_add_u64 v[84:85], s[28:29], 0, v[84:85]
	v_lshl_add_u64 v[84:85], v[208:209], 2, v[84:85]
	s_or_b64 exec, exec, s[12:13]
	v_lshl_add_u32 v90, s49, 2, v88
	v_mov_b64_e32 v[86:87], s[22:23]
	v_mad_i64_i32 v[86:87], s[12:13], v90, s80, v[86:87]
	v_lshl_add_u64 v[86:87], v[208:209], 1, v[86:87]
	v_cmp_ne_u64_e64 s[12:13], 0, v[84:85]
	v_cvt_pk_bf16_f32 v90, v120, v121
	v_cvt_pk_bf16_f32 v91, v122, v123
	v_cvt_pk_bf16_f32 v92, v72, v73
	v_cvt_pk_bf16_f32 v93, v74, v75
	global_store_dwordx4 v[86:87], v[90:93], off
	s_and_saveexec_b64 s[60:61], s[12:13]
	s_cbranch_execz .LBB0_1455
	global_store_dwordx4 v[84:85], v[120:123], off
	global_store_dwordx4 v[84:85], v[72:75], off offset:16
.LBB0_1455:
	s_or_b64 exec, exec, s[60:61]
	v_add_co_u32_e32 v86, vcc, 0x1000, v86
	v_cvt_pk_bf16_f32 v90, v80, v81
	v_cvt_pk_bf16_f32 v91, v82, v83
	v_cvt_pk_bf16_f32 v92, v64, v65
	v_cvt_pk_bf16_f32 v93, v66, v67
	v_addc_co_u32_e32 v87, vcc, 0, v87, vcc
	global_store_dwordx4 v[86:87], v[90:93], off offset:1536
	s_and_b64 exec, exec, s[12:13]
	s_cbranch_execz .LBB0_1457
	v_add_co_u32_e32 v84, vcc, 0x2000, v84
	s_nop 1
	v_addc_co_u32_e32 v85, vcc, 0, v85, vcc
	global_store_dwordx4 v[84:85], v[80:83], off offset:3072
	global_store_dwordx4 v[84:85], v[64:67], off offset:3088
.LBB0_1457:
	s_or_b64 exec, exec, s[58:59]
	s_add_i32 s49, s49, 2
	s_and_saveexec_b64 s[12:13], s[8:9]
	s_cbranch_execz .LBB0_1459
	v_lshl_or_b32 v86, s49, 2, v89
	v_mov_b64_e32 v[84:85], s[22:23]
	v_mad_i64_i32 v[84:85], s[8:9], v86, s80, v[84:85]
	v_lshl_add_u64 v[90:91], v[208:209], 1, v[84:85]
	v_cvt_pk_bf16_f32 v84, v60, v61
	v_cvt_pk_bf16_f32 v85, v62, v63
	v_cvt_pk_bf16_f32 v86, v52, v53
	v_cvt_pk_bf16_f32 v87, v54, v55
	global_store_dwordx4 v[90:91], v[84:87], off
	v_add_co_u32_e32 v90, vcc, 0x1000, v90
	s_nop 0
	v_cvt_pk_bf16_f32 v84, v56, v57
	v_cvt_pk_bf16_f32 v85, v58, v59
	v_cvt_pk_bf16_f32 v86, v48, v49
	v_cvt_pk_bf16_f32 v87, v50, v51
	v_addc_co_u32_e32 v91, vcc, 0, v91, vcc
	global_store_dwordx4 v[90:91], v[84:87], off offset:1536
.LBB0_1459:
	s_or_b64 exec, exec, s[12:13]
	v_add_u32_e32 v247, 0x80, v246
	s_and_saveexec_b64 s[12:13], s[10:11]
	s_cbranch_execz .LBB0_1466
	v_and_b32_e32 v86, 0x3fcf, v247
	v_cmp_lt_u32_e32 vcc, s81, v86
	v_mov_b64_e32 v[84:85], 0
	s_and_saveexec_b64 s[8:9], vcc
	v_ashrrev_i32_e32 v84, 13, v247
	v_and_b32_e32 v84, 0xfffffe, v84
	v_add3_u32 v84, v86, v84, s82
	v_mul_hi_i32_i24_e32 v85, 0x5800, v84
	v_mul_i32_i24_e32 v84, 0x5800, v84
	v_lshl_add_u64 v[84:85], s[28:29], 0, v[84:85]
	v_lshl_add_u64 v[84:85], v[208:209], 2, v[84:85]
	s_or_b64 exec, exec, s[8:9]
	v_lshl_add_u32 v88, s49, 2, v88
	v_mov_b64_e32 v[86:87], s[22:23]
	v_mad_i64_i32 v[86:87], s[8:9], v88, s80, v[86:87]
	v_lshl_add_u64 v[86:87], v[208:209], 1, v[86:87]
	v_cmp_ne_u64_e64 s[8:9], 0, v[84:85]
	v_cvt_pk_bf16_f32 v88, v24, v25
	v_cvt_pk_bf16_f32 v89, v26, v27
	v_cvt_pk_bf16_f32 v90, v8, v9
	v_cvt_pk_bf16_f32 v91, v10, v11
	global_store_dwordx4 v[86:87], v[88:91], off
	s_and_saveexec_b64 s[10:11], s[8:9]
	s_cbranch_execz .LBB0_1464
	global_store_dwordx4 v[84:85], v[24:27], off
	global_store_dwordx4 v[84:85], v[8:11], off offset:16
.LBB0_1464:
	s_or_b64 exec, exec, s[10:11]
	v_add_co_u32_e32 v86, vcc, 0x1000, v86
	v_cvt_pk_bf16_f32 v88, v16, v17
	v_cvt_pk_bf16_f32 v89, v18, v19
	v_cvt_pk_bf16_f32 v90, v0, v1
	v_cvt_pk_bf16_f32 v91, v2, v3
	v_addc_co_u32_e32 v87, vcc, 0, v87, vcc
	global_store_dwordx4 v[86:87], v[88:91], off offset:1536
	s_and_b64 exec, exec, s[8:9]
	s_cbranch_execz .LBB0_1466
	v_add_co_u32_e32 v84, vcc, 0x2000, v84
	s_nop 1
	v_addc_co_u32_e32 v85, vcc, 0, v85, vcc
	global_store_dwordx4 v[84:85], v[16:19], off offset:3072
	global_store_dwordx4 v[84:85], v[0:3], off offset:3088
;     __device__ __forceinline__ void operator()(f32x4 (&acc)[2][2][4][2], const Unit& u, int, int, int, int) const {
;     ...
;         f32x4 wa0[2], wa1[2], wa2[2], ba[2], wg0[2], wg1[2], wg2[2], bg[2];
; #pragma unroll
;         for (int n = 0; n < 2; ++n) { const int ch = f0 + 4 * n;
;             wa0[n] = *(const f32x4*)(cw + ch); wa1[n] = *(const f32x4*)(cw + NUP + ch); wa2[n] = *(const f32x4*)(cw + 2 * NUP + ch); ba[n] = *(const f32x4*)(cb + ch);
;             wg0[n] = *(const f32x4*)(cw + NFF + ch); wg1[n] = *(const f32x4*)(cw + NUP + NFF + ch); wg2[n] = *(const f32x4*)(cw + 2 * NUP + NFF + ch); bg[n] = *(const f32x4*)(cb + NFF + ch); }
; #pragma unroll
;         for (int ai = 0; ai < 2; ++ai)
; #pragma unroll
;             for (int m = 0; m < 4; ++m) { float r[8];
; #pragma unroll
;                 for (int n = 0; n < 2; ++n)
; #pragma unroll
;                     for (int e = 0; e < 4; ++e) { const float A = acc[ai][0][m][n][e], Gv = acc[ai][1][m][n][e];
;                         const float Ap = m > 0 ? acc[ai][0][m > 0 ? m - 1 : 0][n][e] : 0.f, Gp = m > 0 ? acc[ai][1][m > 0 ? m - 1 : 0][n][e] : 0.f;
;                         const float a1 = dpp_prev(A, Ap, 1), a2 = dpp_prev(A, Ap, 2), g1 = dpp_prev(Gv, Gp, 1), g2 = dpp_prev(Gv, Gp, 2);
.LBB0_1466:
	s_or_b64 exec, exec, s[12:13]
	v_lshlrev_b64 v[84:85], 2, v[208:209]
	v_lshl_add_u64 v[88:89], s[30:31], 0, v[84:85]
	v_lshl_add_u64 v[90:91], s[34:35], 0, v[84:85]
	global_load_dwordx4 v[148:151], v[88:89], off
	global_load_dwordx4 v[144:147], v[90:91], off
	v_lshl_add_u64 v[90:91], s[38:39], 0, v[84:85]
	v_lshl_add_u64 v[86:87], s[14:15], 0, v[84:85]
	v_lshl_add_u64 v[88:89], s[16:17], 0, v[84:85]
	v_lshl_add_u64 v[92:93], s[40:41], 0, v[84:85]
	global_load_dwordx4 v[128:131], v[90:91], off
	global_load_dwordx4 v[132:135], v[92:93], off
	v_lshl_add_u64 v[90:91], s[42:43], 0, v[84:85]
	v_lshl_add_u64 v[84:85], s[46:47], 0, v[84:85]
	global_load_dwordx4 v[140:143], v[84:85], off
	v_or_b32_e32 v84, 4, v208
	v_ashrrev_i32_e32 v85, 31, v84
	v_lshlrev_b64 v[96:97], 2, v[84:85]
	v_lshl_add_u64 v[84:85], s[30:31], 0, v[96:97]
	global_load_dwordx4 v[136:139], v[90:91], off
	global_load_dwordx4 v[152:155], v[86:87], off
	global_load_dwordx4 v[100:103], v[86:87], off offset:16
	v_lshl_add_u64 v[86:87], s[34:35], 0, v[96:97]
	global_load_dwordx4 v[108:111], v[84:85], off
	global_load_dwordx4 v[104:107], v[86:87], off
	global_load_dwordx4 v[156:159], v[88:89], off
	global_load_dwordx4 v[112:115], v[88:89], off offset:16
	v_lshl_add_u64 v[84:85], s[38:39], 0, v[96:97]
	v_lshl_add_u64 v[88:89], s[40:41], 0, v[96:97]
	v_lshl_add_u64 v[92:93], s[42:43], 0, v[96:97]
	v_lshl_add_u64 v[96:97], s[46:47], 0, v[96:97]
	global_load_dwordx4 v[84:87], v[84:85], off
	s_nop 0
	global_load_dwordx4 v[88:91], v[88:89], off
	v_mov_b32_dpp v211, v195 row_ror:1 row_mask:0xf bank_mask:0xf bound_ctrl:1
	global_load_dwordx4 v[92:95], v[92:93], off
	v_mov_b32_dpp v213, v195 row_ror:2 row_mask:0xf bank_mask:0xf bound_ctrl:1
	global_load_dwordx4 v[96:99], v[96:97], off
	v_mov_b32_e32 v218, v211
	v_mov_b32_e32 v220, v213
	v_mov_b32_e32 v214, v211
	v_mov_b32_e32 v216, v213
	v_mov_b32_e32 v219, v211
	v_mov_b32_e32 v221, v213
	v_mov_b32_e32 v215, v211
	v_mov_b32_e32 v217, v213
	v_mov_b32_e32 v230, v211
	v_mov_b32_e32 v232, v213
	v_mov_b32_e32 v226, v211
	v_mov_b32_e32 v228, v213
	v_mov_b32_e32 v231, v211
	v_mov_b32_e32 v233, v213
	v_mov_b32_e32 v227, v211
	v_mov_b32_e32 v229, v213
	v_mov_b32_e32 v238, v211
	v_mov_b32_e32 v240, v213
	v_mov_b32_e32 v234, v211
	v_mov_b32_e32 v236, v213
	v_mov_b32_e32 v239, v211
	v_mov_b32_e32 v241, v213
	v_mov_b32_e32 v235, v211
	v_mov_b32_e32 v237, v213
	v_mov_b32_e32 v222, v211
	v_mov_b32_e32 v224, v213
	v_mov_b32_e32 v210, v211
	v_mov_b32_e32 v212, v213
	v_mov_b32_e32 v223, v211
	v_mov_b32_e32 v225, v213
	v_mov_b32_dpp v218, v188 row_shr:1 row_mask:0xf bank_mask:0xf
	v_mov_b32_dpp v220, v188 row_shr:2 row_mask:0xf bank_mask:0xf
	v_mov_b32_dpp v214, v184 row_shr:1 row_mask:0xf bank_mask:0xf
	v_mov_b32_dpp v216, v184 row_shr:2 row_mask:0xf bank_mask:0xf
	v_mov_b32_dpp v219, v189 row_shr:1 row_mask:0xf bank_mask:0xf
	v_mov_b32_dpp v221, v189 row_shr:2 row_mask:0xf bank_mask:0xf
	v_mov_b32_dpp v215, v185 row_shr:1 row_mask:0xf bank_mask:0xf
	v_mov_b32_dpp v217, v185 row_shr:2 row_mask:0xf bank_mask:0xf
	v_mov_b32_dpp v230, v190 row_shr:1 row_mask:0xf bank_mask:0xf
	v_mov_b32_dpp v232, v190 row_shr:2 row_mask:0xf bank_mask:0xf
	v_mov_b32_dpp v226, v186 row_shr:1 row_mask:0xf bank_mask:0xf
	v_mov_b32_dpp v228, v186 row_shr:2 row_mask:0xf bank_mask:0xf
	v_mov_b32_dpp v231, v191 row_shr:1 row_mask:0xf bank_mask:0xf
	v_mov_b32_dpp v233, v191 row_shr:2 row_mask:0xf bank_mask:0xf
	v_mov_b32_dpp v227, v187 row_shr:1 row_mask:0xf bank_mask:0xf
	v_mov_b32_dpp v229, v187 row_shr:2 row_mask:0xf bank_mask:0xf
	v_mov_b32_dpp v238, v180 row_shr:1 row_mask:0xf bank_mask:0xf
	v_mov_b32_dpp v240, v180 row_shr:2 row_mask:0xf bank_mask:0xf
	v_mov_b32_dpp v234, v176 row_shr:1 row_mask:0xf bank_mask:0xf
	v_mov_b32_dpp v236, v176 row_shr:2 row_mask:0xf bank_mask:0xf
	v_mov_b32_dpp v239, v181 row_shr:1 row_mask:0xf bank_mask:0xf
	v_mov_b32_dpp v241, v181 row_shr:2 row_mask:0xf bank_mask:0xf
	v_mov_b32_dpp v235, v177 row_shr:1 row_mask:0xf bank_mask:0xf
	v_mov_b32_dpp v237, v177 row_shr:2 row_mask:0xf bank_mask:0xf
	v_mov_b32_dpp v222, v182 row_shr:1 row_mask:0xf bank_mask:0xf
	v_mov_b32_dpp v224, v182 row_shr:2 row_mask:0xf bank_mask:0xf
	v_mov_b32_dpp v210, v178 row_shr:1 row_mask:0xf bank_mask:0xf
	v_mov_b32_dpp v212, v178 row_shr:2 row_mask:0xf bank_mask:0xf
	v_mov_b32_dpp v223, v183 row_shr:1 row_mask:0xf bank_mask:0xf
	v_mov_b32_dpp v225, v183 row_shr:2 row_mask:0xf bank_mask:0xf
	v_mov_b32_dpp v211, v179 row_shr:1 row_mask:0xf bank_mask:0xf
	v_mov_b32_dpp v213, v179 row_shr:2 row_mask:0xf bank_mask:0xf
	s_and_saveexec_b64 s[8:9], s[6:7]
	s_xor_b64 s[8:9], exec, s[8:9]
	s_cbranch_execz .LBB0_1468
; __device__ __forceinline__ unsigned pk2(float lo, float hi) { const f32x2 v = {lo, hi}; return __builtin_bit_cast(unsigned, __builtin_convertvector(v, bf16x2_t)); }
; __device__ __forceinline__ float silu(float x) { return x * __builtin_amdgcn_rcpf(1.f + __builtin_amdgcn_exp2f(-1.4426950408889634f * x)); }
;     __device__ __forceinline__ void operator()(f32x4 (&acc)[2][2][4][2], const Unit& u, int, int, int, int) const {
;     ...
;         for (int ai = 0; ai < 2; ++ai)
; #pragma unroll
;             for (int m = 0; m < 4; ++m) { float r[8];
; #pragma unroll
;                 for (int n = 0; n < 2; ++n)
; #pragma unroll
;                     for (int e = 0; e < 4; ++e) { const float A = acc[ai][0][m][n][e], Gv = acc[ai][1][m][n][e];
;                         const float Ap = m > 0 ? acc[ai][0][m > 0 ? m - 1 : 0][n][e] : 0.f, Gp = m > 0 ? acc[ai][1][m > 0 ? m - 1 : 0][n][e] : 0.f;
;                         const float a1 = dpp_prev(A, Ap, 1), a2 = dpp_prev(A, Ap, 2), g1 = dpp_prev(Gv, Gp, 1), g2 = dpp_prev(Gv, Gp, 2);
;                         const float ca = ba[n][e] + wa0[n][e] * a2 + wa1[n][e] * a1 + wa2[n][e] * A, cg = bg[n][e] + wg0[n][e] * g2 + wg1[n][e] * g1 + wg2[n][e] * Gv;
;                         r[4 * n + e] = silu(ca) * cg; }
;                 if (!(m == 0 && fr < 2)) { u32x4 w; w.x = pk2(r[0], r[1]); w.y = pk2(r[2], r[3]); w.z = pk2(r[4], r[5]); w.w = pk2(r[6], r[7]);
;                     *(u32x4*)(ACT + (size_t)(rowt + ai * HALF + m * 16) * NFF + f0) = w; }
;                 __builtin_amdgcn_sched_barrier(0); }
	s_waitcnt vmcnt(0) lgkmcnt(0)
	v_pk_fma_f32 v[240:241], v[100:101], v[240:241], v[112:113]
	v_pk_fma_f32 v[232:233], v[154:155], v[232:233], v[158:159]
	v_pk_fma_f32 v[238:239], v[108:109], v[238:239], v[240:241]
	v_pk_fma_f32 v[230:231], v[150:151], v[230:231], v[232:233]
	v_pk_fma_f32 v[238:239], v[180:181], v[104:105], v[238:239]
	v_pk_fma_f32 v[230:231], v[190:191], v[146:147], v[230:231]
	v_mul_f32_e32 v240, 0xbfb8aa3b, v238
	v_mul_f32_e32 v241, 0xbfb8aa3b, v239
	v_exp_f32_e32 v240, v240
	v_exp_f32_e32 v241, v241
	v_pk_fma_f32 v[236:237], v[84:85], v[236:237], v[96:97]
	v_mul_f32_e32 v232, 0xbfb8aa3b, v230
	v_add_f32_e32 v240, 1.0, v240
	v_add_f32_e32 v241, 1.0, v241
	v_rcp_f32_e32 v240, v240
	v_rcp_f32_e32 v241, v241
	v_pk_fma_f32 v[234:235], v[88:89], v[234:235], v[236:237]
	v_pk_fma_f32 v[220:221], v[152:153], v[220:221], v[156:157]
	v_pk_fma_f32 v[234:235], v[176:177], v[92:93], v[234:235]
	v_pk_mul_f32 v[236:237], v[238:239], v[240:241]
	v_exp_f32_e32 v238, v232
	v_mul_f32_e32 v232, 0xbfb8aa3b, v231
	v_exp_f32_e32 v239, v232
	v_pk_mul_f32 v[232:233], v[234:235], v[236:237]
	v_add_f32_e32 v234, 1.0, v238
	v_rcp_f32_e32 v234, v234
	v_add_f32_e32 v235, 1.0, v239
	v_rcp_f32_e32 v235, v235
	v_pk_fma_f32 v[218:219], v[148:149], v[218:219], v[220:221]
	v_pk_fma_f32 v[228:229], v[130:131], v[228:229], v[142:143]
	v_pk_fma_f32 v[218:219], v[188:189], v[144:145], v[218:219]
	v_pk_fma_f32 v[226:227], v[134:135], v[226:227], v[228:229]
	v_mul_f32_e32 v220, 0xbfb8aa3b, v218
	v_pk_mul_f32 v[228:229], v[230:231], v[234:235]
	v_exp_f32_e32 v230, v220
	v_mul_f32_e32 v220, 0xbfb8aa3b, v219
	v_exp_f32_e32 v231, v220
	v_pk_fma_f32 v[226:227], v[186:187], v[138:139], v[226:227]
	v_pk_fma_f32 v[216:217], v[128:129], v[216:217], v[140:141]
	v_pk_mul_f32 v[220:221], v[226:227], v[228:229]
	v_add_f32_e32 v226, 1.0, v230
	v_add_f32_e32 v227, 1.0, v231
	v_rcp_f32_e32 v226, v226
	v_rcp_f32_e32 v227, v227
	v_pk_fma_f32 v[214:215], v[132:133], v[214:215], v[216:217]
	v_pk_fma_f32 v[212:213], v[86:87], v[212:213], v[98:99]
	v_pk_fma_f32 v[214:215], v[184:185], v[136:137], v[214:215]
	v_pk_mul_f32 v[216:217], v[218:219], v[226:227]
	v_pk_fma_f32 v[218:219], v[102:103], v[224:225], v[114:115]
	v_pk_mul_f32 v[214:215], v[214:215], v[216:217]
	v_pk_fma_f32 v[218:219], v[110:111], v[222:223], v[218:219]
	v_pk_fma_f32 v[210:211], v[90:91], v[210:211], v[212:213]
	v_pk_fma_f32 v[218:219], v[182:183], v[106:107], v[218:219]
	v_pk_fma_f32 v[210:211], v[178:179], v[94:95], v[210:211]
	v_mul_f32_e32 v222, 0xbfb8aa3b, v218
	v_mul_f32_e32 v223, 0xbfb8aa3b, v219
	v_exp_f32_e32 v222, v222
	v_exp_f32_e32 v223, v223
	v_add_f32_e32 v216, 1.0, v222
	v_add_f32_e32 v217, 1.0, v223
	v_rcp_f32_e32 v216, v216
	v_rcp_f32_e32 v217, v217
	s_nop 0
	v_pk_mul_f32 v[212:213], v[218:219], v[216:217]
	s_nop 0
	v_pk_mul_f32 v[216:217], v[210:211], v[212:213]
	v_cvt_pk_bf16_f32 v210, v214, v215
	v_mov_b64_e32 v[214:215], s[20:21]
	v_mad_i64_i32 v[214:215], s[10:11], v246, s83, v[214:215]
	v_cvt_pk_bf16_f32 v211, v220, v221
	v_cvt_pk_bf16_f32 v212, v232, v233
	v_cvt_pk_bf16_f32 v213, v216, v217
	v_lshl_add_u64 v[214:215], v[208:209], 1, v[214:215]
	global_store_dwordx4 v[214:215], v[210:213], off
.LBB0_1468:
	s_andn2_saveexec_b64 s[8:9], s[8:9]
	s_or_b64 exec, exec, s[8:9]
	v_mov_b32_dpp v210, v188 row_ror:1 row_mask:0xf bank_mask:0xf bound_ctrl:1
	v_mov_b32_dpp v188, v188 row_ror:2 row_mask:0xf bank_mask:0xf bound_ctrl:1
	v_mov_b32_dpp v211, v189 row_ror:1 row_mask:0xf bank_mask:0xf bound_ctrl:1
	v_mov_b32_dpp v189, v189 row_ror:2 row_mask:0xf bank_mask:0xf bound_ctrl:1
	v_mov_b32_dpp v188, v172 row_shr:2 row_mask:0xf bank_mask:0xf
	v_mov_b32_dpp v210, v172 row_shr:1 row_mask:0xf bank_mask:0xf
	v_mov_b32_dpp v189, v173 row_shr:2 row_mask:0xf bank_mask:0xf
	v_mov_b32_dpp v211, v173 row_shr:1 row_mask:0xf bank_mask:0xf
	s_waitcnt vmcnt(0) lgkmcnt(0)
	v_pk_fma_f32 v[188:189], v[152:153], v[188:189], v[156:157]
	v_mov_b32_dpp v212, v184 row_ror:1 row_mask:0xf bank_mask:0xf bound_ctrl:1
	v_pk_fma_f32 v[188:189], v[148:149], v[210:211], v[188:189]
	v_mov_b32_dpp v184, v184 row_ror:2 row_mask:0xf bank_mask:0xf bound_ctrl:1
	v_pk_fma_f32 v[188:189], v[172:173], v[144:145], v[188:189]
	v_mov_b32_dpp v213, v185 row_ror:1 row_mask:0xf bank_mask:0xf bound_ctrl:1
	v_mul_f32_e32 v210, 0xbfb8aa3b, v188
	v_mul_f32_e32 v211, 0xbfb8aa3b, v189
	v_exp_f32_e32 v210, v210
	v_exp_f32_e32 v211, v211
	v_mov_b32_dpp v185, v185 row_ror:2 row_mask:0xf bank_mask:0xf bound_ctrl:1
	v_mov_b32_dpp v184, v168 row_shr:2 row_mask:0xf bank_mask:0xf
	v_add_f32_e32 v210, 1.0, v210
	v_add_f32_e32 v211, 1.0, v211
	v_rcp_f32_e32 v210, v210
	v_rcp_f32_e32 v211, v211
	v_mov_b32_dpp v185, v169 row_shr:2 row_mask:0xf bank_mask:0xf
	v_mov_b32_dpp v212, v168 row_shr:1 row_mask:0xf bank_mask:0xf
	v_mov_b32_dpp v213, v169 row_shr:1 row_mask:0xf bank_mask:0xf
	v_pk_fma_f32 v[184:185], v[128:129], v[184:185], v[140:141]
	v_pk_mul_f32 v[188:189], v[188:189], v[210:211]
	v_pk_fma_f32 v[184:185], v[132:133], v[212:213], v[184:185]
	v_mov_b32_dpp v210, v186 row_ror:1 row_mask:0xf bank_mask:0xf bound_ctrl:1
	v_pk_fma_f32 v[184:185], v[168:169], v[136:137], v[184:185]
	v_mov_b32_dpp v186, v186 row_ror:2 row_mask:0xf bank_mask:0xf bound_ctrl:1
	v_pk_mul_f32 v[184:185], v[184:185], v[188:189]
	v_mov_b32_dpp v188, v190 row_ror:1 row_mask:0xf bank_mask:0xf bound_ctrl:1
	v_mov_b32_dpp v190, v190 row_ror:2 row_mask:0xf bank_mask:0xf bound_ctrl:1
	v_mov_b32_dpp v189, v191 row_ror:1 row_mask:0xf bank_mask:0xf bound_ctrl:1
	v_mov_b32_dpp v191, v191 row_ror:2 row_mask:0xf bank_mask:0xf bound_ctrl:1
	v_mov_b32_dpp v190, v174 row_shr:2 row_mask:0xf bank_mask:0xf
; __device__ __forceinline__ unsigned pk2(float lo, float hi) { const f32x2 v = {lo, hi}; return __builtin_bit_cast(unsigned, __builtin_convertvector(v, bf16x2_t)); }
; __device__ __forceinline__ float silu(float x) { return x * __builtin_amdgcn_rcpf(1.f + __builtin_amdgcn_exp2f(-1.4426950408889634f * x)); }
;     __device__ __forceinline__ void operator()(f32x4 (&acc)[2][2][4][2], const Unit& u, int, int, int, int) const {
;     ...
;         for (int ai = 0; ai < 2; ++ai)
; #pragma unroll
;             for (int m = 0; m < 4; ++m) { float r[8];
; #pragma unroll
;                 for (int n = 0; n < 2; ++n)
; #pragma unroll
;                     for (int e = 0; e < 4; ++e) { const float A = acc[ai][0][m][n][e], Gv = acc[ai][1][m][n][e];
;                         const float Ap = m > 0 ? acc[ai][0][m > 0 ? m - 1 : 0][n][e] : 0.f, Gp = m > 0 ? acc[ai][1][m > 0 ? m - 1 : 0][n][e] : 0.f;
;                         const float a1 = dpp_prev(A, Ap, 1), a2 = dpp_prev(A, Ap, 2), g1 = dpp_prev(Gv, Gp, 1), g2 = dpp_prev(Gv, Gp, 2);
;                         const float ca = ba[n][e] + wa0[n][e] * a2 + wa1[n][e] * a1 + wa2[n][e] * A, cg = bg[n][e] + wg0[n][e] * g2 + wg1[n][e] * g1 + wg2[n][e] * Gv;
;                         r[4 * n + e] = silu(ca) * cg; }
;                 if (!(m == 0 && fr < 2)) { u32x4 w; w.x = pk2(r[0], r[1]); w.y = pk2(r[2], r[3]); w.z = pk2(r[4], r[5]); w.w = pk2(r[6], r[7]);
;                     *(u32x4*)(ACT + (size_t)(rowt + ai * HALF + m * 16) * NFF + f0) = w; }
;                 __builtin_amdgcn_sched_barrier(0); }
	v_mov_b32_dpp v188, v174 row_shr:1 row_mask:0xf bank_mask:0xf
	v_mov_b32_dpp v191, v175 row_shr:2 row_mask:0xf bank_mask:0xf
	v_mov_b32_dpp v189, v175 row_shr:1 row_mask:0xf bank_mask:0xf
	v_pk_fma_f32 v[190:191], v[154:155], v[190:191], v[158:159]
	v_mov_b32_dpp v211, v187 row_ror:1 row_mask:0xf bank_mask:0xf bound_ctrl:1
	v_pk_fma_f32 v[188:189], v[150:151], v[188:189], v[190:191]
	v_mov_b32_dpp v187, v187 row_ror:2 row_mask:0xf bank_mask:0xf bound_ctrl:1
	v_pk_fma_f32 v[188:189], v[174:175], v[146:147], v[188:189]
	v_mov_b32_dpp v186, v170 row_shr:2 row_mask:0xf bank_mask:0xf
	v_mul_f32_e32 v190, 0xbfb8aa3b, v188
	v_mul_f32_e32 v191, 0xbfb8aa3b, v189
	v_exp_f32_e32 v190, v190
	v_exp_f32_e32 v191, v191
	v_mov_b32_dpp v187, v171 row_shr:2 row_mask:0xf bank_mask:0xf
	v_mov_b32_dpp v210, v170 row_shr:1 row_mask:0xf bank_mask:0xf
	v_add_f32_e32 v190, 1.0, v190
	v_add_f32_e32 v191, 1.0, v191
	v_rcp_f32_e32 v190, v190
	v_rcp_f32_e32 v191, v191
	v_mov_b32_dpp v211, v171 row_shr:1 row_mask:0xf bank_mask:0xf
	v_pk_fma_f32 v[186:187], v[130:131], v[186:187], v[142:143]
	v_pk_mul_f32 v[188:189], v[188:189], v[190:191]
	v_pk_fma_f32 v[186:187], v[134:135], v[210:211], v[186:187]
	v_mov_b32_dpp v190, v176 row_ror:1 row_mask:0xf bank_mask:0xf bound_ctrl:1
	v_pk_fma_f32 v[186:187], v[170:171], v[138:139], v[186:187]
	v_mov_b32_dpp v176, v176 row_ror:2 row_mask:0xf bank_mask:0xf bound_ctrl:1
	v_pk_mul_f32 v[186:187], v[186:187], v[188:189]
	v_mov_b32_dpp v188, v180 row_ror:1 row_mask:0xf bank_mask:0xf bound_ctrl:1
	v_mov_b32_dpp v180, v180 row_ror:2 row_mask:0xf bank_mask:0xf bound_ctrl:1
	v_mov_b32_dpp v189, v181 row_ror:1 row_mask:0xf bank_mask:0xf bound_ctrl:1
	v_mov_b32_dpp v181, v181 row_ror:2 row_mask:0xf bank_mask:0xf bound_ctrl:1
	v_mov_b32_dpp v180, v164 row_shr:2 row_mask:0xf bank_mask:0xf
	v_mov_b32_dpp v188, v164 row_shr:1 row_mask:0xf bank_mask:0xf
	v_mov_b32_dpp v181, v165 row_shr:2 row_mask:0xf bank_mask:0xf
	v_mov_b32_dpp v189, v165 row_shr:1 row_mask:0xf bank_mask:0xf
	v_pk_fma_f32 v[180:181], v[100:101], v[180:181], v[112:113]
	v_mov_b32_dpp v191, v177 row_ror:1 row_mask:0xf bank_mask:0xf bound_ctrl:1
	v_pk_fma_f32 v[180:181], v[108:109], v[188:189], v[180:181]
	v_mov_b32_dpp v177, v177 row_ror:2 row_mask:0xf bank_mask:0xf bound_ctrl:1
	v_pk_fma_f32 v[180:181], v[164:165], v[104:105], v[180:181]
	v_mov_b32_dpp v176, v160 row_shr:2 row_mask:0xf bank_mask:0xf
	v_mul_f32_e32 v188, 0xbfb8aa3b, v180
	v_mul_f32_e32 v189, 0xbfb8aa3b, v181
	v_exp_f32_e32 v188, v188
	v_exp_f32_e32 v189, v189
	v_mov_b32_dpp v177, v161 row_shr:2 row_mask:0xf bank_mask:0xf
	v_mov_b32_dpp v190, v160 row_shr:1 row_mask:0xf bank_mask:0xf
	v_add_f32_e32 v188, 1.0, v188
	v_add_f32_e32 v189, 1.0, v189
	v_rcp_f32_e32 v188, v188
	v_rcp_f32_e32 v189, v189
	v_mov_b32_dpp v191, v161 row_shr:1 row_mask:0xf bank_mask:0xf
	v_pk_fma_f32 v[176:177], v[84:85], v[176:177], v[96:97]
	v_pk_mul_f32 v[180:181], v[180:181], v[188:189]
	v_pk_fma_f32 v[176:177], v[88:89], v[190:191], v[176:177]
	v_mov_b32_dpp v188, v178 row_ror:1 row_mask:0xf bank_mask:0xf bound_ctrl:1
	v_pk_fma_f32 v[176:177], v[160:161], v[92:93], v[176:177]
	v_mov_b32_dpp v178, v178 row_ror:2 row_mask:0xf bank_mask:0xf bound_ctrl:1
	v_pk_mul_f32 v[176:177], v[176:177], v[180:181]
	v_mov_b32_dpp v180, v182 row_ror:1 row_mask:0xf bank_mask:0xf bound_ctrl:1
	v_mov_b32_dpp v182, v182 row_ror:2 row_mask:0xf bank_mask:0xf bound_ctrl:1
	v_mov_b32_dpp v181, v183 row_ror:1 row_mask:0xf bank_mask:0xf bound_ctrl:1
	v_mov_b32_dpp v183, v183 row_ror:2 row_mask:0xf bank_mask:0xf bound_ctrl:1
	v_mov_b32_dpp v182, v166 row_shr:2 row_mask:0xf bank_mask:0xf
	v_mov_b32_dpp v180, v166 row_shr:1 row_mask:0xf bank_mask:0xf
	v_mov_b32_dpp v183, v167 row_shr:2 row_mask:0xf bank_mask:0xf
	v_mov_b32_dpp v181, v167 row_shr:1 row_mask:0xf bank_mask:0xf
	v_pk_fma_f32 v[182:183], v[102:103], v[182:183], v[114:115]
	v_mov_b32_dpp v189, v179 row_ror:1 row_mask:0xf bank_mask:0xf bound_ctrl:1
	v_pk_fma_f32 v[180:181], v[110:111], v[180:181], v[182:183]
	v_mov_b32_dpp v179, v179 row_ror:2 row_mask:0xf bank_mask:0xf bound_ctrl:1
	v_pk_fma_f32 v[180:181], v[166:167], v[106:107], v[180:181]
	v_mov_b32_dpp v178, v162 row_shr:2 row_mask:0xf bank_mask:0xf
	v_mul_f32_e32 v182, 0xbfb8aa3b, v180
	v_mul_f32_e32 v183, 0xbfb8aa3b, v181
	v_exp_f32_e32 v182, v182
	v_exp_f32_e32 v183, v183
	v_mov_b32_dpp v179, v163 row_shr:2 row_mask:0xf bank_mask:0xf
	v_mov_b32_dpp v188, v162 row_shr:1 row_mask:0xf bank_mask:0xf
	v_add_f32_e32 v182, 1.0, v182
	v_add_f32_e32 v183, 1.0, v183
	v_rcp_f32_e32 v182, v182
	v_rcp_f32_e32 v183, v183
	v_mov_b32_dpp v189, v163 row_shr:1 row_mask:0xf bank_mask:0xf
	v_pk_fma_f32 v[178:179], v[86:87], v[178:179], v[98:99]
	v_pk_mul_f32 v[180:181], v[180:181], v[182:183]
	v_pk_fma_f32 v[178:179], v[90:91], v[188:189], v[178:179]
	v_cvt_pk_bf16_f32 v182, v176, v177
	v_pk_fma_f32 v[178:179], v[162:163], v[94:95], v[178:179]
	v_or_b32_e32 v176, 16, v246
	v_pk_mul_f32 v[178:179], v[178:179], v[180:181]
	v_cvt_pk_bf16_f32 v180, v184, v185
	v_cvt_pk_bf16_f32 v183, v178, v179
	v_mov_b64_e32 v[178:179], s[20:21]
	v_mad_i64_i32 v[184:185], s[8:9], v176, s83, v[178:179]
	v_lshlrev_b64 v[176:177], 1, v[208:209]
	v_cvt_pk_bf16_f32 v181, v186, v187
	v_lshl_add_u64 v[184:185], v[184:185], 0, v[176:177]
	global_store_dwordx4 v[184:185], v[180:183], off
	s_nop 1
	v_mov_b32_dpp v180, v172 row_ror:1 row_mask:0xf bank_mask:0xf bound_ctrl:1
	v_mov_b32_dpp v172, v172 row_ror:2 row_mask:0xf bank_mask:0xf bound_ctrl:1
	v_mov_b32_dpp v181, v173 row_ror:1 row_mask:0xf bank_mask:0xf bound_ctrl:1
	v_mov_b32_dpp v173, v173 row_ror:2 row_mask:0xf bank_mask:0xf bound_ctrl:1
; __device__ __forceinline__ unsigned pk2(float lo, float hi) { const f32x2 v = {lo, hi}; return __builtin_bit_cast(unsigned, __builtin_convertvector(v, bf16x2_t)); }
; __device__ __forceinline__ float silu(float x) { return x * __builtin_amdgcn_rcpf(1.f + __builtin_amdgcn_exp2f(-1.4426950408889634f * x)); }
;     __device__ __forceinline__ void operator()(f32x4 (&acc)[2][2][4][2], const Unit& u, int, int, int, int) const {
;     ...
;         for (int ai = 0; ai < 2; ++ai)
; #pragma unroll
;             for (int m = 0; m < 4; ++m) { float r[8];
; #pragma unroll
;                 for (int n = 0; n < 2; ++n)
; #pragma unroll
;                     for (int e = 0; e < 4; ++e) { const float A = acc[ai][0][m][n][e], Gv = acc[ai][1][m][n][e];
;                         const float Ap = m > 0 ? acc[ai][0][m > 0 ? m - 1 : 0][n][e] : 0.f, Gp = m > 0 ? acc[ai][1][m > 0 ? m - 1 : 0][n][e] : 0.f;
;                         const float a1 = dpp_prev(A, Ap, 1), a2 = dpp_prev(A, Ap, 2), g1 = dpp_prev(Gv, Gp, 1), g2 = dpp_prev(Gv, Gp, 2);
;                         const float ca = ba[n][e] + wa0[n][e] * a2 + wa1[n][e] * a1 + wa2[n][e] * A, cg = bg[n][e] + wg0[n][e] * g2 + wg1[n][e] * g1 + wg2[n][e] * Gv;
;                         r[4 * n + e] = silu(ca) * cg; }
;                 if (!(m == 0 && fr < 2)) { u32x4 w; w.x = pk2(r[0], r[1]); w.y = pk2(r[2], r[3]); w.z = pk2(r[4], r[5]); w.w = pk2(r[6], r[7]);
;                     *(u32x4*)(ACT + (size_t)(rowt + ai * HALF + m * 16) * NFF + f0) = w; }
;                 __builtin_amdgcn_sched_barrier(0); }
	v_mov_b32_dpp v172, v124 row_shr:2 row_mask:0xf bank_mask:0xf
	v_mov_b32_dpp v180, v124 row_shr:1 row_mask:0xf bank_mask:0xf
	v_mov_b32_dpp v173, v125 row_shr:2 row_mask:0xf bank_mask:0xf
	v_mov_b32_dpp v181, v125 row_shr:1 row_mask:0xf bank_mask:0xf
	v_pk_fma_f32 v[172:173], v[152:153], v[172:173], v[156:157]
	v_mov_b32_dpp v182, v168 row_ror:1 row_mask:0xf bank_mask:0xf bound_ctrl:1
	v_pk_fma_f32 v[172:173], v[148:149], v[180:181], v[172:173]
	v_mov_b32_dpp v168, v168 row_ror:2 row_mask:0xf bank_mask:0xf bound_ctrl:1
	v_pk_fma_f32 v[172:173], v[124:125], v[144:145], v[172:173]
	v_mov_b32_dpp v183, v169 row_ror:1 row_mask:0xf bank_mask:0xf bound_ctrl:1
	v_mul_f32_e32 v180, 0xbfb8aa3b, v172
	v_mul_f32_e32 v181, 0xbfb8aa3b, v173
	v_exp_f32_e32 v180, v180
	v_exp_f32_e32 v181, v181
	v_mov_b32_dpp v169, v169 row_ror:2 row_mask:0xf bank_mask:0xf bound_ctrl:1
	v_mov_b32_dpp v168, v116 row_shr:2 row_mask:0xf bank_mask:0xf
	v_add_f32_e32 v180, 1.0, v180
	v_add_f32_e32 v181, 1.0, v181
	v_rcp_f32_e32 v180, v180
	v_rcp_f32_e32 v181, v181
	v_mov_b32_dpp v169, v117 row_shr:2 row_mask:0xf bank_mask:0xf
	v_mov_b32_dpp v182, v116 row_shr:1 row_mask:0xf bank_mask:0xf
	v_mov_b32_dpp v183, v117 row_shr:1 row_mask:0xf bank_mask:0xf
	v_pk_fma_f32 v[168:169], v[128:129], v[168:169], v[140:141]
	v_pk_mul_f32 v[172:173], v[172:173], v[180:181]
	v_pk_fma_f32 v[168:169], v[132:133], v[182:183], v[168:169]
	v_mov_b32_dpp v180, v170 row_ror:1 row_mask:0xf bank_mask:0xf bound_ctrl:1
	v_pk_fma_f32 v[168:169], v[116:117], v[136:137], v[168:169]
	v_mov_b32_dpp v170, v170 row_ror:2 row_mask:0xf bank_mask:0xf bound_ctrl:1
	v_pk_mul_f32 v[168:169], v[168:169], v[172:173]
	v_mov_b32_dpp v172, v174 row_ror:1 row_mask:0xf bank_mask:0xf bound_ctrl:1
	v_mov_b32_dpp v174, v174 row_ror:2 row_mask:0xf bank_mask:0xf bound_ctrl:1
	v_mov_b32_dpp v173, v175 row_ror:1 row_mask:0xf bank_mask:0xf bound_ctrl:1
	v_mov_b32_dpp v175, v175 row_ror:2 row_mask:0xf bank_mask:0xf bound_ctrl:1
	v_mov_b32_dpp v174, v126 row_shr:2 row_mask:0xf bank_mask:0xf
	v_mov_b32_dpp v172, v126 row_shr:1 row_mask:0xf bank_mask:0xf
	v_mov_b32_dpp v175, v127 row_shr:2 row_mask:0xf bank_mask:0xf
	v_mov_b32_dpp v173, v127 row_shr:1 row_mask:0xf bank_mask:0xf
	v_pk_fma_f32 v[174:175], v[154:155], v[174:175], v[158:159]
	v_mov_b32_dpp v181, v171 row_ror:1 row_mask:0xf bank_mask:0xf bound_ctrl:1
	v_pk_fma_f32 v[172:173], v[150:151], v[172:173], v[174:175]
	v_mov_b32_dpp v171, v171 row_ror:2 row_mask:0xf bank_mask:0xf bound_ctrl:1
	v_pk_fma_f32 v[172:173], v[126:127], v[146:147], v[172:173]
	v_mov_b32_dpp v170, v118 row_shr:2 row_mask:0xf bank_mask:0xf
	v_mul_f32_e32 v174, 0xbfb8aa3b, v172
	v_mul_f32_e32 v175, 0xbfb8aa3b, v173
	v_exp_f32_e32 v174, v174
	v_exp_f32_e32 v175, v175
	v_mov_b32_dpp v171, v119 row_shr:2 row_mask:0xf bank_mask:0xf
	v_mov_b32_dpp v180, v118 row_shr:1 row_mask:0xf bank_mask:0xf
	v_add_f32_e32 v174, 1.0, v174
	v_add_f32_e32 v175, 1.0, v175
	v_rcp_f32_e32 v174, v174
	v_rcp_f32_e32 v175, v175
	v_mov_b32_dpp v181, v119 row_shr:1 row_mask:0xf bank_mask:0xf
	v_pk_fma_f32 v[170:171], v[130:131], v[170:171], v[142:143]
	v_pk_mul_f32 v[172:173], v[172:173], v[174:175]
	v_pk_fma_f32 v[170:171], v[134:135], v[180:181], v[170:171]
	v_mov_b32_dpp v174, v160 row_ror:1 row_mask:0xf bank_mask:0xf bound_ctrl:1
	v_pk_fma_f32 v[170:171], v[118:119], v[138:139], v[170:171]
	v_mov_b32_dpp v160, v160 row_ror:2 row_mask:0xf bank_mask:0xf bound_ctrl:1
	v_pk_mul_f32 v[170:171], v[170:171], v[172:173]
	v_mov_b32_dpp v172, v164 row_ror:1 row_mask:0xf bank_mask:0xf bound_ctrl:1
	v_mov_b32_dpp v164, v164 row_ror:2 row_mask:0xf bank_mask:0xf bound_ctrl:1
	v_mov_b32_dpp v173, v165 row_ror:1 row_mask:0xf bank_mask:0xf bound_ctrl:1
	v_mov_b32_dpp v165, v165 row_ror:2 row_mask:0xf bank_mask:0xf bound_ctrl:1
	v_mov_b32_dpp v164, v76 row_shr:2 row_mask:0xf bank_mask:0xf
	v_mov_b32_dpp v172, v76 row_shr:1 row_mask:0xf bank_mask:0xf
	v_mov_b32_dpp v165, v77 row_shr:2 row_mask:0xf bank_mask:0xf
	v_mov_b32_dpp v173, v77 row_shr:1 row_mask:0xf bank_mask:0xf
	v_pk_fma_f32 v[164:165], v[100:101], v[164:165], v[112:113]
	v_mov_b32_dpp v175, v161 row_ror:1 row_mask:0xf bank_mask:0xf bound_ctrl:1
	v_pk_fma_f32 v[164:165], v[108:109], v[172:173], v[164:165]
	v_mov_b32_dpp v161, v161 row_ror:2 row_mask:0xf bank_mask:0xf bound_ctrl:1
	v_pk_fma_f32 v[164:165], v[76:77], v[104:105], v[164:165]
	v_mov_b32_dpp v160, v68 row_shr:2 row_mask:0xf bank_mask:0xf
	v_mul_f32_e32 v172, 0xbfb8aa3b, v164
	v_mul_f32_e32 v173, 0xbfb8aa3b, v165
	v_exp_f32_e32 v172, v172
	v_exp_f32_e32 v173, v173
	v_mov_b32_dpp v161, v69 row_shr:2 row_mask:0xf bank_mask:0xf
	v_mov_b32_dpp v174, v68 row_shr:1 row_mask:0xf bank_mask:0xf
	v_add_f32_e32 v172, 1.0, v172
	v_add_f32_e32 v173, 1.0, v173
	v_rcp_f32_e32 v172, v172
	v_rcp_f32_e32 v173, v173
	v_mov_b32_dpp v175, v69 row_shr:1 row_mask:0xf bank_mask:0xf
	v_pk_fma_f32 v[160:161], v[84:85], v[160:161], v[96:97]
	v_pk_mul_f32 v[164:165], v[164:165], v[172:173]
	v_pk_fma_f32 v[160:161], v[88:89], v[174:175], v[160:161]
	v_mov_b32_dpp v172, v162 row_ror:1 row_mask:0xf bank_mask:0xf bound_ctrl:1
	v_pk_fma_f32 v[160:161], v[68:69], v[92:93], v[160:161]
	v_mov_b32_dpp v162, v162 row_ror:2 row_mask:0xf bank_mask:0xf bound_ctrl:1
	v_pk_mul_f32 v[164:165], v[160:161], v[164:165]
	v_mov_b32_dpp v160, v166 row_ror:1 row_mask:0xf bank_mask:0xf bound_ctrl:1
	v_mov_b32_dpp v166, v166 row_ror:2 row_mask:0xf bank_mask:0xf bound_ctrl:1
	v_mov_b32_dpp v161, v167 row_ror:1 row_mask:0xf bank_mask:0xf bound_ctrl:1
	v_mov_b32_dpp v167, v167 row_ror:2 row_mask:0xf bank_mask:0xf bound_ctrl:1
	v_mov_b32_dpp v166, v78 row_shr:2 row_mask:0xf bank_mask:0xf
; __device__ __forceinline__ unsigned pk2(float lo, float hi) { const f32x2 v = {lo, hi}; return __builtin_bit_cast(unsigned, __builtin_convertvector(v, bf16x2_t)); }
; __device__ __forceinline__ float silu(float x) { return x * __builtin_amdgcn_rcpf(1.f + __builtin_amdgcn_exp2f(-1.4426950408889634f * x)); }
;     __device__ __forceinline__ void operator()(f32x4 (&acc)[2][2][4][2], const Unit& u, int, int, int, int) const {
;     ...
;         for (int ai = 0; ai < 2; ++ai)
; #pragma unroll
;             for (int m = 0; m < 4; ++m) { float r[8];
; #pragma unroll
;                 for (int n = 0; n < 2; ++n)
; #pragma unroll
;                     for (int e = 0; e < 4; ++e) { const float A = acc[ai][0][m][n][e], Gv = acc[ai][1][m][n][e];
;                         const float Ap = m > 0 ? acc[ai][0][m > 0 ? m - 1 : 0][n][e] : 0.f, Gp = m > 0 ? acc[ai][1][m > 0 ? m - 1 : 0][n][e] : 0.f;
;                         const float a1 = dpp_prev(A, Ap, 1), a2 = dpp_prev(A, Ap, 2), g1 = dpp_prev(Gv, Gp, 1), g2 = dpp_prev(Gv, Gp, 2);
;                         const float ca = ba[n][e] + wa0[n][e] * a2 + wa1[n][e] * a1 + wa2[n][e] * A, cg = bg[n][e] + wg0[n][e] * g2 + wg1[n][e] * g1 + wg2[n][e] * Gv;
;                         r[4 * n + e] = silu(ca) * cg; }
;                 if (!(m == 0 && fr < 2)) { u32x4 w; w.x = pk2(r[0], r[1]); w.y = pk2(r[2], r[3]); w.z = pk2(r[4], r[5]); w.w = pk2(r[6], r[7]);
;                     *(u32x4*)(ACT + (size_t)(rowt + ai * HALF + m * 16) * NFF + f0) = w; }
;                 __builtin_amdgcn_sched_barrier(0); }
	v_mov_b32_dpp v160, v78 row_shr:1 row_mask:0xf bank_mask:0xf
	v_mov_b32_dpp v167, v79 row_shr:2 row_mask:0xf bank_mask:0xf
	v_mov_b32_dpp v161, v79 row_shr:1 row_mask:0xf bank_mask:0xf
	v_pk_fma_f32 v[166:167], v[102:103], v[166:167], v[114:115]
	v_mov_b32_dpp v173, v163 row_ror:1 row_mask:0xf bank_mask:0xf bound_ctrl:1
	v_pk_fma_f32 v[160:161], v[110:111], v[160:161], v[166:167]
	v_mov_b32_dpp v163, v163 row_ror:2 row_mask:0xf bank_mask:0xf bound_ctrl:1
	v_pk_fma_f32 v[160:161], v[78:79], v[106:107], v[160:161]
	v_mov_b32_dpp v162, v70 row_shr:2 row_mask:0xf bank_mask:0xf
	v_mul_f32_e32 v166, 0xbfb8aa3b, v160
	v_mul_f32_e32 v167, 0xbfb8aa3b, v161
	v_exp_f32_e32 v166, v166
	v_exp_f32_e32 v167, v167
	v_mov_b32_dpp v163, v71 row_shr:2 row_mask:0xf bank_mask:0xf
	v_mov_b32_dpp v172, v70 row_shr:1 row_mask:0xf bank_mask:0xf
	v_add_f32_e32 v166, 1.0, v166
	v_add_f32_e32 v167, 1.0, v167
	v_rcp_f32_e32 v166, v166
	v_rcp_f32_e32 v167, v167
	v_mov_b32_dpp v173, v71 row_shr:1 row_mask:0xf bank_mask:0xf
	v_pk_fma_f32 v[162:163], v[86:87], v[162:163], v[98:99]
	v_pk_mul_f32 v[160:161], v[160:161], v[166:167]
	v_pk_fma_f32 v[162:163], v[90:91], v[172:173], v[162:163]
	s_nop 0
	v_pk_fma_f32 v[162:163], v[70:71], v[94:95], v[162:163]
	s_nop 0
	v_pk_mul_f32 v[166:167], v[162:163], v[160:161]
	v_cvt_pk_bf16_f32 v162, v164, v165
	v_or_b32_e32 v164, 32, v246
	v_mad_i64_i32 v[164:165], s[8:9], v164, s83, v[178:179]
	v_cvt_pk_bf16_f32 v160, v168, v169
	v_cvt_pk_bf16_f32 v161, v170, v171
	v_cvt_pk_bf16_f32 v163, v166, v167
	v_lshl_add_u64 v[164:165], v[164:165], 0, v[176:177]
	global_store_dwordx4 v[164:165], v[160:163], off
	s_nop 1
	v_mov_b32_dpp v160, v124 row_ror:1 row_mask:0xf bank_mask:0xf bound_ctrl:1
	v_mov_b32_dpp v124, v124 row_ror:2 row_mask:0xf bank_mask:0xf bound_ctrl:1
	v_mov_b32_dpp v161, v125 row_ror:1 row_mask:0xf bank_mask:0xf bound_ctrl:1
	v_mov_b32_dpp v125, v125 row_ror:2 row_mask:0xf bank_mask:0xf bound_ctrl:1
	v_mov_b32_dpp v124, v120 row_shr:2 row_mask:0xf bank_mask:0xf
	v_mov_b32_dpp v160, v120 row_shr:1 row_mask:0xf bank_mask:0xf
	v_mov_b32_dpp v125, v121 row_shr:2 row_mask:0xf bank_mask:0xf
	v_mov_b32_dpp v161, v121 row_shr:1 row_mask:0xf bank_mask:0xf
	v_pk_fma_f32 v[124:125], v[152:153], v[124:125], v[156:157]
	v_mov_b32_dpp v162, v116 row_ror:1 row_mask:0xf bank_mask:0xf bound_ctrl:1
	v_pk_fma_f32 v[124:125], v[148:149], v[160:161], v[124:125]
	v_mov_b32_dpp v116, v116 row_ror:2 row_mask:0xf bank_mask:0xf bound_ctrl:1
	v_pk_fma_f32 v[120:121], v[120:121], v[144:145], v[124:125]
	v_mov_b32_dpp v163, v117 row_ror:1 row_mask:0xf bank_mask:0xf bound_ctrl:1
	v_mul_f32_e32 v124, 0xbfb8aa3b, v120
	v_mul_f32_e32 v125, 0xbfb8aa3b, v121
	v_exp_f32_e32 v124, v124
	v_exp_f32_e32 v125, v125
	v_mov_b32_dpp v117, v117 row_ror:2 row_mask:0xf bank_mask:0xf bound_ctrl:1
	v_mov_b32_dpp v116, v80 row_shr:2 row_mask:0xf bank_mask:0xf
	v_add_f32_e32 v124, 1.0, v124
	v_add_f32_e32 v125, 1.0, v125
	v_rcp_f32_e32 v124, v124
	v_rcp_f32_e32 v125, v125
	v_mov_b32_dpp v117, v81 row_shr:2 row_mask:0xf bank_mask:0xf
	v_mov_b32_dpp v162, v80 row_shr:1 row_mask:0xf bank_mask:0xf
	v_mov_b32_dpp v163, v81 row_shr:1 row_mask:0xf bank_mask:0xf
	v_pk_fma_f32 v[116:117], v[128:129], v[116:117], v[140:141]
	s_nop 0
	v_pk_fma_f32 v[116:117], v[132:133], v[162:163], v[116:117]
	s_nop 0
	v_pk_fma_f32 v[80:81], v[80:81], v[136:137], v[116:117]
	v_pk_mul_f32 v[116:117], v[120:121], v[124:125]
	v_mov_b32_dpp v120, v126 row_ror:2 row_mask:0xf bank_mask:0xf bound_ctrl:1
	v_mov_b32_dpp v121, v127 row_ror:2 row_mask:0xf bank_mask:0xf bound_ctrl:1
	v_pk_mul_f32 v[80:81], v[80:81], v[116:117]
	v_mov_b32_dpp v116, v126 row_ror:1 row_mask:0xf bank_mask:0xf bound_ctrl:1
	v_mov_b32_dpp v120, v122 row_shr:2 row_mask:0xf bank_mask:0xf
	v_mov_b32_dpp v117, v127 row_ror:1 row_mask:0xf bank_mask:0xf bound_ctrl:1
	v_mov_b32_dpp v121, v123 row_shr:2 row_mask:0xf bank_mask:0xf
	v_mov_b32_dpp v116, v122 row_shr:1 row_mask:0xf bank_mask:0xf
	v_mov_b32_dpp v117, v123 row_shr:1 row_mask:0xf bank_mask:0xf
	v_pk_fma_f32 v[120:121], v[154:155], v[120:121], v[158:159]
	v_mov_b32_dpp v124, v118 row_ror:1 row_mask:0xf bank_mask:0xf bound_ctrl:1
	v_pk_fma_f32 v[116:117], v[150:151], v[116:117], v[120:121]
	v_mov_b32_dpp v118, v118 row_ror:2 row_mask:0xf bank_mask:0xf bound_ctrl:1
	v_pk_fma_f32 v[116:117], v[122:123], v[146:147], v[116:117]
	v_mov_b32_dpp v125, v119 row_ror:1 row_mask:0xf bank_mask:0xf bound_ctrl:1
	v_mul_f32_e32 v120, 0xbfb8aa3b, v116
	v_mul_f32_e32 v121, 0xbfb8aa3b, v117
	v_exp_f32_e32 v120, v120
	v_exp_f32_e32 v121, v121
	v_mov_b32_dpp v119, v119 row_ror:2 row_mask:0xf bank_mask:0xf bound_ctrl:1
	v_mov_b32_dpp v118, v82 row_shr:2 row_mask:0xf bank_mask:0xf
	v_add_f32_e32 v120, 1.0, v120
	v_add_f32_e32 v121, 1.0, v121
	v_rcp_f32_e32 v120, v120
	v_rcp_f32_e32 v121, v121
	v_mov_b32_dpp v119, v83 row_shr:2 row_mask:0xf bank_mask:0xf
	v_mov_b32_dpp v124, v82 row_shr:1 row_mask:0xf bank_mask:0xf
	v_mov_b32_dpp v125, v83 row_shr:1 row_mask:0xf bank_mask:0xf
	v_pk_fma_f32 v[118:119], v[130:131], v[118:119], v[142:143]
	v_pk_mul_f32 v[116:117], v[116:117], v[120:121]
	v_pk_fma_f32 v[118:119], v[134:135], v[124:125], v[118:119]
	s_nop 0
	v_pk_fma_f32 v[82:83], v[82:83], v[138:139], v[118:119]
	v_mov_b32_dpp v118, v68 row_ror:1 row_mask:0xf bank_mask:0xf bound_ctrl:1
	v_pk_mul_f32 v[82:83], v[82:83], v[116:117]
	v_mov_b32_dpp v116, v76 row_ror:1 row_mask:0xf bank_mask:0xf bound_ctrl:1
	v_mov_b32_dpp v76, v76 row_ror:2 row_mask:0xf bank_mask:0xf bound_ctrl:1
	v_mov_b32_dpp v117, v77 row_ror:1 row_mask:0xf bank_mask:0xf bound_ctrl:1
	v_mov_b32_dpp v77, v77 row_ror:2 row_mask:0xf bank_mask:0xf bound_ctrl:1
; __device__ __forceinline__ unsigned pk2(float lo, float hi) { const f32x2 v = {lo, hi}; return __builtin_bit_cast(unsigned, __builtin_convertvector(v, bf16x2_t)); }
; __device__ __forceinline__ float silu(float x) { return x * __builtin_amdgcn_rcpf(1.f + __builtin_amdgcn_exp2f(-1.4426950408889634f * x)); }
;     __device__ __forceinline__ void operator()(f32x4 (&acc)[2][2][4][2], const Unit& u, int, int, int, int) const {
;     ...
;         for (int ai = 0; ai < 2; ++ai)
; #pragma unroll
;             for (int m = 0; m < 4; ++m) { float r[8];
; #pragma unroll
;                 for (int n = 0; n < 2; ++n)
; #pragma unroll
;                     for (int e = 0; e < 4; ++e) { const float A = acc[ai][0][m][n][e], Gv = acc[ai][1][m][n][e];
;                         const float Ap = m > 0 ? acc[ai][0][m > 0 ? m - 1 : 0][n][e] : 0.f, Gp = m > 0 ? acc[ai][1][m > 0 ? m - 1 : 0][n][e] : 0.f;
;                         const float a1 = dpp_prev(A, Ap, 1), a2 = dpp_prev(A, Ap, 2), g1 = dpp_prev(Gv, Gp, 1), g2 = dpp_prev(Gv, Gp, 2);
;                         const float ca = ba[n][e] + wa0[n][e] * a2 + wa1[n][e] * a1 + wa2[n][e] * A, cg = bg[n][e] + wg0[n][e] * g2 + wg1[n][e] * g1 + wg2[n][e] * Gv;
;                         r[4 * n + e] = silu(ca) * cg; }
;                 if (!(m == 0 && fr < 2)) { u32x4 w; w.x = pk2(r[0], r[1]); w.y = pk2(r[2], r[3]); w.z = pk2(r[4], r[5]); w.w = pk2(r[6], r[7]);
;                     *(u32x4*)(ACT + (size_t)(rowt + ai * HALF + m * 16) * NFF + f0) = w; }
;                 __builtin_amdgcn_sched_barrier(0); }
	v_mov_b32_dpp v76, v72 row_shr:2 row_mask:0xf bank_mask:0xf
	v_mov_b32_dpp v116, v72 row_shr:1 row_mask:0xf bank_mask:0xf
	v_mov_b32_dpp v77, v73 row_shr:2 row_mask:0xf bank_mask:0xf
	v_mov_b32_dpp v117, v73 row_shr:1 row_mask:0xf bank_mask:0xf
	v_pk_fma_f32 v[76:77], v[100:101], v[76:77], v[112:113]
	v_mov_b32_dpp v68, v68 row_ror:2 row_mask:0xf bank_mask:0xf bound_ctrl:1
	v_pk_fma_f32 v[76:77], v[108:109], v[116:117], v[76:77]
	v_mov_b32_dpp v119, v69 row_ror:1 row_mask:0xf bank_mask:0xf bound_ctrl:1
	v_pk_fma_f32 v[72:73], v[72:73], v[104:105], v[76:77]
	v_mov_b32_dpp v69, v69 row_ror:2 row_mask:0xf bank_mask:0xf bound_ctrl:1
	v_mul_f32_e32 v76, 0xbfb8aa3b, v72
	v_mul_f32_e32 v77, 0xbfb8aa3b, v73
	v_exp_f32_e32 v76, v76
	v_exp_f32_e32 v77, v77
	v_mov_b32_dpp v68, v64 row_shr:2 row_mask:0xf bank_mask:0xf
	v_mov_b32_dpp v69, v65 row_shr:2 row_mask:0xf bank_mask:0xf
	v_add_f32_e32 v76, 1.0, v76
	v_add_f32_e32 v77, 1.0, v77
	v_rcp_f32_e32 v76, v76
	v_rcp_f32_e32 v77, v77
	v_mov_b32_dpp v118, v64 row_shr:1 row_mask:0xf bank_mask:0xf
	v_mov_b32_dpp v119, v65 row_shr:1 row_mask:0xf bank_mask:0xf
	v_pk_fma_f32 v[68:69], v[84:85], v[68:69], v[96:97]
	s_nop 0
	v_pk_fma_f32 v[68:69], v[88:89], v[118:119], v[68:69]
	s_nop 0
	v_pk_fma_f32 v[64:65], v[64:65], v[92:93], v[68:69]
	v_pk_mul_f32 v[68:69], v[72:73], v[76:77]
	v_mov_b32_dpp v72, v78 row_ror:2 row_mask:0xf bank_mask:0xf bound_ctrl:1
	v_mov_b32_dpp v73, v79 row_ror:2 row_mask:0xf bank_mask:0xf bound_ctrl:1
	v_pk_mul_f32 v[68:69], v[64:65], v[68:69]
	v_mov_b32_dpp v64, v78 row_ror:1 row_mask:0xf bank_mask:0xf bound_ctrl:1
	v_mov_b32_dpp v72, v74 row_shr:2 row_mask:0xf bank_mask:0xf
	v_mov_b32_dpp v65, v79 row_ror:1 row_mask:0xf bank_mask:0xf bound_ctrl:1
	v_mov_b32_dpp v73, v75 row_shr:2 row_mask:0xf bank_mask:0xf
	v_mov_b32_dpp v64, v74 row_shr:1 row_mask:0xf bank_mask:0xf
	v_mov_b32_dpp v65, v75 row_shr:1 row_mask:0xf bank_mask:0xf
	v_pk_fma_f32 v[72:73], v[102:103], v[72:73], v[114:115]
	v_mov_b32_dpp v76, v70 row_ror:1 row_mask:0xf bank_mask:0xf bound_ctrl:1
	v_pk_fma_f32 v[64:65], v[110:111], v[64:65], v[72:73]
	v_mov_b32_dpp v70, v70 row_ror:2 row_mask:0xf bank_mask:0xf bound_ctrl:1
	v_pk_fma_f32 v[64:65], v[74:75], v[106:107], v[64:65]
	v_mov_b32_dpp v77, v71 row_ror:1 row_mask:0xf bank_mask:0xf bound_ctrl:1
	v_mul_f32_e32 v72, 0xbfb8aa3b, v64
	v_mul_f32_e32 v73, 0xbfb8aa3b, v65
	v_exp_f32_e32 v72, v72
	v_exp_f32_e32 v73, v73
	v_mov_b32_dpp v71, v71 row_ror:2 row_mask:0xf bank_mask:0xf bound_ctrl:1
	v_mov_b32_dpp v70, v66 row_shr:2 row_mask:0xf bank_mask:0xf
	v_add_f32_e32 v72, 1.0, v72
	v_add_f32_e32 v73, 1.0, v73
	v_rcp_f32_e32 v72, v72
	v_rcp_f32_e32 v73, v73
	v_mov_b32_dpp v71, v67 row_shr:2 row_mask:0xf bank_mask:0xf
	v_mov_b32_dpp v76, v66 row_shr:1 row_mask:0xf bank_mask:0xf
	v_mov_b32_dpp v77, v67 row_shr:1 row_mask:0xf bank_mask:0xf
	v_pk_fma_f32 v[70:71], v[86:87], v[70:71], v[98:99]
	v_pk_mul_f32 v[64:65], v[64:65], v[72:73]
	v_pk_fma_f32 v[70:71], v[90:91], v[76:77], v[70:71]
	s_nop 0
	v_pk_fma_f32 v[66:67], v[66:67], v[94:95], v[70:71]
	s_nop 0
	v_pk_mul_f32 v[70:71], v[66:67], v[64:65]
	v_cvt_pk_bf16_f32 v66, v68, v69
	v_or_b32_e32 v68, 48, v246
	v_mad_i64_i32 v[68:69], s[8:9], v68, s83, v[178:179]
	v_cvt_pk_bf16_f32 v64, v80, v81
	v_cvt_pk_bf16_f32 v65, v82, v83
	v_cvt_pk_bf16_f32 v67, v70, v71
	v_lshl_add_u64 v[68:69], v[68:69], 0, v[176:177]
	global_store_dwordx4 v[68:69], v[64:67], off
	s_nop 1
	v_mov_b32_dpp v65, v195 row_ror:1 row_mask:0xf bank_mask:0xf bound_ctrl:1
	v_mov_b32_dpp v67, v195 row_ror:2 row_mask:0xf bank_mask:0xf bound_ctrl:1
	v_mov_b32_e32 v72, v65
	v_mov_b32_e32 v74, v67
	v_mov_b32_e32 v68, v65
	v_mov_b32_e32 v70, v67
	v_mov_b32_e32 v73, v65
	v_mov_b32_e32 v75, v67
	v_mov_b32_e32 v69, v65
	v_mov_b32_e32 v71, v67
	v_mov_b32_e32 v116, v65
	v_mov_b32_e32 v118, v67
	v_mov_b32_e32 v80, v65
	v_mov_b32_e32 v82, v67
	v_mov_b32_e32 v117, v65
	v_mov_b32_e32 v119, v67
	v_mov_b32_e32 v81, v65
	v_mov_b32_e32 v83, v67
	v_mov_b32_e32 v124, v65
	v_mov_b32_e32 v126, v67
	v_mov_b32_e32 v120, v65
	v_mov_b32_e32 v122, v67
	v_mov_b32_e32 v125, v65
	v_mov_b32_e32 v127, v67
	v_mov_b32_e32 v121, v65
	v_mov_b32_e32 v123, v67
	v_mov_b32_e32 v76, v65
	v_mov_b32_e32 v78, v67
	v_mov_b32_e32 v64, v65
	v_mov_b32_e32 v66, v67
	v_mov_b32_e32 v77, v65
	v_mov_b32_e32 v79, v67
	v_mov_b32_dpp v72, v60 row_shr:1 row_mask:0xf bank_mask:0xf
	v_mov_b32_dpp v74, v60 row_shr:2 row_mask:0xf bank_mask:0xf
	v_mov_b32_dpp v68, v56 row_shr:1 row_mask:0xf bank_mask:0xf
	v_mov_b32_dpp v70, v56 row_shr:2 row_mask:0xf bank_mask:0xf
	v_mov_b32_dpp v73, v61 row_shr:1 row_mask:0xf bank_mask:0xf
	v_mov_b32_dpp v75, v61 row_shr:2 row_mask:0xf bank_mask:0xf
	v_mov_b32_dpp v69, v57 row_shr:1 row_mask:0xf bank_mask:0xf
	v_mov_b32_dpp v71, v57 row_shr:2 row_mask:0xf bank_mask:0xf
	v_mov_b32_dpp v116, v62 row_shr:1 row_mask:0xf bank_mask:0xf
	v_mov_b32_dpp v118, v62 row_shr:2 row_mask:0xf bank_mask:0xf
	v_mov_b32_dpp v80, v58 row_shr:1 row_mask:0xf bank_mask:0xf
	v_mov_b32_dpp v82, v58 row_shr:2 row_mask:0xf bank_mask:0xf
	v_mov_b32_dpp v117, v63 row_shr:1 row_mask:0xf bank_mask:0xf
	v_mov_b32_dpp v119, v63 row_shr:2 row_mask:0xf bank_mask:0xf
	v_mov_b32_dpp v81, v59 row_shr:1 row_mask:0xf bank_mask:0xf
	v_mov_b32_dpp v83, v59 row_shr:2 row_mask:0xf bank_mask:0xf
	v_mov_b32_dpp v124, v52 row_shr:1 row_mask:0xf bank_mask:0xf
	v_mov_b32_dpp v126, v52 row_shr:2 row_mask:0xf bank_mask:0xf
	v_mov_b32_dpp v120, v48 row_shr:1 row_mask:0xf bank_mask:0xf
	v_mov_b32_dpp v122, v48 row_shr:2 row_mask:0xf bank_mask:0xf
	v_mov_b32_dpp v125, v53 row_shr:1 row_mask:0xf bank_mask:0xf
	v_mov_b32_dpp v127, v53 row_shr:2 row_mask:0xf bank_mask:0xf
	v_mov_b32_dpp v121, v49 row_shr:1 row_mask:0xf bank_mask:0xf
	v_mov_b32_dpp v123, v49 row_shr:2 row_mask:0xf bank_mask:0xf
	v_mov_b32_dpp v76, v54 row_shr:1 row_mask:0xf bank_mask:0xf
	v_mov_b32_dpp v78, v54 row_shr:2 row_mask:0xf bank_mask:0xf
	v_mov_b32_dpp v64, v50 row_shr:1 row_mask:0xf bank_mask:0xf
	v_mov_b32_dpp v66, v50 row_shr:2 row_mask:0xf bank_mask:0xf
	v_mov_b32_dpp v77, v55 row_shr:1 row_mask:0xf bank_mask:0xf
	v_mov_b32_dpp v79, v55 row_shr:2 row_mask:0xf bank_mask:0xf
	v_mov_b32_dpp v65, v51 row_shr:1 row_mask:0xf bank_mask:0xf
	v_mov_b32_dpp v67, v51 row_shr:2 row_mask:0xf bank_mask:0xf
	s_and_saveexec_b64 s[8:9], s[6:7]
	s_cbranch_execz .LBB0_1470
; __device__ __forceinline__ unsigned pk2(float lo, float hi) { const f32x2 v = {lo, hi}; return __builtin_bit_cast(unsigned, __builtin_convertvector(v, bf16x2_t)); }
; __device__ __forceinline__ float silu(float x) { return x * __builtin_amdgcn_rcpf(1.f + __builtin_amdgcn_exp2f(-1.4426950408889634f * x)); }
;     __device__ __forceinline__ void operator()(f32x4 (&acc)[2][2][4][2], const Unit& u, int, int, int, int) const {
;     ...
;         for (int ai = 0; ai < 2; ++ai)
; #pragma unroll
;             for (int m = 0; m < 4; ++m) { float r[8];
; #pragma unroll
;                 for (int n = 0; n < 2; ++n)
; #pragma unroll
;                     for (int e = 0; e < 4; ++e) { const float A = acc[ai][0][m][n][e], Gv = acc[ai][1][m][n][e];
;                         const float Ap = m > 0 ? acc[ai][0][m > 0 ? m - 1 : 0][n][e] : 0.f, Gp = m > 0 ? acc[ai][1][m > 0 ? m - 1 : 0][n][e] : 0.f;
;                         const float a1 = dpp_prev(A, Ap, 1), a2 = dpp_prev(A, Ap, 2), g1 = dpp_prev(Gv, Gp, 1), g2 = dpp_prev(Gv, Gp, 2);
;                         const float ca = ba[n][e] + wa0[n][e] * a2 + wa1[n][e] * a1 + wa2[n][e] * A, cg = bg[n][e] + wg0[n][e] * g2 + wg1[n][e] * g1 + wg2[n][e] * Gv;
;                         r[4 * n + e] = silu(ca) * cg; }
;                 if (!(m == 0 && fr < 2)) { u32x4 w; w.x = pk2(r[0], r[1]); w.y = pk2(r[2], r[3]); w.z = pk2(r[4], r[5]); w.w = pk2(r[6], r[7]);
;                     *(u32x4*)(ACT + (size_t)(rowt + ai * HALF + m * 16) * NFF + f0) = w; }
;                 __builtin_amdgcn_sched_barrier(0); }
	v_pk_fma_f32 v[126:127], v[100:101], v[126:127], v[112:113]
	v_pk_fma_f32 v[118:119], v[154:155], v[118:119], v[158:159]
	v_pk_fma_f32 v[124:125], v[108:109], v[124:125], v[126:127]
	v_pk_fma_f32 v[116:117], v[150:151], v[116:117], v[118:119]
	v_pk_fma_f32 v[124:125], v[52:53], v[104:105], v[124:125]
	v_pk_fma_f32 v[116:117], v[62:63], v[146:147], v[116:117]
	v_mul_f32_e32 v126, 0xbfb8aa3b, v124
	v_mul_f32_e32 v127, 0xbfb8aa3b, v125
	v_exp_f32_e32 v126, v126
	v_exp_f32_e32 v127, v127
	v_pk_fma_f32 v[122:123], v[84:85], v[122:123], v[96:97]
	v_mul_f32_e32 v118, 0xbfb8aa3b, v116
	v_add_f32_e32 v126, 1.0, v126
	v_add_f32_e32 v127, 1.0, v127
	v_rcp_f32_e32 v126, v126
	v_rcp_f32_e32 v127, v127
	v_pk_fma_f32 v[120:121], v[88:89], v[120:121], v[122:123]
	v_pk_fma_f32 v[74:75], v[152:153], v[74:75], v[156:157]
	v_pk_fma_f32 v[120:121], v[48:49], v[92:93], v[120:121]
	v_pk_mul_f32 v[122:123], v[124:125], v[126:127]
	v_exp_f32_e32 v124, v118
	v_mul_f32_e32 v118, 0xbfb8aa3b, v117
	v_exp_f32_e32 v125, v118
	v_pk_mul_f32 v[118:119], v[120:121], v[122:123]
	v_add_f32_e32 v120, 1.0, v124
	v_rcp_f32_e32 v120, v120
	v_add_f32_e32 v121, 1.0, v125
	v_rcp_f32_e32 v121, v121
	v_pk_fma_f32 v[72:73], v[148:149], v[72:73], v[74:75]
	v_pk_fma_f32 v[82:83], v[130:131], v[82:83], v[142:143]
	v_pk_fma_f32 v[72:73], v[60:61], v[144:145], v[72:73]
	v_pk_fma_f32 v[80:81], v[134:135], v[80:81], v[82:83]
	v_mul_f32_e32 v74, 0xbfb8aa3b, v72
	v_pk_mul_f32 v[82:83], v[116:117], v[120:121]
	v_exp_f32_e32 v116, v74
	v_mul_f32_e32 v74, 0xbfb8aa3b, v73
	v_exp_f32_e32 v117, v74
	v_pk_fma_f32 v[80:81], v[58:59], v[138:139], v[80:81]
	v_pk_fma_f32 v[70:71], v[128:129], v[70:71], v[140:141]
	v_pk_mul_f32 v[74:75], v[80:81], v[82:83]
	v_add_f32_e32 v80, 1.0, v116
	v_add_f32_e32 v81, 1.0, v117
	v_rcp_f32_e32 v80, v80
	v_rcp_f32_e32 v81, v81
	v_pk_fma_f32 v[68:69], v[132:133], v[68:69], v[70:71]
	v_pk_fma_f32 v[66:67], v[86:87], v[66:67], v[98:99]
	v_pk_fma_f32 v[68:69], v[56:57], v[136:137], v[68:69]
	v_pk_mul_f32 v[70:71], v[72:73], v[80:81]
	v_pk_fma_f32 v[72:73], v[102:103], v[78:79], v[114:115]
	v_pk_mul_f32 v[68:69], v[68:69], v[70:71]
	v_pk_fma_f32 v[72:73], v[110:111], v[76:77], v[72:73]
	v_pk_fma_f32 v[64:65], v[90:91], v[64:65], v[66:67]
	v_pk_fma_f32 v[72:73], v[54:55], v[106:107], v[72:73]
	v_pk_fma_f32 v[64:65], v[50:51], v[94:95], v[64:65]
	v_mul_f32_e32 v76, 0xbfb8aa3b, v72
	v_mul_f32_e32 v77, 0xbfb8aa3b, v73
	v_exp_f32_e32 v76, v76
	v_exp_f32_e32 v77, v77
	v_add_f32_e32 v70, 1.0, v76
	v_add_f32_e32 v71, 1.0, v77
	v_rcp_f32_e32 v70, v70
	v_rcp_f32_e32 v71, v71
	s_nop 0
	v_pk_mul_f32 v[66:67], v[72:73], v[70:71]
	s_nop 0
	v_pk_mul_f32 v[70:71], v[64:65], v[66:67]
	v_cvt_pk_bf16_f32 v64, v68, v69
	v_mov_b64_e32 v[68:69], s[20:21]
	v_mad_i64_i32 v[68:69], s[6:7], v247, s83, v[68:69]
	v_cvt_pk_bf16_f32 v65, v74, v75
	v_cvt_pk_bf16_f32 v66, v118, v119
	v_cvt_pk_bf16_f32 v67, v70, v71
	v_lshl_add_u64 v[68:69], v[208:209], 1, v[68:69]
	global_store_dwordx4 v[68:69], v[64:67], off
.LBB0_1470:
	s_or_b64 exec, exec, s[8:9]
	s_nop 0
	v_mov_b32_dpp v64, v60 row_ror:1 row_mask:0xf bank_mask:0xf bound_ctrl:1
	v_mov_b32_dpp v60, v60 row_ror:2 row_mask:0xf bank_mask:0xf bound_ctrl:1
	v_mov_b32_dpp v65, v61 row_ror:1 row_mask:0xf bank_mask:0xf bound_ctrl:1
	v_mov_b32_dpp v61, v61 row_ror:2 row_mask:0xf bank_mask:0xf bound_ctrl:1
	v_mov_b32_dpp v60, v44 row_shr:2 row_mask:0xf bank_mask:0xf
	v_mov_b32_dpp v64, v44 row_shr:1 row_mask:0xf bank_mask:0xf
	v_mov_b32_dpp v61, v45 row_shr:2 row_mask:0xf bank_mask:0xf
	v_mov_b32_dpp v65, v45 row_shr:1 row_mask:0xf bank_mask:0xf
	v_pk_fma_f32 v[60:61], v[152:153], v[60:61], v[156:157]
	v_mov_b32_dpp v66, v56 row_ror:1 row_mask:0xf bank_mask:0xf bound_ctrl:1
	v_pk_fma_f32 v[60:61], v[148:149], v[64:65], v[60:61]
	v_mov_b32_dpp v56, v56 row_ror:2 row_mask:0xf bank_mask:0xf bound_ctrl:1
	v_pk_fma_f32 v[60:61], v[44:45], v[144:145], v[60:61]
	v_mov_b32_dpp v67, v57 row_ror:1 row_mask:0xf bank_mask:0xf bound_ctrl:1
	v_mul_f32_e32 v64, 0xbfb8aa3b, v60
	v_mul_f32_e32 v65, 0xbfb8aa3b, v61
	v_exp_f32_e32 v64, v64
	v_exp_f32_e32 v65, v65
	v_mov_b32_dpp v57, v57 row_ror:2 row_mask:0xf bank_mask:0xf bound_ctrl:1
	v_mov_b32_dpp v56, v40 row_shr:2 row_mask:0xf bank_mask:0xf
	v_add_f32_e32 v64, 1.0, v64
	v_add_f32_e32 v65, 1.0, v65
	v_rcp_f32_e32 v64, v64
	v_rcp_f32_e32 v65, v65
	v_mov_b32_dpp v57, v41 row_shr:2 row_mask:0xf bank_mask:0xf
	v_mov_b32_dpp v66, v40 row_shr:1 row_mask:0xf bank_mask:0xf
	v_mov_b32_dpp v67, v41 row_shr:1 row_mask:0xf bank_mask:0xf
	v_pk_fma_f32 v[56:57], v[128:129], v[56:57], v[140:141]
	v_pk_mul_f32 v[60:61], v[60:61], v[64:65]
	v_pk_fma_f32 v[56:57], v[132:133], v[66:67], v[56:57]
	v_mov_b32_dpp v64, v58 row_ror:1 row_mask:0xf bank_mask:0xf bound_ctrl:1
	v_pk_fma_f32 v[56:57], v[40:41], v[136:137], v[56:57]
	v_mov_b32_dpp v58, v58 row_ror:2 row_mask:0xf bank_mask:0xf bound_ctrl:1
	v_pk_mul_f32 v[56:57], v[56:57], v[60:61]
	v_mov_b32_dpp v60, v62 row_ror:1 row_mask:0xf bank_mask:0xf bound_ctrl:1
	v_mov_b32_dpp v62, v62 row_ror:2 row_mask:0xf bank_mask:0xf bound_ctrl:1
	v_mov_b32_dpp v61, v63 row_ror:1 row_mask:0xf bank_mask:0xf bound_ctrl:1
	v_mov_b32_dpp v63, v63 row_ror:2 row_mask:0xf bank_mask:0xf bound_ctrl:1
	v_mov_b32_dpp v62, v46 row_shr:2 row_mask:0xf bank_mask:0xf
	v_mov_b32_dpp v60, v46 row_shr:1 row_mask:0xf bank_mask:0xf
	v_mov_b32_dpp v63, v47 row_shr:2 row_mask:0xf bank_mask:0xf
	v_mov_b32_dpp v61, v47 row_shr:1 row_mask:0xf bank_mask:0xf
	v_pk_fma_f32 v[62:63], v[154:155], v[62:63], v[158:159]
	v_mov_b32_dpp v65, v59 row_ror:1 row_mask:0xf bank_mask:0xf bound_ctrl:1
	v_pk_fma_f32 v[60:61], v[150:151], v[60:61], v[62:63]
; __device__ __forceinline__ unsigned pk2(float lo, float hi) { const f32x2 v = {lo, hi}; return __builtin_bit_cast(unsigned, __builtin_convertvector(v, bf16x2_t)); }
; __device__ __forceinline__ float silu(float x) { return x * __builtin_amdgcn_rcpf(1.f + __builtin_amdgcn_exp2f(-1.4426950408889634f * x)); }
;     __device__ __forceinline__ void operator()(f32x4 (&acc)[2][2][4][2], const Unit& u, int, int, int, int) const {
;     ...
;         for (int ai = 0; ai < 2; ++ai)
; #pragma unroll
;             for (int m = 0; m < 4; ++m) { float r[8];
; #pragma unroll
;                 for (int n = 0; n < 2; ++n)
; #pragma unroll
;                     for (int e = 0; e < 4; ++e) { const float A = acc[ai][0][m][n][e], Gv = acc[ai][1][m][n][e];
;                         const float Ap = m > 0 ? acc[ai][0][m > 0 ? m - 1 : 0][n][e] : 0.f, Gp = m > 0 ? acc[ai][1][m > 0 ? m - 1 : 0][n][e] : 0.f;
;                         const float a1 = dpp_prev(A, Ap, 1), a2 = dpp_prev(A, Ap, 2), g1 = dpp_prev(Gv, Gp, 1), g2 = dpp_prev(Gv, Gp, 2);
;                         const float ca = ba[n][e] + wa0[n][e] * a2 + wa1[n][e] * a1 + wa2[n][e] * A, cg = bg[n][e] + wg0[n][e] * g2 + wg1[n][e] * g1 + wg2[n][e] * Gv;
;                         r[4 * n + e] = silu(ca) * cg; }
;                 if (!(m == 0 && fr < 2)) { u32x4 w; w.x = pk2(r[0], r[1]); w.y = pk2(r[2], r[3]); w.z = pk2(r[4], r[5]); w.w = pk2(r[6], r[7]);
;                     *(u32x4*)(ACT + (size_t)(rowt + ai * HALF + m * 16) * NFF + f0) = w; }
;                 __builtin_amdgcn_sched_barrier(0); }
	v_mov_b32_dpp v59, v59 row_ror:2 row_mask:0xf bank_mask:0xf bound_ctrl:1
	v_pk_fma_f32 v[60:61], v[46:47], v[146:147], v[60:61]
	v_mov_b32_dpp v58, v42 row_shr:2 row_mask:0xf bank_mask:0xf
	v_mul_f32_e32 v62, 0xbfb8aa3b, v60
	v_mul_f32_e32 v63, 0xbfb8aa3b, v61
	v_exp_f32_e32 v62, v62
	v_exp_f32_e32 v63, v63
	v_mov_b32_dpp v59, v43 row_shr:2 row_mask:0xf bank_mask:0xf
	v_mov_b32_dpp v64, v42 row_shr:1 row_mask:0xf bank_mask:0xf
	v_add_f32_e32 v62, 1.0, v62
	v_add_f32_e32 v63, 1.0, v63
	v_rcp_f32_e32 v62, v62
	v_rcp_f32_e32 v63, v63
	v_mov_b32_dpp v65, v43 row_shr:1 row_mask:0xf bank_mask:0xf
	v_pk_fma_f32 v[58:59], v[130:131], v[58:59], v[142:143]
	v_pk_mul_f32 v[60:61], v[60:61], v[62:63]
	v_pk_fma_f32 v[58:59], v[134:135], v[64:65], v[58:59]
	v_mov_b32_dpp v62, v48 row_ror:1 row_mask:0xf bank_mask:0xf bound_ctrl:1
	v_pk_fma_f32 v[58:59], v[42:43], v[138:139], v[58:59]
	v_mov_b32_dpp v48, v48 row_ror:2 row_mask:0xf bank_mask:0xf bound_ctrl:1
	v_pk_mul_f32 v[58:59], v[58:59], v[60:61]
	v_mov_b32_dpp v60, v52 row_ror:1 row_mask:0xf bank_mask:0xf bound_ctrl:1
	v_mov_b32_dpp v52, v52 row_ror:2 row_mask:0xf bank_mask:0xf bound_ctrl:1
	v_mov_b32_dpp v61, v53 row_ror:1 row_mask:0xf bank_mask:0xf bound_ctrl:1
	v_mov_b32_dpp v53, v53 row_ror:2 row_mask:0xf bank_mask:0xf bound_ctrl:1
	v_mov_b32_dpp v52, v36 row_shr:2 row_mask:0xf bank_mask:0xf
	v_mov_b32_dpp v60, v36 row_shr:1 row_mask:0xf bank_mask:0xf
	v_mov_b32_dpp v53, v37 row_shr:2 row_mask:0xf bank_mask:0xf
	v_mov_b32_dpp v61, v37 row_shr:1 row_mask:0xf bank_mask:0xf
	v_pk_fma_f32 v[52:53], v[100:101], v[52:53], v[112:113]
	v_mov_b32_dpp v63, v49 row_ror:1 row_mask:0xf bank_mask:0xf bound_ctrl:1
	v_pk_fma_f32 v[52:53], v[108:109], v[60:61], v[52:53]
	v_mov_b32_dpp v49, v49 row_ror:2 row_mask:0xf bank_mask:0xf bound_ctrl:1
	v_pk_fma_f32 v[52:53], v[36:37], v[104:105], v[52:53]
	v_mov_b32_dpp v48, v32 row_shr:2 row_mask:0xf bank_mask:0xf
	v_mul_f32_e32 v60, 0xbfb8aa3b, v52
	v_mul_f32_e32 v61, 0xbfb8aa3b, v53
	v_exp_f32_e32 v60, v60
	v_exp_f32_e32 v61, v61
	v_mov_b32_dpp v49, v33 row_shr:2 row_mask:0xf bank_mask:0xf
	v_mov_b32_dpp v62, v32 row_shr:1 row_mask:0xf bank_mask:0xf
	v_add_f32_e32 v60, 1.0, v60
	v_add_f32_e32 v61, 1.0, v61
	v_rcp_f32_e32 v60, v60
	v_rcp_f32_e32 v61, v61
	v_mov_b32_dpp v63, v33 row_shr:1 row_mask:0xf bank_mask:0xf
	v_pk_fma_f32 v[48:49], v[84:85], v[48:49], v[96:97]
	v_pk_mul_f32 v[52:53], v[52:53], v[60:61]
	v_pk_fma_f32 v[48:49], v[88:89], v[62:63], v[48:49]
	v_mov_b32_dpp v60, v50 row_ror:1 row_mask:0xf bank_mask:0xf bound_ctrl:1
	v_pk_fma_f32 v[48:49], v[32:33], v[92:93], v[48:49]
	v_mov_b32_dpp v50, v50 row_ror:2 row_mask:0xf bank_mask:0xf bound_ctrl:1
	v_pk_mul_f32 v[48:49], v[48:49], v[52:53]
	v_mov_b32_dpp v52, v54 row_ror:1 row_mask:0xf bank_mask:0xf bound_ctrl:1
	v_mov_b32_dpp v54, v54 row_ror:2 row_mask:0xf bank_mask:0xf bound_ctrl:1
	v_mov_b32_dpp v53, v55 row_ror:1 row_mask:0xf bank_mask:0xf bound_ctrl:1
	v_mov_b32_dpp v55, v55 row_ror:2 row_mask:0xf bank_mask:0xf bound_ctrl:1
	v_mov_b32_dpp v54, v38 row_shr:2 row_mask:0xf bank_mask:0xf
	v_mov_b32_dpp v52, v38 row_shr:1 row_mask:0xf bank_mask:0xf
	v_mov_b32_dpp v55, v39 row_shr:2 row_mask:0xf bank_mask:0xf
	v_mov_b32_dpp v53, v39 row_shr:1 row_mask:0xf bank_mask:0xf
	v_pk_fma_f32 v[54:55], v[102:103], v[54:55], v[114:115]
	v_mov_b32_dpp v61, v51 row_ror:1 row_mask:0xf bank_mask:0xf bound_ctrl:1
	v_pk_fma_f32 v[52:53], v[110:111], v[52:53], v[54:55]
	v_mov_b32_dpp v51, v51 row_ror:2 row_mask:0xf bank_mask:0xf bound_ctrl:1
	v_pk_fma_f32 v[52:53], v[38:39], v[106:107], v[52:53]
	v_mov_b32_dpp v50, v34 row_shr:2 row_mask:0xf bank_mask:0xf
	v_mul_f32_e32 v54, 0xbfb8aa3b, v52
	v_mul_f32_e32 v55, 0xbfb8aa3b, v53
	v_exp_f32_e32 v54, v54
	v_exp_f32_e32 v55, v55
	v_mov_b32_dpp v51, v35 row_shr:2 row_mask:0xf bank_mask:0xf
	v_mov_b32_dpp v60, v34 row_shr:1 row_mask:0xf bank_mask:0xf
	v_add_f32_e32 v54, 1.0, v54
	v_add_f32_e32 v55, 1.0, v55
	v_rcp_f32_e32 v54, v54
	v_rcp_f32_e32 v55, v55
	v_mov_b32_dpp v61, v35 row_shr:1 row_mask:0xf bank_mask:0xf
	v_pk_fma_f32 v[50:51], v[86:87], v[50:51], v[98:99]
	v_pk_mul_f32 v[52:53], v[52:53], v[54:55]
	v_pk_fma_f32 v[50:51], v[90:91], v[60:61], v[50:51]
	s_nop 0
	v_pk_fma_f32 v[50:51], v[34:35], v[94:95], v[50:51]
	s_nop 0
	v_pk_mul_f32 v[54:55], v[50:51], v[52:53]
	v_cvt_pk_bf16_f32 v52, v48, v49
	v_cvt_pk_bf16_f32 v53, v54, v55
	v_add_u32_e32 v54, 0x90, v246
	v_mov_b64_e32 v[48:49], s[20:21]
	v_mad_i64_i32 v[54:55], s[6:7], v54, s83, v[48:49]
	v_cvt_pk_bf16_f32 v50, v56, v57
	v_cvt_pk_bf16_f32 v51, v58, v59
	v_lshl_add_u64 v[54:55], v[54:55], 0, v[176:177]
	global_store_dwordx4 v[54:55], v[50:53], off
	s_nop 1
	v_mov_b32_dpp v50, v44 row_ror:1 row_mask:0xf bank_mask:0xf bound_ctrl:1
	v_mov_b32_dpp v44, v44 row_ror:2 row_mask:0xf bank_mask:0xf bound_ctrl:1
	v_mov_b32_dpp v51, v45 row_ror:1 row_mask:0xf bank_mask:0xf bound_ctrl:1
	v_mov_b32_dpp v45, v45 row_ror:2 row_mask:0xf bank_mask:0xf bound_ctrl:1
	v_mov_b32_dpp v44, v28 row_shr:2 row_mask:0xf bank_mask:0xf
	v_mov_b32_dpp v50, v28 row_shr:1 row_mask:0xf bank_mask:0xf
	v_mov_b32_dpp v45, v29 row_shr:2 row_mask:0xf bank_mask:0xf
	v_mov_b32_dpp v51, v29 row_shr:1 row_mask:0xf bank_mask:0xf
	v_pk_fma_f32 v[44:45], v[152:153], v[44:45], v[156:157]
	v_mov_b32_dpp v52, v40 row_ror:1 row_mask:0xf bank_mask:0xf bound_ctrl:1
	v_pk_fma_f32 v[44:45], v[148:149], v[50:51], v[44:45]
	v_mov_b32_dpp v40, v40 row_ror:2 row_mask:0xf bank_mask:0xf bound_ctrl:1
	v_pk_fma_f32 v[44:45], v[28:29], v[144:145], v[44:45]
	v_mov_b32_dpp v53, v41 row_ror:1 row_mask:0xf bank_mask:0xf bound_ctrl:1
	v_mul_f32_e32 v50, 0xbfb8aa3b, v44
; __device__ __forceinline__ unsigned pk2(float lo, float hi) { const f32x2 v = {lo, hi}; return __builtin_bit_cast(unsigned, __builtin_convertvector(v, bf16x2_t)); }
; __device__ __forceinline__ float silu(float x) { return x * __builtin_amdgcn_rcpf(1.f + __builtin_amdgcn_exp2f(-1.4426950408889634f * x)); }
;     __device__ __forceinline__ void operator()(f32x4 (&acc)[2][2][4][2], const Unit& u, int, int, int, int) const {
;     ...
;         for (int ai = 0; ai < 2; ++ai)
; #pragma unroll
;             for (int m = 0; m < 4; ++m) { float r[8];
; #pragma unroll
;                 for (int n = 0; n < 2; ++n)
; #pragma unroll
;                     for (int e = 0; e < 4; ++e) { const float A = acc[ai][0][m][n][e], Gv = acc[ai][1][m][n][e];
;                         const float Ap = m > 0 ? acc[ai][0][m > 0 ? m - 1 : 0][n][e] : 0.f, Gp = m > 0 ? acc[ai][1][m > 0 ? m - 1 : 0][n][e] : 0.f;
;                         const float a1 = dpp_prev(A, Ap, 1), a2 = dpp_prev(A, Ap, 2), g1 = dpp_prev(Gv, Gp, 1), g2 = dpp_prev(Gv, Gp, 2);
;                         const float ca = ba[n][e] + wa0[n][e] * a2 + wa1[n][e] * a1 + wa2[n][e] * A, cg = bg[n][e] + wg0[n][e] * g2 + wg1[n][e] * g1 + wg2[n][e] * Gv;
;                         r[4 * n + e] = silu(ca) * cg; }
;                 if (!(m == 0 && fr < 2)) { u32x4 w; w.x = pk2(r[0], r[1]); w.y = pk2(r[2], r[3]); w.z = pk2(r[4], r[5]); w.w = pk2(r[6], r[7]);
;                     *(u32x4*)(ACT + (size_t)(rowt + ai * HALF + m * 16) * NFF + f0) = w; }
;                 __builtin_amdgcn_sched_barrier(0); }
	v_mul_f32_e32 v51, 0xbfb8aa3b, v45
	v_exp_f32_e32 v50, v50
	v_exp_f32_e32 v51, v51
	v_mov_b32_dpp v41, v41 row_ror:2 row_mask:0xf bank_mask:0xf bound_ctrl:1
	v_mov_b32_dpp v40, v20 row_shr:2 row_mask:0xf bank_mask:0xf
	v_add_f32_e32 v50, 1.0, v50
	v_add_f32_e32 v51, 1.0, v51
	v_rcp_f32_e32 v50, v50
	v_rcp_f32_e32 v51, v51
	v_mov_b32_dpp v41, v21 row_shr:2 row_mask:0xf bank_mask:0xf
	v_mov_b32_dpp v52, v20 row_shr:1 row_mask:0xf bank_mask:0xf
	v_mov_b32_dpp v53, v21 row_shr:1 row_mask:0xf bank_mask:0xf
	v_pk_fma_f32 v[40:41], v[128:129], v[40:41], v[140:141]
	v_pk_mul_f32 v[44:45], v[44:45], v[50:51]
	v_pk_fma_f32 v[40:41], v[132:133], v[52:53], v[40:41]
	v_mov_b32_dpp v50, v42 row_ror:1 row_mask:0xf bank_mask:0xf bound_ctrl:1
	v_pk_fma_f32 v[40:41], v[20:21], v[136:137], v[40:41]
	v_mov_b32_dpp v42, v42 row_ror:2 row_mask:0xf bank_mask:0xf bound_ctrl:1
	v_pk_mul_f32 v[40:41], v[40:41], v[44:45]
	v_mov_b32_dpp v44, v46 row_ror:1 row_mask:0xf bank_mask:0xf bound_ctrl:1
	v_mov_b32_dpp v46, v46 row_ror:2 row_mask:0xf bank_mask:0xf bound_ctrl:1
	v_mov_b32_dpp v45, v47 row_ror:1 row_mask:0xf bank_mask:0xf bound_ctrl:1
	v_mov_b32_dpp v47, v47 row_ror:2 row_mask:0xf bank_mask:0xf bound_ctrl:1
	v_mov_b32_dpp v46, v30 row_shr:2 row_mask:0xf bank_mask:0xf
	v_mov_b32_dpp v44, v30 row_shr:1 row_mask:0xf bank_mask:0xf
	v_mov_b32_dpp v47, v31 row_shr:2 row_mask:0xf bank_mask:0xf
	v_mov_b32_dpp v45, v31 row_shr:1 row_mask:0xf bank_mask:0xf
	v_pk_fma_f32 v[46:47], v[154:155], v[46:47], v[158:159]
	v_mov_b32_dpp v51, v43 row_ror:1 row_mask:0xf bank_mask:0xf bound_ctrl:1
	v_pk_fma_f32 v[44:45], v[150:151], v[44:45], v[46:47]
	v_mov_b32_dpp v43, v43 row_ror:2 row_mask:0xf bank_mask:0xf bound_ctrl:1
	v_pk_fma_f32 v[44:45], v[30:31], v[146:147], v[44:45]
	v_mov_b32_dpp v42, v22 row_shr:2 row_mask:0xf bank_mask:0xf
	v_mul_f32_e32 v46, 0xbfb8aa3b, v44
	v_mul_f32_e32 v47, 0xbfb8aa3b, v45
	v_exp_f32_e32 v46, v46
	v_exp_f32_e32 v47, v47
	v_mov_b32_dpp v43, v23 row_shr:2 row_mask:0xf bank_mask:0xf
	v_mov_b32_dpp v50, v22 row_shr:1 row_mask:0xf bank_mask:0xf
	v_add_f32_e32 v46, 1.0, v46
	v_add_f32_e32 v47, 1.0, v47
	v_rcp_f32_e32 v46, v46
	v_rcp_f32_e32 v47, v47
	v_mov_b32_dpp v51, v23 row_shr:1 row_mask:0xf bank_mask:0xf
	v_pk_fma_f32 v[42:43], v[130:131], v[42:43], v[142:143]
	v_pk_mul_f32 v[44:45], v[44:45], v[46:47]
	v_pk_fma_f32 v[42:43], v[134:135], v[50:51], v[42:43]
	v_mov_b32_dpp v46, v32 row_ror:1 row_mask:0xf bank_mask:0xf bound_ctrl:1
	v_pk_fma_f32 v[42:43], v[22:23], v[138:139], v[42:43]
	v_mov_b32_dpp v32, v32 row_ror:2 row_mask:0xf bank_mask:0xf bound_ctrl:1
	v_pk_mul_f32 v[42:43], v[42:43], v[44:45]
	v_mov_b32_dpp v44, v36 row_ror:1 row_mask:0xf bank_mask:0xf bound_ctrl:1
	v_mov_b32_dpp v36, v36 row_ror:2 row_mask:0xf bank_mask:0xf bound_ctrl:1
	v_mov_b32_dpp v45, v37 row_ror:1 row_mask:0xf bank_mask:0xf bound_ctrl:1
	v_mov_b32_dpp v37, v37 row_ror:2 row_mask:0xf bank_mask:0xf bound_ctrl:1
	v_mov_b32_dpp v36, v12 row_shr:2 row_mask:0xf bank_mask:0xf
	v_mov_b32_dpp v44, v12 row_shr:1 row_mask:0xf bank_mask:0xf
	v_mov_b32_dpp v37, v13 row_shr:2 row_mask:0xf bank_mask:0xf
	v_mov_b32_dpp v45, v13 row_shr:1 row_mask:0xf bank_mask:0xf
	v_pk_fma_f32 v[36:37], v[100:101], v[36:37], v[112:113]
	v_mov_b32_dpp v47, v33 row_ror:1 row_mask:0xf bank_mask:0xf bound_ctrl:1
	v_pk_fma_f32 v[36:37], v[108:109], v[44:45], v[36:37]
	v_mov_b32_dpp v33, v33 row_ror:2 row_mask:0xf bank_mask:0xf bound_ctrl:1
	v_pk_fma_f32 v[36:37], v[12:13], v[104:105], v[36:37]
	v_mov_b32_dpp v32, v4 row_shr:2 row_mask:0xf bank_mask:0xf
	v_mul_f32_e32 v44, 0xbfb8aa3b, v36
	v_mul_f32_e32 v45, 0xbfb8aa3b, v37
	v_exp_f32_e32 v44, v44
	v_exp_f32_e32 v45, v45
	v_mov_b32_dpp v33, v5 row_shr:2 row_mask:0xf bank_mask:0xf
	v_mov_b32_dpp v46, v4 row_shr:1 row_mask:0xf bank_mask:0xf
	v_add_f32_e32 v44, 1.0, v44
	v_add_f32_e32 v45, 1.0, v45
	v_rcp_f32_e32 v44, v44
	v_rcp_f32_e32 v45, v45
	v_mov_b32_dpp v47, v5 row_shr:1 row_mask:0xf bank_mask:0xf
	v_pk_fma_f32 v[32:33], v[84:85], v[32:33], v[96:97]
	v_pk_mul_f32 v[36:37], v[36:37], v[44:45]
	v_pk_fma_f32 v[32:33], v[88:89], v[46:47], v[32:33]
	v_mov_b32_dpp v44, v34 row_ror:1 row_mask:0xf bank_mask:0xf bound_ctrl:1
	v_pk_fma_f32 v[32:33], v[4:5], v[92:93], v[32:33]
	v_mov_b32_dpp v34, v34 row_ror:2 row_mask:0xf bank_mask:0xf bound_ctrl:1
	v_pk_mul_f32 v[36:37], v[32:33], v[36:37]
	v_mov_b32_dpp v32, v38 row_ror:1 row_mask:0xf bank_mask:0xf bound_ctrl:1
	v_mov_b32_dpp v38, v38 row_ror:2 row_mask:0xf bank_mask:0xf bound_ctrl:1
	v_mov_b32_dpp v33, v39 row_ror:1 row_mask:0xf bank_mask:0xf bound_ctrl:1
	v_mov_b32_dpp v39, v39 row_ror:2 row_mask:0xf bank_mask:0xf bound_ctrl:1
	v_mov_b32_dpp v38, v14 row_shr:2 row_mask:0xf bank_mask:0xf
	v_mov_b32_dpp v32, v14 row_shr:1 row_mask:0xf bank_mask:0xf
	v_mov_b32_dpp v39, v15 row_shr:2 row_mask:0xf bank_mask:0xf
	v_mov_b32_dpp v33, v15 row_shr:1 row_mask:0xf bank_mask:0xf
	v_pk_fma_f32 v[38:39], v[102:103], v[38:39], v[114:115]
	v_mov_b32_dpp v45, v35 row_ror:1 row_mask:0xf bank_mask:0xf bound_ctrl:1
	v_pk_fma_f32 v[32:33], v[110:111], v[32:33], v[38:39]
	v_mov_b32_dpp v35, v35 row_ror:2 row_mask:0xf bank_mask:0xf bound_ctrl:1
	v_pk_fma_f32 v[32:33], v[14:15], v[106:107], v[32:33]
	v_mov_b32_dpp v34, v6 row_shr:2 row_mask:0xf bank_mask:0xf
	v_mul_f32_e32 v38, 0xbfb8aa3b, v32
	v_mul_f32_e32 v39, 0xbfb8aa3b, v33
	v_exp_f32_e32 v38, v38
	v_exp_f32_e32 v39, v39
	v_mov_b32_dpp v35, v7 row_shr:2 row_mask:0xf bank_mask:0xf
	v_mov_b32_dpp v44, v6 row_shr:1 row_mask:0xf bank_mask:0xf
	v_add_f32_e32 v38, 1.0, v38
	v_add_f32_e32 v39, 1.0, v39
	v_rcp_f32_e32 v38, v38
	v_rcp_f32_e32 v39, v39
	v_mov_b32_dpp v45, v7 row_shr:1 row_mask:0xf bank_mask:0xf
; __device__ __forceinline__ unsigned pk2(float lo, float hi) { const f32x2 v = {lo, hi}; return __builtin_bit_cast(unsigned, __builtin_convertvector(v, bf16x2_t)); }
; __device__ __forceinline__ float silu(float x) { return x * __builtin_amdgcn_rcpf(1.f + __builtin_amdgcn_exp2f(-1.4426950408889634f * x)); }
;     __device__ __forceinline__ void operator()(f32x4 (&acc)[2][2][4][2], const Unit& u, int, int, int, int) const {
;     ...
;         for (int ai = 0; ai < 2; ++ai)
; #pragma unroll
;             for (int m = 0; m < 4; ++m) { float r[8];
; #pragma unroll
;                 for (int n = 0; n < 2; ++n)
; #pragma unroll
;                     for (int e = 0; e < 4; ++e) { const float A = acc[ai][0][m][n][e], Gv = acc[ai][1][m][n][e];
;                         const float Ap = m > 0 ? acc[ai][0][m > 0 ? m - 1 : 0][n][e] : 0.f, Gp = m > 0 ? acc[ai][1][m > 0 ? m - 1 : 0][n][e] : 0.f;
;                         const float a1 = dpp_prev(A, Ap, 1), a2 = dpp_prev(A, Ap, 2), g1 = dpp_prev(Gv, Gp, 1), g2 = dpp_prev(Gv, Gp, 2);
;                         const float ca = ba[n][e] + wa0[n][e] * a2 + wa1[n][e] * a1 + wa2[n][e] * A, cg = bg[n][e] + wg0[n][e] * g2 + wg1[n][e] * g1 + wg2[n][e] * Gv;
;                         r[4 * n + e] = silu(ca) * cg; }
;                 if (!(m == 0 && fr < 2)) { u32x4 w; w.x = pk2(r[0], r[1]); w.y = pk2(r[2], r[3]); w.z = pk2(r[4], r[5]); w.w = pk2(r[6], r[7]);
;                     *(u32x4*)(ACT + (size_t)(rowt + ai * HALF + m * 16) * NFF + f0) = w; }
;                 __builtin_amdgcn_sched_barrier(0); }
	v_pk_fma_f32 v[34:35], v[86:87], v[34:35], v[98:99]
	v_pk_mul_f32 v[32:33], v[32:33], v[38:39]
	v_pk_fma_f32 v[34:35], v[90:91], v[44:45], v[34:35]
	s_nop 0
	v_pk_fma_f32 v[34:35], v[6:7], v[94:95], v[34:35]
	s_nop 0
	v_pk_mul_f32 v[38:39], v[34:35], v[32:33]
	v_cvt_pk_bf16_f32 v34, v36, v37
	v_add_u32_e32 v36, 0xa0, v246
	v_mad_i64_i32 v[36:37], s[6:7], v36, s83, v[48:49]
	v_cvt_pk_bf16_f32 v32, v40, v41
	v_cvt_pk_bf16_f32 v33, v42, v43
	v_cvt_pk_bf16_f32 v35, v38, v39
	v_lshl_add_u64 v[36:37], v[36:37], 0, v[176:177]
	global_store_dwordx4 v[36:37], v[32:35], off
	s_nop 1
	v_mov_b32_dpp v32, v28 row_ror:1 row_mask:0xf bank_mask:0xf bound_ctrl:1
	v_mov_b32_dpp v28, v28 row_ror:2 row_mask:0xf bank_mask:0xf bound_ctrl:1
	v_mov_b32_dpp v33, v29 row_ror:1 row_mask:0xf bank_mask:0xf bound_ctrl:1
	v_mov_b32_dpp v29, v29 row_ror:2 row_mask:0xf bank_mask:0xf bound_ctrl:1
	v_mov_b32_dpp v28, v24 row_shr:2 row_mask:0xf bank_mask:0xf
	v_mov_b32_dpp v32, v24 row_shr:1 row_mask:0xf bank_mask:0xf
	v_mov_b32_dpp v29, v25 row_shr:2 row_mask:0xf bank_mask:0xf
	v_mov_b32_dpp v33, v25 row_shr:1 row_mask:0xf bank_mask:0xf
	v_pk_fma_f32 v[28:29], v[152:153], v[28:29], v[156:157]
	v_mov_b32_dpp v34, v20 row_ror:1 row_mask:0xf bank_mask:0xf bound_ctrl:1
	v_pk_fma_f32 v[28:29], v[148:149], v[32:33], v[28:29]
	v_mov_b32_dpp v20, v20 row_ror:2 row_mask:0xf bank_mask:0xf bound_ctrl:1
	v_pk_fma_f32 v[24:25], v[24:25], v[144:145], v[28:29]
	v_mov_b32_dpp v35, v21 row_ror:1 row_mask:0xf bank_mask:0xf bound_ctrl:1
	v_mul_f32_e32 v28, 0xbfb8aa3b, v24
	v_mul_f32_e32 v29, 0xbfb8aa3b, v25
	v_exp_f32_e32 v28, v28
	v_exp_f32_e32 v29, v29
	v_mov_b32_dpp v21, v21 row_ror:2 row_mask:0xf bank_mask:0xf bound_ctrl:1
	v_mov_b32_dpp v20, v16 row_shr:2 row_mask:0xf bank_mask:0xf
	v_add_f32_e32 v28, 1.0, v28
	v_add_f32_e32 v29, 1.0, v29
	v_rcp_f32_e32 v28, v28
	v_rcp_f32_e32 v29, v29
	v_mov_b32_dpp v21, v17 row_shr:2 row_mask:0xf bank_mask:0xf
	v_mov_b32_dpp v34, v16 row_shr:1 row_mask:0xf bank_mask:0xf
	v_mov_b32_dpp v35, v17 row_shr:1 row_mask:0xf bank_mask:0xf
	v_pk_fma_f32 v[20:21], v[128:129], v[20:21], v[140:141]
	s_nop 0
	v_pk_fma_f32 v[20:21], v[132:133], v[34:35], v[20:21]
	s_nop 0
	v_pk_fma_f32 v[16:17], v[16:17], v[136:137], v[20:21]
	v_pk_mul_f32 v[20:21], v[24:25], v[28:29]
	v_mov_b32_dpp v24, v30 row_ror:2 row_mask:0xf bank_mask:0xf bound_ctrl:1
	v_mov_b32_dpp v25, v31 row_ror:2 row_mask:0xf bank_mask:0xf bound_ctrl:1
	v_pk_mul_f32 v[16:17], v[16:17], v[20:21]
	v_mov_b32_dpp v20, v30 row_ror:1 row_mask:0xf bank_mask:0xf bound_ctrl:1
	v_mov_b32_dpp v24, v26 row_shr:2 row_mask:0xf bank_mask:0xf
	v_mov_b32_dpp v21, v31 row_ror:1 row_mask:0xf bank_mask:0xf bound_ctrl:1
	v_mov_b32_dpp v25, v27 row_shr:2 row_mask:0xf bank_mask:0xf
	v_mov_b32_dpp v20, v26 row_shr:1 row_mask:0xf bank_mask:0xf
	v_mov_b32_dpp v21, v27 row_shr:1 row_mask:0xf bank_mask:0xf
	v_pk_fma_f32 v[24:25], v[154:155], v[24:25], v[158:159]
	v_mov_b32_dpp v28, v22 row_ror:1 row_mask:0xf bank_mask:0xf bound_ctrl:1
	v_pk_fma_f32 v[20:21], v[150:151], v[20:21], v[24:25]
	v_mov_b32_dpp v22, v22 row_ror:2 row_mask:0xf bank_mask:0xf bound_ctrl:1
	v_pk_fma_f32 v[20:21], v[26:27], v[146:147], v[20:21]
	v_mov_b32_dpp v29, v23 row_ror:1 row_mask:0xf bank_mask:0xf bound_ctrl:1
	v_mul_f32_e32 v24, 0xbfb8aa3b, v20
	v_mul_f32_e32 v25, 0xbfb8aa3b, v21
	v_exp_f32_e32 v24, v24
	v_exp_f32_e32 v25, v25
	v_mov_b32_dpp v23, v23 row_ror:2 row_mask:0xf bank_mask:0xf bound_ctrl:1
	v_mov_b32_dpp v22, v18 row_shr:2 row_mask:0xf bank_mask:0xf
	v_add_f32_e32 v24, 1.0, v24
	v_add_f32_e32 v25, 1.0, v25
	v_rcp_f32_e32 v24, v24
	v_rcp_f32_e32 v25, v25
	v_mov_b32_dpp v23, v19 row_shr:2 row_mask:0xf bank_mask:0xf
	v_mov_b32_dpp v28, v18 row_shr:1 row_mask:0xf bank_mask:0xf
	v_mov_b32_dpp v29, v19 row_shr:1 row_mask:0xf bank_mask:0xf
	v_pk_fma_f32 v[22:23], v[130:131], v[22:23], v[142:143]
	v_pk_mul_f32 v[20:21], v[20:21], v[24:25]
	v_pk_fma_f32 v[22:23], v[134:135], v[28:29], v[22:23]
; __device__ __forceinline__ unsigned pk2(float lo, float hi) { const f32x2 v = {lo, hi}; return __builtin_bit_cast(unsigned, __builtin_convertvector(v, bf16x2_t)); }
; __device__ __forceinline__ float silu(float x) { return x * __builtin_amdgcn_rcpf(1.f + __builtin_amdgcn_exp2f(-1.4426950408889634f * x)); }
; #define PG8_BAR __builtin_amdgcn_s_barrier()
; template <class Epi, class Sched, bool ALIGN_EPI = true, bool SP2 = true>
; __device__ __forceinline__ void gemm_phase(PG8_LAS unsigned char* lds, const Gemm g, const Sched& S, const Epi& E) {
;     ...
;         E(acc, cur, wr, wc, fr, fq);
;         if (!has_next) break;
; #pragma unroll
;         for (int a = 0; a < 2; ++a)
; #pragma unroll
;             for (int b = 0; b < 2; ++b)
; #pragma unroll
;                 for (int m = 0; m < 4; ++m)
; #pragma unroll
;                     for (int n = 0; n < 2; ++n) acc[a][b][m][n] = (f32x4){0.f, 0.f, 0.f, 0.f};
;         cur = nxt; cA = nA; cB = nB; ++ui;
;         if constexpr (ALIGN_EPI) { if (wr == 1) PG8_BAR; }
;     __device__ __forceinline__ void operator()(f32x4 (&acc)[2][2][4][2], const Unit& u, int, int, int, int) const {
;     ...
;         for (int ai = 0; ai < 2; ++ai)
; #pragma unroll
;             for (int m = 0; m < 4; ++m) { float r[8];
; #pragma unroll
;                 for (int n = 0; n < 2; ++n)
; #pragma unroll
;                     for (int e = 0; e < 4; ++e) { const float A = acc[ai][0][m][n][e], Gv = acc[ai][1][m][n][e];
;                         const float Ap = m > 0 ? acc[ai][0][m > 0 ? m - 1 : 0][n][e] : 0.f, Gp = m > 0 ? acc[ai][1][m > 0 ? m - 1 : 0][n][e] : 0.f;
;                         const float a1 = dpp_prev(A, Ap, 1), a2 = dpp_prev(A, Ap, 2), g1 = dpp_prev(Gv, Gp, 1), g2 = dpp_prev(Gv, Gp, 2);
;                         const float ca = ba[n][e] + wa0[n][e] * a2 + wa1[n][e] * a1 + wa2[n][e] * A, cg = bg[n][e] + wg0[n][e] * g2 + wg1[n][e] * g1 + wg2[n][e] * Gv;
;                         r[4 * n + e] = silu(ca) * cg; }
;                 if (!(m == 0 && fr < 2)) { u32x4 w; w.x = pk2(r[0], r[1]); w.y = pk2(r[2], r[3]); w.z = pk2(r[4], r[5]); w.w = pk2(r[6], r[7]);
;                     *(u32x4*)(ACT + (size_t)(rowt + ai * HALF + m * 16) * NFF + f0) = w; }
;                 __builtin_amdgcn_sched_barrier(0); }
	s_nop 0
	v_pk_fma_f32 v[18:19], v[18:19], v[138:139], v[22:23]
	v_mov_b32_dpp v22, v4 row_ror:1 row_mask:0xf bank_mask:0xf bound_ctrl:1
	v_pk_mul_f32 v[18:19], v[18:19], v[20:21]
	v_mov_b32_dpp v20, v12 row_ror:1 row_mask:0xf bank_mask:0xf bound_ctrl:1
	v_mov_b32_dpp v12, v12 row_ror:2 row_mask:0xf bank_mask:0xf bound_ctrl:1
	v_mov_b32_dpp v21, v13 row_ror:1 row_mask:0xf bank_mask:0xf bound_ctrl:1
	v_mov_b32_dpp v13, v13 row_ror:2 row_mask:0xf bank_mask:0xf bound_ctrl:1
	v_mov_b32_dpp v12, v8 row_shr:2 row_mask:0xf bank_mask:0xf
	v_mov_b32_dpp v20, v8 row_shr:1 row_mask:0xf bank_mask:0xf
	v_mov_b32_dpp v13, v9 row_shr:2 row_mask:0xf bank_mask:0xf
	v_mov_b32_dpp v21, v9 row_shr:1 row_mask:0xf bank_mask:0xf
	v_pk_fma_f32 v[12:13], v[100:101], v[12:13], v[112:113]
	v_mov_b32_dpp v4, v4 row_ror:2 row_mask:0xf bank_mask:0xf bound_ctrl:1
	v_pk_fma_f32 v[12:13], v[108:109], v[20:21], v[12:13]
	v_mov_b32_dpp v23, v5 row_ror:1 row_mask:0xf bank_mask:0xf bound_ctrl:1
	v_pk_fma_f32 v[8:9], v[8:9], v[104:105], v[12:13]
	v_mov_b32_dpp v5, v5 row_ror:2 row_mask:0xf bank_mask:0xf bound_ctrl:1
	v_mul_f32_e32 v12, 0xbfb8aa3b, v8
	v_mul_f32_e32 v13, 0xbfb8aa3b, v9
	v_exp_f32_e32 v12, v12
	v_exp_f32_e32 v13, v13
	v_mov_b32_dpp v4, v0 row_shr:2 row_mask:0xf bank_mask:0xf
	v_mov_b32_dpp v5, v1 row_shr:2 row_mask:0xf bank_mask:0xf
	v_add_f32_e32 v12, 1.0, v12
	v_add_f32_e32 v13, 1.0, v13
	v_rcp_f32_e32 v12, v12
	v_rcp_f32_e32 v13, v13
	v_mov_b32_dpp v22, v0 row_shr:1 row_mask:0xf bank_mask:0xf
	v_mov_b32_dpp v23, v1 row_shr:1 row_mask:0xf bank_mask:0xf
	v_pk_fma_f32 v[4:5], v[84:85], v[4:5], v[96:97]
	s_nop 0
	v_pk_fma_f32 v[4:5], v[88:89], v[22:23], v[4:5]
	s_nop 0
	v_pk_fma_f32 v[0:1], v[0:1], v[92:93], v[4:5]
	v_pk_mul_f32 v[4:5], v[8:9], v[12:13]
	v_mov_b32_dpp v8, v14 row_ror:2 row_mask:0xf bank_mask:0xf bound_ctrl:1
	v_mov_b32_dpp v9, v15 row_ror:2 row_mask:0xf bank_mask:0xf bound_ctrl:1
	v_pk_mul_f32 v[4:5], v[0:1], v[4:5]
	v_mov_b32_dpp v0, v14 row_ror:1 row_mask:0xf bank_mask:0xf bound_ctrl:1
	v_mov_b32_dpp v8, v10 row_shr:2 row_mask:0xf bank_mask:0xf
	v_mov_b32_dpp v1, v15 row_ror:1 row_mask:0xf bank_mask:0xf bound_ctrl:1
	v_mov_b32_dpp v9, v11 row_shr:2 row_mask:0xf bank_mask:0xf
	v_mov_b32_dpp v0, v10 row_shr:1 row_mask:0xf bank_mask:0xf
	v_mov_b32_dpp v1, v11 row_shr:1 row_mask:0xf bank_mask:0xf
	v_pk_fma_f32 v[8:9], v[102:103], v[8:9], v[114:115]
	v_mov_b32_dpp v12, v6 row_ror:1 row_mask:0xf bank_mask:0xf bound_ctrl:1
	v_pk_fma_f32 v[0:1], v[110:111], v[0:1], v[8:9]
	v_mov_b32_dpp v6, v6 row_ror:2 row_mask:0xf bank_mask:0xf bound_ctrl:1
	v_pk_fma_f32 v[0:1], v[10:11], v[106:107], v[0:1]
	v_mov_b32_dpp v13, v7 row_ror:1 row_mask:0xf bank_mask:0xf bound_ctrl:1
	v_mul_f32_e32 v8, 0xbfb8aa3b, v0
	v_mul_f32_e32 v9, 0xbfb8aa3b, v1
	v_exp_f32_e32 v8, v8
	v_exp_f32_e32 v9, v9
	v_mov_b32_dpp v7, v7 row_ror:2 row_mask:0xf bank_mask:0xf bound_ctrl:1
	v_mov_b32_dpp v6, v2 row_shr:2 row_mask:0xf bank_mask:0xf
	v_add_f32_e32 v8, 1.0, v8
	v_add_f32_e32 v9, 1.0, v9
	v_rcp_f32_e32 v8, v8
	v_rcp_f32_e32 v9, v9
	v_mov_b32_dpp v7, v3 row_shr:2 row_mask:0xf bank_mask:0xf
	v_mov_b32_dpp v12, v2 row_shr:1 row_mask:0xf bank_mask:0xf
	v_mov_b32_dpp v13, v3 row_shr:1 row_mask:0xf bank_mask:0xf
	v_pk_fma_f32 v[6:7], v[86:87], v[6:7], v[98:99]
	v_pk_mul_f32 v[0:1], v[0:1], v[8:9]
	v_pk_fma_f32 v[6:7], v[90:91], v[12:13], v[6:7]
	s_nop 0
	v_pk_fma_f32 v[2:3], v[2:3], v[94:95], v[6:7]
	s_nop 0
	v_pk_mul_f32 v[6:7], v[2:3], v[0:1]
	v_cvt_pk_bf16_f32 v2, v4, v5
	v_add_u32_e32 v4, 0xb0, v246
	v_mad_i64_i32 v[4:5], s[6:7], v4, s83, v[48:49]
	v_cvt_pk_bf16_f32 v0, v16, v17
	v_cvt_pk_bf16_f32 v1, v18, v19
	v_cvt_pk_bf16_f32 v3, v6, v7
	v_lshl_add_u64 v[4:5], v[4:5], 0, v[176:177]
	global_store_dwordx4 v[4:5], v[0:3], off
	s_andn2_b64 vcc, exec, s[4:5]
	s_mov_b64 s[4:5], -1
	s_cbranch_vccnz .LBB0_1441
	s_andn2_b64 vcc, exec, s[18:19]
	s_cbranch_vccnz .LBB0_1440
	s_barrier
	s_branch .LBB0_1440

;     __device__ __forceinline__ void operator()(EPI_ARGS) const {
;         const int row0 = u.pm * BM + wr * 64 + fr, col0 = u.pn * BM + wc * 32 + 8 * fq;
; #pragma unroll
;         for (int ai = 0; ai < 2; ++ai)
; #pragma unroll
;             for (int m = 0; m < 4; ++m) { float* o = X + (size_t)(row0 + ai * HALF + m * 16) * DM + col0;
; #pragma unroll
;                 for (int bj = 0; bj < 2; ++bj)
; #pragma unroll
;                     for (int n = 0; n < 2; ++n)
; #pragma unroll
;                         for (int e = 0; e < 4; ++e) (void)__hip_atomic_fetch_add(o + bj * HALF + 4 * n + e, acc[ai][bj][m][n][e], __ATOMIC_RELAXED, __HIP_MEMORY_SCOPE_AGENT); }
;     }
.LBB0_1533:
	v_lshl_add_u32 v144, s26, 8, v139
	v_lshl_or_b32 v146, s79, 8, v141
	v_ashrrev_i32_e32 v145, 31, v144
	v_ashrrev_i32_e32 v147, 31, v146
	v_lshlrev_b64 v[148:149], 12, v[144:145]
	v_lshl_add_u64 v[148:149], s[16:17], 0, v[148:149]
	v_lshlrev_b64 v[146:147], 2, v[146:147]
	v_lshl_add_u64 v[148:149], v[148:149], 0, v[146:147]
	s_waitcnt vmcnt(0)
	global_atomic_add_f32 v[148:149], v124, off
	global_atomic_add_f32 v[148:149], v125, off offset:4
	global_atomic_add_f32 v[148:149], v126, off offset:8
	global_atomic_add_f32 v[148:149], v127, off offset:12
	global_atomic_add_f32 v[148:149], v120, off offset:16
	global_atomic_add_f32 v[148:149], v121, off offset:20
	global_atomic_add_f32 v[148:149], v122, off offset:24
	global_atomic_add_f32 v[148:149], v123, off offset:28
	global_atomic_add_f32 v[148:149], v108, off offset:512
	global_atomic_add_f32 v[148:149], v109, off offset:516
	global_atomic_add_f32 v[148:149], v110, off offset:520
	global_atomic_add_f32 v[148:149], v111, off offset:524
	global_atomic_add_f32 v[148:149], v104, off offset:528
	global_atomic_add_f32 v[148:149], v105, off offset:532
	global_atomic_add_f32 v[148:149], v106, off offset:536
	global_atomic_add_f32 v[148:149], v107, off offset:540
	v_or_b32_e32 v104, 16, v144
	v_ashrrev_i32_e32 v105, 31, v104
	v_lshlrev_b64 v[104:105], 12, v[104:105]
	v_lshl_add_u64 v[104:105], s[16:17], 0, v[104:105]
	v_lshl_add_u64 v[104:105], v[104:105], 0, v[146:147]
	global_atomic_add_f32 v[104:105], v116, off
	global_atomic_add_f32 v[104:105], v117, off offset:4
	global_atomic_add_f32 v[104:105], v118, off offset:8
	global_atomic_add_f32 v[104:105], v119, off offset:12
	global_atomic_add_f32 v[104:105], v112, off offset:16
	global_atomic_add_f32 v[104:105], v113, off offset:20
	global_atomic_add_f32 v[104:105], v114, off offset:24
	global_atomic_add_f32 v[104:105], v115, off offset:28
	global_atomic_add_f32 v[104:105], v92, off offset:512
	global_atomic_add_f32 v[104:105], v93, off offset:516
	global_atomic_add_f32 v[104:105], v94, off offset:520
	global_atomic_add_f32 v[104:105], v95, off offset:524
	global_atomic_add_f32 v[104:105], v88, off offset:528
	global_atomic_add_f32 v[104:105], v89, off offset:532
	global_atomic_add_f32 v[104:105], v90, off offset:536
	global_atomic_add_f32 v[104:105], v91, off offset:540
	v_or_b32_e32 v88, 32, v144
	v_ashrrev_i32_e32 v89, 31, v88
	v_lshlrev_b64 v[88:89], 12, v[88:89]
	v_lshl_add_u64 v[88:89], s[16:17], 0, v[88:89]
	v_lshl_add_u64 v[88:89], v[88:89], 0, v[146:147]
	global_atomic_add_f32 v[88:89], v100, off
	global_atomic_add_f32 v[88:89], v101, off offset:4
	global_atomic_add_f32 v[88:89], v102, off offset:8
	global_atomic_add_f32 v[88:89], v103, off offset:12
	global_atomic_add_f32 v[88:89], v96, off offset:16
	global_atomic_add_f32 v[88:89], v97, off offset:20
	global_atomic_add_f32 v[88:89], v98, off offset:24
	global_atomic_add_f32 v[88:89], v99, off offset:28
	global_atomic_add_f32 v[88:89], v76, off offset:512
	global_atomic_add_f32 v[88:89], v77, off offset:516
	global_atomic_add_f32 v[88:89], v78, off offset:520
	global_atomic_add_f32 v[88:89], v79, off offset:524
	global_atomic_add_f32 v[88:89], v72, off offset:528
	global_atomic_add_f32 v[88:89], v73, off offset:532
	global_atomic_add_f32 v[88:89], v74, off offset:536
	global_atomic_add_f32 v[88:89], v75, off offset:540
	v_or_b32_e32 v72, 48, v144
	v_ashrrev_i32_e32 v73, 31, v72
	v_lshlrev_b64 v[72:73], 12, v[72:73]
	v_lshl_add_u64 v[72:73], s[16:17], 0, v[72:73]
	v_lshl_add_u64 v[72:73], v[72:73], 0, v[146:147]
	global_atomic_add_f32 v[72:73], v84, off
	global_atomic_add_f32 v[72:73], v85, off offset:4
	global_atomic_add_f32 v[72:73], v86, off offset:8
	global_atomic_add_f32 v[72:73], v87, off offset:12
	global_atomic_add_f32 v[72:73], v80, off offset:16
	global_atomic_add_f32 v[72:73], v81, off offset:20
	global_atomic_add_f32 v[72:73], v82, off offset:24
	global_atomic_add_f32 v[72:73], v83, off offset:28
	global_atomic_add_f32 v[72:73], v68, off offset:512
	global_atomic_add_f32 v[72:73], v69, off offset:516
	global_atomic_add_f32 v[72:73], v70, off offset:520
	global_atomic_add_f32 v[72:73], v71, off offset:524
	global_atomic_add_f32 v[72:73], v64, off offset:528
; #define PG8_BAR __builtin_amdgcn_s_barrier()
; template <class Epi, class Sched, bool ALIGN_EPI = true, bool SP2 = true>
; __device__ __forceinline__ void gemm_phase(PG8_LAS unsigned char* lds, const Gemm g, const Sched& S, const Epi& E) {
;     ...
;         E(acc, cur, wr, wc, fr, fq);
;         if (!has_next) break;
; #pragma unroll
;         for (int a = 0; a < 2; ++a)
; #pragma unroll
;             for (int b = 0; b < 2; ++b)
; #pragma unroll
;                 for (int m = 0; m < 4; ++m)
; #pragma unroll
;                     for (int n = 0; n < 2; ++n) acc[a][b][m][n] = (f32x4){0.f, 0.f, 0.f, 0.f};
;         cur = nxt; cA = nA; cB = nB; ++ui;
;         if constexpr (ALIGN_EPI) { if (wr == 1) PG8_BAR; }
;     __device__ __forceinline__ void operator()(EPI_ARGS) const {
;     ...
;             for (int m = 0; m < 4; ++m) { float* o = X + (size_t)(row0 + ai * HALF + m * 16) * DM + col0;
; #pragma unroll
;                 for (int bj = 0; bj < 2; ++bj)
; #pragma unroll
;                     for (int n = 0; n < 2; ++n)
; #pragma unroll
;                         for (int e = 0; e < 4; ++e) (void)__hip_atomic_fetch_add(o + bj * HALF + 4 * n + e, acc[ai][bj][m][n][e], __ATOMIC_RELAXED, __HIP_MEMORY_SCOPE_AGENT); }
	global_atomic_add_f32 v[72:73], v65, off offset:532
	global_atomic_add_f32 v[72:73], v66, off offset:536
	global_atomic_add_f32 v[72:73], v67, off offset:540
	v_add_co_u32_e32 v66, vcc, s58, v148
	v_lshl_add_u64 v[64:65], v[148:149], 0, s[6:7]
	s_nop 0
	v_addc_co_u32_e32 v67, vcc, 0, v149, vcc
	global_atomic_add_f32 v[66:67], v60, off
	global_atomic_add_f32 v[64:65], v61, off offset:4
	global_atomic_add_f32 v[64:65], v62, off offset:8
	global_atomic_add_f32 v[64:65], v63, off offset:12
	global_atomic_add_f32 v[64:65], v56, off offset:16
	global_atomic_add_f32 v[64:65], v57, off offset:20
	global_atomic_add_f32 v[64:65], v58, off offset:24
	global_atomic_add_f32 v[64:65], v59, off offset:28
	global_atomic_add_f32 v[64:65], v44, off offset:512
	global_atomic_add_f32 v[64:65], v45, off offset:516
	global_atomic_add_f32 v[64:65], v46, off offset:520
	global_atomic_add_f32 v[64:65], v47, off offset:524
	global_atomic_add_f32 v[64:65], v40, off offset:528
	global_atomic_add_f32 v[64:65], v41, off offset:532
	global_atomic_add_f32 v[64:65], v42, off offset:536
	global_atomic_add_f32 v[64:65], v43, off offset:540
	v_add_co_u32_e32 v42, vcc, s59, v148
	v_lshl_add_u64 v[40:41], v[148:149], 0, s[8:9]
	s_nop 0
	v_addc_co_u32_e32 v43, vcc, 0, v149, vcc
	global_atomic_add_f32 v[42:43], v52, off
	global_atomic_add_f32 v[40:41], v53, off offset:4
	global_atomic_add_f32 v[40:41], v54, off offset:8
	global_atomic_add_f32 v[40:41], v55, off offset:12
	global_atomic_add_f32 v[40:41], v48, off offset:16
	global_atomic_add_f32 v[40:41], v49, off offset:20
	global_atomic_add_f32 v[40:41], v50, off offset:24
	global_atomic_add_f32 v[40:41], v51, off offset:28
	global_atomic_add_f32 v[40:41], v28, off offset:512
	global_atomic_add_f32 v[40:41], v29, off offset:516
	global_atomic_add_f32 v[40:41], v30, off offset:520
	global_atomic_add_f32 v[40:41], v31, off offset:524
	global_atomic_add_f32 v[40:41], v24, off offset:528
	global_atomic_add_f32 v[40:41], v25, off offset:532
	global_atomic_add_f32 v[40:41], v26, off offset:536
	global_atomic_add_f32 v[40:41], v27, off offset:540
	v_add_co_u32_e32 v26, vcc, s60, v148
	v_lshl_add_u64 v[24:25], v[148:149], 0, s[10:11]
	s_nop 0
	v_addc_co_u32_e32 v27, vcc, 0, v149, vcc
	global_atomic_add_f32 v[26:27], v36, off
	global_atomic_add_f32 v[24:25], v37, off offset:4
	global_atomic_add_f32 v[24:25], v38, off offset:8
	global_atomic_add_f32 v[24:25], v39, off offset:12
	global_atomic_add_f32 v[24:25], v32, off offset:16
	global_atomic_add_f32 v[24:25], v33, off offset:20
	global_atomic_add_f32 v[24:25], v34, off offset:24
	global_atomic_add_f32 v[24:25], v35, off offset:28
	global_atomic_add_f32 v[24:25], v12, off offset:512
	global_atomic_add_f32 v[24:25], v13, off offset:516
	global_atomic_add_f32 v[24:25], v14, off offset:520
	global_atomic_add_f32 v[24:25], v15, off offset:524
	global_atomic_add_f32 v[24:25], v8, off offset:528
	global_atomic_add_f32 v[24:25], v9, off offset:532
	global_atomic_add_f32 v[24:25], v10, off offset:536
	global_atomic_add_f32 v[24:25], v11, off offset:540
	v_add_co_u32_e32 v10, vcc, s61, v148
	v_lshl_add_u64 v[8:9], v[148:149], 0, s[12:13]
	s_nop 0
	v_addc_co_u32_e32 v11, vcc, 0, v149, vcc
	global_atomic_add_f32 v[10:11], v20, off
	global_atomic_add_f32 v[8:9], v21, off offset:4
	global_atomic_add_f32 v[8:9], v22, off offset:8
	global_atomic_add_f32 v[8:9], v23, off offset:12
	global_atomic_add_f32 v[8:9], v16, off offset:16
	global_atomic_add_f32 v[8:9], v17, off offset:20
	global_atomic_add_f32 v[8:9], v18, off offset:24
	global_atomic_add_f32 v[8:9], v19, off offset:28
	global_atomic_add_f32 v[8:9], v4, off offset:512
	global_atomic_add_f32 v[8:9], v5, off offset:516
	global_atomic_add_f32 v[8:9], v6, off offset:520
	global_atomic_add_f32 v[8:9], v7, off offset:524
	global_atomic_add_f32 v[8:9], v0, off offset:528
	global_atomic_add_f32 v[8:9], v1, off offset:532
	global_atomic_add_f32 v[8:9], v2, off offset:536
	global_atomic_add_f32 v[8:9], v3, off offset:540
	s_andn2_b64 vcc, exec, s[24:25]
	s_mov_b64 s[24:25], -1
	s_cbranch_vccnz .LBB0_1526
	s_andn2_b64 vcc, exec, s[14:15]
	s_cbranch_vccnz .LBB0_1525
	s_barrier
	s_branch .LBB0_1525

; #define INP(i) ((const float*)tab_get(lds, (i)))
; #define WSB(off) ((bf16*)((unsigned char*)tab_get(lds, 31) + (off)))
; #define QNEXT(ctrw, dst) do { __syncthreads(); if (my_tid(lds) == 0) *(volatile LAS int*)(lds + TAB_OFF + 264) = (int)atomicAdd((unsigned*)tab_get(lds, 31) + 8192 + 64 * (ctrw), 1u); \
;         __syncthreads(); dst = __builtin_amdgcn_readfirstlane(*(volatile LAS int*)(lds + TAB_OFF + 264)); } while (0)
; __global__ void __launch_bounds__(512, 2) mega_fwd(Params p) {
;     ...
;         { const bf16* HB = WSB(WS_HB); bf16* ACT = WSB(WS_ACT); const float *cw = INP(26), *cb = INP(27);
;           for (;;) { int it; QNEXT(6, it); if (it >= MP / 64 / 4) break;
.LBB0_1539:
	s_waitcnt vmcnt(63) expcnt(7) lgkmcnt(15)
	s_barrier
	s_getreg_b32 s8, hwreg(HW_REG_HW_ID, 0, 6)
	s_lshl_b32 s8, s8, 2
	s_and_b32 s8, s8, 0xfc
	s_add_i32 s8, s8, 0
	s_add_i32 s8, s8, 0x25a00
	v_mov_b32_e32 v0, s8
	ds_read_b32 v0, v0
	v_mbcnt_lo_u32_b32 v1, -1, 0
	v_mbcnt_hi_u32_b32 v1, -1, v1
	s_waitcnt lgkmcnt(0)
	v_readfirstlane_b32 s8, v0
	s_lshl_b32 s8, s8, 6
	v_sub_u32_e32 v0, 0, v1
	v_cmp_eq_u32_e32 vcc, s8, v0
	s_and_saveexec_b64 s[8:9], vcc
	s_cbranch_execz .LBB0_1541
	ds_read_b64 v[0:1], v72
	s_waitcnt lgkmcnt(0)
	v_readfirstlane_b32 s11, v0
	v_readfirstlane_b32 s10, v1
	s_nop 0
	v_mov_b32_e32 v0, s11
	v_add_co_u32_e32 v0, vcc, 0x8000, v0
	v_mov_b32_e32 v1, s10
	s_nop 0
	v_addc_co_u32_e32 v1, vcc, 0, v1, vcc
	global_atomic_add v0, v[0:1], v73, off offset:1536 sc0
	s_waitcnt vmcnt(0) lgkmcnt(0)
	ds_write_b32 v74, v0

; __device__ __forceinline__ float bflo(unsigned w) { return __uint_as_float(w << 16); }
; __device__ __forceinline__ float bfhi(unsigned w) { return __uint_as_float(w & 0xffff0000u); }
; __device__ __forceinline__ float silu(float x) { return x * __builtin_amdgcn_rcpf(1.f + __builtin_amdgcn_exp2f(-1.4426950408889634f * x)); }
; __device__ __forceinline__ void conv_fix_item(LAS unsigned char* lds, const bf16* HB, int gi, const float* cw, const float* cb, bf16* ACT) {
;     ...
;     for (int part = 0; part < 2; ++part) { const int c0 = part * NFF + f0;
;         const u32x4 u0 = *(const u32x4*)(h + c0), u1 = *(const u32x4*)(h + NUP + c0);
;         u32x4 p2 = {0u, 0u, 0u, 0u}, p3 = {0u, 0u, 0u, 0u}; if (!first) { p2 = *(const u32x4*)(hp + 2 * NUP + c0); p3 = *(const u32x4*)(hp + 3 * NUP + c0); }
; #pragma unroll
;         for (int i = 0; i < 8; ++i) { const float w0 = cw[c0 + i], w1 = cw[NUP + c0 + i], w2 = cw[2 * NUP + c0 + i], bb = cb[c0 + i];
;             const float x0 = (i & 1) ? bfhi(u0[i >> 1]) : bflo(u0[i >> 1]), x1 = (i & 1) ? bfhi(u1[i >> 1]) : bflo(u1[i >> 1]);
;             const float q2 = (i & 1) ? bfhi(p2[i >> 1]) : bflo(p2[i >> 1]), q3 = (i & 1) ? bfhi(p3[i >> 1]) : bflo(p3[i >> 1]);
;             const float c_0 = bb + w0 * q2 + w1 * q3 + w2 * x0, c_1 = bb + w0 * q3 + w1 * x0 + w2 * x1;
;             if (part == 0) { r0[i] = silu(c_0); r1[i] = silu(c_1); } else { r0[i] *= c_0; r1[i] *= c_1; } } }
.LBB0_1543:
	v_lshlrev_b64 v[12:13], 1, v[66:67]
	v_lshl_add_u64 v[76:77], s[18:19], 0, v[12:13]
	v_lshl_add_u64 v[78:79], s[14:15], 0, v[12:13]
	global_load_dwordx4 v[16:19], v[76:77], off
	global_load_dwordx4 v[12:15], v[78:79], off
.LBB0_1544:
	s_waitcnt vmcnt(0) lgkmcnt(0)
	v_lshlrev_b32_e32 v78, 16, v20
	v_and_b32_e32 v79, 0xffff0000, v20
	v_lshlrev_b32_e32 v76, 16, v44
	v_and_b32_e32 v77, 0xffff0000, v44
	v_pk_fma_f32 v[82:83], v[52:53], v[78:79], v[56:57]
	v_lshlrev_b32_e32 v80, 16, v0
	v_and_b32_e32 v81, 0xffff0000, v0
	v_pk_fma_f32 v[82:83], v[60:61], v[76:77], v[82:83]
	v_lshlrev_b32_e32 v44, 16, v45
	v_pk_fma_f32 v[80:81], v[48:49], v[80:81], v[82:83]
	v_lshlrev_b32_e32 v82, 16, v24
	v_and_b32_e32 v83, 0xffff0000, v24
	v_pk_fma_f32 v[52:53], v[52:53], v[82:83], v[56:57]
	v_mul_f32_e32 v0, 0xbfb8aa3b, v80
	v_pk_fma_f32 v[52:53], v[60:61], v[78:79], v[52:53]
	v_exp_f32_e32 v0, v0
	v_pk_fma_f32 v[48:49], v[48:49], v[76:77], v[52:53]
	v_mul_f32_e32 v24, 0xbfb8aa3b, v81
	v_mul_f32_e32 v20, 0xbfb8aa3b, v48
	v_exp_f32_e32 v20, v20
	v_add_f32_e32 v0, 1.0, v0
	v_rcp_f32_e32 v52, v0
	v_exp_f32_e32 v24, v24
	v_add_f32_e32 v0, 1.0, v20
	v_mul_f32_e32 v20, 0xbfb8aa3b, v49
	v_exp_f32_e32 v20, v20
	v_rcp_f32_e32 v56, v0
	v_and_b32_e32 v45, 0xffff0000, v45
	v_add_f32_e32 v0, 1.0, v20
	v_rcp_f32_e32 v57, v0
	v_add_f32_e32 v0, 1.0, v24
	v_rcp_f32_e32 v53, v0
	v_lshlrev_b32_e32 v20, 16, v21
	v_and_b32_e32 v21, 0xffff0000, v21
	v_pk_mul_f32 v[48:49], v[48:49], v[56:57]
	v_pk_fma_f32 v[56:57], v[54:55], v[20:21], v[58:59]
	v_lshlrev_b32_e32 v0, 16, v1
	v_and_b32_e32 v1, 0xffff0000, v1
	v_pk_fma_f32 v[56:57], v[62:63], v[44:45], v[56:57]
	v_pk_mul_f32 v[52:53], v[80:81], v[52:53]
	v_pk_fma_f32 v[80:81], v[50:51], v[0:1], v[56:57]
	v_lshlrev_b32_e32 v0, 16, v25
	v_and_b32_e32 v1, 0xffff0000, v25
	v_pk_fma_f32 v[0:1], v[54:55], v[0:1], v[58:59]
	v_mul_f32_e32 v25, 0xbfb8aa3b, v81
	v_pk_fma_f32 v[0:1], v[62:63], v[20:21], v[0:1]
	v_exp_f32_e32 v25, v25
	v_pk_fma_f32 v[0:1], v[50:51], v[44:45], v[0:1]
	v_lshlrev_b32_e32 v50, 16, v22
	v_mul_f32_e32 v20, 0xbfb8aa3b, v0
	v_mul_f32_e32 v21, 0xbfb8aa3b, v1
	v_exp_f32_e32 v20, v20
	v_exp_f32_e32 v21, v21
	v_and_b32_e32 v51, 0xffff0000, v22
	v_lshlrev_b32_e32 v44, 16, v46
	v_add_f32_e32 v20, 1.0, v20
	v_add_f32_e32 v21, 1.0, v21
	v_rcp_f32_e32 v20, v20
	v_rcp_f32_e32 v21, v21
	v_and_b32_e32 v45, 0xffff0000, v46
	v_pk_fma_f32 v[54:55], v[32:33], v[50:51], v[36:37]
	v_add_co_u32_e32 v62, vcc, s28, v68
	v_pk_mul_f32 v[0:1], v[0:1], v[20:21]
	v_add_f32_e32 v20, 1.0, v25
	v_rcp_f32_e32 v25, v20
	v_lshlrev_b32_e32 v20, 16, v2
	v_and_b32_e32 v21, 0xffff0000, v2
	v_pk_fma_f32 v[54:55], v[40:41], v[44:45], v[54:55]
	v_addc_co_u32_e32 v63, vcc, 0, v69, vcc
	v_pk_fma_f32 v[20:21], v[28:29], v[20:21], v[54:55]
	v_add_co_u32_e32 v54, vcc, s29, v68
	v_mul_f32_e32 v24, 0xbfb8aa3b, v80
	s_nop 0
	v_addc_co_u32_e32 v55, vcc, 0, v69, vcc
	global_load_dwordx2 v[84:85], v[54:55], off offset:3072
	v_add_co_u32_e32 v54, vcc, s29, v70
	v_exp_f32_e32 v24, v24
	s_nop 0
	v_addc_co_u32_e32 v55, vcc, 0, v71, vcc
	v_add_co_u32_e32 v88, vcc, s26, v68
	v_lshlrev_b32_e32 v68, 16, v26
	s_nop 0
	v_addc_co_u32_e32 v89, vcc, 0, v69, vcc
	v_and_b32_e32 v69, 0xffff0000, v26
	v_pk_fma_f32 v[32:33], v[32:33], v[68:69], v[36:37]
	global_load_dwordx2 v[86:87], v[54:55], off offset:3072
	v_pk_fma_f32 v[32:33], v[40:41], v[50:51], v[32:33]
	global_load_dwordx4 v[54:57], v[88:89], off offset:1024
	global_load_dwordx4 v[58:61], v[62:63], off offset:3072
	v_pk_fma_f32 v[28:29], v[28:29], v[44:45], v[32:33]
	v_or_b32_e32 v32, 2, v66
	v_ashrrev_i32_e32 v33, 31, v32
	v_lshlrev_b64 v[32:33], 2, v[32:33]
	v_lshl_add_u64 v[36:37], s[4:5], 0, v[32:33]
	v_lshl_add_u64 v[32:33], s[6:7], 0, v[32:33]
	v_add_f32_e32 v24, 1.0, v24
	global_load_dwordx4 v[68:71], v[36:37], off
	global_load_dwordx4 v[76:79], v[32:33], off
	v_mul_f32_e32 v32, 0xbfb8aa3b, v21
	v_rcp_f32_e32 v24, v24
	v_exp_f32_e32 v36, v32
	v_and_b32_e32 v37, 0xffff0000, v47
	v_or_b32_e32 v40, 6, v66
	v_pk_mul_f32 v[24:25], v[80:81], v[24:25]
	v_add_f32_e32 v75, 1.0, v36
	v_lshlrev_b32_e32 v36, 16, v47
	global_load_dwordx4 v[44:47], v[88:89], off offset:1040
	global_load_dwordx4 v[80:83], v[62:63], off offset:3088
	v_ashrrev_i32_e32 v41, 31, v40
	v_lshlrev_b64 v[40:41], 2, v[40:41]
	v_lshl_add_u64 v[50:51], s[4:5], 0, v[40:41]
	v_lshl_add_u64 v[40:41], s[6:7], 0, v[40:41]
	global_load_dwordx2 v[62:63], v[50:51], off
	global_load_dwordx2 v[66:67], v[40:41], off
	v_mul_f32_e32 v22, 0xbfb8aa3b, v28
	v_exp_f32_e32 v22, v22
	v_mul_f32_e32 v26, 0xbfb8aa3b, v29
	v_exp_f32_e32 v26, v26
	v_lshlrev_b32_e32 v40, 16, v3
	v_add_f32_e32 v22, 1.0, v22
	v_rcp_f32_e32 v32, v22
	v_add_f32_e32 v22, 1.0, v26
	v_lshlrev_b32_e32 v26, 16, v27
	v_and_b32_e32 v27, 0xffff0000, v27
	v_rcp_f32_e32 v33, v22
	v_lshlrev_b32_e32 v22, 16, v23
	v_and_b32_e32 v23, 0xffff0000, v23
	v_pk_fma_f32 v[26:27], v[34:35], v[26:27], v[38:39]
	v_and_b32_e32 v41, 0xffff0000, v3
	v_pk_fma_f32 v[26:27], v[42:43], v[22:23], v[26:27]
	v_pk_fma_f32 v[22:23], v[34:35], v[22:23], v[38:39]
	v_pk_fma_f32 v[26:27], v[30:31], v[36:37], v[26:27]
	v_pk_fma_f32 v[22:23], v[42:43], v[36:37], v[22:23]
	v_mul_f32_e32 v2, 0xbfb8aa3b, v20
	v_pk_fma_f32 v[22:23], v[30:31], v[40:41], v[22:23]
	v_mul_f32_e32 v88, 0xbfb8aa3b, v26
	v_mul_f32_e32 v3, 0xbfb8aa3b, v22
	v_exp_f32_e32 v31, v3
	v_mul_f32_e32 v34, 0xbfb8aa3b, v27
	v_exp_f32_e32 v2, v2
	v_exp_f32_e32 v50, v88
	v_exp_f32_e32 v35, v34
	v_mul_f32_e32 v34, 0xbfb8aa3b, v23
	v_exp_f32_e32 v36, v34
	v_add_f32_e32 v31, 1.0, v31
	v_add_f32_e32 v2, 1.0, v2
	v_add_f32_e32 v30, 1.0, v50
	v_rcp_f32_e32 v34, v31
	v_add_f32_e32 v31, 1.0, v35
	v_rcp_f32_e32 v2, v2
	v_rcp_f32_e32 v3, v75
	v_rcp_f32_e32 v30, v30
	v_rcp_f32_e32 v31, v31
	v_add_f32_e32 v35, 1.0, v36
	v_rcp_f32_e32 v35, v35
	v_pk_mul_f32 v[2:3], v[20:21], v[2:3]
	v_pk_mul_f32 v[20:21], v[26:27], v[30:31]
	v_lshlrev_b32_e32 v30, 16, v12
	v_and_b32_e32 v31, 0xffff0000, v12
	v_pk_mul_f32 v[22:23], v[22:23], v[34:35]
	v_lshlrev_b32_e32 v26, 16, v8
	v_and_b32_e32 v27, 0xffff0000, v8
	v_pk_mul_f32 v[28:29], v[28:29], v[32:33]
	v_lshlrev_b32_e32 v32, 16, v4
	v_and_b32_e32 v33, 0xffff0000, v4
	v_lshlrev_b32_e32 v12, 16, v13
	v_and_b32_e32 v13, 0xffff0000, v13
	v_lshlrev_b32_e32 v8, 16, v9
	v_and_b32_e32 v9, 0xffff0000, v9
	s_waitcnt vmcnt(0) lgkmcnt(0)
; __device__ __forceinline__ float bflo(unsigned w) { return __uint_as_float(w << 16); }
; __device__ __forceinline__ float bfhi(unsigned w) { return __uint_as_float(w & 0xffff0000u); }
; __device__ __forceinline__ unsigned pk2(float lo, float hi) { const f32x2 v = {lo, hi}; return __builtin_bit_cast(unsigned, __builtin_convertvector(v, bf16x2_t)); }
; __device__ __forceinline__ float silu(float x) { return x * __builtin_amdgcn_rcpf(1.f + __builtin_amdgcn_exp2f(-1.4426950408889634f * x)); }
; __device__ __forceinline__ void conv_fix_item(LAS unsigned char* lds, const bf16* HB, int gi, const float* cw, const float* cb, bf16* ACT) {
;     ...
;         for (int i = 0; i < 8; ++i) { const float w0 = cw[c0 + i], w1 = cw[NUP + c0 + i], w2 = cw[2 * NUP + c0 + i], bb = cb[c0 + i];
;             const float x0 = (i & 1) ? bfhi(u0[i >> 1]) : bflo(u0[i >> 1]), x1 = (i & 1) ? bfhi(u1[i >> 1]) : bflo(u1[i >> 1]);
;             const float q2 = (i & 1) ? bfhi(p2[i >> 1]) : bflo(p2[i >> 1]), q3 = (i & 1) ? bfhi(p3[i >> 1]) : bflo(p3[i >> 1]);
;             const float c_0 = bb + w0 * q2 + w1 * q3 + w2 * x0, c_1 = bb + w0 * q3 + w1 * x0 + w2 * x1;
;             if (part == 0) { r0[i] = silu(c_0); r1[i] = silu(c_1); } else { r0[i] *= c_0; r1[i] *= c_1; } } }
;     u32x4 w; w.x = pk2(r0[0], r0[1]); w.y = pk2(r0[2], r0[3]); w.z = pk2(r0[4], r0[5]); w.w = pk2(r0[6], r0[7]); *(u32x4*)(ACT + (size_t)(64 * gi) * NFF + f0) = w;
;     w.x = pk2(r1[0], r1[1]); w.y = pk2(r1[2], r1[3]); w.z = pk2(r1[4], r1[5]); w.w = pk2(r1[6], r1[7]); *(u32x4*)(ACT + (size_t)(64 * gi + 1) * NFF + f0) = w;
	v_pk_fma_f32 v[34:35], v[84:85], v[30:31], v[86:87]
	v_lshlrev_b32_e32 v4, 16, v5
	v_pk_fma_f32 v[34:35], v[54:55], v[26:27], v[34:35]
	v_and_b32_e32 v5, 0xffff0000, v5
	v_pk_fma_f32 v[32:33], v[58:59], v[32:33], v[34:35]
	v_lshlrev_b32_e32 v34, 16, v16
	v_and_b32_e32 v35, 0xffff0000, v16
	v_pk_fma_f32 v[34:35], v[84:85], v[34:35], v[86:87]
	v_lshlrev_b32_e32 v16, 16, v17
	v_pk_fma_f32 v[30:31], v[54:55], v[30:31], v[34:35]
	v_and_b32_e32 v17, 0xffff0000, v17
	v_pk_fma_f32 v[26:27], v[58:59], v[26:27], v[30:31]
	v_pk_fma_f32 v[30:31], v[68:69], v[12:13], v[76:77]
	v_pk_fma_f32 v[16:17], v[68:69], v[16:17], v[76:77]
	v_pk_fma_f32 v[30:31], v[56:57], v[8:9], v[30:31]
	v_pk_fma_f32 v[12:13], v[56:57], v[12:13], v[16:17]
	v_pk_fma_f32 v[4:5], v[60:61], v[4:5], v[30:31]
	v_pk_fma_f32 v[8:9], v[60:61], v[8:9], v[12:13]
	v_lshlrev_b32_e32 v12, 16, v14
	v_and_b32_e32 v13, 0xffff0000, v14
	v_pk_mul_f32 v[4:5], v[24:25], v[4:5]
	v_pk_mul_f32 v[8:9], v[0:1], v[8:9]
	v_lshlrev_b32_e32 v0, 16, v10
	v_and_b32_e32 v1, 0xffff0000, v10
	v_pk_fma_f32 v[24:25], v[70:71], v[12:13], v[78:79]
	v_lshlrev_b32_e32 v16, 16, v6
	v_and_b32_e32 v17, 0xffff0000, v6
	v_pk_fma_f32 v[24:25], v[44:45], v[0:1], v[24:25]
	v_lshlrev_b32_e32 v10, 16, v15
	v_pk_fma_f32 v[16:17], v[80:81], v[16:17], v[24:25]
	v_lshlrev_b32_e32 v6, 16, v7
	v_pk_mul_f32 v[16:17], v[2:3], v[16:17]
	v_lshlrev_b32_e32 v2, 16, v18
	v_and_b32_e32 v3, 0xffff0000, v18
	v_pk_fma_f32 v[2:3], v[70:71], v[2:3], v[78:79]
	v_and_b32_e32 v7, 0xffff0000, v7
	v_pk_fma_f32 v[2:3], v[44:45], v[12:13], v[2:3]
	v_lshlrev_b32_e32 v12, 16, v19
	v_pk_fma_f32 v[0:1], v[80:81], v[0:1], v[2:3]
	v_and_b32_e32 v13, 0xffff0000, v19
	v_pk_mul_f32 v[2:3], v[28:29], v[0:1]
	v_lshlrev_b32_e32 v0, 16, v11
	v_and_b32_e32 v1, 0xffff0000, v11
	v_and_b32_e32 v11, 0xffff0000, v15
	v_pk_fma_f32 v[12:13], v[62:63], v[12:13], v[66:67]
	v_pk_mul_f32 v[26:27], v[48:49], v[26:27]
	v_pk_fma_f32 v[12:13], v[46:47], v[10:11], v[12:13]
	v_pk_fma_f32 v[10:11], v[62:63], v[10:11], v[66:67]
	v_pk_fma_f32 v[12:13], v[82:83], v[0:1], v[12:13]
	v_pk_fma_f32 v[0:1], v[46:47], v[0:1], v[10:11]
	v_pk_mul_f32 v[12:13], v[20:21], v[12:13]
	v_pk_fma_f32 v[0:1], v[82:83], v[6:7], v[0:1]
	v_pk_mul_f32 v[32:33], v[52:53], v[32:33]
	v_pk_mul_f32 v[6:7], v[22:23], v[0:1]
	v_cvt_pk_bf16_f32 v1, v8, v9
	v_lshl_add_u64 v[8:9], s[8:9], 0, v[64:65]
	v_add_co_u32_e32 v10, vcc, s30, v8
	v_cvt_pk_bf16_f32 v0, v26, v27
	v_cvt_pk_bf16_f32 v2, v2, v3
	v_cvt_pk_bf16_f32 v3, v12, v13
	v_addc_co_u32_e32 v11, vcc, -1, v9, vcc
	global_store_dwordx4 v[10:11], v[0:3], off
	s_nop 1
	v_cvt_pk_bf16_f32 v0, v32, v33
	v_cvt_pk_bf16_f32 v1, v4, v5
	v_cvt_pk_bf16_f32 v2, v16, v17
	v_cvt_pk_bf16_f32 v3, v6, v7
	global_store_dwordx4 v[8:9], v[0:3], off

; #define LAS __attribute__((address_space(3)))
; __device__ __forceinline__ void conv_fix_item(LAS unsigned char* lds, const bf16* HB, int gi, const float* cw, const float* cb, bf16* ACT) {
;     const int tid = my_tid(lds); if (tid >= 352) return;
;     const int f0 = 8 * tid; const bool first = (gi & 255) == 0;
;     const bf16* h = HB + (size_t)gi * 4 * NUP; const bf16* hp = HB + (size_t)(gi - 1) * 4 * NUP;
;     float r0[8], r1[8];
; #pragma unroll
;     for (int part = 0; part < 2; ++part) { const int c0 = part * NFF + f0;
;         const u32x4 u0 = *(const u32x4*)(h + c0), u1 = *(const u32x4*)(h + NUP + c0);
;         u32x4 p2 = {0u, 0u, 0u, 0u}, p3 = {0u, 0u, 0u, 0u}; if (!first) { p2 = *(const u32x4*)(hp + 2 * NUP + c0); p3 = *(const u32x4*)(hp + 3 * NUP + c0); }
.LBB0_1546:
	s_getreg_b32 s12, hwreg(HW_REG_HW_ID, 0, 6)
	s_lshl_b32 s12, s12, 2
	s_and_b32 s12, s12, 0xfc
	s_add_i32 s12, s12, 0
	s_add_i32 s12, s12, 0x25a00
	v_mov_b32_e32 v0, s12
	ds_read_b32 v0, v0
	s_waitcnt lgkmcnt(0)
	v_readfirstlane_b32 s12, v0
	v_mbcnt_lo_u32_b32 v0, -1, 0
	v_mbcnt_hi_u32_b32 v0, -1, v0
	s_nop 1
	v_lshl_add_u32 v0, s12, 6, v0
	v_cmp_gt_i32_e32 vcc, s27, v0
	s_and_saveexec_b64 s[12:13], vcc
	s_cbranch_execz .LBB0_1545
	s_add_i32 s40, s31, s10
	s_cmp_lg_u32 s40, 0
	s_mul_i32 s15, s37, 0xb000
	s_cselect_b64 s[16:17], -1, 0
	s_mul_hi_i32 s14, s37, 0xb000
	s_add_u32 s18, s22, s15
	s_addc_u32 s19, s23, s14
	s_add_u32 s14, s18, 0x8400
	s_addc_u32 s15, s19, 0
	s_add_u32 s18, s18, 0x5800
	v_lshlrev_b32_e32 v12, 3, v0
	s_addc_u32 s19, s19, 0
	s_add_u32 s38, s34, s10
	v_ashrrev_i32_e32 v13, 31, v12
	s_addc_u32 s39, s35, s11
	v_lshlrev_b64 v[64:65], 1, v[12:13]
	v_lshl_add_u64 v[4:5], s[38:39], 0, v[64:65]
	v_add_co_u32_e32 v6, vcc, 0x6800000, v4
	s_cmp_eq_u32 s40, 0
	s_nop 0
	v_addc_co_u32_e32 v7, vcc, 0, v5, vcc
	v_add_co_u32_e32 v8, vcc, 0x6802000, v4
	s_nop 1
	v_addc_co_u32_e32 v9, vcc, 0, v5, vcc
	global_load_dwordx4 v[44:47], v[6:7], off
	global_load_dwordx4 v[0:3], v[8:9], off offset:3072
	s_cbranch_scc1 .LBB0_1549
	v_lshl_add_u64 v[6:7], s[18:19], 0, v[64:65]
	v_lshl_add_u64 v[8:9], s[14:15], 0, v[64:65]
	global_load_dwordx4 v[24:27], v[6:7], off
	global_load_dwordx4 v[20:23], v[8:9], off
	s_branch .LBB0_1550

; __device__ __forceinline__ float bflo(unsigned w) { return __uint_as_float(w << 16); }
; __device__ __forceinline__ float bfhi(unsigned w) { return __uint_as_float(w & 0xffff0000u); }
; __device__ __forceinline__ void conv_fix_item(LAS unsigned char* lds, const bf16* HB, int gi, const float* cw, const float* cb, bf16* ACT) {
;     ...
;     for (int part = 0; part < 2; ++part) { const int c0 = part * NFF + f0;
;         const u32x4 u0 = *(const u32x4*)(h + c0), u1 = *(const u32x4*)(h + NUP + c0);
;         u32x4 p2 = {0u, 0u, 0u, 0u}, p3 = {0u, 0u, 0u, 0u}; if (!first) { p2 = *(const u32x4*)(hp + 2 * NUP + c0); p3 = *(const u32x4*)(hp + 3 * NUP + c0); }
; #pragma unroll
;         for (int i = 0; i < 8; ++i) { const float w0 = cw[c0 + i], w1 = cw[NUP + c0 + i], w2 = cw[2 * NUP + c0 + i], bb = cb[c0 + i];
;             const float x0 = (i & 1) ? bfhi(u0[i >> 1]) : bflo(u0[i >> 1]), x1 = (i & 1) ? bfhi(u1[i >> 1]) : bflo(u1[i >> 1]);
.LBB0_1550:
	v_lshlrev_b64 v[6:7], 2, v[12:13]
	v_lshl_add_u64 v[68:69], s[4:5], 0, v[6:7]
	v_lshl_add_u64 v[70:71], s[6:7], 0, v[6:7]
	v_add_co_u32_e32 v6, vcc, 0xb000, v68
	v_add_u32_e32 v66, 0xb00, v12
	s_nop 0
	v_addc_co_u32_e32 v7, vcc, 0, v69, vcc
	v_add_co_u32_e32 v8, vcc, 0x5000, v68
	v_ashrrev_i32_e32 v67, 31, v66
	s_nop 0
	v_addc_co_u32_e32 v9, vcc, 0, v69, vcc
	global_load_dwordx4 v[48:51], v[6:7], off
	global_load_dwordx4 v[28:31], v[6:7], off offset:16
	global_load_dwordx4 v[52:55], v[68:69], off
	global_load_dwordx4 v[32:35], v[68:69], off offset:16
	global_load_dwordx4 v[56:59], v[70:71], off
	global_load_dwordx4 v[36:39], v[70:71], off offset:16
	global_load_dwordx4 v[60:63], v[8:9], off offset:2048
	global_load_dwordx4 v[40:43], v[8:9], off offset:2064
	v_add_co_u32_e32 v6, vcc, 0x6801000, v4
	s_nop 1
	v_addc_co_u32_e32 v7, vcc, 0, v5, vcc
	v_add_co_u32_e32 v4, vcc, 0x6804000, v4
	s_nop 1
	v_addc_co_u32_e32 v5, vcc, 0, v5, vcc
	global_load_dwordx4 v[8:11], v[6:7], off offset:1536
	s_nop 0
	global_load_dwordx4 v[4:7], v[4:5], off offset:512
	s_andn2_b64 vcc, exec, s[16:17]
	s_cbranch_vccz .LBB0_1543
	v_mov_b32_e32 v12, 0
	v_mov_b32_e32 v13, 0
	v_mov_b32_e32 v14, 0
	v_mov_b32_e32 v15, 0
	v_mov_b32_e32 v16, 0
	v_mov_b32_e32 v17, 0
	v_mov_b32_e32 v18, 0
	v_mov_b32_e32 v19, 0
	s_branch .LBB0_1544

; __device__ __forceinline__ unsigned xb_ld(unsigned* p)              { return __hip_atomic_load(p, __ATOMIC_RELAXED, __HIP_MEMORY_SCOPE_AGENT); }
; __device__ __forceinline__ unsigned xb_add(unsigned* p, unsigned v) { return __hip_atomic_fetch_add(p, v, __ATOMIC_RELAXED, __HIP_MEMORY_SCOPE_AGENT); }
; #define XB_SPIN(cond, bar) do { unsigned _sp = 0; while (cond) { __builtin_amdgcn_s_sleep(1); \
;     if ((++_sp & 255u) == 0u) { if (xb_ld(&(bar)[XB_TMO])) break; if (_sp > XB_SPIN_CAP) { atomicAdd(&(bar)[XB_TMO], 1u); break; } } } } while (0)
; __device__ __forceinline__ void xcd_barrier(const XcdBarrier& b, bool leader) {
;     ...
;         const unsigned old = xb_add(&bar[XB_XSUB(b.x)], 1u);
;         const unsigned gen = old / nloc;
;         if (old + 1u == (gen + 1u) * nloc) {
;             __builtin_amdgcn_fence(__ATOMIC_RELEASE, "agent");
;             asm volatile("s_waitcnt vmcnt(0)" ::: "memory");
;             const unsigned og = xb_add(&bar[XB_TOP], 1u);
;             const unsigned tg = og / nx;
;             if (og + 1u == (tg + 1u) * nx) xb_add(&bar[XB_TOPGEN], 1u);
;             else XB_SPIN(xb_ld(&bar[XB_TOPGEN]) == tg, bar);
;             __builtin_amdgcn_fence(__ATOMIC_ACQUIRE, "agent");
;             xb_add(&bar[XB_XGEN(b.x)], 1u);
;             asm volatile("s_waitcnt vmcnt(0)" ::: "memory");
;         } else {
;             XB_SPIN(xb_ld(&bar[XB_XGEN(b.x)]) == gen, bar);
.LBB0_1567:
	s_lshl_b32 s4, s41, 8
	s_add_u32 s4, s40, s4
	s_addc_u32 s5, s37, 0
	v_mov_b32_e32 v1, s4
	v_add_co_u32_e32 v4, vcc, 0x2000, v1
	v_mov_b32_e32 v1, s5
	s_nop 0
	v_addc_co_u32_e32 v5, vcc, 0, v1, vcc
	v_mov_b32_e32 v1, 1
	global_atomic_add v1, v[4:5], v1, off offset:1024 sc0
	v_cvt_f32_u32_e32 v3, v2
	v_sub_u32_e32 v4, 0, v2
	s_add_u32 s27, s4, 0x1000
	s_addc_u32 s26, s5, 0
	v_rcp_iflag_f32_e32 v3, v3
	s_nop 0
	v_mul_f32_e32 v3, 0x4f7ffffe, v3
	v_cvt_u32_f32_e32 v3, v3
	v_mul_lo_u32 v4, v4, v3
	v_mul_hi_u32 v4, v3, v4
	v_add_u32_e32 v3, v3, v4
	s_waitcnt vmcnt(0) lgkmcnt(0)
	v_mul_hi_u32 v3, v1, v3
	v_mul_lo_u32 v5, v3, v2
	v_add_u32_e32 v4, 1, v1
	v_sub_u32_e32 v1, v1, v5
	v_add_u32_e32 v6, 1, v3
	v_cmp_ge_u32_e32 vcc, v1, v2
	v_sub_u32_e32 v5, v1, v2
	s_nop 0
	v_cndmask_b32_e32 v3, v3, v6, vcc
	v_cndmask_b32_e32 v1, v1, v5, vcc
	v_add_u32_e32 v5, 1, v3
	v_cmp_ge_u32_e32 vcc, v1, v2
	s_nop 1
	v_cndmask_b32_e32 v1, v3, v5, vcc
	v_mad_u64_u32 v[2:3], s[4:5], v2, v1, v[2:3]
	v_cmp_ne_u32_e32 vcc, v4, v2
	s_and_saveexec_b64 s[4:5], vcc
	s_xor_b64 s[4:5], exec, s[4:5]
	s_cbranch_execz .LBB0_1580
	v_mov_b32_e32 v0, s27
	v_add_co_u32_e32 v2, vcc, 0x2000, v0
	v_mov_b32_e32 v0, s26
	s_nop 0
	v_addc_co_u32_e32 v3, vcc, 0, v0, vcc
	global_load_dword v0, v[2:3], off offset:1024 sc1
	s_add_u32 s10, s27, 0x2400
	s_addc_u32 s11, s26, 0
	s_waitcnt vmcnt(0) lgkmcnt(0)
	v_cmp_eq_u32_e32 vcc, v0, v1
	s_and_saveexec_b64 s[6:7], vcc
	s_cbranch_execz .LBB0_1579
	s_add_u32 s8, s40, 0x1200
	s_addc_u32 s9, s37, 0
	s_mov_b32 s28, 1
	s_mov_b64 s[12:13], 0
	s_branch .LBB0_1571

; __device__ __forceinline__ unsigned xb_ld(unsigned* p)              { return __hip_atomic_load(p, __ATOMIC_RELAXED, __HIP_MEMORY_SCOPE_AGENT); }
; __device__ __forceinline__ unsigned xb_add(unsigned* p, unsigned v) { return __hip_atomic_fetch_add(p, v, __ATOMIC_RELAXED, __HIP_MEMORY_SCOPE_AGENT); }
; #define XB_SPIN(cond, bar) do { unsigned _sp = 0; while (cond) { __builtin_amdgcn_s_sleep(1); \
;     if ((++_sp & 255u) == 0u) { if (xb_ld(&(bar)[XB_TMO])) break; if (_sp > XB_SPIN_CAP) { atomicAdd(&(bar)[XB_TMO], 1u); break; } } } } while (0)
; __device__ __forceinline__ void xcd_barrier(const XcdBarrier& b, bool leader) {
;     ...
;         if (old + 1u == (gen + 1u) * nloc) {
;             __builtin_amdgcn_fence(__ATOMIC_RELEASE, "agent");
;             asm volatile("s_waitcnt vmcnt(0)" ::: "memory");
;             const unsigned og = xb_add(&bar[XB_TOP], 1u);
;             const unsigned tg = og / nx;
;             if (og + 1u == (tg + 1u) * nx) xb_add(&bar[XB_TOPGEN], 1u);
;             else XB_SPIN(xb_ld(&bar[XB_TOPGEN]) == tg, bar);
.LBB0_1580:
	s_andn2_saveexec_b64 s[4:5], s[4:5]
	s_cbranch_execz .LBB0_1596
	v_mov_b32_e32 v1, s40
	v_add_co_u32_e32 v2, vcc, 0x4000, v1
	v_mov_b32_e32 v1, s37
	buffer_wbl2 sc1
	s_waitcnt vmcnt(0)
	v_addc_co_u32_e32 v3, vcc, 0, v1, vcc
	v_mov_b32_e32 v1, 1
	global_atomic_add v1, v[2:3], v1, off offset:1024 sc0
	v_cvt_f32_u32_e32 v2, v0
	v_sub_u32_e32 v3, 0, v0
	s_add_u32 s4, s40, 0x4500
	s_addc_u32 s5, s37, 0
	v_rcp_iflag_f32_e32 v2, v2
	s_mov_b64 s[8:9], -1
	v_mul_f32_e32 v2, 0x4f7ffffe, v2
	v_cvt_u32_f32_e32 v2, v2
	v_mul_lo_u32 v3, v3, v2
	v_mul_hi_u32 v3, v2, v3
	v_add_u32_e32 v2, v2, v3
	s_waitcnt vmcnt(0) lgkmcnt(0)
	v_mul_hi_u32 v2, v1, v2
	v_mul_lo_u32 v4, v2, v0
	v_add_u32_e32 v3, 1, v1
	v_sub_u32_e32 v1, v1, v4
	v_add_u32_e32 v5, 1, v2
	v_cmp_ge_u32_e32 vcc, v1, v0
	v_sub_u32_e32 v4, v1, v0
	s_nop 0
	v_cndmask_b32_e32 v2, v2, v5, vcc
	v_cndmask_b32_e32 v1, v1, v4, vcc
	v_add_u32_e32 v4, 1, v2
	v_cmp_ge_u32_e32 vcc, v1, v0
	s_nop 1
	v_cndmask_b32_e32 v2, v2, v4, vcc
	v_mad_u64_u32 v[0:1], s[6:7], v0, v2, v[0:1]
	v_cmp_ne_u32_e32 vcc, v3, v0
	v_mov_b64_e32 v[0:1], s[4:5]
	s_and_saveexec_b64 s[6:7], vcc
	s_cbranch_execz .LBB0_1593
	v_mov_b64_e32 v[0:1], s[4:5]
	global_load_dword v0, v[0:1], off sc1
	s_mov_b64 s[12:13], 0
	s_waitcnt vmcnt(0) lgkmcnt(0)
	v_cmp_eq_u32_e32 vcc, v0, v2
	s_and_saveexec_b64 s[10:11], vcc
	s_cbranch_execz .LBB0_1592
	s_add_u32 s8, s40, 0x1200
	s_addc_u32 s9, s37, 0
	s_mov_b32 s24, 1
	s_branch .LBB0_1585

; __device__ __forceinline__ unsigned xb_ld(unsigned* p)              { return __hip_atomic_load(p, __ATOMIC_RELAXED, __HIP_MEMORY_SCOPE_AGENT); }
; #define XB_SPIN(cond, bar) do { unsigned _sp = 0; while (cond) { __builtin_amdgcn_s_sleep(1); \
;     if ((++_sp & 255u) == 0u) { if (xb_ld(&(bar)[XB_TMO])) break; if (_sp > XB_SPIN_CAP) { atomicAdd(&(bar)[XB_TMO], 1u); break; } } } } while (0)
; __device__ __forceinline__ void xcd_barrier(const XcdBarrier& b, bool leader) {
;     ...
;             else XB_SPIN(xb_ld(&bar[XB_TOPGEN]) == tg, bar);
.LBB0_1587:
	v_mov_b64_e32 v[0:1], s[8:9]
	global_load_dword v0, v[0:1], off sc1
	s_mov_b64 s[18:19], 0
	s_mov_b64 s[16:17], -1
	s_waitcnt vmcnt(0) lgkmcnt(0)
	v_cmp_eq_u32_e32 vcc, 0, v0
	s_and_saveexec_b64 s[20:21], vcc
	s_cmp_lt_u32 s24, 0x400001
	s_cselect_b64 s[18:19], -1, 0
	s_xor_b64 s[16:17], exec, -1
	s_and_b64 s[18:19], s[18:19], exec
	s_or_b64 exec, exec, s[20:21]
	s_mov_b64 s[20:21], -1
	s_and_saveexec_b64 s[22:23], s[18:19]
	s_cbranch_execz .LBB0_1584
.LBB0_1590:
	v_mov_b64_e32 v[0:1], s[4:5]
	global_load_dword v0, v[0:1], off sc1
	s_add_i32 s24, s24, 1
	s_or_b64 s[16:17], s[16:17], exec
	s_waitcnt vmcnt(0) lgkmcnt(0)
	v_cmp_ne_u32_e32 vcc, v0, v2
	s_orn2_b64 s[20:21], vcc, exec
	s_branch .LBB0_1584

; __device__ __forceinline__ unsigned pk2(float lo, float hi) { const f32x2 v = {lo, hi}; return __builtin_bit_cast(unsigned, __builtin_convertvector(v, bf16x2_t)); }
; __device__ __forceinline__ float wave_sum(float v) { v += swz_xor<1>(v); v += swz_xor<2>(v); v += swz_xor<4>(v); v += swz_xor<8>(v); v += swz_xor<16>(v); return half_sum(v); }
; #define INP(i) ((const float*)tab_get(lds, (i)))
; #define OUTP() ((float*)tab_get(lds, 30))
; #define WSB(off) ((bf16*)((unsigned char*)tab_get(lds, 31) + (off)))
; #define fresh_lane() (my_tid(lds) & 63)
; __device__ __forceinline__ void rms_row_to_bf16(const float* xrow, const float* g, bf16* orow, int lane) {
;     const f32x4* xr = (const f32x4*)xrow + lane; f32x4 v[4]; float s = 0.f;
; #pragma unroll
;     for (int j = 0; j < 4; ++j) { v[j] = xr[64 * j]; s += (v[j].x * v[j].x + v[j].y * v[j].y) + (v[j].z * v[j].z + v[j].w * v[j].w); }
;     const float rstd = rsqrtf(wave_sum(s) * (1.f / DM) + EPS);
;     u32x2* o8 = (u32x2*)orow + lane;
; #pragma unroll
;     for (int j = 0; j < 4; ++j) { const f32x4 gg = ((const f32x4*)g)[lane + 64 * j]; u32x2 w; w.x = pk2(v[j].x * rstd * gg.x, v[j].y * rstd * gg.y); w.y = pk2(v[j].z * rstd * gg.z, v[j].w * rstd * gg.w); o8[64 * j] = w; }
; }
; __global__ void __launch_bounds__(512, 2) mega_fwd(Params p) {
;     ...
;         { const int lane = fresh_lane(); const float* X = OUTP(); const float* g = INP(24); bf16* H = WSB(WS_H);
;           for (int m = MP + gw; m < MT; m += NGW) rms_row_to_bf16(X + (size_t)m * DM, g, H + (size_t)m * DM, lane); }
.LBB0_1598:
	global_load_dwordx4 v[8:11], v[4:5], off
	global_load_dwordx4 v[12:15], v[4:5], off offset:1024
	global_load_dwordx4 v[16:19], v[4:5], off offset:2048
	global_load_dwordx4 v[20:23], v[4:5], off offset:3072
	global_load_dwordx4 v[24:27], v[0:1], off
	s_add_i32 s11, s11, s44
	v_lshl_add_u64 v[4:5], v[4:5], 0, s[6:7]
	s_cmp_gt_i32 s11, 0x81ff
	s_waitcnt vmcnt(0) lgkmcnt(0)
	v_mul_f32_e32 v7, v9, v9
	v_mul_f32_e32 v28, v11, v11
	v_mul_f32_e32 v29, v13, v13
	v_mul_f32_e32 v30, v15, v15
	v_mul_f32_e32 v31, v17, v17
	v_mul_f32_e32 v32, v19, v19
	v_fmac_f32_e32 v7, v8, v8
	v_fmac_f32_e32 v28, v10, v10
	v_fmac_f32_e32 v29, v12, v12
	v_fmac_f32_e32 v30, v14, v14
	v_mul_f32_e32 v33, v21, v21
	v_mul_f32_e32 v34, v23, v23
	v_fmac_f32_e32 v31, v16, v16
	v_fmac_f32_e32 v32, v18, v18
	v_add_f32_e32 v7, v7, v28
	v_add_f32_e32 v28, v29, v30
	v_fmac_f32_e32 v33, v20, v20
	v_fmac_f32_e32 v34, v22, v22
	v_add_f32_e32 v29, v31, v32
	v_add_f32_e32 v7, v7, v28
	v_add_f32_e32 v30, v33, v34
	v_add_f32_e32 v7, v7, v29
	v_add_f32_e32 v7, v7, v30
	ds_swizzle_b32 v28, v7 offset:swizzle(SWAP,1)
	s_waitcnt lgkmcnt(0)
	v_add_f32_e32 v7, v7, v28
	ds_swizzle_b32 v28, v7 offset:swizzle(SWAP,2)
	s_waitcnt lgkmcnt(0)
	v_add_f32_e32 v7, v7, v28
	ds_swizzle_b32 v28, v7 offset:swizzle(SWAP,4)
	s_waitcnt lgkmcnt(0)
	v_add_f32_e32 v7, v7, v28
	ds_swizzle_b32 v28, v7 offset:swizzle(SWAP,8)
	s_waitcnt lgkmcnt(0)
	v_add_f32_e32 v7, v7, v28
	ds_swizzle_b32 v28, v7 offset:swizzle(SWAP,16)
	s_waitcnt lgkmcnt(0)
	v_add_f32_e32 v7, v7, v28
	v_mov_b32_e32 v28, v7
	s_nop 1
	v_permlane32_swap_b32_e32 v7, v28
	v_add_f32_e32 v7, v7, v28
	v_fmamk_f32 v7, v7, 0x3a800000, v6
	v_mul_f32_e32 v28, 0x4b800000, v7
	v_cmp_gt_f32_e32 vcc, s10, v7
	s_nop 1
	v_cndmask_b32_e32 v7, v7, v28, vcc
	v_rsq_f32_e32 v7, v7
	s_nop 0
	v_mul_f32_e32 v28, 0x45800000, v7
	v_cndmask_b32_e32 v28, v7, v28, vcc
	v_pk_mul_f32 v[8:9], v[8:9], v[28:29] op_sel_hi:[1,0]
	v_pk_mul_f32 v[10:11], v[10:11], v[28:29] op_sel_hi:[1,0]
	v_pk_mul_f32 v[8:9], v[24:25], v[8:9]
	v_pk_mul_f32 v[10:11], v[26:27], v[10:11]
	v_cvt_pk_bf16_f32 v8, v8, v9
	v_cvt_pk_bf16_f32 v9, v10, v11
	global_store_dwordx2 v[2:3], v[8:9], off
	global_load_dwordx4 v[8:11], v[0:1], off offset:1024
	v_pk_mul_f32 v[12:13], v[12:13], v[28:29] op_sel_hi:[1,0]
	v_pk_mul_f32 v[14:15], v[14:15], v[28:29] op_sel_hi:[1,0]
	s_waitcnt vmcnt(0) lgkmcnt(0)
	v_pk_mul_f32 v[8:9], v[8:9], v[12:13]
	v_pk_mul_f32 v[10:11], v[10:11], v[14:15]
	v_cvt_pk_bf16_f32 v8, v8, v9
	v_cvt_pk_bf16_f32 v9, v10, v11
	global_store_dwordx2 v[2:3], v[8:9], off offset:512
	global_load_dwordx4 v[8:11], v[0:1], off offset:2048
	v_pk_mul_f32 v[12:13], v[16:17], v[28:29] op_sel_hi:[1,0]
	v_pk_mul_f32 v[14:15], v[18:19], v[28:29] op_sel_hi:[1,0]
	s_waitcnt vmcnt(0) lgkmcnt(0)
	v_pk_mul_f32 v[8:9], v[8:9], v[12:13]
	v_pk_mul_f32 v[10:11], v[10:11], v[14:15]
	v_cvt_pk_bf16_f32 v8, v8, v9
	v_cvt_pk_bf16_f32 v9, v10, v11
	global_store_dwordx2 v[2:3], v[8:9], off offset:1024
	global_load_dwordx4 v[8:11], v[0:1], off offset:3072
	v_pk_mul_f32 v[12:13], v[20:21], v[28:29] op_sel_hi:[1,0]
	v_pk_mul_f32 v[14:15], v[22:23], v[28:29] op_sel_hi:[1,0]
	s_waitcnt vmcnt(0) lgkmcnt(0)
	v_pk_mul_f32 v[8:9], v[8:9], v[12:13]
	v_pk_mul_f32 v[10:11], v[10:11], v[14:15]
	v_cvt_pk_bf16_f32 v8, v8, v9
	v_cvt_pk_bf16_f32 v9, v10, v11
	global_store_dwordx2 v[2:3], v[8:9], off offset:1536
	v_lshl_add_u64 v[2:3], v[2:3], 0, s[4:5]
	s_cbranch_scc0 .LBB0_1598

;     __device__ __forceinline__ void operator()(EPI_ARGS) const {
;         const int row0 = u.pm * BM + wr * 64 + fr, col0 = u.pn * BM + wc * 32 + 8 * fq;
; #pragma unroll
;         for (int ai = 0; ai < 2; ++ai)
; #pragma unroll
;             for (int m = 0; m < 4; ++m) { const int row = row0 + ai * HALF + m * 16;
;                 const float* b = base + (size_t)row * DM + col0; float* o = X + (size_t)row * DM + col0;
; #pragma unroll
;                 for (int bj = 0; bj < 2; ++bj) { const f32x4 b0 = *(const f32x4*)(b + bj * HALF), b1 = *(const f32x4*)(b + bj * HALF + 4);
;                     *(f32x4*)(o + bj * HALF) = b0 + acc[ai][bj][m][0]; *(f32x4*)(o + bj * HALF + 4) = b1 + acc[ai][bj][m][1]; } }
;     }
.LBB0_1623:
	v_lshl_add_u32 v148, s59, 8, v150
	v_lshl_or_b32 v144, s60, 8, v152
	v_ashrrev_i32_e32 v149, 31, v148
	v_ashrrev_i32_e32 v145, 31, v144
	v_lshlrev_b64 v[146:147], 12, v[148:149]
	v_lshl_add_u64 v[156:157], s[6:7], 0, v[146:147]
	v_lshlrev_b64 v[146:147], 2, v[144:145]
	v_lshl_add_u64 v[144:145], v[156:157], 0, v[146:147]
	global_load_dwordx4 v[156:159], v[144:145], off
	global_load_dwordx4 v[160:163], v[144:145], off offset:16
	s_mov_b64 s[24:25], -1
	s_waitcnt vmcnt(0) lgkmcnt(0)
	v_pk_add_f32 v[126:127], v[126:127], v[158:159]
	v_pk_add_f32 v[124:125], v[124:125], v[156:157]
	v_pk_add_f32 v[122:123], v[122:123], v[162:163]
	v_pk_add_f32 v[120:121], v[120:121], v[160:161]
	global_store_dwordx4 v[144:145], v[124:127], off
	global_store_dwordx4 v[144:145], v[120:123], off offset:16
	global_load_dwordx4 v[120:123], v[144:145], off offset:512
	s_nop 0
	global_load_dwordx4 v[124:127], v[144:145], off offset:528
	s_waitcnt vmcnt(0) lgkmcnt(0)
	v_pk_add_f32 v[118:119], v[118:119], v[122:123]
	v_pk_add_f32 v[114:115], v[114:115], v[126:127]
	v_pk_add_f32 v[112:113], v[112:113], v[124:125]
	global_store_dwordx4 v[144:145], v[112:115], off offset:528
	v_pk_add_f32 v[116:117], v[116:117], v[120:121]
	global_store_dwordx4 v[144:145], v[116:119], off offset:512
	v_or_b32_e32 v112, 16, v148
	v_ashrrev_i32_e32 v113, 31, v112
	v_lshlrev_b64 v[112:113], 12, v[112:113]
	v_lshl_add_u64 v[112:113], s[6:7], 0, v[112:113]
	v_lshl_add_u64 v[120:121], v[112:113], 0, v[146:147]
	global_load_dwordx4 v[112:115], v[120:121], off
	global_load_dwordx4 v[116:119], v[120:121], off offset:16
	s_waitcnt vmcnt(0) lgkmcnt(0)
	v_pk_add_f32 v[110:111], v[110:111], v[114:115]
	v_pk_add_f32 v[108:109], v[108:109], v[112:113]
	v_pk_add_f32 v[106:107], v[106:107], v[118:119]
	v_pk_add_f32 v[104:105], v[104:105], v[116:117]
	global_store_dwordx4 v[120:121], v[108:111], off
	global_store_dwordx4 v[120:121], v[104:107], off offset:16
	global_load_dwordx4 v[104:107], v[120:121], off offset:512
	s_nop 0
	global_load_dwordx4 v[108:111], v[120:121], off offset:528
	s_waitcnt vmcnt(0) lgkmcnt(0)
	v_pk_add_f32 v[102:103], v[102:103], v[106:107]
	v_pk_add_f32 v[98:99], v[98:99], v[110:111]
	v_pk_add_f32 v[96:97], v[96:97], v[108:109]
	global_store_dwordx4 v[120:121], v[96:99], off offset:528
	v_pk_add_f32 v[100:101], v[100:101], v[104:105]
	global_store_dwordx4 v[120:121], v[100:103], off offset:512
	v_or_b32_e32 v96, 32, v148
	v_ashrrev_i32_e32 v97, 31, v96
	v_lshlrev_b64 v[96:97], 12, v[96:97]
	v_lshl_add_u64 v[96:97], s[6:7], 0, v[96:97]
	v_lshl_add_u64 v[104:105], v[96:97], 0, v[146:147]
	global_load_dwordx4 v[96:99], v[104:105], off
	global_load_dwordx4 v[100:103], v[104:105], off offset:16
	s_waitcnt vmcnt(0) lgkmcnt(0)
	v_pk_add_f32 v[94:95], v[94:95], v[98:99]
	v_pk_add_f32 v[92:93], v[92:93], v[96:97]
	v_pk_add_f32 v[90:91], v[90:91], v[102:103]
	v_pk_add_f32 v[88:89], v[88:89], v[100:101]
	global_store_dwordx4 v[104:105], v[92:95], off
	global_store_dwordx4 v[104:105], v[88:91], off offset:16
	global_load_dwordx4 v[88:91], v[104:105], off offset:512
	s_nop 0
	global_load_dwordx4 v[92:95], v[104:105], off offset:528
	s_waitcnt vmcnt(0) lgkmcnt(0)
	v_pk_add_f32 v[86:87], v[86:87], v[90:91]
	v_pk_add_f32 v[82:83], v[82:83], v[94:95]
	v_pk_add_f32 v[80:81], v[80:81], v[92:93]
	global_store_dwordx4 v[104:105], v[80:83], off offset:528
	v_pk_add_f32 v[84:85], v[84:85], v[88:89]
	global_store_dwordx4 v[104:105], v[84:87], off offset:512
	v_or_b32_e32 v80, 48, v148
	v_ashrrev_i32_e32 v81, 31, v80
	v_lshlrev_b64 v[80:81], 12, v[80:81]
	v_lshl_add_u64 v[80:81], s[6:7], 0, v[80:81]
	v_lshl_add_u64 v[88:89], v[80:81], 0, v[146:147]
	global_load_dwordx4 v[80:83], v[88:89], off
	global_load_dwordx4 v[84:87], v[88:89], off offset:16
	s_waitcnt vmcnt(0) lgkmcnt(0)
	v_pk_add_f32 v[78:79], v[78:79], v[82:83]
	v_pk_add_f32 v[76:77], v[76:77], v[80:81]
	v_pk_add_f32 v[74:75], v[74:75], v[86:87]
	v_pk_add_f32 v[72:73], v[72:73], v[84:85]
	global_store_dwordx4 v[88:89], v[76:79], off
	global_store_dwordx4 v[88:89], v[72:75], off offset:16
	global_load_dwordx4 v[72:75], v[88:89], off offset:512
	s_nop 0
	global_load_dwordx4 v[76:79], v[88:89], off offset:528
	s_waitcnt vmcnt(0) lgkmcnt(0)
;     __device__ __forceinline__ void operator()(EPI_ARGS) const {
;         const int row0 = u.pm * BM + wr * 64 + fr, col0 = u.pn * BM + wc * 32 + 8 * fq;
; #pragma unroll
;         for (int ai = 0; ai < 2; ++ai)
; #pragma unroll
;             for (int m = 0; m < 4; ++m) { const int row = row0 + ai * HALF + m * 16;
;                 const float* b = base + (size_t)row * DM + col0; float* o = X + (size_t)row * DM + col0;
; #pragma unroll
;                 for (int bj = 0; bj < 2; ++bj) { const f32x4 b0 = *(const f32x4*)(b + bj * HALF), b1 = *(const f32x4*)(b + bj * HALF + 4);
;                     *(f32x4*)(o + bj * HALF) = b0 + acc[ai][bj][m][0]; *(f32x4*)(o + bj * HALF + 4) = b1 + acc[ai][bj][m][1]; } }
;     }
	v_pk_add_f32 v[70:71], v[70:71], v[74:75]
	v_pk_add_f32 v[68:69], v[68:69], v[72:73]
	v_pk_add_f32 v[66:67], v[66:67], v[78:79]
	v_pk_add_f32 v[64:65], v[64:65], v[76:77]
	v_add_co_u32_e32 v74, vcc, s51, v144
	global_store_dwordx4 v[88:89], v[68:71], off offset:512
	global_store_dwordx4 v[88:89], v[64:67], off offset:528
	v_addc_co_u32_e32 v75, vcc, 0, v145, vcc
	v_lshl_add_u64 v[72:73], v[144:145], 0, s[16:17]
	global_load_dwordx4 v[64:67], v[74:75], off
	global_load_dwordx4 v[68:71], v[72:73], off offset:16
	s_waitcnt vmcnt(0) lgkmcnt(0)
	v_pk_add_f32 v[62:63], v[62:63], v[66:67]
	v_pk_add_f32 v[60:61], v[60:61], v[64:65]
	v_pk_add_f32 v[58:59], v[58:59], v[70:71]
	v_pk_add_f32 v[56:57], v[56:57], v[68:69]
	global_store_dwordx4 v[74:75], v[60:63], off
	global_store_dwordx4 v[72:73], v[56:59], off offset:16
	global_load_dwordx4 v[56:59], v[72:73], off offset:512
	s_nop 0
	global_load_dwordx4 v[60:63], v[72:73], off offset:528
	s_waitcnt vmcnt(0) lgkmcnt(0)
	v_pk_add_f32 v[54:55], v[54:55], v[58:59]
	v_pk_add_f32 v[52:53], v[52:53], v[56:57]
	v_pk_add_f32 v[50:51], v[50:51], v[62:63]
	v_pk_add_f32 v[48:49], v[48:49], v[60:61]
	v_add_co_u32_e32 v58, vcc, s54, v144
	global_store_dwordx4 v[72:73], v[52:55], off offset:512
	global_store_dwordx4 v[72:73], v[48:51], off offset:528
	v_addc_co_u32_e32 v59, vcc, 0, v145, vcc
	v_lshl_add_u64 v[56:57], v[144:145], 0, s[18:19]
	global_load_dwordx4 v[48:51], v[58:59], off
	global_load_dwordx4 v[52:55], v[56:57], off offset:16
	s_waitcnt vmcnt(0) lgkmcnt(0)
	v_pk_add_f32 v[46:47], v[46:47], v[50:51]
	v_pk_add_f32 v[44:45], v[44:45], v[48:49]
	v_pk_add_f32 v[42:43], v[42:43], v[54:55]
	v_pk_add_f32 v[40:41], v[40:41], v[52:53]
	global_store_dwordx4 v[58:59], v[44:47], off
	global_store_dwordx4 v[56:57], v[40:43], off offset:16
	global_load_dwordx4 v[40:43], v[56:57], off offset:512
	s_nop 0
	global_load_dwordx4 v[44:47], v[56:57], off offset:528
	s_waitcnt vmcnt(0) lgkmcnt(0)
	v_pk_add_f32 v[38:39], v[38:39], v[42:43]
	v_pk_add_f32 v[36:37], v[36:37], v[40:41]
	v_pk_add_f32 v[34:35], v[34:35], v[46:47]
	v_pk_add_f32 v[32:33], v[32:33], v[44:45]
	v_add_co_u32_e32 v42, vcc, s55, v144
	global_store_dwordx4 v[56:57], v[36:39], off offset:512
	global_store_dwordx4 v[56:57], v[32:35], off offset:528
	v_addc_co_u32_e32 v43, vcc, 0, v145, vcc
	v_lshl_add_u64 v[40:41], v[144:145], 0, s[20:21]
	global_load_dwordx4 v[32:35], v[42:43], off
	global_load_dwordx4 v[36:39], v[40:41], off offset:16
	s_waitcnt vmcnt(0) lgkmcnt(0)
	v_pk_add_f32 v[30:31], v[30:31], v[34:35]
	v_pk_add_f32 v[28:29], v[28:29], v[32:33]
	v_pk_add_f32 v[26:27], v[26:27], v[38:39]
	v_pk_add_f32 v[24:25], v[24:25], v[36:37]
	global_store_dwordx4 v[42:43], v[28:31], off
	global_store_dwordx4 v[40:41], v[24:27], off offset:16
	global_load_dwordx4 v[24:27], v[40:41], off offset:512
	s_nop 0
	global_load_dwordx4 v[28:31], v[40:41], off offset:528
	s_waitcnt vmcnt(0) lgkmcnt(0)
	v_pk_add_f32 v[22:23], v[22:23], v[26:27]
	v_pk_add_f32 v[20:21], v[20:21], v[24:25]
	v_pk_add_f32 v[18:19], v[18:19], v[30:31]
	v_pk_add_f32 v[16:17], v[16:17], v[28:29]
	v_add_co_u32_e32 v26, vcc, s56, v144
	global_store_dwordx4 v[40:41], v[20:23], off offset:512
	global_store_dwordx4 v[40:41], v[16:19], off offset:528
	v_addc_co_u32_e32 v27, vcc, 0, v145, vcc
	s_nop 0
	v_lshl_add_u64 v[16:17], v[144:145], 0, s[8:9]
	global_load_dwordx4 v[18:21], v[26:27], off
	global_load_dwordx4 v[22:25], v[16:17], off offset:16
	s_and_b64 vcc, exec, s[2:3]
	s_waitcnt vmcnt(0) lgkmcnt(0)
	v_pk_add_f32 v[14:15], v[14:15], v[20:21]
	v_pk_add_f32 v[12:13], v[12:13], v[18:19]
	v_pk_add_f32 v[10:11], v[10:11], v[24:25]
	v_pk_add_f32 v[8:9], v[8:9], v[22:23]
	global_store_dwordx4 v[26:27], v[12:15], off
	global_store_dwordx4 v[16:17], v[8:11], off offset:16
	global_load_dwordx4 v[8:11], v[16:17], off offset:512
	s_nop 0
	global_load_dwordx4 v[12:15], v[16:17], off offset:528
	s_waitcnt vmcnt(0) lgkmcnt(0)
	v_pk_add_f32 v[6:7], v[6:7], v[10:11]
	v_pk_add_f32 v[4:5], v[4:5], v[8:9]
	v_pk_add_f32 v[2:3], v[2:3], v[14:15]
	v_pk_add_f32 v[0:1], v[0:1], v[12:13]
	global_store_dwordx4 v[16:17], v[4:7], off offset:512
	global_store_dwordx4 v[16:17], v[0:3], off offset:528
	s_cbranch_vccnz .LBB0_1608
	s_andn2_b64 vcc, exec, s[10:11]
	s_cbranch_vccnz .LBB0_1607
	s_barrier
	s_branch .LBB0_1607

; __device__ __forceinline__ unsigned xb_ld(unsigned* p)              { return __hip_atomic_load(p, __ATOMIC_RELAXED, __HIP_MEMORY_SCOPE_AGENT); }
; __device__ __forceinline__ unsigned xb_add(unsigned* p, unsigned v) { return __hip_atomic_fetch_add(p, v, __ATOMIC_RELAXED, __HIP_MEMORY_SCOPE_AGENT); }
; #define XB_SPIN(cond, bar) do { unsigned _sp = 0; while (cond) { __builtin_amdgcn_s_sleep(1); \
;     if ((++_sp & 255u) == 0u) { if (xb_ld(&(bar)[XB_TMO])) break; if (_sp > XB_SPIN_CAP) { atomicAdd(&(bar)[XB_TMO], 1u); break; } } } } while (0)
; __device__ __forceinline__ void xcd_barrier(const XcdBarrier& b, bool leader) {
;     ...
;     if (leader) {
;         unsigned* bar = b.bar;
;         __builtin_amdgcn_s_waitcnt(0);
;         unsigned nloc = b.st[0], nx = b.st[1];
;         if (nloc == 0u) { xcd_barrier_complete(bar, b.x, nloc, nx); b.st[0] = nloc; b.st[1] = nx; }
;         const unsigned old = xb_add(&bar[XB_XSUB(b.x)], 1u);
;         const unsigned gen = old / nloc;
;         if (old + 1u == (gen + 1u) * nloc) {
;             __builtin_amdgcn_fence(__ATOMIC_RELEASE, "agent");
;             asm volatile("s_waitcnt vmcnt(0)" ::: "memory");
;             const unsigned og = xb_add(&bar[XB_TOP], 1u);
;             const unsigned tg = og / nx;
;             if (og + 1u == (tg + 1u) * nx) xb_add(&bar[XB_TOPGEN], 1u);
;             else XB_SPIN(xb_ld(&bar[XB_TOPGEN]) == tg, bar);
;             __builtin_amdgcn_fence(__ATOMIC_ACQUIRE, "agent");
;             xb_add(&bar[XB_XGEN(b.x)], 1u);
;             asm volatile("s_waitcnt vmcnt(0)" ::: "memory");
;         } else {
;             XB_SPIN(xb_ld(&bar[XB_XGEN(b.x)]) == gen, bar);
;             __builtin_amdgcn_fence(__ATOMIC_ACQUIRE, "agent");
;             asm volatile("s_waitcnt vmcnt(0)" ::: "memory");
;         }
.LBB0_1642:
	s_lshl_b32 s2, s39, 8
	s_add_u32 s2, s38, s2
	s_addc_u32 s3, s37, 0
	v_mov_b32_e32 v1, s2
	v_add_co_u32_e32 v4, vcc, 0x2000, v1
	v_mov_b32_e32 v1, s3
	s_nop 0
	v_addc_co_u32_e32 v5, vcc, 0, v1, vcc
	v_mov_b32_e32 v1, 1
	global_atomic_add v1, v[4:5], v1, off offset:1024 sc0
	v_cvt_f32_u32_e32 v3, v2
	v_sub_u32_e32 v4, 0, v2
	s_add_u32 s25, s2, 0x1000
	s_addc_u32 s24, s3, 0
	v_rcp_iflag_f32_e32 v3, v3
	s_nop 0
	v_mul_f32_e32 v3, 0x4f7ffffe, v3
	v_cvt_u32_f32_e32 v3, v3
	v_mul_lo_u32 v4, v4, v3
	v_mul_hi_u32 v4, v3, v4
	v_add_u32_e32 v3, v3, v4
	s_waitcnt vmcnt(0) lgkmcnt(0)
	v_mul_hi_u32 v3, v1, v3
	v_mul_lo_u32 v5, v3, v2
	v_add_u32_e32 v4, 1, v1
	v_sub_u32_e32 v1, v1, v5
	v_add_u32_e32 v6, 1, v3
	v_cmp_ge_u32_e32 vcc, v1, v2
	v_sub_u32_e32 v5, v1, v2
	s_nop 0
	v_cndmask_b32_e32 v3, v3, v6, vcc
	v_cndmask_b32_e32 v1, v1, v5, vcc
	v_add_u32_e32 v5, 1, v3
	v_cmp_ge_u32_e32 vcc, v1, v2
	s_nop 1
	v_cndmask_b32_e32 v1, v3, v5, vcc
	v_mad_u64_u32 v[2:3], s[2:3], v2, v1, v[2:3]
	v_cmp_ne_u32_e32 vcc, v4, v2
	s_and_saveexec_b64 s[2:3], vcc
	s_xor_b64 s[2:3], exec, s[2:3]
	s_cbranch_execz .LBB0_1655
	v_mov_b32_e32 v0, s25
	v_add_co_u32_e32 v2, vcc, 0x2000, v0
	v_mov_b32_e32 v0, s24
	s_nop 0
	v_addc_co_u32_e32 v3, vcc, 0, v0, vcc
	global_load_dword v0, v[2:3], off offset:1024 sc1
	s_add_u32 s8, s25, 0x2400
	s_addc_u32 s9, s24, 0
	s_waitcnt vmcnt(0) lgkmcnt(0)
	v_cmp_eq_u32_e32 vcc, v0, v1
	s_and_saveexec_b64 s[4:5], vcc
	s_cbranch_execz .LBB0_1654
	s_add_u32 s6, s38, 0x1200
	s_addc_u32 s7, s37, 0
	s_mov_b32 s26, 1
	s_mov_b64 s[10:11], 0
	s_branch .LBB0_1646

; __device__ __forceinline__ unsigned xb_ld(unsigned* p)              { return __hip_atomic_load(p, __ATOMIC_RELAXED, __HIP_MEMORY_SCOPE_AGENT); }
; __device__ __forceinline__ unsigned xb_add(unsigned* p, unsigned v) { return __hip_atomic_fetch_add(p, v, __ATOMIC_RELAXED, __HIP_MEMORY_SCOPE_AGENT); }
; #define XB_SPIN(cond, bar) do { unsigned _sp = 0; while (cond) { __builtin_amdgcn_s_sleep(1); \
;     if ((++_sp & 255u) == 0u) { if (xb_ld(&(bar)[XB_TMO])) break; if (_sp > XB_SPIN_CAP) { atomicAdd(&(bar)[XB_TMO], 1u); break; } } } } while (0)
; __device__ __forceinline__ void xcd_barrier(const XcdBarrier& b, bool leader) {
;     ...
;         if (old + 1u == (gen + 1u) * nloc) {
;             __builtin_amdgcn_fence(__ATOMIC_RELEASE, "agent");
;             asm volatile("s_waitcnt vmcnt(0)" ::: "memory");
;             const unsigned og = xb_add(&bar[XB_TOP], 1u);
;             const unsigned tg = og / nx;
;             if (og + 1u == (tg + 1u) * nx) xb_add(&bar[XB_TOPGEN], 1u);
;             else XB_SPIN(xb_ld(&bar[XB_TOPGEN]) == tg, bar);
;             __builtin_amdgcn_fence(__ATOMIC_ACQUIRE, "agent");
;             xb_add(&bar[XB_XGEN(b.x)], 1u);
.LBB0_1655:
	s_andn2_saveexec_b64 s[2:3], s[2:3]
	s_cbranch_execz .LBB0_1671
	v_mov_b32_e32 v1, s38
	v_add_co_u32_e32 v2, vcc, 0x4000, v1
	v_mov_b32_e32 v1, s37
	buffer_wbl2 sc1
	s_waitcnt vmcnt(0)
	v_addc_co_u32_e32 v3, vcc, 0, v1, vcc
	v_mov_b32_e32 v1, 1
	global_atomic_add v1, v[2:3], v1, off offset:1024 sc0
	v_cvt_f32_u32_e32 v2, v0
	v_sub_u32_e32 v3, 0, v0
	s_add_u32 s2, s38, 0x4500
	s_addc_u32 s3, s37, 0
	v_rcp_iflag_f32_e32 v2, v2
	s_mov_b64 s[6:7], -1
	v_mul_f32_e32 v2, 0x4f7ffffe, v2
	v_cvt_u32_f32_e32 v2, v2
	v_mul_lo_u32 v3, v3, v2
	v_mul_hi_u32 v3, v2, v3
	v_add_u32_e32 v2, v2, v3
	s_waitcnt vmcnt(0) lgkmcnt(0)
	v_mul_hi_u32 v2, v1, v2
	v_mul_lo_u32 v4, v2, v0
	v_add_u32_e32 v3, 1, v1
	v_sub_u32_e32 v1, v1, v4
	v_add_u32_e32 v5, 1, v2
	v_cmp_ge_u32_e32 vcc, v1, v0
	v_sub_u32_e32 v4, v1, v0
	s_nop 0
	v_cndmask_b32_e32 v2, v2, v5, vcc
	v_cndmask_b32_e32 v1, v1, v4, vcc
	v_add_u32_e32 v4, 1, v2
	v_cmp_ge_u32_e32 vcc, v1, v0
	s_nop 1
	v_cndmask_b32_e32 v2, v2, v4, vcc
	v_mad_u64_u32 v[0:1], s[4:5], v0, v2, v[0:1]
	v_cmp_ne_u32_e32 vcc, v3, v0
	v_mov_b64_e32 v[0:1], s[2:3]
	s_and_saveexec_b64 s[4:5], vcc
	s_cbranch_execz .LBB0_1668
	v_mov_b64_e32 v[0:1], s[2:3]
	global_load_dword v0, v[0:1], off sc1
	s_mov_b64 s[10:11], 0
	s_waitcnt vmcnt(0) lgkmcnt(0)
	v_cmp_eq_u32_e32 vcc, v0, v2
	s_and_saveexec_b64 s[8:9], vcc
	s_cbranch_execz .LBB0_1667
	s_add_u32 s6, s38, 0x1200
	s_addc_u32 s7, s37, 0
	s_mov_b32 s22, 1
	s_branch .LBB0_1660

; __device__ __forceinline__ unsigned xb_ld(unsigned* p)              { return __hip_atomic_load(p, __ATOMIC_RELAXED, __HIP_MEMORY_SCOPE_AGENT); }
; #define XB_SPIN(cond, bar) do { unsigned _sp = 0; while (cond) { __builtin_amdgcn_s_sleep(1); \
;     if ((++_sp & 255u) == 0u) { if (xb_ld(&(bar)[XB_TMO])) break; if (_sp > XB_SPIN_CAP) { atomicAdd(&(bar)[XB_TMO], 1u); break; } } } } while (0)
; __device__ __forceinline__ void xcd_barrier(const XcdBarrier& b, bool leader) {
;     ...
;             else XB_SPIN(xb_ld(&bar[XB_TOPGEN]) == tg, bar);
.LBB0_1662:
	v_mov_b64_e32 v[0:1], s[6:7]
	global_load_dword v0, v[0:1], off sc1
	s_mov_b64 s[16:17], 0
	s_mov_b64 s[14:15], -1
	s_waitcnt vmcnt(0) lgkmcnt(0)
	v_cmp_eq_u32_e32 vcc, 0, v0
	s_and_saveexec_b64 s[18:19], vcc
	s_cmp_lt_u32 s22, 0x400001
	s_cselect_b64 s[16:17], -1, 0
	s_xor_b64 s[14:15], exec, -1
	s_and_b64 s[16:17], s[16:17], exec
	s_or_b64 exec, exec, s[18:19]
	s_mov_b64 s[18:19], -1
	s_and_saveexec_b64 s[20:21], s[16:17]
	s_cbranch_execz .LBB0_1659
.LBB0_1665:
	v_mov_b64_e32 v[0:1], s[2:3]
	global_load_dword v0, v[0:1], off sc1
	s_add_i32 s22, s22, 1
	s_or_b64 s[14:15], s[14:15], exec
	s_waitcnt vmcnt(0) lgkmcnt(0)
	v_cmp_ne_u32_e32 vcc, v0, v2
	s_orn2_b64 s[18:19], vcc, exec
	s_branch .LBB0_1659

;     __device__ __forceinline__ void operator()(f32x4 (&acc)[2][2][4][2], const Unit& u, int, int, int, int) const {
;         const int tid = my_tid(lds), wid = __builtin_amdgcn_readfirstlane(tid >> 6), lane = tid & 63, wr = wid >> 2, wc = wid & 3, fr = lane & 15, fq = lane >> 4;
;         const int f0 = u.pn * 128 + wc * 32 + 8 * fq, rowt = u.pm * BM + wr * 64 + fr;
;         f32x4 wa0[2], wa1[2], wa2[2], ba[2], wg0[2], wg1[2], wg2[2], bg[2];
; #pragma unroll
;         for (int n = 0; n < 2; ++n) { const int ch = f0 + 4 * n;
;             wa0[n] = *(const f32x4*)(cw + ch); wa1[n] = *(const f32x4*)(cw + NUP + ch); wa2[n] = *(const f32x4*)(cw + 2 * NUP + ch); ba[n] = *(const f32x4*)(cb + ch);
;             wg0[n] = *(const f32x4*)(cw + NFF + ch); wg1[n] = *(const f32x4*)(cw + NUP + NFF + ch); wg2[n] = *(const f32x4*)(cw + 2 * NUP + NFF + ch); bg[n] = *(const f32x4*)(cb + NFF + ch); }
; #pragma unroll
;         for (int ai = 0; ai < 2; ++ai)
; #pragma unroll
;             for (int m = 0; m < 4; ++m) { const int bseq = (u.pm * BM + ai * HALF + wr * 64 + m * 16) >> 4;
;                 f32x4 sa[2], sg[2];
; #pragma unroll
;                 for (int n = 0; n < 2; ++n) { sa[n] = (f32x4){0.f, 0.f, 0.f, 0.f}; sg[n] = sa[n]; }
;                 if (fr >= 14) { const float* sp = sbuf + (size_t)(bseq * 2 + (fr - 14)) * NUP + f0; float* co = out + O_SCONV + (size_t)(bseq * 2 + (fr - 14)) * NUP + f0;
; #pragma unroll
;                     for (int n = 0; n < 2; ++n) { sa[n] = *(const f32x4*)(sp + 4 * n); sg[n] = *(const f32x4*)(sp + NFF + 4 * n); *(f32x4*)(co + 4 * n) = acc[ai][0][m][n]; *(f32x4*)(co + NFF + 4 * n) = acc[ai][1][m][n]; } }
;                 float r[8];
; #pragma unroll
;                 for (int n = 0; n < 2; ++n)
; #pragma unroll
;                     for (int e = 0; e < 4; ++e) { const float A = acc[ai][0][m][n][e], Gv = acc[ai][1][m][n][e];
;                         const float a1 = dpp_prev(A, sa[n][e], 1), a2 = dpp_prev(A, sa[n][e], 2), g1 = dpp_prev(Gv, sg[n][e], 1), g2 = dpp_prev(Gv, sg[n][e], 2);
;                         const float ca = ba[n][e] + wa0[n][e] * a2 + wa1[n][e] * a1 + wa2[n][e] * A, cg = bg[n][e] + wg0[n][e] * g2 + wg1[n][e] * g1 + wg2[n][e] * Gv;
;                         r[4 * n + e] = silu(ca) * cg; }
;                 u32x4 w; w.x = pk2(r[0], r[1]); w.y = pk2(r[2], r[3]); w.z = pk2(r[4], r[5]); w.w = pk2(r[6], r[7]);
.LBB0_1693:
	s_getreg_b32 s3, hwreg(HW_REG_HW_ID, 0, 6)
	s_lshl_b32 s3, s3, 2
	s_and_b32 s3, s3, 0xfc
	s_add_i32 s3, s3, 0
	s_add_i32 s3, s3, 0x25a00
	v_mov_b32_e32 v44, s3
	ds_read_b32 v44, v44
	v_mbcnt_lo_u32_b32 v192, -1, 0
	v_mbcnt_hi_u32_b32 v192, -1, v192
	s_lshl_b32 s3, s48, 7
	v_lshrrev_b32_e32 v45, 1, v192
	v_and_b32_e32 v232, 15, v192
	s_waitcnt lgkmcnt(0)
	v_readfirstlane_b32 s39, v44
	v_add_u32_e32 v231, -14, v232
	v_mov_b32_e32 v202, 0
	v_lshl_add_u32 v44, s39, 6, v192
	v_mov_b32_e32 v192, 0
	v_readfirstlane_b32 s39, v44
	s_lshr_b32 s41, s39, 1
	s_and_b32 s41, s41, 0x60
	s_or_b32 s3, s41, s3
	v_and_or_b32 v222, v45, 24, s3
	v_ashrrev_i32_e32 v223, 31, v222
	v_lshlrev_b64 v[224:225], 2, v[222:223]
	v_lshl_add_u64 v[46:47], s[18:19], 0, v[224:225]
	v_lshl_add_u64 v[48:49], s[20:21], 0, v[224:225]
	global_load_dwordx4 v[96:99], v[46:47], off
	global_load_dwordx4 v[100:103], v[48:49], off
	v_lshl_add_u64 v[48:49], s[22:23], 0, v[224:225]
	v_lshl_add_u64 v[50:51], s[24:25], 0, v[224:225]
	global_load_dwordx4 v[80:83], v[48:49], off
	global_load_dwordx4 v[84:87], v[50:51], off
	v_lshl_add_u64 v[48:49], s[26:27], 0, v[224:225]
	global_load_dwordx4 v[88:91], v[48:49], off
	v_lshl_add_u64 v[48:49], s[28:29], 0, v[224:225]
	global_load_dwordx4 v[92:95], v[48:49], off
	v_or_b32_e32 v48, 4, v222
	v_ashrrev_i32_e32 v49, 31, v48
	v_lshl_add_u64 v[44:45], s[4:5], 0, v[224:225]
	v_lshlrev_b64 v[60:61], 2, v[48:49]
	global_load_dwordx4 v[104:107], v[44:45], off
	global_load_dwordx4 v[64:67], v[44:45], off offset:16
	v_lshl_add_u64 v[44:45], s[18:19], 0, v[60:61]
	v_lshl_add_u64 v[46:47], s[6:7], 0, v[224:225]
	v_lshl_add_u64 v[48:49], s[20:21], 0, v[60:61]
	global_load_dwordx4 v[68:71], v[44:45], off
	global_load_dwordx4 v[72:75], v[48:49], off
	global_load_dwordx4 v[108:111], v[46:47], off
	global_load_dwordx4 v[76:79], v[46:47], off offset:16
	v_lshl_add_u64 v[44:45], s[22:23], 0, v[60:61]
	v_lshl_add_u64 v[48:49], s[24:25], 0, v[60:61]
	v_lshl_add_u64 v[52:53], s[26:27], 0, v[60:61]
	v_lshl_add_u64 v[60:61], s[28:29], 0, v[60:61]
	global_load_dwordx4 v[44:47], v[44:45], off
	s_nop 0
	global_load_dwordx4 v[48:51], v[48:49], off
	s_ashr_i32 s41, s39, 2
	global_load_dwordx4 v[52:55], v[52:53], off
	s_lshl_b32 s39, s2, 8
	global_load_dwordx4 v[60:63], v[60:61], off
	s_andn2_b32 s41, s41, 63
	v_cmp_lt_u32_e64 s[2:3], 13, v232
	v_mov_b32_e32 v203, 0
	v_mov_b32_e32 v204, 0
	v_mov_b32_e32 v205, 0
	v_mov_b32_e32 v194, 0
	v_mov_b32_e32 v195, 0
	v_mov_b32_e32 v196, 0
	v_mov_b32_e32 v197, 0
	v_mov_b32_e32 v206, 0
	v_mov_b32_e32 v207, 0
	v_mov_b32_e32 v208, 0
	v_mov_b32_e32 v209, 0
	v_mov_b32_e32 v198, 0
	v_mov_b32_e32 v199, 0
	v_mov_b32_e32 v200, 0
	v_mov_b32_e32 v201, 0
	s_and_saveexec_b64 s[48:49], s[2:3]
	s_cbranch_execz .LBB0_1695
	s_add_i32 s50, s41, s39
	s_ashr_i32 s50, s50, 3
	v_add_u32_e32 v193, s50, v231
	v_mov_b64_e32 v[194:195], s[8:9]
	v_mad_i64_i32 v[194:195], s[50:51], v193, s75, v[194:195]
	v_mov_b64_e32 v[196:197], s[30:31]
	v_lshl_add_u64 v[194:195], v[194:195], 0, v[224:225]
	v_mad_i64_i32 v[196:197], s[50:51], v193, s75, v[196:197]
	v_lshl_add_u64 v[234:235], v[196:197], 0, v[224:225]
	v_add_co_u32_e32 v196, vcc, 0x2000, v194
	s_nop 1
	v_addc_co_u32_e32 v197, vcc, 0, v195, vcc
	v_add_co_u32_e32 v236, vcc, 0x2000, v234
	global_load_dwordx4 v[206:209], v[194:195], off
	global_load_dwordx4 v[202:205], v[196:197], off offset:3072
	v_addc_co_u32_e32 v237, vcc, 0, v235, vcc
	global_store_dwordx4 v[234:235], v[188:191], off
	global_store_dwordx4 v[236:237], v[184:187], off offset:3072
	global_load_dwordx4 v[198:201], v[194:195], off offset:16
	s_nop 0
	global_load_dwordx4 v[194:197], v[196:197], off offset:3088
	s_nop 0
	global_store_dwordx4 v[234:235], v[180:183], off offset:16
	global_store_dwordx4 v[236:237], v[176:179], off offset:3088
.LBB0_1695:
	s_or_b64 exec, exec, s[48:49]
	s_waitcnt vmcnt(0) lgkmcnt(0)
	v_mov_b32_dpp v234, v206 row_ror:1 row_mask:0xf bank_mask:0xf bound_ctrl:1
	v_mov_b32_dpp v206, v206 row_ror:2 row_mask:0xf bank_mask:0xf bound_ctrl:1
	v_mov_b32_dpp v235, v207 row_ror:1 row_mask:0xf bank_mask:0xf bound_ctrl:1
	v_mov_b32_dpp v207, v207 row_ror:2 row_mask:0xf bank_mask:0xf bound_ctrl:1
	v_mov_b32_dpp v206, v188 row_shr:2 row_mask:0xf bank_mask:0xf
	v_mov_b32_dpp v234, v188 row_shr:1 row_mask:0xf bank_mask:0xf
	v_mov_b32_dpp v207, v189 row_shr:2 row_mask:0xf bank_mask:0xf
	v_mov_b32_dpp v235, v189 row_shr:1 row_mask:0xf bank_mask:0xf
	v_pk_fma_f32 v[206:207], v[104:105], v[206:207], v[108:109]
	v_or_b32_e32 v193, s41, v232
	v_pk_fma_f32 v[206:207], v[96:97], v[234:235], v[206:207]
	v_add_u32_e32 v230, s39, v193
	v_pk_fma_f32 v[188:189], v[188:189], v[100:101], v[206:207]
	v_mov_b32_dpp v236, v202 row_ror:1 row_mask:0xf bank_mask:0xf bound_ctrl:1
	v_mul_f32_e32 v193, 0xbfb8aa3b, v188
	v_exp_f32_e32 v193, v193
	v_mul_f32_e32 v206, 0xbfb8aa3b, v189
	v_exp_f32_e32 v207, v206
	v_mov_b32_dpp v202, v202 row_ror:2 row_mask:0xf bank_mask:0xf bound_ctrl:1
	v_add_f32_e32 v193, 1.0, v193
	v_rcp_f32_e32 v206, v193
	v_add_f32_e32 v193, 1.0, v207
	v_mov_b32_dpp v237, v203 row_ror:1 row_mask:0xf bank_mask:0xf bound_ctrl:1
	v_mov_b32_dpp v203, v203 row_ror:2 row_mask:0xf bank_mask:0xf bound_ctrl:1
	v_rcp_f32_e32 v207, v193
	v_mov_b32_dpp v202, v184 row_shr:2 row_mask:0xf bank_mask:0xf
	v_mov_b32_dpp v203, v185 row_shr:2 row_mask:0xf bank_mask:0xf
	v_mov_b32_dpp v236, v184 row_shr:1 row_mask:0xf bank_mask:0xf
	v_mov_b32_dpp v237, v185 row_shr:1 row_mask:0xf bank_mask:0xf
	v_pk_fma_f32 v[202:203], v[80:81], v[202:203], v[92:93]
	v_pk_mul_f32 v[188:189], v[188:189], v[206:207]
	v_pk_fma_f32 v[202:203], v[84:85], v[236:237], v[202:203]
; __device__ __forceinline__ unsigned pk2(float lo, float hi) { const f32x2 v = {lo, hi}; return __builtin_bit_cast(unsigned, __builtin_convertvector(v, bf16x2_t)); }
; __device__ __forceinline__ float silu(float x) { return x * __builtin_amdgcn_rcpf(1.f + __builtin_amdgcn_exp2f(-1.4426950408889634f * x)); }
;     __device__ __forceinline__ void operator()(f32x4 (&acc)[2][2][4][2], const Unit& u, int, int, int, int) const {
;     ...
; #pragma unroll
;         for (int ai = 0; ai < 2; ++ai)
; #pragma unroll
;             for (int m = 0; m < 4; ++m) { const int bseq = (u.pm * BM + ai * HALF + wr * 64 + m * 16) >> 4;
;                 f32x4 sa[2], sg[2];
; #pragma unroll
;                 for (int n = 0; n < 2; ++n) { sa[n] = (f32x4){0.f, 0.f, 0.f, 0.f}; sg[n] = sa[n]; }
;                 if (fr >= 14) { const float* sp = sbuf + (size_t)(bseq * 2 + (fr - 14)) * NUP + f0; float* co = out + O_SCONV + (size_t)(bseq * 2 + (fr - 14)) * NUP + f0;
; #pragma unroll
;                     for (int n = 0; n < 2; ++n) { sa[n] = *(const f32x4*)(sp + 4 * n); sg[n] = *(const f32x4*)(sp + NFF + 4 * n); *(f32x4*)(co + 4 * n) = acc[ai][0][m][n]; *(f32x4*)(co + NFF + 4 * n) = acc[ai][1][m][n]; } }
;                 float r[8];
; #pragma unroll
;                 for (int n = 0; n < 2; ++n)
; #pragma unroll
;                     for (int e = 0; e < 4; ++e) { const float A = acc[ai][0][m][n][e], Gv = acc[ai][1][m][n][e];
;                         const float a1 = dpp_prev(A, sa[n][e], 1), a2 = dpp_prev(A, sa[n][e], 2), g1 = dpp_prev(Gv, sg[n][e], 1), g2 = dpp_prev(Gv, sg[n][e], 2);
;                         const float ca = ba[n][e] + wa0[n][e] * a2 + wa1[n][e] * a1 + wa2[n][e] * A, cg = bg[n][e] + wg0[n][e] * g2 + wg1[n][e] * g1 + wg2[n][e] * Gv;
;                         r[4 * n + e] = silu(ca) * cg; }
;                 u32x4 w; w.x = pk2(r[0], r[1]); w.y = pk2(r[2], r[3]); w.z = pk2(r[4], r[5]); w.w = pk2(r[6], r[7]);
;                 *(u32x4*)(ACT + (size_t)(rowt + ai * HALF + m * 16) * NFF + f0) = w;
;                 __builtin_amdgcn_sched_barrier(0); }
	v_mov_b32_dpp v206, v204 row_ror:1 row_mask:0xf bank_mask:0xf bound_ctrl:1
	v_pk_fma_f32 v[184:185], v[184:185], v[88:89], v[202:203]
	v_mov_b32_dpp v202, v208 row_ror:2 row_mask:0xf bank_mask:0xf bound_ctrl:1
	v_mov_b32_dpp v203, v209 row_ror:2 row_mask:0xf bank_mask:0xf bound_ctrl:1
	v_pk_mul_f32 v[184:185], v[184:185], v[188:189]
	v_mov_b32_dpp v188, v208 row_ror:1 row_mask:0xf bank_mask:0xf bound_ctrl:1
	v_mov_b32_dpp v202, v190 row_shr:2 row_mask:0xf bank_mask:0xf
	v_mov_b32_dpp v189, v209 row_ror:1 row_mask:0xf bank_mask:0xf bound_ctrl:1
	v_mov_b32_dpp v203, v191 row_shr:2 row_mask:0xf bank_mask:0xf
	v_mov_b32_dpp v188, v190 row_shr:1 row_mask:0xf bank_mask:0xf
	v_mov_b32_dpp v189, v191 row_shr:1 row_mask:0xf bank_mask:0xf
	v_pk_fma_f32 v[202:203], v[106:107], v[202:203], v[110:111]
	v_mov_b32_dpp v204, v204 row_ror:2 row_mask:0xf bank_mask:0xf bound_ctrl:1
	v_pk_fma_f32 v[188:189], v[98:99], v[188:189], v[202:203]
	v_mov_b32_dpp v207, v205 row_ror:1 row_mask:0xf bank_mask:0xf bound_ctrl:1
	v_pk_fma_f32 v[188:189], v[190:191], v[102:103], v[188:189]
	v_mov_b32_dpp v205, v205 row_ror:2 row_mask:0xf bank_mask:0xf bound_ctrl:1
	v_mul_f32_e32 v190, 0xbfb8aa3b, v188
	v_mul_f32_e32 v191, 0xbfb8aa3b, v189
	v_exp_f32_e32 v190, v190
	v_exp_f32_e32 v191, v191
	v_mov_b32_dpp v204, v186 row_shr:2 row_mask:0xf bank_mask:0xf
	v_mov_b32_dpp v205, v187 row_shr:2 row_mask:0xf bank_mask:0xf
	v_add_f32_e32 v190, 1.0, v190
	v_add_f32_e32 v191, 1.0, v191
	v_rcp_f32_e32 v190, v190
	v_rcp_f32_e32 v191, v191
	v_mov_b32_dpp v206, v186 row_shr:1 row_mask:0xf bank_mask:0xf
	v_mov_b32_dpp v207, v187 row_shr:1 row_mask:0xf bank_mask:0xf
	v_pk_fma_f32 v[202:203], v[82:83], v[204:205], v[94:95]
	v_pk_mul_f32 v[188:189], v[188:189], v[190:191]
	v_pk_fma_f32 v[202:203], v[86:87], v[206:207], v[202:203]
	v_mov_b32_dpp v190, v198 row_ror:2 row_mask:0xf bank_mask:0xf bound_ctrl:1
	v_pk_fma_f32 v[186:187], v[186:187], v[90:91], v[202:203]
	v_mov_b32_dpp v191, v199 row_ror:2 row_mask:0xf bank_mask:0xf bound_ctrl:1
	v_pk_mul_f32 v[186:187], v[186:187], v[188:189]
	v_mov_b32_dpp v188, v198 row_ror:1 row_mask:0xf bank_mask:0xf bound_ctrl:1
	v_mov_b32_dpp v190, v180 row_shr:2 row_mask:0xf bank_mask:0xf
	v_mov_b32_dpp v189, v199 row_ror:1 row_mask:0xf bank_mask:0xf bound_ctrl:1
	v_mov_b32_dpp v191, v181 row_shr:2 row_mask:0xf bank_mask:0xf
	v_mov_b32_dpp v188, v180 row_shr:1 row_mask:0xf bank_mask:0xf
	v_mov_b32_dpp v189, v181 row_shr:1 row_mask:0xf bank_mask:0xf
	v_pk_fma_f32 v[190:191], v[64:65], v[190:191], v[76:77]
	v_mov_b32_dpp v198, v194 row_ror:1 row_mask:0xf bank_mask:0xf bound_ctrl:1
	v_pk_fma_f32 v[188:189], v[68:69], v[188:189], v[190:191]
	v_mov_b32_dpp v194, v194 row_ror:2 row_mask:0xf bank_mask:0xf bound_ctrl:1
	v_pk_fma_f32 v[180:181], v[180:181], v[72:73], v[188:189]
	v_mov_b32_dpp v199, v195 row_ror:1 row_mask:0xf bank_mask:0xf bound_ctrl:1
	v_mul_f32_e32 v188, 0xbfb8aa3b, v180
	v_mul_f32_e32 v189, 0xbfb8aa3b, v181
	v_exp_f32_e32 v188, v188
	v_exp_f32_e32 v189, v189
	v_mov_b32_dpp v195, v195 row_ror:2 row_mask:0xf bank_mask:0xf bound_ctrl:1
	v_mov_b32_dpp v194, v176 row_shr:2 row_mask:0xf bank_mask:0xf
	v_add_f32_e32 v188, 1.0, v188
	v_add_f32_e32 v189, 1.0, v189
	v_rcp_f32_e32 v188, v188
	v_rcp_f32_e32 v189, v189
	v_mov_b32_dpp v195, v177 row_shr:2 row_mask:0xf bank_mask:0xf
	v_mov_b32_dpp v198, v176 row_shr:1 row_mask:0xf bank_mask:0xf
	v_mov_b32_dpp v199, v177 row_shr:1 row_mask:0xf bank_mask:0xf
	v_pk_fma_f32 v[190:191], v[44:45], v[194:195], v[60:61]
	v_pk_mul_f32 v[180:181], v[180:181], v[188:189]
	v_pk_fma_f32 v[190:191], v[48:49], v[198:199], v[190:191]
	v_mov_b32_dpp v188, v200 row_ror:2 row_mask:0xf bank_mask:0xf bound_ctrl:1
	v_pk_fma_f32 v[176:177], v[176:177], v[52:53], v[190:191]
	v_mov_b32_dpp v189, v201 row_ror:2 row_mask:0xf bank_mask:0xf bound_ctrl:1
	v_pk_mul_f32 v[180:181], v[176:177], v[180:181]
	v_mov_b32_dpp v176, v200 row_ror:1 row_mask:0xf bank_mask:0xf bound_ctrl:1
	v_mov_b32_dpp v188, v182 row_shr:2 row_mask:0xf bank_mask:0xf
	v_mov_b32_dpp v177, v201 row_ror:1 row_mask:0xf bank_mask:0xf bound_ctrl:1
	v_mov_b32_dpp v189, v183 row_shr:2 row_mask:0xf bank_mask:0xf
	v_mov_b32_dpp v176, v182 row_shr:1 row_mask:0xf bank_mask:0xf
	v_mov_b32_dpp v177, v183 row_shr:1 row_mask:0xf bank_mask:0xf
	v_pk_fma_f32 v[188:189], v[66:67], v[188:189], v[78:79]
	v_mov_b32_dpp v194, v196 row_ror:2 row_mask:0xf bank_mask:0xf bound_ctrl:1
	v_pk_fma_f32 v[176:177], v[70:71], v[176:177], v[188:189]
	v_mov_b32_dpp v195, v197 row_ror:2 row_mask:0xf bank_mask:0xf bound_ctrl:1
	v_pk_fma_f32 v[176:177], v[182:183], v[74:75], v[176:177]
	v_mov_b32_dpp v190, v196 row_ror:1 row_mask:0xf bank_mask:0xf bound_ctrl:1
	v_mul_f32_e32 v182, 0xbfb8aa3b, v176
	v_mul_f32_e32 v183, 0xbfb8aa3b, v177
	v_exp_f32_e32 v182, v182
	v_exp_f32_e32 v183, v183
	v_mov_b32_dpp v194, v178 row_shr:2 row_mask:0xf bank_mask:0xf
	v_mov_b32_dpp v191, v197 row_ror:1 row_mask:0xf bank_mask:0xf bound_ctrl:1
	v_add_f32_e32 v182, 1.0, v182
	v_add_f32_e32 v183, 1.0, v183
	v_rcp_f32_e32 v182, v182
	v_rcp_f32_e32 v183, v183
	v_mov_b32_dpp v195, v179 row_shr:2 row_mask:0xf bank_mask:0xf
	v_mov_b32_dpp v190, v178 row_shr:1 row_mask:0xf bank_mask:0xf
	v_mov_b32_dpp v191, v179 row_shr:1 row_mask:0xf bank_mask:0xf
	v_pk_fma_f32 v[188:189], v[46:47], v[194:195], v[62:63]
	v_pk_mul_f32 v[176:177], v[176:177], v[182:183]
	v_pk_fma_f32 v[188:189], v[50:51], v[190:191], v[188:189]
	s_nop 0
	v_pk_fma_f32 v[178:179], v[178:179], v[54:55], v[188:189]
	s_nop 0
	v_pk_mul_f32 v[182:183], v[178:179], v[176:177]
	v_cvt_pk_bf16_f32 v178, v180, v181
	v_mov_b64_e32 v[180:181], s[12:13]
	v_mad_i64_i32 v[180:181], s[48:49], v230, s76, v[180:181]
	v_cvt_pk_bf16_f32 v176, v184, v185
	v_cvt_pk_bf16_f32 v177, v186, v187
	v_cvt_pk_bf16_f32 v179, v182, v183
	v_lshl_add_u64 v[180:181], v[222:223], 1, v[180:181]
	global_store_dwordx4 v[180:181], v[176:179], off
	v_mov_b32_e32 v193, 0
	v_mov_b32_e32 v194, 0
	v_mov_b32_e32 v195, 0
	v_mov_b32_e32 v176, 0
	v_mov_b32_e32 v177, 0
	v_mov_b32_e32 v178, 0
	v_mov_b32_e32 v179, 0
	v_mov_b32_e32 v184, 0
	v_mov_b32_e32 v185, 0
	v_mov_b32_e32 v186, 0
	v_mov_b32_e32 v187, 0
	v_mov_b32_e32 v180, 0
	v_mov_b32_e32 v181, 0
	v_mov_b32_e32 v182, 0
	v_mov_b32_e32 v183, 0
	s_and_saveexec_b64 s[48:49], s[2:3]
	s_cbranch_execz .LBB0_1697
; __device__ __forceinline__ unsigned pk2(float lo, float hi) { const f32x2 v = {lo, hi}; return __builtin_bit_cast(unsigned, __builtin_convertvector(v, bf16x2_t)); }
; __device__ __forceinline__ float silu(float x) { return x * __builtin_amdgcn_rcpf(1.f + __builtin_amdgcn_exp2f(-1.4426950408889634f * x)); }
;     __device__ __forceinline__ void operator()(f32x4 (&acc)[2][2][4][2], const Unit& u, int, int, int, int) const {
;     ...
;                 f32x4 sa[2], sg[2];
; #pragma unroll
;                 for (int n = 0; n < 2; ++n) { sa[n] = (f32x4){0.f, 0.f, 0.f, 0.f}; sg[n] = sa[n]; }
;                 if (fr >= 14) { const float* sp = sbuf + (size_t)(bseq * 2 + (fr - 14)) * NUP + f0; float* co = out + O_SCONV + (size_t)(bseq * 2 + (fr - 14)) * NUP + f0;
; #pragma unroll
;                     for (int n = 0; n < 2; ++n) { sa[n] = *(const f32x4*)(sp + 4 * n); sg[n] = *(const f32x4*)(sp + NFF + 4 * n); *(f32x4*)(co + 4 * n) = acc[ai][0][m][n]; *(f32x4*)(co + NFF + 4 * n) = acc[ai][1][m][n]; } }
;                 float r[8];
; #pragma unroll
;                 for (int n = 0; n < 2; ++n)
; #pragma unroll
;                     for (int e = 0; e < 4; ++e) { const float A = acc[ai][0][m][n][e], Gv = acc[ai][1][m][n][e];
;                         const float a1 = dpp_prev(A, sa[n][e], 1), a2 = dpp_prev(A, sa[n][e], 2), g1 = dpp_prev(Gv, sg[n][e], 1), g2 = dpp_prev(Gv, sg[n][e], 2);
;                         const float ca = ba[n][e] + wa0[n][e] * a2 + wa1[n][e] * a1 + wa2[n][e] * A, cg = bg[n][e] + wg0[n][e] * g2 + wg1[n][e] * g1 + wg2[n][e] * Gv;
;                         r[4 * n + e] = silu(ca) * cg; }
;                 u32x4 w; w.x = pk2(r[0], r[1]); w.y = pk2(r[2], r[3]); w.z = pk2(r[4], r[5]); w.w = pk2(r[6], r[7]);
;                 *(u32x4*)(ACT + (size_t)(rowt + ai * HALF + m * 16) * NFF + f0) = w;
;                 __builtin_amdgcn_sched_barrier(0); }
	s_add_i32 s50, s41, s39
	s_ashr_i32 s50, s50, 3
	v_add3_u32 v180, v232, s50, -12
	v_mov_b64_e32 v[176:177], s[8:9]
	v_mad_i64_i32 v[176:177], s[50:51], v180, s75, v[176:177]
	v_mov_b64_e32 v[178:179], s[30:31]
	v_lshl_add_u64 v[176:177], v[176:177], 0, v[224:225]
	v_mad_i64_i32 v[178:179], s[50:51], v180, s75, v[178:179]
	v_lshl_add_u64 v[188:189], v[178:179], 0, v[224:225]
	v_add_co_u32_e32 v178, vcc, 0x2000, v176
	s_nop 1
	v_addc_co_u32_e32 v179, vcc, 0, v177, vcc
	v_add_co_u32_e32 v190, vcc, 0x2000, v188
	global_load_dwordx4 v[184:187], v[176:177], off
	global_load_dwordx4 v[192:195], v[178:179], off offset:3072
	v_addc_co_u32_e32 v191, vcc, 0, v189, vcc
	global_store_dwordx4 v[188:189], v[172:175], off
	global_store_dwordx4 v[190:191], v[168:171], off offset:3072
	global_load_dwordx4 v[180:183], v[176:177], off offset:16
	s_nop 0
	global_load_dwordx4 v[176:179], v[178:179], off offset:3088
	s_nop 0
	global_store_dwordx4 v[188:189], v[164:167], off offset:16
	global_store_dwordx4 v[190:191], v[160:163], off offset:3088
.LBB0_1697:
	s_or_b64 exec, exec, s[48:49]
	s_waitcnt vmcnt(0) lgkmcnt(0)
	v_mov_b32_dpp v188, v184 row_ror:1 row_mask:0xf bank_mask:0xf bound_ctrl:1
	v_mov_b32_dpp v184, v184 row_ror:2 row_mask:0xf bank_mask:0xf bound_ctrl:1
	v_mov_b32_dpp v189, v185 row_ror:1 row_mask:0xf bank_mask:0xf bound_ctrl:1
	v_mov_b32_dpp v185, v185 row_ror:2 row_mask:0xf bank_mask:0xf bound_ctrl:1
	v_mov_b32_dpp v184, v172 row_shr:2 row_mask:0xf bank_mask:0xf
	v_mov_b32_dpp v188, v172 row_shr:1 row_mask:0xf bank_mask:0xf
	v_mov_b32_dpp v185, v173 row_shr:2 row_mask:0xf bank_mask:0xf
	v_mov_b32_dpp v189, v173 row_shr:1 row_mask:0xf bank_mask:0xf
	v_pk_fma_f32 v[184:185], v[104:105], v[184:185], v[108:109]
	v_mov_b32_dpp v190, v192 row_ror:1 row_mask:0xf bank_mask:0xf bound_ctrl:1
	v_pk_fma_f32 v[184:185], v[96:97], v[188:189], v[184:185]
	v_mov_b32_dpp v192, v192 row_ror:2 row_mask:0xf bank_mask:0xf bound_ctrl:1
	v_pk_fma_f32 v[172:173], v[172:173], v[100:101], v[184:185]
	v_mov_b32_dpp v191, v193 row_ror:1 row_mask:0xf bank_mask:0xf bound_ctrl:1
	v_mul_f32_e32 v184, 0xbfb8aa3b, v172
	v_mul_f32_e32 v185, 0xbfb8aa3b, v173
	v_exp_f32_e32 v184, v184
	v_exp_f32_e32 v185, v185
	v_mov_b32_dpp v193, v193 row_ror:2 row_mask:0xf bank_mask:0xf bound_ctrl:1
	v_mov_b32_dpp v192, v168 row_shr:2 row_mask:0xf bank_mask:0xf
	v_add_f32_e32 v184, 1.0, v184
	v_add_f32_e32 v185, 1.0, v185
	v_rcp_f32_e32 v184, v184
	v_rcp_f32_e32 v185, v185
	v_mov_b32_dpp v193, v169 row_shr:2 row_mask:0xf bank_mask:0xf
	v_mov_b32_dpp v190, v168 row_shr:1 row_mask:0xf bank_mask:0xf
	v_mov_b32_dpp v191, v169 row_shr:1 row_mask:0xf bank_mask:0xf
	v_pk_fma_f32 v[188:189], v[80:81], v[192:193], v[92:93]
	v_pk_mul_f32 v[172:173], v[172:173], v[184:185]
	v_pk_fma_f32 v[188:189], v[84:85], v[190:191], v[188:189]
	v_mov_b32_dpp v184, v186 row_ror:2 row_mask:0xf bank_mask:0xf bound_ctrl:1
	v_pk_fma_f32 v[168:169], v[168:169], v[88:89], v[188:189]
	v_mov_b32_dpp v185, v187 row_ror:2 row_mask:0xf bank_mask:0xf bound_ctrl:1
	v_pk_mul_f32 v[168:169], v[168:169], v[172:173]
	v_mov_b32_dpp v172, v186 row_ror:1 row_mask:0xf bank_mask:0xf bound_ctrl:1
	v_mov_b32_dpp v184, v174 row_shr:2 row_mask:0xf bank_mask:0xf
	v_mov_b32_dpp v173, v187 row_ror:1 row_mask:0xf bank_mask:0xf bound_ctrl:1
	v_mov_b32_dpp v185, v175 row_shr:2 row_mask:0xf bank_mask:0xf
	v_mov_b32_dpp v172, v174 row_shr:1 row_mask:0xf bank_mask:0xf
	v_mov_b32_dpp v173, v175 row_shr:1 row_mask:0xf bank_mask:0xf
	v_pk_fma_f32 v[184:185], v[106:107], v[184:185], v[110:111]
	v_mov_b32_dpp v188, v194 row_ror:2 row_mask:0xf bank_mask:0xf bound_ctrl:1
	v_pk_fma_f32 v[172:173], v[98:99], v[172:173], v[184:185]
	v_mov_b32_dpp v189, v195 row_ror:2 row_mask:0xf bank_mask:0xf bound_ctrl:1
	v_pk_fma_f32 v[172:173], v[174:175], v[102:103], v[172:173]
	v_mov_b32_dpp v186, v194 row_ror:1 row_mask:0xf bank_mask:0xf bound_ctrl:1
	v_mul_f32_e32 v174, 0xbfb8aa3b, v172
	v_mul_f32_e32 v175, 0xbfb8aa3b, v173
	v_exp_f32_e32 v174, v174
	v_exp_f32_e32 v175, v175
	v_mov_b32_dpp v188, v170 row_shr:2 row_mask:0xf bank_mask:0xf
	v_mov_b32_dpp v187, v195 row_ror:1 row_mask:0xf bank_mask:0xf bound_ctrl:1
	v_add_f32_e32 v174, 1.0, v174
	v_add_f32_e32 v175, 1.0, v175
	v_rcp_f32_e32 v174, v174
	v_rcp_f32_e32 v175, v175
	v_mov_b32_dpp v189, v171 row_shr:2 row_mask:0xf bank_mask:0xf
	v_mov_b32_dpp v186, v170 row_shr:1 row_mask:0xf bank_mask:0xf
	v_mov_b32_dpp v187, v171 row_shr:1 row_mask:0xf bank_mask:0xf
	v_pk_fma_f32 v[184:185], v[82:83], v[188:189], v[94:95]
	v_pk_mul_f32 v[172:173], v[172:173], v[174:175]
	v_pk_fma_f32 v[184:185], v[86:87], v[186:187], v[184:185]
	v_mov_b32_dpp v174, v180 row_ror:2 row_mask:0xf bank_mask:0xf bound_ctrl:1
	v_pk_fma_f32 v[170:171], v[170:171], v[90:91], v[184:185]
	v_mov_b32_dpp v175, v181 row_ror:2 row_mask:0xf bank_mask:0xf bound_ctrl:1
	v_pk_mul_f32 v[170:171], v[170:171], v[172:173]
	v_mov_b32_dpp v172, v180 row_ror:1 row_mask:0xf bank_mask:0xf bound_ctrl:1
	v_mov_b32_dpp v174, v164 row_shr:2 row_mask:0xf bank_mask:0xf
	v_mov_b32_dpp v173, v181 row_ror:1 row_mask:0xf bank_mask:0xf bound_ctrl:1
	v_mov_b32_dpp v175, v165 row_shr:2 row_mask:0xf bank_mask:0xf
	v_mov_b32_dpp v172, v164 row_shr:1 row_mask:0xf bank_mask:0xf
	v_mov_b32_dpp v173, v165 row_shr:1 row_mask:0xf bank_mask:0xf
	v_pk_fma_f32 v[174:175], v[64:65], v[174:175], v[76:77]
	v_mov_b32_dpp v180, v176 row_ror:1 row_mask:0xf bank_mask:0xf bound_ctrl:1
	v_pk_fma_f32 v[172:173], v[68:69], v[172:173], v[174:175]
	v_mov_b32_dpp v176, v176 row_ror:2 row_mask:0xf bank_mask:0xf bound_ctrl:1
	v_pk_fma_f32 v[164:165], v[164:165], v[72:73], v[172:173]
; __device__ __forceinline__ unsigned pk2(float lo, float hi) { const f32x2 v = {lo, hi}; return __builtin_bit_cast(unsigned, __builtin_convertvector(v, bf16x2_t)); }
; __device__ __forceinline__ float silu(float x) { return x * __builtin_amdgcn_rcpf(1.f + __builtin_amdgcn_exp2f(-1.4426950408889634f * x)); }
;     __device__ __forceinline__ void operator()(f32x4 (&acc)[2][2][4][2], const Unit& u, int, int, int, int) const {
;     ...
;                 f32x4 sa[2], sg[2];
; #pragma unroll
;                 for (int n = 0; n < 2; ++n) { sa[n] = (f32x4){0.f, 0.f, 0.f, 0.f}; sg[n] = sa[n]; }
;                 if (fr >= 14) { const float* sp = sbuf + (size_t)(bseq * 2 + (fr - 14)) * NUP + f0; float* co = out + O_SCONV + (size_t)(bseq * 2 + (fr - 14)) * NUP + f0;
; #pragma unroll
;                     for (int n = 0; n < 2; ++n) { sa[n] = *(const f32x4*)(sp + 4 * n); sg[n] = *(const f32x4*)(sp + NFF + 4 * n); *(f32x4*)(co + 4 * n) = acc[ai][0][m][n]; *(f32x4*)(co + NFF + 4 * n) = acc[ai][1][m][n]; } }
;                 float r[8];
; #pragma unroll
;                 for (int n = 0; n < 2; ++n)
; #pragma unroll
;                     for (int e = 0; e < 4; ++e) { const float A = acc[ai][0][m][n][e], Gv = acc[ai][1][m][n][e];
;                         const float a1 = dpp_prev(A, sa[n][e], 1), a2 = dpp_prev(A, sa[n][e], 2), g1 = dpp_prev(Gv, sg[n][e], 1), g2 = dpp_prev(Gv, sg[n][e], 2);
;                         const float ca = ba[n][e] + wa0[n][e] * a2 + wa1[n][e] * a1 + wa2[n][e] * A, cg = bg[n][e] + wg0[n][e] * g2 + wg1[n][e] * g1 + wg2[n][e] * Gv;
;                         r[4 * n + e] = silu(ca) * cg; }
;                 u32x4 w; w.x = pk2(r[0], r[1]); w.y = pk2(r[2], r[3]); w.z = pk2(r[4], r[5]); w.w = pk2(r[6], r[7]);
;                 *(u32x4*)(ACT + (size_t)(rowt + ai * HALF + m * 16) * NFF + f0) = w;
;                 __builtin_amdgcn_sched_barrier(0); }
	v_mov_b32_dpp v181, v177 row_ror:1 row_mask:0xf bank_mask:0xf bound_ctrl:1
	v_mul_f32_e32 v172, 0xbfb8aa3b, v164
	v_mul_f32_e32 v173, 0xbfb8aa3b, v165
	v_exp_f32_e32 v172, v172
	v_exp_f32_e32 v173, v173
	v_mov_b32_dpp v177, v177 row_ror:2 row_mask:0xf bank_mask:0xf bound_ctrl:1
	v_mov_b32_dpp v176, v160 row_shr:2 row_mask:0xf bank_mask:0xf
	v_add_f32_e32 v172, 1.0, v172
	v_add_f32_e32 v173, 1.0, v173
	v_rcp_f32_e32 v172, v172
	v_rcp_f32_e32 v173, v173
	v_mov_b32_dpp v177, v161 row_shr:2 row_mask:0xf bank_mask:0xf
	v_mov_b32_dpp v180, v160 row_shr:1 row_mask:0xf bank_mask:0xf
	v_mov_b32_dpp v181, v161 row_shr:1 row_mask:0xf bank_mask:0xf
	v_pk_fma_f32 v[174:175], v[44:45], v[176:177], v[60:61]
	v_pk_mul_f32 v[164:165], v[164:165], v[172:173]
	v_pk_fma_f32 v[174:175], v[48:49], v[180:181], v[174:175]
	v_mov_b32_dpp v172, v182 row_ror:2 row_mask:0xf bank_mask:0xf bound_ctrl:1
	v_pk_fma_f32 v[160:161], v[160:161], v[52:53], v[174:175]
	v_mov_b32_dpp v173, v183 row_ror:2 row_mask:0xf bank_mask:0xf bound_ctrl:1
	v_pk_mul_f32 v[164:165], v[160:161], v[164:165]
	v_mov_b32_dpp v160, v182 row_ror:1 row_mask:0xf bank_mask:0xf bound_ctrl:1
	v_mov_b32_dpp v172, v166 row_shr:2 row_mask:0xf bank_mask:0xf
	v_mov_b32_dpp v161, v183 row_ror:1 row_mask:0xf bank_mask:0xf bound_ctrl:1
	v_mov_b32_dpp v173, v167 row_shr:2 row_mask:0xf bank_mask:0xf
	v_mov_b32_dpp v160, v166 row_shr:1 row_mask:0xf bank_mask:0xf
	v_mov_b32_dpp v161, v167 row_shr:1 row_mask:0xf bank_mask:0xf
	v_pk_fma_f32 v[172:173], v[66:67], v[172:173], v[78:79]
	v_mov_b32_dpp v176, v178 row_ror:2 row_mask:0xf bank_mask:0xf bound_ctrl:1
	v_pk_fma_f32 v[160:161], v[70:71], v[160:161], v[172:173]
	v_mov_b32_dpp v177, v179 row_ror:2 row_mask:0xf bank_mask:0xf bound_ctrl:1
	v_pk_fma_f32 v[160:161], v[166:167], v[74:75], v[160:161]
	v_mov_b32_dpp v174, v178 row_ror:1 row_mask:0xf bank_mask:0xf bound_ctrl:1
	v_mul_f32_e32 v166, 0xbfb8aa3b, v160
	v_mul_f32_e32 v167, 0xbfb8aa3b, v161
	v_exp_f32_e32 v166, v166
	v_exp_f32_e32 v167, v167
	v_mov_b32_dpp v176, v162 row_shr:2 row_mask:0xf bank_mask:0xf
	v_mov_b32_dpp v175, v179 row_ror:1 row_mask:0xf bank_mask:0xf bound_ctrl:1
	v_add_f32_e32 v166, 1.0, v166
	v_add_f32_e32 v167, 1.0, v167
	v_rcp_f32_e32 v166, v166
	v_rcp_f32_e32 v167, v167
	v_mov_b32_dpp v177, v163 row_shr:2 row_mask:0xf bank_mask:0xf
	v_mov_b32_dpp v174, v162 row_shr:1 row_mask:0xf bank_mask:0xf
	v_mov_b32_dpp v175, v163 row_shr:1 row_mask:0xf bank_mask:0xf
	v_pk_fma_f32 v[172:173], v[46:47], v[176:177], v[62:63]
	v_pk_mul_f32 v[160:161], v[160:161], v[166:167]
	v_pk_fma_f32 v[172:173], v[50:51], v[174:175], v[172:173]
	s_nop 0
	v_pk_fma_f32 v[162:163], v[162:163], v[54:55], v[172:173]
	s_nop 0
	v_pk_mul_f32 v[166:167], v[162:163], v[160:161]
	v_cvt_pk_bf16_f32 v162, v164, v165
	v_cvt_pk_bf16_f32 v163, v166, v167
	v_or_b32_e32 v166, 16, v230
	v_mov_b64_e32 v[164:165], s[12:13]
	v_mad_i64_i32 v[164:165], s[48:49], v166, s76, v[164:165]
	v_cvt_pk_bf16_f32 v160, v168, v169
	v_cvt_pk_bf16_f32 v161, v170, v171
	v_lshl_add_u64 v[164:165], v[222:223], 1, v[164:165]
	global_store_dwordx4 v[164:165], v[160:163], off
	s_nop 1
	v_mov_b32_e32 v160, 0
	v_mov_b32_e32 v170, 0
	v_mov_b32_e32 v171, 0
	v_mov_b32_e32 v172, 0
	v_mov_b32_e32 v173, 0
	v_mov_b32_e32 v162, 0
	v_mov_b32_e32 v163, 0
	v_mov_b32_e32 v164, 0
	v_mov_b32_e32 v165, 0
	v_mov_b32_e32 v174, 0
	v_mov_b32_e32 v175, 0
	v_mov_b32_e32 v176, 0
	v_mov_b32_e32 v177, 0
	v_mov_b32_e32 v166, 0
	v_mov_b32_e32 v167, 0
	v_mov_b32_e32 v168, 0
	v_mov_b32_e32 v169, 0
	s_and_saveexec_b64 s[48:49], s[2:3]
	s_cbranch_execz .LBB0_1699
	s_add_i32 s50, s41, s39
	s_ashr_i32 s50, s50, 3
	v_add3_u32 v161, v232, s50, -10
	v_mov_b64_e32 v[162:163], s[8:9]
	v_mad_i64_i32 v[162:163], s[50:51], v161, s75, v[162:163]
	v_mov_b64_e32 v[164:165], s[30:31]
	v_lshl_add_u64 v[162:163], v[162:163], 0, v[224:225]
	v_mad_i64_i32 v[164:165], s[50:51], v161, s75, v[164:165]
	v_lshl_add_u64 v[178:179], v[164:165], 0, v[224:225]
	v_add_co_u32_e32 v164, vcc, 0x2000, v162
	s_nop 1
	v_addc_co_u32_e32 v165, vcc, 0, v163, vcc
	v_add_co_u32_e32 v180, vcc, 0x2000, v178
	global_load_dwordx4 v[174:177], v[162:163], off
	global_load_dwordx4 v[170:173], v[164:165], off offset:3072
	v_addc_co_u32_e32 v181, vcc, 0, v179, vcc
	global_store_dwordx4 v[178:179], v[156:159], off
	global_store_dwordx4 v[180:181], v[152:155], off offset:3072
	global_load_dwordx4 v[166:169], v[162:163], off offset:16
	s_nop 0
	global_load_dwordx4 v[162:165], v[164:165], off offset:3088
	s_nop 0
	global_store_dwordx4 v[178:179], v[148:151], off offset:16
	global_store_dwordx4 v[180:181], v[144:147], off offset:3088
; __device__ __forceinline__ float silu(float x) { return x * __builtin_amdgcn_rcpf(1.f + __builtin_amdgcn_exp2f(-1.4426950408889634f * x)); }
;     __device__ __forceinline__ void operator()(f32x4 (&acc)[2][2][4][2], const Unit& u, int, int, int, int) const {
;     ...
;                 for (int n = 0; n < 2; ++n)
; #pragma unroll
;                     for (int e = 0; e < 4; ++e) { const float A = acc[ai][0][m][n][e], Gv = acc[ai][1][m][n][e];
;                         const float a1 = dpp_prev(A, sa[n][e], 1), a2 = dpp_prev(A, sa[n][e], 2), g1 = dpp_prev(Gv, sg[n][e], 1), g2 = dpp_prev(Gv, sg[n][e], 2);
;                         const float ca = ba[n][e] + wa0[n][e] * a2 + wa1[n][e] * a1 + wa2[n][e] * A, cg = bg[n][e] + wg0[n][e] * g2 + wg1[n][e] * g1 + wg2[n][e] * Gv;
;                         r[4 * n + e] = silu(ca) * cg; }
.LBB0_1699:
	s_or_b64 exec, exec, s[48:49]
	s_waitcnt vmcnt(0) lgkmcnt(0)
	v_mov_b32_dpp v178, v174 row_ror:1 row_mask:0xf bank_mask:0xf bound_ctrl:1
	v_mov_b32_dpp v174, v174 row_ror:2 row_mask:0xf bank_mask:0xf bound_ctrl:1
	v_mov_b32_dpp v179, v175 row_ror:1 row_mask:0xf bank_mask:0xf bound_ctrl:1
	v_mov_b32_dpp v175, v175 row_ror:2 row_mask:0xf bank_mask:0xf bound_ctrl:1
	v_mov_b32_dpp v174, v156 row_shr:2 row_mask:0xf bank_mask:0xf
	v_mov_b32_dpp v178, v156 row_shr:1 row_mask:0xf bank_mask:0xf
	v_mov_b32_dpp v175, v157 row_shr:2 row_mask:0xf bank_mask:0xf
	v_mov_b32_dpp v179, v157 row_shr:1 row_mask:0xf bank_mask:0xf
	v_pk_fma_f32 v[174:175], v[104:105], v[174:175], v[108:109]
	v_mov_b32_dpp v180, v170 row_ror:1 row_mask:0xf bank_mask:0xf bound_ctrl:1
	v_pk_fma_f32 v[174:175], v[96:97], v[178:179], v[174:175]
	v_mov_b32_dpp v170, v170 row_ror:2 row_mask:0xf bank_mask:0xf bound_ctrl:1
	v_pk_fma_f32 v[156:157], v[156:157], v[100:101], v[174:175]
	v_mov_b32_dpp v181, v171 row_ror:1 row_mask:0xf bank_mask:0xf bound_ctrl:1
	v_mul_f32_e32 v161, 0xbfb8aa3b, v156
	v_exp_f32_e32 v161, v161
	v_mul_f32_e32 v174, 0xbfb8aa3b, v157
	v_exp_f32_e32 v175, v174
	v_mov_b32_dpp v171, v171 row_ror:2 row_mask:0xf bank_mask:0xf bound_ctrl:1
	v_add_f32_e32 v161, 1.0, v161
	v_rcp_f32_e32 v174, v161
	v_add_f32_e32 v161, 1.0, v175
	v_rcp_f32_e32 v175, v161
	v_mov_b32_dpp v170, v152 row_shr:2 row_mask:0xf bank_mask:0xf
	v_mov_b32_dpp v171, v153 row_shr:2 row_mask:0xf bank_mask:0xf
	v_mov_b32_dpp v180, v152 row_shr:1 row_mask:0xf bank_mask:0xf
	v_mov_b32_dpp v181, v153 row_shr:1 row_mask:0xf bank_mask:0xf
	v_pk_fma_f32 v[170:171], v[80:81], v[170:171], v[92:93]
	v_pk_mul_f32 v[156:157], v[156:157], v[174:175]
	v_pk_fma_f32 v[170:171], v[84:85], v[180:181], v[170:171]
	v_mov_b32_dpp v174, v172 row_ror:1 row_mask:0xf bank_mask:0xf bound_ctrl:1
	v_pk_fma_f32 v[152:153], v[152:153], v[88:89], v[170:171]
	v_mov_b32_dpp v170, v176 row_ror:2 row_mask:0xf bank_mask:0xf bound_ctrl:1
	v_mov_b32_dpp v171, v177 row_ror:2 row_mask:0xf bank_mask:0xf bound_ctrl:1
	v_pk_mul_f32 v[152:153], v[152:153], v[156:157]
	v_mov_b32_dpp v156, v176 row_ror:1 row_mask:0xf bank_mask:0xf bound_ctrl:1
	v_mov_b32_dpp v170, v158 row_shr:2 row_mask:0xf bank_mask:0xf
	v_mov_b32_dpp v157, v177 row_ror:1 row_mask:0xf bank_mask:0xf bound_ctrl:1
	v_mov_b32_dpp v171, v159 row_shr:2 row_mask:0xf bank_mask:0xf
	v_mov_b32_dpp v156, v158 row_shr:1 row_mask:0xf bank_mask:0xf
	v_mov_b32_dpp v157, v159 row_shr:1 row_mask:0xf bank_mask:0xf
	v_pk_fma_f32 v[170:171], v[106:107], v[170:171], v[110:111]
	v_mov_b32_dpp v172, v172 row_ror:2 row_mask:0xf bank_mask:0xf bound_ctrl:1
	v_pk_fma_f32 v[156:157], v[98:99], v[156:157], v[170:171]
	v_mov_b32_dpp v175, v173 row_ror:1 row_mask:0xf bank_mask:0xf bound_ctrl:1
	v_pk_fma_f32 v[156:157], v[158:159], v[102:103], v[156:157]
	v_mov_b32_dpp v173, v173 row_ror:2 row_mask:0xf bank_mask:0xf bound_ctrl:1
	v_mul_f32_e32 v158, 0xbfb8aa3b, v156
	v_mul_f32_e32 v159, 0xbfb8aa3b, v157
	v_exp_f32_e32 v158, v158
	v_exp_f32_e32 v159, v159
	v_mov_b32_dpp v172, v154 row_shr:2 row_mask:0xf bank_mask:0xf
	v_mov_b32_dpp v173, v155 row_shr:2 row_mask:0xf bank_mask:0xf
	v_add_f32_e32 v158, 1.0, v158
	v_add_f32_e32 v159, 1.0, v159
	v_rcp_f32_e32 v158, v158
	v_rcp_f32_e32 v159, v159
	v_mov_b32_dpp v174, v154 row_shr:1 row_mask:0xf bank_mask:0xf
	v_mov_b32_dpp v175, v155 row_shr:1 row_mask:0xf bank_mask:0xf
	v_pk_fma_f32 v[170:171], v[82:83], v[172:173], v[94:95]
	v_pk_mul_f32 v[156:157], v[156:157], v[158:159]
	v_pk_fma_f32 v[170:171], v[86:87], v[174:175], v[170:171]
	v_mov_b32_dpp v158, v166 row_ror:2 row_mask:0xf bank_mask:0xf bound_ctrl:1
	v_pk_fma_f32 v[154:155], v[154:155], v[90:91], v[170:171]
	v_mov_b32_dpp v159, v167 row_ror:2 row_mask:0xf bank_mask:0xf bound_ctrl:1
	v_pk_mul_f32 v[154:155], v[154:155], v[156:157]
	v_mov_b32_dpp v156, v166 row_ror:1 row_mask:0xf bank_mask:0xf bound_ctrl:1
	v_mov_b32_dpp v158, v148 row_shr:2 row_mask:0xf bank_mask:0xf
	v_mov_b32_dpp v157, v167 row_ror:1 row_mask:0xf bank_mask:0xf bound_ctrl:1
	v_mov_b32_dpp v159, v149 row_shr:2 row_mask:0xf bank_mask:0xf
	v_mov_b32_dpp v156, v148 row_shr:1 row_mask:0xf bank_mask:0xf
	v_mov_b32_dpp v157, v149 row_shr:1 row_mask:0xf bank_mask:0xf
	v_pk_fma_f32 v[158:159], v[64:65], v[158:159], v[76:77]
	v_mov_b32_dpp v166, v162 row_ror:1 row_mask:0xf bank_mask:0xf bound_ctrl:1
	v_pk_fma_f32 v[156:157], v[68:69], v[156:157], v[158:159]
	v_mov_b32_dpp v162, v162 row_ror:2 row_mask:0xf bank_mask:0xf bound_ctrl:1
	v_pk_fma_f32 v[148:149], v[148:149], v[72:73], v[156:157]
	v_mov_b32_dpp v167, v163 row_ror:1 row_mask:0xf bank_mask:0xf bound_ctrl:1
	v_mul_f32_e32 v156, 0xbfb8aa3b, v148
	v_mul_f32_e32 v157, 0xbfb8aa3b, v149
	v_exp_f32_e32 v156, v156
	v_exp_f32_e32 v157, v157
	v_mov_b32_dpp v163, v163 row_ror:2 row_mask:0xf bank_mask:0xf bound_ctrl:1
	v_mov_b32_dpp v162, v144 row_shr:2 row_mask:0xf bank_mask:0xf
	v_add_f32_e32 v156, 1.0, v156
	v_add_f32_e32 v157, 1.0, v157
	v_rcp_f32_e32 v156, v156
	v_rcp_f32_e32 v157, v157
	v_mov_b32_dpp v163, v145 row_shr:2 row_mask:0xf bank_mask:0xf
	v_mov_b32_dpp v166, v144 row_shr:1 row_mask:0xf bank_mask:0xf
	v_mov_b32_dpp v167, v145 row_shr:1 row_mask:0xf bank_mask:0xf
	v_pk_fma_f32 v[158:159], v[44:45], v[162:163], v[60:61]
	v_pk_mul_f32 v[148:149], v[148:149], v[156:157]
	v_pk_fma_f32 v[158:159], v[48:49], v[166:167], v[158:159]
	v_mov_b32_dpp v156, v168 row_ror:2 row_mask:0xf bank_mask:0xf bound_ctrl:1
	v_pk_fma_f32 v[144:145], v[144:145], v[52:53], v[158:159]
	v_mov_b32_dpp v157, v169 row_ror:2 row_mask:0xf bank_mask:0xf bound_ctrl:1
	v_pk_mul_f32 v[148:149], v[144:145], v[148:149]
; __device__ __forceinline__ unsigned pk2(float lo, float hi) { const f32x2 v = {lo, hi}; return __builtin_bit_cast(unsigned, __builtin_convertvector(v, bf16x2_t)); }
; __device__ __forceinline__ float silu(float x) { return x * __builtin_amdgcn_rcpf(1.f + __builtin_amdgcn_exp2f(-1.4426950408889634f * x)); }
;     __device__ __forceinline__ void operator()(f32x4 (&acc)[2][2][4][2], const Unit& u, int, int, int, int) const {
;     ...
;                 f32x4 sa[2], sg[2];
; #pragma unroll
;                 for (int n = 0; n < 2; ++n) { sa[n] = (f32x4){0.f, 0.f, 0.f, 0.f}; sg[n] = sa[n]; }
;                 if (fr >= 14) { const float* sp = sbuf + (size_t)(bseq * 2 + (fr - 14)) * NUP + f0; float* co = out + O_SCONV + (size_t)(bseq * 2 + (fr - 14)) * NUP + f0;
; #pragma unroll
;                     for (int n = 0; n < 2; ++n) { sa[n] = *(const f32x4*)(sp + 4 * n); sg[n] = *(const f32x4*)(sp + NFF + 4 * n); *(f32x4*)(co + 4 * n) = acc[ai][0][m][n]; *(f32x4*)(co + NFF + 4 * n) = acc[ai][1][m][n]; } }
;                 float r[8];
; #pragma unroll
;                 for (int n = 0; n < 2; ++n)
; #pragma unroll
;                     for (int e = 0; e < 4; ++e) { const float A = acc[ai][0][m][n][e], Gv = acc[ai][1][m][n][e];
;                         const float a1 = dpp_prev(A, sa[n][e], 1), a2 = dpp_prev(A, sa[n][e], 2), g1 = dpp_prev(Gv, sg[n][e], 1), g2 = dpp_prev(Gv, sg[n][e], 2);
;                         const float ca = ba[n][e] + wa0[n][e] * a2 + wa1[n][e] * a1 + wa2[n][e] * A, cg = bg[n][e] + wg0[n][e] * g2 + wg1[n][e] * g1 + wg2[n][e] * Gv;
;                         r[4 * n + e] = silu(ca) * cg; }
;                 u32x4 w; w.x = pk2(r[0], r[1]); w.y = pk2(r[2], r[3]); w.z = pk2(r[4], r[5]); w.w = pk2(r[6], r[7]);
;                 *(u32x4*)(ACT + (size_t)(rowt + ai * HALF + m * 16) * NFF + f0) = w;
;                 __builtin_amdgcn_sched_barrier(0); }
	v_mov_b32_dpp v144, v168 row_ror:1 row_mask:0xf bank_mask:0xf bound_ctrl:1
	v_mov_b32_dpp v156, v150 row_shr:2 row_mask:0xf bank_mask:0xf
	v_mov_b32_dpp v145, v169 row_ror:1 row_mask:0xf bank_mask:0xf bound_ctrl:1
	v_mov_b32_dpp v157, v151 row_shr:2 row_mask:0xf bank_mask:0xf
	v_mov_b32_dpp v144, v150 row_shr:1 row_mask:0xf bank_mask:0xf
	v_mov_b32_dpp v145, v151 row_shr:1 row_mask:0xf bank_mask:0xf
	v_pk_fma_f32 v[156:157], v[66:67], v[156:157], v[78:79]
	v_mov_b32_dpp v162, v164 row_ror:2 row_mask:0xf bank_mask:0xf bound_ctrl:1
	v_pk_fma_f32 v[144:145], v[70:71], v[144:145], v[156:157]
	v_mov_b32_dpp v163, v165 row_ror:2 row_mask:0xf bank_mask:0xf bound_ctrl:1
	v_pk_fma_f32 v[144:145], v[150:151], v[74:75], v[144:145]
	v_mov_b32_dpp v158, v164 row_ror:1 row_mask:0xf bank_mask:0xf bound_ctrl:1
	v_mul_f32_e32 v150, 0xbfb8aa3b, v144
	v_mul_f32_e32 v151, 0xbfb8aa3b, v145
	v_exp_f32_e32 v150, v150
	v_exp_f32_e32 v151, v151
	v_mov_b32_dpp v162, v146 row_shr:2 row_mask:0xf bank_mask:0xf
	v_mov_b32_dpp v159, v165 row_ror:1 row_mask:0xf bank_mask:0xf bound_ctrl:1
	v_add_f32_e32 v150, 1.0, v150
	v_add_f32_e32 v151, 1.0, v151
	v_rcp_f32_e32 v150, v150
	v_rcp_f32_e32 v151, v151
	v_mov_b32_dpp v163, v147 row_shr:2 row_mask:0xf bank_mask:0xf
	v_mov_b32_dpp v158, v146 row_shr:1 row_mask:0xf bank_mask:0xf
	v_mov_b32_dpp v159, v147 row_shr:1 row_mask:0xf bank_mask:0xf
	v_pk_fma_f32 v[156:157], v[46:47], v[162:163], v[62:63]
	v_pk_mul_f32 v[144:145], v[144:145], v[150:151]
	v_pk_fma_f32 v[156:157], v[50:51], v[158:159], v[156:157]
	s_nop 0
	v_pk_fma_f32 v[146:147], v[146:147], v[54:55], v[156:157]
	s_nop 0
	v_pk_mul_f32 v[150:151], v[146:147], v[144:145]
	v_cvt_pk_bf16_f32 v146, v148, v149
	v_cvt_pk_bf16_f32 v147, v150, v151
	v_or_b32_e32 v150, 32, v230
	v_mov_b64_e32 v[148:149], s[12:13]
	v_mad_i64_i32 v[148:149], s[48:49], v150, s76, v[148:149]
	v_cvt_pk_bf16_f32 v144, v152, v153
	v_cvt_pk_bf16_f32 v145, v154, v155
	v_lshl_add_u64 v[148:149], v[222:223], 1, v[148:149]
	global_store_dwordx4 v[148:149], v[144:147], off
	v_mov_b32_e32 v161, 0
	v_mov_b32_e32 v162, 0
	v_mov_b32_e32 v163, 0
	v_mov_b32_e32 v144, 0
	v_mov_b32_e32 v145, 0
	v_mov_b32_e32 v146, 0
	v_mov_b32_e32 v147, 0
	v_mov_b32_e32 v152, 0
	v_mov_b32_e32 v153, 0
	v_mov_b32_e32 v154, 0
	v_mov_b32_e32 v155, 0
	v_mov_b32_e32 v148, 0
	v_mov_b32_e32 v149, 0
	v_mov_b32_e32 v150, 0
	v_mov_b32_e32 v151, 0
	s_and_saveexec_b64 s[48:49], s[2:3]
	s_cbranch_execz .LBB0_1701
	s_add_i32 s50, s41, s39
	s_ashr_i32 s50, s50, 3
	v_add3_u32 v148, v232, s50, -8
	v_mov_b64_e32 v[144:145], s[8:9]
	v_mad_i64_i32 v[144:145], s[50:51], v148, s75, v[144:145]
	v_mov_b64_e32 v[146:147], s[30:31]
	v_lshl_add_u64 v[144:145], v[144:145], 0, v[224:225]
	v_mad_i64_i32 v[146:147], s[50:51], v148, s75, v[146:147]
	v_lshl_add_u64 v[156:157], v[146:147], 0, v[224:225]
	v_add_co_u32_e32 v146, vcc, 0x2000, v144
	s_nop 1
	v_addc_co_u32_e32 v147, vcc, 0, v145, vcc
	v_add_co_u32_e32 v158, vcc, 0x2000, v156
	global_load_dwordx4 v[152:155], v[144:145], off
	global_load_dwordx4 v[160:163], v[146:147], off offset:3072
	v_addc_co_u32_e32 v159, vcc, 0, v157, vcc
	global_store_dwordx4 v[156:157], v[140:143], off
	global_store_dwordx4 v[158:159], v[136:139], off offset:3072
	global_load_dwordx4 v[148:151], v[144:145], off offset:16
	s_nop 0
	global_load_dwordx4 v[144:147], v[146:147], off offset:3088
	s_nop 0
	global_store_dwordx4 v[156:157], v[132:135], off offset:16
	global_store_dwordx4 v[158:159], v[128:131], off offset:3088
.LBB0_1701:
	s_or_b64 exec, exec, s[48:49]
	s_waitcnt vmcnt(0) lgkmcnt(0)
	v_mov_b32_dpp v156, v152 row_ror:1 row_mask:0xf bank_mask:0xf bound_ctrl:1
	v_mov_b32_dpp v152, v152 row_ror:2 row_mask:0xf bank_mask:0xf bound_ctrl:1
	v_mov_b32_dpp v157, v153 row_ror:1 row_mask:0xf bank_mask:0xf bound_ctrl:1
	v_mov_b32_dpp v153, v153 row_ror:2 row_mask:0xf bank_mask:0xf bound_ctrl:1
	v_mov_b32_dpp v152, v140 row_shr:2 row_mask:0xf bank_mask:0xf
	v_mov_b32_dpp v156, v140 row_shr:1 row_mask:0xf bank_mask:0xf
	v_mov_b32_dpp v153, v141 row_shr:2 row_mask:0xf bank_mask:0xf
	v_mov_b32_dpp v157, v141 row_shr:1 row_mask:0xf bank_mask:0xf
	v_pk_fma_f32 v[152:153], v[104:105], v[152:153], v[108:109]
	v_mov_b32_dpp v158, v160 row_ror:1 row_mask:0xf bank_mask:0xf bound_ctrl:1
	v_pk_fma_f32 v[152:153], v[96:97], v[156:157], v[152:153]
	v_mov_b32_dpp v160, v160 row_ror:2 row_mask:0xf bank_mask:0xf bound_ctrl:1
	v_pk_fma_f32 v[140:141], v[140:141], v[100:101], v[152:153]
	v_mov_b32_dpp v159, v161 row_ror:1 row_mask:0xf bank_mask:0xf bound_ctrl:1
	v_mul_f32_e32 v152, 0xbfb8aa3b, v140
	v_mul_f32_e32 v153, 0xbfb8aa3b, v141
	v_exp_f32_e32 v152, v152
	v_exp_f32_e32 v153, v153
	v_mov_b32_dpp v161, v161 row_ror:2 row_mask:0xf bank_mask:0xf bound_ctrl:1
	v_mov_b32_dpp v160, v136 row_shr:2 row_mask:0xf bank_mask:0xf
	v_add_f32_e32 v152, 1.0, v152
	v_add_f32_e32 v153, 1.0, v153
	v_rcp_f32_e32 v152, v152
	v_rcp_f32_e32 v153, v153
	v_mov_b32_dpp v161, v137 row_shr:2 row_mask:0xf bank_mask:0xf
	v_mov_b32_dpp v158, v136 row_shr:1 row_mask:0xf bank_mask:0xf
	v_mov_b32_dpp v159, v137 row_shr:1 row_mask:0xf bank_mask:0xf
	v_pk_fma_f32 v[156:157], v[80:81], v[160:161], v[92:93]
	v_pk_mul_f32 v[140:141], v[140:141], v[152:153]
	v_pk_fma_f32 v[156:157], v[84:85], v[158:159], v[156:157]
	v_mov_b32_dpp v152, v154 row_ror:2 row_mask:0xf bank_mask:0xf bound_ctrl:1
	v_pk_fma_f32 v[136:137], v[136:137], v[88:89], v[156:157]
	v_mov_b32_dpp v153, v155 row_ror:2 row_mask:0xf bank_mask:0xf bound_ctrl:1
	v_pk_mul_f32 v[136:137], v[136:137], v[140:141]
	v_mov_b32_dpp v140, v154 row_ror:1 row_mask:0xf bank_mask:0xf bound_ctrl:1
	v_mov_b32_dpp v152, v142 row_shr:2 row_mask:0xf bank_mask:0xf
; __device__ __forceinline__ unsigned pk2(float lo, float hi) { const f32x2 v = {lo, hi}; return __builtin_bit_cast(unsigned, __builtin_convertvector(v, bf16x2_t)); }
; __device__ __forceinline__ float silu(float x) { return x * __builtin_amdgcn_rcpf(1.f + __builtin_amdgcn_exp2f(-1.4426950408889634f * x)); }
;     __device__ __forceinline__ void operator()(f32x4 (&acc)[2][2][4][2], const Unit& u, int, int, int, int) const {
;     ...
;                 f32x4 sa[2], sg[2];
; #pragma unroll
;                 for (int n = 0; n < 2; ++n) { sa[n] = (f32x4){0.f, 0.f, 0.f, 0.f}; sg[n] = sa[n]; }
;                 if (fr >= 14) { const float* sp = sbuf + (size_t)(bseq * 2 + (fr - 14)) * NUP + f0; float* co = out + O_SCONV + (size_t)(bseq * 2 + (fr - 14)) * NUP + f0;
; #pragma unroll
;                     for (int n = 0; n < 2; ++n) { sa[n] = *(const f32x4*)(sp + 4 * n); sg[n] = *(const f32x4*)(sp + NFF + 4 * n); *(f32x4*)(co + 4 * n) = acc[ai][0][m][n]; *(f32x4*)(co + NFF + 4 * n) = acc[ai][1][m][n]; } }
;                 float r[8];
; #pragma unroll
;                 for (int n = 0; n < 2; ++n)
; #pragma unroll
;                     for (int e = 0; e < 4; ++e) { const float A = acc[ai][0][m][n][e], Gv = acc[ai][1][m][n][e];
;                         const float a1 = dpp_prev(A, sa[n][e], 1), a2 = dpp_prev(A, sa[n][e], 2), g1 = dpp_prev(Gv, sg[n][e], 1), g2 = dpp_prev(Gv, sg[n][e], 2);
;                         const float ca = ba[n][e] + wa0[n][e] * a2 + wa1[n][e] * a1 + wa2[n][e] * A, cg = bg[n][e] + wg0[n][e] * g2 + wg1[n][e] * g1 + wg2[n][e] * Gv;
;                         r[4 * n + e] = silu(ca) * cg; }
;                 u32x4 w; w.x = pk2(r[0], r[1]); w.y = pk2(r[2], r[3]); w.z = pk2(r[4], r[5]); w.w = pk2(r[6], r[7]);
;                 *(u32x4*)(ACT + (size_t)(rowt + ai * HALF + m * 16) * NFF + f0) = w;
;                 __builtin_amdgcn_sched_barrier(0); }
	v_mov_b32_dpp v141, v155 row_ror:1 row_mask:0xf bank_mask:0xf bound_ctrl:1
	v_mov_b32_dpp v153, v143 row_shr:2 row_mask:0xf bank_mask:0xf
	v_mov_b32_dpp v140, v142 row_shr:1 row_mask:0xf bank_mask:0xf
	v_mov_b32_dpp v141, v143 row_shr:1 row_mask:0xf bank_mask:0xf
	v_pk_fma_f32 v[152:153], v[106:107], v[152:153], v[110:111]
	v_mov_b32_dpp v156, v162 row_ror:2 row_mask:0xf bank_mask:0xf bound_ctrl:1
	v_pk_fma_f32 v[140:141], v[98:99], v[140:141], v[152:153]
	v_mov_b32_dpp v157, v163 row_ror:2 row_mask:0xf bank_mask:0xf bound_ctrl:1
	v_pk_fma_f32 v[140:141], v[142:143], v[102:103], v[140:141]
	v_mov_b32_dpp v154, v162 row_ror:1 row_mask:0xf bank_mask:0xf bound_ctrl:1
	v_mul_f32_e32 v142, 0xbfb8aa3b, v140
	v_mul_f32_e32 v143, 0xbfb8aa3b, v141
	v_exp_f32_e32 v142, v142
	v_exp_f32_e32 v143, v143
	v_mov_b32_dpp v156, v138 row_shr:2 row_mask:0xf bank_mask:0xf
	v_mov_b32_dpp v155, v163 row_ror:1 row_mask:0xf bank_mask:0xf bound_ctrl:1
	v_add_f32_e32 v142, 1.0, v142
	v_add_f32_e32 v143, 1.0, v143
	v_rcp_f32_e32 v142, v142
	v_rcp_f32_e32 v143, v143
	v_mov_b32_dpp v157, v139 row_shr:2 row_mask:0xf bank_mask:0xf
	v_mov_b32_dpp v154, v138 row_shr:1 row_mask:0xf bank_mask:0xf
	v_mov_b32_dpp v155, v139 row_shr:1 row_mask:0xf bank_mask:0xf
	v_pk_fma_f32 v[152:153], v[82:83], v[156:157], v[94:95]
	v_pk_mul_f32 v[140:141], v[140:141], v[142:143]
	v_pk_fma_f32 v[152:153], v[86:87], v[154:155], v[152:153]
	v_mov_b32_dpp v142, v148 row_ror:2 row_mask:0xf bank_mask:0xf bound_ctrl:1
	v_pk_fma_f32 v[138:139], v[138:139], v[90:91], v[152:153]
	v_mov_b32_dpp v143, v149 row_ror:2 row_mask:0xf bank_mask:0xf bound_ctrl:1
	v_pk_mul_f32 v[138:139], v[138:139], v[140:141]
	v_mov_b32_dpp v140, v148 row_ror:1 row_mask:0xf bank_mask:0xf bound_ctrl:1
	v_mov_b32_dpp v142, v132 row_shr:2 row_mask:0xf bank_mask:0xf
	v_mov_b32_dpp v141, v149 row_ror:1 row_mask:0xf bank_mask:0xf bound_ctrl:1
	v_mov_b32_dpp v143, v133 row_shr:2 row_mask:0xf bank_mask:0xf
	v_mov_b32_dpp v140, v132 row_shr:1 row_mask:0xf bank_mask:0xf
	v_mov_b32_dpp v141, v133 row_shr:1 row_mask:0xf bank_mask:0xf
	v_pk_fma_f32 v[142:143], v[64:65], v[142:143], v[76:77]
	v_mov_b32_dpp v148, v144 row_ror:1 row_mask:0xf bank_mask:0xf bound_ctrl:1
	v_pk_fma_f32 v[140:141], v[68:69], v[140:141], v[142:143]
	v_mov_b32_dpp v144, v144 row_ror:2 row_mask:0xf bank_mask:0xf bound_ctrl:1
	v_pk_fma_f32 v[132:133], v[132:133], v[72:73], v[140:141]
	v_mov_b32_dpp v149, v145 row_ror:1 row_mask:0xf bank_mask:0xf bound_ctrl:1
	v_mul_f32_e32 v140, 0xbfb8aa3b, v132
	v_mul_f32_e32 v141, 0xbfb8aa3b, v133
	v_exp_f32_e32 v140, v140
	v_exp_f32_e32 v141, v141
	v_mov_b32_dpp v145, v145 row_ror:2 row_mask:0xf bank_mask:0xf bound_ctrl:1
	v_mov_b32_dpp v144, v128 row_shr:2 row_mask:0xf bank_mask:0xf
	v_add_f32_e32 v140, 1.0, v140
	v_add_f32_e32 v141, 1.0, v141
	v_rcp_f32_e32 v140, v140
	v_rcp_f32_e32 v141, v141
	v_mov_b32_dpp v145, v129 row_shr:2 row_mask:0xf bank_mask:0xf
	v_mov_b32_dpp v148, v128 row_shr:1 row_mask:0xf bank_mask:0xf
	v_mov_b32_dpp v149, v129 row_shr:1 row_mask:0xf bank_mask:0xf
	v_pk_fma_f32 v[142:143], v[44:45], v[144:145], v[60:61]
	v_pk_mul_f32 v[132:133], v[132:133], v[140:141]
	v_pk_fma_f32 v[142:143], v[48:49], v[148:149], v[142:143]
	v_mov_b32_dpp v140, v150 row_ror:2 row_mask:0xf bank_mask:0xf bound_ctrl:1
	v_pk_fma_f32 v[128:129], v[128:129], v[52:53], v[142:143]
	v_mov_b32_dpp v141, v151 row_ror:2 row_mask:0xf bank_mask:0xf bound_ctrl:1
	v_pk_mul_f32 v[132:133], v[128:129], v[132:133]
	v_mov_b32_dpp v128, v150 row_ror:1 row_mask:0xf bank_mask:0xf bound_ctrl:1
	v_mov_b32_dpp v140, v134 row_shr:2 row_mask:0xf bank_mask:0xf
	v_mov_b32_dpp v129, v151 row_ror:1 row_mask:0xf bank_mask:0xf bound_ctrl:1
	v_mov_b32_dpp v141, v135 row_shr:2 row_mask:0xf bank_mask:0xf
	v_mov_b32_dpp v128, v134 row_shr:1 row_mask:0xf bank_mask:0xf
	v_mov_b32_dpp v129, v135 row_shr:1 row_mask:0xf bank_mask:0xf
	v_pk_fma_f32 v[140:141], v[66:67], v[140:141], v[78:79]
	v_mov_b32_dpp v144, v146 row_ror:2 row_mask:0xf bank_mask:0xf bound_ctrl:1
	v_pk_fma_f32 v[128:129], v[70:71], v[128:129], v[140:141]
	v_mov_b32_dpp v145, v147 row_ror:2 row_mask:0xf bank_mask:0xf bound_ctrl:1
	v_pk_fma_f32 v[128:129], v[134:135], v[74:75], v[128:129]
	v_mov_b32_dpp v142, v146 row_ror:1 row_mask:0xf bank_mask:0xf bound_ctrl:1
	v_mul_f32_e32 v134, 0xbfb8aa3b, v128
	v_mul_f32_e32 v135, 0xbfb8aa3b, v129
	v_exp_f32_e32 v134, v134
	v_exp_f32_e32 v135, v135
	v_mov_b32_dpp v144, v130 row_shr:2 row_mask:0xf bank_mask:0xf
	v_mov_b32_dpp v143, v147 row_ror:1 row_mask:0xf bank_mask:0xf bound_ctrl:1
	v_add_f32_e32 v134, 1.0, v134
	v_add_f32_e32 v135, 1.0, v135
	v_rcp_f32_e32 v134, v134
	v_rcp_f32_e32 v135, v135
	v_mov_b32_dpp v145, v131 row_shr:2 row_mask:0xf bank_mask:0xf
	v_mov_b32_dpp v142, v130 row_shr:1 row_mask:0xf bank_mask:0xf
	v_mov_b32_dpp v143, v131 row_shr:1 row_mask:0xf bank_mask:0xf
	v_pk_fma_f32 v[140:141], v[46:47], v[144:145], v[62:63]
	v_pk_mul_f32 v[128:129], v[128:129], v[134:135]
	v_pk_fma_f32 v[140:141], v[50:51], v[142:143], v[140:141]
	s_nop 0
	v_pk_fma_f32 v[130:131], v[130:131], v[54:55], v[140:141]
	s_nop 0
	v_pk_mul_f32 v[134:135], v[130:131], v[128:129]
	v_cvt_pk_bf16_f32 v130, v132, v133
	v_cvt_pk_bf16_f32 v131, v134, v135
	v_or_b32_e32 v134, 48, v230
	v_mov_b64_e32 v[132:133], s[12:13]
	v_mad_i64_i32 v[132:133], s[48:49], v134, s76, v[132:133]
	v_cvt_pk_bf16_f32 v128, v136, v137
	v_cvt_pk_bf16_f32 v129, v138, v139
	v_lshl_add_u64 v[132:133], v[222:223], 1, v[132:133]
	global_store_dwordx4 v[132:133], v[128:131], off
	s_nop 1
	v_mov_b32_e32 v128, 0
	v_mov_b32_e32 v138, 0
	v_mov_b32_e32 v139, 0
	v_mov_b32_e32 v140, 0
	v_mov_b32_e32 v141, 0
	v_mov_b32_e32 v130, 0
	v_mov_b32_e32 v131, 0
	v_mov_b32_e32 v132, 0
	v_mov_b32_e32 v133, 0
	v_mov_b32_e32 v142, 0
	v_mov_b32_e32 v143, 0
	v_mov_b32_e32 v144, 0
	v_mov_b32_e32 v145, 0
	v_mov_b32_e32 v134, 0
	v_mov_b32_e32 v135, 0
	v_mov_b32_e32 v136, 0
	v_mov_b32_e32 v137, 0
	s_and_saveexec_b64 s[48:49], s[2:3]
	s_cbranch_execz .LBB0_1703
	s_add_i32 s50, s41, s39
	s_addk_i32 s50, 0x80
	s_ashr_i32 s50, s50, 3
	v_add_u32_e32 v129, s50, v231
	v_mov_b64_e32 v[130:131], s[8:9]
	v_mad_i64_i32 v[130:131], s[50:51], v129, s75, v[130:131]
	v_mov_b64_e32 v[132:133], s[30:31]
	v_lshl_add_u64 v[130:131], v[130:131], 0, v[224:225]
	v_mad_i64_i32 v[132:133], s[50:51], v129, s75, v[132:133]
	v_lshl_add_u64 v[146:147], v[132:133], 0, v[224:225]
	v_add_co_u32_e32 v132, vcc, 0x2000, v130
	s_nop 1
	v_addc_co_u32_e32 v133, vcc, 0, v131, vcc
	v_add_co_u32_e32 v148, vcc, 0x2000, v146
	global_load_dwordx4 v[142:145], v[130:131], off
	global_load_dwordx4 v[138:141], v[132:133], off offset:3072
	v_addc_co_u32_e32 v149, vcc, 0, v147, vcc
	global_store_dwordx4 v[146:147], v[124:127], off
	global_store_dwordx4 v[148:149], v[120:123], off offset:3072
	global_load_dwordx4 v[134:137], v[130:131], off offset:16
	s_nop 0
	global_load_dwordx4 v[130:133], v[132:133], off offset:3088
	s_nop 0
	global_store_dwordx4 v[146:147], v[116:119], off offset:16
	global_store_dwordx4 v[148:149], v[112:115], off offset:3088
; __device__ __forceinline__ float silu(float x) { return x * __builtin_amdgcn_rcpf(1.f + __builtin_amdgcn_exp2f(-1.4426950408889634f * x)); }
;     __device__ __forceinline__ void operator()(f32x4 (&acc)[2][2][4][2], const Unit& u, int, int, int, int) const {
;     ...
;                 for (int n = 0; n < 2; ++n)
; #pragma unroll
;                     for (int e = 0; e < 4; ++e) { const float A = acc[ai][0][m][n][e], Gv = acc[ai][1][m][n][e];
;                         const float a1 = dpp_prev(A, sa[n][e], 1), a2 = dpp_prev(A, sa[n][e], 2), g1 = dpp_prev(Gv, sg[n][e], 1), g2 = dpp_prev(Gv, sg[n][e], 2);
;                         const float ca = ba[n][e] + wa0[n][e] * a2 + wa1[n][e] * a1 + wa2[n][e] * A, cg = bg[n][e] + wg0[n][e] * g2 + wg1[n][e] * g1 + wg2[n][e] * Gv;
;                         r[4 * n + e] = silu(ca) * cg; }
.LBB0_1703:
	s_or_b64 exec, exec, s[48:49]
	s_waitcnt vmcnt(0) lgkmcnt(0)
	v_mov_b32_dpp v146, v142 row_ror:1 row_mask:0xf bank_mask:0xf bound_ctrl:1
	v_mov_b32_dpp v142, v142 row_ror:2 row_mask:0xf bank_mask:0xf bound_ctrl:1
	v_mov_b32_dpp v147, v143 row_ror:1 row_mask:0xf bank_mask:0xf bound_ctrl:1
	v_mov_b32_dpp v143, v143 row_ror:2 row_mask:0xf bank_mask:0xf bound_ctrl:1
	v_mov_b32_dpp v142, v124 row_shr:2 row_mask:0xf bank_mask:0xf
	v_mov_b32_dpp v146, v124 row_shr:1 row_mask:0xf bank_mask:0xf
	v_mov_b32_dpp v143, v125 row_shr:2 row_mask:0xf bank_mask:0xf
	v_mov_b32_dpp v147, v125 row_shr:1 row_mask:0xf bank_mask:0xf
	v_pk_fma_f32 v[142:143], v[104:105], v[142:143], v[108:109]
	v_mov_b32_dpp v148, v138 row_ror:1 row_mask:0xf bank_mask:0xf bound_ctrl:1
	v_pk_fma_f32 v[142:143], v[96:97], v[146:147], v[142:143]
	v_mov_b32_dpp v138, v138 row_ror:2 row_mask:0xf bank_mask:0xf bound_ctrl:1
	v_pk_fma_f32 v[124:125], v[124:125], v[100:101], v[142:143]
	v_mov_b32_dpp v149, v139 row_ror:1 row_mask:0xf bank_mask:0xf bound_ctrl:1
	v_mul_f32_e32 v142, 0xbfb8aa3b, v124
	v_mul_f32_e32 v143, 0xbfb8aa3b, v125
	v_exp_f32_e32 v142, v142
	v_exp_f32_e32 v143, v143
	v_mov_b32_dpp v139, v139 row_ror:2 row_mask:0xf bank_mask:0xf bound_ctrl:1
	v_mov_b32_dpp v138, v120 row_shr:2 row_mask:0xf bank_mask:0xf
	v_add_f32_e32 v142, 1.0, v142
	v_add_f32_e32 v143, 1.0, v143
	v_rcp_f32_e32 v142, v142
	v_rcp_f32_e32 v143, v143
	v_mov_b32_dpp v139, v121 row_shr:2 row_mask:0xf bank_mask:0xf
	v_mov_b32_dpp v148, v120 row_shr:1 row_mask:0xf bank_mask:0xf
	v_mov_b32_dpp v149, v121 row_shr:1 row_mask:0xf bank_mask:0xf
	v_pk_fma_f32 v[138:139], v[80:81], v[138:139], v[92:93]
	v_pk_mul_f32 v[124:125], v[124:125], v[142:143]
	v_pk_fma_f32 v[138:139], v[84:85], v[148:149], v[138:139]
	v_mov_b32_dpp v142, v140 row_ror:1 row_mask:0xf bank_mask:0xf bound_ctrl:1
	v_pk_fma_f32 v[120:121], v[120:121], v[88:89], v[138:139]
	v_mov_b32_dpp v138, v144 row_ror:2 row_mask:0xf bank_mask:0xf bound_ctrl:1
	v_mov_b32_dpp v139, v145 row_ror:2 row_mask:0xf bank_mask:0xf bound_ctrl:1
	v_pk_mul_f32 v[120:121], v[120:121], v[124:125]
	v_mov_b32_dpp v124, v144 row_ror:1 row_mask:0xf bank_mask:0xf bound_ctrl:1
	v_mov_b32_dpp v138, v126 row_shr:2 row_mask:0xf bank_mask:0xf
	v_mov_b32_dpp v125, v145 row_ror:1 row_mask:0xf bank_mask:0xf bound_ctrl:1
	v_mov_b32_dpp v139, v127 row_shr:2 row_mask:0xf bank_mask:0xf
	v_mov_b32_dpp v124, v126 row_shr:1 row_mask:0xf bank_mask:0xf
	v_mov_b32_dpp v125, v127 row_shr:1 row_mask:0xf bank_mask:0xf
	v_pk_fma_f32 v[138:139], v[106:107], v[138:139], v[110:111]
	v_mov_b32_dpp v140, v140 row_ror:2 row_mask:0xf bank_mask:0xf bound_ctrl:1
	v_pk_fma_f32 v[124:125], v[98:99], v[124:125], v[138:139]
	v_mov_b32_dpp v143, v141 row_ror:1 row_mask:0xf bank_mask:0xf bound_ctrl:1
	v_pk_fma_f32 v[124:125], v[126:127], v[102:103], v[124:125]
	v_mov_b32_dpp v141, v141 row_ror:2 row_mask:0xf bank_mask:0xf bound_ctrl:1
	v_mul_f32_e32 v126, 0xbfb8aa3b, v124
	v_mul_f32_e32 v127, 0xbfb8aa3b, v125
	v_exp_f32_e32 v126, v126
	v_exp_f32_e32 v127, v127
	v_mov_b32_dpp v140, v122 row_shr:2 row_mask:0xf bank_mask:0xf
	v_mov_b32_dpp v141, v123 row_shr:2 row_mask:0xf bank_mask:0xf
	v_add_f32_e32 v126, 1.0, v126
	v_add_f32_e32 v127, 1.0, v127
	v_rcp_f32_e32 v126, v126
	v_rcp_f32_e32 v127, v127
	v_mov_b32_dpp v142, v122 row_shr:1 row_mask:0xf bank_mask:0xf
	v_mov_b32_dpp v143, v123 row_shr:1 row_mask:0xf bank_mask:0xf
	v_pk_fma_f32 v[138:139], v[82:83], v[140:141], v[94:95]
	v_pk_mul_f32 v[124:125], v[124:125], v[126:127]
	v_pk_fma_f32 v[138:139], v[86:87], v[142:143], v[138:139]
	v_mov_b32_dpp v126, v134 row_ror:2 row_mask:0xf bank_mask:0xf bound_ctrl:1
	v_pk_fma_f32 v[122:123], v[122:123], v[90:91], v[138:139]
	v_mov_b32_dpp v127, v135 row_ror:2 row_mask:0xf bank_mask:0xf bound_ctrl:1
	v_pk_mul_f32 v[122:123], v[122:123], v[124:125]
	v_mov_b32_dpp v124, v134 row_ror:1 row_mask:0xf bank_mask:0xf bound_ctrl:1
	v_mov_b32_dpp v126, v116 row_shr:2 row_mask:0xf bank_mask:0xf
	v_mov_b32_dpp v125, v135 row_ror:1 row_mask:0xf bank_mask:0xf bound_ctrl:1
	v_mov_b32_dpp v127, v117 row_shr:2 row_mask:0xf bank_mask:0xf
	v_mov_b32_dpp v124, v116 row_shr:1 row_mask:0xf bank_mask:0xf
	v_mov_b32_dpp v125, v117 row_shr:1 row_mask:0xf bank_mask:0xf
	v_pk_fma_f32 v[126:127], v[64:65], v[126:127], v[76:77]
	v_mov_b32_dpp v134, v130 row_ror:1 row_mask:0xf bank_mask:0xf bound_ctrl:1
	v_pk_fma_f32 v[124:125], v[68:69], v[124:125], v[126:127]
	v_mov_b32_dpp v130, v130 row_ror:2 row_mask:0xf bank_mask:0xf bound_ctrl:1
	v_pk_fma_f32 v[116:117], v[116:117], v[72:73], v[124:125]
	v_mov_b32_dpp v135, v131 row_ror:1 row_mask:0xf bank_mask:0xf bound_ctrl:1
	v_mul_f32_e32 v124, 0xbfb8aa3b, v116
	v_mul_f32_e32 v125, 0xbfb8aa3b, v117
	v_exp_f32_e32 v124, v124
	v_exp_f32_e32 v125, v125
	v_mov_b32_dpp v131, v131 row_ror:2 row_mask:0xf bank_mask:0xf bound_ctrl:1
	v_mov_b32_dpp v130, v112 row_shr:2 row_mask:0xf bank_mask:0xf
	v_add_f32_e32 v124, 1.0, v124
	v_add_f32_e32 v125, 1.0, v125
	v_rcp_f32_e32 v124, v124
	v_rcp_f32_e32 v125, v125
	v_mov_b32_dpp v131, v113 row_shr:2 row_mask:0xf bank_mask:0xf
	v_mov_b32_dpp v134, v112 row_shr:1 row_mask:0xf bank_mask:0xf
	v_mov_b32_dpp v135, v113 row_shr:1 row_mask:0xf bank_mask:0xf
	v_pk_fma_f32 v[126:127], v[44:45], v[130:131], v[60:61]
	v_pk_mul_f32 v[116:117], v[116:117], v[124:125]
	v_pk_fma_f32 v[126:127], v[48:49], v[134:135], v[126:127]
	v_mov_b32_dpp v124, v136 row_ror:2 row_mask:0xf bank_mask:0xf bound_ctrl:1
	v_pk_fma_f32 v[112:113], v[112:113], v[52:53], v[126:127]
	v_mov_b32_dpp v125, v137 row_ror:2 row_mask:0xf bank_mask:0xf bound_ctrl:1
	v_pk_mul_f32 v[116:117], v[112:113], v[116:117]
; __device__ __forceinline__ unsigned pk2(float lo, float hi) { const f32x2 v = {lo, hi}; return __builtin_bit_cast(unsigned, __builtin_convertvector(v, bf16x2_t)); }
; __device__ __forceinline__ float silu(float x) { return x * __builtin_amdgcn_rcpf(1.f + __builtin_amdgcn_exp2f(-1.4426950408889634f * x)); }
;     __device__ __forceinline__ void operator()(f32x4 (&acc)[2][2][4][2], const Unit& u, int, int, int, int) const {
;     ...
;                 f32x4 sa[2], sg[2];
; #pragma unroll
;                 for (int n = 0; n < 2; ++n) { sa[n] = (f32x4){0.f, 0.f, 0.f, 0.f}; sg[n] = sa[n]; }
;                 if (fr >= 14) { const float* sp = sbuf + (size_t)(bseq * 2 + (fr - 14)) * NUP + f0; float* co = out + O_SCONV + (size_t)(bseq * 2 + (fr - 14)) * NUP + f0;
; #pragma unroll
;                     for (int n = 0; n < 2; ++n) { sa[n] = *(const f32x4*)(sp + 4 * n); sg[n] = *(const f32x4*)(sp + NFF + 4 * n); *(f32x4*)(co + 4 * n) = acc[ai][0][m][n]; *(f32x4*)(co + NFF + 4 * n) = acc[ai][1][m][n]; } }
;                 float r[8];
; #pragma unroll
;                 for (int n = 0; n < 2; ++n)
; #pragma unroll
;                     for (int e = 0; e < 4; ++e) { const float A = acc[ai][0][m][n][e], Gv = acc[ai][1][m][n][e];
;                         const float a1 = dpp_prev(A, sa[n][e], 1), a2 = dpp_prev(A, sa[n][e], 2), g1 = dpp_prev(Gv, sg[n][e], 1), g2 = dpp_prev(Gv, sg[n][e], 2);
;                         const float ca = ba[n][e] + wa0[n][e] * a2 + wa1[n][e] * a1 + wa2[n][e] * A, cg = bg[n][e] + wg0[n][e] * g2 + wg1[n][e] * g1 + wg2[n][e] * Gv;
;                         r[4 * n + e] = silu(ca) * cg; }
;                 u32x4 w; w.x = pk2(r[0], r[1]); w.y = pk2(r[2], r[3]); w.z = pk2(r[4], r[5]); w.w = pk2(r[6], r[7]);
;                 *(u32x4*)(ACT + (size_t)(rowt + ai * HALF + m * 16) * NFF + f0) = w;
;                 __builtin_amdgcn_sched_barrier(0); }
	v_mov_b32_dpp v112, v136 row_ror:1 row_mask:0xf bank_mask:0xf bound_ctrl:1
	v_mov_b32_dpp v124, v118 row_shr:2 row_mask:0xf bank_mask:0xf
	v_mov_b32_dpp v113, v137 row_ror:1 row_mask:0xf bank_mask:0xf bound_ctrl:1
	v_mov_b32_dpp v125, v119 row_shr:2 row_mask:0xf bank_mask:0xf
	v_mov_b32_dpp v112, v118 row_shr:1 row_mask:0xf bank_mask:0xf
	v_mov_b32_dpp v113, v119 row_shr:1 row_mask:0xf bank_mask:0xf
	v_pk_fma_f32 v[124:125], v[66:67], v[124:125], v[78:79]
	v_mov_b32_dpp v130, v132 row_ror:2 row_mask:0xf bank_mask:0xf bound_ctrl:1
	v_pk_fma_f32 v[112:113], v[70:71], v[112:113], v[124:125]
	v_mov_b32_dpp v131, v133 row_ror:2 row_mask:0xf bank_mask:0xf bound_ctrl:1
	v_pk_fma_f32 v[112:113], v[118:119], v[74:75], v[112:113]
	v_mov_b32_dpp v126, v132 row_ror:1 row_mask:0xf bank_mask:0xf bound_ctrl:1
	v_mul_f32_e32 v118, 0xbfb8aa3b, v112
	v_mul_f32_e32 v119, 0xbfb8aa3b, v113
	v_exp_f32_e32 v118, v118
	v_exp_f32_e32 v119, v119
	v_mov_b32_dpp v130, v114 row_shr:2 row_mask:0xf bank_mask:0xf
	v_mov_b32_dpp v127, v133 row_ror:1 row_mask:0xf bank_mask:0xf bound_ctrl:1
	v_add_f32_e32 v118, 1.0, v118
	v_add_f32_e32 v119, 1.0, v119
	v_rcp_f32_e32 v118, v118
	v_rcp_f32_e32 v119, v119
	v_mov_b32_dpp v131, v115 row_shr:2 row_mask:0xf bank_mask:0xf
	v_mov_b32_dpp v126, v114 row_shr:1 row_mask:0xf bank_mask:0xf
	v_mov_b32_dpp v127, v115 row_shr:1 row_mask:0xf bank_mask:0xf
	v_pk_fma_f32 v[124:125], v[46:47], v[130:131], v[62:63]
	v_pk_mul_f32 v[112:113], v[112:113], v[118:119]
	v_pk_fma_f32 v[124:125], v[50:51], v[126:127], v[124:125]
	v_add_u32_e32 v129, 0x80, v230
	v_pk_fma_f32 v[114:115], v[114:115], v[54:55], v[124:125]
	s_nop 0
	v_pk_mul_f32 v[118:119], v[114:115], v[112:113]
	v_cvt_pk_bf16_f32 v114, v116, v117
	v_mov_b64_e32 v[116:117], s[12:13]
	v_mad_i64_i32 v[116:117], s[48:49], v129, s76, v[116:117]
	v_cvt_pk_bf16_f32 v112, v120, v121
	v_cvt_pk_bf16_f32 v113, v122, v123
	v_cvt_pk_bf16_f32 v115, v118, v119
	v_lshl_add_u64 v[116:117], v[222:223], 1, v[116:117]
	global_store_dwordx4 v[116:117], v[112:115], off
	v_mov_b32_e32 v129, 0
	v_mov_b32_e32 v130, 0
	v_mov_b32_e32 v131, 0
	v_mov_b32_e32 v112, 0
	v_mov_b32_e32 v113, 0
	v_mov_b32_e32 v114, 0
	v_mov_b32_e32 v115, 0
	v_mov_b32_e32 v120, 0
	v_mov_b32_e32 v121, 0
	v_mov_b32_e32 v122, 0
	v_mov_b32_e32 v123, 0
	v_mov_b32_e32 v116, 0
	v_mov_b32_e32 v117, 0
	v_mov_b32_e32 v118, 0
	v_mov_b32_e32 v119, 0
	s_and_saveexec_b64 s[48:49], s[2:3]
	s_cbranch_execz .LBB0_1705
	s_add_i32 s50, s41, s39
	s_addk_i32 s50, 0x90
	s_ashr_i32 s50, s50, 3
	v_add_u32_e32 v116, s50, v231
	v_mov_b64_e32 v[112:113], s[8:9]
	v_mad_i64_i32 v[112:113], s[50:51], v116, s75, v[112:113]
	v_mov_b64_e32 v[114:115], s[30:31]
	v_lshl_add_u64 v[112:113], v[112:113], 0, v[224:225]
	v_mad_i64_i32 v[114:115], s[50:51], v116, s75, v[114:115]
	v_lshl_add_u64 v[124:125], v[114:115], 0, v[224:225]
	v_add_co_u32_e32 v114, vcc, 0x2000, v112
	s_nop 1
	v_addc_co_u32_e32 v115, vcc, 0, v113, vcc
	v_add_co_u32_e32 v126, vcc, 0x2000, v124
	global_load_dwordx4 v[120:123], v[112:113], off
	global_load_dwordx4 v[128:131], v[114:115], off offset:3072
	v_addc_co_u32_e32 v127, vcc, 0, v125, vcc
	global_store_dwordx4 v[124:125], v[56:59], off
	global_store_dwordx4 v[126:127], v[40:43], off offset:3072
	global_load_dwordx4 v[116:119], v[112:113], off offset:16
	s_nop 0
	global_load_dwordx4 v[112:115], v[114:115], off offset:3088
	s_nop 0
	global_store_dwordx4 v[124:125], v[36:39], off offset:16
	global_store_dwordx4 v[126:127], v[32:35], off offset:3088
.LBB0_1705:
	s_or_b64 exec, exec, s[48:49]
	s_waitcnt vmcnt(0) lgkmcnt(0)
	v_mov_b32_dpp v124, v120 row_ror:1 row_mask:0xf bank_mask:0xf bound_ctrl:1
	v_mov_b32_dpp v120, v120 row_ror:2 row_mask:0xf bank_mask:0xf bound_ctrl:1
	v_mov_b32_dpp v125, v121 row_ror:1 row_mask:0xf bank_mask:0xf bound_ctrl:1
	v_mov_b32_dpp v121, v121 row_ror:2 row_mask:0xf bank_mask:0xf bound_ctrl:1
	v_mov_b32_dpp v120, v56 row_shr:2 row_mask:0xf bank_mask:0xf
	v_mov_b32_dpp v124, v56 row_shr:1 row_mask:0xf bank_mask:0xf
	v_mov_b32_dpp v121, v57 row_shr:2 row_mask:0xf bank_mask:0xf
	v_mov_b32_dpp v125, v57 row_shr:1 row_mask:0xf bank_mask:0xf
	v_pk_fma_f32 v[120:121], v[104:105], v[120:121], v[108:109]
	v_mov_b32_dpp v126, v128 row_ror:1 row_mask:0xf bank_mask:0xf bound_ctrl:1
	v_pk_fma_f32 v[120:121], v[96:97], v[124:125], v[120:121]
	v_mov_b32_dpp v128, v128 row_ror:2 row_mask:0xf bank_mask:0xf bound_ctrl:1
	v_pk_fma_f32 v[56:57], v[56:57], v[100:101], v[120:121]
	v_mov_b32_dpp v127, v129 row_ror:1 row_mask:0xf bank_mask:0xf bound_ctrl:1
	v_mul_f32_e32 v120, 0xbfb8aa3b, v56
	v_mul_f32_e32 v121, 0xbfb8aa3b, v57
	v_exp_f32_e32 v120, v120
	v_exp_f32_e32 v121, v121
	v_mov_b32_dpp v129, v129 row_ror:2 row_mask:0xf bank_mask:0xf bound_ctrl:1
	v_mov_b32_dpp v128, v40 row_shr:2 row_mask:0xf bank_mask:0xf
	v_add_f32_e32 v120, 1.0, v120
	v_add_f32_e32 v121, 1.0, v121
	v_rcp_f32_e32 v120, v120
	v_rcp_f32_e32 v121, v121
	v_mov_b32_dpp v129, v41 row_shr:2 row_mask:0xf bank_mask:0xf
	v_mov_b32_dpp v126, v40 row_shr:1 row_mask:0xf bank_mask:0xf
	v_mov_b32_dpp v127, v41 row_shr:1 row_mask:0xf bank_mask:0xf
	v_pk_fma_f32 v[124:125], v[80:81], v[128:129], v[92:93]
	v_pk_mul_f32 v[56:57], v[56:57], v[120:121]
	v_pk_fma_f32 v[124:125], v[84:85], v[126:127], v[124:125]
	v_mov_b32_dpp v120, v122 row_ror:2 row_mask:0xf bank_mask:0xf bound_ctrl:1
	v_pk_fma_f32 v[40:41], v[40:41], v[88:89], v[124:125]
	v_mov_b32_dpp v121, v123 row_ror:2 row_mask:0xf bank_mask:0xf bound_ctrl:1
	v_pk_mul_f32 v[40:41], v[40:41], v[56:57]
	v_mov_b32_dpp v56, v122 row_ror:1 row_mask:0xf bank_mask:0xf bound_ctrl:1
	v_mov_b32_dpp v120, v58 row_shr:2 row_mask:0xf bank_mask:0xf
; __device__ __forceinline__ unsigned pk2(float lo, float hi) { const f32x2 v = {lo, hi}; return __builtin_bit_cast(unsigned, __builtin_convertvector(v, bf16x2_t)); }
; __device__ __forceinline__ float silu(float x) { return x * __builtin_amdgcn_rcpf(1.f + __builtin_amdgcn_exp2f(-1.4426950408889634f * x)); }
;     __device__ __forceinline__ void operator()(f32x4 (&acc)[2][2][4][2], const Unit& u, int, int, int, int) const {
;     ...
;                 f32x4 sa[2], sg[2];
; #pragma unroll
;                 for (int n = 0; n < 2; ++n) { sa[n] = (f32x4){0.f, 0.f, 0.f, 0.f}; sg[n] = sa[n]; }
;                 if (fr >= 14) { const float* sp = sbuf + (size_t)(bseq * 2 + (fr - 14)) * NUP + f0; float* co = out + O_SCONV + (size_t)(bseq * 2 + (fr - 14)) * NUP + f0;
; #pragma unroll
;                     for (int n = 0; n < 2; ++n) { sa[n] = *(const f32x4*)(sp + 4 * n); sg[n] = *(const f32x4*)(sp + NFF + 4 * n); *(f32x4*)(co + 4 * n) = acc[ai][0][m][n]; *(f32x4*)(co + NFF + 4 * n) = acc[ai][1][m][n]; } }
;                 float r[8];
; #pragma unroll
;                 for (int n = 0; n < 2; ++n)
; #pragma unroll
;                     for (int e = 0; e < 4; ++e) { const float A = acc[ai][0][m][n][e], Gv = acc[ai][1][m][n][e];
;                         const float a1 = dpp_prev(A, sa[n][e], 1), a2 = dpp_prev(A, sa[n][e], 2), g1 = dpp_prev(Gv, sg[n][e], 1), g2 = dpp_prev(Gv, sg[n][e], 2);
;                         const float ca = ba[n][e] + wa0[n][e] * a2 + wa1[n][e] * a1 + wa2[n][e] * A, cg = bg[n][e] + wg0[n][e] * g2 + wg1[n][e] * g1 + wg2[n][e] * Gv;
;                         r[4 * n + e] = silu(ca) * cg; }
;                 u32x4 w; w.x = pk2(r[0], r[1]); w.y = pk2(r[2], r[3]); w.z = pk2(r[4], r[5]); w.w = pk2(r[6], r[7]);
;                 *(u32x4*)(ACT + (size_t)(rowt + ai * HALF + m * 16) * NFF + f0) = w;
;                 __builtin_amdgcn_sched_barrier(0); }
	v_mov_b32_dpp v57, v123 row_ror:1 row_mask:0xf bank_mask:0xf bound_ctrl:1
	v_mov_b32_dpp v121, v59 row_shr:2 row_mask:0xf bank_mask:0xf
	v_mov_b32_dpp v56, v58 row_shr:1 row_mask:0xf bank_mask:0xf
	v_mov_b32_dpp v57, v59 row_shr:1 row_mask:0xf bank_mask:0xf
	v_pk_fma_f32 v[120:121], v[106:107], v[120:121], v[110:111]
	v_mov_b32_dpp v124, v130 row_ror:2 row_mask:0xf bank_mask:0xf bound_ctrl:1
	v_pk_fma_f32 v[56:57], v[98:99], v[56:57], v[120:121]
	v_mov_b32_dpp v125, v131 row_ror:2 row_mask:0xf bank_mask:0xf bound_ctrl:1
	v_pk_fma_f32 v[56:57], v[58:59], v[102:103], v[56:57]
	v_mov_b32_dpp v122, v130 row_ror:1 row_mask:0xf bank_mask:0xf bound_ctrl:1
	v_mul_f32_e32 v58, 0xbfb8aa3b, v56
	v_mul_f32_e32 v59, 0xbfb8aa3b, v57
	v_exp_f32_e32 v58, v58
	v_exp_f32_e32 v59, v59
	v_mov_b32_dpp v124, v42 row_shr:2 row_mask:0xf bank_mask:0xf
	v_mov_b32_dpp v123, v131 row_ror:1 row_mask:0xf bank_mask:0xf bound_ctrl:1
	v_add_f32_e32 v58, 1.0, v58
	v_add_f32_e32 v59, 1.0, v59
	v_rcp_f32_e32 v58, v58
	v_rcp_f32_e32 v59, v59
	v_mov_b32_dpp v125, v43 row_shr:2 row_mask:0xf bank_mask:0xf
	v_mov_b32_dpp v122, v42 row_shr:1 row_mask:0xf bank_mask:0xf
	v_mov_b32_dpp v123, v43 row_shr:1 row_mask:0xf bank_mask:0xf
	v_pk_fma_f32 v[120:121], v[82:83], v[124:125], v[94:95]
	v_pk_mul_f32 v[56:57], v[56:57], v[58:59]
	v_pk_fma_f32 v[120:121], v[86:87], v[122:123], v[120:121]
	v_mov_b32_dpp v58, v116 row_ror:2 row_mask:0xf bank_mask:0xf bound_ctrl:1
	v_pk_fma_f32 v[42:43], v[42:43], v[90:91], v[120:121]
	v_mov_b32_dpp v59, v117 row_ror:2 row_mask:0xf bank_mask:0xf bound_ctrl:1
	v_pk_mul_f32 v[42:43], v[42:43], v[56:57]
	v_mov_b32_dpp v56, v116 row_ror:1 row_mask:0xf bank_mask:0xf bound_ctrl:1
	v_mov_b32_dpp v58, v36 row_shr:2 row_mask:0xf bank_mask:0xf
	v_mov_b32_dpp v57, v117 row_ror:1 row_mask:0xf bank_mask:0xf bound_ctrl:1
	v_mov_b32_dpp v59, v37 row_shr:2 row_mask:0xf bank_mask:0xf
	v_mov_b32_dpp v56, v36 row_shr:1 row_mask:0xf bank_mask:0xf
	v_mov_b32_dpp v57, v37 row_shr:1 row_mask:0xf bank_mask:0xf
	v_pk_fma_f32 v[58:59], v[64:65], v[58:59], v[76:77]
	v_mov_b32_dpp v116, v112 row_ror:1 row_mask:0xf bank_mask:0xf bound_ctrl:1
	v_pk_fma_f32 v[56:57], v[68:69], v[56:57], v[58:59]
	v_mov_b32_dpp v112, v112 row_ror:2 row_mask:0xf bank_mask:0xf bound_ctrl:1
	v_pk_fma_f32 v[36:37], v[36:37], v[72:73], v[56:57]
	v_mov_b32_dpp v117, v113 row_ror:1 row_mask:0xf bank_mask:0xf bound_ctrl:1
	v_mul_f32_e32 v56, 0xbfb8aa3b, v36
	v_mul_f32_e32 v57, 0xbfb8aa3b, v37
	v_exp_f32_e32 v56, v56
	v_exp_f32_e32 v57, v57
	v_mov_b32_dpp v113, v113 row_ror:2 row_mask:0xf bank_mask:0xf bound_ctrl:1
	v_mov_b32_dpp v112, v32 row_shr:2 row_mask:0xf bank_mask:0xf
	v_add_f32_e32 v56, 1.0, v56
	v_add_f32_e32 v57, 1.0, v57
	v_rcp_f32_e32 v56, v56
	v_rcp_f32_e32 v57, v57
	v_mov_b32_dpp v113, v33 row_shr:2 row_mask:0xf bank_mask:0xf
	v_mov_b32_dpp v116, v32 row_shr:1 row_mask:0xf bank_mask:0xf
	v_mov_b32_dpp v117, v33 row_shr:1 row_mask:0xf bank_mask:0xf
	v_pk_fma_f32 v[58:59], v[44:45], v[112:113], v[60:61]
	v_pk_mul_f32 v[36:37], v[36:37], v[56:57]
	v_pk_fma_f32 v[58:59], v[48:49], v[116:117], v[58:59]
	v_mov_b32_dpp v56, v118 row_ror:2 row_mask:0xf bank_mask:0xf bound_ctrl:1
	v_pk_fma_f32 v[32:33], v[32:33], v[52:53], v[58:59]
	v_mov_b32_dpp v57, v119 row_ror:2 row_mask:0xf bank_mask:0xf bound_ctrl:1
	v_pk_mul_f32 v[36:37], v[32:33], v[36:37]
	v_mov_b32_dpp v32, v118 row_ror:1 row_mask:0xf bank_mask:0xf bound_ctrl:1
	v_mov_b32_dpp v56, v38 row_shr:2 row_mask:0xf bank_mask:0xf
	v_mov_b32_dpp v33, v119 row_ror:1 row_mask:0xf bank_mask:0xf bound_ctrl:1
	v_mov_b32_dpp v57, v39 row_shr:2 row_mask:0xf bank_mask:0xf
	v_mov_b32_dpp v32, v38 row_shr:1 row_mask:0xf bank_mask:0xf
	v_mov_b32_dpp v33, v39 row_shr:1 row_mask:0xf bank_mask:0xf
	v_pk_fma_f32 v[56:57], v[66:67], v[56:57], v[78:79]
	v_mov_b32_dpp v112, v114 row_ror:2 row_mask:0xf bank_mask:0xf bound_ctrl:1
	v_pk_fma_f32 v[32:33], v[70:71], v[32:33], v[56:57]
	v_mov_b32_dpp v113, v115 row_ror:2 row_mask:0xf bank_mask:0xf bound_ctrl:1
	v_pk_fma_f32 v[32:33], v[38:39], v[74:75], v[32:33]
	v_mov_b32_dpp v58, v114 row_ror:1 row_mask:0xf bank_mask:0xf bound_ctrl:1
	v_mul_f32_e32 v38, 0xbfb8aa3b, v32
	v_mul_f32_e32 v39, 0xbfb8aa3b, v33
	v_exp_f32_e32 v38, v38
	v_exp_f32_e32 v39, v39
	v_mov_b32_dpp v112, v34 row_shr:2 row_mask:0xf bank_mask:0xf
	v_mov_b32_dpp v59, v115 row_ror:1 row_mask:0xf bank_mask:0xf bound_ctrl:1
	v_add_f32_e32 v38, 1.0, v38
	v_add_f32_e32 v39, 1.0, v39
	v_rcp_f32_e32 v38, v38
	v_rcp_f32_e32 v39, v39
	v_mov_b32_dpp v113, v35 row_shr:2 row_mask:0xf bank_mask:0xf
	v_mov_b32_dpp v58, v34 row_shr:1 row_mask:0xf bank_mask:0xf
	v_mov_b32_dpp v59, v35 row_shr:1 row_mask:0xf bank_mask:0xf
	v_pk_fma_f32 v[56:57], v[46:47], v[112:113], v[62:63]
	v_pk_mul_f32 v[32:33], v[32:33], v[38:39]
	v_pk_fma_f32 v[56:57], v[50:51], v[58:59], v[56:57]
	s_nop 0
	v_pk_fma_f32 v[34:35], v[34:35], v[54:55], v[56:57]
	s_nop 0
	v_pk_mul_f32 v[38:39], v[34:35], v[32:33]
	v_cvt_pk_bf16_f32 v34, v36, v37
	v_cvt_pk_bf16_f32 v35, v38, v39
	v_add_u32_e32 v38, 0x90, v230
	v_mov_b64_e32 v[36:37], s[12:13]
	v_mad_i64_i32 v[36:37], s[48:49], v38, s76, v[36:37]
	v_cvt_pk_bf16_f32 v32, v40, v41
	v_cvt_pk_bf16_f32 v33, v42, v43
	v_lshl_add_u64 v[36:37], v[222:223], 1, v[36:37]
	global_store_dwordx4 v[36:37], v[32:35], off
	s_nop 1
	v_mov_b32_e32 v32, 0
	v_mov_b32_e32 v56, 0
	v_mov_b32_e32 v57, 0
	v_mov_b32_e32 v58, 0
	v_mov_b32_e32 v59, 0
	v_mov_b32_e32 v34, 0
	v_mov_b32_e32 v35, 0
	v_mov_b32_e32 v36, 0
	v_mov_b32_e32 v37, 0
	v_mov_b32_e32 v112, 0
	v_mov_b32_e32 v113, 0
	v_mov_b32_e32 v114, 0
	v_mov_b32_e32 v115, 0
	v_mov_b32_e32 v38, 0
	v_mov_b32_e32 v39, 0
	v_mov_b32_e32 v40, 0
	v_mov_b32_e32 v41, 0
	s_and_saveexec_b64 s[48:49], s[2:3]
	s_cbranch_execz .LBB0_1707
	s_add_i32 s50, s41, s39
	s_addk_i32 s50, 0xa0
	s_ashr_i32 s50, s50, 3
	v_add_u32_e32 v33, s50, v231
	v_mov_b64_e32 v[34:35], s[8:9]
	v_mad_i64_i32 v[34:35], s[50:51], v33, s75, v[34:35]
	v_mov_b64_e32 v[36:37], s[30:31]
	v_lshl_add_u64 v[34:35], v[34:35], 0, v[224:225]
	v_mad_i64_i32 v[36:37], s[50:51], v33, s75, v[36:37]
	v_lshl_add_u64 v[42:43], v[36:37], 0, v[224:225]
	v_add_co_u32_e32 v36, vcc, 0x2000, v34
	s_nop 1
	v_addc_co_u32_e32 v37, vcc, 0, v35, vcc
	v_add_co_u32_e32 v116, vcc, 0x2000, v42
	global_load_dwordx4 v[112:115], v[34:35], off
	global_load_dwordx4 v[56:59], v[36:37], off offset:3072
	v_addc_co_u32_e32 v117, vcc, 0, v43, vcc
	global_store_dwordx4 v[42:43], v[28:31], off
	global_store_dwordx4 v[116:117], v[24:27], off offset:3072
	global_load_dwordx4 v[38:41], v[34:35], off offset:16
	s_nop 0
	global_load_dwordx4 v[34:37], v[36:37], off offset:3088
	s_nop 0
	global_store_dwordx4 v[42:43], v[20:23], off offset:16
	global_store_dwordx4 v[116:117], v[16:19], off offset:3088
; __device__ __forceinline__ float silu(float x) { return x * __builtin_amdgcn_rcpf(1.f + __builtin_amdgcn_exp2f(-1.4426950408889634f * x)); }
;     __device__ __forceinline__ void operator()(f32x4 (&acc)[2][2][4][2], const Unit& u, int, int, int, int) const {
;     ...
;                 for (int n = 0; n < 2; ++n)
; #pragma unroll
;                     for (int e = 0; e < 4; ++e) { const float A = acc[ai][0][m][n][e], Gv = acc[ai][1][m][n][e];
;                         const float a1 = dpp_prev(A, sa[n][e], 1), a2 = dpp_prev(A, sa[n][e], 2), g1 = dpp_prev(Gv, sg[n][e], 1), g2 = dpp_prev(Gv, sg[n][e], 2);
;                         const float ca = ba[n][e] + wa0[n][e] * a2 + wa1[n][e] * a1 + wa2[n][e] * A, cg = bg[n][e] + wg0[n][e] * g2 + wg1[n][e] * g1 + wg2[n][e] * Gv;
;                         r[4 * n + e] = silu(ca) * cg; }
.LBB0_1707:
	s_or_b64 exec, exec, s[48:49]
	s_waitcnt vmcnt(0) lgkmcnt(0)
	v_mov_b32_dpp v42, v112 row_ror:1 row_mask:0xf bank_mask:0xf bound_ctrl:1
	v_mov_b32_dpp v112, v112 row_ror:2 row_mask:0xf bank_mask:0xf bound_ctrl:1
	v_mov_b32_dpp v43, v113 row_ror:1 row_mask:0xf bank_mask:0xf bound_ctrl:1
	v_mov_b32_dpp v113, v113 row_ror:2 row_mask:0xf bank_mask:0xf bound_ctrl:1
	v_mov_b32_dpp v112, v28 row_shr:2 row_mask:0xf bank_mask:0xf
	v_mov_b32_dpp v42, v28 row_shr:1 row_mask:0xf bank_mask:0xf
	v_mov_b32_dpp v113, v29 row_shr:2 row_mask:0xf bank_mask:0xf
	v_mov_b32_dpp v43, v29 row_shr:1 row_mask:0xf bank_mask:0xf
	v_pk_fma_f32 v[112:113], v[104:105], v[112:113], v[108:109]
	v_mov_b32_dpp v116, v56 row_ror:1 row_mask:0xf bank_mask:0xf bound_ctrl:1
	v_pk_fma_f32 v[42:43], v[96:97], v[42:43], v[112:113]
	v_mov_b32_dpp v56, v56 row_ror:2 row_mask:0xf bank_mask:0xf bound_ctrl:1
	v_pk_fma_f32 v[28:29], v[28:29], v[100:101], v[42:43]
	v_mov_b32_dpp v117, v57 row_ror:1 row_mask:0xf bank_mask:0xf bound_ctrl:1
	v_mul_f32_e32 v33, 0xbfb8aa3b, v28
	v_exp_f32_e32 v33, v33
	v_mul_f32_e32 v42, 0xbfb8aa3b, v29
	v_exp_f32_e32 v43, v42
	v_mov_b32_dpp v57, v57 row_ror:2 row_mask:0xf bank_mask:0xf bound_ctrl:1
	v_add_f32_e32 v33, 1.0, v33
	v_rcp_f32_e32 v42, v33
	v_add_f32_e32 v33, 1.0, v43
	v_rcp_f32_e32 v43, v33
	v_mov_b32_dpp v56, v24 row_shr:2 row_mask:0xf bank_mask:0xf
	v_mov_b32_dpp v57, v25 row_shr:2 row_mask:0xf bank_mask:0xf
	v_mov_b32_dpp v116, v24 row_shr:1 row_mask:0xf bank_mask:0xf
	v_mov_b32_dpp v117, v25 row_shr:1 row_mask:0xf bank_mask:0xf
	v_pk_fma_f32 v[56:57], v[80:81], v[56:57], v[92:93]
	v_pk_mul_f32 v[28:29], v[28:29], v[42:43]
	v_pk_fma_f32 v[56:57], v[84:85], v[116:117], v[56:57]
	v_mov_b32_dpp v42, v114 row_ror:2 row_mask:0xf bank_mask:0xf bound_ctrl:1
	v_pk_fma_f32 v[24:25], v[24:25], v[88:89], v[56:57]
	v_mov_b32_dpp v43, v115 row_ror:2 row_mask:0xf bank_mask:0xf bound_ctrl:1
	v_pk_mul_f32 v[24:25], v[24:25], v[28:29]
	v_mov_b32_dpp v28, v114 row_ror:1 row_mask:0xf bank_mask:0xf bound_ctrl:1
	v_mov_b32_dpp v42, v30 row_shr:2 row_mask:0xf bank_mask:0xf
	v_mov_b32_dpp v29, v115 row_ror:1 row_mask:0xf bank_mask:0xf bound_ctrl:1
	v_mov_b32_dpp v43, v31 row_shr:2 row_mask:0xf bank_mask:0xf
	v_mov_b32_dpp v28, v30 row_shr:1 row_mask:0xf bank_mask:0xf
	v_mov_b32_dpp v29, v31 row_shr:1 row_mask:0xf bank_mask:0xf
	v_pk_fma_f32 v[42:43], v[106:107], v[42:43], v[110:111]
	v_mov_b32_dpp v56, v58 row_ror:1 row_mask:0xf bank_mask:0xf bound_ctrl:1
	v_pk_fma_f32 v[28:29], v[98:99], v[28:29], v[42:43]
	v_mov_b32_dpp v58, v58 row_ror:2 row_mask:0xf bank_mask:0xf bound_ctrl:1
	v_pk_fma_f32 v[28:29], v[30:31], v[102:103], v[28:29]
	v_mov_b32_dpp v57, v59 row_ror:1 row_mask:0xf bank_mask:0xf bound_ctrl:1
	v_mul_f32_e32 v30, 0xbfb8aa3b, v28
	v_mul_f32_e32 v31, 0xbfb8aa3b, v29
	v_exp_f32_e32 v30, v30
	v_exp_f32_e32 v31, v31
	v_mov_b32_dpp v59, v59 row_ror:2 row_mask:0xf bank_mask:0xf bound_ctrl:1
	v_mov_b32_dpp v58, v26 row_shr:2 row_mask:0xf bank_mask:0xf
	v_add_f32_e32 v30, 1.0, v30
	v_add_f32_e32 v31, 1.0, v31
	v_rcp_f32_e32 v30, v30
	v_rcp_f32_e32 v31, v31
	v_mov_b32_dpp v59, v27 row_shr:2 row_mask:0xf bank_mask:0xf
	v_mov_b32_dpp v56, v26 row_shr:1 row_mask:0xf bank_mask:0xf
	v_mov_b32_dpp v57, v27 row_shr:1 row_mask:0xf bank_mask:0xf
	v_pk_fma_f32 v[42:43], v[82:83], v[58:59], v[94:95]
	v_pk_mul_f32 v[28:29], v[28:29], v[30:31]
	v_pk_fma_f32 v[42:43], v[86:87], v[56:57], v[42:43]
	v_mov_b32_dpp v30, v38 row_ror:2 row_mask:0xf bank_mask:0xf bound_ctrl:1
	v_pk_fma_f32 v[26:27], v[26:27], v[90:91], v[42:43]
	v_mov_b32_dpp v31, v39 row_ror:2 row_mask:0xf bank_mask:0xf bound_ctrl:1
	v_pk_mul_f32 v[26:27], v[26:27], v[28:29]
	v_mov_b32_dpp v28, v38 row_ror:1 row_mask:0xf bank_mask:0xf bound_ctrl:1
	v_mov_b32_dpp v30, v20 row_shr:2 row_mask:0xf bank_mask:0xf
	v_mov_b32_dpp v29, v39 row_ror:1 row_mask:0xf bank_mask:0xf bound_ctrl:1
	v_mov_b32_dpp v31, v21 row_shr:2 row_mask:0xf bank_mask:0xf
	v_mov_b32_dpp v28, v20 row_shr:1 row_mask:0xf bank_mask:0xf
	v_mov_b32_dpp v29, v21 row_shr:1 row_mask:0xf bank_mask:0xf
	v_pk_fma_f32 v[30:31], v[64:65], v[30:31], v[76:77]
	v_mov_b32_dpp v38, v34 row_ror:1 row_mask:0xf bank_mask:0xf bound_ctrl:1
	v_pk_fma_f32 v[28:29], v[68:69], v[28:29], v[30:31]
	v_mov_b32_dpp v34, v34 row_ror:2 row_mask:0xf bank_mask:0xf bound_ctrl:1
	v_pk_fma_f32 v[20:21], v[20:21], v[72:73], v[28:29]
	v_mov_b32_dpp v39, v35 row_ror:1 row_mask:0xf bank_mask:0xf bound_ctrl:1
	v_mul_f32_e32 v28, 0xbfb8aa3b, v20
	v_mul_f32_e32 v29, 0xbfb8aa3b, v21
	v_exp_f32_e32 v28, v28
	v_exp_f32_e32 v29, v29
	v_mov_b32_dpp v35, v35 row_ror:2 row_mask:0xf bank_mask:0xf bound_ctrl:1
	v_mov_b32_dpp v34, v16 row_shr:2 row_mask:0xf bank_mask:0xf
	v_add_f32_e32 v28, 1.0, v28
	v_add_f32_e32 v29, 1.0, v29
	v_rcp_f32_e32 v28, v28
	v_rcp_f32_e32 v29, v29
	v_mov_b32_dpp v35, v17 row_shr:2 row_mask:0xf bank_mask:0xf
	v_mov_b32_dpp v38, v16 row_shr:1 row_mask:0xf bank_mask:0xf
	v_mov_b32_dpp v39, v17 row_shr:1 row_mask:0xf bank_mask:0xf
	v_pk_fma_f32 v[30:31], v[44:45], v[34:35], v[60:61]
	v_pk_mul_f32 v[20:21], v[20:21], v[28:29]
	v_pk_fma_f32 v[30:31], v[48:49], v[38:39], v[30:31]
	v_mov_b32_dpp v28, v40 row_ror:2 row_mask:0xf bank_mask:0xf bound_ctrl:1
	v_pk_fma_f32 v[16:17], v[16:17], v[52:53], v[30:31]
	v_mov_b32_dpp v29, v41 row_ror:2 row_mask:0xf bank_mask:0xf bound_ctrl:1
	v_pk_mul_f32 v[20:21], v[16:17], v[20:21]
	v_mov_b32_dpp v16, v40 row_ror:1 row_mask:0xf bank_mask:0xf bound_ctrl:1
	v_mov_b32_dpp v28, v22 row_shr:2 row_mask:0xf bank_mask:0xf
	v_mov_b32_dpp v17, v41 row_ror:1 row_mask:0xf bank_mask:0xf bound_ctrl:1
	v_mov_b32_dpp v29, v23 row_shr:2 row_mask:0xf bank_mask:0xf
; __device__ __forceinline__ unsigned pk2(float lo, float hi) { const f32x2 v = {lo, hi}; return __builtin_bit_cast(unsigned, __builtin_convertvector(v, bf16x2_t)); }
; __device__ __forceinline__ float silu(float x) { return x * __builtin_amdgcn_rcpf(1.f + __builtin_amdgcn_exp2f(-1.4426950408889634f * x)); }
;     __device__ __forceinline__ void operator()(f32x4 (&acc)[2][2][4][2], const Unit& u, int, int, int, int) const {
;     ...
;                 f32x4 sa[2], sg[2];
; #pragma unroll
;                 for (int n = 0; n < 2; ++n) { sa[n] = (f32x4){0.f, 0.f, 0.f, 0.f}; sg[n] = sa[n]; }
;                 if (fr >= 14) { const float* sp = sbuf + (size_t)(bseq * 2 + (fr - 14)) * NUP + f0; float* co = out + O_SCONV + (size_t)(bseq * 2 + (fr - 14)) * NUP + f0;
; #pragma unroll
;                     for (int n = 0; n < 2; ++n) { sa[n] = *(const f32x4*)(sp + 4 * n); sg[n] = *(const f32x4*)(sp + NFF + 4 * n); *(f32x4*)(co + 4 * n) = acc[ai][0][m][n]; *(f32x4*)(co + NFF + 4 * n) = acc[ai][1][m][n]; } }
;                 float r[8];
; #pragma unroll
;                 for (int n = 0; n < 2; ++n)
; #pragma unroll
;                     for (int e = 0; e < 4; ++e) { const float A = acc[ai][0][m][n][e], Gv = acc[ai][1][m][n][e];
;                         const float a1 = dpp_prev(A, sa[n][e], 1), a2 = dpp_prev(A, sa[n][e], 2), g1 = dpp_prev(Gv, sg[n][e], 1), g2 = dpp_prev(Gv, sg[n][e], 2);
;                         const float ca = ba[n][e] + wa0[n][e] * a2 + wa1[n][e] * a1 + wa2[n][e] * A, cg = bg[n][e] + wg0[n][e] * g2 + wg1[n][e] * g1 + wg2[n][e] * Gv;
;                         r[4 * n + e] = silu(ca) * cg; }
;                 u32x4 w; w.x = pk2(r[0], r[1]); w.y = pk2(r[2], r[3]); w.z = pk2(r[4], r[5]); w.w = pk2(r[6], r[7]);
;                 *(u32x4*)(ACT + (size_t)(rowt + ai * HALF + m * 16) * NFF + f0) = w;
;                 __builtin_amdgcn_sched_barrier(0); }
	v_mov_b32_dpp v16, v22 row_shr:1 row_mask:0xf bank_mask:0xf
	v_mov_b32_dpp v17, v23 row_shr:1 row_mask:0xf bank_mask:0xf
	v_pk_fma_f32 v[28:29], v[66:67], v[28:29], v[78:79]
	v_mov_b32_dpp v34, v36 row_ror:2 row_mask:0xf bank_mask:0xf bound_ctrl:1
	v_pk_fma_f32 v[16:17], v[70:71], v[16:17], v[28:29]
	v_mov_b32_dpp v35, v37 row_ror:2 row_mask:0xf bank_mask:0xf bound_ctrl:1
	v_pk_fma_f32 v[16:17], v[22:23], v[74:75], v[16:17]
	v_mov_b32_dpp v30, v36 row_ror:1 row_mask:0xf bank_mask:0xf bound_ctrl:1
	v_mul_f32_e32 v22, 0xbfb8aa3b, v16
	v_mul_f32_e32 v23, 0xbfb8aa3b, v17
	v_exp_f32_e32 v22, v22
	v_exp_f32_e32 v23, v23
	v_mov_b32_dpp v34, v18 row_shr:2 row_mask:0xf bank_mask:0xf
	v_mov_b32_dpp v31, v37 row_ror:1 row_mask:0xf bank_mask:0xf bound_ctrl:1
	v_add_f32_e32 v22, 1.0, v22
	v_add_f32_e32 v23, 1.0, v23
	v_rcp_f32_e32 v22, v22
	v_rcp_f32_e32 v23, v23
	v_mov_b32_dpp v35, v19 row_shr:2 row_mask:0xf bank_mask:0xf
	v_mov_b32_dpp v30, v18 row_shr:1 row_mask:0xf bank_mask:0xf
	v_mov_b32_dpp v31, v19 row_shr:1 row_mask:0xf bank_mask:0xf
	v_pk_fma_f32 v[28:29], v[46:47], v[34:35], v[62:63]
	v_pk_mul_f32 v[16:17], v[16:17], v[22:23]
	v_pk_fma_f32 v[28:29], v[50:51], v[30:31], v[28:29]
	s_nop 0
	v_pk_fma_f32 v[18:19], v[18:19], v[54:55], v[28:29]
	s_nop 0
	v_pk_mul_f32 v[22:23], v[18:19], v[16:17]
	v_cvt_pk_bf16_f32 v18, v20, v21
	v_cvt_pk_bf16_f32 v19, v22, v23
	v_add_u32_e32 v22, 0xa0, v230
	v_mov_b64_e32 v[20:21], s[12:13]
	v_mad_i64_i32 v[20:21], s[48:49], v22, s76, v[20:21]
	v_cvt_pk_bf16_f32 v16, v24, v25
	v_cvt_pk_bf16_f32 v17, v26, v27
	v_lshl_add_u64 v[20:21], v[222:223], 1, v[20:21]
	global_store_dwordx4 v[20:21], v[16:19], off
	v_mov_b32_e32 v33, 0
	v_mov_b32_e32 v34, 0
	v_mov_b32_e32 v35, 0
	v_mov_b32_e32 v16, 0
	v_mov_b32_e32 v17, 0
	v_mov_b32_e32 v18, 0
	v_mov_b32_e32 v19, 0
	v_mov_b32_e32 v24, 0
	v_mov_b32_e32 v25, 0
	v_mov_b32_e32 v26, 0
	v_mov_b32_e32 v27, 0
	v_mov_b32_e32 v20, 0
	v_mov_b32_e32 v21, 0
	v_mov_b32_e32 v22, 0
	v_mov_b32_e32 v23, 0
	s_and_saveexec_b64 s[48:49], s[2:3]
	s_cbranch_execz .LBB0_1709
	s_add_i32 s2, s41, s39
	s_addk_i32 s2, 0xb0
	s_ashr_i32 s2, s2, 3
	v_add_u32_e32 v20, s2, v231
	v_mov_b64_e32 v[16:17], s[8:9]
	v_mad_i64_i32 v[16:17], s[2:3], v20, s75, v[16:17]
	v_mov_b64_e32 v[18:19], s[30:31]
	v_lshl_add_u64 v[16:17], v[16:17], 0, v[224:225]
	v_mad_i64_i32 v[18:19], s[2:3], v20, s75, v[18:19]
	v_lshl_add_u64 v[28:29], v[18:19], 0, v[224:225]
	v_add_co_u32_e32 v18, vcc, 0x2000, v16
	s_nop 1
	v_addc_co_u32_e32 v19, vcc, 0, v17, vcc
	v_add_co_u32_e32 v30, vcc, 0x2000, v28
	global_load_dwordx4 v[24:27], v[16:17], off
	global_load_dwordx4 v[32:35], v[18:19], off offset:3072
	v_addc_co_u32_e32 v31, vcc, 0, v29, vcc
	global_store_dwordx4 v[28:29], v[12:15], off
	global_store_dwordx4 v[30:31], v[8:11], off offset:3072
	global_load_dwordx4 v[20:23], v[16:17], off offset:16
	s_nop 0
	global_load_dwordx4 v[16:19], v[18:19], off offset:3088
	s_nop 0
	global_store_dwordx4 v[28:29], v[4:7], off offset:16
	global_store_dwordx4 v[30:31], v[0:3], off offset:3088
.LBB0_1709:
	s_or_b64 exec, exec, s[48:49]
	s_waitcnt vmcnt(0) lgkmcnt(0)
	v_mov_b32_dpp v28, v24 row_ror:1 row_mask:0xf bank_mask:0xf bound_ctrl:1
	v_mov_b32_dpp v24, v24 row_ror:2 row_mask:0xf bank_mask:0xf bound_ctrl:1
	v_mov_b32_dpp v29, v25 row_ror:1 row_mask:0xf bank_mask:0xf bound_ctrl:1
	v_mov_b32_dpp v25, v25 row_ror:2 row_mask:0xf bank_mask:0xf bound_ctrl:1
	v_mov_b32_dpp v24, v12 row_shr:2 row_mask:0xf bank_mask:0xf
	v_mov_b32_dpp v28, v12 row_shr:1 row_mask:0xf bank_mask:0xf
	v_mov_b32_dpp v25, v13 row_shr:2 row_mask:0xf bank_mask:0xf
	v_mov_b32_dpp v29, v13 row_shr:1 row_mask:0xf bank_mask:0xf
	v_pk_fma_f32 v[24:25], v[104:105], v[24:25], v[108:109]
	v_mov_b32_dpp v30, v32 row_ror:1 row_mask:0xf bank_mask:0xf bound_ctrl:1
	v_pk_fma_f32 v[24:25], v[96:97], v[28:29], v[24:25]
	v_mov_b32_dpp v32, v32 row_ror:2 row_mask:0xf bank_mask:0xf bound_ctrl:1
	v_pk_fma_f32 v[12:13], v[12:13], v[100:101], v[24:25]
	v_mov_b32_dpp v31, v33 row_ror:1 row_mask:0xf bank_mask:0xf bound_ctrl:1
	v_mul_f32_e32 v24, 0xbfb8aa3b, v12
	v_mul_f32_e32 v25, 0xbfb8aa3b, v13
	v_exp_f32_e32 v24, v24
	v_exp_f32_e32 v25, v25
	v_mov_b32_dpp v33, v33 row_ror:2 row_mask:0xf bank_mask:0xf bound_ctrl:1
	v_mov_b32_dpp v32, v8 row_shr:2 row_mask:0xf bank_mask:0xf
	v_add_f32_e32 v24, 1.0, v24
	v_add_f32_e32 v25, 1.0, v25
	v_rcp_f32_e32 v24, v24
	v_rcp_f32_e32 v25, v25
	v_mov_b32_dpp v33, v9 row_shr:2 row_mask:0xf bank_mask:0xf
	v_mov_b32_dpp v30, v8 row_shr:1 row_mask:0xf bank_mask:0xf
	v_mov_b32_dpp v31, v9 row_shr:1 row_mask:0xf bank_mask:0xf
	v_pk_fma_f32 v[28:29], v[80:81], v[32:33], v[92:93]
	v_pk_mul_f32 v[12:13], v[12:13], v[24:25]
	v_pk_fma_f32 v[28:29], v[84:85], v[30:31], v[28:29]
	v_mov_b32_dpp v24, v26 row_ror:2 row_mask:0xf bank_mask:0xf bound_ctrl:1
	v_pk_fma_f32 v[8:9], v[8:9], v[88:89], v[28:29]
	v_mov_b32_dpp v25, v27 row_ror:2 row_mask:0xf bank_mask:0xf bound_ctrl:1
	v_pk_mul_f32 v[8:9], v[8:9], v[12:13]
	v_mov_b32_dpp v12, v26 row_ror:1 row_mask:0xf bank_mask:0xf bound_ctrl:1
	v_mov_b32_dpp v24, v14 row_shr:2 row_mask:0xf bank_mask:0xf
	v_mov_b32_dpp v13, v27 row_ror:1 row_mask:0xf bank_mask:0xf bound_ctrl:1
; __device__ __forceinline__ unsigned pk2(float lo, float hi) { const f32x2 v = {lo, hi}; return __builtin_bit_cast(unsigned, __builtin_convertvector(v, bf16x2_t)); }
; __device__ __forceinline__ float silu(float x) { return x * __builtin_amdgcn_rcpf(1.f + __builtin_amdgcn_exp2f(-1.4426950408889634f * x)); }
; #define PG8_BAR __builtin_amdgcn_s_barrier()
; template <class Epi, class Sched, bool ALIGN_EPI = true, bool SP2 = true>
; __device__ __forceinline__ void gemm_phase(PG8_LAS unsigned char* lds, const Gemm g, const Sched& S, const Epi& E) {
;     ...
;         E(acc, cur, wr, wc, fr, fq);
;         if (!has_next) break;
; #pragma unroll
;         for (int a = 0; a < 2; ++a)
; #pragma unroll
;             for (int b = 0; b < 2; ++b)
; #pragma unroll
;                 for (int m = 0; m < 4; ++m)
; #pragma unroll
;                     for (int n = 0; n < 2; ++n) acc[a][b][m][n] = (f32x4){0.f, 0.f, 0.f, 0.f};
;         cur = nxt; cA = nA; cB = nB; ++ui;
;         if constexpr (ALIGN_EPI) { if (wr == 1) PG8_BAR; }
;     }
;     __device__ __forceinline__ void operator()(f32x4 (&acc)[2][2][4][2], const Unit& u, int, int, int, int) const {
;     ...
;                 for (int n = 0; n < 2; ++n)
; #pragma unroll
;                     for (int e = 0; e < 4; ++e) { const float A = acc[ai][0][m][n][e], Gv = acc[ai][1][m][n][e];
;                         const float a1 = dpp_prev(A, sa[n][e], 1), a2 = dpp_prev(A, sa[n][e], 2), g1 = dpp_prev(Gv, sg[n][e], 1), g2 = dpp_prev(Gv, sg[n][e], 2);
;                         const float ca = ba[n][e] + wa0[n][e] * a2 + wa1[n][e] * a1 + wa2[n][e] * A, cg = bg[n][e] + wg0[n][e] * g2 + wg1[n][e] * g1 + wg2[n][e] * Gv;
;                         r[4 * n + e] = silu(ca) * cg; }
;                 u32x4 w; w.x = pk2(r[0], r[1]); w.y = pk2(r[2], r[3]); w.z = pk2(r[4], r[5]); w.w = pk2(r[6], r[7]);
;                 *(u32x4*)(ACT + (size_t)(rowt + ai * HALF + m * 16) * NFF + f0) = w;
;                 __builtin_amdgcn_sched_barrier(0); }
	v_mov_b32_dpp v25, v15 row_shr:2 row_mask:0xf bank_mask:0xf
	v_mov_b32_dpp v12, v14 row_shr:1 row_mask:0xf bank_mask:0xf
	v_mov_b32_dpp v13, v15 row_shr:1 row_mask:0xf bank_mask:0xf
	v_pk_fma_f32 v[24:25], v[106:107], v[24:25], v[110:111]
	v_mov_b32_dpp v28, v34 row_ror:2 row_mask:0xf bank_mask:0xf bound_ctrl:1
	v_pk_fma_f32 v[12:13], v[98:99], v[12:13], v[24:25]
	v_mov_b32_dpp v29, v35 row_ror:2 row_mask:0xf bank_mask:0xf bound_ctrl:1
	v_pk_fma_f32 v[12:13], v[14:15], v[102:103], v[12:13]
	v_mov_b32_dpp v26, v34 row_ror:1 row_mask:0xf bank_mask:0xf bound_ctrl:1
	v_mul_f32_e32 v14, 0xbfb8aa3b, v12
	v_mul_f32_e32 v15, 0xbfb8aa3b, v13
	v_exp_f32_e32 v14, v14
	v_exp_f32_e32 v15, v15
	v_mov_b32_dpp v28, v10 row_shr:2 row_mask:0xf bank_mask:0xf
	v_mov_b32_dpp v27, v35 row_ror:1 row_mask:0xf bank_mask:0xf bound_ctrl:1
	v_add_f32_e32 v14, 1.0, v14
	v_add_f32_e32 v15, 1.0, v15
	v_rcp_f32_e32 v14, v14
	v_rcp_f32_e32 v15, v15
	v_mov_b32_dpp v29, v11 row_shr:2 row_mask:0xf bank_mask:0xf
	v_mov_b32_dpp v26, v10 row_shr:1 row_mask:0xf bank_mask:0xf
	v_mov_b32_dpp v27, v11 row_shr:1 row_mask:0xf bank_mask:0xf
	v_pk_fma_f32 v[24:25], v[82:83], v[28:29], v[94:95]
	v_pk_mul_f32 v[12:13], v[12:13], v[14:15]
	v_pk_fma_f32 v[24:25], v[86:87], v[26:27], v[24:25]
	v_mov_b32_dpp v14, v20 row_ror:2 row_mask:0xf bank_mask:0xf bound_ctrl:1
	v_pk_fma_f32 v[10:11], v[10:11], v[90:91], v[24:25]
	v_mov_b32_dpp v15, v21 row_ror:2 row_mask:0xf bank_mask:0xf bound_ctrl:1
	v_pk_mul_f32 v[10:11], v[10:11], v[12:13]
	v_mov_b32_dpp v12, v20 row_ror:1 row_mask:0xf bank_mask:0xf bound_ctrl:1
	v_mov_b32_dpp v14, v4 row_shr:2 row_mask:0xf bank_mask:0xf
	v_mov_b32_dpp v13, v21 row_ror:1 row_mask:0xf bank_mask:0xf bound_ctrl:1
	v_mov_b32_dpp v15, v5 row_shr:2 row_mask:0xf bank_mask:0xf
	v_mov_b32_dpp v12, v4 row_shr:1 row_mask:0xf bank_mask:0xf
	v_mov_b32_dpp v13, v5 row_shr:1 row_mask:0xf bank_mask:0xf
	v_pk_fma_f32 v[14:15], v[64:65], v[14:15], v[76:77]
	v_mov_b32_dpp v20, v16 row_ror:1 row_mask:0xf bank_mask:0xf bound_ctrl:1
	v_pk_fma_f32 v[12:13], v[68:69], v[12:13], v[14:15]
	v_mov_b32_dpp v16, v16 row_ror:2 row_mask:0xf bank_mask:0xf bound_ctrl:1
	v_pk_fma_f32 v[4:5], v[4:5], v[72:73], v[12:13]
	v_mov_b32_dpp v21, v17 row_ror:1 row_mask:0xf bank_mask:0xf bound_ctrl:1
	v_mul_f32_e32 v12, 0xbfb8aa3b, v4
	v_mul_f32_e32 v13, 0xbfb8aa3b, v5
	v_exp_f32_e32 v12, v12
	v_exp_f32_e32 v13, v13
	v_mov_b32_dpp v17, v17 row_ror:2 row_mask:0xf bank_mask:0xf bound_ctrl:1
	v_mov_b32_dpp v16, v0 row_shr:2 row_mask:0xf bank_mask:0xf
	v_add_f32_e32 v12, 1.0, v12
	v_add_f32_e32 v13, 1.0, v13
	v_rcp_f32_e32 v12, v12
	v_rcp_f32_e32 v13, v13
	v_mov_b32_dpp v17, v1 row_shr:2 row_mask:0xf bank_mask:0xf
	v_mov_b32_dpp v20, v0 row_shr:1 row_mask:0xf bank_mask:0xf
	v_mov_b32_dpp v21, v1 row_shr:1 row_mask:0xf bank_mask:0xf
	v_pk_fma_f32 v[14:15], v[44:45], v[16:17], v[60:61]
	v_pk_mul_f32 v[4:5], v[4:5], v[12:13]
	v_pk_fma_f32 v[14:15], v[48:49], v[20:21], v[14:15]
	v_mov_b32_dpp v12, v22 row_ror:2 row_mask:0xf bank_mask:0xf bound_ctrl:1
	v_pk_fma_f32 v[0:1], v[0:1], v[52:53], v[14:15]
	v_mov_b32_dpp v13, v23 row_ror:2 row_mask:0xf bank_mask:0xf bound_ctrl:1
	v_pk_mul_f32 v[4:5], v[0:1], v[4:5]
	v_mov_b32_dpp v0, v22 row_ror:1 row_mask:0xf bank_mask:0xf bound_ctrl:1
	v_mov_b32_dpp v12, v6 row_shr:2 row_mask:0xf bank_mask:0xf
	v_mov_b32_dpp v1, v23 row_ror:1 row_mask:0xf bank_mask:0xf bound_ctrl:1
	v_mov_b32_dpp v13, v7 row_shr:2 row_mask:0xf bank_mask:0xf
	v_mov_b32_dpp v0, v6 row_shr:1 row_mask:0xf bank_mask:0xf
	v_mov_b32_dpp v1, v7 row_shr:1 row_mask:0xf bank_mask:0xf
	v_pk_fma_f32 v[12:13], v[66:67], v[12:13], v[78:79]
	v_mov_b32_dpp v16, v18 row_ror:2 row_mask:0xf bank_mask:0xf bound_ctrl:1
	v_pk_fma_f32 v[0:1], v[70:71], v[0:1], v[12:13]
	v_mov_b32_dpp v17, v19 row_ror:2 row_mask:0xf bank_mask:0xf bound_ctrl:1
	v_pk_fma_f32 v[0:1], v[6:7], v[74:75], v[0:1]
	v_mov_b32_dpp v14, v18 row_ror:1 row_mask:0xf bank_mask:0xf bound_ctrl:1
	v_mul_f32_e32 v6, 0xbfb8aa3b, v0
	v_mul_f32_e32 v7, 0xbfb8aa3b, v1
	v_exp_f32_e32 v6, v6
	v_exp_f32_e32 v7, v7
	v_mov_b32_dpp v16, v2 row_shr:2 row_mask:0xf bank_mask:0xf
	v_mov_b32_dpp v15, v19 row_ror:1 row_mask:0xf bank_mask:0xf bound_ctrl:1
	v_add_f32_e32 v6, 1.0, v6
	v_add_f32_e32 v7, 1.0, v7
	v_rcp_f32_e32 v6, v6
	v_rcp_f32_e32 v7, v7
	v_mov_b32_dpp v17, v3 row_shr:2 row_mask:0xf bank_mask:0xf
	v_mov_b32_dpp v14, v2 row_shr:1 row_mask:0xf bank_mask:0xf
	v_mov_b32_dpp v15, v3 row_shr:1 row_mask:0xf bank_mask:0xf
	v_pk_fma_f32 v[12:13], v[46:47], v[16:17], v[62:63]
	v_pk_mul_f32 v[0:1], v[0:1], v[6:7]
	v_pk_fma_f32 v[12:13], v[50:51], v[14:15], v[12:13]
	s_nop 0
	v_pk_fma_f32 v[2:3], v[2:3], v[54:55], v[12:13]
	s_nop 0
	v_pk_mul_f32 v[6:7], v[2:3], v[0:1]
	v_cvt_pk_bf16_f32 v2, v4, v5
	v_cvt_pk_bf16_f32 v3, v6, v7
	v_add_u32_e32 v6, 0xb0, v230
	v_mov_b64_e32 v[4:5], s[12:13]
	v_mad_i64_i32 v[4:5], s[2:3], v6, s76, v[4:5]
	v_cvt_pk_bf16_f32 v0, v8, v9
	v_cvt_pk_bf16_f32 v1, v10, v11
	v_lshl_add_u64 v[4:5], v[222:223], 1, v[4:5]
	global_store_dwordx4 v[4:5], v[0:3], off
	s_andn2_b64 vcc, exec, s[34:35]
	s_mov_b64 s[2:3], -1
	s_cbranch_vccnz .LBB0_1682
	s_andn2_b64 vcc, exec, s[10:11]
	s_cbranch_vccnz .LBB0_1681
	s_barrier
	s_branch .LBB0_1681

; #define LAS __attribute__((address_space(3)))
; __device__ __forceinline__ int my_tid(LAS unsigned char* lds) {
;     const unsigned hw = (unsigned)__builtin_amdgcn_s_getreg((5 << 11) | 4) & 63u;
;     const int wv = __builtin_amdgcn_readfirstlane(*(volatile LAS int*)(lds + TAB_OFF + 512 + 4 * hw));
;     int ln; asm volatile("v_mbcnt_lo_u32_b32 %0, -1, 0\n\tv_mbcnt_hi_u32_b32 %0, -1, %0" : "=v"(ln));
;     return wv * 64 + ln;
.LBB0_1715:
	s_barrier
	s_getreg_b32 s2, hwreg(HW_REG_HW_ID, 0, 6)
	s_lshl_b32 s2, s2, 2
	s_and_b32 s2, s2, 0xfc
	s_add_i32 s2, s2, 0
	s_add_i32 s2, s2, 0x25a00
	v_mov_b32_e32 v4, s2
	ds_read_b32 v4, v4
	v_mbcnt_lo_u32_b32 v5, -1, 0
	v_mbcnt_hi_u32_b32 v5, -1, v5
	s_waitcnt lgkmcnt(0)
	v_readfirstlane_b32 s2, v4
	s_lshl_b32 s2, s2, 6
	v_sub_u32_e32 v4, 0, v5
	v_cmp_eq_u32_e32 vcc, s2, v4
	s_and_saveexec_b64 s[2:3], vcc
	s_cbranch_execz .LBB0_1717
	v_mov_b32_e32 v4, s4
	ds_read_b64 v[4:5], v4
	s_waitcnt lgkmcnt(0)
	v_readfirstlane_b32 s7, v4
	v_readfirstlane_b32 s6, v5
	s_nop 0
	v_mov_b32_e32 v4, s7
	v_add_co_u32_e32 v4, vcc, 0x8000, v4
	v_mov_b32_e32 v5, s6
	s_nop 0
	v_addc_co_u32_e32 v5, vcc, 0, v5, vcc
	global_atomic_add v4, v[4:5], v6, off offset:1024 sc0
	s_waitcnt vmcnt(0) lgkmcnt(0)
	ds_write_b32 v7, v4

; __device__ __forceinline__ float wave_sum(float v) { v += swz_xor<1>(v); v += swz_xor<2>(v); v += swz_xor<4>(v); v += swz_xor<8>(v); v += swz_xor<16>(v); return half_sum(v); }
; #define QNEXT(ctrw, dst) do { __syncthreads(); if (my_tid(lds) == 0) *(volatile LAS int*)(lds + TAB_OFF + 264) = (int)atomicAdd((unsigned*)tab_get(lds, 31) + 8192 + 64 * (ctrw), 1u); \
;         __syncthreads(); dst = __builtin_amdgcn_readfirstlane(*(volatile LAS int*)(lds + TAB_OFF + 264)); } while (0)
; __device__ __forceinline__ void rms_row_f32_inplace(float* xrow, const float* g, int lane) {
;     f32x4* xr = (f32x4*)xrow + lane; f32x4 v[4]; float s = 0.f;
; #pragma unroll
;     for (int j = 0; j < 4; ++j) { v[j] = xr[64 * j]; s += (v[j].x * v[j].x + v[j].y * v[j].y) + (v[j].z * v[j].z + v[j].w * v[j].w); }
;     const float rstd = rsqrtf(wave_sum(s) * (1.f / DM) + EPS);
; #pragma unroll
;     for (int j = 0; j < 4; ++j) { const f32x4 gg = ((const f32x4*)g)[lane + 64 * j]; xr[64 * j] = v[j] * rstd * gg; }
; }
; __global__ void __launch_bounds__(512, 2) mega_fwd(Params p) {
;     ...
;           for (;;) { int it; QNEXT(4, it); if (it >= MP / 64) break;
; #pragma unroll 1
;               for (int k = 0; k < 8; ++k) rms_row_f32_inplace(X + (size_t)(it * 64 + wave * 8 + k) * DM, g, lane); } }
.LBB0_1719:
	v_lshl_add_u64 v[30:31], v[4:5], 0, s[2:3]
	global_load_dwordx4 v[10:13], v[30:31], off
	global_load_dwordx4 v[14:17], v[30:31], off offset:1024
	global_load_dwordx4 v[18:21], v[30:31], off offset:2048
	global_load_dwordx4 v[22:25], v[30:31], off offset:3072
	global_load_dwordx4 v[26:29], v[0:1], off
	s_add_u32 s2, s2, 0x1000
	s_addc_u32 s3, s3, 0
	s_cmpk_eq_u32 s2, 0x8000
	s_waitcnt vmcnt(0) lgkmcnt(0)
	v_mul_f32_e32 v9, v11, v11
	v_mul_f32_e32 v32, v13, v13
	v_mul_f32_e32 v33, v15, v15
	v_mul_f32_e32 v34, v17, v17
	v_mul_f32_e32 v35, v19, v19
	v_mul_f32_e32 v36, v21, v21
	v_fmac_f32_e32 v9, v10, v10
	v_fmac_f32_e32 v32, v12, v12
	v_fmac_f32_e32 v33, v14, v14
	v_fmac_f32_e32 v34, v16, v16
	v_mul_f32_e32 v37, v23, v23
	v_mul_f32_e32 v38, v25, v25
	v_fmac_f32_e32 v35, v18, v18
	v_fmac_f32_e32 v36, v20, v20
	v_add_f32_e32 v9, v9, v32
	v_add_f32_e32 v32, v33, v34
	v_fmac_f32_e32 v37, v22, v22
	v_fmac_f32_e32 v38, v24, v24
	v_add_f32_e32 v33, v35, v36
	v_add_f32_e32 v9, v9, v32
	v_add_f32_e32 v34, v37, v38
	v_add_f32_e32 v9, v9, v33
	v_add_f32_e32 v9, v9, v34
	ds_swizzle_b32 v32, v9 offset:swizzle(SWAP,1)
	s_waitcnt lgkmcnt(0)
	v_add_f32_e32 v9, v9, v32
	ds_swizzle_b32 v32, v9 offset:swizzle(SWAP,2)
	s_waitcnt lgkmcnt(0)
	v_add_f32_e32 v9, v9, v32
	ds_swizzle_b32 v32, v9 offset:swizzle(SWAP,4)
	s_waitcnt lgkmcnt(0)
	v_add_f32_e32 v9, v9, v32
	ds_swizzle_b32 v32, v9 offset:swizzle(SWAP,8)
	s_waitcnt lgkmcnt(0)
	v_add_f32_e32 v9, v9, v32
	ds_swizzle_b32 v32, v9 offset:swizzle(SWAP,16)
	s_waitcnt lgkmcnt(0)
	v_add_f32_e32 v9, v9, v32
	v_mov_b32_e32 v32, v9
	s_nop 1
	v_permlane32_swap_b32_e32 v9, v32
	v_add_f32_e32 v9, v9, v32
	v_fmamk_f32 v9, v9, 0x3a800000, v8
	v_mul_f32_e32 v32, 0x4b800000, v9
	v_cmp_gt_f32_e32 vcc, s5, v9
	s_nop 1
	v_cndmask_b32_e32 v9, v9, v32, vcc
	v_rsq_f32_e32 v9, v9
	s_nop 0
	v_mul_f32_e32 v32, 0x45800000, v9
	v_cndmask_b32_e32 v32, v9, v32, vcc
	v_pk_mul_f32 v[10:11], v[10:11], v[32:33] op_sel_hi:[1,0]
	v_pk_mul_f32 v[12:13], v[12:13], v[32:33] op_sel_hi:[1,0]
	v_pk_mul_f32 v[10:11], v[26:27], v[10:11]
	v_pk_mul_f32 v[12:13], v[28:29], v[12:13]
	global_store_dwordx4 v[30:31], v[10:13], off
	global_load_dwordx4 v[10:13], v[0:1], off offset:1024
	v_pk_mul_f32 v[16:17], v[16:17], v[32:33] op_sel_hi:[1,0]
	v_pk_mul_f32 v[14:15], v[14:15], v[32:33] op_sel_hi:[1,0]
	s_waitcnt vmcnt(0) lgkmcnt(0)
	v_pk_mul_f32 v[12:13], v[12:13], v[16:17]
	v_pk_mul_f32 v[10:11], v[10:11], v[14:15]
	global_store_dwordx4 v[30:31], v[10:13], off offset:1024
	global_load_dwordx4 v[10:13], v[0:1], off offset:2048
	v_pk_mul_f32 v[14:15], v[20:21], v[32:33] op_sel_hi:[1,0]
	v_pk_mul_f32 v[16:17], v[18:19], v[32:33] op_sel_hi:[1,0]
	s_waitcnt vmcnt(0) lgkmcnt(0)
	v_pk_mul_f32 v[12:13], v[12:13], v[14:15]
	v_pk_mul_f32 v[10:11], v[10:11], v[16:17]
	global_store_dwordx4 v[30:31], v[10:13], off offset:2048
	global_load_dwordx4 v[10:13], v[0:1], off offset:3072
	v_pk_mul_f32 v[14:15], v[24:25], v[32:33] op_sel_hi:[1,0]
	v_pk_mul_f32 v[16:17], v[22:23], v[32:33] op_sel_hi:[1,0]
	s_waitcnt vmcnt(0) lgkmcnt(0)
	v_pk_mul_f32 v[12:13], v[12:13], v[14:15]
	v_pk_mul_f32 v[10:11], v[10:11], v[16:17]
	global_store_dwordx4 v[30:31], v[10:13], off offset:3072
	s_cbranch_scc0 .LBB0_1719
	s_mov_b64 s[2:3], 0
	s_branch .LBB0_1714

; __device__ __forceinline__ unsigned xb_ld(unsigned* p)              { return __hip_atomic_load(p, __ATOMIC_RELAXED, __HIP_MEMORY_SCOPE_AGENT); }
; __device__ __forceinline__ unsigned xb_add(unsigned* p, unsigned v) { return __hip_atomic_fetch_add(p, v, __ATOMIC_RELAXED, __HIP_MEMORY_SCOPE_AGENT); }
; #define XB_SPIN(cond, bar) do { unsigned _sp = 0; while (cond) { __builtin_amdgcn_s_sleep(1); \
;     if ((++_sp & 255u) == 0u) { if (xb_ld(&(bar)[XB_TMO])) break; if (_sp > XB_SPIN_CAP) { atomicAdd(&(bar)[XB_TMO], 1u); break; } } } } while (0)
; __device__ __forceinline__ void xcd_barrier(const XcdBarrier& b, bool leader) {
;     ...
;     if (leader) {
;         unsigned* bar = b.bar;
;         __builtin_amdgcn_s_waitcnt(0);
;         unsigned nloc = b.st[0], nx = b.st[1];
;         if (nloc == 0u) { xcd_barrier_complete(bar, b.x, nloc, nx); b.st[0] = nloc; b.st[1] = nx; }
;         const unsigned old = xb_add(&bar[XB_XSUB(b.x)], 1u);
;         const unsigned gen = old / nloc;
;         if (old + 1u == (gen + 1u) * nloc) {
;             __builtin_amdgcn_fence(__ATOMIC_RELEASE, "agent");
;             asm volatile("s_waitcnt vmcnt(0)" ::: "memory");
;             const unsigned og = xb_add(&bar[XB_TOP], 1u);
;             const unsigned tg = og / nx;
;             if (og + 1u == (tg + 1u) * nx) xb_add(&bar[XB_TOPGEN], 1u);
;             else XB_SPIN(xb_ld(&bar[XB_TOPGEN]) == tg, bar);
;             __builtin_amdgcn_fence(__ATOMIC_ACQUIRE, "agent");
;             xb_add(&bar[XB_XGEN(b.x)], 1u);
;             asm volatile("s_waitcnt vmcnt(0)" ::: "memory");
;         } else {
;             XB_SPIN(xb_ld(&bar[XB_XGEN(b.x)]) == gen, bar);
;             __builtin_amdgcn_fence(__ATOMIC_ACQUIRE, "agent");
;             asm volatile("s_waitcnt vmcnt(0)" ::: "memory");
;         }
.LBB0_1736:
	s_lshl_b32 s2, s38, 8
	s_add_u32 s2, s37, s2
	s_addc_u32 s3, s33, 0
	v_mov_b32_e32 v1, s2
	v_add_co_u32_e32 v4, vcc, 0x2000, v1
	v_mov_b32_e32 v1, s3
	s_nop 0
	v_addc_co_u32_e32 v5, vcc, 0, v1, vcc
	v_mov_b32_e32 v1, 1
	global_atomic_add v1, v[4:5], v1, off offset:1024 sc0
	v_cvt_f32_u32_e32 v3, v2
	v_sub_u32_e32 v4, 0, v2
	s_add_u32 s25, s2, 0x1000
	s_addc_u32 s24, s3, 0
	v_rcp_iflag_f32_e32 v3, v3
	s_nop 0
	v_mul_f32_e32 v3, 0x4f7ffffe, v3
	v_cvt_u32_f32_e32 v3, v3
	v_mul_lo_u32 v4, v4, v3
	v_mul_hi_u32 v4, v3, v4
	v_add_u32_e32 v3, v3, v4
	s_waitcnt vmcnt(0) lgkmcnt(0)
	v_mul_hi_u32 v3, v1, v3
	v_mul_lo_u32 v5, v3, v2
	v_add_u32_e32 v4, 1, v1
	v_sub_u32_e32 v1, v1, v5
	v_add_u32_e32 v6, 1, v3
	v_cmp_ge_u32_e32 vcc, v1, v2
	v_sub_u32_e32 v5, v1, v2
	s_nop 0
	v_cndmask_b32_e32 v3, v3, v6, vcc
	v_cndmask_b32_e32 v1, v1, v5, vcc
	v_add_u32_e32 v5, 1, v3
	v_cmp_ge_u32_e32 vcc, v1, v2
	s_nop 1
	v_cndmask_b32_e32 v1, v3, v5, vcc
	v_mad_u64_u32 v[2:3], s[2:3], v2, v1, v[2:3]
	v_cmp_ne_u32_e32 vcc, v4, v2
	s_and_saveexec_b64 s[2:3], vcc
	s_xor_b64 s[2:3], exec, s[2:3]
	s_cbranch_execz .LBB0_1749
	v_mov_b32_e32 v0, s25
	v_add_co_u32_e32 v2, vcc, 0x2000, v0
	v_mov_b32_e32 v0, s24
	s_nop 0
	v_addc_co_u32_e32 v3, vcc, 0, v0, vcc
	global_load_dword v0, v[2:3], off offset:1024 sc1
	s_add_u32 s8, s25, 0x2400
	s_addc_u32 s9, s24, 0
	s_waitcnt vmcnt(0) lgkmcnt(0)
	v_cmp_eq_u32_e32 vcc, v0, v1
	s_and_saveexec_b64 s[4:5], vcc
	s_cbranch_execz .LBB0_1748
	s_add_u32 s6, s37, 0x1200
	s_addc_u32 s7, s33, 0
	s_mov_b32 s26, 1
	s_mov_b64 s[10:11], 0
	s_branch .LBB0_1740

; __device__ __forceinline__ unsigned xb_ld(unsigned* p)              { return __hip_atomic_load(p, __ATOMIC_RELAXED, __HIP_MEMORY_SCOPE_AGENT); }
; __device__ __forceinline__ unsigned xb_add(unsigned* p, unsigned v) { return __hip_atomic_fetch_add(p, v, __ATOMIC_RELAXED, __HIP_MEMORY_SCOPE_AGENT); }
; #define XB_SPIN(cond, bar) do { unsigned _sp = 0; while (cond) { __builtin_amdgcn_s_sleep(1); \
;     if ((++_sp & 255u) == 0u) { if (xb_ld(&(bar)[XB_TMO])) break; if (_sp > XB_SPIN_CAP) { atomicAdd(&(bar)[XB_TMO], 1u); break; } } } } while (0)
; __device__ __forceinline__ void xcd_barrier(const XcdBarrier& b, bool leader) {
;     ...
;         if (old + 1u == (gen + 1u) * nloc) {
;             __builtin_amdgcn_fence(__ATOMIC_RELEASE, "agent");
;             asm volatile("s_waitcnt vmcnt(0)" ::: "memory");
;             const unsigned og = xb_add(&bar[XB_TOP], 1u);
;             const unsigned tg = og / nx;
;             if (og + 1u == (tg + 1u) * nx) xb_add(&bar[XB_TOPGEN], 1u);
;             else XB_SPIN(xb_ld(&bar[XB_TOPGEN]) == tg, bar);
;             __builtin_amdgcn_fence(__ATOMIC_ACQUIRE, "agent");
;             xb_add(&bar[XB_XGEN(b.x)], 1u);
.LBB0_1749:
	s_andn2_saveexec_b64 s[2:3], s[2:3]
	s_cbranch_execz .LBB0_1765
	v_mov_b32_e32 v1, s37
	v_add_co_u32_e32 v2, vcc, 0x4000, v1
	v_mov_b32_e32 v1, s33
	buffer_wbl2 sc1
	s_waitcnt vmcnt(0)
	v_addc_co_u32_e32 v3, vcc, 0, v1, vcc
	v_mov_b32_e32 v1, 1
	global_atomic_add v1, v[2:3], v1, off offset:1024 sc0
	v_cvt_f32_u32_e32 v2, v0
	v_sub_u32_e32 v3, 0, v0
	s_add_u32 s2, s37, 0x4500
	s_addc_u32 s3, s33, 0
	v_rcp_iflag_f32_e32 v2, v2
	s_mov_b64 s[6:7], -1
	v_mul_f32_e32 v2, 0x4f7ffffe, v2
	v_cvt_u32_f32_e32 v2, v2
	v_mul_lo_u32 v3, v3, v2
	v_mul_hi_u32 v3, v2, v3
	v_add_u32_e32 v2, v2, v3
	s_waitcnt vmcnt(0) lgkmcnt(0)
	v_mul_hi_u32 v2, v1, v2
	v_mul_lo_u32 v4, v2, v0
	v_add_u32_e32 v3, 1, v1
	v_sub_u32_e32 v1, v1, v4
	v_add_u32_e32 v5, 1, v2
	v_cmp_ge_u32_e32 vcc, v1, v0
	v_sub_u32_e32 v4, v1, v0
	s_nop 0
	v_cndmask_b32_e32 v2, v2, v5, vcc
	v_cndmask_b32_e32 v1, v1, v4, vcc
	v_add_u32_e32 v4, 1, v2
	v_cmp_ge_u32_e32 vcc, v1, v0
	s_nop 1
	v_cndmask_b32_e32 v2, v2, v4, vcc
	v_mad_u64_u32 v[0:1], s[4:5], v0, v2, v[0:1]
	v_cmp_ne_u32_e32 vcc, v3, v0
	v_mov_b64_e32 v[0:1], s[2:3]
	s_and_saveexec_b64 s[4:5], vcc
	s_cbranch_execz .LBB0_1762
	v_mov_b64_e32 v[0:1], s[2:3]
	global_load_dword v0, v[0:1], off sc1
	s_mov_b64 s[10:11], 0
	s_waitcnt vmcnt(0) lgkmcnt(0)
	v_cmp_eq_u32_e32 vcc, v0, v2
	s_and_saveexec_b64 s[8:9], vcc
	s_cbranch_execz .LBB0_1761
	s_add_u32 s6, s37, 0x1200
	s_addc_u32 s7, s33, 0
	s_mov_b32 s22, 1
	s_branch .LBB0_1754

;     __device__ __forceinline__ void operator()(EPI_ARGS) const {
;         const int row0 = u.pm * BM + wr * 64 + fr, col0 = u.pn * BM + wc * 32 + 8 * fq;
; #pragma unroll
;         for (int ai = 0; ai < 2; ++ai)
; #pragma unroll
;             for (int m = 0; m < 4; ++m) { float* o = X + (size_t)(row0 + ai * HALF + m * 16) * DM + col0;
; #pragma unroll
;                 for (int bj = 0; bj < 2; ++bj)
; #pragma unroll
;                     for (int n = 0; n < 2; ++n)
; #pragma unroll
;                         for (int e = 0; e < 4; ++e) (void)__hip_atomic_fetch_add(o + bj * HALF + 4 * n + e, acc[ai][bj][m][n][e], __ATOMIC_RELAXED, __HIP_MEMORY_SCOPE_AGENT); }
;     }
.LBB0_1788:
	v_lshl_add_u32 v148, s64, 8, v143
	v_lshl_or_b32 v150, s70, 8, v145
	v_ashrrev_i32_e32 v149, 31, v148
	v_ashrrev_i32_e32 v151, 31, v150
	v_lshlrev_b64 v[152:153], 12, v[148:149]
	v_lshl_add_u64 v[152:153], s[20:21], 0, v[152:153]
	v_lshlrev_b64 v[150:151], 2, v[150:151]
	v_lshl_add_u64 v[152:153], v[152:153], 0, v[150:151]
	s_waitcnt vmcnt(0)
	global_atomic_add_f32 v[152:153], v124, off
	global_atomic_add_f32 v[152:153], v125, off offset:4
	global_atomic_add_f32 v[152:153], v126, off offset:8
	global_atomic_add_f32 v[152:153], v127, off offset:12
	global_atomic_add_f32 v[152:153], v120, off offset:16
	global_atomic_add_f32 v[152:153], v121, off offset:20
	global_atomic_add_f32 v[152:153], v122, off offset:24
	global_atomic_add_f32 v[152:153], v123, off offset:28
	global_atomic_add_f32 v[152:153], v108, off offset:512
	global_atomic_add_f32 v[152:153], v109, off offset:516
	global_atomic_add_f32 v[152:153], v110, off offset:520
	global_atomic_add_f32 v[152:153], v111, off offset:524
	global_atomic_add_f32 v[152:153], v104, off offset:528
	global_atomic_add_f32 v[152:153], v105, off offset:532
	global_atomic_add_f32 v[152:153], v106, off offset:536
	global_atomic_add_f32 v[152:153], v107, off offset:540
	v_or_b32_e32 v104, 16, v148
	v_ashrrev_i32_e32 v105, 31, v104
	v_lshlrev_b64 v[104:105], 12, v[104:105]
	v_lshl_add_u64 v[104:105], s[20:21], 0, v[104:105]
	v_lshl_add_u64 v[104:105], v[104:105], 0, v[150:151]
	global_atomic_add_f32 v[104:105], v116, off
	global_atomic_add_f32 v[104:105], v117, off offset:4
	global_atomic_add_f32 v[104:105], v118, off offset:8
	global_atomic_add_f32 v[104:105], v119, off offset:12
	global_atomic_add_f32 v[104:105], v112, off offset:16
	global_atomic_add_f32 v[104:105], v113, off offset:20
	global_atomic_add_f32 v[104:105], v114, off offset:24
	global_atomic_add_f32 v[104:105], v115, off offset:28
	global_atomic_add_f32 v[104:105], v92, off offset:512
	global_atomic_add_f32 v[104:105], v93, off offset:516
	global_atomic_add_f32 v[104:105], v94, off offset:520
	global_atomic_add_f32 v[104:105], v95, off offset:524
	global_atomic_add_f32 v[104:105], v88, off offset:528
	global_atomic_add_f32 v[104:105], v89, off offset:532
	global_atomic_add_f32 v[104:105], v90, off offset:536
	global_atomic_add_f32 v[104:105], v91, off offset:540
	v_or_b32_e32 v88, 32, v148
	v_ashrrev_i32_e32 v89, 31, v88
	v_lshlrev_b64 v[88:89], 12, v[88:89]
	v_lshl_add_u64 v[88:89], s[20:21], 0, v[88:89]
	v_lshl_add_u64 v[88:89], v[88:89], 0, v[150:151]
	global_atomic_add_f32 v[88:89], v100, off
	global_atomic_add_f32 v[88:89], v101, off offset:4
	global_atomic_add_f32 v[88:89], v102, off offset:8
	global_atomic_add_f32 v[88:89], v103, off offset:12
	global_atomic_add_f32 v[88:89], v96, off offset:16
	global_atomic_add_f32 v[88:89], v97, off offset:20
	global_atomic_add_f32 v[88:89], v98, off offset:24
	global_atomic_add_f32 v[88:89], v99, off offset:28
	global_atomic_add_f32 v[88:89], v76, off offset:512
	global_atomic_add_f32 v[88:89], v77, off offset:516
	global_atomic_add_f32 v[88:89], v78, off offset:520
	global_atomic_add_f32 v[88:89], v79, off offset:524
	global_atomic_add_f32 v[88:89], v72, off offset:528
	global_atomic_add_f32 v[88:89], v73, off offset:532
	global_atomic_add_f32 v[88:89], v74, off offset:536
	global_atomic_add_f32 v[88:89], v75, off offset:540
	v_or_b32_e32 v72, 48, v148
	v_ashrrev_i32_e32 v73, 31, v72
	v_lshlrev_b64 v[72:73], 12, v[72:73]
	v_lshl_add_u64 v[72:73], s[20:21], 0, v[72:73]
	v_lshl_add_u64 v[72:73], v[72:73], 0, v[150:151]
	global_atomic_add_f32 v[72:73], v84, off
	global_atomic_add_f32 v[72:73], v85, off offset:4
	global_atomic_add_f32 v[72:73], v86, off offset:8
	global_atomic_add_f32 v[72:73], v87, off offset:12
	global_atomic_add_f32 v[72:73], v80, off offset:16
	global_atomic_add_f32 v[72:73], v81, off offset:20
	global_atomic_add_f32 v[72:73], v82, off offset:24
	global_atomic_add_f32 v[72:73], v83, off offset:28
	global_atomic_add_f32 v[72:73], v68, off offset:512
	global_atomic_add_f32 v[72:73], v69, off offset:516
	global_atomic_add_f32 v[72:73], v70, off offset:520
	global_atomic_add_f32 v[72:73], v71, off offset:524
	global_atomic_add_f32 v[72:73], v64, off offset:528
;     __device__ __forceinline__ void operator()(EPI_ARGS) const {
;         const int row0 = u.pm * BM + wr * 64 + fr, col0 = u.pn * BM + wc * 32 + 8 * fq;
; #pragma unroll
;         for (int ai = 0; ai < 2; ++ai)
; #pragma unroll
;             for (int m = 0; m < 4; ++m) { float* o = X + (size_t)(row0 + ai * HALF + m * 16) * DM + col0;
; #pragma unroll
;                 for (int bj = 0; bj < 2; ++bj)
; #pragma unroll
;                     for (int n = 0; n < 2; ++n)
; #pragma unroll
;                         for (int e = 0; e < 4; ++e) (void)__hip_atomic_fetch_add(o + bj * HALF + 4 * n + e, acc[ai][bj][m][n][e], __ATOMIC_RELAXED, __HIP_MEMORY_SCOPE_AGENT); }
;     }
	global_atomic_add_f32 v[72:73], v65, off offset:532
	global_atomic_add_f32 v[72:73], v66, off offset:536
	global_atomic_add_f32 v[72:73], v67, off offset:540
	v_add_co_u32_e32 v66, vcc, s41, v152
	v_lshl_add_u64 v[64:65], v[152:153], 0, s[12:13]
	s_nop 0
	v_addc_co_u32_e32 v67, vcc, 0, v153, vcc
	global_atomic_add_f32 v[66:67], v60, off
	global_atomic_add_f32 v[64:65], v61, off offset:4
	global_atomic_add_f32 v[64:65], v62, off offset:8
	global_atomic_add_f32 v[64:65], v63, off offset:12
	global_atomic_add_f32 v[64:65], v56, off offset:16
	global_atomic_add_f32 v[64:65], v57, off offset:20
	global_atomic_add_f32 v[64:65], v58, off offset:24
	global_atomic_add_f32 v[64:65], v59, off offset:28
	global_atomic_add_f32 v[64:65], v44, off offset:512
	global_atomic_add_f32 v[64:65], v45, off offset:516
	global_atomic_add_f32 v[64:65], v46, off offset:520
	global_atomic_add_f32 v[64:65], v47, off offset:524
	global_atomic_add_f32 v[64:65], v40, off offset:528
	global_atomic_add_f32 v[64:65], v41, off offset:532
	global_atomic_add_f32 v[64:65], v42, off offset:536
	global_atomic_add_f32 v[64:65], v43, off offset:540
	v_add_co_u32_e32 v42, vcc, s42, v152
	v_lshl_add_u64 v[40:41], v[152:153], 0, s[14:15]
	s_nop 0
	v_addc_co_u32_e32 v43, vcc, 0, v153, vcc
	global_atomic_add_f32 v[42:43], v52, off
	global_atomic_add_f32 v[40:41], v53, off offset:4
	global_atomic_add_f32 v[40:41], v54, off offset:8
	global_atomic_add_f32 v[40:41], v55, off offset:12
	global_atomic_add_f32 v[40:41], v48, off offset:16
	global_atomic_add_f32 v[40:41], v49, off offset:20
	global_atomic_add_f32 v[40:41], v50, off offset:24
	global_atomic_add_f32 v[40:41], v51, off offset:28
	global_atomic_add_f32 v[40:41], v28, off offset:512
	global_atomic_add_f32 v[40:41], v29, off offset:516
	global_atomic_add_f32 v[40:41], v30, off offset:520
	global_atomic_add_f32 v[40:41], v31, off offset:524
	global_atomic_add_f32 v[40:41], v24, off offset:528
	global_atomic_add_f32 v[40:41], v25, off offset:532
	global_atomic_add_f32 v[40:41], v26, off offset:536
	global_atomic_add_f32 v[40:41], v27, off offset:540
	v_add_co_u32_e32 v26, vcc, s43, v152
	v_lshl_add_u64 v[24:25], v[152:153], 0, s[16:17]
	s_nop 0
	v_addc_co_u32_e32 v27, vcc, 0, v153, vcc
	global_atomic_add_f32 v[26:27], v36, off
	global_atomic_add_f32 v[24:25], v37, off offset:4
	global_atomic_add_f32 v[24:25], v38, off offset:8
	global_atomic_add_f32 v[24:25], v39, off offset:12
	global_atomic_add_f32 v[24:25], v32, off offset:16
	global_atomic_add_f32 v[24:25], v33, off offset:20
	global_atomic_add_f32 v[24:25], v34, off offset:24
	global_atomic_add_f32 v[24:25], v35, off offset:28
	global_atomic_add_f32 v[24:25], v12, off offset:512
	global_atomic_add_f32 v[24:25], v13, off offset:516
	global_atomic_add_f32 v[24:25], v14, off offset:520
	global_atomic_add_f32 v[24:25], v15, off offset:524
	global_atomic_add_f32 v[24:25], v8, off offset:528
	global_atomic_add_f32 v[24:25], v9, off offset:532
	global_atomic_add_f32 v[24:25], v10, off offset:536
	global_atomic_add_f32 v[24:25], v11, off offset:540
	v_add_co_u32_e32 v10, vcc, s45, v152
	v_lshl_add_u64 v[8:9], v[152:153], 0, s[6:7]
	s_nop 0
	v_addc_co_u32_e32 v11, vcc, 0, v153, vcc
	global_atomic_add_f32 v[10:11], v20, off
	global_atomic_add_f32 v[8:9], v21, off offset:4
	global_atomic_add_f32 v[8:9], v22, off offset:8
	global_atomic_add_f32 v[8:9], v23, off offset:12
	global_atomic_add_f32 v[8:9], v16, off offset:16
	global_atomic_add_f32 v[8:9], v17, off offset:20
	global_atomic_add_f32 v[8:9], v18, off offset:24
	global_atomic_add_f32 v[8:9], v19, off offset:28
	global_atomic_add_f32 v[8:9], v4, off offset:512
	global_atomic_add_f32 v[8:9], v5, off offset:516
	global_atomic_add_f32 v[8:9], v6, off offset:520
	global_atomic_add_f32 v[8:9], v7, off offset:524
	global_atomic_add_f32 v[8:9], v0, off offset:528
	global_atomic_add_f32 v[8:9], v1, off offset:532
	global_atomic_add_f32 v[8:9], v2, off offset:536
	global_atomic_add_f32 v[8:9], v3, off offset:540
	s_and_b64 vcc, exec, s[2:3]
	s_mov_b64 s[2:3], -1
	s_cbranch_vccnz .LBB0_1777
	s_andn2_b64 vcc, exec, s[18:19]
	s_cbranch_vccnz .LBB0_1776
	s_barrier
	s_branch .LBB0_1776

; __device__ __forceinline__ unsigned xb_ld(unsigned* p)              { return __hip_atomic_load(p, __ATOMIC_RELAXED, __HIP_MEMORY_SCOPE_AGENT); }
; __device__ __forceinline__ unsigned xb_add(unsigned* p, unsigned v) { return __hip_atomic_fetch_add(p, v, __ATOMIC_RELAXED, __HIP_MEMORY_SCOPE_AGENT); }
; #define XB_SPIN(cond, bar) do { unsigned _sp = 0; while (cond) { __builtin_amdgcn_s_sleep(1); \
;     if ((++_sp & 255u) == 0u) { if (xb_ld(&(bar)[XB_TMO])) break; if (_sp > XB_SPIN_CAP) { atomicAdd(&(bar)[XB_TMO], 1u); break; } } } } while (0)
; __device__ __forceinline__ void xcd_barrier(const XcdBarrier& b, bool leader) {
;     ...
;     if (leader) {
;         unsigned* bar = b.bar;
;         __builtin_amdgcn_s_waitcnt(0);
;         unsigned nloc = b.st[0], nx = b.st[1];
;         if (nloc == 0u) { xcd_barrier_complete(bar, b.x, nloc, nx); b.st[0] = nloc; b.st[1] = nx; }
;         const unsigned old = xb_add(&bar[XB_XSUB(b.x)], 1u);
;         const unsigned gen = old / nloc;
;         if (old + 1u == (gen + 1u) * nloc) {
;             __builtin_amdgcn_fence(__ATOMIC_RELEASE, "agent");
;             asm volatile("s_waitcnt vmcnt(0)" ::: "memory");
;             const unsigned og = xb_add(&bar[XB_TOP], 1u);
;             const unsigned tg = og / nx;
;             if (og + 1u == (tg + 1u) * nx) xb_add(&bar[XB_TOPGEN], 1u);
;             else XB_SPIN(xb_ld(&bar[XB_TOPGEN]) == tg, bar);
;             __builtin_amdgcn_fence(__ATOMIC_ACQUIRE, "agent");
;             xb_add(&bar[XB_XGEN(b.x)], 1u);
;             asm volatile("s_waitcnt vmcnt(0)" ::: "memory");
;         } else {
;             XB_SPIN(xb_ld(&bar[XB_XGEN(b.x)]) == gen, bar);
;             __builtin_amdgcn_fence(__ATOMIC_ACQUIRE, "agent");
;             asm volatile("s_waitcnt vmcnt(0)" ::: "memory");
;         }
.LBB0_1806:
	s_lshl_b32 s2, s33, 8
	s_add_u32 s2, s1, s2
	s_addc_u32 s3, s0, 0
	v_mov_b32_e32 v1, s2
	v_add_co_u32_e32 v4, vcc, 0x2000, v1
	v_mov_b32_e32 v1, s3
	s_nop 0
	v_addc_co_u32_e32 v5, vcc, 0, v1, vcc
	v_mov_b32_e32 v1, 1
	global_atomic_add v1, v[4:5], v1, off offset:1024 sc0
	v_cvt_f32_u32_e32 v3, v2
	v_sub_u32_e32 v4, 0, v2
	s_add_u32 s25, s2, 0x1000
	s_addc_u32 s24, s3, 0
	v_rcp_iflag_f32_e32 v3, v3
	s_nop 0
	v_mul_f32_e32 v3, 0x4f7ffffe, v3
	v_cvt_u32_f32_e32 v3, v3
	v_mul_lo_u32 v4, v4, v3
	v_mul_hi_u32 v4, v3, v4
	v_add_u32_e32 v3, v3, v4
	s_waitcnt vmcnt(0) lgkmcnt(0)
	v_mul_hi_u32 v3, v1, v3
	v_mul_lo_u32 v5, v3, v2
	v_add_u32_e32 v4, 1, v1
	v_sub_u32_e32 v1, v1, v5
	v_add_u32_e32 v6, 1, v3
	v_cmp_ge_u32_e32 vcc, v1, v2
	v_sub_u32_e32 v5, v1, v2
	s_nop 0
	v_cndmask_b32_e32 v3, v3, v6, vcc
	v_cndmask_b32_e32 v1, v1, v5, vcc
	v_add_u32_e32 v5, 1, v3
	v_cmp_ge_u32_e32 vcc, v1, v2
	s_nop 1
	v_cndmask_b32_e32 v1, v3, v5, vcc
	v_mad_u64_u32 v[2:3], s[2:3], v2, v1, v[2:3]
	v_cmp_ne_u32_e32 vcc, v4, v2
	s_and_saveexec_b64 s[2:3], vcc
	s_xor_b64 s[2:3], exec, s[2:3]
	s_cbranch_execz .LBB0_1819
	v_mov_b32_e32 v0, s25
	v_add_co_u32_e32 v2, vcc, 0x2000, v0
	v_mov_b32_e32 v0, s24
	s_nop 0
	v_addc_co_u32_e32 v3, vcc, 0, v0, vcc
	global_load_dword v0, v[2:3], off offset:1024 sc1
	s_add_u32 s8, s25, 0x2400
	s_addc_u32 s9, s24, 0
	s_waitcnt vmcnt(0) lgkmcnt(0)
	v_cmp_eq_u32_e32 vcc, v0, v1
	s_and_saveexec_b64 s[4:5], vcc
	s_cbranch_execz .LBB0_1818
	s_add_u32 s6, s1, 0x1200
	s_addc_u32 s7, s0, 0
	s_mov_b32 s26, 1
	s_mov_b64 s[10:11], 0
	s_branch .LBB0_1810

; __device__ __forceinline__ float wave_sum(float v) { v += swz_xor<1>(v); v += swz_xor<2>(v); v += swz_xor<4>(v); v += swz_xor<8>(v); v += swz_xor<16>(v); return half_sum(v); }
; #define INP(i) ((const float*)tab_get(lds, (i)))
; #define OUTP() ((float*)tab_get(lds, 30))
; #define fresh_lane() (my_tid(lds) & 63)
; __device__ __forceinline__ void rms_row_f32_inplace(float* xrow, const float* g, int lane) {
;     f32x4* xr = (f32x4*)xrow + lane; f32x4 v[4]; float s = 0.f;
; #pragma unroll
;     for (int j = 0; j < 4; ++j) { v[j] = xr[64 * j]; s += (v[j].x * v[j].x + v[j].y * v[j].y) + (v[j].z * v[j].z + v[j].w * v[j].w); }
;     const float rstd = rsqrtf(wave_sum(s) * (1.f / DM) + EPS);
; #pragma unroll
;     for (int j = 0; j < 4; ++j) { const f32x4 gg = ((const f32x4*)g)[lane + 64 * j]; xr[64 * j] = v[j] * rstd * gg; }
; }
; __global__ void __launch_bounds__(512, 2) mega_fwd(Params p) {
;     ...
;     { const int lane = fresh_lane(); float* X = OUTP(); const float* g = INP(29); for (int m = MP + gw; m < MT; m += NGW) rms_row_f32_inplace(X + (size_t)m * DM, g, lane); }
.LBB0_1837:
	global_load_dwordx4 v[6:9], v[2:3], off
	global_load_dwordx4 v[10:13], v[2:3], off offset:1024
	global_load_dwordx4 v[14:17], v[2:3], off offset:2048
	global_load_dwordx4 v[18:21], v[2:3], off offset:3072
	global_load_dwordx4 v[22:25], v[0:1], off
	s_add_i32 s36, s36, s44
	s_cmp_gt_i32 s36, 0x81ff
	s_waitcnt vmcnt(0) lgkmcnt(0)
	v_mul_f32_e32 v5, v7, v7
	v_mul_f32_e32 v26, v9, v9
	v_mul_f32_e32 v27, v11, v11
	v_mul_f32_e32 v28, v13, v13
	v_mul_f32_e32 v29, v15, v15
	v_mul_f32_e32 v30, v17, v17
	v_fmac_f32_e32 v5, v6, v6
	v_fmac_f32_e32 v26, v8, v8
	v_fmac_f32_e32 v27, v10, v10
	v_fmac_f32_e32 v28, v12, v12
	v_mul_f32_e32 v31, v19, v19
	v_mul_f32_e32 v32, v21, v21
	v_fmac_f32_e32 v29, v14, v14
	v_fmac_f32_e32 v30, v16, v16
	v_add_f32_e32 v5, v5, v26
	v_add_f32_e32 v26, v27, v28
	v_fmac_f32_e32 v31, v18, v18
	v_fmac_f32_e32 v32, v20, v20
	v_add_f32_e32 v27, v29, v30
	v_add_f32_e32 v5, v5, v26
	v_add_f32_e32 v28, v31, v32
	v_add_f32_e32 v5, v5, v27
	v_add_f32_e32 v5, v5, v28
	ds_swizzle_b32 v26, v5 offset:swizzle(SWAP,1)
	s_waitcnt lgkmcnt(0)
	v_add_f32_e32 v5, v5, v26
	ds_swizzle_b32 v26, v5 offset:swizzle(SWAP,2)
	s_waitcnt lgkmcnt(0)
	v_add_f32_e32 v5, v5, v26
	ds_swizzle_b32 v26, v5 offset:swizzle(SWAP,4)
	s_waitcnt lgkmcnt(0)
	v_add_f32_e32 v5, v5, v26
	ds_swizzle_b32 v26, v5 offset:swizzle(SWAP,8)
	s_waitcnt lgkmcnt(0)
	v_add_f32_e32 v5, v5, v26
	ds_swizzle_b32 v26, v5 offset:swizzle(SWAP,16)
	s_waitcnt lgkmcnt(0)
	v_add_f32_e32 v5, v5, v26
	v_mov_b32_e32 v26, v5
	s_nop 1
	v_permlane32_swap_b32_e32 v5, v26
	v_add_f32_e32 v5, v5, v26
	v_fmamk_f32 v5, v5, 0x3a800000, v4
	v_mul_f32_e32 v26, 0x4b800000, v5
	v_cmp_gt_f32_e32 vcc, s2, v5
	s_nop 1
	v_cndmask_b32_e32 v5, v5, v26, vcc
	v_rsq_f32_e32 v5, v5
	s_nop 0
	v_mul_f32_e32 v26, 0x45800000, v5
	v_cndmask_b32_e32 v26, v5, v26, vcc
	v_pk_mul_f32 v[6:7], v[6:7], v[26:27] op_sel_hi:[1,0]
	v_pk_mul_f32 v[8:9], v[8:9], v[26:27] op_sel_hi:[1,0]
	v_pk_mul_f32 v[6:7], v[22:23], v[6:7]
	v_pk_mul_f32 v[8:9], v[24:25], v[8:9]
	global_store_dwordx4 v[2:3], v[6:9], off
	global_load_dwordx4 v[6:9], v[0:1], off offset:1024
	v_pk_mul_f32 v[12:13], v[12:13], v[26:27] op_sel_hi:[1,0]
	v_pk_mul_f32 v[10:11], v[10:11], v[26:27] op_sel_hi:[1,0]
	s_waitcnt vmcnt(0) lgkmcnt(0)
	v_pk_mul_f32 v[8:9], v[8:9], v[12:13]
	v_pk_mul_f32 v[6:7], v[6:7], v[10:11]
	global_store_dwordx4 v[2:3], v[6:9], off offset:1024
	global_load_dwordx4 v[6:9], v[0:1], off offset:2048
	v_pk_mul_f32 v[10:11], v[16:17], v[26:27] op_sel_hi:[1,0]
	v_pk_mul_f32 v[12:13], v[14:15], v[26:27] op_sel_hi:[1,0]
	s_waitcnt vmcnt(0) lgkmcnt(0)
	v_pk_mul_f32 v[8:9], v[8:9], v[10:11]
	v_pk_mul_f32 v[6:7], v[6:7], v[12:13]
	global_store_dwordx4 v[2:3], v[6:9], off offset:2048
	global_load_dwordx4 v[6:9], v[0:1], off offset:3072
	v_pk_mul_f32 v[10:11], v[20:21], v[26:27] op_sel_hi:[1,0]
	v_pk_mul_f32 v[12:13], v[18:19], v[26:27] op_sel_hi:[1,0]
	s_waitcnt vmcnt(0) lgkmcnt(0)
	v_pk_mul_f32 v[8:9], v[8:9], v[10:11]
	v_pk_mul_f32 v[6:7], v[6:7], v[12:13]
	global_store_dwordx4 v[2:3], v[6:9], off offset:3072
	v_lshl_add_u64 v[2:3], v[2:3], 0, s[0:1]
	s_cbranch_scc0 .LBB0_1837
